# v43: v41 plus LDS-DMA loads in saddr form (SGPR base + 32-bit VGPR offset) at 293 sites, dropping one v_lshl_add_u64 per load where the 64-bit address is not reused
# baseline (speedup 1.0000x reference)
.LBB0_273:
	s_waitcnt lgkmcnt(0)
	s_cmp_lg_u64 s[8:9], 0
	s_cselect_b64 s[12:13], -1, 0
	s_add_u32 s14, s10, 0x12100000
	s_addc_u32 s15, s11, 0
	s_add_u32 s10, s10, 0x3100000
	s_mov_b64 s[16:17], 0x80
	s_addc_u32 s11, s11, 0
	s_and_b32 s7, s1, 3
	s_add_i32 m0, s29, 0x18000
	v_lshl_add_u64 v[8:9], v[8:9], 0, s[16:17]
	s_lshl_b32 s47, s0, 6
	s_lshl_b32 s18, s0, 13
	s_lshl_b32 s48, s7, 5
	s_lshl_b32 s19, s7, 12
	s_waitcnt vmcnt(4)
	s_barrier
	global_load_lds_dwordx4 v[8:9], off
	v_lshl_add_u64 v[6:7], v[6:7], 0, s[16:17]
	s_add_i32 m0, s29, 0x1a000
	s_add_i32 s49, s29, 0x8000
	s_add_i32 s51, s29, 0xa000
	global_load_lds_dwordx4 v[6:7], off
	v_lshl_add_u64 v[4:5], v[4:5], 0, s[16:17]
	s_mov_b32 m0, s49
	s_add_u32 s0, s30, 0x40080
	global_load_lds_dwordx4 v[4:5], off
	v_lshl_add_u64 v[2:3], v[2:3], 0, s[16:17]
	s_mov_b32 m0, s51
	s_addc_u32 s1, s31, 0
	global_load_lds_dwordx4 v[2:3], off
	s_add_i32 m0, s29, 0x1c000
	s_nop 0
	global_load_lds_dwordx4 v142, s[0:1]
	s_add_i32 m0, s29, 0x1e000
	v_bfe_u32 v156, v10, 4, 2
	global_load_lds_dwordx4 v138, s[0:1]
	v_and_b32_e32 v1, 15, v10
	v_lshlrev_b32_e32 v2, 4, v156
	v_lshlrev_b32_e32 v3, 2, v10
	v_lshl_or_b32 v2, v1, 6, v2
	v_and_b32_e32 v3, 32, v3
	v_bitop3_b32 v4, v2, s18, v3 bitop3:0xde
	v_bitop3_b32 v157, v2, s19, v3 bitop3:0xde
	v_lshlrev_b32_e32 v2, 14, v11
	v_and_b32_e32 v2, 0xffff8000, v2
	v_lshl_add_u32 v2, v12, 11, v2
	v_and_b32_e32 v3, 1, v11
	v_lshl_or_b32 v2, v3, 6, v2
	v_lshl_add_u32 v146, v13, 1, v2
	v_lshlrev_b32_e32 v2, 14, v15
	v_and_b32_e32 v2, 0xffff8000, v2
	s_waitcnt vmcnt(6)
	s_cmp_eq_u32 s7, 0
	v_lshl_add_u32 v2, v14, 11, v2
	v_and_b32_e32 v3, 1, v15
	s_cselect_b64 s[18:19], -1, 0
	v_lshl_or_b32 v2, v3, 6, v2
	s_add_i32 s52, 0, 0x10000
	s_add_i32 s53, 0, 0x14000
	s_sext_i32_i8 s55, s6
	v_mov_b32_e32 v147, v143
	v_lshl_add_u32 v148, v16, 1, v2
	v_mov_b32_e32 v149, v143
	v_mov_b64_e32 v[150:151], 0xd00
	v_mov_b64_e32 v[152:153], 0xcff
	v_add_u32_e32 v158, s52, v157
	v_add_u32_e32 v159, 0, v4
	v_add_u32_e32 v160, s53, v157
	s_movk_i32 s54, 0x1800
	v_mov_b32_e32 v161, 0x3db504f3
	s_barrier
	s_branch .LBB0_275

.LBB0_277:
	s_ashr_i32 s23, s22, 31
	s_lshl_b64 s[0:1], s[22:23], 19
	v_cmp_lt_i64_e32 vcc, s[24:25], v[150:151]
	s_add_u32 s24, s5, s0
	s_addc_u32 s25, s38, s1
	s_and_b64 s[0:1], vcc, exec
	s_cselect_b32 s23, s25, s35
	s_cselect_b32 s56, s24, s34
	s_ashr_i32 s21, s20, 31
	s_lshl_b64 s[0:1], s[20:21], 19
	s_add_u32 s26, s39, s0
	s_addc_u32 s27, s40, s1
	s_and_b64 s[0:1], vcc, exec
	s_cselect_b32 s21, s27, s31
	s_cselect_b32 s57, s26, s30
	s_add_u32 s58, s30, 0x100
	s_addc_u32 s59, s31, 0
	s_add_u32 s30, s34, 0x40080
	s_addc_u32 s31, s35, 0
	s_mov_b32 s60, -2
	ds_read_b128 v[130:133], v158
	ds_read_b128 v[134:137], v158 offset:1024
	ds_read_b128 v[162:165], v158 offset:2048
	ds_read_b128 v[166:169], v158 offset:3072
	s_add_u32 s0, s30, 0xfffc0080
	s_addc_u32 s1, s31, -1
	s_cmp_eq_u32 s60, 12
	s_cselect_b32 s37, s23, s1
	s_cselect_b32 s36, s56, s0
	s_cselect_b32 s35, s21, s59
	s_cselect_b32 s34, s57, s58
	s_add_i32 m0, s29, 0xc000
	ds_read_b128 v[170:173], v159
	ds_read_b128 v[174:177], v159 offset:1024
	ds_read_b128 v[178:181], v159 offset:2048
	ds_read_b128 v[182:185], v159 offset:3072
	ds_read_b128 v[186:189], v159 offset:4096
	ds_read_b128 v[190:193], v159 offset:5120
	ds_read_b128 v[194:197], v159 offset:6144
	ds_read_b128 v[198:201], v159 offset:7168
	global_load_lds_dwordx4 v148, s[30:31]
	s_add_i32 m0, s29, 0xe000
	s_nop 0
	global_load_lds_dwordx4 v146, s[30:31]
	s_waitcnt lgkmcnt(8)
	s_waitcnt vmcnt(10)
	s_barrier
	s_waitcnt lgkmcnt(0)
	s_waitcnt lgkmcnt(0)
	v_mfma_f32_16x16x32_bf16 v[126:129], v[130:133], v[170:173], 0
	v_mfma_f32_16x16x32_bf16 v[122:125], v[162:165], v[170:173], 0
	v_mfma_f32_16x16x32_bf16 v[118:121], v[130:133], v[178:181], 0
	v_mfma_f32_16x16x32_bf16 v[110:113], v[162:165], v[178:181], 0
	v_mfma_f32_16x16x32_bf16 v[102:105], v[130:133], v[186:189], 0
	v_mfma_f32_16x16x32_bf16 v[94:97], v[162:165], v[186:189], 0
	v_mfma_f32_16x16x32_bf16 v[86:89], v[130:133], v[194:197], 0
	v_mfma_f32_16x16x32_bf16 v[78:81], v[162:165], v[194:197], 0
	v_mfma_f32_16x16x32_bf16 v[126:129], v[134:137], v[174:177], v[126:129]
	v_mfma_f32_16x16x32_bf16 v[122:125], v[166:169], v[174:177], v[122:125]
	v_mfma_f32_16x16x32_bf16 v[118:121], v[134:137], v[182:185], v[118:121]
	v_mfma_f32_16x16x32_bf16 v[110:113], v[166:169], v[182:185], v[110:113]
	v_mfma_f32_16x16x32_bf16 v[102:105], v[134:137], v[190:193], v[102:105]
	v_mfma_f32_16x16x32_bf16 v[94:97], v[166:169], v[190:193], v[94:97]
	v_mfma_f32_16x16x32_bf16 v[86:89], v[134:137], v[198:201], v[86:89]
	v_mfma_f32_16x16x32_bf16 v[78:81], v[166:169], v[198:201], v[78:81]
	s_barrier
	s_add_i32 s0, s52, s41
	v_lshl_add_u64 v[154:155], s[34:35], 0, v[142:143]
	s_mov_b32 m0, s0
	ds_read_b128 v[202:205], v160
	ds_read_b128 v[206:209], v160 offset:1024
	ds_read_b128 v[210:213], v160 offset:2048
	ds_read_b128 v[214:217], v160 offset:3072
	global_load_lds_dwordx4 v[154:155], off
	v_lshl_add_u64 v[218:219], s[34:35], 0, v[138:139]
	s_add_i32 m0, s0, 0x2000
	s_nop 0
	global_load_lds_dwordx4 v[218:219], off
	s_waitcnt vmcnt(10)
	s_barrier
	s_waitcnt lgkmcnt(0)
	s_waitcnt lgkmcnt(0)
	v_mfma_f32_16x16x32_bf16 v[114:117], v[202:205], v[170:173], 0
	v_mfma_f32_16x16x32_bf16 v[106:109], v[210:213], v[170:173], 0
	v_mfma_f32_16x16x32_bf16 v[98:101], v[202:205], v[178:181], 0
	v_mfma_f32_16x16x32_bf16 v[90:93], v[210:213], v[178:181], 0
	v_mfma_f32_16x16x32_bf16 v[82:85], v[202:205], v[186:189], 0
	v_mfma_f32_16x16x32_bf16 v[74:77], v[210:213], v[186:189], 0
	v_mfma_f32_16x16x32_bf16 v[70:73], v[202:205], v[194:197], 0
	v_mfma_f32_16x16x32_bf16 v[66:69], v[210:213], v[194:197], 0
	v_mfma_f32_16x16x32_bf16 v[114:117], v[206:209], v[174:177], v[114:117]
	v_mfma_f32_16x16x32_bf16 v[106:109], v[214:217], v[174:177], v[106:109]
	v_mfma_f32_16x16x32_bf16 v[98:101], v[206:209], v[182:185], v[98:101]
	v_mfma_f32_16x16x32_bf16 v[90:93], v[214:217], v[182:185], v[90:93]
	v_mfma_f32_16x16x32_bf16 v[82:85], v[206:209], v[190:193], v[82:85]
	v_mfma_f32_16x16x32_bf16 v[74:77], v[214:217], v[190:193], v[74:77]
	v_mfma_f32_16x16x32_bf16 v[70:73], v[206:209], v[198:201], v[70:73]
	v_mfma_f32_16x16x32_bf16 v[66:69], v[214:217], v[198:201], v[66:69]
	s_mov_b32 m0, s29
	v_lshl_add_u64 v[220:221], s[36:37], 0, v[144:145]
	s_barrier
	ds_read_b128 v[170:173], v159 offset:16384
	ds_read_b128 v[174:177], v159 offset:17408
	ds_read_b128 v[178:181], v159 offset:18432
	ds_read_b128 v[182:185], v159 offset:19456
	ds_read_b128 v[186:189], v159 offset:20480
	ds_read_b128 v[190:193], v159 offset:21504
	ds_read_b128 v[194:197], v159 offset:22528
	ds_read_b128 v[198:201], v159 offset:23552
	global_load_lds_dwordx4 v[220:221], off
	v_lshl_add_u64 v[222:223], s[36:37], 0, v[140:141]
	s_mov_b32 m0, s43
	s_nop 0
	global_load_lds_dwordx4 v[222:223], off
	s_waitcnt vmcnt(10)
	s_barrier
	s_waitcnt lgkmcnt(0)
	s_waitcnt lgkmcnt(0)
	v_mfma_f32_16x16x32_bf16 v[62:65], v[130:133], v[170:173], 0
	v_mfma_f32_16x16x32_bf16 v[58:61], v[162:165], v[170:173], 0
	v_mfma_f32_16x16x32_bf16 v[54:57], v[130:133], v[178:181], 0
	v_mfma_f32_16x16x32_bf16 v[46:49], v[162:165], v[178:181], 0
	v_mfma_f32_16x16x32_bf16 v[38:41], v[130:133], v[186:189], 0
	v_mfma_f32_16x16x32_bf16 v[30:33], v[162:165], v[186:189], 0
	v_mfma_f32_16x16x32_bf16 v[22:25], v[130:133], v[194:197], 0
	v_mfma_f32_16x16x32_bf16 v[14:17], v[162:165], v[194:197], 0
	v_mfma_f32_16x16x32_bf16 v[62:65], v[134:137], v[174:177], v[62:65]
	v_mfma_f32_16x16x32_bf16 v[58:61], v[166:169], v[174:177], v[58:61]
	v_mfma_f32_16x16x32_bf16 v[54:57], v[134:137], v[182:185], v[54:57]
	v_mfma_f32_16x16x32_bf16 v[46:49], v[166:169], v[182:185], v[46:49]
	v_mfma_f32_16x16x32_bf16 v[38:41], v[134:137], v[190:193], v[38:41]
	v_mfma_f32_16x16x32_bf16 v[30:33], v[166:169], v[190:193], v[30:33]
	v_mfma_f32_16x16x32_bf16 v[22:25], v[134:137], v[198:201], v[22:25]
	v_mfma_f32_16x16x32_bf16 v[14:17], v[166:169], v[198:201], v[14:17]
	s_barrier
	s_add_u32 s0, s34, 0x40000
	s_addc_u32 s1, s35, 0
	s_add_i32 s61, s53, s41
	s_mov_b32 m0, s61
	s_nop 0
	global_load_lds_dwordx4 v142, s[0:1]
	s_add_i32 m0, s61, 0x2000
	s_nop 0
	global_load_lds_dwordx4 v138, s[0:1]
	s_waitcnt vmcnt(10)
	s_barrier
	v_mfma_f32_16x16x32_bf16 v[50:53], v[202:205], v[170:173], 0
	v_mfma_f32_16x16x32_bf16 v[42:45], v[210:213], v[170:173], 0
	v_mfma_f32_16x16x32_bf16 v[34:37], v[202:205], v[178:181], 0
	v_mfma_f32_16x16x32_bf16 v[26:29], v[210:213], v[178:181], 0
	v_mfma_f32_16x16x32_bf16 v[18:21], v[202:205], v[186:189], 0
	v_mfma_f32_16x16x32_bf16 v[10:13], v[210:213], v[186:189], 0
	v_mfma_f32_16x16x32_bf16 v[6:9], v[202:205], v[194:197], 0
	v_mfma_f32_16x16x32_bf16 v[2:5], v[210:213], v[194:197], 0
	v_mfma_f32_16x16x32_bf16 v[50:53], v[206:209], v[174:177], v[50:53]
	v_mfma_f32_16x16x32_bf16 v[42:45], v[214:217], v[174:177], v[42:45]
	v_mfma_f32_16x16x32_bf16 v[34:37], v[206:209], v[182:185], v[34:37]
	v_mfma_f32_16x16x32_bf16 v[26:29], v[214:217], v[182:185], v[26:29]
	v_mfma_f32_16x16x32_bf16 v[18:21], v[206:209], v[190:193], v[18:21]
	v_mfma_f32_16x16x32_bf16 v[10:13], v[214:217], v[190:193], v[10:13]
	v_mfma_f32_16x16x32_bf16 v[6:9], v[206:209], v[198:201], v[6:9]
	v_mfma_f32_16x16x32_bf16 v[2:5], v[214:217], v[198:201], v[2:5]
	s_add_i32 s61, 0, 0x18000
	v_add_u32_e32 v166, s61, v157
	s_barrier
	ds_read_b128 v[130:133], v166
	ds_read_b128 v[134:137], v166 offset:1024
	ds_read_b128 v[162:165], v166 offset:2048
	ds_read_b128 v[166:169], v166 offset:3072
	s_add_u32 s0, s36, 0x40000
	s_addc_u32 s1, s37, 0
	s_mov_b32 m0, s44
	ds_read_b128 v[170:173], v159 offset:32768
	ds_read_b128 v[174:177], v159 offset:33792
	ds_read_b128 v[178:181], v159 offset:34816
	ds_read_b128 v[182:185], v159 offset:35840
	ds_read_b128 v[186:189], v159 offset:36864
	ds_read_b128 v[190:193], v159 offset:37888
	ds_read_b128 v[194:197], v159 offset:38912
	ds_read_b128 v[198:201], v159 offset:39936
	global_load_lds_dwordx4 v144, s[0:1]
	s_mov_b32 m0, s45
	s_nop 0
	global_load_lds_dwordx4 v140, s[0:1]
	s_waitcnt lgkmcnt(8)
	s_waitcnt vmcnt(10)
	s_barrier
	s_waitcnt lgkmcnt(0)
	s_waitcnt lgkmcnt(0)
	v_mfma_f32_16x16x32_bf16 v[126:129], v[130:133], v[170:173], v[126:129]
	v_mfma_f32_16x16x32_bf16 v[122:125], v[162:165], v[170:173], v[122:125]
	v_mfma_f32_16x16x32_bf16 v[118:121], v[130:133], v[178:181], v[118:121]
	v_mfma_f32_16x16x32_bf16 v[110:113], v[162:165], v[178:181], v[110:113]
	v_mfma_f32_16x16x32_bf16 v[102:105], v[130:133], v[186:189], v[102:105]
	v_mfma_f32_16x16x32_bf16 v[94:97], v[162:165], v[186:189], v[94:97]
	v_mfma_f32_16x16x32_bf16 v[86:89], v[130:133], v[194:197], v[86:89]
	v_mfma_f32_16x16x32_bf16 v[78:81], v[162:165], v[194:197], v[78:81]
	v_mfma_f32_16x16x32_bf16 v[126:129], v[134:137], v[174:177], v[126:129]
	v_mfma_f32_16x16x32_bf16 v[122:125], v[166:169], v[174:177], v[122:125]
	v_mfma_f32_16x16x32_bf16 v[118:121], v[134:137], v[182:185], v[118:121]
	v_mfma_f32_16x16x32_bf16 v[110:113], v[166:169], v[182:185], v[110:113]
	v_mfma_f32_16x16x32_bf16 v[102:105], v[134:137], v[190:193], v[102:105]
	v_mfma_f32_16x16x32_bf16 v[94:97], v[166:169], v[190:193], v[94:97]
	v_mfma_f32_16x16x32_bf16 v[86:89], v[134:137], v[198:201], v[86:89]
	v_mfma_f32_16x16x32_bf16 v[78:81], v[166:169], v[198:201], v[78:81]
	s_barrier
	s_add_i32 s36, 0, 0x1c000
	s_add_i32 s0, s61, s41
	v_add_u32_e32 v214, s36, v157
	v_lshl_add_u64 v[154:155], v[154:155], 0, s[16:17]
	s_mov_b32 m0, s0
	ds_read_b128 v[202:205], v214
	ds_read_b128 v[206:209], v214 offset:1024
	ds_read_b128 v[210:213], v214 offset:2048
	ds_read_b128 v[214:217], v214 offset:3072
	global_load_lds_dwordx4 v[154:155], off
	v_lshl_add_u64 v[154:155], v[218:219], 0, s[16:17]
	s_add_i32 m0, s0, 0x2000
	s_nop 0
	global_load_lds_dwordx4 v[154:155], off
	s_waitcnt vmcnt(10)
	s_barrier
	s_waitcnt lgkmcnt(0)
	s_waitcnt lgkmcnt(0)
	v_mfma_f32_16x16x32_bf16 v[114:117], v[202:205], v[170:173], v[114:117]
	v_mfma_f32_16x16x32_bf16 v[106:109], v[210:213], v[170:173], v[106:109]
	v_mfma_f32_16x16x32_bf16 v[98:101], v[202:205], v[178:181], v[98:101]
	v_mfma_f32_16x16x32_bf16 v[90:93], v[210:213], v[178:181], v[90:93]
	v_mfma_f32_16x16x32_bf16 v[82:85], v[202:205], v[186:189], v[82:85]
	v_mfma_f32_16x16x32_bf16 v[74:77], v[210:213], v[186:189], v[74:77]
	v_mfma_f32_16x16x32_bf16 v[70:73], v[202:205], v[194:197], v[70:73]
	v_mfma_f32_16x16x32_bf16 v[66:69], v[210:213], v[194:197], v[66:69]
	v_mfma_f32_16x16x32_bf16 v[114:117], v[206:209], v[174:177], v[114:117]
	v_mfma_f32_16x16x32_bf16 v[106:109], v[214:217], v[174:177], v[106:109]
	v_mfma_f32_16x16x32_bf16 v[98:101], v[206:209], v[182:185], v[98:101]
	v_mfma_f32_16x16x32_bf16 v[90:93], v[214:217], v[182:185], v[90:93]
	v_mfma_f32_16x16x32_bf16 v[82:85], v[206:209], v[190:193], v[82:85]
	v_mfma_f32_16x16x32_bf16 v[74:77], v[214:217], v[190:193], v[74:77]
	v_mfma_f32_16x16x32_bf16 v[70:73], v[206:209], v[198:201], v[70:73]
	v_mfma_f32_16x16x32_bf16 v[66:69], v[214:217], v[198:201], v[66:69]
	s_mov_b32 m0, s49
	v_lshl_add_u64 v[154:155], v[220:221], 0, s[16:17]
	s_barrier
	ds_read_b128 v[170:173], v159 offset:49152
	ds_read_b128 v[174:177], v159 offset:50176
	ds_read_b128 v[178:181], v159 offset:51200
	ds_read_b128 v[182:185], v159 offset:52224
	ds_read_b128 v[186:189], v159 offset:53248
	ds_read_b128 v[190:193], v159 offset:54272
	ds_read_b128 v[194:197], v159 offset:55296
	ds_read_b128 v[198:201], v159 offset:56320
	global_load_lds_dwordx4 v[154:155], off
	v_lshl_add_u64 v[154:155], v[222:223], 0, s[16:17]
	s_mov_b32 m0, s51
	s_nop 0
	global_load_lds_dwordx4 v[154:155], off
	s_waitcnt vmcnt(10)
	s_barrier
	s_waitcnt lgkmcnt(0)
	s_waitcnt lgkmcnt(0)
	v_mfma_f32_16x16x32_bf16 v[62:65], v[130:133], v[170:173], v[62:65]
	v_mfma_f32_16x16x32_bf16 v[58:61], v[162:165], v[170:173], v[58:61]
	v_mfma_f32_16x16x32_bf16 v[54:57], v[130:133], v[178:181], v[54:57]
	v_mfma_f32_16x16x32_bf16 v[46:49], v[162:165], v[178:181], v[46:49]
	v_mfma_f32_16x16x32_bf16 v[38:41], v[130:133], v[186:189], v[38:41]
	v_mfma_f32_16x16x32_bf16 v[30:33], v[162:165], v[186:189], v[30:33]
	v_mfma_f32_16x16x32_bf16 v[22:25], v[130:133], v[194:197], v[22:25]
	v_mfma_f32_16x16x32_bf16 v[14:17], v[162:165], v[194:197], v[14:17]
	v_mfma_f32_16x16x32_bf16 v[62:65], v[134:137], v[174:177], v[62:65]
	v_mfma_f32_16x16x32_bf16 v[58:61], v[166:169], v[174:177], v[58:61]
	v_mfma_f32_16x16x32_bf16 v[54:57], v[134:137], v[182:185], v[54:57]
	v_mfma_f32_16x16x32_bf16 v[46:49], v[166:169], v[182:185], v[46:49]
	v_mfma_f32_16x16x32_bf16 v[38:41], v[134:137], v[190:193], v[38:41]
	v_mfma_f32_16x16x32_bf16 v[30:33], v[166:169], v[190:193], v[30:33]
	v_mfma_f32_16x16x32_bf16 v[22:25], v[134:137], v[198:201], v[22:25]
	v_mfma_f32_16x16x32_bf16 v[14:17], v[166:169], v[198:201], v[14:17]
	s_barrier
	s_add_u32 s0, s34, 0x40080
	s_addc_u32 s1, s35, 0
	s_add_i32 s34, s36, s41
	s_mov_b32 m0, s34
	s_nop 0
	global_load_lds_dwordx4 v142, s[0:1]
	v_lshl_add_u64 v[130:131], s[0:1], 0, v[138:139]
	s_add_i32 m0, s34, 0x2000
	s_nop 0
	global_load_lds_dwordx4 v[130:131], off
	s_waitcnt vmcnt(10)
	s_barrier
	v_mfma_f32_16x16x32_bf16 v[50:53], v[202:205], v[170:173], v[50:53]
	v_mfma_f32_16x16x32_bf16 v[42:45], v[210:213], v[170:173], v[42:45]
	v_mfma_f32_16x16x32_bf16 v[34:37], v[202:205], v[178:181], v[34:37]
	v_mfma_f32_16x16x32_bf16 v[26:29], v[210:213], v[178:181], v[26:29]
	v_mfma_f32_16x16x32_bf16 v[18:21], v[202:205], v[186:189], v[18:21]
	v_mfma_f32_16x16x32_bf16 v[10:13], v[210:213], v[186:189], v[10:13]
	v_mfma_f32_16x16x32_bf16 v[6:9], v[202:205], v[194:197], v[6:9]
	v_mfma_f32_16x16x32_bf16 v[2:5], v[210:213], v[194:197], v[2:5]
	v_mfma_f32_16x16x32_bf16 v[50:53], v[206:209], v[174:177], v[50:53]
	v_mfma_f32_16x16x32_bf16 v[42:45], v[214:217], v[174:177], v[42:45]
	v_mfma_f32_16x16x32_bf16 v[34:37], v[206:209], v[182:185], v[34:37]
	v_mfma_f32_16x16x32_bf16 v[26:29], v[214:217], v[182:185], v[26:29]
	v_mfma_f32_16x16x32_bf16 v[18:21], v[206:209], v[190:193], v[18:21]
	v_mfma_f32_16x16x32_bf16 v[10:13], v[214:217], v[190:193], v[10:13]
	v_mfma_f32_16x16x32_bf16 v[6:9], v[206:209], v[198:201], v[6:9]
	v_mfma_f32_16x16x32_bf16 v[2:5], v[214:217], v[198:201], v[2:5]
	s_add_i32 s60, s60, 2
	s_add_u32 s58, s58, 0x100
	s_addc_u32 s59, s59, 0
	s_add_u32 s30, s30, 0x100
	s_addc_u32 s31, s31, 0
	s_cmp_gt_u32 s60, 13
	s_barrier
	s_cbranch_scc1 .Lpeel_exit_0
.LBB0_278:
	ds_read_b128 v[130:133], v158
	ds_read_b128 v[134:137], v158 offset:1024
	ds_read_b128 v[162:165], v158 offset:2048
	ds_read_b128 v[166:169], v158 offset:3072
	s_add_u32 s0, s30, 0xfffc0080
	s_addc_u32 s1, s31, -1
	s_cmp_eq_u32 s60, 12
	s_cselect_b32 s37, s23, s1
	s_cselect_b32 s36, s56, s0
	s_cselect_b32 s35, s21, s59
	s_cselect_b32 s34, s57, s58
	s_add_i32 m0, s29, 0xc000
	ds_read_b128 v[170:173], v159
	ds_read_b128 v[174:177], v159 offset:1024
	ds_read_b128 v[178:181], v159 offset:2048
	ds_read_b128 v[182:185], v159 offset:3072
	ds_read_b128 v[186:189], v159 offset:4096
	ds_read_b128 v[190:193], v159 offset:5120
	ds_read_b128 v[194:197], v159 offset:6144
	ds_read_b128 v[198:201], v159 offset:7168
	global_load_lds_dwordx4 v148, s[30:31]
	s_add_i32 m0, s29, 0xe000
	s_nop 0
	global_load_lds_dwordx4 v146, s[30:31]
	s_waitcnt lgkmcnt(8)
	s_waitcnt vmcnt(10)
	s_barrier
	s_waitcnt lgkmcnt(0)
	s_waitcnt lgkmcnt(0)
	v_mfma_f32_16x16x32_bf16 v[126:129], v[130:133], v[170:173], v[126:129]
	v_mfma_f32_16x16x32_bf16 v[122:125], v[162:165], v[170:173], v[122:125]
	v_mfma_f32_16x16x32_bf16 v[118:121], v[130:133], v[178:181], v[118:121]
	v_mfma_f32_16x16x32_bf16 v[110:113], v[162:165], v[178:181], v[110:113]
	v_mfma_f32_16x16x32_bf16 v[102:105], v[130:133], v[186:189], v[102:105]
	v_mfma_f32_16x16x32_bf16 v[94:97], v[162:165], v[186:189], v[94:97]
	v_mfma_f32_16x16x32_bf16 v[86:89], v[130:133], v[194:197], v[86:89]
	v_mfma_f32_16x16x32_bf16 v[78:81], v[162:165], v[194:197], v[78:81]
	v_mfma_f32_16x16x32_bf16 v[126:129], v[134:137], v[174:177], v[126:129]
	v_mfma_f32_16x16x32_bf16 v[122:125], v[166:169], v[174:177], v[122:125]
	v_mfma_f32_16x16x32_bf16 v[118:121], v[134:137], v[182:185], v[118:121]
	v_mfma_f32_16x16x32_bf16 v[110:113], v[166:169], v[182:185], v[110:113]
	v_mfma_f32_16x16x32_bf16 v[102:105], v[134:137], v[190:193], v[102:105]
	v_mfma_f32_16x16x32_bf16 v[94:97], v[166:169], v[190:193], v[94:97]
	v_mfma_f32_16x16x32_bf16 v[86:89], v[134:137], v[198:201], v[86:89]
	v_mfma_f32_16x16x32_bf16 v[78:81], v[166:169], v[198:201], v[78:81]
	s_barrier
	s_add_i32 s0, s52, s41
	v_lshl_add_u64 v[154:155], s[34:35], 0, v[142:143]
	s_mov_b32 m0, s0
	ds_read_b128 v[202:205], v160
	ds_read_b128 v[206:209], v160 offset:1024
	ds_read_b128 v[210:213], v160 offset:2048
	ds_read_b128 v[214:217], v160 offset:3072
	global_load_lds_dwordx4 v[154:155], off
	v_lshl_add_u64 v[218:219], s[34:35], 0, v[138:139]
	s_add_i32 m0, s0, 0x2000
	s_nop 0
	global_load_lds_dwordx4 v[218:219], off
	s_waitcnt vmcnt(10)
	s_barrier
	s_waitcnt lgkmcnt(0)
	s_waitcnt lgkmcnt(0)
	v_mfma_f32_16x16x32_bf16 v[114:117], v[202:205], v[170:173], v[114:117]
	v_mfma_f32_16x16x32_bf16 v[106:109], v[210:213], v[170:173], v[106:109]
	v_mfma_f32_16x16x32_bf16 v[98:101], v[202:205], v[178:181], v[98:101]
	v_mfma_f32_16x16x32_bf16 v[90:93], v[210:213], v[178:181], v[90:93]
	v_mfma_f32_16x16x32_bf16 v[82:85], v[202:205], v[186:189], v[82:85]
	v_mfma_f32_16x16x32_bf16 v[74:77], v[210:213], v[186:189], v[74:77]
	v_mfma_f32_16x16x32_bf16 v[70:73], v[202:205], v[194:197], v[70:73]
	v_mfma_f32_16x16x32_bf16 v[66:69], v[210:213], v[194:197], v[66:69]
	v_mfma_f32_16x16x32_bf16 v[114:117], v[206:209], v[174:177], v[114:117]
	v_mfma_f32_16x16x32_bf16 v[106:109], v[214:217], v[174:177], v[106:109]
	v_mfma_f32_16x16x32_bf16 v[98:101], v[206:209], v[182:185], v[98:101]
	v_mfma_f32_16x16x32_bf16 v[90:93], v[214:217], v[182:185], v[90:93]
	v_mfma_f32_16x16x32_bf16 v[82:85], v[206:209], v[190:193], v[82:85]
	v_mfma_f32_16x16x32_bf16 v[74:77], v[214:217], v[190:193], v[74:77]
	v_mfma_f32_16x16x32_bf16 v[70:73], v[206:209], v[198:201], v[70:73]
	v_mfma_f32_16x16x32_bf16 v[66:69], v[214:217], v[198:201], v[66:69]
	s_mov_b32 m0, s29
	v_lshl_add_u64 v[220:221], s[36:37], 0, v[144:145]
	s_barrier
	ds_read_b128 v[170:173], v159 offset:16384
	ds_read_b128 v[174:177], v159 offset:17408
	ds_read_b128 v[178:181], v159 offset:18432
	ds_read_b128 v[182:185], v159 offset:19456
	ds_read_b128 v[186:189], v159 offset:20480
	ds_read_b128 v[190:193], v159 offset:21504
	ds_read_b128 v[194:197], v159 offset:22528
	ds_read_b128 v[198:201], v159 offset:23552
	global_load_lds_dwordx4 v[220:221], off
	v_lshl_add_u64 v[222:223], s[36:37], 0, v[140:141]
	s_mov_b32 m0, s43
	s_nop 0
	global_load_lds_dwordx4 v[222:223], off
	s_waitcnt vmcnt(10)
	s_barrier
	s_waitcnt lgkmcnt(0)
	s_waitcnt lgkmcnt(0)
	v_mfma_f32_16x16x32_bf16 v[62:65], v[130:133], v[170:173], v[62:65]
	v_mfma_f32_16x16x32_bf16 v[58:61], v[162:165], v[170:173], v[58:61]
	v_mfma_f32_16x16x32_bf16 v[54:57], v[130:133], v[178:181], v[54:57]
	v_mfma_f32_16x16x32_bf16 v[46:49], v[162:165], v[178:181], v[46:49]
	v_mfma_f32_16x16x32_bf16 v[38:41], v[130:133], v[186:189], v[38:41]
	v_mfma_f32_16x16x32_bf16 v[30:33], v[162:165], v[186:189], v[30:33]
	v_mfma_f32_16x16x32_bf16 v[22:25], v[130:133], v[194:197], v[22:25]
	v_mfma_f32_16x16x32_bf16 v[14:17], v[162:165], v[194:197], v[14:17]
	v_mfma_f32_16x16x32_bf16 v[62:65], v[134:137], v[174:177], v[62:65]
	v_mfma_f32_16x16x32_bf16 v[58:61], v[166:169], v[174:177], v[58:61]
	v_mfma_f32_16x16x32_bf16 v[54:57], v[134:137], v[182:185], v[54:57]
	v_mfma_f32_16x16x32_bf16 v[46:49], v[166:169], v[182:185], v[46:49]
	v_mfma_f32_16x16x32_bf16 v[38:41], v[134:137], v[190:193], v[38:41]
	v_mfma_f32_16x16x32_bf16 v[30:33], v[166:169], v[190:193], v[30:33]
	v_mfma_f32_16x16x32_bf16 v[22:25], v[134:137], v[198:201], v[22:25]
	v_mfma_f32_16x16x32_bf16 v[14:17], v[166:169], v[198:201], v[14:17]
	s_barrier
	s_add_u32 s0, s34, 0x40000
	s_addc_u32 s1, s35, 0
	s_add_i32 s61, s53, s41
	s_mov_b32 m0, s61
	s_nop 0
	global_load_lds_dwordx4 v142, s[0:1]
	s_add_i32 m0, s61, 0x2000
	s_nop 0
	global_load_lds_dwordx4 v138, s[0:1]
	s_waitcnt vmcnt(10)
	s_barrier
	v_mfma_f32_16x16x32_bf16 v[50:53], v[202:205], v[170:173], v[50:53]
	v_mfma_f32_16x16x32_bf16 v[42:45], v[210:213], v[170:173], v[42:45]
	v_mfma_f32_16x16x32_bf16 v[34:37], v[202:205], v[178:181], v[34:37]
	v_mfma_f32_16x16x32_bf16 v[26:29], v[210:213], v[178:181], v[26:29]
	v_mfma_f32_16x16x32_bf16 v[18:21], v[202:205], v[186:189], v[18:21]
	v_mfma_f32_16x16x32_bf16 v[10:13], v[210:213], v[186:189], v[10:13]
	v_mfma_f32_16x16x32_bf16 v[6:9], v[202:205], v[194:197], v[6:9]
	v_mfma_f32_16x16x32_bf16 v[2:5], v[210:213], v[194:197], v[2:5]
	v_mfma_f32_16x16x32_bf16 v[50:53], v[206:209], v[174:177], v[50:53]
	v_mfma_f32_16x16x32_bf16 v[42:45], v[214:217], v[174:177], v[42:45]
	v_mfma_f32_16x16x32_bf16 v[34:37], v[206:209], v[182:185], v[34:37]
	v_mfma_f32_16x16x32_bf16 v[26:29], v[214:217], v[182:185], v[26:29]
	v_mfma_f32_16x16x32_bf16 v[18:21], v[206:209], v[190:193], v[18:21]
	v_mfma_f32_16x16x32_bf16 v[10:13], v[214:217], v[190:193], v[10:13]
	v_mfma_f32_16x16x32_bf16 v[6:9], v[206:209], v[198:201], v[6:9]
	v_mfma_f32_16x16x32_bf16 v[2:5], v[214:217], v[198:201], v[2:5]
	s_add_i32 s61, 0, 0x18000
	v_add_u32_e32 v166, s61, v157
	s_barrier
	ds_read_b128 v[130:133], v166
	ds_read_b128 v[134:137], v166 offset:1024
	ds_read_b128 v[162:165], v166 offset:2048
	ds_read_b128 v[166:169], v166 offset:3072
	s_add_u32 s0, s36, 0x40000
	s_addc_u32 s1, s37, 0
	s_mov_b32 m0, s44
	ds_read_b128 v[170:173], v159 offset:32768
	ds_read_b128 v[174:177], v159 offset:33792
	ds_read_b128 v[178:181], v159 offset:34816
	ds_read_b128 v[182:185], v159 offset:35840
	ds_read_b128 v[186:189], v159 offset:36864
	ds_read_b128 v[190:193], v159 offset:37888
	ds_read_b128 v[194:197], v159 offset:38912
	ds_read_b128 v[198:201], v159 offset:39936
	global_load_lds_dwordx4 v144, s[0:1]
	s_mov_b32 m0, s45
	s_nop 0
	global_load_lds_dwordx4 v140, s[0:1]
	s_waitcnt lgkmcnt(8)
	s_waitcnt vmcnt(10)
	s_barrier
	s_waitcnt lgkmcnt(0)
	s_waitcnt lgkmcnt(0)
	v_mfma_f32_16x16x32_bf16 v[126:129], v[130:133], v[170:173], v[126:129]
	v_mfma_f32_16x16x32_bf16 v[122:125], v[162:165], v[170:173], v[122:125]
	v_mfma_f32_16x16x32_bf16 v[118:121], v[130:133], v[178:181], v[118:121]
	v_mfma_f32_16x16x32_bf16 v[110:113], v[162:165], v[178:181], v[110:113]
	v_mfma_f32_16x16x32_bf16 v[102:105], v[130:133], v[186:189], v[102:105]
	v_mfma_f32_16x16x32_bf16 v[94:97], v[162:165], v[186:189], v[94:97]
	v_mfma_f32_16x16x32_bf16 v[86:89], v[130:133], v[194:197], v[86:89]
	v_mfma_f32_16x16x32_bf16 v[78:81], v[162:165], v[194:197], v[78:81]
	v_mfma_f32_16x16x32_bf16 v[126:129], v[134:137], v[174:177], v[126:129]
	v_mfma_f32_16x16x32_bf16 v[122:125], v[166:169], v[174:177], v[122:125]
	v_mfma_f32_16x16x32_bf16 v[118:121], v[134:137], v[182:185], v[118:121]
	v_mfma_f32_16x16x32_bf16 v[110:113], v[166:169], v[182:185], v[110:113]
	v_mfma_f32_16x16x32_bf16 v[102:105], v[134:137], v[190:193], v[102:105]
	v_mfma_f32_16x16x32_bf16 v[94:97], v[166:169], v[190:193], v[94:97]
	v_mfma_f32_16x16x32_bf16 v[86:89], v[134:137], v[198:201], v[86:89]
	v_mfma_f32_16x16x32_bf16 v[78:81], v[166:169], v[198:201], v[78:81]
	s_barrier
	s_add_i32 s36, 0, 0x1c000
	s_add_i32 s0, s61, s41
	v_add_u32_e32 v214, s36, v157
	v_lshl_add_u64 v[154:155], v[154:155], 0, s[16:17]
	s_mov_b32 m0, s0
	ds_read_b128 v[202:205], v214
	ds_read_b128 v[206:209], v214 offset:1024
	ds_read_b128 v[210:213], v214 offset:2048
	ds_read_b128 v[214:217], v214 offset:3072
	global_load_lds_dwordx4 v[154:155], off
	v_lshl_add_u64 v[154:155], v[218:219], 0, s[16:17]
	s_add_i32 m0, s0, 0x2000
	s_nop 0
	global_load_lds_dwordx4 v[154:155], off
	s_waitcnt vmcnt(10)
	s_barrier
	s_waitcnt lgkmcnt(0)
	s_waitcnt lgkmcnt(0)
	v_mfma_f32_16x16x32_bf16 v[114:117], v[202:205], v[170:173], v[114:117]
	v_mfma_f32_16x16x32_bf16 v[106:109], v[210:213], v[170:173], v[106:109]
	v_mfma_f32_16x16x32_bf16 v[98:101], v[202:205], v[178:181], v[98:101]
	v_mfma_f32_16x16x32_bf16 v[90:93], v[210:213], v[178:181], v[90:93]
	v_mfma_f32_16x16x32_bf16 v[82:85], v[202:205], v[186:189], v[82:85]
	v_mfma_f32_16x16x32_bf16 v[74:77], v[210:213], v[186:189], v[74:77]
	v_mfma_f32_16x16x32_bf16 v[70:73], v[202:205], v[194:197], v[70:73]
	v_mfma_f32_16x16x32_bf16 v[66:69], v[210:213], v[194:197], v[66:69]
	v_mfma_f32_16x16x32_bf16 v[114:117], v[206:209], v[174:177], v[114:117]
	v_mfma_f32_16x16x32_bf16 v[106:109], v[214:217], v[174:177], v[106:109]
	v_mfma_f32_16x16x32_bf16 v[98:101], v[206:209], v[182:185], v[98:101]
	v_mfma_f32_16x16x32_bf16 v[90:93], v[214:217], v[182:185], v[90:93]
	v_mfma_f32_16x16x32_bf16 v[82:85], v[206:209], v[190:193], v[82:85]
	v_mfma_f32_16x16x32_bf16 v[74:77], v[214:217], v[190:193], v[74:77]
	v_mfma_f32_16x16x32_bf16 v[70:73], v[206:209], v[198:201], v[70:73]
	v_mfma_f32_16x16x32_bf16 v[66:69], v[214:217], v[198:201], v[66:69]
	s_mov_b32 m0, s49
	v_lshl_add_u64 v[154:155], v[220:221], 0, s[16:17]
	s_barrier
	ds_read_b128 v[170:173], v159 offset:49152
	ds_read_b128 v[174:177], v159 offset:50176
	ds_read_b128 v[178:181], v159 offset:51200
	ds_read_b128 v[182:185], v159 offset:52224
	ds_read_b128 v[186:189], v159 offset:53248
	ds_read_b128 v[190:193], v159 offset:54272
	ds_read_b128 v[194:197], v159 offset:55296
	ds_read_b128 v[198:201], v159 offset:56320
	global_load_lds_dwordx4 v[154:155], off
	v_lshl_add_u64 v[154:155], v[222:223], 0, s[16:17]
	s_mov_b32 m0, s51
	s_nop 0
	global_load_lds_dwordx4 v[154:155], off
	s_waitcnt vmcnt(10)
	s_barrier
	s_waitcnt lgkmcnt(0)
	s_waitcnt lgkmcnt(0)
	v_mfma_f32_16x16x32_bf16 v[62:65], v[130:133], v[170:173], v[62:65]
	v_mfma_f32_16x16x32_bf16 v[58:61], v[162:165], v[170:173], v[58:61]
	v_mfma_f32_16x16x32_bf16 v[54:57], v[130:133], v[178:181], v[54:57]
	v_mfma_f32_16x16x32_bf16 v[46:49], v[162:165], v[178:181], v[46:49]
	v_mfma_f32_16x16x32_bf16 v[38:41], v[130:133], v[186:189], v[38:41]
	v_mfma_f32_16x16x32_bf16 v[30:33], v[162:165], v[186:189], v[30:33]
	v_mfma_f32_16x16x32_bf16 v[22:25], v[130:133], v[194:197], v[22:25]
	v_mfma_f32_16x16x32_bf16 v[14:17], v[162:165], v[194:197], v[14:17]
	v_mfma_f32_16x16x32_bf16 v[62:65], v[134:137], v[174:177], v[62:65]
	v_mfma_f32_16x16x32_bf16 v[58:61], v[166:169], v[174:177], v[58:61]
	v_mfma_f32_16x16x32_bf16 v[54:57], v[134:137], v[182:185], v[54:57]
	v_mfma_f32_16x16x32_bf16 v[46:49], v[166:169], v[182:185], v[46:49]
	v_mfma_f32_16x16x32_bf16 v[38:41], v[134:137], v[190:193], v[38:41]
	v_mfma_f32_16x16x32_bf16 v[30:33], v[166:169], v[190:193], v[30:33]
	v_mfma_f32_16x16x32_bf16 v[22:25], v[134:137], v[198:201], v[22:25]
	v_mfma_f32_16x16x32_bf16 v[14:17], v[166:169], v[198:201], v[14:17]
	s_barrier
	s_add_u32 s0, s34, 0x40080
	s_addc_u32 s1, s35, 0
	s_add_i32 s34, s36, s41
	s_mov_b32 m0, s34
	s_nop 0
	global_load_lds_dwordx4 v142, s[0:1]
	v_lshl_add_u64 v[130:131], s[0:1], 0, v[138:139]
	s_add_i32 m0, s34, 0x2000
	s_nop 0
	global_load_lds_dwordx4 v[130:131], off
	s_waitcnt vmcnt(10)
	s_barrier
	v_mfma_f32_16x16x32_bf16 v[50:53], v[202:205], v[170:173], v[50:53]
	v_mfma_f32_16x16x32_bf16 v[42:45], v[210:213], v[170:173], v[42:45]
	v_mfma_f32_16x16x32_bf16 v[34:37], v[202:205], v[178:181], v[34:37]
	v_mfma_f32_16x16x32_bf16 v[26:29], v[210:213], v[178:181], v[26:29]
	v_mfma_f32_16x16x32_bf16 v[18:21], v[202:205], v[186:189], v[18:21]
	v_mfma_f32_16x16x32_bf16 v[10:13], v[210:213], v[186:189], v[10:13]
	v_mfma_f32_16x16x32_bf16 v[6:9], v[202:205], v[194:197], v[6:9]
	v_mfma_f32_16x16x32_bf16 v[2:5], v[210:213], v[194:197], v[2:5]
	v_mfma_f32_16x16x32_bf16 v[50:53], v[206:209], v[174:177], v[50:53]
	v_mfma_f32_16x16x32_bf16 v[42:45], v[214:217], v[174:177], v[42:45]
	v_mfma_f32_16x16x32_bf16 v[34:37], v[206:209], v[182:185], v[34:37]
	v_mfma_f32_16x16x32_bf16 v[26:29], v[214:217], v[182:185], v[26:29]
	v_mfma_f32_16x16x32_bf16 v[18:21], v[206:209], v[190:193], v[18:21]
	v_mfma_f32_16x16x32_bf16 v[10:13], v[214:217], v[190:193], v[10:13]
	v_mfma_f32_16x16x32_bf16 v[6:9], v[206:209], v[198:201], v[6:9]
	v_mfma_f32_16x16x32_bf16 v[2:5], v[214:217], v[198:201], v[2:5]
	s_add_i32 s60, s60, 2
	s_add_u32 s58, s58, 0x100
	s_addc_u32 s59, s59, 0
	s_add_u32 s30, s30, 0x100
	s_addc_u32 s31, s31, 0
	s_cmp_gt_u32 s60, 13
	s_barrier
	s_cbranch_scc0 .LBB0_278

.LBB0_432:
	s_lshl_b32 s0, s0, 5
	s_and_b32 s45, s0, 0x60
	s_lshl_b32 s44, s1, 6
	s_lshl_b32 s28, s1, 13
	s_lshl_b32 s30, s45, 7
	s_add_u32 s0, s22, 0x780080
	s_addc_u32 s1, s23, 0
	s_add_i32 m0, s6, 0x18000
	s_waitcnt vmcnt(4)
	s_barrier
	global_load_lds_dwordx4 v138, s[0:1]
	v_lshl_add_u64 v[14:15], s[0:1], 0, v[134:135]
	s_add_i32 m0, s6, 0x1a000
	s_mov_b64 s[26:27], 0x80
	s_add_i32 s46, s6, 0x8000
	s_add_i32 s47, s6, 0xa000
	global_load_lds_dwordx4 v[14:15], off
	v_lshl_add_u64 v[4:5], v[4:5], 0, s[26:27]
	s_mov_b32 m0, s46
	s_add_u32 s0, s22, 0x7c0080
	global_load_lds_dwordx4 v[4:5], off
	v_lshl_add_u64 v[2:3], v[2:3], 0, s[26:27]
	s_mov_b32 m0, s47
	s_addc_u32 s1, s23, 0
	global_load_lds_dwordx4 v[2:3], off
	s_add_i32 m0, s6, 0x1c000
	s_nop 0
	global_load_lds_dwordx4 v138, s[0:1]
	s_add_i32 m0, s6, 0x1e000
	v_bfe_u32 v133, v6, 4, 2
	global_load_lds_dwordx4 v134, s[0:1]
	v_and_b32_e32 v131, 15, v6
	v_lshlrev_b32_e32 v2, 4, v133
	v_lshlrev_b32_e32 v3, 2, v6
	v_lshl_or_b32 v2, v131, 6, v2
	v_and_b32_e32 v3, 32, v3
	v_bitop3_b32 v4, v2, s28, v3 bitop3:0xde
	v_bitop3_b32 v151, v2, s30, v3 bitop3:0xde
	v_lshlrev_b32_e32 v2, 14, v7
	v_and_b32_e32 v2, 0xffff8000, v2
	v_lshl_add_u32 v2, v8, 11, v2
	v_and_b32_e32 v3, 1, v7
	v_lshl_or_b32 v2, v3, 6, v2
	v_lshl_add_u32 v142, v9, 1, v2
	v_lshlrev_b32_e32 v2, 14, v11
	v_and_b32_e32 v2, 0xffff8000, v2
	s_waitcnt vmcnt(6)
	v_lshl_add_u32 v2, v10, 11, v2
	v_and_b32_e32 v3, 1, v11
	s_add_i32 s52, 0, 0x10000
	v_lshl_or_b32 v2, v3, 6, v2
	v_add_u32_e32 v152, s52, v151
	s_add_i32 s54, 0, 0x14000
	s_add_i32 s52, s52, s5
	s_mov_b32 s48, 0x18000
	s_mov_b32 s49, 0x8000
	v_mov_b32_e32 v143, v139
	v_lshl_add_u32 v144, v12, 1, v2
	v_mov_b32_e32 v145, v139
	v_add_u32_e32 v153, 0, v4
	v_add_u32_e32 v154, s54, v151
	s_mov_b32 s28, 0x3fd744fd
	s_add_i32 s50, s6, 0xc000
	s_add_i32 s51, s6, 0xe000
	s_add_i32 s53, s52, 0x2000
	s_add_i32 s54, s54, s5
	s_mov_b32 s59, s2
	s_mov_b64 s[34:35], s[8:9]
	s_mov_b32 s55, 0
	s_barrier
.LBB0_433:
	s_add_i32 s55, s55, 1
	s_mov_b64 s[0:1], s[14:15]
	s_lshr_b32 s14, s55, 2
	s_mul_i32 s14, s14, s74
	s_mov_b64 s[36:37], s[34:35]
	s_mov_b32 s35, s56
	s_add_i32 s56, s14, s2
	s_cmpk_lt_i32 s56, 0x100
	s_cselect_b64 s[38:39], -1, 0
	s_cmpk_gt_i32 s56, 0xff
	s_mov_b32 s34, s57
	s_cselect_b64 s[30:31], -1, 0
	s_and_b32 s57, s55, 3
	s_and_b64 s[14:15], s[38:39], exec
	s_cselect_b32 s14, s56, s35
	s_cselect_b32 s34, s57, s34
	s_ashr_i32 s15, s14, 31
	s_lshl_b64 s[14:15], s[14:15], 19
	s_add_u32 s14, s20, s14
	s_addc_u32 s15, s21, s15
	s_and_b64 s[40:41], s[38:39], exec
	s_cselect_b32 s60, s15, s1
	s_cselect_b32 s61, s14, s0
	s_ashr_i32 s35, s34, 31
	s_lshl_b64 s[34:35], s[34:35], 19
	s_add_u32 s34, s8, s34
	s_addc_u32 s35, s9, s35
	s_and_b64 s[38:39], s[38:39], exec
	s_cselect_b32 s62, s35, s37
	s_cselect_b32 s63, s34, s36
	s_add_u32 s66, s36, 0x100
	s_addc_u32 s67, s37, 0
	s_add_u32 s36, s0, 0x40080
	s_addc_u32 s37, s1, 0
	s_mov_b32 s69, -2
	s_waitcnt vmcnt(0)
	ds_read_b128 v[146:149], v152
	ds_read_b128 v[156:159], v152 offset:1024
	ds_read_b128 v[160:163], v152 offset:2048
	ds_read_b128 v[164:167], v152 offset:3072
	s_add_u32 s0, s36, 0xfffc0080
	s_addc_u32 s1, s37, -1
	s_cmp_eq_u32 s69, 12
	s_cselect_b32 s41, s60, s1
	s_cselect_b32 s40, s61, s0
	s_cselect_b32 s39, s62, s67
	s_cselect_b32 s38, s63, s66
	s_mov_b32 m0, s50
	ds_read_b128 v[168:171], v153
	ds_read_b128 v[172:175], v153 offset:1024
	ds_read_b128 v[176:179], v153 offset:2048
	ds_read_b128 v[180:183], v153 offset:3072
	ds_read_b128 v[184:187], v153 offset:4096
	ds_read_b128 v[188:191], v153 offset:5120
	ds_read_b128 v[192:195], v153 offset:6144
	ds_read_b128 v[196:199], v153 offset:7168
	global_load_lds_dwordx4 v144, s[36:37]
	s_mov_b32 m0, s51
	s_nop 0
	global_load_lds_dwordx4 v142, s[36:37]
	s_waitcnt lgkmcnt(8)
	s_waitcnt vmcnt(10)
	s_barrier
	s_waitcnt lgkmcnt(0)
	s_waitcnt lgkmcnt(0)
	v_mfma_f32_16x16x32_bf16 v[126:129], v[146:149], v[168:171], 0
	v_mfma_f32_16x16x32_bf16 v[122:125], v[160:163], v[168:171], 0
	v_mfma_f32_16x16x32_bf16 v[114:117], v[146:149], v[176:179], 0
	v_mfma_f32_16x16x32_bf16 v[106:109], v[160:163], v[176:179], 0
	v_mfma_f32_16x16x32_bf16 v[98:101], v[146:149], v[184:187], 0
	v_mfma_f32_16x16x32_bf16 v[90:93], v[160:163], v[184:187], 0
	v_mfma_f32_16x16x32_bf16 v[82:85], v[146:149], v[192:195], 0
	v_mfma_f32_16x16x32_bf16 v[74:77], v[160:163], v[192:195], 0
	v_mfma_f32_16x16x32_bf16 v[126:129], v[156:159], v[172:175], v[126:129]
	v_mfma_f32_16x16x32_bf16 v[122:125], v[164:167], v[172:175], v[122:125]
	v_mfma_f32_16x16x32_bf16 v[114:117], v[156:159], v[180:183], v[114:117]
	v_mfma_f32_16x16x32_bf16 v[106:109], v[164:167], v[180:183], v[106:109]
	v_mfma_f32_16x16x32_bf16 v[98:101], v[156:159], v[188:191], v[98:101]
	v_mfma_f32_16x16x32_bf16 v[90:93], v[164:167], v[188:191], v[90:93]
	v_mfma_f32_16x16x32_bf16 v[82:85], v[156:159], v[196:199], v[82:85]
	v_mfma_f32_16x16x32_bf16 v[74:77], v[164:167], v[196:199], v[74:77]
	s_barrier
	s_mov_b32 m0, s52
	v_lshl_add_u64 v[216:217], s[38:39], 0, v[138:139]
	ds_read_b128 v[200:203], v154
	ds_read_b128 v[204:207], v154 offset:1024
	ds_read_b128 v[208:211], v154 offset:2048
	ds_read_b128 v[212:215], v154 offset:3072
	global_load_lds_dwordx4 v[216:217], off
	v_lshl_add_u64 v[218:219], s[38:39], 0, v[134:135]
	s_mov_b32 m0, s53
	s_nop 0
	global_load_lds_dwordx4 v[218:219], off
	s_waitcnt vmcnt(10)
	s_barrier
	s_waitcnt lgkmcnt(0)
	s_waitcnt lgkmcnt(0)
	v_mfma_f32_16x16x32_bf16 v[118:121], v[200:203], v[168:171], 0
	v_mfma_f32_16x16x32_bf16 v[110:113], v[208:211], v[168:171], 0
	v_mfma_f32_16x16x32_bf16 v[102:105], v[200:203], v[176:179], 0
	v_mfma_f32_16x16x32_bf16 v[94:97], v[208:211], v[176:179], 0
	v_mfma_f32_16x16x32_bf16 v[86:89], v[200:203], v[184:187], 0
	v_mfma_f32_16x16x32_bf16 v[78:81], v[208:211], v[184:187], 0
	v_mfma_f32_16x16x32_bf16 v[70:73], v[200:203], v[192:195], 0
	v_mfma_f32_16x16x32_bf16 v[66:69], v[208:211], v[192:195], 0
	v_mfma_f32_16x16x32_bf16 v[118:121], v[204:207], v[172:175], v[118:121]
	v_mfma_f32_16x16x32_bf16 v[110:113], v[212:215], v[172:175], v[110:113]
	v_mfma_f32_16x16x32_bf16 v[102:105], v[204:207], v[180:183], v[102:105]
	v_mfma_f32_16x16x32_bf16 v[94:97], v[212:215], v[180:183], v[94:97]
	v_mfma_f32_16x16x32_bf16 v[86:89], v[204:207], v[188:191], v[86:89]
	v_mfma_f32_16x16x32_bf16 v[78:81], v[212:215], v[188:191], v[78:81]
	v_mfma_f32_16x16x32_bf16 v[70:73], v[204:207], v[196:199], v[70:73]
	v_mfma_f32_16x16x32_bf16 v[66:69], v[212:215], v[196:199], v[66:69]
	s_mov_b32 m0, s6
	v_lshl_add_u64 v[220:221], s[40:41], 0, v[140:141]
	s_barrier
	ds_read_b128 v[168:171], v153 offset:16384
	ds_read_b128 v[172:175], v153 offset:17408
	ds_read_b128 v[176:179], v153 offset:18432
	ds_read_b128 v[180:183], v153 offset:19456
	ds_read_b128 v[184:187], v153 offset:20480
	ds_read_b128 v[188:191], v153 offset:21504
	ds_read_b128 v[192:195], v153 offset:22528
	ds_read_b128 v[196:199], v153 offset:23552
	global_load_lds_dwordx4 v[220:221], off
	v_lshl_add_u64 v[222:223], s[40:41], 0, v[136:137]
	s_mov_b32 m0, s7
	s_nop 0
	global_load_lds_dwordx4 v[222:223], off
	s_waitcnt vmcnt(10)
	s_barrier
	s_waitcnt lgkmcnt(0)
	s_waitcnt lgkmcnt(0)
	v_mfma_f32_16x16x32_bf16 v[62:65], v[146:149], v[168:171], 0
	v_mfma_f32_16x16x32_bf16 v[58:61], v[160:163], v[168:171], 0
	v_mfma_f32_16x16x32_bf16 v[50:53], v[146:149], v[176:179], 0
	v_mfma_f32_16x16x32_bf16 v[42:45], v[160:163], v[176:179], 0
	v_mfma_f32_16x16x32_bf16 v[34:37], v[146:149], v[184:187], 0
	v_mfma_f32_16x16x32_bf16 v[26:29], v[160:163], v[184:187], 0
	v_mfma_f32_16x16x32_bf16 v[18:21], v[146:149], v[192:195], 0
	v_mfma_f32_16x16x32_bf16 v[10:13], v[160:163], v[192:195], 0
	v_mfma_f32_16x16x32_bf16 v[62:65], v[156:159], v[172:175], v[62:65]
	v_mfma_f32_16x16x32_bf16 v[58:61], v[164:167], v[172:175], v[58:61]
	v_mfma_f32_16x16x32_bf16 v[50:53], v[156:159], v[180:183], v[50:53]
	v_mfma_f32_16x16x32_bf16 v[42:45], v[164:167], v[180:183], v[42:45]
	v_mfma_f32_16x16x32_bf16 v[34:37], v[156:159], v[188:191], v[34:37]
	v_mfma_f32_16x16x32_bf16 v[26:29], v[164:167], v[188:191], v[26:29]
	v_mfma_f32_16x16x32_bf16 v[18:21], v[156:159], v[196:199], v[18:21]
	v_mfma_f32_16x16x32_bf16 v[10:13], v[164:167], v[196:199], v[10:13]
	s_barrier
	s_add_u32 s0, s38, 0x40000
	s_addc_u32 s1, s39, 0
	s_mov_b32 m0, s54
	s_nop 0
	global_load_lds_dwordx4 v138, s[0:1]
	s_add_i32 m0, s54, 0x2000
	s_nop 0
	global_load_lds_dwordx4 v134, s[0:1]
	s_waitcnt vmcnt(10)
	s_barrier
	v_mfma_f32_16x16x32_bf16 v[54:57], v[200:203], v[168:171], 0
	v_mfma_f32_16x16x32_bf16 v[46:49], v[208:211], v[168:171], 0
	v_mfma_f32_16x16x32_bf16 v[38:41], v[200:203], v[176:179], 0
	v_mfma_f32_16x16x32_bf16 v[30:33], v[208:211], v[176:179], 0
	v_mfma_f32_16x16x32_bf16 v[22:25], v[200:203], v[184:187], 0
	v_mfma_f32_16x16x32_bf16 v[14:17], v[208:211], v[184:187], 0
	v_mfma_f32_16x16x32_bf16 v[6:9], v[200:203], v[192:195], 0
	v_mfma_f32_16x16x32_bf16 v[2:5], v[208:211], v[192:195], 0
	v_mfma_f32_16x16x32_bf16 v[54:57], v[204:207], v[172:175], v[54:57]
	v_mfma_f32_16x16x32_bf16 v[46:49], v[212:215], v[172:175], v[46:49]
	v_mfma_f32_16x16x32_bf16 v[38:41], v[204:207], v[180:183], v[38:41]
	v_mfma_f32_16x16x32_bf16 v[30:33], v[212:215], v[180:183], v[30:33]
	v_mfma_f32_16x16x32_bf16 v[22:25], v[204:207], v[188:191], v[22:25]
	v_mfma_f32_16x16x32_bf16 v[14:17], v[212:215], v[188:191], v[14:17]
	v_mfma_f32_16x16x32_bf16 v[6:9], v[204:207], v[196:199], v[6:9]
	v_mfma_f32_16x16x32_bf16 v[2:5], v[212:215], v[196:199], v[2:5]
	s_add_i32 s70, 0, 0x18000
	v_add_u32_e32 v155, s70, v151
	s_barrier
	ds_read_b128 v[146:149], v155
	ds_read_b128 v[156:159], v155 offset:1024
	ds_read_b128 v[160:163], v155 offset:2048
	ds_read_b128 v[164:167], v155 offset:3072
	s_add_u32 s0, s40, 0x40000
	s_addc_u32 s1, s41, 0
	s_mov_b32 m0, s29
	ds_read_b128 v[168:171], v153 offset:32768
	ds_read_b128 v[172:175], v153 offset:33792
	ds_read_b128 v[176:179], v153 offset:34816
	ds_read_b128 v[180:183], v153 offset:35840
	ds_read_b128 v[184:187], v153 offset:36864
	ds_read_b128 v[188:191], v153 offset:37888
	ds_read_b128 v[192:195], v153 offset:38912
	ds_read_b128 v[196:199], v153 offset:39936
	global_load_lds_dwordx4 v140, s[0:1]
	s_mov_b32 m0, s42
	s_nop 0
	global_load_lds_dwordx4 v136, s[0:1]
	s_waitcnt lgkmcnt(8)
	s_waitcnt vmcnt(10)
	s_barrier
	s_waitcnt lgkmcnt(0)
	s_waitcnt lgkmcnt(0)
	v_mfma_f32_16x16x32_bf16 v[126:129], v[146:149], v[168:171], v[126:129]
	v_mfma_f32_16x16x32_bf16 v[122:125], v[160:163], v[168:171], v[122:125]
	v_mfma_f32_16x16x32_bf16 v[114:117], v[146:149], v[176:179], v[114:117]
	v_mfma_f32_16x16x32_bf16 v[106:109], v[160:163], v[176:179], v[106:109]
	v_mfma_f32_16x16x32_bf16 v[98:101], v[146:149], v[184:187], v[98:101]
	v_mfma_f32_16x16x32_bf16 v[90:93], v[160:163], v[184:187], v[90:93]
	v_mfma_f32_16x16x32_bf16 v[82:85], v[146:149], v[192:195], v[82:85]
	v_mfma_f32_16x16x32_bf16 v[74:77], v[160:163], v[192:195], v[74:77]
	v_mfma_f32_16x16x32_bf16 v[126:129], v[156:159], v[172:175], v[126:129]
	v_mfma_f32_16x16x32_bf16 v[122:125], v[164:167], v[172:175], v[122:125]
	v_mfma_f32_16x16x32_bf16 v[114:117], v[156:159], v[180:183], v[114:117]
	v_mfma_f32_16x16x32_bf16 v[106:109], v[164:167], v[180:183], v[106:109]
	v_mfma_f32_16x16x32_bf16 v[98:101], v[156:159], v[188:191], v[98:101]
	v_mfma_f32_16x16x32_bf16 v[90:93], v[164:167], v[188:191], v[90:93]
	v_mfma_f32_16x16x32_bf16 v[82:85], v[156:159], v[196:199], v[82:85]
	v_mfma_f32_16x16x32_bf16 v[74:77], v[164:167], v[196:199], v[74:77]
	s_barrier
	s_add_i32 s40, 0, 0x1c000
	s_add_i32 s0, s70, s5
	v_add_u32_e32 v155, s40, v151
	v_lshl_add_u64 v[216:217], v[216:217], 0, s[26:27]
	s_mov_b32 m0, s0
	ds_read_b128 v[200:203], v155
	ds_read_b128 v[204:207], v155 offset:1024
	ds_read_b128 v[208:211], v155 offset:2048
	ds_read_b128 v[212:215], v155 offset:3072
	global_load_lds_dwordx4 v[216:217], off
	v_lshl_add_u64 v[216:217], v[218:219], 0, s[26:27]
	s_add_i32 m0, s0, 0x2000
	s_nop 0
	global_load_lds_dwordx4 v[216:217], off
	s_waitcnt vmcnt(10)
	s_barrier
	s_waitcnt lgkmcnt(0)
	s_waitcnt lgkmcnt(0)
	v_mfma_f32_16x16x32_bf16 v[118:121], v[200:203], v[168:171], v[118:121]
	v_mfma_f32_16x16x32_bf16 v[110:113], v[208:211], v[168:171], v[110:113]
	v_mfma_f32_16x16x32_bf16 v[102:105], v[200:203], v[176:179], v[102:105]
	v_mfma_f32_16x16x32_bf16 v[94:97], v[208:211], v[176:179], v[94:97]
	v_mfma_f32_16x16x32_bf16 v[86:89], v[200:203], v[184:187], v[86:89]
	v_mfma_f32_16x16x32_bf16 v[78:81], v[208:211], v[184:187], v[78:81]
	v_mfma_f32_16x16x32_bf16 v[70:73], v[200:203], v[192:195], v[70:73]
	v_mfma_f32_16x16x32_bf16 v[66:69], v[208:211], v[192:195], v[66:69]
	v_mfma_f32_16x16x32_bf16 v[118:121], v[204:207], v[172:175], v[118:121]
	v_mfma_f32_16x16x32_bf16 v[110:113], v[212:215], v[172:175], v[110:113]
	v_mfma_f32_16x16x32_bf16 v[102:105], v[204:207], v[180:183], v[102:105]
	v_mfma_f32_16x16x32_bf16 v[94:97], v[212:215], v[180:183], v[94:97]
	v_mfma_f32_16x16x32_bf16 v[86:89], v[204:207], v[188:191], v[86:89]
	v_mfma_f32_16x16x32_bf16 v[78:81], v[212:215], v[188:191], v[78:81]
	v_mfma_f32_16x16x32_bf16 v[70:73], v[204:207], v[196:199], v[70:73]
	v_mfma_f32_16x16x32_bf16 v[66:69], v[212:215], v[196:199], v[66:69]
	s_mov_b32 m0, s46
	v_lshl_add_u64 v[216:217], v[220:221], 0, s[26:27]
	s_barrier
	ds_read_b128 v[168:171], v153 offset:49152
	ds_read_b128 v[172:175], v153 offset:50176
	ds_read_b128 v[176:179], v153 offset:51200
	ds_read_b128 v[180:183], v153 offset:52224
	ds_read_b128 v[184:187], v153 offset:53248
	ds_read_b128 v[188:191], v153 offset:54272
	ds_read_b128 v[192:195], v153 offset:55296
	ds_read_b128 v[196:199], v153 offset:56320
	global_load_lds_dwordx4 v[216:217], off
	v_lshl_add_u64 v[216:217], v[222:223], 0, s[26:27]
	s_mov_b32 m0, s47
	s_nop 0
	global_load_lds_dwordx4 v[216:217], off
	s_waitcnt vmcnt(10)
	s_barrier
	s_waitcnt lgkmcnt(0)
	s_waitcnt lgkmcnt(0)
	v_mfma_f32_16x16x32_bf16 v[62:65], v[146:149], v[168:171], v[62:65]
	v_mfma_f32_16x16x32_bf16 v[58:61], v[160:163], v[168:171], v[58:61]
	v_mfma_f32_16x16x32_bf16 v[50:53], v[146:149], v[176:179], v[50:53]
	v_mfma_f32_16x16x32_bf16 v[42:45], v[160:163], v[176:179], v[42:45]
	v_mfma_f32_16x16x32_bf16 v[34:37], v[146:149], v[184:187], v[34:37]
	v_mfma_f32_16x16x32_bf16 v[26:29], v[160:163], v[184:187], v[26:29]
	v_mfma_f32_16x16x32_bf16 v[18:21], v[146:149], v[192:195], v[18:21]
	v_mfma_f32_16x16x32_bf16 v[10:13], v[160:163], v[192:195], v[10:13]
	v_mfma_f32_16x16x32_bf16 v[62:65], v[156:159], v[172:175], v[62:65]
	v_mfma_f32_16x16x32_bf16 v[58:61], v[164:167], v[172:175], v[58:61]
	v_mfma_f32_16x16x32_bf16 v[50:53], v[156:159], v[180:183], v[50:53]
	v_mfma_f32_16x16x32_bf16 v[42:45], v[164:167], v[180:183], v[42:45]
	v_mfma_f32_16x16x32_bf16 v[34:37], v[156:159], v[188:191], v[34:37]
	v_mfma_f32_16x16x32_bf16 v[26:29], v[164:167], v[188:191], v[26:29]
	v_mfma_f32_16x16x32_bf16 v[18:21], v[156:159], v[196:199], v[18:21]
	v_mfma_f32_16x16x32_bf16 v[10:13], v[164:167], v[196:199], v[10:13]
	s_barrier
	s_add_u32 s0, s38, 0x40080
	s_addc_u32 s1, s39, 0
	s_add_i32 s38, s40, s5
	s_mov_b32 m0, s38
	s_nop 0
	global_load_lds_dwordx4 v138, s[0:1]
	s_add_i32 m0, s38, 0x2000
	s_nop 0
	global_load_lds_dwordx4 v134, s[0:1]
	s_waitcnt vmcnt(10)
	s_barrier
	v_mfma_f32_16x16x32_bf16 v[54:57], v[200:203], v[168:171], v[54:57]
	v_mfma_f32_16x16x32_bf16 v[46:49], v[208:211], v[168:171], v[46:49]
	v_mfma_f32_16x16x32_bf16 v[38:41], v[200:203], v[176:179], v[38:41]
	v_mfma_f32_16x16x32_bf16 v[30:33], v[208:211], v[176:179], v[30:33]
	v_mfma_f32_16x16x32_bf16 v[22:25], v[200:203], v[184:187], v[22:25]
	v_mfma_f32_16x16x32_bf16 v[14:17], v[208:211], v[184:187], v[14:17]
	v_mfma_f32_16x16x32_bf16 v[6:9], v[200:203], v[192:195], v[6:9]
	v_mfma_f32_16x16x32_bf16 v[2:5], v[208:211], v[192:195], v[2:5]
	v_mfma_f32_16x16x32_bf16 v[54:57], v[204:207], v[172:175], v[54:57]
	v_mfma_f32_16x16x32_bf16 v[46:49], v[212:215], v[172:175], v[46:49]
	v_mfma_f32_16x16x32_bf16 v[38:41], v[204:207], v[180:183], v[38:41]
	v_mfma_f32_16x16x32_bf16 v[30:33], v[212:215], v[180:183], v[30:33]
	v_mfma_f32_16x16x32_bf16 v[22:25], v[204:207], v[188:191], v[22:25]
	v_mfma_f32_16x16x32_bf16 v[14:17], v[212:215], v[188:191], v[14:17]
	v_mfma_f32_16x16x32_bf16 v[6:9], v[204:207], v[196:199], v[6:9]
	v_mfma_f32_16x16x32_bf16 v[2:5], v[212:215], v[196:199], v[2:5]
	s_add_i32 s69, s69, 2
	s_add_u32 s66, s66, 0x100
	s_addc_u32 s67, s67, 0
	s_add_u32 s36, s36, 0x100
	s_addc_u32 s37, s37, 0
	s_cmp_gt_u32 s69, 13
	s_barrier
	s_cbranch_scc1 .Lpeel_exit_1
.LBB0_434:
	ds_read_b128 v[146:149], v152
	ds_read_b128 v[156:159], v152 offset:1024
	ds_read_b128 v[160:163], v152 offset:2048
	ds_read_b128 v[164:167], v152 offset:3072
	s_add_u32 s0, s36, 0xfffc0080
	s_addc_u32 s1, s37, -1
	s_cmp_eq_u32 s69, 12
	s_cselect_b32 s41, s60, s1
	s_cselect_b32 s40, s61, s0
	s_cselect_b32 s39, s62, s67
	s_cselect_b32 s38, s63, s66
	s_mov_b32 m0, s50
	ds_read_b128 v[168:171], v153
	ds_read_b128 v[172:175], v153 offset:1024
	ds_read_b128 v[176:179], v153 offset:2048
	ds_read_b128 v[180:183], v153 offset:3072
	ds_read_b128 v[184:187], v153 offset:4096
	ds_read_b128 v[188:191], v153 offset:5120
	ds_read_b128 v[192:195], v153 offset:6144
	ds_read_b128 v[196:199], v153 offset:7168
	global_load_lds_dwordx4 v144, s[36:37]
	s_mov_b32 m0, s51
	s_nop 0
	global_load_lds_dwordx4 v142, s[36:37]
	s_waitcnt lgkmcnt(8)
	s_waitcnt vmcnt(10)
	s_barrier
	s_waitcnt lgkmcnt(0)
	s_waitcnt lgkmcnt(0)
	v_mfma_f32_16x16x32_bf16 v[126:129], v[146:149], v[168:171], v[126:129]
	v_mfma_f32_16x16x32_bf16 v[122:125], v[160:163], v[168:171], v[122:125]
	v_mfma_f32_16x16x32_bf16 v[114:117], v[146:149], v[176:179], v[114:117]
	v_mfma_f32_16x16x32_bf16 v[106:109], v[160:163], v[176:179], v[106:109]
	v_mfma_f32_16x16x32_bf16 v[98:101], v[146:149], v[184:187], v[98:101]
	v_mfma_f32_16x16x32_bf16 v[90:93], v[160:163], v[184:187], v[90:93]
	v_mfma_f32_16x16x32_bf16 v[82:85], v[146:149], v[192:195], v[82:85]
	v_mfma_f32_16x16x32_bf16 v[74:77], v[160:163], v[192:195], v[74:77]
	v_mfma_f32_16x16x32_bf16 v[126:129], v[156:159], v[172:175], v[126:129]
	v_mfma_f32_16x16x32_bf16 v[122:125], v[164:167], v[172:175], v[122:125]
	v_mfma_f32_16x16x32_bf16 v[114:117], v[156:159], v[180:183], v[114:117]
	v_mfma_f32_16x16x32_bf16 v[106:109], v[164:167], v[180:183], v[106:109]
	v_mfma_f32_16x16x32_bf16 v[98:101], v[156:159], v[188:191], v[98:101]
	v_mfma_f32_16x16x32_bf16 v[90:93], v[164:167], v[188:191], v[90:93]
	v_mfma_f32_16x16x32_bf16 v[82:85], v[156:159], v[196:199], v[82:85]
	v_mfma_f32_16x16x32_bf16 v[74:77], v[164:167], v[196:199], v[74:77]
	s_barrier
	s_mov_b32 m0, s52
	v_lshl_add_u64 v[216:217], s[38:39], 0, v[138:139]
	ds_read_b128 v[200:203], v154
	ds_read_b128 v[204:207], v154 offset:1024
	ds_read_b128 v[208:211], v154 offset:2048
	ds_read_b128 v[212:215], v154 offset:3072
	global_load_lds_dwordx4 v[216:217], off
	v_lshl_add_u64 v[218:219], s[38:39], 0, v[134:135]
	s_mov_b32 m0, s53
	s_nop 0
	global_load_lds_dwordx4 v[218:219], off
	s_waitcnt vmcnt(10)
	s_barrier
	s_waitcnt lgkmcnt(0)
	s_waitcnt lgkmcnt(0)
	v_mfma_f32_16x16x32_bf16 v[118:121], v[200:203], v[168:171], v[118:121]
	v_mfma_f32_16x16x32_bf16 v[110:113], v[208:211], v[168:171], v[110:113]
	v_mfma_f32_16x16x32_bf16 v[102:105], v[200:203], v[176:179], v[102:105]
	v_mfma_f32_16x16x32_bf16 v[94:97], v[208:211], v[176:179], v[94:97]
	v_mfma_f32_16x16x32_bf16 v[86:89], v[200:203], v[184:187], v[86:89]
	v_mfma_f32_16x16x32_bf16 v[78:81], v[208:211], v[184:187], v[78:81]
	v_mfma_f32_16x16x32_bf16 v[70:73], v[200:203], v[192:195], v[70:73]
	v_mfma_f32_16x16x32_bf16 v[66:69], v[208:211], v[192:195], v[66:69]
	v_mfma_f32_16x16x32_bf16 v[118:121], v[204:207], v[172:175], v[118:121]
	v_mfma_f32_16x16x32_bf16 v[110:113], v[212:215], v[172:175], v[110:113]
	v_mfma_f32_16x16x32_bf16 v[102:105], v[204:207], v[180:183], v[102:105]
	v_mfma_f32_16x16x32_bf16 v[94:97], v[212:215], v[180:183], v[94:97]
	v_mfma_f32_16x16x32_bf16 v[86:89], v[204:207], v[188:191], v[86:89]
	v_mfma_f32_16x16x32_bf16 v[78:81], v[212:215], v[188:191], v[78:81]
	v_mfma_f32_16x16x32_bf16 v[70:73], v[204:207], v[196:199], v[70:73]
	v_mfma_f32_16x16x32_bf16 v[66:69], v[212:215], v[196:199], v[66:69]
	s_mov_b32 m0, s6
	v_lshl_add_u64 v[220:221], s[40:41], 0, v[140:141]
	s_barrier
	ds_read_b128 v[168:171], v153 offset:16384
	ds_read_b128 v[172:175], v153 offset:17408
	ds_read_b128 v[176:179], v153 offset:18432
	ds_read_b128 v[180:183], v153 offset:19456
	ds_read_b128 v[184:187], v153 offset:20480
	ds_read_b128 v[188:191], v153 offset:21504
	ds_read_b128 v[192:195], v153 offset:22528
	ds_read_b128 v[196:199], v153 offset:23552
	global_load_lds_dwordx4 v[220:221], off
	v_lshl_add_u64 v[222:223], s[40:41], 0, v[136:137]
	s_mov_b32 m0, s7
	s_nop 0
	global_load_lds_dwordx4 v[222:223], off
	s_waitcnt vmcnt(10)
	s_barrier
	s_waitcnt lgkmcnt(0)
	s_waitcnt lgkmcnt(0)
	v_mfma_f32_16x16x32_bf16 v[62:65], v[146:149], v[168:171], v[62:65]
	v_mfma_f32_16x16x32_bf16 v[58:61], v[160:163], v[168:171], v[58:61]
	v_mfma_f32_16x16x32_bf16 v[50:53], v[146:149], v[176:179], v[50:53]
	v_mfma_f32_16x16x32_bf16 v[42:45], v[160:163], v[176:179], v[42:45]
	v_mfma_f32_16x16x32_bf16 v[34:37], v[146:149], v[184:187], v[34:37]
	v_mfma_f32_16x16x32_bf16 v[26:29], v[160:163], v[184:187], v[26:29]
	v_mfma_f32_16x16x32_bf16 v[18:21], v[146:149], v[192:195], v[18:21]
	v_mfma_f32_16x16x32_bf16 v[10:13], v[160:163], v[192:195], v[10:13]
	v_mfma_f32_16x16x32_bf16 v[62:65], v[156:159], v[172:175], v[62:65]
	v_mfma_f32_16x16x32_bf16 v[58:61], v[164:167], v[172:175], v[58:61]
	v_mfma_f32_16x16x32_bf16 v[50:53], v[156:159], v[180:183], v[50:53]
	v_mfma_f32_16x16x32_bf16 v[42:45], v[164:167], v[180:183], v[42:45]
	v_mfma_f32_16x16x32_bf16 v[34:37], v[156:159], v[188:191], v[34:37]
	v_mfma_f32_16x16x32_bf16 v[26:29], v[164:167], v[188:191], v[26:29]
	v_mfma_f32_16x16x32_bf16 v[18:21], v[156:159], v[196:199], v[18:21]
	v_mfma_f32_16x16x32_bf16 v[10:13], v[164:167], v[196:199], v[10:13]
	s_barrier
	s_add_u32 s0, s38, 0x40000
	s_addc_u32 s1, s39, 0
	s_mov_b32 m0, s54
	s_nop 0
	global_load_lds_dwordx4 v138, s[0:1]
	s_add_i32 m0, s54, 0x2000
	s_nop 0
	global_load_lds_dwordx4 v134, s[0:1]
	s_waitcnt vmcnt(10)
	s_barrier
	v_mfma_f32_16x16x32_bf16 v[54:57], v[200:203], v[168:171], v[54:57]
	v_mfma_f32_16x16x32_bf16 v[46:49], v[208:211], v[168:171], v[46:49]
	v_mfma_f32_16x16x32_bf16 v[38:41], v[200:203], v[176:179], v[38:41]
	v_mfma_f32_16x16x32_bf16 v[30:33], v[208:211], v[176:179], v[30:33]
	v_mfma_f32_16x16x32_bf16 v[22:25], v[200:203], v[184:187], v[22:25]
	v_mfma_f32_16x16x32_bf16 v[14:17], v[208:211], v[184:187], v[14:17]
	v_mfma_f32_16x16x32_bf16 v[6:9], v[200:203], v[192:195], v[6:9]
	v_mfma_f32_16x16x32_bf16 v[2:5], v[208:211], v[192:195], v[2:5]
	v_mfma_f32_16x16x32_bf16 v[54:57], v[204:207], v[172:175], v[54:57]
	v_mfma_f32_16x16x32_bf16 v[46:49], v[212:215], v[172:175], v[46:49]
	v_mfma_f32_16x16x32_bf16 v[38:41], v[204:207], v[180:183], v[38:41]
	v_mfma_f32_16x16x32_bf16 v[30:33], v[212:215], v[180:183], v[30:33]
	v_mfma_f32_16x16x32_bf16 v[22:25], v[204:207], v[188:191], v[22:25]
	v_mfma_f32_16x16x32_bf16 v[14:17], v[212:215], v[188:191], v[14:17]
	v_mfma_f32_16x16x32_bf16 v[6:9], v[204:207], v[196:199], v[6:9]
	v_mfma_f32_16x16x32_bf16 v[2:5], v[212:215], v[196:199], v[2:5]
	s_add_i32 s70, 0, 0x18000
	v_add_u32_e32 v155, s70, v151
	s_barrier
	ds_read_b128 v[146:149], v155
	ds_read_b128 v[156:159], v155 offset:1024
	ds_read_b128 v[160:163], v155 offset:2048
	ds_read_b128 v[164:167], v155 offset:3072
	s_add_u32 s0, s40, 0x40000
	s_addc_u32 s1, s41, 0
	s_mov_b32 m0, s29
	ds_read_b128 v[168:171], v153 offset:32768
	ds_read_b128 v[172:175], v153 offset:33792
	ds_read_b128 v[176:179], v153 offset:34816
	ds_read_b128 v[180:183], v153 offset:35840
	ds_read_b128 v[184:187], v153 offset:36864
	ds_read_b128 v[188:191], v153 offset:37888
	ds_read_b128 v[192:195], v153 offset:38912
	ds_read_b128 v[196:199], v153 offset:39936
	global_load_lds_dwordx4 v140, s[0:1]
	s_mov_b32 m0, s42
	s_nop 0
	global_load_lds_dwordx4 v136, s[0:1]
	s_waitcnt lgkmcnt(8)
	s_waitcnt vmcnt(10)
	s_barrier
	s_waitcnt lgkmcnt(0)
	s_waitcnt lgkmcnt(0)
	v_mfma_f32_16x16x32_bf16 v[126:129], v[146:149], v[168:171], v[126:129]
	v_mfma_f32_16x16x32_bf16 v[122:125], v[160:163], v[168:171], v[122:125]
	v_mfma_f32_16x16x32_bf16 v[114:117], v[146:149], v[176:179], v[114:117]
	v_mfma_f32_16x16x32_bf16 v[106:109], v[160:163], v[176:179], v[106:109]
	v_mfma_f32_16x16x32_bf16 v[98:101], v[146:149], v[184:187], v[98:101]
	v_mfma_f32_16x16x32_bf16 v[90:93], v[160:163], v[184:187], v[90:93]
	v_mfma_f32_16x16x32_bf16 v[82:85], v[146:149], v[192:195], v[82:85]
	v_mfma_f32_16x16x32_bf16 v[74:77], v[160:163], v[192:195], v[74:77]
	v_mfma_f32_16x16x32_bf16 v[126:129], v[156:159], v[172:175], v[126:129]
	v_mfma_f32_16x16x32_bf16 v[122:125], v[164:167], v[172:175], v[122:125]
	v_mfma_f32_16x16x32_bf16 v[114:117], v[156:159], v[180:183], v[114:117]
	v_mfma_f32_16x16x32_bf16 v[106:109], v[164:167], v[180:183], v[106:109]
	v_mfma_f32_16x16x32_bf16 v[98:101], v[156:159], v[188:191], v[98:101]
	v_mfma_f32_16x16x32_bf16 v[90:93], v[164:167], v[188:191], v[90:93]
	v_mfma_f32_16x16x32_bf16 v[82:85], v[156:159], v[196:199], v[82:85]
	v_mfma_f32_16x16x32_bf16 v[74:77], v[164:167], v[196:199], v[74:77]
	s_barrier
	s_add_i32 s40, 0, 0x1c000
	s_add_i32 s0, s70, s5
	v_add_u32_e32 v155, s40, v151
	v_lshl_add_u64 v[216:217], v[216:217], 0, s[26:27]
	s_mov_b32 m0, s0
	ds_read_b128 v[200:203], v155
	ds_read_b128 v[204:207], v155 offset:1024
	ds_read_b128 v[208:211], v155 offset:2048
	ds_read_b128 v[212:215], v155 offset:3072
	global_load_lds_dwordx4 v[216:217], off
	v_lshl_add_u64 v[216:217], v[218:219], 0, s[26:27]
	s_add_i32 m0, s0, 0x2000
	s_nop 0
	global_load_lds_dwordx4 v[216:217], off
	s_waitcnt vmcnt(10)
	s_barrier
	s_waitcnt lgkmcnt(0)
	s_waitcnt lgkmcnt(0)
	v_mfma_f32_16x16x32_bf16 v[118:121], v[200:203], v[168:171], v[118:121]
	v_mfma_f32_16x16x32_bf16 v[110:113], v[208:211], v[168:171], v[110:113]
	v_mfma_f32_16x16x32_bf16 v[102:105], v[200:203], v[176:179], v[102:105]
	v_mfma_f32_16x16x32_bf16 v[94:97], v[208:211], v[176:179], v[94:97]
	v_mfma_f32_16x16x32_bf16 v[86:89], v[200:203], v[184:187], v[86:89]
	v_mfma_f32_16x16x32_bf16 v[78:81], v[208:211], v[184:187], v[78:81]
	v_mfma_f32_16x16x32_bf16 v[70:73], v[200:203], v[192:195], v[70:73]
	v_mfma_f32_16x16x32_bf16 v[66:69], v[208:211], v[192:195], v[66:69]
	v_mfma_f32_16x16x32_bf16 v[118:121], v[204:207], v[172:175], v[118:121]
	v_mfma_f32_16x16x32_bf16 v[110:113], v[212:215], v[172:175], v[110:113]
	v_mfma_f32_16x16x32_bf16 v[102:105], v[204:207], v[180:183], v[102:105]
	v_mfma_f32_16x16x32_bf16 v[94:97], v[212:215], v[180:183], v[94:97]
	v_mfma_f32_16x16x32_bf16 v[86:89], v[204:207], v[188:191], v[86:89]
	v_mfma_f32_16x16x32_bf16 v[78:81], v[212:215], v[188:191], v[78:81]
	v_mfma_f32_16x16x32_bf16 v[70:73], v[204:207], v[196:199], v[70:73]
	v_mfma_f32_16x16x32_bf16 v[66:69], v[212:215], v[196:199], v[66:69]
	s_mov_b32 m0, s46
	v_lshl_add_u64 v[216:217], v[220:221], 0, s[26:27]
	s_barrier
	ds_read_b128 v[168:171], v153 offset:49152
	ds_read_b128 v[172:175], v153 offset:50176
	ds_read_b128 v[176:179], v153 offset:51200
	ds_read_b128 v[180:183], v153 offset:52224
	ds_read_b128 v[184:187], v153 offset:53248
	ds_read_b128 v[188:191], v153 offset:54272
	ds_read_b128 v[192:195], v153 offset:55296
	ds_read_b128 v[196:199], v153 offset:56320
	global_load_lds_dwordx4 v[216:217], off
	v_lshl_add_u64 v[216:217], v[222:223], 0, s[26:27]
	s_mov_b32 m0, s47
	s_nop 0
	global_load_lds_dwordx4 v[216:217], off
	s_waitcnt vmcnt(10)
	s_barrier
	s_waitcnt lgkmcnt(0)
	s_waitcnt lgkmcnt(0)
	v_mfma_f32_16x16x32_bf16 v[62:65], v[146:149], v[168:171], v[62:65]
	v_mfma_f32_16x16x32_bf16 v[58:61], v[160:163], v[168:171], v[58:61]
	v_mfma_f32_16x16x32_bf16 v[50:53], v[146:149], v[176:179], v[50:53]
	v_mfma_f32_16x16x32_bf16 v[42:45], v[160:163], v[176:179], v[42:45]
	v_mfma_f32_16x16x32_bf16 v[34:37], v[146:149], v[184:187], v[34:37]
	v_mfma_f32_16x16x32_bf16 v[26:29], v[160:163], v[184:187], v[26:29]
	v_mfma_f32_16x16x32_bf16 v[18:21], v[146:149], v[192:195], v[18:21]
	v_mfma_f32_16x16x32_bf16 v[10:13], v[160:163], v[192:195], v[10:13]
	v_mfma_f32_16x16x32_bf16 v[62:65], v[156:159], v[172:175], v[62:65]
	v_mfma_f32_16x16x32_bf16 v[58:61], v[164:167], v[172:175], v[58:61]
	v_mfma_f32_16x16x32_bf16 v[50:53], v[156:159], v[180:183], v[50:53]
	v_mfma_f32_16x16x32_bf16 v[42:45], v[164:167], v[180:183], v[42:45]
	v_mfma_f32_16x16x32_bf16 v[34:37], v[156:159], v[188:191], v[34:37]
	v_mfma_f32_16x16x32_bf16 v[26:29], v[164:167], v[188:191], v[26:29]
	v_mfma_f32_16x16x32_bf16 v[18:21], v[156:159], v[196:199], v[18:21]
	v_mfma_f32_16x16x32_bf16 v[10:13], v[164:167], v[196:199], v[10:13]
	s_barrier
	s_add_u32 s0, s38, 0x40080
	s_addc_u32 s1, s39, 0
	s_add_i32 s38, s40, s5
	s_mov_b32 m0, s38
	s_nop 0
	global_load_lds_dwordx4 v138, s[0:1]
	s_add_i32 m0, s38, 0x2000
	s_nop 0
	global_load_lds_dwordx4 v134, s[0:1]
	s_waitcnt vmcnt(10)
	s_barrier
	v_mfma_f32_16x16x32_bf16 v[54:57], v[200:203], v[168:171], v[54:57]
	v_mfma_f32_16x16x32_bf16 v[46:49], v[208:211], v[168:171], v[46:49]
	v_mfma_f32_16x16x32_bf16 v[38:41], v[200:203], v[176:179], v[38:41]
	v_mfma_f32_16x16x32_bf16 v[30:33], v[208:211], v[176:179], v[30:33]
	v_mfma_f32_16x16x32_bf16 v[22:25], v[200:203], v[184:187], v[22:25]
	v_mfma_f32_16x16x32_bf16 v[14:17], v[208:211], v[184:187], v[14:17]
	v_mfma_f32_16x16x32_bf16 v[6:9], v[200:203], v[192:195], v[6:9]
	v_mfma_f32_16x16x32_bf16 v[2:5], v[208:211], v[192:195], v[2:5]
	v_mfma_f32_16x16x32_bf16 v[54:57], v[204:207], v[172:175], v[54:57]
	v_mfma_f32_16x16x32_bf16 v[46:49], v[212:215], v[172:175], v[46:49]
	v_mfma_f32_16x16x32_bf16 v[38:41], v[204:207], v[180:183], v[38:41]
	v_mfma_f32_16x16x32_bf16 v[30:33], v[212:215], v[180:183], v[30:33]
	v_mfma_f32_16x16x32_bf16 v[22:25], v[204:207], v[188:191], v[22:25]
	v_mfma_f32_16x16x32_bf16 v[14:17], v[212:215], v[188:191], v[14:17]
	v_mfma_f32_16x16x32_bf16 v[6:9], v[204:207], v[196:199], v[6:9]
	v_mfma_f32_16x16x32_bf16 v[2:5], v[212:215], v[196:199], v[2:5]
	s_add_i32 s69, s69, 2
	s_add_u32 s66, s66, 0x100
	s_addc_u32 s67, s67, 0
	s_add_u32 s36, s36, 0x100
	s_addc_u32 s37, s37, 0
	s_cmp_gt_u32 s69, 13
	s_barrier
	s_cbranch_scc0 .LBB0_434

.LBB0_676:
	v_bfe_u32 v196, v2, 4, 2
	v_and_b32_e32 v195, 15, v2
	v_lshlrev_b32_e32 v3, 4, v196
	v_lshlrev_b32_e32 v2, 2, v2
	v_lshl_or_b32 v3, v195, 6, v3
	s_lshl_b32 s0, s8, 13
	v_and_b32_e32 v2, 32, v2
	v_bitop3_b32 v8, v3, s0, v2 bitop3:0xde
	s_lshl_b32 s0, s1, 5
	v_mov_b32_e32 v165, v163
	s_and_b32 s50, s0, 0x60
	v_lshl_add_u64 v[4:5], s[30:31], 0, v[164:165]
	v_mov_b32_e32 v167, v163
	s_lshl_b32 s0, s50, 7
	v_lshl_add_u64 v[6:7], s[30:31], 0, v[166:167]
	v_bitop3_b32 v197, v3, s0, v2 bitop3:0xde
	s_add_i32 m0, s45, 0x18000
	v_lshl_add_u64 v[2:3], v[4:5], 0, s[20:21]
	v_mov_b32_e32 v169, v163
	s_lshl_b32 s49, s8, 6
	s_waitcnt vmcnt(4)
	s_barrier
	global_load_lds_dwordx4 v[2:3], off
	v_lshl_add_u64 v[2:3], v[6:7], 0, s[20:21]
	s_add_i32 m0, s45, 0x1a000
	s_add_i32 s51, s45, 0x8000
	s_add_i32 s52, s45, 0xa000
	v_mov_b32_e32 v171, v163
	global_load_lds_dwordx4 v[2:3], off
	v_lshl_add_u64 v[2:3], s[18:19], 0, v[168:169]
	s_mov_b32 m0, s51
	s_add_u32 s0, s30, 0x20080
	global_load_lds_dwordx4 v[2:3], off
	v_lshl_add_u64 v[2:3], s[18:19], 0, v[170:171]
	s_mov_b32 m0, s52
	s_addc_u32 s1, s31, 0
	global_load_lds_dwordx4 v[2:3], off
	s_add_i32 m0, s45, 0x1c000
	s_nop 0
	global_load_lds_dwordx4 v164, s[0:1]
	s_add_i32 m0, s45, 0x1e000
	s_mov_b32 s53, 0
	global_load_lds_dwordx4 v166, s[0:1]
	s_waitcnt vmcnt(6)
	v_add_u32_e32 v169, 0, v8
	s_barrier
	s_waitcnt vmcnt(0)

.LBB0_687:
	s_ashr_i32 s0, s54, 5
	s_ashr_i32 s1, s0, 31
	s_lshl_b64 s[0:1], s[0:1], 21
	s_add_u32 s12, s4, s0
	s_addc_u32 s13, s5, s1
	s_ashr_i32 s25, s24, 31
	s_lshl_b64 s[0:1], s[24:25], 18
	s_add_u32 s12, s12, s0
	s_addc_u32 s13, s13, s1
	s_and_b64 s[0:1], s[10:11], exec
	s_cselect_b32 s25, s13, s31
	s_cselect_b32 s27, s12, s30
	v_mov_b32_e32 v173, v163
	v_mov_b32_e32 v175, v163
	s_add_u32 s29, s30, 0x100
	s_addc_u32 s55, s31, 0
	v_lshl_add_u64 v[176:177], s[18:19], 0, v[174:175]
	v_lshl_add_u64 v[178:179], s[18:19], 0, v[172:173]
	s_mov_b32 s56, -2
	s_mov_b64 s[34:35], 0
	s_add_u32 s10, s34, 0x100
	s_addc_u32 s11, s35, 0
	s_add_u32 s30, s29, s34
	s_addc_u32 s31, s55, s35
	s_cmpk_eq_i32 s34, 0x300
	s_cselect_b64 vcc, -1, 0
	s_and_b64 s[0:1], vcc, exec
	s_cselect_b32 s1, 0, s10
	s_cselect_b32 s0, 0, s11
	s_cselect_b32 s30, s27, s30
	s_cselect_b32 s31, s25, s31
	s_add_u32 s36, s14, s1
	s_addc_u32 s37, s15, s0
	s_add_i32 s1, 0, 0x10000
	v_add_u32_e32 v14, s1, v197
	ds_read_b128 v[2:5], v14
	ds_read_b128 v[6:9], v14 offset:1024
	ds_read_b128 v[10:13], v14 offset:2048
	ds_read_b128 v[14:17], v14 offset:3072
	v_cndmask_b32_e32 v162, v168, v171, vcc
	v_cndmask_b32_e32 v184, v170, v198, vcc
	v_cndmask_b32_e32 v175, v172, v199, vcc
	v_cndmask_b32_e32 v173, v174, v200, vcc
	v_lshl_add_u64 v[18:19], v[178:179], 0, s[34:35]
	s_add_i32 m0, s45, 0xc000
	ds_read_b128 v[202:205], v169
	ds_read_b128 v[206:209], v169 offset:1024
	ds_read_b128 v[210:213], v169 offset:2048
	ds_read_b128 v[214:217], v169 offset:3072
	ds_read_b128 v[218:221], v169 offset:4096
	ds_read_b128 v[222:225], v169 offset:5120
	ds_read_b128 v[226:229], v169 offset:6144
	ds_read_b128 v[230:233], v169 offset:7168
	global_load_lds_dwordx4 v[18:19], off
	v_lshl_add_u64 v[18:19], v[176:177], 0, s[34:35]
	s_add_i32 m0, s45, 0xe000
	s_nop 0
	global_load_lds_dwordx4 v[18:19], off
	s_waitcnt lgkmcnt(8)
	s_waitcnt vmcnt(10)
	s_barrier
	s_waitcnt lgkmcnt(0)
	s_waitcnt lgkmcnt(0)
	v_mfma_scale_f32_16x16x128_f8f6f4 v[158:161], v[2:9], v[202:209], 0, v188, v188 op_sel_hi:[0,0,0]
	v_mfma_scale_f32_16x16x128_f8f6f4 v[150:153], v[10:17], v[202:209], 0, v188, v188 op_sel_hi:[0,0,0]
	v_mfma_scale_f32_16x16x128_f8f6f4 v[142:145], v[2:9], v[210:217], 0, v188, v188 op_sel_hi:[0,0,0]
	v_mfma_scale_f32_16x16x128_f8f6f4 v[134:137], v[10:17], v[210:217], 0, v188, v188 op_sel_hi:[0,0,0]
	v_mfma_scale_f32_16x16x128_f8f6f4 v[126:129], v[2:9], v[218:225], 0, v188, v188 op_sel_hi:[0,0,0]
	v_mfma_scale_f32_16x16x128_f8f6f4 v[118:121], v[10:17], v[218:225], 0, v188, v188 op_sel_hi:[0,0,0]
	v_mfma_scale_f32_16x16x128_f8f6f4 v[110:113], v[2:9], v[226:233], 0, v188, v188 op_sel_hi:[0,0,0]
	v_mfma_scale_f32_16x16x128_f8f6f4 v[102:105], v[10:17], v[226:233], 0, v188, v188 op_sel_hi:[0,0,0]
	s_barrier
	s_add_i32 s0, 0, 0x14000
	s_add_i32 s1, s1, s43
	v_add_u32_e32 v30, s0, v197
	v_lshl_add_u64 v[180:181], s[30:31], 0, v[164:165]
	s_mov_b32 m0, s1
	ds_read_b128 v[18:21], v30
	ds_read_b128 v[22:25], v30 offset:1024
	ds_read_b128 v[26:29], v30 offset:2048
	ds_read_b128 v[30:33], v30 offset:3072
	global_load_lds_dwordx4 v[180:181], off
	v_lshl_add_u64 v[182:183], s[30:31], 0, v[166:167]
	s_add_i32 m0, s1, 0x2000
	s_nop 0
	global_load_lds_dwordx4 v[182:183], off
	s_waitcnt vmcnt(10)
	s_barrier
	s_waitcnt lgkmcnt(0)
	s_waitcnt lgkmcnt(0)
	v_mfma_scale_f32_16x16x128_f8f6f4 v[154:157], v[18:25], v[202:209], 0, v188, v188 op_sel_hi:[0,0,0]
	v_mfma_scale_f32_16x16x128_f8f6f4 v[146:149], v[26:33], v[202:209], 0, v188, v188 op_sel_hi:[0,0,0]
	v_mfma_scale_f32_16x16x128_f8f6f4 v[138:141], v[18:25], v[210:217], 0, v188, v188 op_sel_hi:[0,0,0]
	v_mfma_scale_f32_16x16x128_f8f6f4 v[130:133], v[26:33], v[210:217], 0, v188, v188 op_sel_hi:[0,0,0]
	v_mfma_scale_f32_16x16x128_f8f6f4 v[122:125], v[18:25], v[218:225], 0, v188, v188 op_sel_hi:[0,0,0]
	v_mfma_scale_f32_16x16x128_f8f6f4 v[114:117], v[26:33], v[218:225], 0, v188, v188 op_sel_hi:[0,0,0]
	v_mfma_scale_f32_16x16x128_f8f6f4 v[106:109], v[18:25], v[226:233], 0, v188, v188 op_sel_hi:[0,0,0]
	v_mfma_scale_f32_16x16x128_f8f6f4 v[98:101], v[26:33], v[226:233], 0, v188, v188 op_sel_hi:[0,0,0]
	s_mov_b32 m0, s45
	s_barrier
	ds_read_b128 v[202:205], v169 offset:16384
	ds_read_b128 v[206:209], v169 offset:17408
	ds_read_b128 v[210:213], v169 offset:18432
	ds_read_b128 v[214:217], v169 offset:19456
	ds_read_b128 v[218:221], v169 offset:20480
	ds_read_b128 v[222:225], v169 offset:21504
	ds_read_b128 v[226:229], v169 offset:22528
	ds_read_b128 v[230:233], v169 offset:23552
	global_load_lds_dwordx4 v162, s[36:37]
	s_mov_b32 m0, s46
	v_mov_b32_e32 v185, v163
	global_load_lds_dwordx4 v184, s[36:37]
	s_waitcnt vmcnt(10)
	s_barrier
	s_waitcnt lgkmcnt(0)
	v_lshl_add_u64 v[186:187], s[36:37], 0, v[162:163]
	v_lshl_add_u64 v[184:185], s[36:37], 0, v[184:185]
	s_waitcnt lgkmcnt(0)
	v_mfma_scale_f32_16x16x128_f8f6f4 v[94:97], v[2:9], v[202:209], 0, v188, v188 op_sel_hi:[0,0,0]
	v_mfma_scale_f32_16x16x128_f8f6f4 v[86:89], v[10:17], v[202:209], 0, v188, v188 op_sel_hi:[0,0,0]
	v_mfma_scale_f32_16x16x128_f8f6f4 v[78:81], v[2:9], v[210:217], 0, v188, v188 op_sel_hi:[0,0,0]
	v_mfma_scale_f32_16x16x128_f8f6f4 v[70:73], v[10:17], v[210:217], 0, v188, v188 op_sel_hi:[0,0,0]
	v_mfma_scale_f32_16x16x128_f8f6f4 v[62:65], v[2:9], v[218:225], 0, v188, v188 op_sel_hi:[0,0,0]
	v_mfma_scale_f32_16x16x128_f8f6f4 v[54:57], v[10:17], v[218:225], 0, v188, v188 op_sel_hi:[0,0,0]
	v_mfma_scale_f32_16x16x128_f8f6f4 v[46:49], v[2:9], v[226:233], 0, v188, v188 op_sel_hi:[0,0,0]
	v_mfma_scale_f32_16x16x128_f8f6f4 v[38:41], v[10:17], v[226:233], 0, v188, v188 op_sel_hi:[0,0,0]
	s_barrier
	s_add_u32 s34, s30, 0x20000
	s_addc_u32 s35, s31, 0
	s_add_i32 s0, s0, s43
	s_mov_b32 m0, s0
	s_nop 0
	global_load_lds_dwordx4 v164, s[34:35]
	s_add_i32 m0, s0, 0x2000
	s_nop 0
	global_load_lds_dwordx4 v166, s[34:35]
	s_waitcnt vmcnt(10)
	s_barrier
	v_mfma_scale_f32_16x16x128_f8f6f4 v[90:93], v[18:25], v[202:209], 0, v188, v188 op_sel_hi:[0,0,0]
	v_mfma_scale_f32_16x16x128_f8f6f4 v[82:85], v[26:33], v[202:209], 0, v188, v188 op_sel_hi:[0,0,0]
	v_mfma_scale_f32_16x16x128_f8f6f4 v[74:77], v[18:25], v[210:217], 0, v188, v188 op_sel_hi:[0,0,0]
	v_mfma_scale_f32_16x16x128_f8f6f4 v[66:69], v[26:33], v[210:217], 0, v188, v188 op_sel_hi:[0,0,0]
	v_mfma_scale_f32_16x16x128_f8f6f4 v[58:61], v[18:25], v[218:225], 0, v188, v188 op_sel_hi:[0,0,0]
	v_mfma_scale_f32_16x16x128_f8f6f4 v[50:53], v[26:33], v[218:225], 0, v188, v188 op_sel_hi:[0,0,0]
	v_mfma_scale_f32_16x16x128_f8f6f4 v[42:45], v[18:25], v[226:233], 0, v188, v188 op_sel_hi:[0,0,0]
	v_mfma_scale_f32_16x16x128_f8f6f4 v[34:37], v[26:33], v[226:233], 0, v188, v188 op_sel_hi:[0,0,0]
	s_add_i32 s0, 0, 0x18000
	v_add_u32_e32 v14, s0, v197
	s_barrier
	ds_read_b128 v[2:5], v14
	ds_read_b128 v[6:9], v14 offset:1024
	ds_read_b128 v[10:13], v14 offset:2048
	ds_read_b128 v[14:17], v14 offset:3072
	s_mov_b32 m0, s47
	ds_read_b128 v[18:21], v169 offset:32768
	ds_read_b128 v[22:25], v169 offset:33792
	ds_read_b128 v[26:29], v169 offset:34816
	ds_read_b128 v[30:33], v169 offset:35840
	ds_read_b128 v[202:205], v169 offset:36864
	ds_read_b128 v[206:209], v169 offset:37888
	ds_read_b128 v[210:213], v169 offset:38912
	ds_read_b128 v[214:217], v169 offset:39936
	global_load_lds_dwordx4 v175, s[36:37]
	s_mov_b32 m0, s48
	s_nop 0
	global_load_lds_dwordx4 v173, s[36:37]
	s_waitcnt lgkmcnt(8)
	s_waitcnt vmcnt(10)
	s_barrier
	s_waitcnt lgkmcnt(0)
	s_waitcnt lgkmcnt(0)
	v_mfma_scale_f32_16x16x128_f8f6f4 v[158:161], v[2:9], v[18:25], v[158:161], v188, v188 op_sel_hi:[0,0,0]
	v_mfma_scale_f32_16x16x128_f8f6f4 v[150:153], v[10:17], v[18:25], v[150:153], v188, v188 op_sel_hi:[0,0,0]
	v_mfma_scale_f32_16x16x128_f8f6f4 v[142:145], v[2:9], v[26:33], v[142:145], v188, v188 op_sel_hi:[0,0,0]
	v_mfma_scale_f32_16x16x128_f8f6f4 v[134:137], v[10:17], v[26:33], v[134:137], v188, v188 op_sel_hi:[0,0,0]
	v_mfma_scale_f32_16x16x128_f8f6f4 v[126:129], v[2:9], v[202:209], v[126:129], v188, v188 op_sel_hi:[0,0,0]
	v_mfma_scale_f32_16x16x128_f8f6f4 v[118:121], v[10:17], v[202:209], v[118:121], v188, v188 op_sel_hi:[0,0,0]
	v_mfma_scale_f32_16x16x128_f8f6f4 v[110:113], v[2:9], v[210:217], v[110:113], v188, v188 op_sel_hi:[0,0,0]
	v_mfma_scale_f32_16x16x128_f8f6f4 v[102:105], v[10:17], v[210:217], v[102:105], v188, v188 op_sel_hi:[0,0,0]
	s_barrier
	s_add_i32 s34, 0, 0x1c000
	s_add_i32 s0, s0, s43
	v_add_u32_e32 v162, s34, v197
	v_lshl_add_u64 v[180:181], v[180:181], 0, s[20:21]
	s_mov_b32 m0, s0
	ds_read_b128 v[218:221], v162
	ds_read_b128 v[222:225], v162 offset:1024
	ds_read_b128 v[226:229], v162 offset:2048
	ds_read_b128 v[230:233], v162 offset:3072
	global_load_lds_dwordx4 v[180:181], off
	v_lshl_add_u64 v[180:181], v[182:183], 0, s[20:21]
	s_add_i32 m0, s0, 0x2000
	s_nop 0
	global_load_lds_dwordx4 v[180:181], off
	s_waitcnt vmcnt(10)
	s_barrier
	s_waitcnt lgkmcnt(0)
	s_waitcnt lgkmcnt(0)
	v_mfma_scale_f32_16x16x128_f8f6f4 v[154:157], v[218:225], v[18:25], v[154:157], v188, v188 op_sel_hi:[0,0,0]
	v_mfma_scale_f32_16x16x128_f8f6f4 v[146:149], v[226:233], v[18:25], v[146:149], v188, v188 op_sel_hi:[0,0,0]
	v_mfma_scale_f32_16x16x128_f8f6f4 v[138:141], v[218:225], v[26:33], v[138:141], v188, v188 op_sel_hi:[0,0,0]
	v_mfma_scale_f32_16x16x128_f8f6f4 v[130:133], v[226:233], v[26:33], v[130:133], v188, v188 op_sel_hi:[0,0,0]
	v_mfma_scale_f32_16x16x128_f8f6f4 v[122:125], v[218:225], v[202:209], v[122:125], v188, v188 op_sel_hi:[0,0,0]
	v_mfma_scale_f32_16x16x128_f8f6f4 v[114:117], v[226:233], v[202:209], v[114:117], v188, v188 op_sel_hi:[0,0,0]
	v_mfma_scale_f32_16x16x128_f8f6f4 v[106:109], v[218:225], v[210:217], v[106:109], v188, v188 op_sel_hi:[0,0,0]
	v_mfma_scale_f32_16x16x128_f8f6f4 v[98:101], v[226:233], v[210:217], v[98:101], v188, v188 op_sel_hi:[0,0,0]
	s_mov_b32 m0, s51
	v_lshl_add_u64 v[180:181], v[186:187], 0, s[20:21]
	s_barrier
	ds_read_b128 v[18:21], v169 offset:49152
	ds_read_b128 v[22:25], v169 offset:50176
	ds_read_b128 v[26:29], v169 offset:51200
	ds_read_b128 v[30:33], v169 offset:52224
	ds_read_b128 v[202:205], v169 offset:53248
	ds_read_b128 v[206:209], v169 offset:54272
	ds_read_b128 v[210:213], v169 offset:55296
	ds_read_b128 v[214:217], v169 offset:56320
	global_load_lds_dwordx4 v[180:181], off
	v_lshl_add_u64 v[180:181], v[184:185], 0, s[20:21]
	s_mov_b32 m0, s52
	s_nop 0
	global_load_lds_dwordx4 v[180:181], off
	s_waitcnt vmcnt(10)
	s_barrier
	s_waitcnt lgkmcnt(0)
	s_waitcnt lgkmcnt(0)
	v_mfma_scale_f32_16x16x128_f8f6f4 v[94:97], v[2:9], v[18:25], v[94:97], v188, v188 op_sel_hi:[0,0,0]
	v_mfma_scale_f32_16x16x128_f8f6f4 v[86:89], v[10:17], v[18:25], v[86:89], v188, v188 op_sel_hi:[0,0,0]
	v_mfma_scale_f32_16x16x128_f8f6f4 v[78:81], v[2:9], v[26:33], v[78:81], v188, v188 op_sel_hi:[0,0,0]
	v_mfma_scale_f32_16x16x128_f8f6f4 v[70:73], v[10:17], v[26:33], v[70:73], v188, v188 op_sel_hi:[0,0,0]
	v_mfma_scale_f32_16x16x128_f8f6f4 v[62:65], v[2:9], v[202:209], v[62:65], v188, v188 op_sel_hi:[0,0,0]
	v_mfma_scale_f32_16x16x128_f8f6f4 v[54:57], v[10:17], v[202:209], v[54:57], v188, v188 op_sel_hi:[0,0,0]
	v_mfma_scale_f32_16x16x128_f8f6f4 v[46:49], v[2:9], v[210:217], v[46:49], v188, v188 op_sel_hi:[0,0,0]
	v_mfma_scale_f32_16x16x128_f8f6f4 v[38:41], v[10:17], v[210:217], v[38:41], v188, v188 op_sel_hi:[0,0,0]
	s_barrier
	s_add_u32 s0, s30, 0x20080
	s_addc_u32 s1, s31, 0
	s_add_i32 s30, s34, s43
	s_mov_b32 m0, s30
	s_nop 0
	global_load_lds_dwordx4 v164, s[0:1]
	s_add_i32 m0, s30, 0x2000
	s_nop 0
	global_load_lds_dwordx4 v166, s[0:1]
	s_waitcnt vmcnt(10)
	s_barrier
	v_mfma_scale_f32_16x16x128_f8f6f4 v[90:93], v[218:225], v[18:25], v[90:93], v188, v188 op_sel_hi:[0,0,0]
	v_mfma_scale_f32_16x16x128_f8f6f4 v[82:85], v[226:233], v[18:25], v[82:85], v188, v188 op_sel_hi:[0,0,0]
	v_mfma_scale_f32_16x16x128_f8f6f4 v[74:77], v[218:225], v[26:33], v[74:77], v188, v188 op_sel_hi:[0,0,0]
	v_mfma_scale_f32_16x16x128_f8f6f4 v[66:69], v[226:233], v[26:33], v[66:69], v188, v188 op_sel_hi:[0,0,0]
	v_mfma_scale_f32_16x16x128_f8f6f4 v[58:61], v[218:225], v[202:209], v[58:61], v188, v188 op_sel_hi:[0,0,0]
	v_mfma_scale_f32_16x16x128_f8f6f4 v[50:53], v[226:233], v[202:209], v[50:53], v188, v188 op_sel_hi:[0,0,0]
	v_mfma_scale_f32_16x16x128_f8f6f4 v[42:45], v[218:225], v[210:217], v[42:45], v188, v188 op_sel_hi:[0,0,0]
	v_mfma_scale_f32_16x16x128_f8f6f4 v[34:37], v[226:233], v[210:217], v[34:37], v188, v188 op_sel_hi:[0,0,0]
	s_add_i32 s56, s56, 2
	s_cmp_gt_u32 s56, 5
	s_mov_b64 s[34:35], s[10:11]
	s_barrier
	s_cbranch_scc1 .Lpeel_exit_2
.LBB0_688:
	s_add_u32 s10, s34, 0x100
	s_addc_u32 s11, s35, 0
	s_add_u32 s30, s29, s34
	s_addc_u32 s31, s55, s35
	s_cmpk_eq_i32 s34, 0x300
	s_cselect_b64 vcc, -1, 0
	s_and_b64 s[0:1], vcc, exec
	s_cselect_b32 s1, 0, s10
	s_cselect_b32 s0, 0, s11
	s_cselect_b32 s30, s27, s30
	s_cselect_b32 s31, s25, s31
	s_add_u32 s36, s14, s1
	s_addc_u32 s37, s15, s0
	s_add_i32 s1, 0, 0x10000
	v_add_u32_e32 v14, s1, v197
	ds_read_b128 v[2:5], v14
	ds_read_b128 v[6:9], v14 offset:1024
	ds_read_b128 v[10:13], v14 offset:2048
	ds_read_b128 v[14:17], v14 offset:3072
	v_cndmask_b32_e32 v162, v168, v171, vcc
	v_cndmask_b32_e32 v184, v170, v198, vcc
	v_cndmask_b32_e32 v175, v172, v199, vcc
	v_cndmask_b32_e32 v173, v174, v200, vcc
	v_lshl_add_u64 v[18:19], v[178:179], 0, s[34:35]
	s_add_i32 m0, s45, 0xc000
	ds_read_b128 v[202:205], v169
	ds_read_b128 v[206:209], v169 offset:1024
	ds_read_b128 v[210:213], v169 offset:2048
	ds_read_b128 v[214:217], v169 offset:3072
	ds_read_b128 v[218:221], v169 offset:4096
	ds_read_b128 v[222:225], v169 offset:5120
	ds_read_b128 v[226:229], v169 offset:6144
	ds_read_b128 v[230:233], v169 offset:7168
	global_load_lds_dwordx4 v[18:19], off
	v_lshl_add_u64 v[18:19], v[176:177], 0, s[34:35]
	s_add_i32 m0, s45, 0xe000
	s_nop 0
	global_load_lds_dwordx4 v[18:19], off
	s_waitcnt lgkmcnt(8)
	s_waitcnt vmcnt(10)
	s_barrier
	s_waitcnt lgkmcnt(0)
	s_waitcnt lgkmcnt(0)
	v_mfma_scale_f32_16x16x128_f8f6f4 v[158:161], v[2:9], v[202:209], v[158:161], v188, v188 op_sel_hi:[0,0,0]
	v_mfma_scale_f32_16x16x128_f8f6f4 v[150:153], v[10:17], v[202:209], v[150:153], v188, v188 op_sel_hi:[0,0,0]
	v_mfma_scale_f32_16x16x128_f8f6f4 v[142:145], v[2:9], v[210:217], v[142:145], v188, v188 op_sel_hi:[0,0,0]
	v_mfma_scale_f32_16x16x128_f8f6f4 v[134:137], v[10:17], v[210:217], v[134:137], v188, v188 op_sel_hi:[0,0,0]
	v_mfma_scale_f32_16x16x128_f8f6f4 v[126:129], v[2:9], v[218:225], v[126:129], v188, v188 op_sel_hi:[0,0,0]
	v_mfma_scale_f32_16x16x128_f8f6f4 v[118:121], v[10:17], v[218:225], v[118:121], v188, v188 op_sel_hi:[0,0,0]
	v_mfma_scale_f32_16x16x128_f8f6f4 v[110:113], v[2:9], v[226:233], v[110:113], v188, v188 op_sel_hi:[0,0,0]
	v_mfma_scale_f32_16x16x128_f8f6f4 v[102:105], v[10:17], v[226:233], v[102:105], v188, v188 op_sel_hi:[0,0,0]
	s_barrier
	s_add_i32 s0, 0, 0x14000
	s_add_i32 s1, s1, s43
	v_add_u32_e32 v30, s0, v197
	v_lshl_add_u64 v[180:181], s[30:31], 0, v[164:165]
	s_mov_b32 m0, s1
	ds_read_b128 v[18:21], v30
	ds_read_b128 v[22:25], v30 offset:1024
	ds_read_b128 v[26:29], v30 offset:2048
	ds_read_b128 v[30:33], v30 offset:3072
	global_load_lds_dwordx4 v[180:181], off
	v_lshl_add_u64 v[182:183], s[30:31], 0, v[166:167]
	s_add_i32 m0, s1, 0x2000
	s_nop 0
	global_load_lds_dwordx4 v[182:183], off
	s_waitcnt vmcnt(10)
	s_barrier
	s_waitcnt lgkmcnt(0)
	s_waitcnt lgkmcnt(0)
	v_mfma_scale_f32_16x16x128_f8f6f4 v[154:157], v[18:25], v[202:209], v[154:157], v188, v188 op_sel_hi:[0,0,0]
	v_mfma_scale_f32_16x16x128_f8f6f4 v[146:149], v[26:33], v[202:209], v[146:149], v188, v188 op_sel_hi:[0,0,0]
	v_mfma_scale_f32_16x16x128_f8f6f4 v[138:141], v[18:25], v[210:217], v[138:141], v188, v188 op_sel_hi:[0,0,0]
	v_mfma_scale_f32_16x16x128_f8f6f4 v[130:133], v[26:33], v[210:217], v[130:133], v188, v188 op_sel_hi:[0,0,0]
	v_mfma_scale_f32_16x16x128_f8f6f4 v[122:125], v[18:25], v[218:225], v[122:125], v188, v188 op_sel_hi:[0,0,0]
	v_mfma_scale_f32_16x16x128_f8f6f4 v[114:117], v[26:33], v[218:225], v[114:117], v188, v188 op_sel_hi:[0,0,0]
	v_mfma_scale_f32_16x16x128_f8f6f4 v[106:109], v[18:25], v[226:233], v[106:109], v188, v188 op_sel_hi:[0,0,0]
	v_mfma_scale_f32_16x16x128_f8f6f4 v[98:101], v[26:33], v[226:233], v[98:101], v188, v188 op_sel_hi:[0,0,0]
	s_mov_b32 m0, s45
	s_barrier
	ds_read_b128 v[202:205], v169 offset:16384
	ds_read_b128 v[206:209], v169 offset:17408
	ds_read_b128 v[210:213], v169 offset:18432
	ds_read_b128 v[214:217], v169 offset:19456
	ds_read_b128 v[218:221], v169 offset:20480
	ds_read_b128 v[222:225], v169 offset:21504
	ds_read_b128 v[226:229], v169 offset:22528
	ds_read_b128 v[230:233], v169 offset:23552
	global_load_lds_dwordx4 v162, s[36:37]
	s_mov_b32 m0, s46
	v_mov_b32_e32 v185, v163
	global_load_lds_dwordx4 v184, s[36:37]
	s_waitcnt vmcnt(10)
	s_barrier
	s_waitcnt lgkmcnt(0)
	v_lshl_add_u64 v[186:187], s[36:37], 0, v[162:163]
	v_lshl_add_u64 v[184:185], s[36:37], 0, v[184:185]
	s_waitcnt lgkmcnt(0)
	v_mfma_scale_f32_16x16x128_f8f6f4 v[94:97], v[2:9], v[202:209], v[94:97], v188, v188 op_sel_hi:[0,0,0]
	v_mfma_scale_f32_16x16x128_f8f6f4 v[86:89], v[10:17], v[202:209], v[86:89], v188, v188 op_sel_hi:[0,0,0]
	v_mfma_scale_f32_16x16x128_f8f6f4 v[78:81], v[2:9], v[210:217], v[78:81], v188, v188 op_sel_hi:[0,0,0]
	v_mfma_scale_f32_16x16x128_f8f6f4 v[70:73], v[10:17], v[210:217], v[70:73], v188, v188 op_sel_hi:[0,0,0]
	v_mfma_scale_f32_16x16x128_f8f6f4 v[62:65], v[2:9], v[218:225], v[62:65], v188, v188 op_sel_hi:[0,0,0]
	v_mfma_scale_f32_16x16x128_f8f6f4 v[54:57], v[10:17], v[218:225], v[54:57], v188, v188 op_sel_hi:[0,0,0]
	v_mfma_scale_f32_16x16x128_f8f6f4 v[46:49], v[2:9], v[226:233], v[46:49], v188, v188 op_sel_hi:[0,0,0]
	v_mfma_scale_f32_16x16x128_f8f6f4 v[38:41], v[10:17], v[226:233], v[38:41], v188, v188 op_sel_hi:[0,0,0]
	s_barrier
	s_add_u32 s34, s30, 0x20000
	s_addc_u32 s35, s31, 0
	s_add_i32 s0, s0, s43
	s_mov_b32 m0, s0
	s_nop 0
	global_load_lds_dwordx4 v164, s[34:35]
	s_add_i32 m0, s0, 0x2000
	s_nop 0
	global_load_lds_dwordx4 v166, s[34:35]
	s_waitcnt vmcnt(10)
	s_barrier
	v_mfma_scale_f32_16x16x128_f8f6f4 v[90:93], v[18:25], v[202:209], v[90:93], v188, v188 op_sel_hi:[0,0,0]
	v_mfma_scale_f32_16x16x128_f8f6f4 v[82:85], v[26:33], v[202:209], v[82:85], v188, v188 op_sel_hi:[0,0,0]
	v_mfma_scale_f32_16x16x128_f8f6f4 v[74:77], v[18:25], v[210:217], v[74:77], v188, v188 op_sel_hi:[0,0,0]
	v_mfma_scale_f32_16x16x128_f8f6f4 v[66:69], v[26:33], v[210:217], v[66:69], v188, v188 op_sel_hi:[0,0,0]
	v_mfma_scale_f32_16x16x128_f8f6f4 v[58:61], v[18:25], v[218:225], v[58:61], v188, v188 op_sel_hi:[0,0,0]
	v_mfma_scale_f32_16x16x128_f8f6f4 v[50:53], v[26:33], v[218:225], v[50:53], v188, v188 op_sel_hi:[0,0,0]
	v_mfma_scale_f32_16x16x128_f8f6f4 v[42:45], v[18:25], v[226:233], v[42:45], v188, v188 op_sel_hi:[0,0,0]
	v_mfma_scale_f32_16x16x128_f8f6f4 v[34:37], v[26:33], v[226:233], v[34:37], v188, v188 op_sel_hi:[0,0,0]
	s_add_i32 s0, 0, 0x18000
	v_add_u32_e32 v14, s0, v197
	s_barrier
	ds_read_b128 v[2:5], v14
	ds_read_b128 v[6:9], v14 offset:1024
	ds_read_b128 v[10:13], v14 offset:2048
	ds_read_b128 v[14:17], v14 offset:3072
	s_mov_b32 m0, s47
	ds_read_b128 v[18:21], v169 offset:32768
	ds_read_b128 v[22:25], v169 offset:33792
	ds_read_b128 v[26:29], v169 offset:34816
	ds_read_b128 v[30:33], v169 offset:35840
	ds_read_b128 v[202:205], v169 offset:36864
	ds_read_b128 v[206:209], v169 offset:37888
	ds_read_b128 v[210:213], v169 offset:38912
	ds_read_b128 v[214:217], v169 offset:39936
	global_load_lds_dwordx4 v175, s[36:37]
	s_mov_b32 m0, s48
	s_nop 0
	global_load_lds_dwordx4 v173, s[36:37]
	s_waitcnt lgkmcnt(8)
	s_waitcnt vmcnt(10)
	s_barrier
	s_waitcnt lgkmcnt(0)
	s_waitcnt lgkmcnt(0)
	v_mfma_scale_f32_16x16x128_f8f6f4 v[158:161], v[2:9], v[18:25], v[158:161], v188, v188 op_sel_hi:[0,0,0]
	v_mfma_scale_f32_16x16x128_f8f6f4 v[150:153], v[10:17], v[18:25], v[150:153], v188, v188 op_sel_hi:[0,0,0]
	v_mfma_scale_f32_16x16x128_f8f6f4 v[142:145], v[2:9], v[26:33], v[142:145], v188, v188 op_sel_hi:[0,0,0]
	v_mfma_scale_f32_16x16x128_f8f6f4 v[134:137], v[10:17], v[26:33], v[134:137], v188, v188 op_sel_hi:[0,0,0]
	v_mfma_scale_f32_16x16x128_f8f6f4 v[126:129], v[2:9], v[202:209], v[126:129], v188, v188 op_sel_hi:[0,0,0]
	v_mfma_scale_f32_16x16x128_f8f6f4 v[118:121], v[10:17], v[202:209], v[118:121], v188, v188 op_sel_hi:[0,0,0]
	v_mfma_scale_f32_16x16x128_f8f6f4 v[110:113], v[2:9], v[210:217], v[110:113], v188, v188 op_sel_hi:[0,0,0]
	v_mfma_scale_f32_16x16x128_f8f6f4 v[102:105], v[10:17], v[210:217], v[102:105], v188, v188 op_sel_hi:[0,0,0]
	s_barrier
	s_add_i32 s34, 0, 0x1c000
	s_add_i32 s0, s0, s43
	v_add_u32_e32 v162, s34, v197
	v_lshl_add_u64 v[180:181], v[180:181], 0, s[20:21]
	s_mov_b32 m0, s0
	ds_read_b128 v[218:221], v162
	ds_read_b128 v[222:225], v162 offset:1024
	ds_read_b128 v[226:229], v162 offset:2048
	ds_read_b128 v[230:233], v162 offset:3072
	global_load_lds_dwordx4 v[180:181], off
	v_lshl_add_u64 v[180:181], v[182:183], 0, s[20:21]
	s_add_i32 m0, s0, 0x2000
	s_nop 0
	global_load_lds_dwordx4 v[180:181], off
	s_waitcnt vmcnt(10)
	s_barrier
	s_waitcnt lgkmcnt(0)
	s_waitcnt lgkmcnt(0)
	v_mfma_scale_f32_16x16x128_f8f6f4 v[154:157], v[218:225], v[18:25], v[154:157], v188, v188 op_sel_hi:[0,0,0]
	v_mfma_scale_f32_16x16x128_f8f6f4 v[146:149], v[226:233], v[18:25], v[146:149], v188, v188 op_sel_hi:[0,0,0]
	v_mfma_scale_f32_16x16x128_f8f6f4 v[138:141], v[218:225], v[26:33], v[138:141], v188, v188 op_sel_hi:[0,0,0]
	v_mfma_scale_f32_16x16x128_f8f6f4 v[130:133], v[226:233], v[26:33], v[130:133], v188, v188 op_sel_hi:[0,0,0]
	v_mfma_scale_f32_16x16x128_f8f6f4 v[122:125], v[218:225], v[202:209], v[122:125], v188, v188 op_sel_hi:[0,0,0]
	v_mfma_scale_f32_16x16x128_f8f6f4 v[114:117], v[226:233], v[202:209], v[114:117], v188, v188 op_sel_hi:[0,0,0]
	v_mfma_scale_f32_16x16x128_f8f6f4 v[106:109], v[218:225], v[210:217], v[106:109], v188, v188 op_sel_hi:[0,0,0]
	v_mfma_scale_f32_16x16x128_f8f6f4 v[98:101], v[226:233], v[210:217], v[98:101], v188, v188 op_sel_hi:[0,0,0]
	s_mov_b32 m0, s51
	v_lshl_add_u64 v[180:181], v[186:187], 0, s[20:21]
	s_barrier
	ds_read_b128 v[18:21], v169 offset:49152
	ds_read_b128 v[22:25], v169 offset:50176
	ds_read_b128 v[26:29], v169 offset:51200
	ds_read_b128 v[30:33], v169 offset:52224
	ds_read_b128 v[202:205], v169 offset:53248
	ds_read_b128 v[206:209], v169 offset:54272
	ds_read_b128 v[210:213], v169 offset:55296
	ds_read_b128 v[214:217], v169 offset:56320
	global_load_lds_dwordx4 v[180:181], off
	v_lshl_add_u64 v[180:181], v[184:185], 0, s[20:21]
	s_mov_b32 m0, s52
	s_nop 0
	global_load_lds_dwordx4 v[180:181], off
	s_waitcnt vmcnt(10)
	s_barrier
	s_waitcnt lgkmcnt(0)
	s_waitcnt lgkmcnt(0)
	v_mfma_scale_f32_16x16x128_f8f6f4 v[94:97], v[2:9], v[18:25], v[94:97], v188, v188 op_sel_hi:[0,0,0]
	v_mfma_scale_f32_16x16x128_f8f6f4 v[86:89], v[10:17], v[18:25], v[86:89], v188, v188 op_sel_hi:[0,0,0]
	v_mfma_scale_f32_16x16x128_f8f6f4 v[78:81], v[2:9], v[26:33], v[78:81], v188, v188 op_sel_hi:[0,0,0]
	v_mfma_scale_f32_16x16x128_f8f6f4 v[70:73], v[10:17], v[26:33], v[70:73], v188, v188 op_sel_hi:[0,0,0]
	v_mfma_scale_f32_16x16x128_f8f6f4 v[62:65], v[2:9], v[202:209], v[62:65], v188, v188 op_sel_hi:[0,0,0]
	v_mfma_scale_f32_16x16x128_f8f6f4 v[54:57], v[10:17], v[202:209], v[54:57], v188, v188 op_sel_hi:[0,0,0]
	v_mfma_scale_f32_16x16x128_f8f6f4 v[46:49], v[2:9], v[210:217], v[46:49], v188, v188 op_sel_hi:[0,0,0]
	v_mfma_scale_f32_16x16x128_f8f6f4 v[38:41], v[10:17], v[210:217], v[38:41], v188, v188 op_sel_hi:[0,0,0]
	s_barrier
	s_add_u32 s0, s30, 0x20080
	s_addc_u32 s1, s31, 0
	s_add_i32 s30, s34, s43
	s_mov_b32 m0, s30
	s_nop 0
	global_load_lds_dwordx4 v164, s[0:1]
	s_add_i32 m0, s30, 0x2000
	s_nop 0
	global_load_lds_dwordx4 v166, s[0:1]
	s_waitcnt vmcnt(10)
	s_barrier
	v_mfma_scale_f32_16x16x128_f8f6f4 v[90:93], v[218:225], v[18:25], v[90:93], v188, v188 op_sel_hi:[0,0,0]
	v_mfma_scale_f32_16x16x128_f8f6f4 v[82:85], v[226:233], v[18:25], v[82:85], v188, v188 op_sel_hi:[0,0,0]
	v_mfma_scale_f32_16x16x128_f8f6f4 v[74:77], v[218:225], v[26:33], v[74:77], v188, v188 op_sel_hi:[0,0,0]
	v_mfma_scale_f32_16x16x128_f8f6f4 v[66:69], v[226:233], v[26:33], v[66:69], v188, v188 op_sel_hi:[0,0,0]
	v_mfma_scale_f32_16x16x128_f8f6f4 v[58:61], v[218:225], v[202:209], v[58:61], v188, v188 op_sel_hi:[0,0,0]
	v_mfma_scale_f32_16x16x128_f8f6f4 v[50:53], v[226:233], v[202:209], v[50:53], v188, v188 op_sel_hi:[0,0,0]
	v_mfma_scale_f32_16x16x128_f8f6f4 v[42:45], v[218:225], v[210:217], v[42:45], v188, v188 op_sel_hi:[0,0,0]
	v_mfma_scale_f32_16x16x128_f8f6f4 v[34:37], v[226:233], v[210:217], v[34:37], v188, v188 op_sel_hi:[0,0,0]
	s_add_i32 s56, s56, 2
	s_cmp_gt_u32 s56, 5
	s_mov_b64 s[34:35], s[10:11]
	s_barrier
	s_cbranch_scc0 .LBB0_688

.LBB0_747:
	s_add_u32 s10, s10, 0x12100000
	s_addc_u32 s11, s11, 0
	s_lshl_b32 s0, s0, 5
	s_mov_b64 s[12:13], 0x80
	s_and_b32 s42, s0, 0x60
	s_add_i32 m0, s25, 0x18000
	v_lshl_add_u64 v[4:5], v[4:5], 0, s[12:13]
	s_lshl_b32 s41, s1, 6
	s_lshl_b32 s9, s1, 13
	s_lshl_b32 s14, s42, 7
	s_waitcnt vmcnt(4)
	s_barrier
	global_load_lds_dwordx4 v[4:5], off
	s_add_i32 m0, s25, 0x1a000
	s_add_u32 s0, s28, 0x8000
	v_lshl_add_u64 v[2:3], v[2:3], 0, s[12:13]
	s_addc_u32 s1, s29, 0
	s_add_i32 s43, s25, 0x8000
	global_load_lds_dwordx4 v[2:3], off
	s_mov_b32 m0, s43
	s_add_i32 s44, s25, 0xa000
	global_load_lds_dwordx4 v152, s[0:1]
	v_lshl_add_u64 v[2:3], s[0:1], 0, v[148:149]
	s_add_u32 s0, s26, 0x20080
	s_mov_b32 m0, s44
	s_addc_u32 s1, s27, 0
	global_load_lds_dwordx4 v[2:3], off
	s_add_i32 m0, s25, 0x1c000
	s_nop 0
	global_load_lds_dwordx4 v150, s[0:1]
	s_add_i32 m0, s25, 0x1e000
	v_bfe_u32 v167, v6, 4, 2
	global_load_lds_dwordx4 v146, s[0:1]
	v_and_b32_e32 v166, 15, v6
	v_lshlrev_b32_e32 v2, 4, v167
	v_lshlrev_b32_e32 v3, 2, v6
	v_lshl_or_b32 v2, v166, 6, v2
	v_and_b32_e32 v3, 32, v3
	v_bitop3_b32 v4, v2, s9, v3 bitop3:0xde
	v_bitop3_b32 v168, v2, s14, v3 bitop3:0xde
	v_lshlrev_b32_e32 v2, 10, v7
	v_and_b32_e32 v2, 0xfffff800, v2
	v_lshl_add_u32 v2, v8, 7, v2
	v_and_b32_e32 v3, 1, v7
	v_lshl_or_b32 v2, v3, 6, v2
	v_lshl_add_u32 v154, v9, 1, v2
	v_lshlrev_b32_e32 v2, 10, v11
	v_and_b32_e32 v2, 0xfffff800, v2
	s_waitcnt vmcnt(6)
	v_lshl_add_u32 v2, v10, 7, v2
	v_and_b32_e32 v3, 1, v11
	v_lshl_or_b32 v2, v3, 6, v2
	s_add_i32 s45, 0, 0x10000
	s_add_i32 s46, 0, 0x14000
	s_sext_i32_i8 s48, s8
	v_mov_b32_e32 v155, v151
	v_lshl_add_u32 v156, v12, 1, v2
	v_mov_b32_e32 v157, v151
	v_mov_b64_e32 v[158:159], 0x800
	v_mov_b64_e32 v[160:161], 0x7ff
	v_add_u32_e32 v169, s45, v168
	v_add_u32_e32 v170, 0, v4
	v_mov_b32_e32 v171, 0x7f7f7f7f
	v_add_u32_e32 v172, s46, v168
	s_mov_b32 s14, 0x3d000000
	s_mov_b32 s47, 0xc3d00000
	v_mov_b32_e32 v173, 0x43d00000
	s_barrier

.LBB0_754:
	s_ashr_i32 s19, s18, 31
	s_lshl_b64 s[0:1], s[18:19], 18
	v_cmp_lt_i64_e32 vcc, s[20:21], v[158:159]
	s_add_u32 s20, s5, s0
	s_addc_u32 s21, s6, s1
	s_and_b64 s[0:1], vcc, exec
	s_cselect_b32 s19, s21, s29
	s_cselect_b32 s49, s20, s28
	s_ashr_i32 s0, s18, 5
	s_ashr_i32 s1, s0, 31
	s_lshl_b64 s[0:1], s[0:1], 20
	s_add_u32 s22, s7, s0
	s_addc_u32 s23, s15, s1
	s_ashr_i32 s17, s16, 31
	s_lshl_b64 s[0:1], s[16:17], 18
	s_add_u32 s22, s22, s0
	s_addc_u32 s23, s23, s1
	s_and_b64 s[0:1], vcc, exec
	s_cselect_b32 s17, s23, s27
	s_cselect_b32 s50, s22, s26
	s_add_u32 s51, s26, 0x100
	s_addc_u32 s52, s27, 0
	s_add_u32 s26, s28, 0xc000
	s_addc_u32 s27, s29, 0
	s_mov_b32 s53, -2
	ds_read_b128 v[2:5], v169
	ds_read_b128 v[6:9], v169 offset:1024
	ds_read_b128 v[10:13], v169 offset:2048
	ds_read_b128 v[14:17], v169 offset:3072
	s_add_u32 s0, s26, 0x4000
	s_addc_u32 s1, s27, 0
	s_cmp_eq_u32 s53, 4
	s_cselect_b32 s34, s49, s0
	s_cselect_b32 s35, s19, s1
	s_cselect_b32 s28, s50, s51
	s_cselect_b32 s29, s17, s52
	s_add_u32 s30, s34, 0x8000
	s_addc_u32 s31, s35, 0
	s_add_i32 m0, s25, 0xc000
	ds_read_b128 v[174:177], v170
	ds_read_b128 v[178:181], v170 offset:1024
	ds_read_b128 v[182:185], v170 offset:2048
	ds_read_b128 v[186:189], v170 offset:3072
	ds_read_b128 v[190:193], v170 offset:4096
	ds_read_b128 v[194:197], v170 offset:5120
	ds_read_b128 v[198:201], v170 offset:6144
	ds_read_b128 v[202:205], v170 offset:7168
	global_load_lds_dwordx4 v156, s[26:27]
	s_add_i32 m0, s25, 0xe000
	s_nop 0
	global_load_lds_dwordx4 v154, s[26:27]
	s_waitcnt lgkmcnt(8)
	s_waitcnt vmcnt(10)
	s_barrier
	s_waitcnt lgkmcnt(0)
	s_waitcnt lgkmcnt(0)
	v_mfma_scale_f32_16x16x128_f8f6f4 v[142:145], v[2:9], v[174:181], 0, v171, v171 op_sel_hi:[0,0,0]
	v_mfma_scale_f32_16x16x128_f8f6f4 v[138:141], v[10:17], v[174:181], 0, v171, v171 op_sel_hi:[0,0,0]
	v_mfma_scale_f32_16x16x128_f8f6f4 v[126:129], v[2:9], v[182:189], 0, v171, v171 op_sel_hi:[0,0,0]
	v_mfma_scale_f32_16x16x128_f8f6f4 v[122:125], v[10:17], v[182:189], 0, v171, v171 op_sel_hi:[0,0,0]
	v_mfma_scale_f32_16x16x128_f8f6f4 v[110:113], v[2:9], v[190:197], 0, v171, v171 op_sel_hi:[0,0,0]
	v_mfma_scale_f32_16x16x128_f8f6f4 v[106:109], v[10:17], v[190:197], 0, v171, v171 op_sel_hi:[0,0,0]
	v_mfma_scale_f32_16x16x128_f8f6f4 v[94:97], v[2:9], v[198:205], 0, v171, v171 op_sel_hi:[0,0,0]
	v_mfma_scale_f32_16x16x128_f8f6f4 v[90:93], v[10:17], v[198:205], 0, v171, v171 op_sel_hi:[0,0,0]
	s_barrier
	s_add_i32 s0, s45, s36
	v_lshl_add_u64 v[162:163], s[28:29], 0, v[150:151]
	s_mov_b32 m0, s0
	ds_read_b128 v[206:209], v172
	ds_read_b128 v[210:213], v172 offset:1024
	ds_read_b128 v[214:217], v172 offset:2048
	ds_read_b128 v[218:221], v172 offset:3072
	global_load_lds_dwordx4 v[162:163], off
	v_lshl_add_u64 v[164:165], s[28:29], 0, v[146:147]
	s_add_i32 m0, s0, 0x2000
	s_nop 0
	global_load_lds_dwordx4 v[164:165], off
	s_waitcnt vmcnt(10)
	s_barrier
	s_waitcnt lgkmcnt(0)
	s_waitcnt lgkmcnt(0)
	v_mfma_scale_f32_16x16x128_f8f6f4 v[134:137], v[206:213], v[174:181], 0, v171, v171 op_sel_hi:[0,0,0]
	v_mfma_scale_f32_16x16x128_f8f6f4 v[130:133], v[214:221], v[174:181], 0, v171, v171 op_sel_hi:[0,0,0]
	v_mfma_scale_f32_16x16x128_f8f6f4 v[118:121], v[206:213], v[182:189], 0, v171, v171 op_sel_hi:[0,0,0]
	v_mfma_scale_f32_16x16x128_f8f6f4 v[114:117], v[214:221], v[182:189], 0, v171, v171 op_sel_hi:[0,0,0]
	v_mfma_scale_f32_16x16x128_f8f6f4 v[102:105], v[206:213], v[190:197], 0, v171, v171 op_sel_hi:[0,0,0]
	v_mfma_scale_f32_16x16x128_f8f6f4 v[98:101], v[214:221], v[190:197], 0, v171, v171 op_sel_hi:[0,0,0]
	v_mfma_scale_f32_16x16x128_f8f6f4 v[86:89], v[206:213], v[198:205], 0, v171, v171 op_sel_hi:[0,0,0]
	v_mfma_scale_f32_16x16x128_f8f6f4 v[82:85], v[214:221], v[198:205], 0, v171, v171 op_sel_hi:[0,0,0]
	s_mov_b32 m0, s25
	s_barrier
	ds_read_b128 v[174:177], v170 offset:16384
	ds_read_b128 v[178:181], v170 offset:17408
	ds_read_b128 v[182:185], v170 offset:18432
	ds_read_b128 v[186:189], v170 offset:19456
	ds_read_b128 v[190:193], v170 offset:20480
	ds_read_b128 v[194:197], v170 offset:21504
	ds_read_b128 v[198:201], v170 offset:22528
	ds_read_b128 v[202:205], v170 offset:23552
	global_load_lds_dwordx4 v152, s[34:35]
	v_lshl_add_u64 v[222:223], s[34:35], 0, v[148:149]
	s_mov_b32 m0, s37
	s_nop 0
	global_load_lds_dwordx4 v[222:223], off
	s_waitcnt vmcnt(10)
	s_barrier
	s_waitcnt lgkmcnt(0)
	s_waitcnt lgkmcnt(0)
	v_mfma_scale_f32_16x16x128_f8f6f4 v[78:81], v[2:9], v[174:181], 0, v171, v171 op_sel_hi:[0,0,0]
	v_mfma_scale_f32_16x16x128_f8f6f4 v[74:77], v[10:17], v[174:181], 0, v171, v171 op_sel_hi:[0,0,0]
	v_mfma_scale_f32_16x16x128_f8f6f4 v[62:65], v[2:9], v[182:189], 0, v171, v171 op_sel_hi:[0,0,0]
	v_mfma_scale_f32_16x16x128_f8f6f4 v[58:61], v[10:17], v[182:189], 0, v171, v171 op_sel_hi:[0,0,0]
	v_mfma_scale_f32_16x16x128_f8f6f4 v[46:49], v[2:9], v[190:197], 0, v171, v171 op_sel_hi:[0,0,0]
	v_mfma_scale_f32_16x16x128_f8f6f4 v[42:45], v[10:17], v[190:197], 0, v171, v171 op_sel_hi:[0,0,0]
	v_mfma_scale_f32_16x16x128_f8f6f4 v[30:33], v[2:9], v[198:205], 0, v171, v171 op_sel_hi:[0,0,0]
	v_mfma_scale_f32_16x16x128_f8f6f4 v[26:29], v[10:17], v[198:205], 0, v171, v171 op_sel_hi:[0,0,0]
	s_barrier
	s_add_u32 s0, s28, 0x20000
	s_addc_u32 s1, s29, 0
	s_add_i32 s54, s46, s36
	s_mov_b32 m0, s54
	s_nop 0
	global_load_lds_dwordx4 v150, s[0:1]
	s_add_i32 m0, s54, 0x2000
	s_nop 0
	global_load_lds_dwordx4 v146, s[0:1]
	s_waitcnt vmcnt(10)
	s_barrier
	v_mfma_scale_f32_16x16x128_f8f6f4 v[70:73], v[206:213], v[174:181], 0, v171, v171 op_sel_hi:[0,0,0]
	v_mfma_scale_f32_16x16x128_f8f6f4 v[66:69], v[214:221], v[174:181], 0, v171, v171 op_sel_hi:[0,0,0]
	v_mfma_scale_f32_16x16x128_f8f6f4 v[54:57], v[206:213], v[182:189], 0, v171, v171 op_sel_hi:[0,0,0]
	v_mfma_scale_f32_16x16x128_f8f6f4 v[50:53], v[214:221], v[182:189], 0, v171, v171 op_sel_hi:[0,0,0]
	v_mfma_scale_f32_16x16x128_f8f6f4 v[38:41], v[206:213], v[190:197], 0, v171, v171 op_sel_hi:[0,0,0]
	v_mfma_scale_f32_16x16x128_f8f6f4 v[34:37], v[214:221], v[190:197], 0, v171, v171 op_sel_hi:[0,0,0]
	v_mfma_scale_f32_16x16x128_f8f6f4 v[22:25], v[206:213], v[198:205], 0, v171, v171 op_sel_hi:[0,0,0]
	v_mfma_scale_f32_16x16x128_f8f6f4 v[18:21], v[214:221], v[198:205], 0, v171, v171 op_sel_hi:[0,0,0]
	s_add_i32 s54, 0, 0x18000
	v_add_u32_e32 v14, s54, v168
	s_barrier
	ds_read_b128 v[2:5], v14
	ds_read_b128 v[6:9], v14 offset:1024
	ds_read_b128 v[10:13], v14 offset:2048
	ds_read_b128 v[14:17], v14 offset:3072
	s_add_u32 s0, s34, 0x4000
	s_addc_u32 s1, s35, 0
	s_mov_b32 m0, s38
	ds_read_b128 v[174:177], v170 offset:32768
	ds_read_b128 v[178:181], v170 offset:33792
	ds_read_b128 v[182:185], v170 offset:34816
	ds_read_b128 v[186:189], v170 offset:35840
	ds_read_b128 v[190:193], v170 offset:36864
	ds_read_b128 v[194:197], v170 offset:37888
	ds_read_b128 v[198:201], v170 offset:38912
	ds_read_b128 v[202:205], v170 offset:39936
	global_load_lds_dwordx4 v152, s[0:1]
	s_mov_b32 m0, s39
	s_nop 0
	global_load_lds_dwordx4 v148, s[0:1]
	s_waitcnt lgkmcnt(8)
	s_waitcnt vmcnt(10)
	s_barrier
	s_waitcnt lgkmcnt(0)
	s_waitcnt lgkmcnt(0)
	v_mfma_scale_f32_16x16x128_f8f6f4 v[142:145], v[2:9], v[174:181], v[142:145], v171, v171 op_sel_hi:[0,0,0]
	v_mfma_scale_f32_16x16x128_f8f6f4 v[138:141], v[10:17], v[174:181], v[138:141], v171, v171 op_sel_hi:[0,0,0]
	v_mfma_scale_f32_16x16x128_f8f6f4 v[126:129], v[2:9], v[182:189], v[126:129], v171, v171 op_sel_hi:[0,0,0]
	v_mfma_scale_f32_16x16x128_f8f6f4 v[122:125], v[10:17], v[182:189], v[122:125], v171, v171 op_sel_hi:[0,0,0]
	v_mfma_scale_f32_16x16x128_f8f6f4 v[110:113], v[2:9], v[190:197], v[110:113], v171, v171 op_sel_hi:[0,0,0]
	v_mfma_scale_f32_16x16x128_f8f6f4 v[106:109], v[10:17], v[190:197], v[106:109], v171, v171 op_sel_hi:[0,0,0]
	v_mfma_scale_f32_16x16x128_f8f6f4 v[94:97], v[2:9], v[198:205], v[94:97], v171, v171 op_sel_hi:[0,0,0]
	v_mfma_scale_f32_16x16x128_f8f6f4 v[90:93], v[10:17], v[198:205], v[90:93], v171, v171 op_sel_hi:[0,0,0]
	s_barrier
	s_add_i32 s34, 0, 0x1c000
	s_add_i32 s0, s54, s36
	v_add_u32_e32 v218, s34, v168
	v_lshl_add_u64 v[162:163], v[162:163], 0, s[12:13]
	s_mov_b32 m0, s0
	ds_read_b128 v[206:209], v218
	ds_read_b128 v[210:213], v218 offset:1024
	ds_read_b128 v[214:217], v218 offset:2048
	ds_read_b128 v[218:221], v218 offset:3072
	global_load_lds_dwordx4 v[162:163], off
	v_lshl_add_u64 v[162:163], v[164:165], 0, s[12:13]
	s_add_i32 m0, s0, 0x2000
	s_nop 0
	global_load_lds_dwordx4 v[162:163], off
	s_waitcnt vmcnt(10)
	s_barrier
	s_waitcnt lgkmcnt(0)
	s_waitcnt lgkmcnt(0)
	v_mfma_scale_f32_16x16x128_f8f6f4 v[134:137], v[206:213], v[174:181], v[134:137], v171, v171 op_sel_hi:[0,0,0]
	v_mfma_scale_f32_16x16x128_f8f6f4 v[130:133], v[214:221], v[174:181], v[130:133], v171, v171 op_sel_hi:[0,0,0]
	v_mfma_scale_f32_16x16x128_f8f6f4 v[118:121], v[206:213], v[182:189], v[118:121], v171, v171 op_sel_hi:[0,0,0]
	v_mfma_scale_f32_16x16x128_f8f6f4 v[114:117], v[214:221], v[182:189], v[114:117], v171, v171 op_sel_hi:[0,0,0]
	v_mfma_scale_f32_16x16x128_f8f6f4 v[102:105], v[206:213], v[190:197], v[102:105], v171, v171 op_sel_hi:[0,0,0]
	v_mfma_scale_f32_16x16x128_f8f6f4 v[98:101], v[214:221], v[190:197], v[98:101], v171, v171 op_sel_hi:[0,0,0]
	v_mfma_scale_f32_16x16x128_f8f6f4 v[86:89], v[206:213], v[198:205], v[86:89], v171, v171 op_sel_hi:[0,0,0]
	v_mfma_scale_f32_16x16x128_f8f6f4 v[82:85], v[214:221], v[198:205], v[82:85], v171, v171 op_sel_hi:[0,0,0]
	s_mov_b32 m0, s43
	s_barrier
	ds_read_b128 v[174:177], v170 offset:49152
	ds_read_b128 v[178:181], v170 offset:50176
	ds_read_b128 v[182:185], v170 offset:51200
	ds_read_b128 v[186:189], v170 offset:52224
	ds_read_b128 v[190:193], v170 offset:53248
	ds_read_b128 v[194:197], v170 offset:54272
	ds_read_b128 v[198:201], v170 offset:55296
	ds_read_b128 v[202:205], v170 offset:56320
	global_load_lds_dwordx4 v152, s[30:31]
	v_lshl_add_u64 v[162:163], s[30:31], 0, v[148:149]
	s_mov_b32 m0, s44
	s_nop 0
	global_load_lds_dwordx4 v[162:163], off
	s_waitcnt vmcnt(10)
	s_barrier
	s_waitcnt lgkmcnt(0)
	s_waitcnt lgkmcnt(0)
	v_mfma_scale_f32_16x16x128_f8f6f4 v[78:81], v[2:9], v[174:181], v[78:81], v171, v171 op_sel_hi:[0,0,0]
	v_mfma_scale_f32_16x16x128_f8f6f4 v[74:77], v[10:17], v[174:181], v[74:77], v171, v171 op_sel_hi:[0,0,0]
	v_mfma_scale_f32_16x16x128_f8f6f4 v[62:65], v[2:9], v[182:189], v[62:65], v171, v171 op_sel_hi:[0,0,0]
	v_mfma_scale_f32_16x16x128_f8f6f4 v[58:61], v[10:17], v[182:189], v[58:61], v171, v171 op_sel_hi:[0,0,0]
	v_mfma_scale_f32_16x16x128_f8f6f4 v[46:49], v[2:9], v[190:197], v[46:49], v171, v171 op_sel_hi:[0,0,0]
	v_mfma_scale_f32_16x16x128_f8f6f4 v[42:45], v[10:17], v[190:197], v[42:45], v171, v171 op_sel_hi:[0,0,0]
	v_mfma_scale_f32_16x16x128_f8f6f4 v[30:33], v[2:9], v[198:205], v[30:33], v171, v171 op_sel_hi:[0,0,0]
	v_mfma_scale_f32_16x16x128_f8f6f4 v[26:29], v[10:17], v[198:205], v[26:29], v171, v171 op_sel_hi:[0,0,0]
	s_barrier
	s_add_u32 s0, s28, 0x20080
	s_addc_u32 s1, s29, 0
	s_add_i32 s28, s34, s36
	s_mov_b32 m0, s28
	s_nop 0
	global_load_lds_dwordx4 v150, s[0:1]
	s_add_i32 m0, s28, 0x2000
	s_nop 0
	global_load_lds_dwordx4 v146, s[0:1]
	s_waitcnt vmcnt(10)
	s_barrier
	v_mfma_scale_f32_16x16x128_f8f6f4 v[70:73], v[206:213], v[174:181], v[70:73], v171, v171 op_sel_hi:[0,0,0]
	v_mfma_scale_f32_16x16x128_f8f6f4 v[66:69], v[214:221], v[174:181], v[66:69], v171, v171 op_sel_hi:[0,0,0]
	v_mfma_scale_f32_16x16x128_f8f6f4 v[54:57], v[206:213], v[182:189], v[54:57], v171, v171 op_sel_hi:[0,0,0]
	v_mfma_scale_f32_16x16x128_f8f6f4 v[50:53], v[214:221], v[182:189], v[50:53], v171, v171 op_sel_hi:[0,0,0]
	v_mfma_scale_f32_16x16x128_f8f6f4 v[38:41], v[206:213], v[190:197], v[38:41], v171, v171 op_sel_hi:[0,0,0]
	v_mfma_scale_f32_16x16x128_f8f6f4 v[34:37], v[214:221], v[190:197], v[34:37], v171, v171 op_sel_hi:[0,0,0]
	v_mfma_scale_f32_16x16x128_f8f6f4 v[22:25], v[206:213], v[198:205], v[22:25], v171, v171 op_sel_hi:[0,0,0]
	v_mfma_scale_f32_16x16x128_f8f6f4 v[18:21], v[214:221], v[198:205], v[18:21], v171, v171 op_sel_hi:[0,0,0]
	s_add_i32 s53, s53, 2
	s_add_u32 s51, s51, 0x100
	s_addc_u32 s52, s52, 0
	s_add_u32 s26, s26, 0x10000
	s_addc_u32 s27, s27, 0
	s_cmp_gt_u32 s53, 5
	s_barrier
	s_cbranch_scc1 .Lpeel_exit_3
.LBB0_755:
	ds_read_b128 v[2:5], v169
	ds_read_b128 v[6:9], v169 offset:1024
	ds_read_b128 v[10:13], v169 offset:2048
	ds_read_b128 v[14:17], v169 offset:3072
	s_add_u32 s0, s26, 0x4000
	s_addc_u32 s1, s27, 0
	s_cmp_eq_u32 s53, 4
	s_cselect_b32 s34, s49, s0
	s_cselect_b32 s35, s19, s1
	s_cselect_b32 s28, s50, s51
	s_cselect_b32 s29, s17, s52
	s_add_u32 s30, s34, 0x8000
	s_addc_u32 s31, s35, 0
	s_add_i32 m0, s25, 0xc000
	ds_read_b128 v[174:177], v170
	ds_read_b128 v[178:181], v170 offset:1024
	ds_read_b128 v[182:185], v170 offset:2048
	ds_read_b128 v[186:189], v170 offset:3072
	ds_read_b128 v[190:193], v170 offset:4096
	ds_read_b128 v[194:197], v170 offset:5120
	ds_read_b128 v[198:201], v170 offset:6144
	ds_read_b128 v[202:205], v170 offset:7168
	global_load_lds_dwordx4 v156, s[26:27]
	s_add_i32 m0, s25, 0xe000
	s_nop 0
	global_load_lds_dwordx4 v154, s[26:27]
	s_waitcnt lgkmcnt(8)
	s_waitcnt vmcnt(10)
	s_barrier
	s_waitcnt lgkmcnt(0)
	s_waitcnt lgkmcnt(0)
	v_mfma_scale_f32_16x16x128_f8f6f4 v[142:145], v[2:9], v[174:181], v[142:145], v171, v171 op_sel_hi:[0,0,0]
	v_mfma_scale_f32_16x16x128_f8f6f4 v[138:141], v[10:17], v[174:181], v[138:141], v171, v171 op_sel_hi:[0,0,0]
	v_mfma_scale_f32_16x16x128_f8f6f4 v[126:129], v[2:9], v[182:189], v[126:129], v171, v171 op_sel_hi:[0,0,0]
	v_mfma_scale_f32_16x16x128_f8f6f4 v[122:125], v[10:17], v[182:189], v[122:125], v171, v171 op_sel_hi:[0,0,0]
	v_mfma_scale_f32_16x16x128_f8f6f4 v[110:113], v[2:9], v[190:197], v[110:113], v171, v171 op_sel_hi:[0,0,0]
	v_mfma_scale_f32_16x16x128_f8f6f4 v[106:109], v[10:17], v[190:197], v[106:109], v171, v171 op_sel_hi:[0,0,0]
	v_mfma_scale_f32_16x16x128_f8f6f4 v[94:97], v[2:9], v[198:205], v[94:97], v171, v171 op_sel_hi:[0,0,0]
	v_mfma_scale_f32_16x16x128_f8f6f4 v[90:93], v[10:17], v[198:205], v[90:93], v171, v171 op_sel_hi:[0,0,0]
	s_barrier
	s_add_i32 s0, s45, s36
	v_lshl_add_u64 v[162:163], s[28:29], 0, v[150:151]
	s_mov_b32 m0, s0
	ds_read_b128 v[206:209], v172
	ds_read_b128 v[210:213], v172 offset:1024
	ds_read_b128 v[214:217], v172 offset:2048
	ds_read_b128 v[218:221], v172 offset:3072
	global_load_lds_dwordx4 v[162:163], off
	v_lshl_add_u64 v[164:165], s[28:29], 0, v[146:147]
	s_add_i32 m0, s0, 0x2000
	s_nop 0
	global_load_lds_dwordx4 v[164:165], off
	s_waitcnt vmcnt(10)
	s_barrier
	s_waitcnt lgkmcnt(0)
	s_waitcnt lgkmcnt(0)
	v_mfma_scale_f32_16x16x128_f8f6f4 v[134:137], v[206:213], v[174:181], v[134:137], v171, v171 op_sel_hi:[0,0,0]
	v_mfma_scale_f32_16x16x128_f8f6f4 v[130:133], v[214:221], v[174:181], v[130:133], v171, v171 op_sel_hi:[0,0,0]
	v_mfma_scale_f32_16x16x128_f8f6f4 v[118:121], v[206:213], v[182:189], v[118:121], v171, v171 op_sel_hi:[0,0,0]
	v_mfma_scale_f32_16x16x128_f8f6f4 v[114:117], v[214:221], v[182:189], v[114:117], v171, v171 op_sel_hi:[0,0,0]
	v_mfma_scale_f32_16x16x128_f8f6f4 v[102:105], v[206:213], v[190:197], v[102:105], v171, v171 op_sel_hi:[0,0,0]
	v_mfma_scale_f32_16x16x128_f8f6f4 v[98:101], v[214:221], v[190:197], v[98:101], v171, v171 op_sel_hi:[0,0,0]
	v_mfma_scale_f32_16x16x128_f8f6f4 v[86:89], v[206:213], v[198:205], v[86:89], v171, v171 op_sel_hi:[0,0,0]
	v_mfma_scale_f32_16x16x128_f8f6f4 v[82:85], v[214:221], v[198:205], v[82:85], v171, v171 op_sel_hi:[0,0,0]
	s_mov_b32 m0, s25
	s_barrier
	ds_read_b128 v[174:177], v170 offset:16384
	ds_read_b128 v[178:181], v170 offset:17408
	ds_read_b128 v[182:185], v170 offset:18432
	ds_read_b128 v[186:189], v170 offset:19456
	ds_read_b128 v[190:193], v170 offset:20480
	ds_read_b128 v[194:197], v170 offset:21504
	ds_read_b128 v[198:201], v170 offset:22528
	ds_read_b128 v[202:205], v170 offset:23552
	global_load_lds_dwordx4 v152, s[34:35]
	v_lshl_add_u64 v[222:223], s[34:35], 0, v[148:149]
	s_mov_b32 m0, s37
	s_nop 0
	global_load_lds_dwordx4 v[222:223], off
	s_waitcnt vmcnt(10)
	s_barrier
	s_waitcnt lgkmcnt(0)
	s_waitcnt lgkmcnt(0)
	v_mfma_scale_f32_16x16x128_f8f6f4 v[78:81], v[2:9], v[174:181], v[78:81], v171, v171 op_sel_hi:[0,0,0]
	v_mfma_scale_f32_16x16x128_f8f6f4 v[74:77], v[10:17], v[174:181], v[74:77], v171, v171 op_sel_hi:[0,0,0]
	v_mfma_scale_f32_16x16x128_f8f6f4 v[62:65], v[2:9], v[182:189], v[62:65], v171, v171 op_sel_hi:[0,0,0]
	v_mfma_scale_f32_16x16x128_f8f6f4 v[58:61], v[10:17], v[182:189], v[58:61], v171, v171 op_sel_hi:[0,0,0]
	v_mfma_scale_f32_16x16x128_f8f6f4 v[46:49], v[2:9], v[190:197], v[46:49], v171, v171 op_sel_hi:[0,0,0]
	v_mfma_scale_f32_16x16x128_f8f6f4 v[42:45], v[10:17], v[190:197], v[42:45], v171, v171 op_sel_hi:[0,0,0]
	v_mfma_scale_f32_16x16x128_f8f6f4 v[30:33], v[2:9], v[198:205], v[30:33], v171, v171 op_sel_hi:[0,0,0]
	v_mfma_scale_f32_16x16x128_f8f6f4 v[26:29], v[10:17], v[198:205], v[26:29], v171, v171 op_sel_hi:[0,0,0]
	s_barrier
	s_add_u32 s0, s28, 0x20000
	s_addc_u32 s1, s29, 0
	s_add_i32 s54, s46, s36
	s_mov_b32 m0, s54
	s_nop 0
	global_load_lds_dwordx4 v150, s[0:1]
	s_add_i32 m0, s54, 0x2000
	s_nop 0
	global_load_lds_dwordx4 v146, s[0:1]
	s_waitcnt vmcnt(10)
	s_barrier
	v_mfma_scale_f32_16x16x128_f8f6f4 v[70:73], v[206:213], v[174:181], v[70:73], v171, v171 op_sel_hi:[0,0,0]
	v_mfma_scale_f32_16x16x128_f8f6f4 v[66:69], v[214:221], v[174:181], v[66:69], v171, v171 op_sel_hi:[0,0,0]
	v_mfma_scale_f32_16x16x128_f8f6f4 v[54:57], v[206:213], v[182:189], v[54:57], v171, v171 op_sel_hi:[0,0,0]
	v_mfma_scale_f32_16x16x128_f8f6f4 v[50:53], v[214:221], v[182:189], v[50:53], v171, v171 op_sel_hi:[0,0,0]
	v_mfma_scale_f32_16x16x128_f8f6f4 v[38:41], v[206:213], v[190:197], v[38:41], v171, v171 op_sel_hi:[0,0,0]
	v_mfma_scale_f32_16x16x128_f8f6f4 v[34:37], v[214:221], v[190:197], v[34:37], v171, v171 op_sel_hi:[0,0,0]
	v_mfma_scale_f32_16x16x128_f8f6f4 v[22:25], v[206:213], v[198:205], v[22:25], v171, v171 op_sel_hi:[0,0,0]
	v_mfma_scale_f32_16x16x128_f8f6f4 v[18:21], v[214:221], v[198:205], v[18:21], v171, v171 op_sel_hi:[0,0,0]
	s_add_i32 s54, 0, 0x18000
	v_add_u32_e32 v14, s54, v168
	s_barrier
	ds_read_b128 v[2:5], v14
	ds_read_b128 v[6:9], v14 offset:1024
	ds_read_b128 v[10:13], v14 offset:2048
	ds_read_b128 v[14:17], v14 offset:3072
	s_add_u32 s0, s34, 0x4000
	s_addc_u32 s1, s35, 0
	s_mov_b32 m0, s38
	ds_read_b128 v[174:177], v170 offset:32768
	ds_read_b128 v[178:181], v170 offset:33792
	ds_read_b128 v[182:185], v170 offset:34816
	ds_read_b128 v[186:189], v170 offset:35840
	ds_read_b128 v[190:193], v170 offset:36864
	ds_read_b128 v[194:197], v170 offset:37888
	ds_read_b128 v[198:201], v170 offset:38912
	ds_read_b128 v[202:205], v170 offset:39936
	global_load_lds_dwordx4 v152, s[0:1]
	s_mov_b32 m0, s39
	s_nop 0
	global_load_lds_dwordx4 v148, s[0:1]
	s_waitcnt lgkmcnt(8)
	s_waitcnt vmcnt(10)
	s_barrier
	s_waitcnt lgkmcnt(0)
	s_waitcnt lgkmcnt(0)
	v_mfma_scale_f32_16x16x128_f8f6f4 v[142:145], v[2:9], v[174:181], v[142:145], v171, v171 op_sel_hi:[0,0,0]
	v_mfma_scale_f32_16x16x128_f8f6f4 v[138:141], v[10:17], v[174:181], v[138:141], v171, v171 op_sel_hi:[0,0,0]
	v_mfma_scale_f32_16x16x128_f8f6f4 v[126:129], v[2:9], v[182:189], v[126:129], v171, v171 op_sel_hi:[0,0,0]
	v_mfma_scale_f32_16x16x128_f8f6f4 v[122:125], v[10:17], v[182:189], v[122:125], v171, v171 op_sel_hi:[0,0,0]
	v_mfma_scale_f32_16x16x128_f8f6f4 v[110:113], v[2:9], v[190:197], v[110:113], v171, v171 op_sel_hi:[0,0,0]
	v_mfma_scale_f32_16x16x128_f8f6f4 v[106:109], v[10:17], v[190:197], v[106:109], v171, v171 op_sel_hi:[0,0,0]
	v_mfma_scale_f32_16x16x128_f8f6f4 v[94:97], v[2:9], v[198:205], v[94:97], v171, v171 op_sel_hi:[0,0,0]
	v_mfma_scale_f32_16x16x128_f8f6f4 v[90:93], v[10:17], v[198:205], v[90:93], v171, v171 op_sel_hi:[0,0,0]
	s_barrier
	s_add_i32 s34, 0, 0x1c000
	s_add_i32 s0, s54, s36
	v_add_u32_e32 v218, s34, v168
	v_lshl_add_u64 v[162:163], v[162:163], 0, s[12:13]
	s_mov_b32 m0, s0
	ds_read_b128 v[206:209], v218
	ds_read_b128 v[210:213], v218 offset:1024
	ds_read_b128 v[214:217], v218 offset:2048
	ds_read_b128 v[218:221], v218 offset:3072
	global_load_lds_dwordx4 v[162:163], off
	v_lshl_add_u64 v[162:163], v[164:165], 0, s[12:13]
	s_add_i32 m0, s0, 0x2000
	s_nop 0
	global_load_lds_dwordx4 v[162:163], off
	s_waitcnt vmcnt(10)
	s_barrier
	s_waitcnt lgkmcnt(0)
	s_waitcnt lgkmcnt(0)
	v_mfma_scale_f32_16x16x128_f8f6f4 v[134:137], v[206:213], v[174:181], v[134:137], v171, v171 op_sel_hi:[0,0,0]
	v_mfma_scale_f32_16x16x128_f8f6f4 v[130:133], v[214:221], v[174:181], v[130:133], v171, v171 op_sel_hi:[0,0,0]
	v_mfma_scale_f32_16x16x128_f8f6f4 v[118:121], v[206:213], v[182:189], v[118:121], v171, v171 op_sel_hi:[0,0,0]
	v_mfma_scale_f32_16x16x128_f8f6f4 v[114:117], v[214:221], v[182:189], v[114:117], v171, v171 op_sel_hi:[0,0,0]
	v_mfma_scale_f32_16x16x128_f8f6f4 v[102:105], v[206:213], v[190:197], v[102:105], v171, v171 op_sel_hi:[0,0,0]
	v_mfma_scale_f32_16x16x128_f8f6f4 v[98:101], v[214:221], v[190:197], v[98:101], v171, v171 op_sel_hi:[0,0,0]
	v_mfma_scale_f32_16x16x128_f8f6f4 v[86:89], v[206:213], v[198:205], v[86:89], v171, v171 op_sel_hi:[0,0,0]
	v_mfma_scale_f32_16x16x128_f8f6f4 v[82:85], v[214:221], v[198:205], v[82:85], v171, v171 op_sel_hi:[0,0,0]
	s_mov_b32 m0, s43
	s_barrier
	ds_read_b128 v[174:177], v170 offset:49152
	ds_read_b128 v[178:181], v170 offset:50176
	ds_read_b128 v[182:185], v170 offset:51200
	ds_read_b128 v[186:189], v170 offset:52224
	ds_read_b128 v[190:193], v170 offset:53248
	ds_read_b128 v[194:197], v170 offset:54272
	ds_read_b128 v[198:201], v170 offset:55296
	ds_read_b128 v[202:205], v170 offset:56320
	global_load_lds_dwordx4 v152, s[30:31]
	v_lshl_add_u64 v[162:163], s[30:31], 0, v[148:149]
	s_mov_b32 m0, s44
	s_nop 0
	global_load_lds_dwordx4 v[162:163], off
	s_waitcnt vmcnt(10)
	s_barrier
	s_waitcnt lgkmcnt(0)
	s_waitcnt lgkmcnt(0)
	v_mfma_scale_f32_16x16x128_f8f6f4 v[78:81], v[2:9], v[174:181], v[78:81], v171, v171 op_sel_hi:[0,0,0]
	v_mfma_scale_f32_16x16x128_f8f6f4 v[74:77], v[10:17], v[174:181], v[74:77], v171, v171 op_sel_hi:[0,0,0]
	v_mfma_scale_f32_16x16x128_f8f6f4 v[62:65], v[2:9], v[182:189], v[62:65], v171, v171 op_sel_hi:[0,0,0]
	v_mfma_scale_f32_16x16x128_f8f6f4 v[58:61], v[10:17], v[182:189], v[58:61], v171, v171 op_sel_hi:[0,0,0]
	v_mfma_scale_f32_16x16x128_f8f6f4 v[46:49], v[2:9], v[190:197], v[46:49], v171, v171 op_sel_hi:[0,0,0]
	v_mfma_scale_f32_16x16x128_f8f6f4 v[42:45], v[10:17], v[190:197], v[42:45], v171, v171 op_sel_hi:[0,0,0]
	v_mfma_scale_f32_16x16x128_f8f6f4 v[30:33], v[2:9], v[198:205], v[30:33], v171, v171 op_sel_hi:[0,0,0]
	v_mfma_scale_f32_16x16x128_f8f6f4 v[26:29], v[10:17], v[198:205], v[26:29], v171, v171 op_sel_hi:[0,0,0]
	s_barrier
	s_add_u32 s0, s28, 0x20080
	s_addc_u32 s1, s29, 0
	s_add_i32 s28, s34, s36
	s_mov_b32 m0, s28
	s_nop 0
	global_load_lds_dwordx4 v150, s[0:1]
	s_add_i32 m0, s28, 0x2000
	s_nop 0
	global_load_lds_dwordx4 v146, s[0:1]
	s_waitcnt vmcnt(10)
	s_barrier
	v_mfma_scale_f32_16x16x128_f8f6f4 v[70:73], v[206:213], v[174:181], v[70:73], v171, v171 op_sel_hi:[0,0,0]
	v_mfma_scale_f32_16x16x128_f8f6f4 v[66:69], v[214:221], v[174:181], v[66:69], v171, v171 op_sel_hi:[0,0,0]
	v_mfma_scale_f32_16x16x128_f8f6f4 v[54:57], v[206:213], v[182:189], v[54:57], v171, v171 op_sel_hi:[0,0,0]
	v_mfma_scale_f32_16x16x128_f8f6f4 v[50:53], v[214:221], v[182:189], v[50:53], v171, v171 op_sel_hi:[0,0,0]
	v_mfma_scale_f32_16x16x128_f8f6f4 v[38:41], v[206:213], v[190:197], v[38:41], v171, v171 op_sel_hi:[0,0,0]
	v_mfma_scale_f32_16x16x128_f8f6f4 v[34:37], v[214:221], v[190:197], v[34:37], v171, v171 op_sel_hi:[0,0,0]
	v_mfma_scale_f32_16x16x128_f8f6f4 v[22:25], v[206:213], v[198:205], v[22:25], v171, v171 op_sel_hi:[0,0,0]
	v_mfma_scale_f32_16x16x128_f8f6f4 v[18:21], v[214:221], v[198:205], v[18:21], v171, v171 op_sel_hi:[0,0,0]
	s_add_i32 s53, s53, 2
	s_add_u32 s51, s51, 0x100
	s_addc_u32 s52, s52, 0
	s_add_u32 s26, s26, 0x10000
	s_addc_u32 s27, s27, 0
	s_cmp_gt_u32 s53, 5
	s_barrier
	s_cbranch_scc0 .LBB0_755

.LBB0_890:
	s_add_u32 s12, s14, 0x12100000
	s_addc_u32 s13, s15, 0
	v_bfe_u32 v150, v16, 4, 2
	s_add_u32 s14, s14, 0x3100000
	v_and_b32_e32 v147, 15, v16
	v_lshlrev_b32_e32 v17, 4, v150
	v_lshlrev_b32_e32 v16, 2, v16
	s_mov_b64 s[16:17], 0x80
	s_sext_i32_i8 s50, s8
	s_addc_u32 s15, s15, 0
	s_and_b32 s8, s1, 3
	s_lshl_b32 s43, s0, 6
	v_lshl_or_b32 v17, v147, 6, v17
	s_lshl_b32 s0, s0, 13
	v_and_b32_e32 v16, 32, v16
	s_add_i32 m0, s25, 0x18000
	v_lshl_add_u64 v[8:9], v[8:9], 0, s[16:17]
	v_bitop3_b32 v18, v17, s0, v16 bitop3:0xde
	s_lshl_b32 s44, s8, 5
	s_lshl_b32 s0, s8, 12
	s_waitcnt vmcnt(4)
	s_barrier
	global_load_lds_dwordx4 v[8:9], off
	v_lshl_add_u64 v[6:7], v[6:7], 0, s[16:17]
	s_add_i32 m0, s25, 0x1a000
	s_add_i32 s45, s25, 0x8000
	s_add_i32 s46, s25, 0xa000
	v_bitop3_b32 v151, v17, s0, v16 bitop3:0xde
	global_load_lds_dwordx4 v[6:7], off
	v_lshl_add_u64 v[4:5], v[4:5], 0, s[16:17]
	s_mov_b32 m0, s45
	s_add_u32 s0, s30, 0x40080
	global_load_lds_dwordx4 v[4:5], off
	v_lshl_add_u64 v[2:3], v[2:3], 0, s[16:17]
	s_mov_b32 m0, s46
	s_addc_u32 s1, s31, 0
	global_load_lds_dwordx4 v[2:3], off
	s_add_i32 m0, s25, 0x1c000
	s_nop 0
	global_load_lds_dwordx4 v134, s[0:1]
	s_add_i32 m0, s25, 0x1e000
	s_cmp_eq_u32 s8, 0
	global_load_lds_dwordx4 v130, s[0:1]
	v_lshlrev_b32_e32 v2, 14, v10
	v_and_b32_e32 v2, 0xffff8000, v2
	v_lshl_add_u32 v2, v11, 11, v2
	v_and_b32_e32 v3, 1, v10
	v_lshl_or_b32 v2, v3, 6, v2
	v_lshl_add_u32 v138, v12, 1, v2
	v_lshlrev_b32_e32 v2, 14, v14
	v_and_b32_e32 v2, 0xffff8000, v2
	s_waitcnt vmcnt(6)
	v_lshl_add_u32 v2, v13, 11, v2
	v_and_b32_e32 v3, 1, v14
	s_cselect_b64 s[18:19], -1, 0
	v_lshl_or_b32 v2, v3, 6, v2
	s_add_i32 s47, 0, 0x10000
	s_add_i32 s48, 0, 0x14000
	v_mov_b32_e32 v139, v135
	v_lshl_add_u32 v140, v15, 1, v2
	v_mov_b32_e32 v141, v135
	v_mov_b64_e32 v[142:143], 0xd00
	v_mov_b64_e32 v[144:145], 0xcff
	v_add_u32_e32 v152, s47, v151
	v_add_u32_e32 v153, 0, v18
	v_add_u32_e32 v154, s48, v151
	s_movk_i32 s49, 0x1800
	v_mov_b32_e32 v155, 0x3db504f3
	s_barrier
	s_branch .LBB0_892

.LBB0_894:
	s_ashr_i32 s23, s22, 31
	s_lshl_b64 s[0:1], s[22:23], 19
	v_cmp_lt_i64_e32 vcc, s[26:27], v[142:143]
	s_add_u32 s26, s5, s0
	s_addc_u32 s27, s6, s1
	s_and_b64 s[0:1], vcc, exec
	s_cselect_b32 s23, s27, s35
	s_cselect_b32 s51, s26, s34
	s_ashr_i32 s21, s20, 31
	s_lshl_b64 s[0:1], s[20:21], 19
	s_add_u32 s28, s7, s0
	s_addc_u32 s29, s10, s1
	s_and_b64 s[0:1], vcc, exec
	s_cselect_b32 s21, s29, s31
	s_cselect_b32 s52, s28, s30
	s_add_u32 s53, s30, 0x100
	s_addc_u32 s54, s31, 0
	s_add_u32 s30, s34, 0x40080
	s_addc_u32 s31, s35, 0
	s_mov_b32 s55, -2
	ds_read_b128 v[156:159], v152
	ds_read_b128 v[160:163], v152 offset:1024
	ds_read_b128 v[164:167], v152 offset:2048
	ds_read_b128 v[168:171], v152 offset:3072
	s_add_u32 s0, s30, 0xfffc0080
	s_addc_u32 s1, s31, -1
	s_cmp_eq_u32 s55, 12
	s_cselect_b32 s37, s23, s1
	s_cselect_b32 s36, s51, s0
	s_cselect_b32 s35, s21, s54
	s_cselect_b32 s34, s52, s53
	s_add_i32 m0, s25, 0xc000
	ds_read_b128 v[172:175], v153
	ds_read_b128 v[176:179], v153 offset:1024
	ds_read_b128 v[180:183], v153 offset:2048
	ds_read_b128 v[184:187], v153 offset:3072
	ds_read_b128 v[188:191], v153 offset:4096
	ds_read_b128 v[192:195], v153 offset:5120
	ds_read_b128 v[196:199], v153 offset:6144
	ds_read_b128 v[200:203], v153 offset:7168
	global_load_lds_dwordx4 v140, s[30:31]
	s_add_i32 m0, s25, 0xe000
	s_nop 0
	global_load_lds_dwordx4 v138, s[30:31]
	s_waitcnt lgkmcnt(8)
	s_waitcnt vmcnt(10)
	s_barrier
	s_waitcnt lgkmcnt(0)
	s_waitcnt lgkmcnt(0)
	v_mfma_f32_16x16x32_bf16 v[126:129], v[156:159], v[172:175], 0
	v_mfma_f32_16x16x32_bf16 v[122:125], v[164:167], v[172:175], 0
	v_mfma_f32_16x16x32_bf16 v[118:121], v[156:159], v[180:183], 0
	v_mfma_f32_16x16x32_bf16 v[110:113], v[164:167], v[180:183], 0
	v_mfma_f32_16x16x32_bf16 v[102:105], v[156:159], v[188:191], 0
	v_mfma_f32_16x16x32_bf16 v[94:97], v[164:167], v[188:191], 0
	v_mfma_f32_16x16x32_bf16 v[86:89], v[156:159], v[196:199], 0
	v_mfma_f32_16x16x32_bf16 v[78:81], v[164:167], v[196:199], 0
	v_mfma_f32_16x16x32_bf16 v[126:129], v[160:163], v[176:179], v[126:129]
	v_mfma_f32_16x16x32_bf16 v[122:125], v[168:171], v[176:179], v[122:125]
	v_mfma_f32_16x16x32_bf16 v[118:121], v[160:163], v[184:187], v[118:121]
	v_mfma_f32_16x16x32_bf16 v[110:113], v[168:171], v[184:187], v[110:113]
	v_mfma_f32_16x16x32_bf16 v[102:105], v[160:163], v[192:195], v[102:105]
	v_mfma_f32_16x16x32_bf16 v[94:97], v[168:171], v[192:195], v[94:97]
	v_mfma_f32_16x16x32_bf16 v[86:89], v[160:163], v[200:203], v[86:89]
	v_mfma_f32_16x16x32_bf16 v[78:81], v[168:171], v[200:203], v[78:81]
	s_barrier
	s_add_i32 s0, s47, s11
	v_lshl_add_u64 v[148:149], s[34:35], 0, v[134:135]
	s_mov_b32 m0, s0
	ds_read_b128 v[204:207], v154
	ds_read_b128 v[208:211], v154 offset:1024
	ds_read_b128 v[212:215], v154 offset:2048
	ds_read_b128 v[216:219], v154 offset:3072
	global_load_lds_dwordx4 v[148:149], off
	v_lshl_add_u64 v[220:221], s[34:35], 0, v[130:131]
	s_add_i32 m0, s0, 0x2000
	s_nop 0
	global_load_lds_dwordx4 v[220:221], off
	s_waitcnt vmcnt(10)
	s_barrier
	s_waitcnt lgkmcnt(0)
	s_waitcnt lgkmcnt(0)
	v_mfma_f32_16x16x32_bf16 v[114:117], v[204:207], v[172:175], 0
	v_mfma_f32_16x16x32_bf16 v[106:109], v[212:215], v[172:175], 0
	v_mfma_f32_16x16x32_bf16 v[98:101], v[204:207], v[180:183], 0
	v_mfma_f32_16x16x32_bf16 v[90:93], v[212:215], v[180:183], 0
	v_mfma_f32_16x16x32_bf16 v[82:85], v[204:207], v[188:191], 0
	v_mfma_f32_16x16x32_bf16 v[74:77], v[212:215], v[188:191], 0
	v_mfma_f32_16x16x32_bf16 v[70:73], v[204:207], v[196:199], 0
	v_mfma_f32_16x16x32_bf16 v[66:69], v[212:215], v[196:199], 0
	v_mfma_f32_16x16x32_bf16 v[114:117], v[208:211], v[176:179], v[114:117]
	v_mfma_f32_16x16x32_bf16 v[106:109], v[216:219], v[176:179], v[106:109]
	v_mfma_f32_16x16x32_bf16 v[98:101], v[208:211], v[184:187], v[98:101]
	v_mfma_f32_16x16x32_bf16 v[90:93], v[216:219], v[184:187], v[90:93]
	v_mfma_f32_16x16x32_bf16 v[82:85], v[208:211], v[192:195], v[82:85]
	v_mfma_f32_16x16x32_bf16 v[74:77], v[216:219], v[192:195], v[74:77]
	v_mfma_f32_16x16x32_bf16 v[70:73], v[208:211], v[200:203], v[70:73]
	v_mfma_f32_16x16x32_bf16 v[66:69], v[216:219], v[200:203], v[66:69]
	s_mov_b32 m0, s25
	v_lshl_add_u64 v[222:223], s[36:37], 0, v[136:137]
	s_barrier
	ds_read_b128 v[172:175], v153 offset:16384
	ds_read_b128 v[176:179], v153 offset:17408
	ds_read_b128 v[180:183], v153 offset:18432
	ds_read_b128 v[184:187], v153 offset:19456
	ds_read_b128 v[188:191], v153 offset:20480
	ds_read_b128 v[192:195], v153 offset:21504
	ds_read_b128 v[196:199], v153 offset:22528
	ds_read_b128 v[200:203], v153 offset:23552
	global_load_lds_dwordx4 v[222:223], off
	v_lshl_add_u64 v[224:225], s[36:37], 0, v[132:133]
	s_mov_b32 m0, s39
	s_nop 0
	global_load_lds_dwordx4 v[224:225], off
	s_waitcnt vmcnt(10)
	s_barrier
	s_waitcnt lgkmcnt(0)
	s_waitcnt lgkmcnt(0)
	v_mfma_f32_16x16x32_bf16 v[62:65], v[156:159], v[172:175], 0
	v_mfma_f32_16x16x32_bf16 v[58:61], v[164:167], v[172:175], 0
	v_mfma_f32_16x16x32_bf16 v[54:57], v[156:159], v[180:183], 0
	v_mfma_f32_16x16x32_bf16 v[46:49], v[164:167], v[180:183], 0
	v_mfma_f32_16x16x32_bf16 v[38:41], v[156:159], v[188:191], 0
	v_mfma_f32_16x16x32_bf16 v[30:33], v[164:167], v[188:191], 0
	v_mfma_f32_16x16x32_bf16 v[22:25], v[156:159], v[196:199], 0
	v_mfma_f32_16x16x32_bf16 v[14:17], v[164:167], v[196:199], 0
	v_mfma_f32_16x16x32_bf16 v[62:65], v[160:163], v[176:179], v[62:65]
	v_mfma_f32_16x16x32_bf16 v[58:61], v[168:171], v[176:179], v[58:61]
	v_mfma_f32_16x16x32_bf16 v[54:57], v[160:163], v[184:187], v[54:57]
	v_mfma_f32_16x16x32_bf16 v[46:49], v[168:171], v[184:187], v[46:49]
	v_mfma_f32_16x16x32_bf16 v[38:41], v[160:163], v[192:195], v[38:41]
	v_mfma_f32_16x16x32_bf16 v[30:33], v[168:171], v[192:195], v[30:33]
	v_mfma_f32_16x16x32_bf16 v[22:25], v[160:163], v[200:203], v[22:25]
	v_mfma_f32_16x16x32_bf16 v[14:17], v[168:171], v[200:203], v[14:17]
	s_barrier
	s_add_u32 s0, s34, 0x40000
	s_addc_u32 s1, s35, 0
	s_add_i32 s56, s48, s11
	s_mov_b32 m0, s56
	s_nop 0
	global_load_lds_dwordx4 v134, s[0:1]
	s_add_i32 m0, s56, 0x2000
	s_nop 0
	global_load_lds_dwordx4 v130, s[0:1]
	s_waitcnt vmcnt(10)
	s_barrier
	v_mfma_f32_16x16x32_bf16 v[50:53], v[204:207], v[172:175], 0
	v_mfma_f32_16x16x32_bf16 v[42:45], v[212:215], v[172:175], 0
	v_mfma_f32_16x16x32_bf16 v[34:37], v[204:207], v[180:183], 0
	v_mfma_f32_16x16x32_bf16 v[26:29], v[212:215], v[180:183], 0
	v_mfma_f32_16x16x32_bf16 v[18:21], v[204:207], v[188:191], 0
	v_mfma_f32_16x16x32_bf16 v[10:13], v[212:215], v[188:191], 0
	v_mfma_f32_16x16x32_bf16 v[6:9], v[204:207], v[196:199], 0
	v_mfma_f32_16x16x32_bf16 v[2:5], v[212:215], v[196:199], 0
	v_mfma_f32_16x16x32_bf16 v[50:53], v[208:211], v[176:179], v[50:53]
	v_mfma_f32_16x16x32_bf16 v[42:45], v[216:219], v[176:179], v[42:45]
	v_mfma_f32_16x16x32_bf16 v[34:37], v[208:211], v[184:187], v[34:37]
	v_mfma_f32_16x16x32_bf16 v[26:29], v[216:219], v[184:187], v[26:29]
	v_mfma_f32_16x16x32_bf16 v[18:21], v[208:211], v[192:195], v[18:21]
	v_mfma_f32_16x16x32_bf16 v[10:13], v[216:219], v[192:195], v[10:13]
	v_mfma_f32_16x16x32_bf16 v[6:9], v[208:211], v[200:203], v[6:9]
	v_mfma_f32_16x16x32_bf16 v[2:5], v[216:219], v[200:203], v[2:5]
	s_add_i32 s56, 0, 0x18000
	v_add_u32_e32 v146, s56, v151
	s_barrier
	ds_read_b128 v[156:159], v146
	ds_read_b128 v[160:163], v146 offset:1024
	ds_read_b128 v[164:167], v146 offset:2048
	ds_read_b128 v[168:171], v146 offset:3072
	s_add_u32 s0, s36, 0x40000
	s_addc_u32 s1, s37, 0
	s_mov_b32 m0, s40
	ds_read_b128 v[172:175], v153 offset:32768
	ds_read_b128 v[176:179], v153 offset:33792
	ds_read_b128 v[180:183], v153 offset:34816
	ds_read_b128 v[184:187], v153 offset:35840
	ds_read_b128 v[188:191], v153 offset:36864
	ds_read_b128 v[192:195], v153 offset:37888
	ds_read_b128 v[196:199], v153 offset:38912
	ds_read_b128 v[200:203], v153 offset:39936
	global_load_lds_dwordx4 v136, s[0:1]
	s_mov_b32 m0, s41
	s_nop 0
	global_load_lds_dwordx4 v132, s[0:1]
	s_waitcnt lgkmcnt(8)
	s_waitcnt vmcnt(10)
	s_barrier
	s_waitcnt lgkmcnt(0)
	s_waitcnt lgkmcnt(0)
	v_mfma_f32_16x16x32_bf16 v[126:129], v[156:159], v[172:175], v[126:129]
	v_mfma_f32_16x16x32_bf16 v[122:125], v[164:167], v[172:175], v[122:125]
	v_mfma_f32_16x16x32_bf16 v[118:121], v[156:159], v[180:183], v[118:121]
	v_mfma_f32_16x16x32_bf16 v[110:113], v[164:167], v[180:183], v[110:113]
	v_mfma_f32_16x16x32_bf16 v[102:105], v[156:159], v[188:191], v[102:105]
	v_mfma_f32_16x16x32_bf16 v[94:97], v[164:167], v[188:191], v[94:97]
	v_mfma_f32_16x16x32_bf16 v[86:89], v[156:159], v[196:199], v[86:89]
	v_mfma_f32_16x16x32_bf16 v[78:81], v[164:167], v[196:199], v[78:81]
	v_mfma_f32_16x16x32_bf16 v[126:129], v[160:163], v[176:179], v[126:129]
	v_mfma_f32_16x16x32_bf16 v[122:125], v[168:171], v[176:179], v[122:125]
	v_mfma_f32_16x16x32_bf16 v[118:121], v[160:163], v[184:187], v[118:121]
	v_mfma_f32_16x16x32_bf16 v[110:113], v[168:171], v[184:187], v[110:113]
	v_mfma_f32_16x16x32_bf16 v[102:105], v[160:163], v[192:195], v[102:105]
	v_mfma_f32_16x16x32_bf16 v[94:97], v[168:171], v[192:195], v[94:97]
	v_mfma_f32_16x16x32_bf16 v[86:89], v[160:163], v[200:203], v[86:89]
	v_mfma_f32_16x16x32_bf16 v[78:81], v[168:171], v[200:203], v[78:81]
	s_barrier
	s_add_i32 s36, 0, 0x1c000
	s_add_i32 s0, s56, s11
	v_add_u32_e32 v146, s36, v151
	v_lshl_add_u64 v[148:149], v[148:149], 0, s[16:17]
	s_mov_b32 m0, s0
	ds_read_b128 v[204:207], v146
	ds_read_b128 v[208:211], v146 offset:1024
	ds_read_b128 v[212:215], v146 offset:2048
	ds_read_b128 v[216:219], v146 offset:3072
	global_load_lds_dwordx4 v[148:149], off
	v_lshl_add_u64 v[148:149], v[220:221], 0, s[16:17]
	s_add_i32 m0, s0, 0x2000
	s_nop 0
	global_load_lds_dwordx4 v[148:149], off
	s_waitcnt vmcnt(10)
	s_barrier
	s_waitcnt lgkmcnt(0)
	s_waitcnt lgkmcnt(0)
	v_mfma_f32_16x16x32_bf16 v[114:117], v[204:207], v[172:175], v[114:117]
	v_mfma_f32_16x16x32_bf16 v[106:109], v[212:215], v[172:175], v[106:109]
	v_mfma_f32_16x16x32_bf16 v[98:101], v[204:207], v[180:183], v[98:101]
	v_mfma_f32_16x16x32_bf16 v[90:93], v[212:215], v[180:183], v[90:93]
	v_mfma_f32_16x16x32_bf16 v[82:85], v[204:207], v[188:191], v[82:85]
	v_mfma_f32_16x16x32_bf16 v[74:77], v[212:215], v[188:191], v[74:77]
	v_mfma_f32_16x16x32_bf16 v[70:73], v[204:207], v[196:199], v[70:73]
	v_mfma_f32_16x16x32_bf16 v[66:69], v[212:215], v[196:199], v[66:69]
	v_mfma_f32_16x16x32_bf16 v[114:117], v[208:211], v[176:179], v[114:117]
	v_mfma_f32_16x16x32_bf16 v[106:109], v[216:219], v[176:179], v[106:109]
	v_mfma_f32_16x16x32_bf16 v[98:101], v[208:211], v[184:187], v[98:101]
	v_mfma_f32_16x16x32_bf16 v[90:93], v[216:219], v[184:187], v[90:93]
	v_mfma_f32_16x16x32_bf16 v[82:85], v[208:211], v[192:195], v[82:85]
	v_mfma_f32_16x16x32_bf16 v[74:77], v[216:219], v[192:195], v[74:77]
	v_mfma_f32_16x16x32_bf16 v[70:73], v[208:211], v[200:203], v[70:73]
	v_mfma_f32_16x16x32_bf16 v[66:69], v[216:219], v[200:203], v[66:69]
	s_mov_b32 m0, s45
	v_lshl_add_u64 v[148:149], v[222:223], 0, s[16:17]
	s_barrier
	ds_read_b128 v[172:175], v153 offset:49152
	ds_read_b128 v[176:179], v153 offset:50176
	ds_read_b128 v[180:183], v153 offset:51200
	ds_read_b128 v[184:187], v153 offset:52224
	ds_read_b128 v[188:191], v153 offset:53248
	ds_read_b128 v[192:195], v153 offset:54272
	ds_read_b128 v[196:199], v153 offset:55296
	ds_read_b128 v[200:203], v153 offset:56320
	global_load_lds_dwordx4 v[148:149], off
	v_lshl_add_u64 v[148:149], v[224:225], 0, s[16:17]
	s_mov_b32 m0, s46
	s_nop 0
	global_load_lds_dwordx4 v[148:149], off
	s_waitcnt vmcnt(10)
	s_barrier
	s_waitcnt lgkmcnt(0)
	s_waitcnt lgkmcnt(0)
	v_mfma_f32_16x16x32_bf16 v[62:65], v[156:159], v[172:175], v[62:65]
	v_mfma_f32_16x16x32_bf16 v[58:61], v[164:167], v[172:175], v[58:61]
	v_mfma_f32_16x16x32_bf16 v[54:57], v[156:159], v[180:183], v[54:57]
	v_mfma_f32_16x16x32_bf16 v[46:49], v[164:167], v[180:183], v[46:49]
	v_mfma_f32_16x16x32_bf16 v[38:41], v[156:159], v[188:191], v[38:41]
	v_mfma_f32_16x16x32_bf16 v[30:33], v[164:167], v[188:191], v[30:33]
	v_mfma_f32_16x16x32_bf16 v[22:25], v[156:159], v[196:199], v[22:25]
	v_mfma_f32_16x16x32_bf16 v[14:17], v[164:167], v[196:199], v[14:17]
	v_mfma_f32_16x16x32_bf16 v[62:65], v[160:163], v[176:179], v[62:65]
	v_mfma_f32_16x16x32_bf16 v[58:61], v[168:171], v[176:179], v[58:61]
	v_mfma_f32_16x16x32_bf16 v[54:57], v[160:163], v[184:187], v[54:57]
	v_mfma_f32_16x16x32_bf16 v[46:49], v[168:171], v[184:187], v[46:49]
	v_mfma_f32_16x16x32_bf16 v[38:41], v[160:163], v[192:195], v[38:41]
	v_mfma_f32_16x16x32_bf16 v[30:33], v[168:171], v[192:195], v[30:33]
	v_mfma_f32_16x16x32_bf16 v[22:25], v[160:163], v[200:203], v[22:25]
	v_mfma_f32_16x16x32_bf16 v[14:17], v[168:171], v[200:203], v[14:17]
	s_barrier
	s_add_u32 s0, s34, 0x40080
	s_addc_u32 s1, s35, 0
	s_add_i32 s34, s36, s11
	s_mov_b32 m0, s34
	s_nop 0
	global_load_lds_dwordx4 v134, s[0:1]
	v_lshl_add_u64 v[148:149], s[0:1], 0, v[130:131]
	s_add_i32 m0, s34, 0x2000
	s_nop 0
	global_load_lds_dwordx4 v[148:149], off
	s_waitcnt vmcnt(10)
	s_barrier
	v_mfma_f32_16x16x32_bf16 v[50:53], v[204:207], v[172:175], v[50:53]
	v_mfma_f32_16x16x32_bf16 v[42:45], v[212:215], v[172:175], v[42:45]
	v_mfma_f32_16x16x32_bf16 v[34:37], v[204:207], v[180:183], v[34:37]
	v_mfma_f32_16x16x32_bf16 v[26:29], v[212:215], v[180:183], v[26:29]
	v_mfma_f32_16x16x32_bf16 v[18:21], v[204:207], v[188:191], v[18:21]
	v_mfma_f32_16x16x32_bf16 v[10:13], v[212:215], v[188:191], v[10:13]
	v_mfma_f32_16x16x32_bf16 v[6:9], v[204:207], v[196:199], v[6:9]
	v_mfma_f32_16x16x32_bf16 v[2:5], v[212:215], v[196:199], v[2:5]
	v_mfma_f32_16x16x32_bf16 v[50:53], v[208:211], v[176:179], v[50:53]
	v_mfma_f32_16x16x32_bf16 v[42:45], v[216:219], v[176:179], v[42:45]
	v_mfma_f32_16x16x32_bf16 v[34:37], v[208:211], v[184:187], v[34:37]
	v_mfma_f32_16x16x32_bf16 v[26:29], v[216:219], v[184:187], v[26:29]
	v_mfma_f32_16x16x32_bf16 v[18:21], v[208:211], v[192:195], v[18:21]
	v_mfma_f32_16x16x32_bf16 v[10:13], v[216:219], v[192:195], v[10:13]
	v_mfma_f32_16x16x32_bf16 v[6:9], v[208:211], v[200:203], v[6:9]
	v_mfma_f32_16x16x32_bf16 v[2:5], v[216:219], v[200:203], v[2:5]
	s_add_i32 s55, s55, 2
	s_add_u32 s53, s53, 0x100
	s_addc_u32 s54, s54, 0
	s_add_u32 s30, s30, 0x100
	s_addc_u32 s31, s31, 0
	s_cmp_gt_u32 s55, 13
	s_barrier
	s_cbranch_scc1 .Lpeel_exit_4
.LBB0_895:
	ds_read_b128 v[156:159], v152
	ds_read_b128 v[160:163], v152 offset:1024
	ds_read_b128 v[164:167], v152 offset:2048
	ds_read_b128 v[168:171], v152 offset:3072
	s_add_u32 s0, s30, 0xfffc0080
	s_addc_u32 s1, s31, -1
	s_cmp_eq_u32 s55, 12
	s_cselect_b32 s37, s23, s1
	s_cselect_b32 s36, s51, s0
	s_cselect_b32 s35, s21, s54
	s_cselect_b32 s34, s52, s53
	s_add_i32 m0, s25, 0xc000
	ds_read_b128 v[172:175], v153
	ds_read_b128 v[176:179], v153 offset:1024
	ds_read_b128 v[180:183], v153 offset:2048
	ds_read_b128 v[184:187], v153 offset:3072
	ds_read_b128 v[188:191], v153 offset:4096
	ds_read_b128 v[192:195], v153 offset:5120
	ds_read_b128 v[196:199], v153 offset:6144
	ds_read_b128 v[200:203], v153 offset:7168
	global_load_lds_dwordx4 v140, s[30:31]
	s_add_i32 m0, s25, 0xe000
	s_nop 0
	global_load_lds_dwordx4 v138, s[30:31]
	s_waitcnt lgkmcnt(8)
	s_waitcnt vmcnt(10)
	s_barrier
	s_waitcnt lgkmcnt(0)
	s_waitcnt lgkmcnt(0)
	v_mfma_f32_16x16x32_bf16 v[126:129], v[156:159], v[172:175], v[126:129]
	v_mfma_f32_16x16x32_bf16 v[122:125], v[164:167], v[172:175], v[122:125]
	v_mfma_f32_16x16x32_bf16 v[118:121], v[156:159], v[180:183], v[118:121]
	v_mfma_f32_16x16x32_bf16 v[110:113], v[164:167], v[180:183], v[110:113]
	v_mfma_f32_16x16x32_bf16 v[102:105], v[156:159], v[188:191], v[102:105]
	v_mfma_f32_16x16x32_bf16 v[94:97], v[164:167], v[188:191], v[94:97]
	v_mfma_f32_16x16x32_bf16 v[86:89], v[156:159], v[196:199], v[86:89]
	v_mfma_f32_16x16x32_bf16 v[78:81], v[164:167], v[196:199], v[78:81]
	v_mfma_f32_16x16x32_bf16 v[126:129], v[160:163], v[176:179], v[126:129]
	v_mfma_f32_16x16x32_bf16 v[122:125], v[168:171], v[176:179], v[122:125]
	v_mfma_f32_16x16x32_bf16 v[118:121], v[160:163], v[184:187], v[118:121]
	v_mfma_f32_16x16x32_bf16 v[110:113], v[168:171], v[184:187], v[110:113]
	v_mfma_f32_16x16x32_bf16 v[102:105], v[160:163], v[192:195], v[102:105]
	v_mfma_f32_16x16x32_bf16 v[94:97], v[168:171], v[192:195], v[94:97]
	v_mfma_f32_16x16x32_bf16 v[86:89], v[160:163], v[200:203], v[86:89]
	v_mfma_f32_16x16x32_bf16 v[78:81], v[168:171], v[200:203], v[78:81]
	s_barrier
	s_add_i32 s0, s47, s11
	v_lshl_add_u64 v[148:149], s[34:35], 0, v[134:135]
	s_mov_b32 m0, s0
	ds_read_b128 v[204:207], v154
	ds_read_b128 v[208:211], v154 offset:1024
	ds_read_b128 v[212:215], v154 offset:2048
	ds_read_b128 v[216:219], v154 offset:3072
	global_load_lds_dwordx4 v[148:149], off
	v_lshl_add_u64 v[220:221], s[34:35], 0, v[130:131]
	s_add_i32 m0, s0, 0x2000
	s_nop 0
	global_load_lds_dwordx4 v[220:221], off
	s_waitcnt vmcnt(10)
	s_barrier
	s_waitcnt lgkmcnt(0)
	s_waitcnt lgkmcnt(0)
	v_mfma_f32_16x16x32_bf16 v[114:117], v[204:207], v[172:175], v[114:117]
	v_mfma_f32_16x16x32_bf16 v[106:109], v[212:215], v[172:175], v[106:109]
	v_mfma_f32_16x16x32_bf16 v[98:101], v[204:207], v[180:183], v[98:101]
	v_mfma_f32_16x16x32_bf16 v[90:93], v[212:215], v[180:183], v[90:93]
	v_mfma_f32_16x16x32_bf16 v[82:85], v[204:207], v[188:191], v[82:85]
	v_mfma_f32_16x16x32_bf16 v[74:77], v[212:215], v[188:191], v[74:77]
	v_mfma_f32_16x16x32_bf16 v[70:73], v[204:207], v[196:199], v[70:73]
	v_mfma_f32_16x16x32_bf16 v[66:69], v[212:215], v[196:199], v[66:69]
	v_mfma_f32_16x16x32_bf16 v[114:117], v[208:211], v[176:179], v[114:117]
	v_mfma_f32_16x16x32_bf16 v[106:109], v[216:219], v[176:179], v[106:109]
	v_mfma_f32_16x16x32_bf16 v[98:101], v[208:211], v[184:187], v[98:101]
	v_mfma_f32_16x16x32_bf16 v[90:93], v[216:219], v[184:187], v[90:93]
	v_mfma_f32_16x16x32_bf16 v[82:85], v[208:211], v[192:195], v[82:85]
	v_mfma_f32_16x16x32_bf16 v[74:77], v[216:219], v[192:195], v[74:77]
	v_mfma_f32_16x16x32_bf16 v[70:73], v[208:211], v[200:203], v[70:73]
	v_mfma_f32_16x16x32_bf16 v[66:69], v[216:219], v[200:203], v[66:69]
	s_mov_b32 m0, s25
	v_lshl_add_u64 v[222:223], s[36:37], 0, v[136:137]
	s_barrier
	ds_read_b128 v[172:175], v153 offset:16384
	ds_read_b128 v[176:179], v153 offset:17408
	ds_read_b128 v[180:183], v153 offset:18432
	ds_read_b128 v[184:187], v153 offset:19456
	ds_read_b128 v[188:191], v153 offset:20480
	ds_read_b128 v[192:195], v153 offset:21504
	ds_read_b128 v[196:199], v153 offset:22528
	ds_read_b128 v[200:203], v153 offset:23552
	global_load_lds_dwordx4 v[222:223], off
	v_lshl_add_u64 v[224:225], s[36:37], 0, v[132:133]
	s_mov_b32 m0, s39
	s_nop 0
	global_load_lds_dwordx4 v[224:225], off
	s_waitcnt vmcnt(10)
	s_barrier
	s_waitcnt lgkmcnt(0)
	s_waitcnt lgkmcnt(0)
	v_mfma_f32_16x16x32_bf16 v[62:65], v[156:159], v[172:175], v[62:65]
	v_mfma_f32_16x16x32_bf16 v[58:61], v[164:167], v[172:175], v[58:61]
	v_mfma_f32_16x16x32_bf16 v[54:57], v[156:159], v[180:183], v[54:57]
	v_mfma_f32_16x16x32_bf16 v[46:49], v[164:167], v[180:183], v[46:49]
	v_mfma_f32_16x16x32_bf16 v[38:41], v[156:159], v[188:191], v[38:41]
	v_mfma_f32_16x16x32_bf16 v[30:33], v[164:167], v[188:191], v[30:33]
	v_mfma_f32_16x16x32_bf16 v[22:25], v[156:159], v[196:199], v[22:25]
	v_mfma_f32_16x16x32_bf16 v[14:17], v[164:167], v[196:199], v[14:17]
	v_mfma_f32_16x16x32_bf16 v[62:65], v[160:163], v[176:179], v[62:65]
	v_mfma_f32_16x16x32_bf16 v[58:61], v[168:171], v[176:179], v[58:61]
	v_mfma_f32_16x16x32_bf16 v[54:57], v[160:163], v[184:187], v[54:57]
	v_mfma_f32_16x16x32_bf16 v[46:49], v[168:171], v[184:187], v[46:49]
	v_mfma_f32_16x16x32_bf16 v[38:41], v[160:163], v[192:195], v[38:41]
	v_mfma_f32_16x16x32_bf16 v[30:33], v[168:171], v[192:195], v[30:33]
	v_mfma_f32_16x16x32_bf16 v[22:25], v[160:163], v[200:203], v[22:25]
	v_mfma_f32_16x16x32_bf16 v[14:17], v[168:171], v[200:203], v[14:17]
	s_barrier
	s_add_u32 s0, s34, 0x40000
	s_addc_u32 s1, s35, 0
	s_add_i32 s56, s48, s11
	s_mov_b32 m0, s56
	s_nop 0
	global_load_lds_dwordx4 v134, s[0:1]
	s_add_i32 m0, s56, 0x2000
	s_nop 0
	global_load_lds_dwordx4 v130, s[0:1]
	s_waitcnt vmcnt(10)
	s_barrier
	v_mfma_f32_16x16x32_bf16 v[50:53], v[204:207], v[172:175], v[50:53]
	v_mfma_f32_16x16x32_bf16 v[42:45], v[212:215], v[172:175], v[42:45]
	v_mfma_f32_16x16x32_bf16 v[34:37], v[204:207], v[180:183], v[34:37]
	v_mfma_f32_16x16x32_bf16 v[26:29], v[212:215], v[180:183], v[26:29]
	v_mfma_f32_16x16x32_bf16 v[18:21], v[204:207], v[188:191], v[18:21]
	v_mfma_f32_16x16x32_bf16 v[10:13], v[212:215], v[188:191], v[10:13]
	v_mfma_f32_16x16x32_bf16 v[6:9], v[204:207], v[196:199], v[6:9]
	v_mfma_f32_16x16x32_bf16 v[2:5], v[212:215], v[196:199], v[2:5]
	v_mfma_f32_16x16x32_bf16 v[50:53], v[208:211], v[176:179], v[50:53]
	v_mfma_f32_16x16x32_bf16 v[42:45], v[216:219], v[176:179], v[42:45]
	v_mfma_f32_16x16x32_bf16 v[34:37], v[208:211], v[184:187], v[34:37]
	v_mfma_f32_16x16x32_bf16 v[26:29], v[216:219], v[184:187], v[26:29]
	v_mfma_f32_16x16x32_bf16 v[18:21], v[208:211], v[192:195], v[18:21]
	v_mfma_f32_16x16x32_bf16 v[10:13], v[216:219], v[192:195], v[10:13]
	v_mfma_f32_16x16x32_bf16 v[6:9], v[208:211], v[200:203], v[6:9]
	v_mfma_f32_16x16x32_bf16 v[2:5], v[216:219], v[200:203], v[2:5]
	s_add_i32 s56, 0, 0x18000
	v_add_u32_e32 v146, s56, v151
	s_barrier
	ds_read_b128 v[156:159], v146
	ds_read_b128 v[160:163], v146 offset:1024
	ds_read_b128 v[164:167], v146 offset:2048
	ds_read_b128 v[168:171], v146 offset:3072
	s_add_u32 s0, s36, 0x40000
	s_addc_u32 s1, s37, 0
	s_mov_b32 m0, s40
	ds_read_b128 v[172:175], v153 offset:32768
	ds_read_b128 v[176:179], v153 offset:33792
	ds_read_b128 v[180:183], v153 offset:34816
	ds_read_b128 v[184:187], v153 offset:35840
	ds_read_b128 v[188:191], v153 offset:36864
	ds_read_b128 v[192:195], v153 offset:37888
	ds_read_b128 v[196:199], v153 offset:38912
	ds_read_b128 v[200:203], v153 offset:39936
	global_load_lds_dwordx4 v136, s[0:1]
	s_mov_b32 m0, s41
	s_nop 0
	global_load_lds_dwordx4 v132, s[0:1]
	s_waitcnt lgkmcnt(8)
	s_waitcnt vmcnt(10)
	s_barrier
	s_waitcnt lgkmcnt(0)
	s_waitcnt lgkmcnt(0)
	v_mfma_f32_16x16x32_bf16 v[126:129], v[156:159], v[172:175], v[126:129]
	v_mfma_f32_16x16x32_bf16 v[122:125], v[164:167], v[172:175], v[122:125]
	v_mfma_f32_16x16x32_bf16 v[118:121], v[156:159], v[180:183], v[118:121]
	v_mfma_f32_16x16x32_bf16 v[110:113], v[164:167], v[180:183], v[110:113]
	v_mfma_f32_16x16x32_bf16 v[102:105], v[156:159], v[188:191], v[102:105]
	v_mfma_f32_16x16x32_bf16 v[94:97], v[164:167], v[188:191], v[94:97]
	v_mfma_f32_16x16x32_bf16 v[86:89], v[156:159], v[196:199], v[86:89]
	v_mfma_f32_16x16x32_bf16 v[78:81], v[164:167], v[196:199], v[78:81]
	v_mfma_f32_16x16x32_bf16 v[126:129], v[160:163], v[176:179], v[126:129]
	v_mfma_f32_16x16x32_bf16 v[122:125], v[168:171], v[176:179], v[122:125]
	v_mfma_f32_16x16x32_bf16 v[118:121], v[160:163], v[184:187], v[118:121]
	v_mfma_f32_16x16x32_bf16 v[110:113], v[168:171], v[184:187], v[110:113]
	v_mfma_f32_16x16x32_bf16 v[102:105], v[160:163], v[192:195], v[102:105]
	v_mfma_f32_16x16x32_bf16 v[94:97], v[168:171], v[192:195], v[94:97]
	v_mfma_f32_16x16x32_bf16 v[86:89], v[160:163], v[200:203], v[86:89]
	v_mfma_f32_16x16x32_bf16 v[78:81], v[168:171], v[200:203], v[78:81]
	s_barrier
	s_add_i32 s36, 0, 0x1c000
	s_add_i32 s0, s56, s11
	v_add_u32_e32 v146, s36, v151
	v_lshl_add_u64 v[148:149], v[148:149], 0, s[16:17]
	s_mov_b32 m0, s0
	ds_read_b128 v[204:207], v146
	ds_read_b128 v[208:211], v146 offset:1024
	ds_read_b128 v[212:215], v146 offset:2048
	ds_read_b128 v[216:219], v146 offset:3072
	global_load_lds_dwordx4 v[148:149], off
	v_lshl_add_u64 v[148:149], v[220:221], 0, s[16:17]
	s_add_i32 m0, s0, 0x2000
	s_nop 0
	global_load_lds_dwordx4 v[148:149], off
	s_waitcnt vmcnt(10)
	s_barrier
	s_waitcnt lgkmcnt(0)
	s_waitcnt lgkmcnt(0)
	v_mfma_f32_16x16x32_bf16 v[114:117], v[204:207], v[172:175], v[114:117]
	v_mfma_f32_16x16x32_bf16 v[106:109], v[212:215], v[172:175], v[106:109]
	v_mfma_f32_16x16x32_bf16 v[98:101], v[204:207], v[180:183], v[98:101]
	v_mfma_f32_16x16x32_bf16 v[90:93], v[212:215], v[180:183], v[90:93]
	v_mfma_f32_16x16x32_bf16 v[82:85], v[204:207], v[188:191], v[82:85]
	v_mfma_f32_16x16x32_bf16 v[74:77], v[212:215], v[188:191], v[74:77]
	v_mfma_f32_16x16x32_bf16 v[70:73], v[204:207], v[196:199], v[70:73]
	v_mfma_f32_16x16x32_bf16 v[66:69], v[212:215], v[196:199], v[66:69]
	v_mfma_f32_16x16x32_bf16 v[114:117], v[208:211], v[176:179], v[114:117]
	v_mfma_f32_16x16x32_bf16 v[106:109], v[216:219], v[176:179], v[106:109]
	v_mfma_f32_16x16x32_bf16 v[98:101], v[208:211], v[184:187], v[98:101]
	v_mfma_f32_16x16x32_bf16 v[90:93], v[216:219], v[184:187], v[90:93]
	v_mfma_f32_16x16x32_bf16 v[82:85], v[208:211], v[192:195], v[82:85]
	v_mfma_f32_16x16x32_bf16 v[74:77], v[216:219], v[192:195], v[74:77]
	v_mfma_f32_16x16x32_bf16 v[70:73], v[208:211], v[200:203], v[70:73]
	v_mfma_f32_16x16x32_bf16 v[66:69], v[216:219], v[200:203], v[66:69]
	s_mov_b32 m0, s45
	v_lshl_add_u64 v[148:149], v[222:223], 0, s[16:17]
	s_barrier
	ds_read_b128 v[172:175], v153 offset:49152
	ds_read_b128 v[176:179], v153 offset:50176
	ds_read_b128 v[180:183], v153 offset:51200
	ds_read_b128 v[184:187], v153 offset:52224
	ds_read_b128 v[188:191], v153 offset:53248
	ds_read_b128 v[192:195], v153 offset:54272
	ds_read_b128 v[196:199], v153 offset:55296
	ds_read_b128 v[200:203], v153 offset:56320
	global_load_lds_dwordx4 v[148:149], off
	v_lshl_add_u64 v[148:149], v[224:225], 0, s[16:17]
	s_mov_b32 m0, s46
	s_nop 0
	global_load_lds_dwordx4 v[148:149], off
	s_waitcnt vmcnt(10)
	s_barrier
	s_waitcnt lgkmcnt(0)
	s_waitcnt lgkmcnt(0)
	v_mfma_f32_16x16x32_bf16 v[62:65], v[156:159], v[172:175], v[62:65]
	v_mfma_f32_16x16x32_bf16 v[58:61], v[164:167], v[172:175], v[58:61]
	v_mfma_f32_16x16x32_bf16 v[54:57], v[156:159], v[180:183], v[54:57]
	v_mfma_f32_16x16x32_bf16 v[46:49], v[164:167], v[180:183], v[46:49]
	v_mfma_f32_16x16x32_bf16 v[38:41], v[156:159], v[188:191], v[38:41]
	v_mfma_f32_16x16x32_bf16 v[30:33], v[164:167], v[188:191], v[30:33]
	v_mfma_f32_16x16x32_bf16 v[22:25], v[156:159], v[196:199], v[22:25]
	v_mfma_f32_16x16x32_bf16 v[14:17], v[164:167], v[196:199], v[14:17]
	v_mfma_f32_16x16x32_bf16 v[62:65], v[160:163], v[176:179], v[62:65]
	v_mfma_f32_16x16x32_bf16 v[58:61], v[168:171], v[176:179], v[58:61]
	v_mfma_f32_16x16x32_bf16 v[54:57], v[160:163], v[184:187], v[54:57]
	v_mfma_f32_16x16x32_bf16 v[46:49], v[168:171], v[184:187], v[46:49]
	v_mfma_f32_16x16x32_bf16 v[38:41], v[160:163], v[192:195], v[38:41]
	v_mfma_f32_16x16x32_bf16 v[30:33], v[168:171], v[192:195], v[30:33]
	v_mfma_f32_16x16x32_bf16 v[22:25], v[160:163], v[200:203], v[22:25]
	v_mfma_f32_16x16x32_bf16 v[14:17], v[168:171], v[200:203], v[14:17]
	s_barrier
	s_add_u32 s0, s34, 0x40080
	s_addc_u32 s1, s35, 0
	s_add_i32 s34, s36, s11
	s_mov_b32 m0, s34
	s_nop 0
	global_load_lds_dwordx4 v134, s[0:1]
	v_lshl_add_u64 v[148:149], s[0:1], 0, v[130:131]
	s_add_i32 m0, s34, 0x2000
	s_nop 0
	global_load_lds_dwordx4 v[148:149], off
	s_waitcnt vmcnt(10)
	s_barrier
	v_mfma_f32_16x16x32_bf16 v[50:53], v[204:207], v[172:175], v[50:53]
	v_mfma_f32_16x16x32_bf16 v[42:45], v[212:215], v[172:175], v[42:45]
	v_mfma_f32_16x16x32_bf16 v[34:37], v[204:207], v[180:183], v[34:37]
	v_mfma_f32_16x16x32_bf16 v[26:29], v[212:215], v[180:183], v[26:29]
	v_mfma_f32_16x16x32_bf16 v[18:21], v[204:207], v[188:191], v[18:21]
	v_mfma_f32_16x16x32_bf16 v[10:13], v[212:215], v[188:191], v[10:13]
	v_mfma_f32_16x16x32_bf16 v[6:9], v[204:207], v[196:199], v[6:9]
	v_mfma_f32_16x16x32_bf16 v[2:5], v[212:215], v[196:199], v[2:5]
	v_mfma_f32_16x16x32_bf16 v[50:53], v[208:211], v[176:179], v[50:53]
	v_mfma_f32_16x16x32_bf16 v[42:45], v[216:219], v[176:179], v[42:45]
	v_mfma_f32_16x16x32_bf16 v[34:37], v[208:211], v[184:187], v[34:37]
	v_mfma_f32_16x16x32_bf16 v[26:29], v[216:219], v[184:187], v[26:29]
	v_mfma_f32_16x16x32_bf16 v[18:21], v[208:211], v[192:195], v[18:21]
	v_mfma_f32_16x16x32_bf16 v[10:13], v[216:219], v[192:195], v[10:13]
	v_mfma_f32_16x16x32_bf16 v[6:9], v[208:211], v[200:203], v[6:9]
	v_mfma_f32_16x16x32_bf16 v[2:5], v[216:219], v[200:203], v[2:5]
	s_add_i32 s55, s55, 2
	s_add_u32 s53, s53, 0x100
	s_addc_u32 s54, s54, 0
	s_add_u32 s30, s30, 0x100
	s_addc_u32 s31, s31, 0
	s_cmp_gt_u32 s55, 13
	s_barrier
	s_cbranch_scc0 .LBB0_895

.LBB0_1045:
	v_bfe_u32 v153, v12, 4, 2
	s_lshl_b32 s0, s0, 5
	v_and_b32_e32 v151, 15, v12
	v_lshlrev_b32_e32 v13, 4, v153
	v_lshlrev_b32_e32 v12, 2, v12
	s_and_b32 s45, s0, 0x60
	s_lshl_b32 s44, s1, 6
	v_lshl_or_b32 v13, v151, 6, v13
	s_lshl_b32 s1, s1, 13
	v_and_b32_e32 v12, 32, v12
	s_lshl_b32 s0, s45, 7
	v_bitop3_b32 v169, v13, s0, v12 bitop3:0xde
	s_add_u32 s0, s22, 0x1000080
	v_bitop3_b32 v14, v13, s1, v12 bitop3:0xde
	s_addc_u32 s1, s23, 0
	s_add_i32 m0, s6, 0x18000
	s_waitcnt vmcnt(4)
	s_barrier
	global_load_lds_dwordx4 v158, s[0:1]
	v_lshl_add_u64 v[12:13], s[0:1], 0, v[154:155]
	s_add_i32 m0, s6, 0x1a000
	s_mov_b64 s[28:29], 0x80
	s_add_i32 s48, s6, 0x8000
	s_add_i32 s49, s6, 0xa000
	global_load_lds_dwordx4 v[12:13], off
	v_lshl_add_u64 v[4:5], v[4:5], 0, s[28:29]
	s_mov_b32 m0, s48
	s_add_u32 s0, s22, 0x1040080
	global_load_lds_dwordx4 v[4:5], off
	v_lshl_add_u64 v[2:3], v[2:3], 0, s[28:29]
	s_mov_b32 m0, s49
	s_addc_u32 s1, s23, 0
	global_load_lds_dwordx4 v[2:3], off
	s_add_i32 m0, s6, 0x1c000
	s_nop 0
	global_load_lds_dwordx4 v158, s[0:1]
	s_add_i32 m0, s6, 0x1e000
	s_add_i32 s52, 0, 0x10000
	global_load_lds_dwordx4 v154, s[0:1]
	v_lshlrev_b32_e32 v2, 14, v6
	v_and_b32_e32 v2, 0xffff8000, v2
	v_lshl_add_u32 v2, v7, 11, v2
	v_and_b32_e32 v3, 1, v6
	v_lshl_or_b32 v2, v3, 6, v2
	v_lshl_add_u32 v162, v8, 1, v2
	v_lshlrev_b32_e32 v2, 14, v10
	v_and_b32_e32 v2, 0xffff8000, v2
	s_waitcnt vmcnt(6)
	v_lshl_add_u32 v2, v9, 11, v2
	v_and_b32_e32 v3, 1, v10
	v_lshl_or_b32 v2, v3, 6, v2
	v_add_u32_e32 v170, s52, v169
	s_add_i32 s54, 0, 0x14000
	s_add_i32 s52, s52, s5
	s_mov_b32 s46, 0x18000
	s_mov_b32 s47, 0x8000
	v_mov_b32_e32 v163, v159
	v_lshl_add_u32 v164, v11, 1, v2
	v_mov_b32_e32 v165, v159
	v_add_u32_e32 v171, 0, v14
	v_add_u32_e32 v172, s54, v169
	s_mov_b32 s30, 0x3fd744fd
	s_add_i32 s50, s6, 0xc000
	s_add_i32 s51, s6, 0xe000
	s_add_i32 s53, s52, 0x2000
	s_add_i32 s54, s54, s5
	s_mov_b32 s59, s2
	s_mov_b64 s[36:37], s[8:9]
	s_mov_b32 s55, 0
	s_barrier
.LBB0_1046:
	s_add_i32 s55, s55, 1
	s_mov_b64 s[0:1], s[26:27]
	s_lshr_b32 s26, s55, 2
	s_mul_i32 s26, s26, s74
	s_mov_b64 s[38:39], s[36:37]
	s_mov_b32 s37, s56
	s_add_i32 s56, s26, s2
	s_cmpk_lt_i32 s56, 0x100
	s_cselect_b64 s[40:41], -1, 0
	s_cmpk_gt_i32 s56, 0xff
	s_mov_b32 s36, s57
	s_cselect_b64 s[34:35], -1, 0
	s_and_b32 s57, s55, 3
	s_and_b64 s[26:27], s[40:41], exec
	s_cselect_b32 s26, s56, s37
	s_cselect_b32 s36, s57, s36
	s_ashr_i32 s27, s26, 31
	s_lshl_b64 s[26:27], s[26:27], 19
	s_add_u32 s26, s20, s26
	s_addc_u32 s27, s21, s27
	s_and_b64 s[42:43], s[40:41], exec
	s_cselect_b32 s60, s27, s1
	s_cselect_b32 s61, s26, s0
	s_ashr_i32 s37, s36, 31
	s_lshl_b64 s[36:37], s[36:37], 19
	s_add_u32 s36, s8, s36
	s_addc_u32 s37, s9, s37
	s_and_b64 s[40:41], s[40:41], exec
	s_cselect_b32 s62, s37, s39
	s_cselect_b32 s63, s36, s38
	s_add_u32 s64, s38, 0x100
	s_addc_u32 s65, s39, 0
	s_add_u32 s38, s0, 0x40080
	s_addc_u32 s39, s1, 0
	s_mov_b32 s69, -2
	s_waitcnt vmcnt(0)
	ds_read_b128 v[130:133], v170
	ds_read_b128 v[134:137], v170 offset:1024
	ds_read_b128 v[138:141], v170 offset:2048
	ds_read_b128 v[142:145], v170 offset:3072
	s_add_u32 s0, s38, 0xfffc0080
	s_addc_u32 s1, s39, -1
	s_cmp_eq_u32 s69, 12
	s_cselect_b32 s43, s60, s1
	s_cselect_b32 s42, s61, s0
	s_cselect_b32 s41, s62, s65
	s_cselect_b32 s40, s63, s64
	s_mov_b32 m0, s50
	ds_read_b128 v[146:149], v171
	ds_read_b128 v[174:177], v171 offset:1024
	ds_read_b128 v[178:181], v171 offset:2048
	ds_read_b128 v[182:185], v171 offset:3072
	ds_read_b128 v[186:189], v171 offset:4096
	ds_read_b128 v[190:193], v171 offset:5120
	ds_read_b128 v[194:197], v171 offset:6144
	ds_read_b128 v[198:201], v171 offset:7168
	global_load_lds_dwordx4 v164, s[38:39]
	s_mov_b32 m0, s51
	s_nop 0
	global_load_lds_dwordx4 v162, s[38:39]
	s_waitcnt lgkmcnt(8)
	s_waitcnt vmcnt(10)
	s_barrier
	s_waitcnt lgkmcnt(0)
	s_waitcnt lgkmcnt(0)
	v_mfma_f32_16x16x32_bf16 v[126:129], v[130:133], v[146:149], 0
	v_mfma_f32_16x16x32_bf16 v[122:125], v[138:141], v[146:149], 0
	v_mfma_f32_16x16x32_bf16 v[118:121], v[130:133], v[178:181], 0
	v_mfma_f32_16x16x32_bf16 v[110:113], v[138:141], v[178:181], 0
	v_mfma_f32_16x16x32_bf16 v[98:101], v[130:133], v[186:189], 0
	v_mfma_f32_16x16x32_bf16 v[90:93], v[138:141], v[186:189], 0
	v_mfma_f32_16x16x32_bf16 v[82:85], v[130:133], v[194:197], 0
	v_mfma_f32_16x16x32_bf16 v[74:77], v[138:141], v[194:197], 0
	v_mfma_f32_16x16x32_bf16 v[126:129], v[134:137], v[174:177], v[126:129]
	v_mfma_f32_16x16x32_bf16 v[122:125], v[142:145], v[174:177], v[122:125]
	v_mfma_f32_16x16x32_bf16 v[118:121], v[134:137], v[182:185], v[118:121]
	v_mfma_f32_16x16x32_bf16 v[110:113], v[142:145], v[182:185], v[110:113]
	v_mfma_f32_16x16x32_bf16 v[98:101], v[134:137], v[190:193], v[98:101]
	v_mfma_f32_16x16x32_bf16 v[90:93], v[142:145], v[190:193], v[90:93]
	v_mfma_f32_16x16x32_bf16 v[82:85], v[134:137], v[198:201], v[82:85]
	v_mfma_f32_16x16x32_bf16 v[74:77], v[142:145], v[198:201], v[74:77]
	s_barrier
	s_mov_b32 m0, s52
	v_lshl_add_u64 v[166:167], s[40:41], 0, v[158:159]
	ds_read_b128 v[202:205], v172
	ds_read_b128 v[206:209], v172 offset:1024
	ds_read_b128 v[210:213], v172 offset:2048
	ds_read_b128 v[214:217], v172 offset:3072
	global_load_lds_dwordx4 v[166:167], off
	v_lshl_add_u64 v[218:219], s[40:41], 0, v[154:155]
	s_mov_b32 m0, s53
	s_nop 0
	global_load_lds_dwordx4 v[218:219], off
	s_waitcnt vmcnt(10)
	s_barrier
	s_waitcnt lgkmcnt(0)
	s_waitcnt lgkmcnt(0)
	v_mfma_f32_16x16x32_bf16 v[114:117], v[202:205], v[146:149], 0
	v_mfma_f32_16x16x32_bf16 v[106:109], v[210:213], v[146:149], 0
	v_mfma_f32_16x16x32_bf16 v[102:105], v[202:205], v[178:181], 0
	v_mfma_f32_16x16x32_bf16 v[94:97], v[210:213], v[178:181], 0
	v_mfma_f32_16x16x32_bf16 v[86:89], v[202:205], v[186:189], 0
	v_mfma_f32_16x16x32_bf16 v[78:81], v[210:213], v[186:189], 0
	v_mfma_f32_16x16x32_bf16 v[70:73], v[202:205], v[194:197], 0
	v_mfma_f32_16x16x32_bf16 v[66:69], v[210:213], v[194:197], 0
	v_mfma_f32_16x16x32_bf16 v[114:117], v[206:209], v[174:177], v[114:117]
	v_mfma_f32_16x16x32_bf16 v[106:109], v[214:217], v[174:177], v[106:109]
	v_mfma_f32_16x16x32_bf16 v[102:105], v[206:209], v[182:185], v[102:105]
	v_mfma_f32_16x16x32_bf16 v[94:97], v[214:217], v[182:185], v[94:97]
	v_mfma_f32_16x16x32_bf16 v[86:89], v[206:209], v[190:193], v[86:89]
	v_mfma_f32_16x16x32_bf16 v[78:81], v[214:217], v[190:193], v[78:81]
	v_mfma_f32_16x16x32_bf16 v[70:73], v[206:209], v[198:201], v[70:73]
	v_mfma_f32_16x16x32_bf16 v[66:69], v[214:217], v[198:201], v[66:69]
	s_mov_b32 m0, s6
	v_lshl_add_u64 v[220:221], s[42:43], 0, v[160:161]
	s_barrier
	ds_read_b128 v[146:149], v171 offset:16384
	ds_read_b128 v[174:177], v171 offset:17408
	ds_read_b128 v[178:181], v171 offset:18432
	ds_read_b128 v[182:185], v171 offset:19456
	ds_read_b128 v[186:189], v171 offset:20480
	ds_read_b128 v[190:193], v171 offset:21504
	ds_read_b128 v[194:197], v171 offset:22528
	ds_read_b128 v[198:201], v171 offset:23552
	global_load_lds_dwordx4 v[220:221], off
	v_lshl_add_u64 v[222:223], s[42:43], 0, v[156:157]
	s_mov_b32 m0, s7
	s_nop 0
	global_load_lds_dwordx4 v[222:223], off
	s_waitcnt vmcnt(10)
	s_barrier
	s_waitcnt lgkmcnt(0)
	s_waitcnt lgkmcnt(0)
	v_mfma_f32_16x16x32_bf16 v[62:65], v[130:133], v[146:149], 0
	v_mfma_f32_16x16x32_bf16 v[58:61], v[138:141], v[146:149], 0
	v_mfma_f32_16x16x32_bf16 v[50:53], v[130:133], v[178:181], 0
	v_mfma_f32_16x16x32_bf16 v[42:45], v[138:141], v[178:181], 0
	v_mfma_f32_16x16x32_bf16 v[34:37], v[130:133], v[186:189], 0
	v_mfma_f32_16x16x32_bf16 v[26:29], v[138:141], v[186:189], 0
	v_mfma_f32_16x16x32_bf16 v[18:21], v[130:133], v[194:197], 0
	v_mfma_f32_16x16x32_bf16 v[10:13], v[138:141], v[194:197], 0
	v_mfma_f32_16x16x32_bf16 v[62:65], v[134:137], v[174:177], v[62:65]
	v_mfma_f32_16x16x32_bf16 v[58:61], v[142:145], v[174:177], v[58:61]
	v_mfma_f32_16x16x32_bf16 v[50:53], v[134:137], v[182:185], v[50:53]
	v_mfma_f32_16x16x32_bf16 v[42:45], v[142:145], v[182:185], v[42:45]
	v_mfma_f32_16x16x32_bf16 v[34:37], v[134:137], v[190:193], v[34:37]
	v_mfma_f32_16x16x32_bf16 v[26:29], v[142:145], v[190:193], v[26:29]
	v_mfma_f32_16x16x32_bf16 v[18:21], v[134:137], v[198:201], v[18:21]
	v_mfma_f32_16x16x32_bf16 v[10:13], v[142:145], v[198:201], v[10:13]
	s_barrier
	s_add_u32 s0, s40, 0x40000
	s_addc_u32 s1, s41, 0
	s_mov_b32 m0, s54
	s_nop 0
	global_load_lds_dwordx4 v158, s[0:1]
	s_add_i32 m0, s54, 0x2000
	s_nop 0
	global_load_lds_dwordx4 v154, s[0:1]
	s_waitcnt vmcnt(10)
	s_barrier
	v_mfma_f32_16x16x32_bf16 v[54:57], v[202:205], v[146:149], 0
	v_mfma_f32_16x16x32_bf16 v[46:49], v[210:213], v[146:149], 0
	v_mfma_f32_16x16x32_bf16 v[38:41], v[202:205], v[178:181], 0
	v_mfma_f32_16x16x32_bf16 v[30:33], v[210:213], v[178:181], 0
	v_mfma_f32_16x16x32_bf16 v[22:25], v[202:205], v[186:189], 0
	v_mfma_f32_16x16x32_bf16 v[14:17], v[210:213], v[186:189], 0
	v_mfma_f32_16x16x32_bf16 v[6:9], v[202:205], v[194:197], 0
	v_mfma_f32_16x16x32_bf16 v[2:5], v[210:213], v[194:197], 0
	v_mfma_f32_16x16x32_bf16 v[54:57], v[206:209], v[174:177], v[54:57]
	v_mfma_f32_16x16x32_bf16 v[46:49], v[214:217], v[174:177], v[46:49]
	v_mfma_f32_16x16x32_bf16 v[38:41], v[206:209], v[182:185], v[38:41]
	v_mfma_f32_16x16x32_bf16 v[30:33], v[214:217], v[182:185], v[30:33]
	v_mfma_f32_16x16x32_bf16 v[22:25], v[206:209], v[190:193], v[22:25]
	v_mfma_f32_16x16x32_bf16 v[14:17], v[214:217], v[190:193], v[14:17]
	v_mfma_f32_16x16x32_bf16 v[6:9], v[206:209], v[198:201], v[6:9]
	v_mfma_f32_16x16x32_bf16 v[2:5], v[214:217], v[198:201], v[2:5]
	s_add_i32 s70, 0, 0x18000
	v_add_u32_e32 v142, s70, v169
	s_barrier
	ds_read_b128 v[130:133], v142
	ds_read_b128 v[134:137], v142 offset:1024
	ds_read_b128 v[138:141], v142 offset:2048
	ds_read_b128 v[142:145], v142 offset:3072
	s_add_u32 s0, s42, 0x40000
	s_addc_u32 s1, s43, 0
	s_mov_b32 m0, s10
	ds_read_b128 v[146:149], v171 offset:32768
	ds_read_b128 v[174:177], v171 offset:33792
	ds_read_b128 v[178:181], v171 offset:34816
	ds_read_b128 v[182:185], v171 offset:35840
	ds_read_b128 v[186:189], v171 offset:36864
	ds_read_b128 v[190:193], v171 offset:37888
	ds_read_b128 v[194:197], v171 offset:38912
	ds_read_b128 v[198:201], v171 offset:39936
	global_load_lds_dwordx4 v160, s[0:1]
	s_mov_b32 m0, s11
	s_nop 0
	global_load_lds_dwordx4 v156, s[0:1]
	s_waitcnt lgkmcnt(8)
	s_waitcnt vmcnt(10)
	s_barrier
	s_waitcnt lgkmcnt(0)
	s_waitcnt lgkmcnt(0)
	v_mfma_f32_16x16x32_bf16 v[126:129], v[130:133], v[146:149], v[126:129]
	v_mfma_f32_16x16x32_bf16 v[122:125], v[138:141], v[146:149], v[122:125]
	v_mfma_f32_16x16x32_bf16 v[118:121], v[130:133], v[178:181], v[118:121]
	v_mfma_f32_16x16x32_bf16 v[110:113], v[138:141], v[178:181], v[110:113]
	v_mfma_f32_16x16x32_bf16 v[98:101], v[130:133], v[186:189], v[98:101]
	v_mfma_f32_16x16x32_bf16 v[90:93], v[138:141], v[186:189], v[90:93]
	v_mfma_f32_16x16x32_bf16 v[82:85], v[130:133], v[194:197], v[82:85]
	v_mfma_f32_16x16x32_bf16 v[74:77], v[138:141], v[194:197], v[74:77]
	v_mfma_f32_16x16x32_bf16 v[126:129], v[134:137], v[174:177], v[126:129]
	v_mfma_f32_16x16x32_bf16 v[122:125], v[142:145], v[174:177], v[122:125]
	v_mfma_f32_16x16x32_bf16 v[118:121], v[134:137], v[182:185], v[118:121]
	v_mfma_f32_16x16x32_bf16 v[110:113], v[142:145], v[182:185], v[110:113]
	v_mfma_f32_16x16x32_bf16 v[98:101], v[134:137], v[190:193], v[98:101]
	v_mfma_f32_16x16x32_bf16 v[90:93], v[142:145], v[190:193], v[90:93]
	v_mfma_f32_16x16x32_bf16 v[82:85], v[134:137], v[198:201], v[82:85]
	v_mfma_f32_16x16x32_bf16 v[74:77], v[142:145], v[198:201], v[74:77]
	s_barrier
	s_add_i32 s42, 0, 0x1c000
	s_add_i32 s0, s70, s5
	v_add_u32_e32 v173, s42, v169
	v_lshl_add_u64 v[166:167], v[166:167], 0, s[28:29]
	s_mov_b32 m0, s0
	ds_read_b128 v[202:205], v173
	ds_read_b128 v[206:209], v173 offset:1024
	ds_read_b128 v[210:213], v173 offset:2048
	ds_read_b128 v[214:217], v173 offset:3072
	global_load_lds_dwordx4 v[166:167], off
	v_lshl_add_u64 v[166:167], v[218:219], 0, s[28:29]
	s_add_i32 m0, s0, 0x2000
	s_nop 0
	global_load_lds_dwordx4 v[166:167], off
	s_waitcnt vmcnt(10)
	s_barrier
	s_waitcnt lgkmcnt(0)
	s_waitcnt lgkmcnt(0)
	v_mfma_f32_16x16x32_bf16 v[114:117], v[202:205], v[146:149], v[114:117]
	v_mfma_f32_16x16x32_bf16 v[106:109], v[210:213], v[146:149], v[106:109]
	v_mfma_f32_16x16x32_bf16 v[102:105], v[202:205], v[178:181], v[102:105]
	v_mfma_f32_16x16x32_bf16 v[94:97], v[210:213], v[178:181], v[94:97]
	v_mfma_f32_16x16x32_bf16 v[86:89], v[202:205], v[186:189], v[86:89]
	v_mfma_f32_16x16x32_bf16 v[78:81], v[210:213], v[186:189], v[78:81]
	v_mfma_f32_16x16x32_bf16 v[70:73], v[202:205], v[194:197], v[70:73]
	v_mfma_f32_16x16x32_bf16 v[66:69], v[210:213], v[194:197], v[66:69]
	v_mfma_f32_16x16x32_bf16 v[114:117], v[206:209], v[174:177], v[114:117]
	v_mfma_f32_16x16x32_bf16 v[106:109], v[214:217], v[174:177], v[106:109]
	v_mfma_f32_16x16x32_bf16 v[102:105], v[206:209], v[182:185], v[102:105]
	v_mfma_f32_16x16x32_bf16 v[94:97], v[214:217], v[182:185], v[94:97]
	v_mfma_f32_16x16x32_bf16 v[86:89], v[206:209], v[190:193], v[86:89]
	v_mfma_f32_16x16x32_bf16 v[78:81], v[214:217], v[190:193], v[78:81]
	v_mfma_f32_16x16x32_bf16 v[70:73], v[206:209], v[198:201], v[70:73]
	v_mfma_f32_16x16x32_bf16 v[66:69], v[214:217], v[198:201], v[66:69]
	s_mov_b32 m0, s48
	v_lshl_add_u64 v[166:167], v[220:221], 0, s[28:29]
	s_barrier
	ds_read_b128 v[146:149], v171 offset:49152
	ds_read_b128 v[174:177], v171 offset:50176
	ds_read_b128 v[178:181], v171 offset:51200
	ds_read_b128 v[182:185], v171 offset:52224
	ds_read_b128 v[186:189], v171 offset:53248
	ds_read_b128 v[190:193], v171 offset:54272
	ds_read_b128 v[194:197], v171 offset:55296
	ds_read_b128 v[198:201], v171 offset:56320
	global_load_lds_dwordx4 v[166:167], off
	v_lshl_add_u64 v[166:167], v[222:223], 0, s[28:29]
	s_mov_b32 m0, s49
	s_nop 0
	global_load_lds_dwordx4 v[166:167], off
	s_waitcnt vmcnt(10)
	s_barrier
	s_waitcnt lgkmcnt(0)
	s_waitcnt lgkmcnt(0)
	v_mfma_f32_16x16x32_bf16 v[62:65], v[130:133], v[146:149], v[62:65]
	v_mfma_f32_16x16x32_bf16 v[58:61], v[138:141], v[146:149], v[58:61]
	v_mfma_f32_16x16x32_bf16 v[50:53], v[130:133], v[178:181], v[50:53]
	v_mfma_f32_16x16x32_bf16 v[42:45], v[138:141], v[178:181], v[42:45]
	v_mfma_f32_16x16x32_bf16 v[34:37], v[130:133], v[186:189], v[34:37]
	v_mfma_f32_16x16x32_bf16 v[26:29], v[138:141], v[186:189], v[26:29]
	v_mfma_f32_16x16x32_bf16 v[18:21], v[130:133], v[194:197], v[18:21]
	v_mfma_f32_16x16x32_bf16 v[10:13], v[138:141], v[194:197], v[10:13]
	v_mfma_f32_16x16x32_bf16 v[62:65], v[134:137], v[174:177], v[62:65]
	v_mfma_f32_16x16x32_bf16 v[58:61], v[142:145], v[174:177], v[58:61]
	v_mfma_f32_16x16x32_bf16 v[50:53], v[134:137], v[182:185], v[50:53]
	v_mfma_f32_16x16x32_bf16 v[42:45], v[142:145], v[182:185], v[42:45]
	v_mfma_f32_16x16x32_bf16 v[34:37], v[134:137], v[190:193], v[34:37]
	v_mfma_f32_16x16x32_bf16 v[26:29], v[142:145], v[190:193], v[26:29]
	v_mfma_f32_16x16x32_bf16 v[18:21], v[134:137], v[198:201], v[18:21]
	v_mfma_f32_16x16x32_bf16 v[10:13], v[142:145], v[198:201], v[10:13]
	s_barrier
	s_add_u32 s0, s40, 0x40080
	s_addc_u32 s1, s41, 0
	s_add_i32 s40, s42, s5
	s_mov_b32 m0, s40
	s_nop 0
	global_load_lds_dwordx4 v158, s[0:1]
	s_add_i32 m0, s40, 0x2000
	s_nop 0
	global_load_lds_dwordx4 v154, s[0:1]
	s_waitcnt vmcnt(10)
	s_barrier
	v_mfma_f32_16x16x32_bf16 v[54:57], v[202:205], v[146:149], v[54:57]
	v_mfma_f32_16x16x32_bf16 v[46:49], v[210:213], v[146:149], v[46:49]
	v_mfma_f32_16x16x32_bf16 v[38:41], v[202:205], v[178:181], v[38:41]
	v_mfma_f32_16x16x32_bf16 v[30:33], v[210:213], v[178:181], v[30:33]
	v_mfma_f32_16x16x32_bf16 v[22:25], v[202:205], v[186:189], v[22:25]
	v_mfma_f32_16x16x32_bf16 v[14:17], v[210:213], v[186:189], v[14:17]
	v_mfma_f32_16x16x32_bf16 v[6:9], v[202:205], v[194:197], v[6:9]
	v_mfma_f32_16x16x32_bf16 v[2:5], v[210:213], v[194:197], v[2:5]
	v_mfma_f32_16x16x32_bf16 v[54:57], v[206:209], v[174:177], v[54:57]
	v_mfma_f32_16x16x32_bf16 v[46:49], v[214:217], v[174:177], v[46:49]
	v_mfma_f32_16x16x32_bf16 v[38:41], v[206:209], v[182:185], v[38:41]
	v_mfma_f32_16x16x32_bf16 v[30:33], v[214:217], v[182:185], v[30:33]
	v_mfma_f32_16x16x32_bf16 v[22:25], v[206:209], v[190:193], v[22:25]
	v_mfma_f32_16x16x32_bf16 v[14:17], v[214:217], v[190:193], v[14:17]
	v_mfma_f32_16x16x32_bf16 v[6:9], v[206:209], v[198:201], v[6:9]
	v_mfma_f32_16x16x32_bf16 v[2:5], v[214:217], v[198:201], v[2:5]
	s_add_i32 s69, s69, 2
	s_add_u32 s64, s64, 0x100
	s_addc_u32 s65, s65, 0
	s_add_u32 s38, s38, 0x100
	s_addc_u32 s39, s39, 0
	s_cmp_gt_u32 s69, 13
	s_barrier
	s_cbranch_scc1 .Lpeel_exit_5
.LBB0_1047:
	ds_read_b128 v[130:133], v170
	ds_read_b128 v[134:137], v170 offset:1024
	ds_read_b128 v[138:141], v170 offset:2048
	ds_read_b128 v[142:145], v170 offset:3072
	s_add_u32 s0, s38, 0xfffc0080
	s_addc_u32 s1, s39, -1
	s_cmp_eq_u32 s69, 12
	s_cselect_b32 s43, s60, s1
	s_cselect_b32 s42, s61, s0
	s_cselect_b32 s41, s62, s65
	s_cselect_b32 s40, s63, s64
	s_mov_b32 m0, s50
	ds_read_b128 v[146:149], v171
	ds_read_b128 v[174:177], v171 offset:1024
	ds_read_b128 v[178:181], v171 offset:2048
	ds_read_b128 v[182:185], v171 offset:3072
	ds_read_b128 v[186:189], v171 offset:4096
	ds_read_b128 v[190:193], v171 offset:5120
	ds_read_b128 v[194:197], v171 offset:6144
	ds_read_b128 v[198:201], v171 offset:7168
	global_load_lds_dwordx4 v164, s[38:39]
	s_mov_b32 m0, s51
	s_nop 0
	global_load_lds_dwordx4 v162, s[38:39]
	s_waitcnt lgkmcnt(8)
	s_waitcnt vmcnt(10)
	s_barrier
	s_waitcnt lgkmcnt(0)
	s_waitcnt lgkmcnt(0)
	v_mfma_f32_16x16x32_bf16 v[126:129], v[130:133], v[146:149], v[126:129]
	v_mfma_f32_16x16x32_bf16 v[122:125], v[138:141], v[146:149], v[122:125]
	v_mfma_f32_16x16x32_bf16 v[118:121], v[130:133], v[178:181], v[118:121]
	v_mfma_f32_16x16x32_bf16 v[110:113], v[138:141], v[178:181], v[110:113]
	v_mfma_f32_16x16x32_bf16 v[98:101], v[130:133], v[186:189], v[98:101]
	v_mfma_f32_16x16x32_bf16 v[90:93], v[138:141], v[186:189], v[90:93]
	v_mfma_f32_16x16x32_bf16 v[82:85], v[130:133], v[194:197], v[82:85]
	v_mfma_f32_16x16x32_bf16 v[74:77], v[138:141], v[194:197], v[74:77]
	v_mfma_f32_16x16x32_bf16 v[126:129], v[134:137], v[174:177], v[126:129]
	v_mfma_f32_16x16x32_bf16 v[122:125], v[142:145], v[174:177], v[122:125]
	v_mfma_f32_16x16x32_bf16 v[118:121], v[134:137], v[182:185], v[118:121]
	v_mfma_f32_16x16x32_bf16 v[110:113], v[142:145], v[182:185], v[110:113]
	v_mfma_f32_16x16x32_bf16 v[98:101], v[134:137], v[190:193], v[98:101]
	v_mfma_f32_16x16x32_bf16 v[90:93], v[142:145], v[190:193], v[90:93]
	v_mfma_f32_16x16x32_bf16 v[82:85], v[134:137], v[198:201], v[82:85]
	v_mfma_f32_16x16x32_bf16 v[74:77], v[142:145], v[198:201], v[74:77]
	s_barrier
	s_mov_b32 m0, s52
	v_lshl_add_u64 v[166:167], s[40:41], 0, v[158:159]
	ds_read_b128 v[202:205], v172
	ds_read_b128 v[206:209], v172 offset:1024
	ds_read_b128 v[210:213], v172 offset:2048
	ds_read_b128 v[214:217], v172 offset:3072
	global_load_lds_dwordx4 v[166:167], off
	v_lshl_add_u64 v[218:219], s[40:41], 0, v[154:155]
	s_mov_b32 m0, s53
	s_nop 0
	global_load_lds_dwordx4 v[218:219], off
	s_waitcnt vmcnt(10)
	s_barrier
	s_waitcnt lgkmcnt(0)
	s_waitcnt lgkmcnt(0)
	v_mfma_f32_16x16x32_bf16 v[114:117], v[202:205], v[146:149], v[114:117]
	v_mfma_f32_16x16x32_bf16 v[106:109], v[210:213], v[146:149], v[106:109]
	v_mfma_f32_16x16x32_bf16 v[102:105], v[202:205], v[178:181], v[102:105]
	v_mfma_f32_16x16x32_bf16 v[94:97], v[210:213], v[178:181], v[94:97]
	v_mfma_f32_16x16x32_bf16 v[86:89], v[202:205], v[186:189], v[86:89]
	v_mfma_f32_16x16x32_bf16 v[78:81], v[210:213], v[186:189], v[78:81]
	v_mfma_f32_16x16x32_bf16 v[70:73], v[202:205], v[194:197], v[70:73]
	v_mfma_f32_16x16x32_bf16 v[66:69], v[210:213], v[194:197], v[66:69]
	v_mfma_f32_16x16x32_bf16 v[114:117], v[206:209], v[174:177], v[114:117]
	v_mfma_f32_16x16x32_bf16 v[106:109], v[214:217], v[174:177], v[106:109]
	v_mfma_f32_16x16x32_bf16 v[102:105], v[206:209], v[182:185], v[102:105]
	v_mfma_f32_16x16x32_bf16 v[94:97], v[214:217], v[182:185], v[94:97]
	v_mfma_f32_16x16x32_bf16 v[86:89], v[206:209], v[190:193], v[86:89]
	v_mfma_f32_16x16x32_bf16 v[78:81], v[214:217], v[190:193], v[78:81]
	v_mfma_f32_16x16x32_bf16 v[70:73], v[206:209], v[198:201], v[70:73]
	v_mfma_f32_16x16x32_bf16 v[66:69], v[214:217], v[198:201], v[66:69]
	s_mov_b32 m0, s6
	v_lshl_add_u64 v[220:221], s[42:43], 0, v[160:161]
	s_barrier
	ds_read_b128 v[146:149], v171 offset:16384
	ds_read_b128 v[174:177], v171 offset:17408
	ds_read_b128 v[178:181], v171 offset:18432
	ds_read_b128 v[182:185], v171 offset:19456
	ds_read_b128 v[186:189], v171 offset:20480
	ds_read_b128 v[190:193], v171 offset:21504
	ds_read_b128 v[194:197], v171 offset:22528
	ds_read_b128 v[198:201], v171 offset:23552
	global_load_lds_dwordx4 v[220:221], off
	v_lshl_add_u64 v[222:223], s[42:43], 0, v[156:157]
	s_mov_b32 m0, s7
	s_nop 0
	global_load_lds_dwordx4 v[222:223], off
	s_waitcnt vmcnt(10)
	s_barrier
	s_waitcnt lgkmcnt(0)
	s_waitcnt lgkmcnt(0)
	v_mfma_f32_16x16x32_bf16 v[62:65], v[130:133], v[146:149], v[62:65]
	v_mfma_f32_16x16x32_bf16 v[58:61], v[138:141], v[146:149], v[58:61]
	v_mfma_f32_16x16x32_bf16 v[50:53], v[130:133], v[178:181], v[50:53]
	v_mfma_f32_16x16x32_bf16 v[42:45], v[138:141], v[178:181], v[42:45]
	v_mfma_f32_16x16x32_bf16 v[34:37], v[130:133], v[186:189], v[34:37]
	v_mfma_f32_16x16x32_bf16 v[26:29], v[138:141], v[186:189], v[26:29]
	v_mfma_f32_16x16x32_bf16 v[18:21], v[130:133], v[194:197], v[18:21]
	v_mfma_f32_16x16x32_bf16 v[10:13], v[138:141], v[194:197], v[10:13]
	v_mfma_f32_16x16x32_bf16 v[62:65], v[134:137], v[174:177], v[62:65]
	v_mfma_f32_16x16x32_bf16 v[58:61], v[142:145], v[174:177], v[58:61]
	v_mfma_f32_16x16x32_bf16 v[50:53], v[134:137], v[182:185], v[50:53]
	v_mfma_f32_16x16x32_bf16 v[42:45], v[142:145], v[182:185], v[42:45]
	v_mfma_f32_16x16x32_bf16 v[34:37], v[134:137], v[190:193], v[34:37]
	v_mfma_f32_16x16x32_bf16 v[26:29], v[142:145], v[190:193], v[26:29]
	v_mfma_f32_16x16x32_bf16 v[18:21], v[134:137], v[198:201], v[18:21]
	v_mfma_f32_16x16x32_bf16 v[10:13], v[142:145], v[198:201], v[10:13]
	s_barrier
	s_add_u32 s0, s40, 0x40000
	s_addc_u32 s1, s41, 0
	s_mov_b32 m0, s54
	s_nop 0
	global_load_lds_dwordx4 v158, s[0:1]
	s_add_i32 m0, s54, 0x2000
	s_nop 0
	global_load_lds_dwordx4 v154, s[0:1]
	s_waitcnt vmcnt(10)
	s_barrier
	v_mfma_f32_16x16x32_bf16 v[54:57], v[202:205], v[146:149], v[54:57]
	v_mfma_f32_16x16x32_bf16 v[46:49], v[210:213], v[146:149], v[46:49]
	v_mfma_f32_16x16x32_bf16 v[38:41], v[202:205], v[178:181], v[38:41]
	v_mfma_f32_16x16x32_bf16 v[30:33], v[210:213], v[178:181], v[30:33]
	v_mfma_f32_16x16x32_bf16 v[22:25], v[202:205], v[186:189], v[22:25]
	v_mfma_f32_16x16x32_bf16 v[14:17], v[210:213], v[186:189], v[14:17]
	v_mfma_f32_16x16x32_bf16 v[6:9], v[202:205], v[194:197], v[6:9]
	v_mfma_f32_16x16x32_bf16 v[2:5], v[210:213], v[194:197], v[2:5]
	v_mfma_f32_16x16x32_bf16 v[54:57], v[206:209], v[174:177], v[54:57]
	v_mfma_f32_16x16x32_bf16 v[46:49], v[214:217], v[174:177], v[46:49]
	v_mfma_f32_16x16x32_bf16 v[38:41], v[206:209], v[182:185], v[38:41]
	v_mfma_f32_16x16x32_bf16 v[30:33], v[214:217], v[182:185], v[30:33]
	v_mfma_f32_16x16x32_bf16 v[22:25], v[206:209], v[190:193], v[22:25]
	v_mfma_f32_16x16x32_bf16 v[14:17], v[214:217], v[190:193], v[14:17]
	v_mfma_f32_16x16x32_bf16 v[6:9], v[206:209], v[198:201], v[6:9]
	v_mfma_f32_16x16x32_bf16 v[2:5], v[214:217], v[198:201], v[2:5]
	s_add_i32 s70, 0, 0x18000
	v_add_u32_e32 v142, s70, v169
	s_barrier
	ds_read_b128 v[130:133], v142
	ds_read_b128 v[134:137], v142 offset:1024
	ds_read_b128 v[138:141], v142 offset:2048
	ds_read_b128 v[142:145], v142 offset:3072
	s_add_u32 s0, s42, 0x40000
	s_addc_u32 s1, s43, 0
	s_mov_b32 m0, s10
	ds_read_b128 v[146:149], v171 offset:32768
	ds_read_b128 v[174:177], v171 offset:33792
	ds_read_b128 v[178:181], v171 offset:34816
	ds_read_b128 v[182:185], v171 offset:35840
	ds_read_b128 v[186:189], v171 offset:36864
	ds_read_b128 v[190:193], v171 offset:37888
	ds_read_b128 v[194:197], v171 offset:38912
	ds_read_b128 v[198:201], v171 offset:39936
	global_load_lds_dwordx4 v160, s[0:1]
	s_mov_b32 m0, s11
	s_nop 0
	global_load_lds_dwordx4 v156, s[0:1]
	s_waitcnt lgkmcnt(8)
	s_waitcnt vmcnt(10)
	s_barrier
	s_waitcnt lgkmcnt(0)
	s_waitcnt lgkmcnt(0)
	v_mfma_f32_16x16x32_bf16 v[126:129], v[130:133], v[146:149], v[126:129]
	v_mfma_f32_16x16x32_bf16 v[122:125], v[138:141], v[146:149], v[122:125]
	v_mfma_f32_16x16x32_bf16 v[118:121], v[130:133], v[178:181], v[118:121]
	v_mfma_f32_16x16x32_bf16 v[110:113], v[138:141], v[178:181], v[110:113]
	v_mfma_f32_16x16x32_bf16 v[98:101], v[130:133], v[186:189], v[98:101]
	v_mfma_f32_16x16x32_bf16 v[90:93], v[138:141], v[186:189], v[90:93]
	v_mfma_f32_16x16x32_bf16 v[82:85], v[130:133], v[194:197], v[82:85]
	v_mfma_f32_16x16x32_bf16 v[74:77], v[138:141], v[194:197], v[74:77]
	v_mfma_f32_16x16x32_bf16 v[126:129], v[134:137], v[174:177], v[126:129]
	v_mfma_f32_16x16x32_bf16 v[122:125], v[142:145], v[174:177], v[122:125]
	v_mfma_f32_16x16x32_bf16 v[118:121], v[134:137], v[182:185], v[118:121]
	v_mfma_f32_16x16x32_bf16 v[110:113], v[142:145], v[182:185], v[110:113]
	v_mfma_f32_16x16x32_bf16 v[98:101], v[134:137], v[190:193], v[98:101]
	v_mfma_f32_16x16x32_bf16 v[90:93], v[142:145], v[190:193], v[90:93]
	v_mfma_f32_16x16x32_bf16 v[82:85], v[134:137], v[198:201], v[82:85]
	v_mfma_f32_16x16x32_bf16 v[74:77], v[142:145], v[198:201], v[74:77]
	s_barrier
	s_add_i32 s42, 0, 0x1c000
	s_add_i32 s0, s70, s5
	v_add_u32_e32 v173, s42, v169
	v_lshl_add_u64 v[166:167], v[166:167], 0, s[28:29]
	s_mov_b32 m0, s0
	ds_read_b128 v[202:205], v173
	ds_read_b128 v[206:209], v173 offset:1024
	ds_read_b128 v[210:213], v173 offset:2048
	ds_read_b128 v[214:217], v173 offset:3072
	global_load_lds_dwordx4 v[166:167], off
	v_lshl_add_u64 v[166:167], v[218:219], 0, s[28:29]
	s_add_i32 m0, s0, 0x2000
	s_nop 0
	global_load_lds_dwordx4 v[166:167], off
	s_waitcnt vmcnt(10)
	s_barrier
	s_waitcnt lgkmcnt(0)
	s_waitcnt lgkmcnt(0)
	v_mfma_f32_16x16x32_bf16 v[114:117], v[202:205], v[146:149], v[114:117]
	v_mfma_f32_16x16x32_bf16 v[106:109], v[210:213], v[146:149], v[106:109]
	v_mfma_f32_16x16x32_bf16 v[102:105], v[202:205], v[178:181], v[102:105]
	v_mfma_f32_16x16x32_bf16 v[94:97], v[210:213], v[178:181], v[94:97]
	v_mfma_f32_16x16x32_bf16 v[86:89], v[202:205], v[186:189], v[86:89]
	v_mfma_f32_16x16x32_bf16 v[78:81], v[210:213], v[186:189], v[78:81]
	v_mfma_f32_16x16x32_bf16 v[70:73], v[202:205], v[194:197], v[70:73]
	v_mfma_f32_16x16x32_bf16 v[66:69], v[210:213], v[194:197], v[66:69]
	v_mfma_f32_16x16x32_bf16 v[114:117], v[206:209], v[174:177], v[114:117]
	v_mfma_f32_16x16x32_bf16 v[106:109], v[214:217], v[174:177], v[106:109]
	v_mfma_f32_16x16x32_bf16 v[102:105], v[206:209], v[182:185], v[102:105]
	v_mfma_f32_16x16x32_bf16 v[94:97], v[214:217], v[182:185], v[94:97]
	v_mfma_f32_16x16x32_bf16 v[86:89], v[206:209], v[190:193], v[86:89]
	v_mfma_f32_16x16x32_bf16 v[78:81], v[214:217], v[190:193], v[78:81]
	v_mfma_f32_16x16x32_bf16 v[70:73], v[206:209], v[198:201], v[70:73]
	v_mfma_f32_16x16x32_bf16 v[66:69], v[214:217], v[198:201], v[66:69]
	s_mov_b32 m0, s48
	v_lshl_add_u64 v[166:167], v[220:221], 0, s[28:29]
	s_barrier
	ds_read_b128 v[146:149], v171 offset:49152
	ds_read_b128 v[174:177], v171 offset:50176
	ds_read_b128 v[178:181], v171 offset:51200
	ds_read_b128 v[182:185], v171 offset:52224
	ds_read_b128 v[186:189], v171 offset:53248
	ds_read_b128 v[190:193], v171 offset:54272
	ds_read_b128 v[194:197], v171 offset:55296
	ds_read_b128 v[198:201], v171 offset:56320
	global_load_lds_dwordx4 v[166:167], off
	v_lshl_add_u64 v[166:167], v[222:223], 0, s[28:29]
	s_mov_b32 m0, s49
	s_nop 0
	global_load_lds_dwordx4 v[166:167], off
	s_waitcnt vmcnt(10)
	s_barrier
	s_waitcnt lgkmcnt(0)
	s_waitcnt lgkmcnt(0)
	v_mfma_f32_16x16x32_bf16 v[62:65], v[130:133], v[146:149], v[62:65]
	v_mfma_f32_16x16x32_bf16 v[58:61], v[138:141], v[146:149], v[58:61]
	v_mfma_f32_16x16x32_bf16 v[50:53], v[130:133], v[178:181], v[50:53]
	v_mfma_f32_16x16x32_bf16 v[42:45], v[138:141], v[178:181], v[42:45]
	v_mfma_f32_16x16x32_bf16 v[34:37], v[130:133], v[186:189], v[34:37]
	v_mfma_f32_16x16x32_bf16 v[26:29], v[138:141], v[186:189], v[26:29]
	v_mfma_f32_16x16x32_bf16 v[18:21], v[130:133], v[194:197], v[18:21]
	v_mfma_f32_16x16x32_bf16 v[10:13], v[138:141], v[194:197], v[10:13]
	v_mfma_f32_16x16x32_bf16 v[62:65], v[134:137], v[174:177], v[62:65]
	v_mfma_f32_16x16x32_bf16 v[58:61], v[142:145], v[174:177], v[58:61]
	v_mfma_f32_16x16x32_bf16 v[50:53], v[134:137], v[182:185], v[50:53]
	v_mfma_f32_16x16x32_bf16 v[42:45], v[142:145], v[182:185], v[42:45]
	v_mfma_f32_16x16x32_bf16 v[34:37], v[134:137], v[190:193], v[34:37]
	v_mfma_f32_16x16x32_bf16 v[26:29], v[142:145], v[190:193], v[26:29]
	v_mfma_f32_16x16x32_bf16 v[18:21], v[134:137], v[198:201], v[18:21]
	v_mfma_f32_16x16x32_bf16 v[10:13], v[142:145], v[198:201], v[10:13]
	s_barrier
	s_add_u32 s0, s40, 0x40080
	s_addc_u32 s1, s41, 0
	s_add_i32 s40, s42, s5
	s_mov_b32 m0, s40
	s_nop 0
	global_load_lds_dwordx4 v158, s[0:1]
	s_add_i32 m0, s40, 0x2000
	s_nop 0
	global_load_lds_dwordx4 v154, s[0:1]
	s_waitcnt vmcnt(10)
	s_barrier
	v_mfma_f32_16x16x32_bf16 v[54:57], v[202:205], v[146:149], v[54:57]
	v_mfma_f32_16x16x32_bf16 v[46:49], v[210:213], v[146:149], v[46:49]
	v_mfma_f32_16x16x32_bf16 v[38:41], v[202:205], v[178:181], v[38:41]
	v_mfma_f32_16x16x32_bf16 v[30:33], v[210:213], v[178:181], v[30:33]
	v_mfma_f32_16x16x32_bf16 v[22:25], v[202:205], v[186:189], v[22:25]
	v_mfma_f32_16x16x32_bf16 v[14:17], v[210:213], v[186:189], v[14:17]
	v_mfma_f32_16x16x32_bf16 v[6:9], v[202:205], v[194:197], v[6:9]
	v_mfma_f32_16x16x32_bf16 v[2:5], v[210:213], v[194:197], v[2:5]
	v_mfma_f32_16x16x32_bf16 v[54:57], v[206:209], v[174:177], v[54:57]
	v_mfma_f32_16x16x32_bf16 v[46:49], v[214:217], v[174:177], v[46:49]
	v_mfma_f32_16x16x32_bf16 v[38:41], v[206:209], v[182:185], v[38:41]
	v_mfma_f32_16x16x32_bf16 v[30:33], v[214:217], v[182:185], v[30:33]
	v_mfma_f32_16x16x32_bf16 v[22:25], v[206:209], v[190:193], v[22:25]
	v_mfma_f32_16x16x32_bf16 v[14:17], v[214:217], v[190:193], v[14:17]
	v_mfma_f32_16x16x32_bf16 v[6:9], v[206:209], v[198:201], v[6:9]
	v_mfma_f32_16x16x32_bf16 v[2:5], v[214:217], v[198:201], v[2:5]
	s_add_i32 s69, s69, 2
	s_add_u32 s64, s64, 0x100
	s_addc_u32 s65, s65, 0
	s_add_u32 s38, s38, 0x100
	s_addc_u32 s39, s39, 0
	s_cmp_gt_u32 s69, 13
	s_barrier
	s_cbranch_scc0 .LBB0_1047

.LBB0_1290:
	v_bfe_u32 v196, v2, 4, 2
	v_and_b32_e32 v195, 15, v2
	v_lshlrev_b32_e32 v3, 4, v196
	v_lshlrev_b32_e32 v2, 2, v2
	v_lshl_or_b32 v3, v195, 6, v3
	s_lshl_b32 s0, s8, 13
	v_and_b32_e32 v2, 32, v2
	v_bitop3_b32 v8, v3, s0, v2 bitop3:0xde
	s_lshl_b32 s0, s1, 5
	v_mov_b32_e32 v165, v163
	s_and_b32 s50, s0, 0x60
	v_lshl_add_u64 v[4:5], s[34:35], 0, v[164:165]
	v_mov_b32_e32 v167, v163
	s_lshl_b32 s0, s50, 7
	v_lshl_add_u64 v[6:7], s[34:35], 0, v[166:167]
	v_bitop3_b32 v197, v3, s0, v2 bitop3:0xde
	s_add_i32 m0, s45, 0x18000
	v_lshl_add_u64 v[2:3], v[4:5], 0, s[22:23]
	v_mov_b32_e32 v169, v163
	s_lshl_b32 s49, s8, 6
	s_waitcnt vmcnt(4)
	s_barrier
	global_load_lds_dwordx4 v[2:3], off
	v_lshl_add_u64 v[2:3], v[6:7], 0, s[22:23]
	s_add_i32 m0, s45, 0x1a000
	s_add_i32 s51, s45, 0x8000
	s_add_i32 s52, s45, 0xa000
	v_mov_b32_e32 v171, v163
	global_load_lds_dwordx4 v[2:3], off
	v_lshl_add_u64 v[2:3], s[20:21], 0, v[168:169]
	s_mov_b32 m0, s51
	s_add_u32 s0, s34, 0x20080
	global_load_lds_dwordx4 v[2:3], off
	v_lshl_add_u64 v[2:3], s[20:21], 0, v[170:171]
	s_mov_b32 m0, s52
	s_addc_u32 s1, s35, 0
	global_load_lds_dwordx4 v[2:3], off
	s_add_i32 m0, s45, 0x1c000
	s_nop 0
	global_load_lds_dwordx4 v164, s[0:1]
	s_add_i32 m0, s45, 0x1e000
	s_mov_b32 s53, 0
	global_load_lds_dwordx4 v166, s[0:1]
	s_waitcnt vmcnt(6)
	v_add_u32_e32 v169, 0, v8
	s_barrier
	s_waitcnt vmcnt(0)

.LBB0_1301:
	s_ashr_i32 s0, s54, 5
	s_ashr_i32 s1, s0, 31
	s_lshl_b64 s[0:1], s[0:1], 21
	s_add_u32 s14, s4, s0
	s_addc_u32 s15, s5, s1
	s_ashr_i32 s27, s26, 31
	s_lshl_b64 s[0:1], s[26:27], 18
	s_add_u32 s14, s14, s0
	s_addc_u32 s15, s15, s1
	s_and_b64 s[0:1], s[12:13], exec
	s_cselect_b32 s27, s15, s35
	s_cselect_b32 s29, s14, s34
	v_mov_b32_e32 v173, v163
	v_mov_b32_e32 v175, v163
	s_add_u32 s31, s34, 0x100
	s_addc_u32 s55, s35, 0
	v_lshl_add_u64 v[176:177], s[20:21], 0, v[174:175]
	v_lshl_add_u64 v[178:179], s[20:21], 0, v[172:173]
	s_mov_b32 s56, -2
	s_mov_b64 s[36:37], 0
	s_add_u32 s12, s36, 0x100
	s_addc_u32 s13, s37, 0
	s_add_u32 s34, s31, s36
	s_addc_u32 s35, s55, s37
	s_cmpk_eq_i32 s36, 0x300
	s_cselect_b64 vcc, -1, 0
	s_and_b64 s[0:1], vcc, exec
	s_cselect_b32 s1, 0, s12
	s_cselect_b32 s0, 0, s13
	s_cselect_b32 s34, s29, s34
	s_cselect_b32 s35, s27, s35
	s_add_u32 s38, s16, s1
	s_addc_u32 s39, s17, s0
	s_add_i32 s1, 0, 0x10000
	v_add_u32_e32 v14, s1, v197
	ds_read_b128 v[2:5], v14
	ds_read_b128 v[6:9], v14 offset:1024
	ds_read_b128 v[10:13], v14 offset:2048
	ds_read_b128 v[14:17], v14 offset:3072
	v_cndmask_b32_e32 v162, v168, v171, vcc
	v_cndmask_b32_e32 v184, v170, v198, vcc
	v_cndmask_b32_e32 v175, v172, v199, vcc
	v_cndmask_b32_e32 v173, v174, v200, vcc
	v_lshl_add_u64 v[18:19], v[178:179], 0, s[36:37]
	s_add_i32 m0, s45, 0xc000
	ds_read_b128 v[202:205], v169
	ds_read_b128 v[206:209], v169 offset:1024
	ds_read_b128 v[210:213], v169 offset:2048
	ds_read_b128 v[214:217], v169 offset:3072
	ds_read_b128 v[218:221], v169 offset:4096
	ds_read_b128 v[222:225], v169 offset:5120
	ds_read_b128 v[226:229], v169 offset:6144
	ds_read_b128 v[230:233], v169 offset:7168
	global_load_lds_dwordx4 v[18:19], off
	v_lshl_add_u64 v[18:19], v[176:177], 0, s[36:37]
	s_add_i32 m0, s45, 0xe000
	s_nop 0
	global_load_lds_dwordx4 v[18:19], off
	s_waitcnt lgkmcnt(8)
	s_waitcnt vmcnt(10)
	s_barrier
	s_waitcnt lgkmcnt(0)
	s_waitcnt lgkmcnt(0)
	v_mfma_scale_f32_16x16x128_f8f6f4 v[158:161], v[2:9], v[202:209], 0, v188, v188 op_sel_hi:[0,0,0]
	v_mfma_scale_f32_16x16x128_f8f6f4 v[150:153], v[10:17], v[202:209], 0, v188, v188 op_sel_hi:[0,0,0]
	v_mfma_scale_f32_16x16x128_f8f6f4 v[142:145], v[2:9], v[210:217], 0, v188, v188 op_sel_hi:[0,0,0]
	v_mfma_scale_f32_16x16x128_f8f6f4 v[134:137], v[10:17], v[210:217], 0, v188, v188 op_sel_hi:[0,0,0]
	v_mfma_scale_f32_16x16x128_f8f6f4 v[126:129], v[2:9], v[218:225], 0, v188, v188 op_sel_hi:[0,0,0]
	v_mfma_scale_f32_16x16x128_f8f6f4 v[118:121], v[10:17], v[218:225], 0, v188, v188 op_sel_hi:[0,0,0]
	v_mfma_scale_f32_16x16x128_f8f6f4 v[110:113], v[2:9], v[226:233], 0, v188, v188 op_sel_hi:[0,0,0]
	v_mfma_scale_f32_16x16x128_f8f6f4 v[102:105], v[10:17], v[226:233], 0, v188, v188 op_sel_hi:[0,0,0]
	s_barrier
	s_add_i32 s0, 0, 0x14000
	s_add_i32 s1, s1, s43
	v_add_u32_e32 v30, s0, v197
	v_lshl_add_u64 v[180:181], s[34:35], 0, v[164:165]
	s_mov_b32 m0, s1
	ds_read_b128 v[18:21], v30
	ds_read_b128 v[22:25], v30 offset:1024
	ds_read_b128 v[26:29], v30 offset:2048
	ds_read_b128 v[30:33], v30 offset:3072
	global_load_lds_dwordx4 v[180:181], off
	v_lshl_add_u64 v[182:183], s[34:35], 0, v[166:167]
	s_add_i32 m0, s1, 0x2000
	s_nop 0
	global_load_lds_dwordx4 v[182:183], off
	s_waitcnt vmcnt(10)
	s_barrier
	s_waitcnt lgkmcnt(0)
	s_waitcnt lgkmcnt(0)
	v_mfma_scale_f32_16x16x128_f8f6f4 v[154:157], v[18:25], v[202:209], 0, v188, v188 op_sel_hi:[0,0,0]
	v_mfma_scale_f32_16x16x128_f8f6f4 v[146:149], v[26:33], v[202:209], 0, v188, v188 op_sel_hi:[0,0,0]
	v_mfma_scale_f32_16x16x128_f8f6f4 v[138:141], v[18:25], v[210:217], 0, v188, v188 op_sel_hi:[0,0,0]
	v_mfma_scale_f32_16x16x128_f8f6f4 v[130:133], v[26:33], v[210:217], 0, v188, v188 op_sel_hi:[0,0,0]
	v_mfma_scale_f32_16x16x128_f8f6f4 v[122:125], v[18:25], v[218:225], 0, v188, v188 op_sel_hi:[0,0,0]
	v_mfma_scale_f32_16x16x128_f8f6f4 v[114:117], v[26:33], v[218:225], 0, v188, v188 op_sel_hi:[0,0,0]
	v_mfma_scale_f32_16x16x128_f8f6f4 v[106:109], v[18:25], v[226:233], 0, v188, v188 op_sel_hi:[0,0,0]
	v_mfma_scale_f32_16x16x128_f8f6f4 v[98:101], v[26:33], v[226:233], 0, v188, v188 op_sel_hi:[0,0,0]
	s_mov_b32 m0, s45
	s_barrier
	ds_read_b128 v[202:205], v169 offset:16384
	ds_read_b128 v[206:209], v169 offset:17408
	ds_read_b128 v[210:213], v169 offset:18432
	ds_read_b128 v[214:217], v169 offset:19456
	ds_read_b128 v[218:221], v169 offset:20480
	ds_read_b128 v[222:225], v169 offset:21504
	ds_read_b128 v[226:229], v169 offset:22528
	ds_read_b128 v[230:233], v169 offset:23552
	global_load_lds_dwordx4 v162, s[38:39]
	s_mov_b32 m0, s46
	v_mov_b32_e32 v185, v163
	global_load_lds_dwordx4 v184, s[38:39]
	s_waitcnt vmcnt(10)
	s_barrier
	s_waitcnt lgkmcnt(0)
	v_lshl_add_u64 v[186:187], s[38:39], 0, v[162:163]
	v_lshl_add_u64 v[184:185], s[38:39], 0, v[184:185]
	s_waitcnt lgkmcnt(0)
	v_mfma_scale_f32_16x16x128_f8f6f4 v[94:97], v[2:9], v[202:209], 0, v188, v188 op_sel_hi:[0,0,0]
	v_mfma_scale_f32_16x16x128_f8f6f4 v[86:89], v[10:17], v[202:209], 0, v188, v188 op_sel_hi:[0,0,0]
	v_mfma_scale_f32_16x16x128_f8f6f4 v[78:81], v[2:9], v[210:217], 0, v188, v188 op_sel_hi:[0,0,0]
	v_mfma_scale_f32_16x16x128_f8f6f4 v[70:73], v[10:17], v[210:217], 0, v188, v188 op_sel_hi:[0,0,0]
	v_mfma_scale_f32_16x16x128_f8f6f4 v[62:65], v[2:9], v[218:225], 0, v188, v188 op_sel_hi:[0,0,0]
	v_mfma_scale_f32_16x16x128_f8f6f4 v[54:57], v[10:17], v[218:225], 0, v188, v188 op_sel_hi:[0,0,0]
	v_mfma_scale_f32_16x16x128_f8f6f4 v[46:49], v[2:9], v[226:233], 0, v188, v188 op_sel_hi:[0,0,0]
	v_mfma_scale_f32_16x16x128_f8f6f4 v[38:41], v[10:17], v[226:233], 0, v188, v188 op_sel_hi:[0,0,0]
	s_barrier
	s_add_u32 s36, s34, 0x20000
	s_addc_u32 s37, s35, 0
	s_add_i32 s0, s0, s43
	s_mov_b32 m0, s0
	s_nop 0
	global_load_lds_dwordx4 v164, s[36:37]
	s_add_i32 m0, s0, 0x2000
	s_nop 0
	global_load_lds_dwordx4 v166, s[36:37]
	s_waitcnt vmcnt(10)
	s_barrier
	v_mfma_scale_f32_16x16x128_f8f6f4 v[90:93], v[18:25], v[202:209], 0, v188, v188 op_sel_hi:[0,0,0]
	v_mfma_scale_f32_16x16x128_f8f6f4 v[82:85], v[26:33], v[202:209], 0, v188, v188 op_sel_hi:[0,0,0]
	v_mfma_scale_f32_16x16x128_f8f6f4 v[74:77], v[18:25], v[210:217], 0, v188, v188 op_sel_hi:[0,0,0]
	v_mfma_scale_f32_16x16x128_f8f6f4 v[66:69], v[26:33], v[210:217], 0, v188, v188 op_sel_hi:[0,0,0]
	v_mfma_scale_f32_16x16x128_f8f6f4 v[58:61], v[18:25], v[218:225], 0, v188, v188 op_sel_hi:[0,0,0]
	v_mfma_scale_f32_16x16x128_f8f6f4 v[50:53], v[26:33], v[218:225], 0, v188, v188 op_sel_hi:[0,0,0]
	v_mfma_scale_f32_16x16x128_f8f6f4 v[42:45], v[18:25], v[226:233], 0, v188, v188 op_sel_hi:[0,0,0]
	v_mfma_scale_f32_16x16x128_f8f6f4 v[34:37], v[26:33], v[226:233], 0, v188, v188 op_sel_hi:[0,0,0]
	s_add_i32 s0, 0, 0x18000
	v_add_u32_e32 v14, s0, v197
	s_barrier
	ds_read_b128 v[2:5], v14
	ds_read_b128 v[6:9], v14 offset:1024
	ds_read_b128 v[10:13], v14 offset:2048
	ds_read_b128 v[14:17], v14 offset:3072
	s_mov_b32 m0, s47
	ds_read_b128 v[18:21], v169 offset:32768
	ds_read_b128 v[22:25], v169 offset:33792
	ds_read_b128 v[26:29], v169 offset:34816
	ds_read_b128 v[30:33], v169 offset:35840
	ds_read_b128 v[202:205], v169 offset:36864
	ds_read_b128 v[206:209], v169 offset:37888
	ds_read_b128 v[210:213], v169 offset:38912
	ds_read_b128 v[214:217], v169 offset:39936
	global_load_lds_dwordx4 v175, s[38:39]
	s_mov_b32 m0, s48
	s_nop 0
	global_load_lds_dwordx4 v173, s[38:39]
	s_waitcnt lgkmcnt(8)
	s_waitcnt vmcnt(10)
	s_barrier
	s_waitcnt lgkmcnt(0)
	s_waitcnt lgkmcnt(0)
	v_mfma_scale_f32_16x16x128_f8f6f4 v[158:161], v[2:9], v[18:25], v[158:161], v188, v188 op_sel_hi:[0,0,0]
	v_mfma_scale_f32_16x16x128_f8f6f4 v[150:153], v[10:17], v[18:25], v[150:153], v188, v188 op_sel_hi:[0,0,0]
	v_mfma_scale_f32_16x16x128_f8f6f4 v[142:145], v[2:9], v[26:33], v[142:145], v188, v188 op_sel_hi:[0,0,0]
	v_mfma_scale_f32_16x16x128_f8f6f4 v[134:137], v[10:17], v[26:33], v[134:137], v188, v188 op_sel_hi:[0,0,0]
	v_mfma_scale_f32_16x16x128_f8f6f4 v[126:129], v[2:9], v[202:209], v[126:129], v188, v188 op_sel_hi:[0,0,0]
	v_mfma_scale_f32_16x16x128_f8f6f4 v[118:121], v[10:17], v[202:209], v[118:121], v188, v188 op_sel_hi:[0,0,0]
	v_mfma_scale_f32_16x16x128_f8f6f4 v[110:113], v[2:9], v[210:217], v[110:113], v188, v188 op_sel_hi:[0,0,0]
	v_mfma_scale_f32_16x16x128_f8f6f4 v[102:105], v[10:17], v[210:217], v[102:105], v188, v188 op_sel_hi:[0,0,0]
	s_barrier
	s_add_i32 s36, 0, 0x1c000
	s_add_i32 s0, s0, s43
	v_add_u32_e32 v162, s36, v197
	v_lshl_add_u64 v[180:181], v[180:181], 0, s[22:23]
	s_mov_b32 m0, s0
	ds_read_b128 v[218:221], v162
	ds_read_b128 v[222:225], v162 offset:1024
	ds_read_b128 v[226:229], v162 offset:2048
	ds_read_b128 v[230:233], v162 offset:3072
	global_load_lds_dwordx4 v[180:181], off
	v_lshl_add_u64 v[180:181], v[182:183], 0, s[22:23]
	s_add_i32 m0, s0, 0x2000
	s_nop 0
	global_load_lds_dwordx4 v[180:181], off
	s_waitcnt vmcnt(10)
	s_barrier
	s_waitcnt lgkmcnt(0)
	s_waitcnt lgkmcnt(0)
	v_mfma_scale_f32_16x16x128_f8f6f4 v[154:157], v[218:225], v[18:25], v[154:157], v188, v188 op_sel_hi:[0,0,0]
	v_mfma_scale_f32_16x16x128_f8f6f4 v[146:149], v[226:233], v[18:25], v[146:149], v188, v188 op_sel_hi:[0,0,0]
	v_mfma_scale_f32_16x16x128_f8f6f4 v[138:141], v[218:225], v[26:33], v[138:141], v188, v188 op_sel_hi:[0,0,0]
	v_mfma_scale_f32_16x16x128_f8f6f4 v[130:133], v[226:233], v[26:33], v[130:133], v188, v188 op_sel_hi:[0,0,0]
	v_mfma_scale_f32_16x16x128_f8f6f4 v[122:125], v[218:225], v[202:209], v[122:125], v188, v188 op_sel_hi:[0,0,0]
	v_mfma_scale_f32_16x16x128_f8f6f4 v[114:117], v[226:233], v[202:209], v[114:117], v188, v188 op_sel_hi:[0,0,0]
	v_mfma_scale_f32_16x16x128_f8f6f4 v[106:109], v[218:225], v[210:217], v[106:109], v188, v188 op_sel_hi:[0,0,0]
	v_mfma_scale_f32_16x16x128_f8f6f4 v[98:101], v[226:233], v[210:217], v[98:101], v188, v188 op_sel_hi:[0,0,0]
	s_mov_b32 m0, s51
	v_lshl_add_u64 v[180:181], v[186:187], 0, s[22:23]
	s_barrier
	ds_read_b128 v[18:21], v169 offset:49152
	ds_read_b128 v[22:25], v169 offset:50176
	ds_read_b128 v[26:29], v169 offset:51200
	ds_read_b128 v[30:33], v169 offset:52224
	ds_read_b128 v[202:205], v169 offset:53248
	ds_read_b128 v[206:209], v169 offset:54272
	ds_read_b128 v[210:213], v169 offset:55296
	ds_read_b128 v[214:217], v169 offset:56320
	global_load_lds_dwordx4 v[180:181], off
	v_lshl_add_u64 v[180:181], v[184:185], 0, s[22:23]
	s_mov_b32 m0, s52
	s_nop 0
	global_load_lds_dwordx4 v[180:181], off
	s_waitcnt vmcnt(10)
	s_barrier
	s_waitcnt lgkmcnt(0)
	s_waitcnt lgkmcnt(0)
	v_mfma_scale_f32_16x16x128_f8f6f4 v[94:97], v[2:9], v[18:25], v[94:97], v188, v188 op_sel_hi:[0,0,0]
	v_mfma_scale_f32_16x16x128_f8f6f4 v[86:89], v[10:17], v[18:25], v[86:89], v188, v188 op_sel_hi:[0,0,0]
	v_mfma_scale_f32_16x16x128_f8f6f4 v[78:81], v[2:9], v[26:33], v[78:81], v188, v188 op_sel_hi:[0,0,0]
	v_mfma_scale_f32_16x16x128_f8f6f4 v[70:73], v[10:17], v[26:33], v[70:73], v188, v188 op_sel_hi:[0,0,0]
	v_mfma_scale_f32_16x16x128_f8f6f4 v[62:65], v[2:9], v[202:209], v[62:65], v188, v188 op_sel_hi:[0,0,0]
	v_mfma_scale_f32_16x16x128_f8f6f4 v[54:57], v[10:17], v[202:209], v[54:57], v188, v188 op_sel_hi:[0,0,0]
	v_mfma_scale_f32_16x16x128_f8f6f4 v[46:49], v[2:9], v[210:217], v[46:49], v188, v188 op_sel_hi:[0,0,0]
	v_mfma_scale_f32_16x16x128_f8f6f4 v[38:41], v[10:17], v[210:217], v[38:41], v188, v188 op_sel_hi:[0,0,0]
	s_barrier
	s_add_u32 s0, s34, 0x20080
	s_addc_u32 s1, s35, 0
	s_add_i32 s34, s36, s43
	s_mov_b32 m0, s34
	s_nop 0
	global_load_lds_dwordx4 v164, s[0:1]
	s_add_i32 m0, s34, 0x2000
	s_nop 0
	global_load_lds_dwordx4 v166, s[0:1]
	s_waitcnt vmcnt(10)
	s_barrier
	v_mfma_scale_f32_16x16x128_f8f6f4 v[90:93], v[218:225], v[18:25], v[90:93], v188, v188 op_sel_hi:[0,0,0]
	v_mfma_scale_f32_16x16x128_f8f6f4 v[82:85], v[226:233], v[18:25], v[82:85], v188, v188 op_sel_hi:[0,0,0]
	v_mfma_scale_f32_16x16x128_f8f6f4 v[74:77], v[218:225], v[26:33], v[74:77], v188, v188 op_sel_hi:[0,0,0]
	v_mfma_scale_f32_16x16x128_f8f6f4 v[66:69], v[226:233], v[26:33], v[66:69], v188, v188 op_sel_hi:[0,0,0]
	v_mfma_scale_f32_16x16x128_f8f6f4 v[58:61], v[218:225], v[202:209], v[58:61], v188, v188 op_sel_hi:[0,0,0]
	v_mfma_scale_f32_16x16x128_f8f6f4 v[50:53], v[226:233], v[202:209], v[50:53], v188, v188 op_sel_hi:[0,0,0]
	v_mfma_scale_f32_16x16x128_f8f6f4 v[42:45], v[218:225], v[210:217], v[42:45], v188, v188 op_sel_hi:[0,0,0]
	v_mfma_scale_f32_16x16x128_f8f6f4 v[34:37], v[226:233], v[210:217], v[34:37], v188, v188 op_sel_hi:[0,0,0]
	s_add_i32 s56, s56, 2
	s_cmp_gt_u32 s56, 5
	s_mov_b64 s[36:37], s[12:13]
	s_barrier
	s_cbranch_scc1 .Lpeel_exit_6
.LBB0_1302:
	s_add_u32 s12, s36, 0x100
	s_addc_u32 s13, s37, 0
	s_add_u32 s34, s31, s36
	s_addc_u32 s35, s55, s37
	s_cmpk_eq_i32 s36, 0x300
	s_cselect_b64 vcc, -1, 0
	s_and_b64 s[0:1], vcc, exec
	s_cselect_b32 s1, 0, s12
	s_cselect_b32 s0, 0, s13
	s_cselect_b32 s34, s29, s34
	s_cselect_b32 s35, s27, s35
	s_add_u32 s38, s16, s1
	s_addc_u32 s39, s17, s0
	s_add_i32 s1, 0, 0x10000
	v_add_u32_e32 v14, s1, v197
	ds_read_b128 v[2:5], v14
	ds_read_b128 v[6:9], v14 offset:1024
	ds_read_b128 v[10:13], v14 offset:2048
	ds_read_b128 v[14:17], v14 offset:3072
	v_cndmask_b32_e32 v162, v168, v171, vcc
	v_cndmask_b32_e32 v184, v170, v198, vcc
	v_cndmask_b32_e32 v175, v172, v199, vcc
	v_cndmask_b32_e32 v173, v174, v200, vcc
	v_lshl_add_u64 v[18:19], v[178:179], 0, s[36:37]
	s_add_i32 m0, s45, 0xc000
	ds_read_b128 v[202:205], v169
	ds_read_b128 v[206:209], v169 offset:1024
	ds_read_b128 v[210:213], v169 offset:2048
	ds_read_b128 v[214:217], v169 offset:3072
	ds_read_b128 v[218:221], v169 offset:4096
	ds_read_b128 v[222:225], v169 offset:5120
	ds_read_b128 v[226:229], v169 offset:6144
	ds_read_b128 v[230:233], v169 offset:7168
	global_load_lds_dwordx4 v[18:19], off
	v_lshl_add_u64 v[18:19], v[176:177], 0, s[36:37]
	s_add_i32 m0, s45, 0xe000
	s_nop 0
	global_load_lds_dwordx4 v[18:19], off
	s_waitcnt lgkmcnt(8)
	s_waitcnt vmcnt(10)
	s_barrier
	s_waitcnt lgkmcnt(0)
	s_waitcnt lgkmcnt(0)
	v_mfma_scale_f32_16x16x128_f8f6f4 v[158:161], v[2:9], v[202:209], v[158:161], v188, v188 op_sel_hi:[0,0,0]
	v_mfma_scale_f32_16x16x128_f8f6f4 v[150:153], v[10:17], v[202:209], v[150:153], v188, v188 op_sel_hi:[0,0,0]
	v_mfma_scale_f32_16x16x128_f8f6f4 v[142:145], v[2:9], v[210:217], v[142:145], v188, v188 op_sel_hi:[0,0,0]
	v_mfma_scale_f32_16x16x128_f8f6f4 v[134:137], v[10:17], v[210:217], v[134:137], v188, v188 op_sel_hi:[0,0,0]
	v_mfma_scale_f32_16x16x128_f8f6f4 v[126:129], v[2:9], v[218:225], v[126:129], v188, v188 op_sel_hi:[0,0,0]
	v_mfma_scale_f32_16x16x128_f8f6f4 v[118:121], v[10:17], v[218:225], v[118:121], v188, v188 op_sel_hi:[0,0,0]
	v_mfma_scale_f32_16x16x128_f8f6f4 v[110:113], v[2:9], v[226:233], v[110:113], v188, v188 op_sel_hi:[0,0,0]
	v_mfma_scale_f32_16x16x128_f8f6f4 v[102:105], v[10:17], v[226:233], v[102:105], v188, v188 op_sel_hi:[0,0,0]
	s_barrier
	s_add_i32 s0, 0, 0x14000
	s_add_i32 s1, s1, s43
	v_add_u32_e32 v30, s0, v197
	v_lshl_add_u64 v[180:181], s[34:35], 0, v[164:165]
	s_mov_b32 m0, s1
	ds_read_b128 v[18:21], v30
	ds_read_b128 v[22:25], v30 offset:1024
	ds_read_b128 v[26:29], v30 offset:2048
	ds_read_b128 v[30:33], v30 offset:3072
	global_load_lds_dwordx4 v[180:181], off
	v_lshl_add_u64 v[182:183], s[34:35], 0, v[166:167]
	s_add_i32 m0, s1, 0x2000
	s_nop 0
	global_load_lds_dwordx4 v[182:183], off
	s_waitcnt vmcnt(10)
	s_barrier
	s_waitcnt lgkmcnt(0)
	s_waitcnt lgkmcnt(0)
	v_mfma_scale_f32_16x16x128_f8f6f4 v[154:157], v[18:25], v[202:209], v[154:157], v188, v188 op_sel_hi:[0,0,0]
	v_mfma_scale_f32_16x16x128_f8f6f4 v[146:149], v[26:33], v[202:209], v[146:149], v188, v188 op_sel_hi:[0,0,0]
	v_mfma_scale_f32_16x16x128_f8f6f4 v[138:141], v[18:25], v[210:217], v[138:141], v188, v188 op_sel_hi:[0,0,0]
	v_mfma_scale_f32_16x16x128_f8f6f4 v[130:133], v[26:33], v[210:217], v[130:133], v188, v188 op_sel_hi:[0,0,0]
	v_mfma_scale_f32_16x16x128_f8f6f4 v[122:125], v[18:25], v[218:225], v[122:125], v188, v188 op_sel_hi:[0,0,0]
	v_mfma_scale_f32_16x16x128_f8f6f4 v[114:117], v[26:33], v[218:225], v[114:117], v188, v188 op_sel_hi:[0,0,0]
	v_mfma_scale_f32_16x16x128_f8f6f4 v[106:109], v[18:25], v[226:233], v[106:109], v188, v188 op_sel_hi:[0,0,0]
	v_mfma_scale_f32_16x16x128_f8f6f4 v[98:101], v[26:33], v[226:233], v[98:101], v188, v188 op_sel_hi:[0,0,0]
	s_mov_b32 m0, s45
	s_barrier
	ds_read_b128 v[202:205], v169 offset:16384
	ds_read_b128 v[206:209], v169 offset:17408
	ds_read_b128 v[210:213], v169 offset:18432
	ds_read_b128 v[214:217], v169 offset:19456
	ds_read_b128 v[218:221], v169 offset:20480
	ds_read_b128 v[222:225], v169 offset:21504
	ds_read_b128 v[226:229], v169 offset:22528
	ds_read_b128 v[230:233], v169 offset:23552
	global_load_lds_dwordx4 v162, s[38:39]
	s_mov_b32 m0, s46
	v_mov_b32_e32 v185, v163
	global_load_lds_dwordx4 v184, s[38:39]
	s_waitcnt vmcnt(10)
	s_barrier
	s_waitcnt lgkmcnt(0)
	v_lshl_add_u64 v[186:187], s[38:39], 0, v[162:163]
	v_lshl_add_u64 v[184:185], s[38:39], 0, v[184:185]
	s_waitcnt lgkmcnt(0)
	v_mfma_scale_f32_16x16x128_f8f6f4 v[94:97], v[2:9], v[202:209], v[94:97], v188, v188 op_sel_hi:[0,0,0]
	v_mfma_scale_f32_16x16x128_f8f6f4 v[86:89], v[10:17], v[202:209], v[86:89], v188, v188 op_sel_hi:[0,0,0]
	v_mfma_scale_f32_16x16x128_f8f6f4 v[78:81], v[2:9], v[210:217], v[78:81], v188, v188 op_sel_hi:[0,0,0]
	v_mfma_scale_f32_16x16x128_f8f6f4 v[70:73], v[10:17], v[210:217], v[70:73], v188, v188 op_sel_hi:[0,0,0]
	v_mfma_scale_f32_16x16x128_f8f6f4 v[62:65], v[2:9], v[218:225], v[62:65], v188, v188 op_sel_hi:[0,0,0]
	v_mfma_scale_f32_16x16x128_f8f6f4 v[54:57], v[10:17], v[218:225], v[54:57], v188, v188 op_sel_hi:[0,0,0]
	v_mfma_scale_f32_16x16x128_f8f6f4 v[46:49], v[2:9], v[226:233], v[46:49], v188, v188 op_sel_hi:[0,0,0]
	v_mfma_scale_f32_16x16x128_f8f6f4 v[38:41], v[10:17], v[226:233], v[38:41], v188, v188 op_sel_hi:[0,0,0]
	s_barrier
	s_add_u32 s36, s34, 0x20000
	s_addc_u32 s37, s35, 0
	s_add_i32 s0, s0, s43
	s_mov_b32 m0, s0
	s_nop 0
	global_load_lds_dwordx4 v164, s[36:37]
	s_add_i32 m0, s0, 0x2000
	s_nop 0
	global_load_lds_dwordx4 v166, s[36:37]
	s_waitcnt vmcnt(10)
	s_barrier
	v_mfma_scale_f32_16x16x128_f8f6f4 v[90:93], v[18:25], v[202:209], v[90:93], v188, v188 op_sel_hi:[0,0,0]
	v_mfma_scale_f32_16x16x128_f8f6f4 v[82:85], v[26:33], v[202:209], v[82:85], v188, v188 op_sel_hi:[0,0,0]
	v_mfma_scale_f32_16x16x128_f8f6f4 v[74:77], v[18:25], v[210:217], v[74:77], v188, v188 op_sel_hi:[0,0,0]
	v_mfma_scale_f32_16x16x128_f8f6f4 v[66:69], v[26:33], v[210:217], v[66:69], v188, v188 op_sel_hi:[0,0,0]
	v_mfma_scale_f32_16x16x128_f8f6f4 v[58:61], v[18:25], v[218:225], v[58:61], v188, v188 op_sel_hi:[0,0,0]
	v_mfma_scale_f32_16x16x128_f8f6f4 v[50:53], v[26:33], v[218:225], v[50:53], v188, v188 op_sel_hi:[0,0,0]
	v_mfma_scale_f32_16x16x128_f8f6f4 v[42:45], v[18:25], v[226:233], v[42:45], v188, v188 op_sel_hi:[0,0,0]
	v_mfma_scale_f32_16x16x128_f8f6f4 v[34:37], v[26:33], v[226:233], v[34:37], v188, v188 op_sel_hi:[0,0,0]
	s_add_i32 s0, 0, 0x18000
	v_add_u32_e32 v14, s0, v197
	s_barrier
	ds_read_b128 v[2:5], v14
	ds_read_b128 v[6:9], v14 offset:1024
	ds_read_b128 v[10:13], v14 offset:2048
	ds_read_b128 v[14:17], v14 offset:3072
	s_mov_b32 m0, s47
	ds_read_b128 v[18:21], v169 offset:32768
	ds_read_b128 v[22:25], v169 offset:33792
	ds_read_b128 v[26:29], v169 offset:34816
	ds_read_b128 v[30:33], v169 offset:35840
	ds_read_b128 v[202:205], v169 offset:36864
	ds_read_b128 v[206:209], v169 offset:37888
	ds_read_b128 v[210:213], v169 offset:38912
	ds_read_b128 v[214:217], v169 offset:39936
	global_load_lds_dwordx4 v175, s[38:39]
	s_mov_b32 m0, s48
	s_nop 0
	global_load_lds_dwordx4 v173, s[38:39]
	s_waitcnt lgkmcnt(8)
	s_waitcnt vmcnt(10)
	s_barrier
	s_waitcnt lgkmcnt(0)
	s_waitcnt lgkmcnt(0)
	v_mfma_scale_f32_16x16x128_f8f6f4 v[158:161], v[2:9], v[18:25], v[158:161], v188, v188 op_sel_hi:[0,0,0]
	v_mfma_scale_f32_16x16x128_f8f6f4 v[150:153], v[10:17], v[18:25], v[150:153], v188, v188 op_sel_hi:[0,0,0]
	v_mfma_scale_f32_16x16x128_f8f6f4 v[142:145], v[2:9], v[26:33], v[142:145], v188, v188 op_sel_hi:[0,0,0]
	v_mfma_scale_f32_16x16x128_f8f6f4 v[134:137], v[10:17], v[26:33], v[134:137], v188, v188 op_sel_hi:[0,0,0]
	v_mfma_scale_f32_16x16x128_f8f6f4 v[126:129], v[2:9], v[202:209], v[126:129], v188, v188 op_sel_hi:[0,0,0]
	v_mfma_scale_f32_16x16x128_f8f6f4 v[118:121], v[10:17], v[202:209], v[118:121], v188, v188 op_sel_hi:[0,0,0]
	v_mfma_scale_f32_16x16x128_f8f6f4 v[110:113], v[2:9], v[210:217], v[110:113], v188, v188 op_sel_hi:[0,0,0]
	v_mfma_scale_f32_16x16x128_f8f6f4 v[102:105], v[10:17], v[210:217], v[102:105], v188, v188 op_sel_hi:[0,0,0]
	s_barrier
	s_add_i32 s36, 0, 0x1c000
	s_add_i32 s0, s0, s43
	v_add_u32_e32 v162, s36, v197
	v_lshl_add_u64 v[180:181], v[180:181], 0, s[22:23]
	s_mov_b32 m0, s0
	ds_read_b128 v[218:221], v162
	ds_read_b128 v[222:225], v162 offset:1024
	ds_read_b128 v[226:229], v162 offset:2048
	ds_read_b128 v[230:233], v162 offset:3072
	global_load_lds_dwordx4 v[180:181], off
	v_lshl_add_u64 v[180:181], v[182:183], 0, s[22:23]
	s_add_i32 m0, s0, 0x2000
	s_nop 0
	global_load_lds_dwordx4 v[180:181], off
	s_waitcnt vmcnt(10)
	s_barrier
	s_waitcnt lgkmcnt(0)
	s_waitcnt lgkmcnt(0)
	v_mfma_scale_f32_16x16x128_f8f6f4 v[154:157], v[218:225], v[18:25], v[154:157], v188, v188 op_sel_hi:[0,0,0]
	v_mfma_scale_f32_16x16x128_f8f6f4 v[146:149], v[226:233], v[18:25], v[146:149], v188, v188 op_sel_hi:[0,0,0]
	v_mfma_scale_f32_16x16x128_f8f6f4 v[138:141], v[218:225], v[26:33], v[138:141], v188, v188 op_sel_hi:[0,0,0]
	v_mfma_scale_f32_16x16x128_f8f6f4 v[130:133], v[226:233], v[26:33], v[130:133], v188, v188 op_sel_hi:[0,0,0]
	v_mfma_scale_f32_16x16x128_f8f6f4 v[122:125], v[218:225], v[202:209], v[122:125], v188, v188 op_sel_hi:[0,0,0]
	v_mfma_scale_f32_16x16x128_f8f6f4 v[114:117], v[226:233], v[202:209], v[114:117], v188, v188 op_sel_hi:[0,0,0]
	v_mfma_scale_f32_16x16x128_f8f6f4 v[106:109], v[218:225], v[210:217], v[106:109], v188, v188 op_sel_hi:[0,0,0]
	v_mfma_scale_f32_16x16x128_f8f6f4 v[98:101], v[226:233], v[210:217], v[98:101], v188, v188 op_sel_hi:[0,0,0]
	s_mov_b32 m0, s51
	v_lshl_add_u64 v[180:181], v[186:187], 0, s[22:23]
	s_barrier
	ds_read_b128 v[18:21], v169 offset:49152
	ds_read_b128 v[22:25], v169 offset:50176
	ds_read_b128 v[26:29], v169 offset:51200
	ds_read_b128 v[30:33], v169 offset:52224
	ds_read_b128 v[202:205], v169 offset:53248
	ds_read_b128 v[206:209], v169 offset:54272
	ds_read_b128 v[210:213], v169 offset:55296
	ds_read_b128 v[214:217], v169 offset:56320
	global_load_lds_dwordx4 v[180:181], off
	v_lshl_add_u64 v[180:181], v[184:185], 0, s[22:23]
	s_mov_b32 m0, s52
	s_nop 0
	global_load_lds_dwordx4 v[180:181], off
	s_waitcnt vmcnt(10)
	s_barrier
	s_waitcnt lgkmcnt(0)
	s_waitcnt lgkmcnt(0)
	v_mfma_scale_f32_16x16x128_f8f6f4 v[94:97], v[2:9], v[18:25], v[94:97], v188, v188 op_sel_hi:[0,0,0]
	v_mfma_scale_f32_16x16x128_f8f6f4 v[86:89], v[10:17], v[18:25], v[86:89], v188, v188 op_sel_hi:[0,0,0]
	v_mfma_scale_f32_16x16x128_f8f6f4 v[78:81], v[2:9], v[26:33], v[78:81], v188, v188 op_sel_hi:[0,0,0]
	v_mfma_scale_f32_16x16x128_f8f6f4 v[70:73], v[10:17], v[26:33], v[70:73], v188, v188 op_sel_hi:[0,0,0]
	v_mfma_scale_f32_16x16x128_f8f6f4 v[62:65], v[2:9], v[202:209], v[62:65], v188, v188 op_sel_hi:[0,0,0]
	v_mfma_scale_f32_16x16x128_f8f6f4 v[54:57], v[10:17], v[202:209], v[54:57], v188, v188 op_sel_hi:[0,0,0]
	v_mfma_scale_f32_16x16x128_f8f6f4 v[46:49], v[2:9], v[210:217], v[46:49], v188, v188 op_sel_hi:[0,0,0]
	v_mfma_scale_f32_16x16x128_f8f6f4 v[38:41], v[10:17], v[210:217], v[38:41], v188, v188 op_sel_hi:[0,0,0]
	s_barrier
	s_add_u32 s0, s34, 0x20080
	s_addc_u32 s1, s35, 0
	s_add_i32 s34, s36, s43
	s_mov_b32 m0, s34
	s_nop 0
	global_load_lds_dwordx4 v164, s[0:1]
	s_add_i32 m0, s34, 0x2000
	s_nop 0
	global_load_lds_dwordx4 v166, s[0:1]
	s_waitcnt vmcnt(10)
	s_barrier
	v_mfma_scale_f32_16x16x128_f8f6f4 v[90:93], v[218:225], v[18:25], v[90:93], v188, v188 op_sel_hi:[0,0,0]
	v_mfma_scale_f32_16x16x128_f8f6f4 v[82:85], v[226:233], v[18:25], v[82:85], v188, v188 op_sel_hi:[0,0,0]
	v_mfma_scale_f32_16x16x128_f8f6f4 v[74:77], v[218:225], v[26:33], v[74:77], v188, v188 op_sel_hi:[0,0,0]
	v_mfma_scale_f32_16x16x128_f8f6f4 v[66:69], v[226:233], v[26:33], v[66:69], v188, v188 op_sel_hi:[0,0,0]
	v_mfma_scale_f32_16x16x128_f8f6f4 v[58:61], v[218:225], v[202:209], v[58:61], v188, v188 op_sel_hi:[0,0,0]
	v_mfma_scale_f32_16x16x128_f8f6f4 v[50:53], v[226:233], v[202:209], v[50:53], v188, v188 op_sel_hi:[0,0,0]
	v_mfma_scale_f32_16x16x128_f8f6f4 v[42:45], v[218:225], v[210:217], v[42:45], v188, v188 op_sel_hi:[0,0,0]
	v_mfma_scale_f32_16x16x128_f8f6f4 v[34:37], v[226:233], v[210:217], v[34:37], v188, v188 op_sel_hi:[0,0,0]
	s_add_i32 s56, s56, 2
	s_cmp_gt_u32 s56, 5
	s_mov_b64 s[36:37], s[12:13]
	s_barrier
	s_cbranch_scc0 .LBB0_1302

.LBB0_1361:
	s_add_u32 s12, s14, 0x12100000
	s_addc_u32 s13, s15, 0
	s_lshl_b32 s0, s0, 5
	s_mov_b64 s[14:15], 0x80
	s_and_b32 s42, s0, 0x60
	s_add_i32 m0, s17, 0x18000
	v_lshl_add_u64 v[4:5], v[4:5], 0, s[14:15]
	s_lshl_b32 s41, s1, 6
	s_lshl_b32 s9, s1, 13
	s_lshl_b32 s16, s42, 7
	s_waitcnt vmcnt(4)
	s_barrier
	global_load_lds_dwordx4 v[4:5], off
	s_add_i32 m0, s17, 0x1a000
	s_add_u32 s0, s30, 0x8000
	v_lshl_add_u64 v[2:3], v[2:3], 0, s[14:15]
	s_addc_u32 s1, s31, 0
	s_add_i32 s43, s17, 0x8000
	global_load_lds_dwordx4 v[2:3], off
	s_mov_b32 m0, s43
	s_add_i32 s44, s17, 0xa000
	global_load_lds_dwordx4 v152, s[0:1]
	v_lshl_add_u64 v[2:3], s[0:1], 0, v[148:149]
	s_add_u32 s0, s28, 0x20080
	s_mov_b32 m0, s44
	s_addc_u32 s1, s29, 0
	global_load_lds_dwordx4 v[2:3], off
	s_add_i32 m0, s17, 0x1c000
	s_nop 0
	global_load_lds_dwordx4 v150, s[0:1]
	s_add_i32 m0, s17, 0x1e000
	v_bfe_u32 v167, v6, 4, 2
	global_load_lds_dwordx4 v146, s[0:1]
	v_and_b32_e32 v166, 15, v6
	v_lshlrev_b32_e32 v2, 4, v167
	v_lshlrev_b32_e32 v3, 2, v6
	v_lshl_or_b32 v2, v166, 6, v2
	v_and_b32_e32 v3, 32, v3
	v_bitop3_b32 v4, v2, s9, v3 bitop3:0xde
	v_bitop3_b32 v168, v2, s16, v3 bitop3:0xde
	v_lshlrev_b32_e32 v2, 10, v7
	v_and_b32_e32 v2, 0xfffff800, v2
	v_lshl_add_u32 v2, v8, 7, v2
	v_and_b32_e32 v3, 1, v7
	v_lshl_or_b32 v2, v3, 6, v2
	v_lshl_add_u32 v154, v9, 1, v2
	v_lshlrev_b32_e32 v2, 10, v11
	v_and_b32_e32 v2, 0xfffff800, v2
	s_waitcnt vmcnt(6)
	v_lshl_add_u32 v2, v10, 7, v2
	v_and_b32_e32 v3, 1, v11
	v_lshl_or_b32 v2, v3, 6, v2
	s_add_i32 s45, 0, 0x10000
	s_add_i32 s46, 0, 0x14000
	s_sext_i32_i8 s48, s8
	v_mov_b32_e32 v155, v151
	v_lshl_add_u32 v156, v12, 1, v2
	v_mov_b32_e32 v157, v151
	v_mov_b64_e32 v[158:159], 0x800
	v_mov_b64_e32 v[160:161], 0x7ff
	v_add_u32_e32 v169, s45, v168
	v_add_u32_e32 v170, 0, v4
	v_mov_b32_e32 v171, 0x7f7f7f7f
	v_add_u32_e32 v172, s46, v168
	s_mov_b32 s16, 0x3d000000
	s_mov_b32 s47, 0xc3d00000
	v_mov_b32_e32 v173, 0x43d00000
	s_barrier

.LBB0_1368:
	s_ashr_i32 s21, s20, 31
	s_lshl_b64 s[0:1], s[20:21], 18
	v_cmp_lt_i64_e32 vcc, s[22:23], v[158:159]
	s_add_u32 s22, s5, s0
	s_addc_u32 s23, s6, s1
	s_and_b64 s[0:1], vcc, exec
	s_cselect_b32 s21, s23, s31
	s_cselect_b32 s49, s22, s30
	s_ashr_i32 s0, s20, 5
	s_ashr_i32 s1, s0, 31
	s_lshl_b64 s[0:1], s[0:1], 20
	s_add_u32 s24, s7, s0
	s_addc_u32 s25, s10, s1
	s_ashr_i32 s19, s18, 31
	s_lshl_b64 s[0:1], s[18:19], 18
	s_add_u32 s24, s24, s0
	s_addc_u32 s25, s25, s1
	s_and_b64 s[0:1], vcc, exec
	s_cselect_b32 s19, s25, s29
	s_cselect_b32 s50, s24, s28
	s_add_u32 s51, s28, 0x100
	s_addc_u32 s52, s29, 0
	s_add_u32 s28, s30, 0xc000
	s_addc_u32 s29, s31, 0
	s_mov_b32 s53, -2
	ds_read_b128 v[2:5], v169
	ds_read_b128 v[6:9], v169 offset:1024
	ds_read_b128 v[10:13], v169 offset:2048
	ds_read_b128 v[14:17], v169 offset:3072
	s_add_u32 s0, s28, 0x4000
	s_addc_u32 s1, s29, 0
	s_cmp_eq_u32 s53, 4
	s_cselect_b32 s36, s49, s0
	s_cselect_b32 s37, s21, s1
	s_cselect_b32 s30, s50, s51
	s_cselect_b32 s31, s19, s52
	s_add_u32 s34, s36, 0x8000
	s_addc_u32 s35, s37, 0
	s_add_i32 m0, s17, 0xc000
	ds_read_b128 v[174:177], v170
	ds_read_b128 v[178:181], v170 offset:1024
	ds_read_b128 v[182:185], v170 offset:2048
	ds_read_b128 v[186:189], v170 offset:3072
	ds_read_b128 v[190:193], v170 offset:4096
	ds_read_b128 v[194:197], v170 offset:5120
	ds_read_b128 v[198:201], v170 offset:6144
	ds_read_b128 v[202:205], v170 offset:7168
	global_load_lds_dwordx4 v156, s[28:29]
	s_add_i32 m0, s17, 0xe000
	s_nop 0
	global_load_lds_dwordx4 v154, s[28:29]
	s_waitcnt lgkmcnt(8)
	s_waitcnt vmcnt(10)
	s_barrier
	s_waitcnt lgkmcnt(0)
	s_waitcnt lgkmcnt(0)
	v_mfma_scale_f32_16x16x128_f8f6f4 v[142:145], v[2:9], v[174:181], 0, v171, v171 op_sel_hi:[0,0,0]
	v_mfma_scale_f32_16x16x128_f8f6f4 v[138:141], v[10:17], v[174:181], 0, v171, v171 op_sel_hi:[0,0,0]
	v_mfma_scale_f32_16x16x128_f8f6f4 v[126:129], v[2:9], v[182:189], 0, v171, v171 op_sel_hi:[0,0,0]
	v_mfma_scale_f32_16x16x128_f8f6f4 v[122:125], v[10:17], v[182:189], 0, v171, v171 op_sel_hi:[0,0,0]
	v_mfma_scale_f32_16x16x128_f8f6f4 v[110:113], v[2:9], v[190:197], 0, v171, v171 op_sel_hi:[0,0,0]
	v_mfma_scale_f32_16x16x128_f8f6f4 v[106:109], v[10:17], v[190:197], 0, v171, v171 op_sel_hi:[0,0,0]
	v_mfma_scale_f32_16x16x128_f8f6f4 v[94:97], v[2:9], v[198:205], 0, v171, v171 op_sel_hi:[0,0,0]
	v_mfma_scale_f32_16x16x128_f8f6f4 v[90:93], v[10:17], v[198:205], 0, v171, v171 op_sel_hi:[0,0,0]
	s_barrier
	s_add_i32 s0, s45, s11
	v_lshl_add_u64 v[162:163], s[30:31], 0, v[150:151]
	s_mov_b32 m0, s0
	ds_read_b128 v[206:209], v172
	ds_read_b128 v[210:213], v172 offset:1024
	ds_read_b128 v[214:217], v172 offset:2048
	ds_read_b128 v[218:221], v172 offset:3072
	global_load_lds_dwordx4 v[162:163], off
	v_lshl_add_u64 v[164:165], s[30:31], 0, v[146:147]
	s_add_i32 m0, s0, 0x2000
	s_nop 0
	global_load_lds_dwordx4 v[164:165], off
	s_waitcnt vmcnt(10)
	s_barrier
	s_waitcnt lgkmcnt(0)
	s_waitcnt lgkmcnt(0)
	v_mfma_scale_f32_16x16x128_f8f6f4 v[134:137], v[206:213], v[174:181], 0, v171, v171 op_sel_hi:[0,0,0]
	v_mfma_scale_f32_16x16x128_f8f6f4 v[130:133], v[214:221], v[174:181], 0, v171, v171 op_sel_hi:[0,0,0]
	v_mfma_scale_f32_16x16x128_f8f6f4 v[118:121], v[206:213], v[182:189], 0, v171, v171 op_sel_hi:[0,0,0]
	v_mfma_scale_f32_16x16x128_f8f6f4 v[114:117], v[214:221], v[182:189], 0, v171, v171 op_sel_hi:[0,0,0]
	v_mfma_scale_f32_16x16x128_f8f6f4 v[102:105], v[206:213], v[190:197], 0, v171, v171 op_sel_hi:[0,0,0]
	v_mfma_scale_f32_16x16x128_f8f6f4 v[98:101], v[214:221], v[190:197], 0, v171, v171 op_sel_hi:[0,0,0]
	v_mfma_scale_f32_16x16x128_f8f6f4 v[86:89], v[206:213], v[198:205], 0, v171, v171 op_sel_hi:[0,0,0]
	v_mfma_scale_f32_16x16x128_f8f6f4 v[82:85], v[214:221], v[198:205], 0, v171, v171 op_sel_hi:[0,0,0]
	s_mov_b32 m0, s17
	s_barrier
	ds_read_b128 v[174:177], v170 offset:16384
	ds_read_b128 v[178:181], v170 offset:17408
	ds_read_b128 v[182:185], v170 offset:18432
	ds_read_b128 v[186:189], v170 offset:19456
	ds_read_b128 v[190:193], v170 offset:20480
	ds_read_b128 v[194:197], v170 offset:21504
	ds_read_b128 v[198:201], v170 offset:22528
	ds_read_b128 v[202:205], v170 offset:23552
	global_load_lds_dwordx4 v152, s[36:37]
	v_lshl_add_u64 v[222:223], s[36:37], 0, v[148:149]
	s_mov_b32 m0, s27
	s_nop 0
	global_load_lds_dwordx4 v[222:223], off
	s_waitcnt vmcnt(10)
	s_barrier
	s_waitcnt lgkmcnt(0)
	s_waitcnt lgkmcnt(0)
	v_mfma_scale_f32_16x16x128_f8f6f4 v[78:81], v[2:9], v[174:181], 0, v171, v171 op_sel_hi:[0,0,0]
	v_mfma_scale_f32_16x16x128_f8f6f4 v[74:77], v[10:17], v[174:181], 0, v171, v171 op_sel_hi:[0,0,0]
	v_mfma_scale_f32_16x16x128_f8f6f4 v[62:65], v[2:9], v[182:189], 0, v171, v171 op_sel_hi:[0,0,0]
	v_mfma_scale_f32_16x16x128_f8f6f4 v[58:61], v[10:17], v[182:189], 0, v171, v171 op_sel_hi:[0,0,0]
	v_mfma_scale_f32_16x16x128_f8f6f4 v[46:49], v[2:9], v[190:197], 0, v171, v171 op_sel_hi:[0,0,0]
	v_mfma_scale_f32_16x16x128_f8f6f4 v[42:45], v[10:17], v[190:197], 0, v171, v171 op_sel_hi:[0,0,0]
	v_mfma_scale_f32_16x16x128_f8f6f4 v[30:33], v[2:9], v[198:205], 0, v171, v171 op_sel_hi:[0,0,0]
	v_mfma_scale_f32_16x16x128_f8f6f4 v[26:29], v[10:17], v[198:205], 0, v171, v171 op_sel_hi:[0,0,0]
	s_barrier
	s_add_u32 s0, s30, 0x20000
	s_addc_u32 s1, s31, 0
	s_add_i32 s54, s46, s11
	s_mov_b32 m0, s54
	s_nop 0
	global_load_lds_dwordx4 v150, s[0:1]
	s_add_i32 m0, s54, 0x2000
	s_nop 0
	global_load_lds_dwordx4 v146, s[0:1]
	s_waitcnt vmcnt(10)
	s_barrier
	v_mfma_scale_f32_16x16x128_f8f6f4 v[70:73], v[206:213], v[174:181], 0, v171, v171 op_sel_hi:[0,0,0]
	v_mfma_scale_f32_16x16x128_f8f6f4 v[66:69], v[214:221], v[174:181], 0, v171, v171 op_sel_hi:[0,0,0]
	v_mfma_scale_f32_16x16x128_f8f6f4 v[54:57], v[206:213], v[182:189], 0, v171, v171 op_sel_hi:[0,0,0]
	v_mfma_scale_f32_16x16x128_f8f6f4 v[50:53], v[214:221], v[182:189], 0, v171, v171 op_sel_hi:[0,0,0]
	v_mfma_scale_f32_16x16x128_f8f6f4 v[38:41], v[206:213], v[190:197], 0, v171, v171 op_sel_hi:[0,0,0]
	v_mfma_scale_f32_16x16x128_f8f6f4 v[34:37], v[214:221], v[190:197], 0, v171, v171 op_sel_hi:[0,0,0]
	v_mfma_scale_f32_16x16x128_f8f6f4 v[22:25], v[206:213], v[198:205], 0, v171, v171 op_sel_hi:[0,0,0]
	v_mfma_scale_f32_16x16x128_f8f6f4 v[18:21], v[214:221], v[198:205], 0, v171, v171 op_sel_hi:[0,0,0]
	s_add_i32 s54, 0, 0x18000
	v_add_u32_e32 v14, s54, v168
	s_barrier
	ds_read_b128 v[2:5], v14
	ds_read_b128 v[6:9], v14 offset:1024
	ds_read_b128 v[10:13], v14 offset:2048
	ds_read_b128 v[14:17], v14 offset:3072
	s_add_u32 s0, s36, 0x4000
	s_addc_u32 s1, s37, 0
	s_mov_b32 m0, s38
	ds_read_b128 v[174:177], v170 offset:32768
	ds_read_b128 v[178:181], v170 offset:33792
	ds_read_b128 v[182:185], v170 offset:34816
	ds_read_b128 v[186:189], v170 offset:35840
	ds_read_b128 v[190:193], v170 offset:36864
	ds_read_b128 v[194:197], v170 offset:37888
	ds_read_b128 v[198:201], v170 offset:38912
	ds_read_b128 v[202:205], v170 offset:39936
	global_load_lds_dwordx4 v152, s[0:1]
	s_mov_b32 m0, s39
	s_nop 0
	global_load_lds_dwordx4 v148, s[0:1]
	s_waitcnt lgkmcnt(8)
	s_waitcnt vmcnt(10)
	s_barrier
	s_waitcnt lgkmcnt(0)
	s_waitcnt lgkmcnt(0)
	v_mfma_scale_f32_16x16x128_f8f6f4 v[142:145], v[2:9], v[174:181], v[142:145], v171, v171 op_sel_hi:[0,0,0]
	v_mfma_scale_f32_16x16x128_f8f6f4 v[138:141], v[10:17], v[174:181], v[138:141], v171, v171 op_sel_hi:[0,0,0]
	v_mfma_scale_f32_16x16x128_f8f6f4 v[126:129], v[2:9], v[182:189], v[126:129], v171, v171 op_sel_hi:[0,0,0]
	v_mfma_scale_f32_16x16x128_f8f6f4 v[122:125], v[10:17], v[182:189], v[122:125], v171, v171 op_sel_hi:[0,0,0]
	v_mfma_scale_f32_16x16x128_f8f6f4 v[110:113], v[2:9], v[190:197], v[110:113], v171, v171 op_sel_hi:[0,0,0]
	v_mfma_scale_f32_16x16x128_f8f6f4 v[106:109], v[10:17], v[190:197], v[106:109], v171, v171 op_sel_hi:[0,0,0]
	v_mfma_scale_f32_16x16x128_f8f6f4 v[94:97], v[2:9], v[198:205], v[94:97], v171, v171 op_sel_hi:[0,0,0]
	v_mfma_scale_f32_16x16x128_f8f6f4 v[90:93], v[10:17], v[198:205], v[90:93], v171, v171 op_sel_hi:[0,0,0]
	s_barrier
	s_add_i32 s36, 0, 0x1c000
	s_add_i32 s0, s54, s11
	v_add_u32_e32 v218, s36, v168
	v_lshl_add_u64 v[162:163], v[162:163], 0, s[14:15]
	s_mov_b32 m0, s0
	ds_read_b128 v[206:209], v218
	ds_read_b128 v[210:213], v218 offset:1024
	ds_read_b128 v[214:217], v218 offset:2048
	ds_read_b128 v[218:221], v218 offset:3072
	global_load_lds_dwordx4 v[162:163], off
	v_lshl_add_u64 v[162:163], v[164:165], 0, s[14:15]
	s_add_i32 m0, s0, 0x2000
	s_nop 0
	global_load_lds_dwordx4 v[162:163], off
	s_waitcnt vmcnt(10)
	s_barrier
	s_waitcnt lgkmcnt(0)
	s_waitcnt lgkmcnt(0)
	v_mfma_scale_f32_16x16x128_f8f6f4 v[134:137], v[206:213], v[174:181], v[134:137], v171, v171 op_sel_hi:[0,0,0]
	v_mfma_scale_f32_16x16x128_f8f6f4 v[130:133], v[214:221], v[174:181], v[130:133], v171, v171 op_sel_hi:[0,0,0]
	v_mfma_scale_f32_16x16x128_f8f6f4 v[118:121], v[206:213], v[182:189], v[118:121], v171, v171 op_sel_hi:[0,0,0]
	v_mfma_scale_f32_16x16x128_f8f6f4 v[114:117], v[214:221], v[182:189], v[114:117], v171, v171 op_sel_hi:[0,0,0]
	v_mfma_scale_f32_16x16x128_f8f6f4 v[102:105], v[206:213], v[190:197], v[102:105], v171, v171 op_sel_hi:[0,0,0]
	v_mfma_scale_f32_16x16x128_f8f6f4 v[98:101], v[214:221], v[190:197], v[98:101], v171, v171 op_sel_hi:[0,0,0]
	v_mfma_scale_f32_16x16x128_f8f6f4 v[86:89], v[206:213], v[198:205], v[86:89], v171, v171 op_sel_hi:[0,0,0]
	v_mfma_scale_f32_16x16x128_f8f6f4 v[82:85], v[214:221], v[198:205], v[82:85], v171, v171 op_sel_hi:[0,0,0]
	s_mov_b32 m0, s43
	s_barrier
	ds_read_b128 v[174:177], v170 offset:49152
	ds_read_b128 v[178:181], v170 offset:50176
	ds_read_b128 v[182:185], v170 offset:51200
	ds_read_b128 v[186:189], v170 offset:52224
	ds_read_b128 v[190:193], v170 offset:53248
	ds_read_b128 v[194:197], v170 offset:54272
	ds_read_b128 v[198:201], v170 offset:55296
	ds_read_b128 v[202:205], v170 offset:56320
	global_load_lds_dwordx4 v152, s[34:35]
	v_lshl_add_u64 v[162:163], s[34:35], 0, v[148:149]
	s_mov_b32 m0, s44
	s_nop 0
	global_load_lds_dwordx4 v[162:163], off
	s_waitcnt vmcnt(10)
	s_barrier
	s_waitcnt lgkmcnt(0)
	s_waitcnt lgkmcnt(0)
	v_mfma_scale_f32_16x16x128_f8f6f4 v[78:81], v[2:9], v[174:181], v[78:81], v171, v171 op_sel_hi:[0,0,0]
	v_mfma_scale_f32_16x16x128_f8f6f4 v[74:77], v[10:17], v[174:181], v[74:77], v171, v171 op_sel_hi:[0,0,0]
	v_mfma_scale_f32_16x16x128_f8f6f4 v[62:65], v[2:9], v[182:189], v[62:65], v171, v171 op_sel_hi:[0,0,0]
	v_mfma_scale_f32_16x16x128_f8f6f4 v[58:61], v[10:17], v[182:189], v[58:61], v171, v171 op_sel_hi:[0,0,0]
	v_mfma_scale_f32_16x16x128_f8f6f4 v[46:49], v[2:9], v[190:197], v[46:49], v171, v171 op_sel_hi:[0,0,0]
	v_mfma_scale_f32_16x16x128_f8f6f4 v[42:45], v[10:17], v[190:197], v[42:45], v171, v171 op_sel_hi:[0,0,0]
	v_mfma_scale_f32_16x16x128_f8f6f4 v[30:33], v[2:9], v[198:205], v[30:33], v171, v171 op_sel_hi:[0,0,0]
	v_mfma_scale_f32_16x16x128_f8f6f4 v[26:29], v[10:17], v[198:205], v[26:29], v171, v171 op_sel_hi:[0,0,0]
	s_barrier
	s_add_u32 s0, s30, 0x20080
	s_addc_u32 s1, s31, 0
	s_add_i32 s30, s36, s11
	s_mov_b32 m0, s30
	s_nop 0
	global_load_lds_dwordx4 v150, s[0:1]
	s_add_i32 m0, s30, 0x2000
	s_nop 0
	global_load_lds_dwordx4 v146, s[0:1]
	s_waitcnt vmcnt(10)
	s_barrier
	v_mfma_scale_f32_16x16x128_f8f6f4 v[70:73], v[206:213], v[174:181], v[70:73], v171, v171 op_sel_hi:[0,0,0]
	v_mfma_scale_f32_16x16x128_f8f6f4 v[66:69], v[214:221], v[174:181], v[66:69], v171, v171 op_sel_hi:[0,0,0]
	v_mfma_scale_f32_16x16x128_f8f6f4 v[54:57], v[206:213], v[182:189], v[54:57], v171, v171 op_sel_hi:[0,0,0]
	v_mfma_scale_f32_16x16x128_f8f6f4 v[50:53], v[214:221], v[182:189], v[50:53], v171, v171 op_sel_hi:[0,0,0]
	v_mfma_scale_f32_16x16x128_f8f6f4 v[38:41], v[206:213], v[190:197], v[38:41], v171, v171 op_sel_hi:[0,0,0]
	v_mfma_scale_f32_16x16x128_f8f6f4 v[34:37], v[214:221], v[190:197], v[34:37], v171, v171 op_sel_hi:[0,0,0]
	v_mfma_scale_f32_16x16x128_f8f6f4 v[22:25], v[206:213], v[198:205], v[22:25], v171, v171 op_sel_hi:[0,0,0]
	v_mfma_scale_f32_16x16x128_f8f6f4 v[18:21], v[214:221], v[198:205], v[18:21], v171, v171 op_sel_hi:[0,0,0]
	s_add_i32 s53, s53, 2
	s_add_u32 s51, s51, 0x100
	s_addc_u32 s52, s52, 0
	s_add_u32 s28, s28, 0x10000
	s_addc_u32 s29, s29, 0
	s_cmp_gt_u32 s53, 5
	s_barrier
	s_cbranch_scc1 .Lpeel_exit_7
.LBB0_1369:
	ds_read_b128 v[2:5], v169
	ds_read_b128 v[6:9], v169 offset:1024
	ds_read_b128 v[10:13], v169 offset:2048
	ds_read_b128 v[14:17], v169 offset:3072
	s_add_u32 s0, s28, 0x4000
	s_addc_u32 s1, s29, 0
	s_cmp_eq_u32 s53, 4
	s_cselect_b32 s36, s49, s0
	s_cselect_b32 s37, s21, s1
	s_cselect_b32 s30, s50, s51
	s_cselect_b32 s31, s19, s52
	s_add_u32 s34, s36, 0x8000
	s_addc_u32 s35, s37, 0
	s_add_i32 m0, s17, 0xc000
	ds_read_b128 v[174:177], v170
	ds_read_b128 v[178:181], v170 offset:1024
	ds_read_b128 v[182:185], v170 offset:2048
	ds_read_b128 v[186:189], v170 offset:3072
	ds_read_b128 v[190:193], v170 offset:4096
	ds_read_b128 v[194:197], v170 offset:5120
	ds_read_b128 v[198:201], v170 offset:6144
	ds_read_b128 v[202:205], v170 offset:7168
	global_load_lds_dwordx4 v156, s[28:29]
	s_add_i32 m0, s17, 0xe000
	s_nop 0
	global_load_lds_dwordx4 v154, s[28:29]
	s_waitcnt lgkmcnt(8)
	s_waitcnt vmcnt(10)
	s_barrier
	s_waitcnt lgkmcnt(0)
	s_waitcnt lgkmcnt(0)
	v_mfma_scale_f32_16x16x128_f8f6f4 v[142:145], v[2:9], v[174:181], v[142:145], v171, v171 op_sel_hi:[0,0,0]
	v_mfma_scale_f32_16x16x128_f8f6f4 v[138:141], v[10:17], v[174:181], v[138:141], v171, v171 op_sel_hi:[0,0,0]
	v_mfma_scale_f32_16x16x128_f8f6f4 v[126:129], v[2:9], v[182:189], v[126:129], v171, v171 op_sel_hi:[0,0,0]
	v_mfma_scale_f32_16x16x128_f8f6f4 v[122:125], v[10:17], v[182:189], v[122:125], v171, v171 op_sel_hi:[0,0,0]
	v_mfma_scale_f32_16x16x128_f8f6f4 v[110:113], v[2:9], v[190:197], v[110:113], v171, v171 op_sel_hi:[0,0,0]
	v_mfma_scale_f32_16x16x128_f8f6f4 v[106:109], v[10:17], v[190:197], v[106:109], v171, v171 op_sel_hi:[0,0,0]
	v_mfma_scale_f32_16x16x128_f8f6f4 v[94:97], v[2:9], v[198:205], v[94:97], v171, v171 op_sel_hi:[0,0,0]
	v_mfma_scale_f32_16x16x128_f8f6f4 v[90:93], v[10:17], v[198:205], v[90:93], v171, v171 op_sel_hi:[0,0,0]
	s_barrier
	s_add_i32 s0, s45, s11
	v_lshl_add_u64 v[162:163], s[30:31], 0, v[150:151]
	s_mov_b32 m0, s0
	ds_read_b128 v[206:209], v172
	ds_read_b128 v[210:213], v172 offset:1024
	ds_read_b128 v[214:217], v172 offset:2048
	ds_read_b128 v[218:221], v172 offset:3072
	global_load_lds_dwordx4 v[162:163], off
	v_lshl_add_u64 v[164:165], s[30:31], 0, v[146:147]
	s_add_i32 m0, s0, 0x2000
	s_nop 0
	global_load_lds_dwordx4 v[164:165], off
	s_waitcnt vmcnt(10)
	s_barrier
	s_waitcnt lgkmcnt(0)
	s_waitcnt lgkmcnt(0)
	v_mfma_scale_f32_16x16x128_f8f6f4 v[134:137], v[206:213], v[174:181], v[134:137], v171, v171 op_sel_hi:[0,0,0]
	v_mfma_scale_f32_16x16x128_f8f6f4 v[130:133], v[214:221], v[174:181], v[130:133], v171, v171 op_sel_hi:[0,0,0]
	v_mfma_scale_f32_16x16x128_f8f6f4 v[118:121], v[206:213], v[182:189], v[118:121], v171, v171 op_sel_hi:[0,0,0]
	v_mfma_scale_f32_16x16x128_f8f6f4 v[114:117], v[214:221], v[182:189], v[114:117], v171, v171 op_sel_hi:[0,0,0]
	v_mfma_scale_f32_16x16x128_f8f6f4 v[102:105], v[206:213], v[190:197], v[102:105], v171, v171 op_sel_hi:[0,0,0]
	v_mfma_scale_f32_16x16x128_f8f6f4 v[98:101], v[214:221], v[190:197], v[98:101], v171, v171 op_sel_hi:[0,0,0]
	v_mfma_scale_f32_16x16x128_f8f6f4 v[86:89], v[206:213], v[198:205], v[86:89], v171, v171 op_sel_hi:[0,0,0]
	v_mfma_scale_f32_16x16x128_f8f6f4 v[82:85], v[214:221], v[198:205], v[82:85], v171, v171 op_sel_hi:[0,0,0]
	s_mov_b32 m0, s17
	s_barrier
	ds_read_b128 v[174:177], v170 offset:16384
	ds_read_b128 v[178:181], v170 offset:17408
	ds_read_b128 v[182:185], v170 offset:18432
	ds_read_b128 v[186:189], v170 offset:19456
	ds_read_b128 v[190:193], v170 offset:20480
	ds_read_b128 v[194:197], v170 offset:21504
	ds_read_b128 v[198:201], v170 offset:22528
	ds_read_b128 v[202:205], v170 offset:23552
	global_load_lds_dwordx4 v152, s[36:37]
	v_lshl_add_u64 v[222:223], s[36:37], 0, v[148:149]
	s_mov_b32 m0, s27
	s_nop 0
	global_load_lds_dwordx4 v[222:223], off
	s_waitcnt vmcnt(10)
	s_barrier
	s_waitcnt lgkmcnt(0)
	s_waitcnt lgkmcnt(0)
	v_mfma_scale_f32_16x16x128_f8f6f4 v[78:81], v[2:9], v[174:181], v[78:81], v171, v171 op_sel_hi:[0,0,0]
	v_mfma_scale_f32_16x16x128_f8f6f4 v[74:77], v[10:17], v[174:181], v[74:77], v171, v171 op_sel_hi:[0,0,0]
	v_mfma_scale_f32_16x16x128_f8f6f4 v[62:65], v[2:9], v[182:189], v[62:65], v171, v171 op_sel_hi:[0,0,0]
	v_mfma_scale_f32_16x16x128_f8f6f4 v[58:61], v[10:17], v[182:189], v[58:61], v171, v171 op_sel_hi:[0,0,0]
	v_mfma_scale_f32_16x16x128_f8f6f4 v[46:49], v[2:9], v[190:197], v[46:49], v171, v171 op_sel_hi:[0,0,0]
	v_mfma_scale_f32_16x16x128_f8f6f4 v[42:45], v[10:17], v[190:197], v[42:45], v171, v171 op_sel_hi:[0,0,0]
	v_mfma_scale_f32_16x16x128_f8f6f4 v[30:33], v[2:9], v[198:205], v[30:33], v171, v171 op_sel_hi:[0,0,0]
	v_mfma_scale_f32_16x16x128_f8f6f4 v[26:29], v[10:17], v[198:205], v[26:29], v171, v171 op_sel_hi:[0,0,0]
	s_barrier
	s_add_u32 s0, s30, 0x20000
	s_addc_u32 s1, s31, 0
	s_add_i32 s54, s46, s11
	s_mov_b32 m0, s54
	s_nop 0
	global_load_lds_dwordx4 v150, s[0:1]
	s_add_i32 m0, s54, 0x2000
	s_nop 0
	global_load_lds_dwordx4 v146, s[0:1]
	s_waitcnt vmcnt(10)
	s_barrier
	v_mfma_scale_f32_16x16x128_f8f6f4 v[70:73], v[206:213], v[174:181], v[70:73], v171, v171 op_sel_hi:[0,0,0]
	v_mfma_scale_f32_16x16x128_f8f6f4 v[66:69], v[214:221], v[174:181], v[66:69], v171, v171 op_sel_hi:[0,0,0]
	v_mfma_scale_f32_16x16x128_f8f6f4 v[54:57], v[206:213], v[182:189], v[54:57], v171, v171 op_sel_hi:[0,0,0]
	v_mfma_scale_f32_16x16x128_f8f6f4 v[50:53], v[214:221], v[182:189], v[50:53], v171, v171 op_sel_hi:[0,0,0]
	v_mfma_scale_f32_16x16x128_f8f6f4 v[38:41], v[206:213], v[190:197], v[38:41], v171, v171 op_sel_hi:[0,0,0]
	v_mfma_scale_f32_16x16x128_f8f6f4 v[34:37], v[214:221], v[190:197], v[34:37], v171, v171 op_sel_hi:[0,0,0]
	v_mfma_scale_f32_16x16x128_f8f6f4 v[22:25], v[206:213], v[198:205], v[22:25], v171, v171 op_sel_hi:[0,0,0]
	v_mfma_scale_f32_16x16x128_f8f6f4 v[18:21], v[214:221], v[198:205], v[18:21], v171, v171 op_sel_hi:[0,0,0]
	s_add_i32 s54, 0, 0x18000
	v_add_u32_e32 v14, s54, v168
	s_barrier
	ds_read_b128 v[2:5], v14
	ds_read_b128 v[6:9], v14 offset:1024
	ds_read_b128 v[10:13], v14 offset:2048
	ds_read_b128 v[14:17], v14 offset:3072
	s_add_u32 s0, s36, 0x4000
	s_addc_u32 s1, s37, 0
	s_mov_b32 m0, s38
	ds_read_b128 v[174:177], v170 offset:32768
	ds_read_b128 v[178:181], v170 offset:33792
	ds_read_b128 v[182:185], v170 offset:34816
	ds_read_b128 v[186:189], v170 offset:35840
	ds_read_b128 v[190:193], v170 offset:36864
	ds_read_b128 v[194:197], v170 offset:37888
	ds_read_b128 v[198:201], v170 offset:38912
	ds_read_b128 v[202:205], v170 offset:39936
	global_load_lds_dwordx4 v152, s[0:1]
	s_mov_b32 m0, s39
	s_nop 0
	global_load_lds_dwordx4 v148, s[0:1]
	s_waitcnt lgkmcnt(8)
	s_waitcnt vmcnt(10)
	s_barrier
	s_waitcnt lgkmcnt(0)
	s_waitcnt lgkmcnt(0)
	v_mfma_scale_f32_16x16x128_f8f6f4 v[142:145], v[2:9], v[174:181], v[142:145], v171, v171 op_sel_hi:[0,0,0]
	v_mfma_scale_f32_16x16x128_f8f6f4 v[138:141], v[10:17], v[174:181], v[138:141], v171, v171 op_sel_hi:[0,0,0]
	v_mfma_scale_f32_16x16x128_f8f6f4 v[126:129], v[2:9], v[182:189], v[126:129], v171, v171 op_sel_hi:[0,0,0]
	v_mfma_scale_f32_16x16x128_f8f6f4 v[122:125], v[10:17], v[182:189], v[122:125], v171, v171 op_sel_hi:[0,0,0]
	v_mfma_scale_f32_16x16x128_f8f6f4 v[110:113], v[2:9], v[190:197], v[110:113], v171, v171 op_sel_hi:[0,0,0]
	v_mfma_scale_f32_16x16x128_f8f6f4 v[106:109], v[10:17], v[190:197], v[106:109], v171, v171 op_sel_hi:[0,0,0]
	v_mfma_scale_f32_16x16x128_f8f6f4 v[94:97], v[2:9], v[198:205], v[94:97], v171, v171 op_sel_hi:[0,0,0]
	v_mfma_scale_f32_16x16x128_f8f6f4 v[90:93], v[10:17], v[198:205], v[90:93], v171, v171 op_sel_hi:[0,0,0]
	s_barrier
	s_add_i32 s36, 0, 0x1c000
	s_add_i32 s0, s54, s11
	v_add_u32_e32 v218, s36, v168
	v_lshl_add_u64 v[162:163], v[162:163], 0, s[14:15]
	s_mov_b32 m0, s0
	ds_read_b128 v[206:209], v218
	ds_read_b128 v[210:213], v218 offset:1024
	ds_read_b128 v[214:217], v218 offset:2048
	ds_read_b128 v[218:221], v218 offset:3072
	global_load_lds_dwordx4 v[162:163], off
	v_lshl_add_u64 v[162:163], v[164:165], 0, s[14:15]
	s_add_i32 m0, s0, 0x2000
	s_nop 0
	global_load_lds_dwordx4 v[162:163], off
	s_waitcnt vmcnt(10)
	s_barrier
	s_waitcnt lgkmcnt(0)
	s_waitcnt lgkmcnt(0)
	v_mfma_scale_f32_16x16x128_f8f6f4 v[134:137], v[206:213], v[174:181], v[134:137], v171, v171 op_sel_hi:[0,0,0]
	v_mfma_scale_f32_16x16x128_f8f6f4 v[130:133], v[214:221], v[174:181], v[130:133], v171, v171 op_sel_hi:[0,0,0]
	v_mfma_scale_f32_16x16x128_f8f6f4 v[118:121], v[206:213], v[182:189], v[118:121], v171, v171 op_sel_hi:[0,0,0]
	v_mfma_scale_f32_16x16x128_f8f6f4 v[114:117], v[214:221], v[182:189], v[114:117], v171, v171 op_sel_hi:[0,0,0]
	v_mfma_scale_f32_16x16x128_f8f6f4 v[102:105], v[206:213], v[190:197], v[102:105], v171, v171 op_sel_hi:[0,0,0]
	v_mfma_scale_f32_16x16x128_f8f6f4 v[98:101], v[214:221], v[190:197], v[98:101], v171, v171 op_sel_hi:[0,0,0]
	v_mfma_scale_f32_16x16x128_f8f6f4 v[86:89], v[206:213], v[198:205], v[86:89], v171, v171 op_sel_hi:[0,0,0]
	v_mfma_scale_f32_16x16x128_f8f6f4 v[82:85], v[214:221], v[198:205], v[82:85], v171, v171 op_sel_hi:[0,0,0]
	s_mov_b32 m0, s43
	s_barrier
	ds_read_b128 v[174:177], v170 offset:49152
	ds_read_b128 v[178:181], v170 offset:50176
	ds_read_b128 v[182:185], v170 offset:51200
	ds_read_b128 v[186:189], v170 offset:52224
	ds_read_b128 v[190:193], v170 offset:53248
	ds_read_b128 v[194:197], v170 offset:54272
	ds_read_b128 v[198:201], v170 offset:55296
	ds_read_b128 v[202:205], v170 offset:56320
	global_load_lds_dwordx4 v152, s[34:35]
	v_lshl_add_u64 v[162:163], s[34:35], 0, v[148:149]
	s_mov_b32 m0, s44
	s_nop 0
	global_load_lds_dwordx4 v[162:163], off
	s_waitcnt vmcnt(10)
	s_barrier
	s_waitcnt lgkmcnt(0)
	s_waitcnt lgkmcnt(0)
	v_mfma_scale_f32_16x16x128_f8f6f4 v[78:81], v[2:9], v[174:181], v[78:81], v171, v171 op_sel_hi:[0,0,0]
	v_mfma_scale_f32_16x16x128_f8f6f4 v[74:77], v[10:17], v[174:181], v[74:77], v171, v171 op_sel_hi:[0,0,0]
	v_mfma_scale_f32_16x16x128_f8f6f4 v[62:65], v[2:9], v[182:189], v[62:65], v171, v171 op_sel_hi:[0,0,0]
	v_mfma_scale_f32_16x16x128_f8f6f4 v[58:61], v[10:17], v[182:189], v[58:61], v171, v171 op_sel_hi:[0,0,0]
	v_mfma_scale_f32_16x16x128_f8f6f4 v[46:49], v[2:9], v[190:197], v[46:49], v171, v171 op_sel_hi:[0,0,0]
	v_mfma_scale_f32_16x16x128_f8f6f4 v[42:45], v[10:17], v[190:197], v[42:45], v171, v171 op_sel_hi:[0,0,0]
	v_mfma_scale_f32_16x16x128_f8f6f4 v[30:33], v[2:9], v[198:205], v[30:33], v171, v171 op_sel_hi:[0,0,0]
	v_mfma_scale_f32_16x16x128_f8f6f4 v[26:29], v[10:17], v[198:205], v[26:29], v171, v171 op_sel_hi:[0,0,0]
	s_barrier
	s_add_u32 s0, s30, 0x20080
	s_addc_u32 s1, s31, 0
	s_add_i32 s30, s36, s11
	s_mov_b32 m0, s30
	s_nop 0
	global_load_lds_dwordx4 v150, s[0:1]
	s_add_i32 m0, s30, 0x2000
	s_nop 0
	global_load_lds_dwordx4 v146, s[0:1]
	s_waitcnt vmcnt(10)
	s_barrier
	v_mfma_scale_f32_16x16x128_f8f6f4 v[70:73], v[206:213], v[174:181], v[70:73], v171, v171 op_sel_hi:[0,0,0]
	v_mfma_scale_f32_16x16x128_f8f6f4 v[66:69], v[214:221], v[174:181], v[66:69], v171, v171 op_sel_hi:[0,0,0]
	v_mfma_scale_f32_16x16x128_f8f6f4 v[54:57], v[206:213], v[182:189], v[54:57], v171, v171 op_sel_hi:[0,0,0]
	v_mfma_scale_f32_16x16x128_f8f6f4 v[50:53], v[214:221], v[182:189], v[50:53], v171, v171 op_sel_hi:[0,0,0]
	v_mfma_scale_f32_16x16x128_f8f6f4 v[38:41], v[206:213], v[190:197], v[38:41], v171, v171 op_sel_hi:[0,0,0]
	v_mfma_scale_f32_16x16x128_f8f6f4 v[34:37], v[214:221], v[190:197], v[34:37], v171, v171 op_sel_hi:[0,0,0]
	v_mfma_scale_f32_16x16x128_f8f6f4 v[22:25], v[206:213], v[198:205], v[22:25], v171, v171 op_sel_hi:[0,0,0]
	v_mfma_scale_f32_16x16x128_f8f6f4 v[18:21], v[214:221], v[198:205], v[18:21], v171, v171 op_sel_hi:[0,0,0]
	s_add_i32 s53, s53, 2
	s_add_u32 s51, s51, 0x100
	s_addc_u32 s52, s52, 0
	s_add_u32 s28, s28, 0x10000
	s_addc_u32 s29, s29, 0
	s_cmp_gt_u32 s53, 5
	s_barrier
	s_cbranch_scc0 .LBB0_1369

.LBB0_1504:
	s_add_u32 s36, s14, 0x12100000
	v_bfe_u32 v147, v16, 4, 2
	s_addc_u32 s37, s15, 0
	v_and_b32_e32 v146, 15, v16
	v_lshlrev_b32_e32 v17, 4, v147
	v_lshlrev_b32_e32 v16, 2, v16
	s_mov_b64 s[14:15], 0x80
	s_and_b32 s1, s1, 3
	s_lshl_b32 s38, s0, 6
	v_lshl_or_b32 v17, v146, 6, v17
	s_lshl_b32 s0, s0, 13
	v_and_b32_e32 v16, 32, v16
	s_add_i32 m0, s10, 0x18000
	v_lshl_add_u64 v[8:9], v[8:9], 0, s[14:15]
	v_bitop3_b32 v18, v17, s0, v16 bitop3:0xde
	s_lshl_b32 s39, s1, 5
	s_lshl_b32 s0, s1, 12
	s_waitcnt vmcnt(4)
	s_barrier
	global_load_lds_dwordx4 v[8:9], off
	v_lshl_add_u64 v[6:7], v[6:7], 0, s[14:15]
	s_add_i32 m0, s10, 0x1a000
	s_add_i32 s40, s10, 0x8000
	s_add_i32 s41, s10, 0xa000
	v_bitop3_b32 v148, v17, s0, v16 bitop3:0xde
	global_load_lds_dwordx4 v[6:7], off
	v_lshl_add_u64 v[4:5], v[4:5], 0, s[14:15]
	s_mov_b32 m0, s40
	s_add_u32 s0, s26, 0x40080
	global_load_lds_dwordx4 v[4:5], off
	v_lshl_add_u64 v[2:3], v[2:3], 0, s[14:15]
	s_mov_b32 m0, s41
	s_addc_u32 s1, s27, 0
	global_load_lds_dwordx4 v[2:3], off
	s_add_i32 m0, s10, 0x1c000
	s_nop 0
	global_load_lds_dwordx4 v134, s[0:1]
	s_add_i32 m0, s10, 0x1e000
	s_add_i32 s42, 0, 0x10000
	global_load_lds_dwordx4 v130, s[0:1]
	v_lshlrev_b32_e32 v2, 14, v10
	v_and_b32_e32 v2, 0xffff8000, v2
	v_lshl_add_u32 v2, v11, 11, v2
	v_and_b32_e32 v3, 1, v10
	v_lshl_or_b32 v2, v3, 6, v2
	v_lshl_add_u32 v138, v12, 1, v2
	v_lshlrev_b32_e32 v2, 14, v14
	v_and_b32_e32 v2, 0xffff8000, v2
	s_waitcnt vmcnt(6)
	v_lshl_add_u32 v2, v13, 11, v2
	v_and_b32_e32 v3, 1, v14
	v_lshl_or_b32 v2, v3, 6, v2
	s_add_i32 s43, 0, 0x14000
	s_sext_i32_i8 s44, s12
	v_mov_b32_e32 v139, v135
	v_lshl_add_u32 v140, v15, 1, v2
	v_mov_b32_e32 v141, v135
	v_mov_b64_e32 v[142:143], 0x800
	v_mov_b64_e32 v[144:145], 0x7ff
	v_add_u32_e32 v149, s42, v148
	v_add_u32_e32 v150, 0, v18
	v_add_u32_e32 v151, s43, v148
	s_barrier
	s_branch .LBB0_1506

.LBB0_1512:
	s_ashr_i32 s21, s20, 31
	s_lshl_b64 s[0:1], s[20:21], 19
	v_cmp_lt_i64_e32 vcc, s[22:23], v[142:143]
	s_add_u32 s22, s5, s0
	s_addc_u32 s23, s6, s1
	s_and_b64 s[0:1], vcc, exec
	s_cselect_b32 s21, s23, s29
	s_cselect_b32 s45, s22, s28
	s_ashr_i32 s19, s18, 31
	s_lshl_b64 s[0:1], s[18:19], 19
	s_add_u32 s24, s7, s0
	s_addc_u32 s25, s8, s1
	s_and_b64 s[0:1], vcc, exec
	s_cselect_b32 s19, s25, s27
	s_cselect_b32 s46, s24, s26
	s_add_u32 s47, s26, 0x100
	s_addc_u32 s48, s27, 0
	s_add_u32 s26, s28, 0x40080
	s_addc_u32 s27, s29, 0
	s_mov_b32 s49, -2
	ds_read_b128 v[152:155], v149
	ds_read_b128 v[156:159], v149 offset:1024
	ds_read_b128 v[160:163], v149 offset:2048
	ds_read_b128 v[164:167], v149 offset:3072
	s_add_u32 s0, s26, 0xfffc0080
	s_addc_u32 s1, s27, -1
	s_cmp_eq_u32 s49, 12
	s_cselect_b32 s31, s21, s1
	s_cselect_b32 s30, s45, s0
	s_cselect_b32 s29, s19, s48
	s_cselect_b32 s28, s46, s47
	s_add_i32 m0, s10, 0xc000
	ds_read_b128 v[168:171], v150
	ds_read_b128 v[172:175], v150 offset:1024
	ds_read_b128 v[176:179], v150 offset:2048
	ds_read_b128 v[180:183], v150 offset:3072
	ds_read_b128 v[184:187], v150 offset:4096
	ds_read_b128 v[188:191], v150 offset:5120
	ds_read_b128 v[192:195], v150 offset:6144
	ds_read_b128 v[196:199], v150 offset:7168
	global_load_lds_dwordx4 v140, s[26:27]
	s_add_i32 m0, s10, 0xe000
	s_nop 0
	global_load_lds_dwordx4 v138, s[26:27]
	s_waitcnt lgkmcnt(8)
	s_waitcnt vmcnt(10)
	s_barrier
	s_waitcnt lgkmcnt(0)
	s_waitcnt lgkmcnt(0)
	v_mfma_f32_16x16x32_bf16 v[126:129], v[152:155], v[168:171], 0
	v_mfma_f32_16x16x32_bf16 v[122:125], v[160:163], v[168:171], 0
	v_mfma_f32_16x16x32_bf16 v[118:121], v[152:155], v[176:179], 0
	v_mfma_f32_16x16x32_bf16 v[110:113], v[160:163], v[176:179], 0
	v_mfma_f32_16x16x32_bf16 v[102:105], v[152:155], v[184:187], 0
	v_mfma_f32_16x16x32_bf16 v[94:97], v[160:163], v[184:187], 0
	v_mfma_f32_16x16x32_bf16 v[86:89], v[152:155], v[192:195], 0
	v_mfma_f32_16x16x32_bf16 v[78:81], v[160:163], v[192:195], 0
	v_mfma_f32_16x16x32_bf16 v[126:129], v[156:159], v[172:175], v[126:129]
	v_mfma_f32_16x16x32_bf16 v[122:125], v[164:167], v[172:175], v[122:125]
	v_mfma_f32_16x16x32_bf16 v[118:121], v[156:159], v[180:183], v[118:121]
	v_mfma_f32_16x16x32_bf16 v[110:113], v[164:167], v[180:183], v[110:113]
	v_mfma_f32_16x16x32_bf16 v[102:105], v[156:159], v[188:191], v[102:105]
	v_mfma_f32_16x16x32_bf16 v[94:97], v[164:167], v[188:191], v[94:97]
	v_mfma_f32_16x16x32_bf16 v[86:89], v[156:159], v[196:199], v[86:89]
	v_mfma_f32_16x16x32_bf16 v[78:81], v[164:167], v[196:199], v[78:81]
	s_barrier
	s_add_i32 s0, s42, s9
	v_lshl_add_u64 v[216:217], s[28:29], 0, v[134:135]
	s_mov_b32 m0, s0
	ds_read_b128 v[200:203], v151
	ds_read_b128 v[204:207], v151 offset:1024
	ds_read_b128 v[208:211], v151 offset:2048
	ds_read_b128 v[212:215], v151 offset:3072
	global_load_lds_dwordx4 v[216:217], off
	v_lshl_add_u64 v[218:219], s[28:29], 0, v[130:131]
	s_add_i32 m0, s0, 0x2000
	s_nop 0
	global_load_lds_dwordx4 v[218:219], off
	s_waitcnt vmcnt(10)
	s_barrier
	s_waitcnt lgkmcnt(0)
	s_waitcnt lgkmcnt(0)
	v_mfma_f32_16x16x32_bf16 v[114:117], v[200:203], v[168:171], 0
	v_mfma_f32_16x16x32_bf16 v[106:109], v[208:211], v[168:171], 0
	v_mfma_f32_16x16x32_bf16 v[98:101], v[200:203], v[176:179], 0
	v_mfma_f32_16x16x32_bf16 v[90:93], v[208:211], v[176:179], 0
	v_mfma_f32_16x16x32_bf16 v[82:85], v[200:203], v[184:187], 0
	v_mfma_f32_16x16x32_bf16 v[74:77], v[208:211], v[184:187], 0
	v_mfma_f32_16x16x32_bf16 v[70:73], v[200:203], v[192:195], 0
	v_mfma_f32_16x16x32_bf16 v[66:69], v[208:211], v[192:195], 0
	v_mfma_f32_16x16x32_bf16 v[114:117], v[204:207], v[172:175], v[114:117]
	v_mfma_f32_16x16x32_bf16 v[106:109], v[212:215], v[172:175], v[106:109]
	v_mfma_f32_16x16x32_bf16 v[98:101], v[204:207], v[180:183], v[98:101]
	v_mfma_f32_16x16x32_bf16 v[90:93], v[212:215], v[180:183], v[90:93]
	v_mfma_f32_16x16x32_bf16 v[82:85], v[204:207], v[188:191], v[82:85]
	v_mfma_f32_16x16x32_bf16 v[74:77], v[212:215], v[188:191], v[74:77]
	v_mfma_f32_16x16x32_bf16 v[70:73], v[204:207], v[196:199], v[70:73]
	v_mfma_f32_16x16x32_bf16 v[66:69], v[212:215], v[196:199], v[66:69]
	s_mov_b32 m0, s10
	v_lshl_add_u64 v[220:221], s[30:31], 0, v[136:137]
	s_barrier
	ds_read_b128 v[168:171], v150 offset:16384
	ds_read_b128 v[172:175], v150 offset:17408
	ds_read_b128 v[176:179], v150 offset:18432
	ds_read_b128 v[180:183], v150 offset:19456
	ds_read_b128 v[184:187], v150 offset:20480
	ds_read_b128 v[188:191], v150 offset:21504
	ds_read_b128 v[192:195], v150 offset:22528
	ds_read_b128 v[196:199], v150 offset:23552
	global_load_lds_dwordx4 v[220:221], off
	v_lshl_add_u64 v[222:223], s[30:31], 0, v[132:133]
	s_mov_b32 m0, s11
	s_nop 0
	global_load_lds_dwordx4 v[222:223], off
	s_waitcnt vmcnt(10)
	s_barrier
	s_waitcnt lgkmcnt(0)
	s_waitcnt lgkmcnt(0)
	v_mfma_f32_16x16x32_bf16 v[62:65], v[152:155], v[168:171], 0
	v_mfma_f32_16x16x32_bf16 v[58:61], v[160:163], v[168:171], 0
	v_mfma_f32_16x16x32_bf16 v[54:57], v[152:155], v[176:179], 0
	v_mfma_f32_16x16x32_bf16 v[50:53], v[160:163], v[176:179], 0
	v_mfma_f32_16x16x32_bf16 v[38:41], v[152:155], v[184:187], 0
	v_mfma_f32_16x16x32_bf16 v[34:37], v[160:163], v[184:187], 0
	v_mfma_f32_16x16x32_bf16 v[22:25], v[152:155], v[192:195], 0
	v_mfma_f32_16x16x32_bf16 v[18:21], v[160:163], v[192:195], 0
	v_mfma_f32_16x16x32_bf16 v[62:65], v[156:159], v[172:175], v[62:65]
	v_mfma_f32_16x16x32_bf16 v[58:61], v[164:167], v[172:175], v[58:61]
	v_mfma_f32_16x16x32_bf16 v[54:57], v[156:159], v[180:183], v[54:57]
	v_mfma_f32_16x16x32_bf16 v[50:53], v[164:167], v[180:183], v[50:53]
	v_mfma_f32_16x16x32_bf16 v[38:41], v[156:159], v[188:191], v[38:41]
	v_mfma_f32_16x16x32_bf16 v[34:37], v[164:167], v[188:191], v[34:37]
	v_mfma_f32_16x16x32_bf16 v[22:25], v[156:159], v[196:199], v[22:25]
	v_mfma_f32_16x16x32_bf16 v[18:21], v[164:167], v[196:199], v[18:21]
	s_barrier
	s_add_u32 s0, s28, 0x40000
	s_addc_u32 s1, s29, 0
	s_add_i32 s50, s43, s9
	s_mov_b32 m0, s50
	s_nop 0
	global_load_lds_dwordx4 v134, s[0:1]
	s_add_i32 m0, s50, 0x2000
	s_nop 0
	global_load_lds_dwordx4 v130, s[0:1]
	s_waitcnt vmcnt(10)
	s_barrier
	v_mfma_f32_16x16x32_bf16 v[46:49], v[200:203], v[168:171], 0
	v_mfma_f32_16x16x32_bf16 v[42:45], v[208:211], v[168:171], 0
	v_mfma_f32_16x16x32_bf16 v[30:33], v[200:203], v[176:179], 0
	v_mfma_f32_16x16x32_bf16 v[26:29], v[208:211], v[176:179], 0
	v_mfma_f32_16x16x32_bf16 v[14:17], v[200:203], v[184:187], 0
	v_mfma_f32_16x16x32_bf16 v[10:13], v[208:211], v[184:187], 0
	v_mfma_f32_16x16x32_bf16 v[6:9], v[200:203], v[192:195], 0
	v_mfma_f32_16x16x32_bf16 v[2:5], v[208:211], v[192:195], 0
	v_mfma_f32_16x16x32_bf16 v[46:49], v[204:207], v[172:175], v[46:49]
	v_mfma_f32_16x16x32_bf16 v[42:45], v[212:215], v[172:175], v[42:45]
	v_mfma_f32_16x16x32_bf16 v[30:33], v[204:207], v[180:183], v[30:33]
	v_mfma_f32_16x16x32_bf16 v[26:29], v[212:215], v[180:183], v[26:29]
	v_mfma_f32_16x16x32_bf16 v[14:17], v[204:207], v[188:191], v[14:17]
	v_mfma_f32_16x16x32_bf16 v[10:13], v[212:215], v[188:191], v[10:13]
	v_mfma_f32_16x16x32_bf16 v[6:9], v[204:207], v[196:199], v[6:9]
	v_mfma_f32_16x16x32_bf16 v[2:5], v[212:215], v[196:199], v[2:5]
	s_add_i32 s50, 0, 0x18000
	v_add_u32_e32 v164, s50, v148
	s_barrier
	ds_read_b128 v[152:155], v164
	ds_read_b128 v[156:159], v164 offset:1024
	ds_read_b128 v[160:163], v164 offset:2048
	ds_read_b128 v[164:167], v164 offset:3072
	s_add_u32 s0, s30, 0x40000
	s_addc_u32 s1, s31, 0
	s_mov_b32 m0, s17
	ds_read_b128 v[168:171], v150 offset:32768
	ds_read_b128 v[172:175], v150 offset:33792
	ds_read_b128 v[176:179], v150 offset:34816
	ds_read_b128 v[180:183], v150 offset:35840
	ds_read_b128 v[184:187], v150 offset:36864
	ds_read_b128 v[188:191], v150 offset:37888
	ds_read_b128 v[192:195], v150 offset:38912
	ds_read_b128 v[196:199], v150 offset:39936
	global_load_lds_dwordx4 v136, s[0:1]
	s_mov_b32 m0, s34
	s_nop 0
	global_load_lds_dwordx4 v132, s[0:1]
	s_waitcnt lgkmcnt(8)
	s_waitcnt vmcnt(10)
	s_barrier
	s_waitcnt lgkmcnt(0)
	s_waitcnt lgkmcnt(0)
	v_mfma_f32_16x16x32_bf16 v[126:129], v[152:155], v[168:171], v[126:129]
	v_mfma_f32_16x16x32_bf16 v[122:125], v[160:163], v[168:171], v[122:125]
	v_mfma_f32_16x16x32_bf16 v[118:121], v[152:155], v[176:179], v[118:121]
	v_mfma_f32_16x16x32_bf16 v[110:113], v[160:163], v[176:179], v[110:113]
	v_mfma_f32_16x16x32_bf16 v[102:105], v[152:155], v[184:187], v[102:105]
	v_mfma_f32_16x16x32_bf16 v[94:97], v[160:163], v[184:187], v[94:97]
	v_mfma_f32_16x16x32_bf16 v[86:89], v[152:155], v[192:195], v[86:89]
	v_mfma_f32_16x16x32_bf16 v[78:81], v[160:163], v[192:195], v[78:81]
	v_mfma_f32_16x16x32_bf16 v[126:129], v[156:159], v[172:175], v[126:129]
	v_mfma_f32_16x16x32_bf16 v[122:125], v[164:167], v[172:175], v[122:125]
	v_mfma_f32_16x16x32_bf16 v[118:121], v[156:159], v[180:183], v[118:121]
	v_mfma_f32_16x16x32_bf16 v[110:113], v[164:167], v[180:183], v[110:113]
	v_mfma_f32_16x16x32_bf16 v[102:105], v[156:159], v[188:191], v[102:105]
	v_mfma_f32_16x16x32_bf16 v[94:97], v[164:167], v[188:191], v[94:97]
	v_mfma_f32_16x16x32_bf16 v[86:89], v[156:159], v[196:199], v[86:89]
	v_mfma_f32_16x16x32_bf16 v[78:81], v[164:167], v[196:199], v[78:81]
	s_barrier
	s_add_i32 s30, 0, 0x1c000
	s_add_i32 s0, s50, s9
	v_add_u32_e32 v212, s30, v148
	v_lshl_add_u64 v[216:217], v[216:217], 0, s[14:15]
	s_mov_b32 m0, s0
	ds_read_b128 v[200:203], v212
	ds_read_b128 v[204:207], v212 offset:1024
	ds_read_b128 v[208:211], v212 offset:2048
	ds_read_b128 v[212:215], v212 offset:3072
	global_load_lds_dwordx4 v[216:217], off
	v_lshl_add_u64 v[216:217], v[218:219], 0, s[14:15]
	s_add_i32 m0, s0, 0x2000
	s_nop 0
	global_load_lds_dwordx4 v[216:217], off
	s_waitcnt vmcnt(10)
	s_barrier
	s_waitcnt lgkmcnt(0)
	s_waitcnt lgkmcnt(0)
	v_mfma_f32_16x16x32_bf16 v[114:117], v[200:203], v[168:171], v[114:117]
	v_mfma_f32_16x16x32_bf16 v[106:109], v[208:211], v[168:171], v[106:109]
	v_mfma_f32_16x16x32_bf16 v[98:101], v[200:203], v[176:179], v[98:101]
	v_mfma_f32_16x16x32_bf16 v[90:93], v[208:211], v[176:179], v[90:93]
	v_mfma_f32_16x16x32_bf16 v[82:85], v[200:203], v[184:187], v[82:85]
	v_mfma_f32_16x16x32_bf16 v[74:77], v[208:211], v[184:187], v[74:77]
	v_mfma_f32_16x16x32_bf16 v[70:73], v[200:203], v[192:195], v[70:73]
	v_mfma_f32_16x16x32_bf16 v[66:69], v[208:211], v[192:195], v[66:69]
	v_mfma_f32_16x16x32_bf16 v[114:117], v[204:207], v[172:175], v[114:117]
	v_mfma_f32_16x16x32_bf16 v[106:109], v[212:215], v[172:175], v[106:109]
	v_mfma_f32_16x16x32_bf16 v[98:101], v[204:207], v[180:183], v[98:101]
	v_mfma_f32_16x16x32_bf16 v[90:93], v[212:215], v[180:183], v[90:93]
	v_mfma_f32_16x16x32_bf16 v[82:85], v[204:207], v[188:191], v[82:85]
	v_mfma_f32_16x16x32_bf16 v[74:77], v[212:215], v[188:191], v[74:77]
	v_mfma_f32_16x16x32_bf16 v[70:73], v[204:207], v[196:199], v[70:73]
	v_mfma_f32_16x16x32_bf16 v[66:69], v[212:215], v[196:199], v[66:69]
	s_mov_b32 m0, s40
	v_lshl_add_u64 v[216:217], v[220:221], 0, s[14:15]
	s_barrier
	ds_read_b128 v[168:171], v150 offset:49152
	ds_read_b128 v[172:175], v150 offset:50176
	ds_read_b128 v[176:179], v150 offset:51200
	ds_read_b128 v[180:183], v150 offset:52224
	ds_read_b128 v[184:187], v150 offset:53248
	ds_read_b128 v[188:191], v150 offset:54272
	ds_read_b128 v[192:195], v150 offset:55296
	ds_read_b128 v[196:199], v150 offset:56320
	global_load_lds_dwordx4 v[216:217], off
	v_lshl_add_u64 v[216:217], v[222:223], 0, s[14:15]
	s_mov_b32 m0, s41
	s_nop 0
	global_load_lds_dwordx4 v[216:217], off
	s_waitcnt vmcnt(10)
	s_barrier
	s_waitcnt lgkmcnt(0)
	s_waitcnt lgkmcnt(0)
	v_mfma_f32_16x16x32_bf16 v[62:65], v[152:155], v[168:171], v[62:65]
	v_mfma_f32_16x16x32_bf16 v[58:61], v[160:163], v[168:171], v[58:61]
	v_mfma_f32_16x16x32_bf16 v[54:57], v[152:155], v[176:179], v[54:57]
	v_mfma_f32_16x16x32_bf16 v[50:53], v[160:163], v[176:179], v[50:53]
	v_mfma_f32_16x16x32_bf16 v[38:41], v[152:155], v[184:187], v[38:41]
	v_mfma_f32_16x16x32_bf16 v[34:37], v[160:163], v[184:187], v[34:37]
	v_mfma_f32_16x16x32_bf16 v[22:25], v[152:155], v[192:195], v[22:25]
	v_mfma_f32_16x16x32_bf16 v[18:21], v[160:163], v[192:195], v[18:21]
	v_mfma_f32_16x16x32_bf16 v[62:65], v[156:159], v[172:175], v[62:65]
	v_mfma_f32_16x16x32_bf16 v[58:61], v[164:167], v[172:175], v[58:61]
	v_mfma_f32_16x16x32_bf16 v[54:57], v[156:159], v[180:183], v[54:57]
	v_mfma_f32_16x16x32_bf16 v[50:53], v[164:167], v[180:183], v[50:53]
	v_mfma_f32_16x16x32_bf16 v[38:41], v[156:159], v[188:191], v[38:41]
	v_mfma_f32_16x16x32_bf16 v[34:37], v[164:167], v[188:191], v[34:37]
	v_mfma_f32_16x16x32_bf16 v[22:25], v[156:159], v[196:199], v[22:25]
	v_mfma_f32_16x16x32_bf16 v[18:21], v[164:167], v[196:199], v[18:21]
	s_barrier
	s_add_u32 s0, s28, 0x40080
	s_addc_u32 s1, s29, 0
	s_add_i32 s28, s30, s9
	s_mov_b32 m0, s28
	s_nop 0
	global_load_lds_dwordx4 v134, s[0:1]
	s_add_i32 m0, s28, 0x2000
	s_nop 0
	global_load_lds_dwordx4 v130, s[0:1]
	s_waitcnt vmcnt(10)
	s_barrier
	v_mfma_f32_16x16x32_bf16 v[46:49], v[200:203], v[168:171], v[46:49]
	v_mfma_f32_16x16x32_bf16 v[42:45], v[208:211], v[168:171], v[42:45]
	v_mfma_f32_16x16x32_bf16 v[30:33], v[200:203], v[176:179], v[30:33]
	v_mfma_f32_16x16x32_bf16 v[26:29], v[208:211], v[176:179], v[26:29]
	v_mfma_f32_16x16x32_bf16 v[14:17], v[200:203], v[184:187], v[14:17]
	v_mfma_f32_16x16x32_bf16 v[10:13], v[208:211], v[184:187], v[10:13]
	v_mfma_f32_16x16x32_bf16 v[6:9], v[200:203], v[192:195], v[6:9]
	v_mfma_f32_16x16x32_bf16 v[2:5], v[208:211], v[192:195], v[2:5]
	v_mfma_f32_16x16x32_bf16 v[46:49], v[204:207], v[172:175], v[46:49]
	v_mfma_f32_16x16x32_bf16 v[42:45], v[212:215], v[172:175], v[42:45]
	v_mfma_f32_16x16x32_bf16 v[30:33], v[204:207], v[180:183], v[30:33]
	v_mfma_f32_16x16x32_bf16 v[26:29], v[212:215], v[180:183], v[26:29]
	v_mfma_f32_16x16x32_bf16 v[14:17], v[204:207], v[188:191], v[14:17]
	v_mfma_f32_16x16x32_bf16 v[10:13], v[212:215], v[188:191], v[10:13]
	v_mfma_f32_16x16x32_bf16 v[6:9], v[204:207], v[196:199], v[6:9]
	v_mfma_f32_16x16x32_bf16 v[2:5], v[212:215], v[196:199], v[2:5]
	s_add_i32 s49, s49, 2
	s_add_u32 s47, s47, 0x100
	s_addc_u32 s48, s48, 0
	s_add_u32 s26, s26, 0x100
	s_addc_u32 s27, s27, 0
	s_cmp_gt_u32 s49, 13
	s_barrier
	s_cbranch_scc1 .Lpeel_exit_8
.LBB0_1513:
	ds_read_b128 v[152:155], v149
	ds_read_b128 v[156:159], v149 offset:1024
	ds_read_b128 v[160:163], v149 offset:2048
	ds_read_b128 v[164:167], v149 offset:3072
	s_add_u32 s0, s26, 0xfffc0080
	s_addc_u32 s1, s27, -1
	s_cmp_eq_u32 s49, 12
	s_cselect_b32 s31, s21, s1
	s_cselect_b32 s30, s45, s0
	s_cselect_b32 s29, s19, s48
	s_cselect_b32 s28, s46, s47
	s_add_i32 m0, s10, 0xc000
	ds_read_b128 v[168:171], v150
	ds_read_b128 v[172:175], v150 offset:1024
	ds_read_b128 v[176:179], v150 offset:2048
	ds_read_b128 v[180:183], v150 offset:3072
	ds_read_b128 v[184:187], v150 offset:4096
	ds_read_b128 v[188:191], v150 offset:5120
	ds_read_b128 v[192:195], v150 offset:6144
	ds_read_b128 v[196:199], v150 offset:7168
	global_load_lds_dwordx4 v140, s[26:27]
	s_add_i32 m0, s10, 0xe000
	s_nop 0
	global_load_lds_dwordx4 v138, s[26:27]
	s_waitcnt lgkmcnt(8)
	s_waitcnt vmcnt(10)
	s_barrier
	s_waitcnt lgkmcnt(0)
	s_waitcnt lgkmcnt(0)
	v_mfma_f32_16x16x32_bf16 v[126:129], v[152:155], v[168:171], v[126:129]
	v_mfma_f32_16x16x32_bf16 v[122:125], v[160:163], v[168:171], v[122:125]
	v_mfma_f32_16x16x32_bf16 v[118:121], v[152:155], v[176:179], v[118:121]
	v_mfma_f32_16x16x32_bf16 v[110:113], v[160:163], v[176:179], v[110:113]
	v_mfma_f32_16x16x32_bf16 v[102:105], v[152:155], v[184:187], v[102:105]
	v_mfma_f32_16x16x32_bf16 v[94:97], v[160:163], v[184:187], v[94:97]
	v_mfma_f32_16x16x32_bf16 v[86:89], v[152:155], v[192:195], v[86:89]
	v_mfma_f32_16x16x32_bf16 v[78:81], v[160:163], v[192:195], v[78:81]
	v_mfma_f32_16x16x32_bf16 v[126:129], v[156:159], v[172:175], v[126:129]
	v_mfma_f32_16x16x32_bf16 v[122:125], v[164:167], v[172:175], v[122:125]
	v_mfma_f32_16x16x32_bf16 v[118:121], v[156:159], v[180:183], v[118:121]
	v_mfma_f32_16x16x32_bf16 v[110:113], v[164:167], v[180:183], v[110:113]
	v_mfma_f32_16x16x32_bf16 v[102:105], v[156:159], v[188:191], v[102:105]
	v_mfma_f32_16x16x32_bf16 v[94:97], v[164:167], v[188:191], v[94:97]
	v_mfma_f32_16x16x32_bf16 v[86:89], v[156:159], v[196:199], v[86:89]
	v_mfma_f32_16x16x32_bf16 v[78:81], v[164:167], v[196:199], v[78:81]
	s_barrier
	s_add_i32 s0, s42, s9
	v_lshl_add_u64 v[216:217], s[28:29], 0, v[134:135]
	s_mov_b32 m0, s0
	ds_read_b128 v[200:203], v151
	ds_read_b128 v[204:207], v151 offset:1024
	ds_read_b128 v[208:211], v151 offset:2048
	ds_read_b128 v[212:215], v151 offset:3072
	global_load_lds_dwordx4 v[216:217], off
	v_lshl_add_u64 v[218:219], s[28:29], 0, v[130:131]
	s_add_i32 m0, s0, 0x2000
	s_nop 0
	global_load_lds_dwordx4 v[218:219], off
	s_waitcnt vmcnt(10)
	s_barrier
	s_waitcnt lgkmcnt(0)
	s_waitcnt lgkmcnt(0)
	v_mfma_f32_16x16x32_bf16 v[114:117], v[200:203], v[168:171], v[114:117]
	v_mfma_f32_16x16x32_bf16 v[106:109], v[208:211], v[168:171], v[106:109]
	v_mfma_f32_16x16x32_bf16 v[98:101], v[200:203], v[176:179], v[98:101]
	v_mfma_f32_16x16x32_bf16 v[90:93], v[208:211], v[176:179], v[90:93]
	v_mfma_f32_16x16x32_bf16 v[82:85], v[200:203], v[184:187], v[82:85]
	v_mfma_f32_16x16x32_bf16 v[74:77], v[208:211], v[184:187], v[74:77]
	v_mfma_f32_16x16x32_bf16 v[70:73], v[200:203], v[192:195], v[70:73]
	v_mfma_f32_16x16x32_bf16 v[66:69], v[208:211], v[192:195], v[66:69]
	v_mfma_f32_16x16x32_bf16 v[114:117], v[204:207], v[172:175], v[114:117]
	v_mfma_f32_16x16x32_bf16 v[106:109], v[212:215], v[172:175], v[106:109]
	v_mfma_f32_16x16x32_bf16 v[98:101], v[204:207], v[180:183], v[98:101]
	v_mfma_f32_16x16x32_bf16 v[90:93], v[212:215], v[180:183], v[90:93]
	v_mfma_f32_16x16x32_bf16 v[82:85], v[204:207], v[188:191], v[82:85]
	v_mfma_f32_16x16x32_bf16 v[74:77], v[212:215], v[188:191], v[74:77]
	v_mfma_f32_16x16x32_bf16 v[70:73], v[204:207], v[196:199], v[70:73]
	v_mfma_f32_16x16x32_bf16 v[66:69], v[212:215], v[196:199], v[66:69]
	s_mov_b32 m0, s10
	v_lshl_add_u64 v[220:221], s[30:31], 0, v[136:137]
	s_barrier
	ds_read_b128 v[168:171], v150 offset:16384
	ds_read_b128 v[172:175], v150 offset:17408
	ds_read_b128 v[176:179], v150 offset:18432
	ds_read_b128 v[180:183], v150 offset:19456
	ds_read_b128 v[184:187], v150 offset:20480
	ds_read_b128 v[188:191], v150 offset:21504
	ds_read_b128 v[192:195], v150 offset:22528
	ds_read_b128 v[196:199], v150 offset:23552
	global_load_lds_dwordx4 v[220:221], off
	v_lshl_add_u64 v[222:223], s[30:31], 0, v[132:133]
	s_mov_b32 m0, s11
	s_nop 0
	global_load_lds_dwordx4 v[222:223], off
	s_waitcnt vmcnt(10)
	s_barrier
	s_waitcnt lgkmcnt(0)
	s_waitcnt lgkmcnt(0)
	v_mfma_f32_16x16x32_bf16 v[62:65], v[152:155], v[168:171], v[62:65]
	v_mfma_f32_16x16x32_bf16 v[58:61], v[160:163], v[168:171], v[58:61]
	v_mfma_f32_16x16x32_bf16 v[54:57], v[152:155], v[176:179], v[54:57]
	v_mfma_f32_16x16x32_bf16 v[50:53], v[160:163], v[176:179], v[50:53]
	v_mfma_f32_16x16x32_bf16 v[38:41], v[152:155], v[184:187], v[38:41]
	v_mfma_f32_16x16x32_bf16 v[34:37], v[160:163], v[184:187], v[34:37]
	v_mfma_f32_16x16x32_bf16 v[22:25], v[152:155], v[192:195], v[22:25]
	v_mfma_f32_16x16x32_bf16 v[18:21], v[160:163], v[192:195], v[18:21]
	v_mfma_f32_16x16x32_bf16 v[62:65], v[156:159], v[172:175], v[62:65]
	v_mfma_f32_16x16x32_bf16 v[58:61], v[164:167], v[172:175], v[58:61]
	v_mfma_f32_16x16x32_bf16 v[54:57], v[156:159], v[180:183], v[54:57]
	v_mfma_f32_16x16x32_bf16 v[50:53], v[164:167], v[180:183], v[50:53]
	v_mfma_f32_16x16x32_bf16 v[38:41], v[156:159], v[188:191], v[38:41]
	v_mfma_f32_16x16x32_bf16 v[34:37], v[164:167], v[188:191], v[34:37]
	v_mfma_f32_16x16x32_bf16 v[22:25], v[156:159], v[196:199], v[22:25]
	v_mfma_f32_16x16x32_bf16 v[18:21], v[164:167], v[196:199], v[18:21]
	s_barrier
	s_add_u32 s0, s28, 0x40000
	s_addc_u32 s1, s29, 0
	s_add_i32 s50, s43, s9
	s_mov_b32 m0, s50
	s_nop 0
	global_load_lds_dwordx4 v134, s[0:1]
	s_add_i32 m0, s50, 0x2000
	s_nop 0
	global_load_lds_dwordx4 v130, s[0:1]
	s_waitcnt vmcnt(10)
	s_barrier
	v_mfma_f32_16x16x32_bf16 v[46:49], v[200:203], v[168:171], v[46:49]
	v_mfma_f32_16x16x32_bf16 v[42:45], v[208:211], v[168:171], v[42:45]
	v_mfma_f32_16x16x32_bf16 v[30:33], v[200:203], v[176:179], v[30:33]
	v_mfma_f32_16x16x32_bf16 v[26:29], v[208:211], v[176:179], v[26:29]
	v_mfma_f32_16x16x32_bf16 v[14:17], v[200:203], v[184:187], v[14:17]
	v_mfma_f32_16x16x32_bf16 v[10:13], v[208:211], v[184:187], v[10:13]
	v_mfma_f32_16x16x32_bf16 v[6:9], v[200:203], v[192:195], v[6:9]
	v_mfma_f32_16x16x32_bf16 v[2:5], v[208:211], v[192:195], v[2:5]
	v_mfma_f32_16x16x32_bf16 v[46:49], v[204:207], v[172:175], v[46:49]
	v_mfma_f32_16x16x32_bf16 v[42:45], v[212:215], v[172:175], v[42:45]
	v_mfma_f32_16x16x32_bf16 v[30:33], v[204:207], v[180:183], v[30:33]
	v_mfma_f32_16x16x32_bf16 v[26:29], v[212:215], v[180:183], v[26:29]
	v_mfma_f32_16x16x32_bf16 v[14:17], v[204:207], v[188:191], v[14:17]
	v_mfma_f32_16x16x32_bf16 v[10:13], v[212:215], v[188:191], v[10:13]
	v_mfma_f32_16x16x32_bf16 v[6:9], v[204:207], v[196:199], v[6:9]
	v_mfma_f32_16x16x32_bf16 v[2:5], v[212:215], v[196:199], v[2:5]
	s_add_i32 s50, 0, 0x18000
	v_add_u32_e32 v164, s50, v148
	s_barrier
	ds_read_b128 v[152:155], v164
	ds_read_b128 v[156:159], v164 offset:1024
	ds_read_b128 v[160:163], v164 offset:2048
	ds_read_b128 v[164:167], v164 offset:3072
	s_add_u32 s0, s30, 0x40000
	s_addc_u32 s1, s31, 0
	s_mov_b32 m0, s17
	ds_read_b128 v[168:171], v150 offset:32768
	ds_read_b128 v[172:175], v150 offset:33792
	ds_read_b128 v[176:179], v150 offset:34816
	ds_read_b128 v[180:183], v150 offset:35840
	ds_read_b128 v[184:187], v150 offset:36864
	ds_read_b128 v[188:191], v150 offset:37888
	ds_read_b128 v[192:195], v150 offset:38912
	ds_read_b128 v[196:199], v150 offset:39936
	global_load_lds_dwordx4 v136, s[0:1]
	s_mov_b32 m0, s34
	s_nop 0
	global_load_lds_dwordx4 v132, s[0:1]
	s_waitcnt lgkmcnt(8)
	s_waitcnt vmcnt(10)
	s_barrier
	s_waitcnt lgkmcnt(0)
	s_waitcnt lgkmcnt(0)
	v_mfma_f32_16x16x32_bf16 v[126:129], v[152:155], v[168:171], v[126:129]
	v_mfma_f32_16x16x32_bf16 v[122:125], v[160:163], v[168:171], v[122:125]
	v_mfma_f32_16x16x32_bf16 v[118:121], v[152:155], v[176:179], v[118:121]
	v_mfma_f32_16x16x32_bf16 v[110:113], v[160:163], v[176:179], v[110:113]
	v_mfma_f32_16x16x32_bf16 v[102:105], v[152:155], v[184:187], v[102:105]
	v_mfma_f32_16x16x32_bf16 v[94:97], v[160:163], v[184:187], v[94:97]
	v_mfma_f32_16x16x32_bf16 v[86:89], v[152:155], v[192:195], v[86:89]
	v_mfma_f32_16x16x32_bf16 v[78:81], v[160:163], v[192:195], v[78:81]
	v_mfma_f32_16x16x32_bf16 v[126:129], v[156:159], v[172:175], v[126:129]
	v_mfma_f32_16x16x32_bf16 v[122:125], v[164:167], v[172:175], v[122:125]
	v_mfma_f32_16x16x32_bf16 v[118:121], v[156:159], v[180:183], v[118:121]
	v_mfma_f32_16x16x32_bf16 v[110:113], v[164:167], v[180:183], v[110:113]
	v_mfma_f32_16x16x32_bf16 v[102:105], v[156:159], v[188:191], v[102:105]
	v_mfma_f32_16x16x32_bf16 v[94:97], v[164:167], v[188:191], v[94:97]
	v_mfma_f32_16x16x32_bf16 v[86:89], v[156:159], v[196:199], v[86:89]
	v_mfma_f32_16x16x32_bf16 v[78:81], v[164:167], v[196:199], v[78:81]
	s_barrier
	s_add_i32 s30, 0, 0x1c000
	s_add_i32 s0, s50, s9
	v_add_u32_e32 v212, s30, v148
	v_lshl_add_u64 v[216:217], v[216:217], 0, s[14:15]
	s_mov_b32 m0, s0
	ds_read_b128 v[200:203], v212
	ds_read_b128 v[204:207], v212 offset:1024
	ds_read_b128 v[208:211], v212 offset:2048
	ds_read_b128 v[212:215], v212 offset:3072
	global_load_lds_dwordx4 v[216:217], off
	v_lshl_add_u64 v[216:217], v[218:219], 0, s[14:15]
	s_add_i32 m0, s0, 0x2000
	s_nop 0
	global_load_lds_dwordx4 v[216:217], off
	s_waitcnt vmcnt(10)
	s_barrier
	s_waitcnt lgkmcnt(0)
	s_waitcnt lgkmcnt(0)
	v_mfma_f32_16x16x32_bf16 v[114:117], v[200:203], v[168:171], v[114:117]
	v_mfma_f32_16x16x32_bf16 v[106:109], v[208:211], v[168:171], v[106:109]
	v_mfma_f32_16x16x32_bf16 v[98:101], v[200:203], v[176:179], v[98:101]
	v_mfma_f32_16x16x32_bf16 v[90:93], v[208:211], v[176:179], v[90:93]
	v_mfma_f32_16x16x32_bf16 v[82:85], v[200:203], v[184:187], v[82:85]
	v_mfma_f32_16x16x32_bf16 v[74:77], v[208:211], v[184:187], v[74:77]
	v_mfma_f32_16x16x32_bf16 v[70:73], v[200:203], v[192:195], v[70:73]
	v_mfma_f32_16x16x32_bf16 v[66:69], v[208:211], v[192:195], v[66:69]
	v_mfma_f32_16x16x32_bf16 v[114:117], v[204:207], v[172:175], v[114:117]
	v_mfma_f32_16x16x32_bf16 v[106:109], v[212:215], v[172:175], v[106:109]
	v_mfma_f32_16x16x32_bf16 v[98:101], v[204:207], v[180:183], v[98:101]
	v_mfma_f32_16x16x32_bf16 v[90:93], v[212:215], v[180:183], v[90:93]
	v_mfma_f32_16x16x32_bf16 v[82:85], v[204:207], v[188:191], v[82:85]
	v_mfma_f32_16x16x32_bf16 v[74:77], v[212:215], v[188:191], v[74:77]
	v_mfma_f32_16x16x32_bf16 v[70:73], v[204:207], v[196:199], v[70:73]
	v_mfma_f32_16x16x32_bf16 v[66:69], v[212:215], v[196:199], v[66:69]
	s_mov_b32 m0, s40
	v_lshl_add_u64 v[216:217], v[220:221], 0, s[14:15]
	s_barrier
	ds_read_b128 v[168:171], v150 offset:49152
	ds_read_b128 v[172:175], v150 offset:50176
	ds_read_b128 v[176:179], v150 offset:51200
	ds_read_b128 v[180:183], v150 offset:52224
	ds_read_b128 v[184:187], v150 offset:53248
	ds_read_b128 v[188:191], v150 offset:54272
	ds_read_b128 v[192:195], v150 offset:55296
	ds_read_b128 v[196:199], v150 offset:56320
	global_load_lds_dwordx4 v[216:217], off
	v_lshl_add_u64 v[216:217], v[222:223], 0, s[14:15]
	s_mov_b32 m0, s41
	s_nop 0
	global_load_lds_dwordx4 v[216:217], off
	s_waitcnt vmcnt(10)
	s_barrier
	s_waitcnt lgkmcnt(0)
	s_waitcnt lgkmcnt(0)
	v_mfma_f32_16x16x32_bf16 v[62:65], v[152:155], v[168:171], v[62:65]
	v_mfma_f32_16x16x32_bf16 v[58:61], v[160:163], v[168:171], v[58:61]
	v_mfma_f32_16x16x32_bf16 v[54:57], v[152:155], v[176:179], v[54:57]
	v_mfma_f32_16x16x32_bf16 v[50:53], v[160:163], v[176:179], v[50:53]
	v_mfma_f32_16x16x32_bf16 v[38:41], v[152:155], v[184:187], v[38:41]
	v_mfma_f32_16x16x32_bf16 v[34:37], v[160:163], v[184:187], v[34:37]
	v_mfma_f32_16x16x32_bf16 v[22:25], v[152:155], v[192:195], v[22:25]
	v_mfma_f32_16x16x32_bf16 v[18:21], v[160:163], v[192:195], v[18:21]
	v_mfma_f32_16x16x32_bf16 v[62:65], v[156:159], v[172:175], v[62:65]
	v_mfma_f32_16x16x32_bf16 v[58:61], v[164:167], v[172:175], v[58:61]
	v_mfma_f32_16x16x32_bf16 v[54:57], v[156:159], v[180:183], v[54:57]
	v_mfma_f32_16x16x32_bf16 v[50:53], v[164:167], v[180:183], v[50:53]
	v_mfma_f32_16x16x32_bf16 v[38:41], v[156:159], v[188:191], v[38:41]
	v_mfma_f32_16x16x32_bf16 v[34:37], v[164:167], v[188:191], v[34:37]
	v_mfma_f32_16x16x32_bf16 v[22:25], v[156:159], v[196:199], v[22:25]
	v_mfma_f32_16x16x32_bf16 v[18:21], v[164:167], v[196:199], v[18:21]
	s_barrier
	s_add_u32 s0, s28, 0x40080
	s_addc_u32 s1, s29, 0
	s_add_i32 s28, s30, s9
	s_mov_b32 m0, s28
	s_nop 0
	global_load_lds_dwordx4 v134, s[0:1]
	s_add_i32 m0, s28, 0x2000
	s_nop 0
	global_load_lds_dwordx4 v130, s[0:1]
	s_waitcnt vmcnt(10)
	s_barrier
	v_mfma_f32_16x16x32_bf16 v[46:49], v[200:203], v[168:171], v[46:49]
	v_mfma_f32_16x16x32_bf16 v[42:45], v[208:211], v[168:171], v[42:45]
	v_mfma_f32_16x16x32_bf16 v[30:33], v[200:203], v[176:179], v[30:33]
	v_mfma_f32_16x16x32_bf16 v[26:29], v[208:211], v[176:179], v[26:29]
	v_mfma_f32_16x16x32_bf16 v[14:17], v[200:203], v[184:187], v[14:17]
	v_mfma_f32_16x16x32_bf16 v[10:13], v[208:211], v[184:187], v[10:13]
	v_mfma_f32_16x16x32_bf16 v[6:9], v[200:203], v[192:195], v[6:9]
	v_mfma_f32_16x16x32_bf16 v[2:5], v[208:211], v[192:195], v[2:5]
	v_mfma_f32_16x16x32_bf16 v[46:49], v[204:207], v[172:175], v[46:49]
	v_mfma_f32_16x16x32_bf16 v[42:45], v[212:215], v[172:175], v[42:45]
	v_mfma_f32_16x16x32_bf16 v[30:33], v[204:207], v[180:183], v[30:33]
	v_mfma_f32_16x16x32_bf16 v[26:29], v[212:215], v[180:183], v[26:29]
	v_mfma_f32_16x16x32_bf16 v[14:17], v[204:207], v[188:191], v[14:17]
	v_mfma_f32_16x16x32_bf16 v[10:13], v[212:215], v[188:191], v[10:13]
	v_mfma_f32_16x16x32_bf16 v[6:9], v[204:207], v[196:199], v[6:9]
	v_mfma_f32_16x16x32_bf16 v[2:5], v[212:215], v[196:199], v[2:5]
	s_add_i32 s49, s49, 2
	s_add_u32 s47, s47, 0x100
	s_addc_u32 s48, s48, 0
	s_add_u32 s26, s26, 0x100
	s_addc_u32 s27, s27, 0
	s_cmp_gt_u32 s49, 13
	s_barrier
	s_cbranch_scc0 .LBB0_1513

.LBB0_1637:
	s_add_u32 s8, s18, 0x2a100000
	s_addc_u32 s9, s19, 0
	s_lshl_b32 s0, s0, 5
	s_mov_b64 s[26:27], 0x80
	s_and_b32 s11, s0, 0x60
	s_add_i32 m0, s39, 0x18000
	v_lshl_add_u64 v[8:9], v[8:9], 0, s[26:27]
	s_lshl_b32 s10, s1, 6
	s_lshl_b32 s4, s1, 13
	s_lshl_b32 s5, s11, 7
	s_waitcnt vmcnt(4)
	s_barrier
	global_load_lds_dwordx4 v[8:9], off
	v_lshl_add_u64 v[6:7], v[6:7], 0, s[26:27]
	s_add_i32 m0, s39, 0x1a000
	s_add_i32 s6, s39, 0x8000
	s_add_i32 s7, s39, 0xa000
	global_load_lds_dwordx4 v[6:7], off
	v_lshl_add_u64 v[4:5], v[4:5], 0, s[26:27]
	s_mov_b32 m0, s6
	s_add_u32 s0, s14, 0x10080
	global_load_lds_dwordx4 v[4:5], off
	v_lshl_add_u64 v[2:3], v[2:3], 0, s[26:27]
	s_mov_b32 m0, s7
	s_addc_u32 s1, s15, 0
	global_load_lds_dwordx4 v[2:3], off
	s_add_i32 m0, s39, 0x1c000
	s_nop 0
	global_load_lds_dwordx4 v158, s[0:1]
	s_add_i32 m0, s39, 0x1e000
	v_bfe_u32 v223, v10, 4, 2
	global_load_lds_dwordx4 v154, s[0:1]
	v_and_b32_e32 v222, 15, v10
	v_lshlrev_b32_e32 v2, 4, v223
	v_lshlrev_b32_e32 v3, 2, v10
	v_lshl_or_b32 v2, v222, 6, v2
	v_and_b32_e32 v3, 32, v3
	s_waitcnt vmcnt(6)
	v_bitop3_b32 v4, v2, s4, v3 bitop3:0xde
	v_bitop3_b32 v224, v2, s5, v3 bitop3:0xde
	s_add_i32 s85, 0, 0x10000
	s_add_i32 s4, 0, 0x14000
	s_mov_b32 s89, 0x18000
	s_mov_b32 s84, 0x8000
	v_mov_b64_e32 v[162:163], 0x1000
	v_mov_b64_e32 v[164:165], 0xfff
	v_add_u32_e32 v225, s85, v224
	v_add_u32_e32 v226, 0, v4
	v_add_u32_e32 v227, s4, v224
	s_mov_b32 s5, 0xbfb8aa3b
	s_mov_b32 s72, 0x3f2aaaab
	s_mov_b32 s28, 0x3e9b6dac
	s_mov_b32 s30, 0x3f2aaada
	s_mov_b32 s34, 0x3f317218
	s_mov_b32 s36, 0xb102e308
	s_mov_b32 s73, 0x7f800000
	s_mov_b32 s77, 0x33800000
	s_mov_b32 s38, 0x41000000
	s_mov_b32 s29, 0xc3d00000
	v_mov_b32_e32 v228, 0x7f800000
	v_mov_b32_e32 v229, 0x7fc00000
	v_mov_b32_e32 v230, 0xff800000
	v_mov_b32_e32 v231, 0x43d00000
	s_barrier

.LBB0_1645:
	s_add_u32 s57, s48, s56
	s_addc_u32 s58, s49, 0
	s_add_u32 s59, s57, 0x100
	s_addc_u32 s60, s58, 0
	s_and_b64 s[0:1], s[54:55], exec
	s_cselect_b32 s61, s43, s60
	s_cselect_b32 s60, s83, s59
	s_add_u32 s0, s14, s56
	s_addc_u32 s1, s15, 0
	s_add_u32 s56, s0, 0x100
	s_addc_u32 s59, s1, 0
	s_and_b64 s[0:1], s[54:55], exec
	s_cselect_b32 s63, s41, s59
	s_cselect_b32 s62, s94, s56
	s_add_u32 s64, s57, 0x40080
	s_addc_u32 s65, s58, 0
	s_add_i32 s0, s85, s37
	s_add_i32 m0, s39, 0xc000
	s_add_i32 s71, s39, 0xe000
	s_add_i32 s70, s0, 0x2000
	s_add_u32 s58, s62, 0x10000
	s_addc_u32 s59, s63, 0
	s_add_i32 s1, s4, s37
	ds_read_b128 v[26:29], v225
	ds_read_b128 v[30:33], v225 offset:1024
	ds_read_b128 v[42:45], v225 offset:2048
	ds_read_b128 v[46:49], v225 offset:3072
	s_add_i32 s96, s1, 0x2000
	s_add_i32 s81, 0, 0x18000
	s_add_u32 s56, s60, 0x40000
	s_addc_u32 s57, s61, 0
	s_add_i32 s78, s81, s37
	s_add_i32 s79, 0, 0x1c000
	s_add_i32 s80, s78, 0x2000
	s_add_u32 s54, s62, 0x10080
	s_addc_u32 s55, s63, 0
	s_add_i32 vcc_hi, s79, s37
	s_add_i32 vcc_lo, vcc_hi, 0x2000
	ds_read_b128 v[146:149], v226
	ds_read_b128 v[150:153], v226 offset:1024
	ds_read_b128 v[166:169], v226 offset:2048
	ds_read_b128 v[170:173], v226 offset:3072
	ds_read_b128 v[174:177], v226 offset:4096
	ds_read_b128 v[178:181], v226 offset:5120
	ds_read_b128 v[182:185], v226 offset:6144
	ds_read_b128 v[186:189], v226 offset:7168
	global_load_lds_dwordx4 v160, s[64:65]
	s_mov_b32 m0, s71
	s_nop 0
	global_load_lds_dwordx4 v156, s[64:65]
	s_waitcnt lgkmcnt(8)
	s_waitcnt vmcnt(10)
	s_barrier
	s_waitcnt lgkmcnt(0)
	s_waitcnt lgkmcnt(0)
	v_mfma_f32_16x16x32_bf16 v[142:145], v[26:29], v[146:149], v[142:145]
	v_mfma_f32_16x16x32_bf16 v[134:137], v[42:45], v[146:149], v[134:137]
	v_mfma_f32_16x16x32_bf16 v[126:129], v[26:29], v[166:169], v[126:129]
	v_mfma_f32_16x16x32_bf16 v[118:121], v[42:45], v[166:169], v[118:121]
	v_mfma_f32_16x16x32_bf16 v[110:113], v[26:29], v[174:177], v[110:113]
	v_mfma_f32_16x16x32_bf16 v[102:105], v[42:45], v[174:177], v[102:105]
	v_mfma_f32_16x16x32_bf16 v[94:97], v[26:29], v[182:185], v[94:97]
	v_mfma_f32_16x16x32_bf16 v[86:89], v[42:45], v[182:185], v[86:89]
	v_mfma_f32_16x16x32_bf16 v[142:145], v[30:33], v[150:153], v[142:145]
	v_mfma_f32_16x16x32_bf16 v[134:137], v[46:49], v[150:153], v[134:137]
	v_mfma_f32_16x16x32_bf16 v[126:129], v[30:33], v[170:173], v[126:129]
	v_mfma_f32_16x16x32_bf16 v[118:121], v[46:49], v[170:173], v[118:121]
	v_mfma_f32_16x16x32_bf16 v[110:113], v[30:33], v[178:181], v[110:113]
	v_mfma_f32_16x16x32_bf16 v[102:105], v[46:49], v[178:181], v[102:105]
	v_mfma_f32_16x16x32_bf16 v[94:97], v[30:33], v[186:189], v[94:97]
	v_mfma_f32_16x16x32_bf16 v[86:89], v[46:49], v[186:189], v[86:89]
	s_barrier
	s_mov_b32 m0, s0
	v_lshl_add_u64 v[206:207], s[62:63], 0, v[158:159]
	ds_read_b128 v[190:193], v227
	ds_read_b128 v[194:197], v227 offset:1024
	ds_read_b128 v[198:201], v227 offset:2048
	ds_read_b128 v[202:205], v227 offset:3072
	global_load_lds_dwordx4 v[206:207], off
	v_lshl_add_u64 v[208:209], s[62:63], 0, v[154:155]
	s_mov_b32 m0, s70
	s_nop 0
	global_load_lds_dwordx4 v[208:209], off
	s_waitcnt vmcnt(10)
	s_barrier
	s_waitcnt lgkmcnt(0)
	s_waitcnt lgkmcnt(0)
	v_mfma_f32_16x16x32_bf16 v[138:141], v[190:193], v[146:149], v[138:141]
	v_mfma_f32_16x16x32_bf16 v[130:133], v[198:201], v[146:149], v[130:133]
	v_mfma_f32_16x16x32_bf16 v[122:125], v[190:193], v[166:169], v[122:125]
	v_mfma_f32_16x16x32_bf16 v[114:117], v[198:201], v[166:169], v[114:117]
	v_mfma_f32_16x16x32_bf16 v[106:109], v[190:193], v[174:177], v[106:109]
	v_mfma_f32_16x16x32_bf16 v[98:101], v[198:201], v[174:177], v[98:101]
	v_mfma_f32_16x16x32_bf16 v[90:93], v[190:193], v[182:185], v[90:93]
	v_mfma_f32_16x16x32_bf16 v[82:85], v[198:201], v[182:185], v[82:85]
	v_mfma_f32_16x16x32_bf16 v[138:141], v[194:197], v[150:153], v[138:141]
	v_mfma_f32_16x16x32_bf16 v[130:133], v[202:205], v[150:153], v[130:133]
	v_mfma_f32_16x16x32_bf16 v[122:125], v[194:197], v[170:173], v[122:125]
	v_mfma_f32_16x16x32_bf16 v[114:117], v[202:205], v[170:173], v[114:117]
	v_mfma_f32_16x16x32_bf16 v[106:109], v[194:197], v[178:181], v[106:109]
	v_mfma_f32_16x16x32_bf16 v[98:101], v[202:205], v[178:181], v[98:101]
	v_mfma_f32_16x16x32_bf16 v[90:93], v[194:197], v[186:189], v[90:93]
	v_mfma_f32_16x16x32_bf16 v[82:85], v[202:205], v[186:189], v[82:85]
	s_mov_b32 m0, s39
	v_lshl_add_u64 v[210:211], s[60:61], 0, v[160:161]
	s_barrier
	ds_read_b128 v[146:149], v226 offset:16384
	ds_read_b128 v[150:153], v226 offset:17408
	ds_read_b128 v[166:169], v226 offset:18432
	ds_read_b128 v[170:173], v226 offset:19456
	ds_read_b128 v[174:177], v226 offset:20480
	ds_read_b128 v[178:181], v226 offset:21504
	ds_read_b128 v[182:185], v226 offset:22528
	ds_read_b128 v[186:189], v226 offset:23552
	global_load_lds_dwordx4 v[210:211], off
	v_lshl_add_u64 v[212:213], s[60:61], 0, v[156:157]
	s_mov_b32 m0, s53
	s_nop 0
	global_load_lds_dwordx4 v[212:213], off
	s_waitcnt vmcnt(10)
	s_barrier
	s_waitcnt lgkmcnt(0)
	s_waitcnt lgkmcnt(0)
	v_mfma_f32_16x16x32_bf16 v[78:81], v[26:29], v[146:149], v[78:81]
	v_mfma_f32_16x16x32_bf16 v[70:73], v[42:45], v[146:149], v[70:73]
	v_mfma_f32_16x16x32_bf16 v[62:65], v[26:29], v[166:169], v[62:65]
	v_mfma_f32_16x16x32_bf16 v[54:57], v[42:45], v[166:169], v[54:57]
	v_mfma_f32_16x16x32_bf16 v[38:41], v[26:29], v[174:177], v[38:41]
	v_mfma_f32_16x16x32_bf16 v[22:25], v[42:45], v[174:177], v[22:25]
	v_mfma_f32_16x16x32_bf16 v[14:17], v[26:29], v[182:185], v[14:17]
	v_mfma_f32_16x16x32_bf16 v[6:9], v[42:45], v[182:185], v[6:9]
	v_mfma_f32_16x16x32_bf16 v[78:81], v[30:33], v[150:153], v[78:81]
	v_mfma_f32_16x16x32_bf16 v[70:73], v[46:49], v[150:153], v[70:73]
	v_mfma_f32_16x16x32_bf16 v[62:65], v[30:33], v[170:173], v[62:65]
	v_mfma_f32_16x16x32_bf16 v[54:57], v[46:49], v[170:173], v[54:57]
	v_mfma_f32_16x16x32_bf16 v[38:41], v[30:33], v[178:181], v[38:41]
	v_mfma_f32_16x16x32_bf16 v[22:25], v[46:49], v[178:181], v[22:25]
	v_mfma_f32_16x16x32_bf16 v[14:17], v[30:33], v[186:189], v[14:17]
	v_mfma_f32_16x16x32_bf16 v[6:9], v[46:49], v[186:189], v[6:9]
	s_barrier
	s_mov_b32 m0, s1
	s_nop 0
	global_load_lds_dwordx4 v158, s[58:59]
	v_lshl_add_u64 v[26:27], s[58:59], 0, v[154:155]
	s_mov_b32 m0, s96
	s_nop 0
	global_load_lds_dwordx4 v[26:27], off
	s_waitcnt vmcnt(10)
	s_barrier
	v_mfma_f32_16x16x32_bf16 v[34:37], v[190:193], v[174:177], v[34:37]
	v_mfma_f32_16x16x32_bf16 v[18:21], v[198:201], v[174:177], v[18:21]
	v_mfma_f32_16x16x32_bf16 v[10:13], v[190:193], v[182:185], v[10:13]
	v_mfma_f32_16x16x32_bf16 v[2:5], v[198:201], v[182:185], v[2:5]
	v_mfma_f32_16x16x32_bf16 v[26:29], v[190:193], v[146:149], v[74:77]
	v_mfma_f32_16x16x32_bf16 v[30:33], v[198:201], v[146:149], v[66:69]
	v_mfma_f32_16x16x32_bf16 v[42:45], v[190:193], v[166:169], v[58:61]
	v_mfma_f32_16x16x32_bf16 v[46:49], v[198:201], v[166:169], v[50:53]
	v_mfma_f32_16x16x32_bf16 v[34:37], v[194:197], v[178:181], v[34:37]
	v_mfma_f32_16x16x32_bf16 v[18:21], v[202:205], v[178:181], v[18:21]
	v_mfma_f32_16x16x32_bf16 v[10:13], v[194:197], v[186:189], v[10:13]
	v_mfma_f32_16x16x32_bf16 v[2:5], v[202:205], v[186:189], v[2:5]
	v_mfma_f32_16x16x32_bf16 v[26:29], v[194:197], v[150:153], v[26:29]
	v_mfma_f32_16x16x32_bf16 v[30:33], v[202:205], v[150:153], v[30:33]
	v_mfma_f32_16x16x32_bf16 v[42:45], v[194:197], v[170:173], v[42:45]
	v_mfma_f32_16x16x32_bf16 v[46:49], v[202:205], v[170:173], v[46:49]
	v_add_u32_e32 v74, s81, v224
	s_barrier
	ds_read_b128 v[50:53], v74
	ds_read_b128 v[58:61], v74 offset:1024
	ds_read_b128 v[66:69], v74 offset:2048
	ds_read_b128 v[74:77], v74 offset:3072
	s_mov_b32 m0, s66
	ds_read_b128 v[146:149], v226 offset:32768
	ds_read_b128 v[150:153], v226 offset:33792
	ds_read_b128 v[166:169], v226 offset:34816
	ds_read_b128 v[170:173], v226 offset:35840
	ds_read_b128 v[174:177], v226 offset:36864
	ds_read_b128 v[178:181], v226 offset:37888
	ds_read_b128 v[182:185], v226 offset:38912
	ds_read_b128 v[186:189], v226 offset:39936
	global_load_lds_dwordx4 v160, s[56:57]
	s_mov_b32 m0, s67
	s_nop 0
	global_load_lds_dwordx4 v156, s[56:57]
	s_waitcnt lgkmcnt(8)
	s_waitcnt vmcnt(10)
	s_barrier
	s_waitcnt lgkmcnt(0)
	s_waitcnt lgkmcnt(0)
	v_mfma_f32_16x16x32_bf16 v[142:145], v[50:53], v[146:149], v[142:145]
	v_mfma_f32_16x16x32_bf16 v[134:137], v[66:69], v[146:149], v[134:137]
	v_mfma_f32_16x16x32_bf16 v[126:129], v[50:53], v[166:169], v[126:129]
	v_mfma_f32_16x16x32_bf16 v[118:121], v[66:69], v[166:169], v[118:121]
	v_mfma_f32_16x16x32_bf16 v[110:113], v[50:53], v[174:177], v[110:113]
	v_mfma_f32_16x16x32_bf16 v[102:105], v[66:69], v[174:177], v[102:105]
	v_mfma_f32_16x16x32_bf16 v[94:97], v[50:53], v[182:185], v[94:97]
	v_mfma_f32_16x16x32_bf16 v[86:89], v[66:69], v[182:185], v[86:89]
	v_mfma_f32_16x16x32_bf16 v[142:145], v[58:61], v[150:153], v[142:145]
	v_mfma_f32_16x16x32_bf16 v[134:137], v[74:77], v[150:153], v[134:137]
	v_mfma_f32_16x16x32_bf16 v[126:129], v[58:61], v[170:173], v[126:129]
	v_mfma_f32_16x16x32_bf16 v[118:121], v[74:77], v[170:173], v[118:121]
	v_mfma_f32_16x16x32_bf16 v[110:113], v[58:61], v[178:181], v[110:113]
	v_mfma_f32_16x16x32_bf16 v[102:105], v[74:77], v[178:181], v[102:105]
	v_mfma_f32_16x16x32_bf16 v[94:97], v[58:61], v[186:189], v[94:97]
	v_mfma_f32_16x16x32_bf16 v[86:89], v[74:77], v[186:189], v[86:89]
	s_barrier
	s_mov_b32 m0, s78
	v_add_u32_e32 v202, s79, v224
	v_lshl_add_u64 v[206:207], v[206:207], 0, s[26:27]
	ds_read_b128 v[190:193], v202
	ds_read_b128 v[194:197], v202 offset:1024
	ds_read_b128 v[198:201], v202 offset:2048
	ds_read_b128 v[202:205], v202 offset:3072
	global_load_lds_dwordx4 v[206:207], off
	v_lshl_add_u64 v[206:207], v[208:209], 0, s[26:27]
	s_mov_b32 m0, s80
	s_nop 0
	global_load_lds_dwordx4 v[206:207], off
	s_waitcnt vmcnt(10)
	s_barrier
	s_waitcnt lgkmcnt(0)
	s_waitcnt lgkmcnt(0)
	v_mfma_f32_16x16x32_bf16 v[138:141], v[190:193], v[146:149], v[138:141]
	v_mfma_f32_16x16x32_bf16 v[130:133], v[198:201], v[146:149], v[130:133]
	v_mfma_f32_16x16x32_bf16 v[122:125], v[190:193], v[166:169], v[122:125]
	v_mfma_f32_16x16x32_bf16 v[114:117], v[198:201], v[166:169], v[114:117]
	v_mfma_f32_16x16x32_bf16 v[106:109], v[190:193], v[174:177], v[106:109]
	v_mfma_f32_16x16x32_bf16 v[98:101], v[198:201], v[174:177], v[98:101]
	v_mfma_f32_16x16x32_bf16 v[90:93], v[190:193], v[182:185], v[90:93]
	v_mfma_f32_16x16x32_bf16 v[82:85], v[198:201], v[182:185], v[82:85]
	v_mfma_f32_16x16x32_bf16 v[138:141], v[194:197], v[150:153], v[138:141]
	v_mfma_f32_16x16x32_bf16 v[130:133], v[202:205], v[150:153], v[130:133]
	v_mfma_f32_16x16x32_bf16 v[122:125], v[194:197], v[170:173], v[122:125]
	v_mfma_f32_16x16x32_bf16 v[114:117], v[202:205], v[170:173], v[114:117]
	v_mfma_f32_16x16x32_bf16 v[106:109], v[194:197], v[178:181], v[106:109]
	v_mfma_f32_16x16x32_bf16 v[98:101], v[202:205], v[178:181], v[98:101]
	v_mfma_f32_16x16x32_bf16 v[90:93], v[194:197], v[186:189], v[90:93]
	v_mfma_f32_16x16x32_bf16 v[82:85], v[202:205], v[186:189], v[82:85]
	s_mov_b32 m0, s6
	v_lshl_add_u64 v[206:207], v[210:211], 0, s[26:27]
	s_barrier
	ds_read_b128 v[146:149], v226 offset:49152
	ds_read_b128 v[150:153], v226 offset:50176
	ds_read_b128 v[166:169], v226 offset:51200
	ds_read_b128 v[170:173], v226 offset:52224
	ds_read_b128 v[174:177], v226 offset:53248
	ds_read_b128 v[178:181], v226 offset:54272
	ds_read_b128 v[182:185], v226 offset:55296
	ds_read_b128 v[186:189], v226 offset:56320
	global_load_lds_dwordx4 v[206:207], off
	v_lshl_add_u64 v[206:207], v[212:213], 0, s[26:27]
	s_mov_b32 m0, s7
	s_nop 0
	global_load_lds_dwordx4 v[206:207], off
	s_waitcnt vmcnt(10)
	s_barrier
	s_waitcnt lgkmcnt(0)
	s_waitcnt lgkmcnt(0)
	v_mfma_f32_16x16x32_bf16 v[78:81], v[50:53], v[146:149], v[78:81]
	v_mfma_f32_16x16x32_bf16 v[70:73], v[66:69], v[146:149], v[70:73]
	v_mfma_f32_16x16x32_bf16 v[62:65], v[50:53], v[166:169], v[62:65]
	v_mfma_f32_16x16x32_bf16 v[54:57], v[66:69], v[166:169], v[54:57]
	v_mfma_f32_16x16x32_bf16 v[38:41], v[50:53], v[174:177], v[38:41]
	v_mfma_f32_16x16x32_bf16 v[22:25], v[66:69], v[174:177], v[22:25]
	v_mfma_f32_16x16x32_bf16 v[14:17], v[50:53], v[182:185], v[14:17]
	v_mfma_f32_16x16x32_bf16 v[6:9], v[66:69], v[182:185], v[6:9]
	v_mfma_f32_16x16x32_bf16 v[78:81], v[58:61], v[150:153], v[78:81]
	v_mfma_f32_16x16x32_bf16 v[70:73], v[74:77], v[150:153], v[70:73]
	v_mfma_f32_16x16x32_bf16 v[62:65], v[58:61], v[170:173], v[62:65]
	v_mfma_f32_16x16x32_bf16 v[54:57], v[74:77], v[170:173], v[54:57]
	v_mfma_f32_16x16x32_bf16 v[38:41], v[58:61], v[178:181], v[38:41]
	v_mfma_f32_16x16x32_bf16 v[22:25], v[74:77], v[178:181], v[22:25]
	v_mfma_f32_16x16x32_bf16 v[14:17], v[58:61], v[186:189], v[14:17]
	v_mfma_f32_16x16x32_bf16 v[6:9], v[74:77], v[186:189], v[6:9]
	s_barrier
	s_mov_b32 m0, vcc_hi
	s_nop 0
	global_load_lds_dwordx4 v158, s[54:55]
	v_lshl_add_u64 v[50:51], s[54:55], 0, v[154:155]
	s_mov_b32 m0, vcc_lo
	s_nop 0
	global_load_lds_dwordx4 v[50:51], off
	s_waitcnt vmcnt(10)
	s_barrier
	v_mfma_f32_16x16x32_bf16 v[26:29], v[190:193], v[146:149], v[26:29]
	v_mfma_f32_16x16x32_bf16 v[74:77], v[194:197], v[150:153], v[26:29]
	v_mfma_f32_16x16x32_bf16 v[26:29], v[198:201], v[146:149], v[30:33]
	v_mfma_f32_16x16x32_bf16 v[66:69], v[202:205], v[150:153], v[26:29]
	v_mfma_f32_16x16x32_bf16 v[26:29], v[190:193], v[166:169], v[42:45]
	v_mfma_f32_16x16x32_bf16 v[58:61], v[194:197], v[170:173], v[26:29]
	v_mfma_f32_16x16x32_bf16 v[26:29], v[198:201], v[166:169], v[46:49]
	v_mfma_f32_16x16x32_bf16 v[50:53], v[202:205], v[170:173], v[26:29]
	v_mfma_f32_16x16x32_bf16 v[26:29], v[190:193], v[174:177], v[34:37]
	v_mfma_f32_16x16x32_bf16 v[18:21], v[198:201], v[174:177], v[18:21]
	v_mfma_f32_16x16x32_bf16 v[10:13], v[190:193], v[182:185], v[10:13]
	v_mfma_f32_16x16x32_bf16 v[2:5], v[198:201], v[182:185], v[2:5]
	v_mfma_f32_16x16x32_bf16 v[34:37], v[194:197], v[178:181], v[26:29]
	v_mfma_f32_16x16x32_bf16 v[18:21], v[202:205], v[178:181], v[18:21]
	v_mfma_f32_16x16x32_bf16 v[10:13], v[194:197], v[186:189], v[10:13]
	v_mfma_f32_16x16x32_bf16 v[2:5], v[202:205], v[186:189], v[2:5]
	s_movk_i32 s56, 0x100
	s_andn2_b64 vcc, exec, s[50:51]
	s_mov_b64 s[54:55], -1
	s_mov_b64 s[50:51], 0
	s_barrier
	s_cbranch_vccz .LBB0_1645
	s_lshl_b32 s0, s82, 7
	s_and_b32 s1, s0, 0x380
	v_mov_b32_e32 v167, v222
	v_mov_b32_e32 v26, v223
	s_or_b32 s1, s1, s11
	s_cmp_lt_u32 s82, 8
	v_lshl_add_u32 v166, v26, 3, s1
	s_mov_b32 s1, 0x32100000
	s_cselect_b32 s1, s1, 0x1a100000
	s_cselect_b32 s49, s9, s17
	s_cselect_b32 s48, s8, s16
	s_add_u32 s50, s18, s1
	s_addc_u32 s51, s19, 0
	s_and_b32 s0, s0, 0xfffffc00
	v_add_u32_e32 v26, s0, v166
	s_load_dwordx2 s[0:1], s[20:21], 0x78
	v_ashrrev_i32_e32 v27, 31, v26
	v_readlane_b32 s56, v254, 5
	v_lshlrev_b64 v[146:147], 2, v[26:27]
	v_readlane_b32 s57, v254, 6
	v_readlane_b32 s58, v254, 7
	v_readlane_b32 s59, v254, 8
	s_waitcnt lgkmcnt(0)
	v_lshl_add_u64 v[26:27], s[0:1], 0, v[146:147]
	v_lshl_add_u64 v[42:43], s[56:57], 0, v[146:147]
	v_lshl_add_u64 v[150:151], s[58:59], 0, v[146:147]
	global_load_dwordx4 v[30:33], v[26:27], off offset:16
	global_load_dwordx4 v[46:49], v[26:27], off
	s_nop 0
	global_load_dwordx4 v[26:29], v[42:43], off offset:16
	s_nop 0
	global_load_dwordx4 v[42:45], v[42:43], off
	s_nop 0
	global_load_dwordx4 v[146:149], v[150:151], off offset:16
	s_nop 0
	global_load_dwordx4 v[150:153], v[150:151], off
	s_lshl_b32 s0, s52, 8
	s_add_i32 s0, s0, s10
	s_waitcnt vmcnt(0)
	v_add_f32_e32 v134, v134, v30
	v_add_f32_e32 v142, v142, v46
	v_add_f32_e32 v138, v138, v42
	v_max_f32_e32 v168, v150, v150
	v_mul_f32_e64 v150, |v150|, s5
	v_exp_f32_e32 v232, v150
	v_mul_f32_e32 v138, 0xbfb8aa3b, v138
	v_exp_f32_e32 v138, v138
	v_mul_f32_e32 v142, 0xbfb8aa3b, v142
	v_add_f32_e32 v172, 1.0, v232
	v_add_f32_e32 v150, -1.0, v172
	v_sub_f32_e32 v169, v150, v172
	v_add_f32_e32 v169, 1.0, v169
	v_sub_f32_e32 v150, v232, v150
	v_add_f32_e32 v174, v150, v169
	v_max_f32_e32 v150, v151, v151
	v_min_f32_e32 v169, 0, v150
	v_mul_f32_e64 v150, |v151|, s5
	v_exp_f32_e32 v233, v150
	v_cvt_f64_f32_e32 v[170:171], v172
	v_frexp_exp_i32_f64_e32 v170, v[170:171]
	v_frexp_mant_f32_e32 v173, v172
	v_add_f32_e32 v171, 1.0, v233
	v_add_f32_e32 v150, -1.0, v171
	v_sub_f32_e32 v151, v150, v171
	v_add_f32_e32 v151, 1.0, v151
	v_sub_f32_e32 v150, v233, v150
	v_add_f32_e32 v175, v150, v151
	v_frexp_mant_f32_e32 v176, v171
	v_cvt_f64_f32_e32 v[150:151], v171
	v_cmp_gt_f32_e32 vcc, s72, v173
	v_frexp_exp_i32_f64_e32 v150, v[150:151]
	v_cmp_gt_f32_e64 s[14:15], s72, v176
	v_subbrev_co_u32_e32 v176, vcc, 0, v170, vcc
	s_nop 0
	v_subbrev_co_u32_e64 v173, s[14:15], 0, v150, s[14:15]
	v_sub_u32_e32 v151, 0, v176
	v_ldexp_f32 v150, v172, v151
	v_sub_u32_e32 v172, 0, v173
	v_ldexp_f32 v170, v174, v151
	v_ldexp_f32 v151, v171, v172
	v_ldexp_f32 v171, v175, v172
	v_pk_add_f32 v[174:175], v[150:151], 1.0 op_sel_hi:[1,0]
	v_pk_add_f32 v[184:185], v[150:151], -1.0 op_sel_hi:[1,0]
	v_pk_add_f32 v[178:179], v[174:175], -1.0 op_sel_hi:[1,0]
	v_pk_add_f32 v[186:187], v[184:185], 1.0 op_sel_hi:[1,0]
	v_pk_add_f32 v[178:179], v[150:151], v[178:179] neg_lo:[0,1] neg_hi:[0,1]
	v_pk_add_f32 v[150:151], v[150:151], v[186:187] neg_lo:[0,1] neg_hi:[0,1]
	v_pk_add_f32 v[178:179], v[170:171], v[178:179]
	v_pk_add_f32 v[150:151], v[170:171], v[150:151]
	v_pk_add_f32 v[180:181], v[174:175], v[178:179]
	v_pk_add_f32 v[170:171], v[184:185], v[150:151]
	v_rcp_f32_e32 v182, v180
	v_rcp_f32_e32 v183, v181
	v_pk_add_f32 v[174:175], v[180:181], v[174:175] neg_lo:[0,1] neg_hi:[0,1]
	v_pk_add_f32 v[184:185], v[170:171], v[184:185] neg_lo:[0,1] neg_hi:[0,1]
	v_pk_add_f32 v[174:175], v[178:179], v[174:175] neg_lo:[0,1] neg_hi:[0,1]
	v_pk_mul_f32 v[186:187], v[170:171], v[182:183]
	v_pk_add_f32 v[150:151], v[150:151], v[184:185] neg_lo:[0,1] neg_hi:[0,1]
	v_pk_mul_f32 v[178:179], v[180:181], v[186:187]
	s_mov_b32 s14, 0x3ecc95a3
	v_pk_fma_f32 v[184:185], v[186:187], v[180:181], v[178:179] neg_lo:[0,0,1] neg_hi:[0,0,1]
	v_cvt_f32_i32_e32 v177, v173
	v_pk_fma_f32 v[184:185], v[186:187], v[174:175], v[184:185]
	v_cvt_f32_i32_e32 v176, v176
	v_pk_add_f32 v[188:189], v[178:179], v[184:185]
	v_add_f32_e32 v138, 1.0, v138
	v_pk_add_f32 v[190:191], v[170:171], v[188:189] neg_lo:[0,1] neg_hi:[0,1]
	v_pk_add_f32 v[178:179], v[188:189], v[178:179] neg_lo:[0,1] neg_hi:[0,1]
	v_pk_add_f32 v[170:171], v[170:171], v[190:191] neg_lo:[0,1] neg_hi:[0,1]
	v_rcp_f32_e32 v249, v138
	v_pk_add_f32 v[170:171], v[170:171], v[188:189] neg_lo:[0,1] neg_hi:[0,1]
	v_add_f32_e32 v138, v143, v47
	v_pk_add_f32 v[150:151], v[150:151], v[170:171]
	v_pk_add_f32 v[170:171], v[178:179], v[184:185] neg_lo:[0,1] neg_hi:[0,1]
	v_mul_f32_e32 v138, 0xbfb8aa3b, v138
	v_pk_add_f32 v[150:151], v[170:171], v[150:151]
	v_exp_f32_e32 v138, v138
	v_pk_add_f32 v[170:171], v[190:191], v[150:151]
	v_exp_f32_e32 v142, v142
	v_pk_mul_f32 v[178:179], v[182:183], v[170:171]
	v_pk_add_f32 v[190:191], v[190:191], v[170:171] neg_lo:[0,1] neg_hi:[0,1]
	v_pk_mul_f32 v[184:185], v[180:181], v[178:179]
	v_pk_add_f32 v[150:151], v[150:151], v[190:191]
	v_pk_fma_f32 v[180:181], v[178:179], v[180:181], v[184:185] neg_lo:[0,0,1] neg_hi:[0,0,1]
	v_pk_add_f32 v[196:197], v[186:187], v[178:179]
	v_pk_fma_f32 v[174:175], v[178:179], v[174:175], v[180:181]
	v_add_f32_e32 v138, 1.0, v138
	v_pk_add_f32 v[180:181], v[184:185], v[174:175]
	v_rcp_f32_e32 v143, v138
	v_pk_add_f32 v[192:193], v[170:171], v[180:181] neg_lo:[0,1] neg_hi:[0,1]
	v_pk_add_f32 v[188:189], v[180:181], v[184:185] neg_lo:[0,1] neg_hi:[0,1]
	v_pk_add_f32 v[194:195], v[170:171], v[192:193] neg_lo:[0,1] neg_hi:[0,1]
	v_mov_b32_e32 v170, v181
	v_mov_b32_e32 v184, v185
	v_mov_b32_e32 v185, v193
	v_pk_add_f32 v[194:195], v[194:195], v[180:181] neg_lo:[0,1] neg_hi:[0,1]
	v_pk_add_f32 v[170:171], v[170:171], v[184:185] neg_lo:[0,1] neg_hi:[0,1]
	v_mov_b32_e32 v180, v175
	v_pk_add_f32 v[170:171], v[170:171], v[180:181] neg_lo:[0,1] neg_hi:[0,1]
	v_pk_add_f32 v[188:189], v[188:189], v[174:175] neg_lo:[0,1] neg_hi:[0,1]
	v_mov_b32_e32 v195, v171
	v_pk_add_f32 v[150:151], v[150:151], v[194:195]
	v_mov_b32_e32 v189, v170
	v_pk_add_f32 v[150:151], v[188:189], v[150:151]
	v_pk_add_f32 v[170:171], v[196:197], v[186:187] neg_lo:[0,1] neg_hi:[0,1]
	v_pk_add_f32 v[150:151], v[192:193], v[150:151]
	v_pk_add_f32 v[170:171], v[178:179], v[170:171] neg_lo:[0,1] neg_hi:[0,1]
	v_pk_mul_f32 v[150:151], v[182:183], v[150:151]
	v_pk_mul_f32 v[182:183], v[176:177], s[34:35] op_sel_hi:[1,0]
	v_pk_add_f32 v[150:151], v[170:171], v[150:151]
	v_pk_fma_f32 v[184:185], v[176:177], s[34:35], v[182:183] op_sel_hi:[1,0,1] neg_lo:[0,0,1] neg_hi:[0,0,1]
	v_pk_add_f32 v[174:175], v[196:197], v[150:151]
	v_pk_fma_f32 v[184:185], v[176:177], s[36:37], v[184:185] op_sel_hi:[1,0,1]
	v_pk_add_f32 v[170:171], v[174:175], v[196:197] neg_lo:[0,1] neg_hi:[0,1]
	v_pk_mul_f32 v[178:179], v[174:175], v[174:175]
	v_pk_add_f32 v[170:171], v[150:151], v[170:171] neg_lo:[0,1] neg_hi:[0,1]
	v_mov_b64_e32 v[150:151], s[14:15]
	v_pk_fma_f32 v[180:181], v[178:179], s[28:29], v[150:151] op_sel_hi:[1,0,0]
	v_ldexp_f32 v172, v174, 1
	v_pk_fma_f32 v[180:181], v[178:179], v[180:181], s[30:31] op_sel_hi:[1,1,0]
	v_ldexp_f32 v173, v175, 1
	v_pk_mul_f32 v[174:175], v[174:175], v[178:179]
	v_ldexp_f32 v170, v170, 1
	v_pk_mul_f32 v[174:175], v[174:175], v[180:181]
	v_ldexp_f32 v171, v171, 1
	v_pk_add_f32 v[178:179], v[172:173], v[174:175]
	v_pk_add_f32 v[176:177], v[182:183], v[184:185]
	v_pk_add_f32 v[172:173], v[178:179], v[172:173] neg_lo:[0,1] neg_hi:[0,1]
	v_pk_add_f32 v[182:183], v[176:177], v[182:183] neg_lo:[0,1] neg_hi:[0,1]
	v_pk_add_f32 v[172:173], v[174:175], v[172:173] neg_lo:[0,1] neg_hi:[0,1]
	v_pk_add_f32 v[182:183], v[184:185], v[182:183] neg_lo:[0,1] neg_hi:[0,1]
	v_pk_add_f32 v[170:171], v[170:171], v[172:173]
	v_add_f32_e32 v138, v139, v43
	v_pk_add_f32 v[190:191], v[178:179], v[170:171]
	v_mul_f32_e32 v138, 0xbfb8aa3b, v138
	v_pk_add_f32 v[172:173], v[190:191], v[178:179] neg_lo:[0,1] neg_hi:[0,1]
	v_exp_f32_e32 v138, v138
	v_pk_add_f32 v[170:171], v[170:171], v[172:173] neg_lo:[0,1] neg_hi:[0,1]
	v_add_f32_e32 v142, 1.0, v142
	v_pk_add_f32 v[184:185], v[182:183], v[170:171]
	v_add_f32_e32 v138, 1.0, v138
	v_pk_add_f32 v[172:173], v[184:185], v[182:183] neg_lo:[0,1] neg_hi:[0,1]
	v_rcp_f32_e32 v250, v138
	v_pk_add_f32 v[188:189], v[170:171], v[172:173] neg_lo:[0,1] neg_hi:[0,1]
	v_max_f32_e32 v170, v152, v152
	v_mul_f32_e64 v152, |v152|, s5
	v_exp_f32_e32 v236, v152
	v_pk_add_f32 v[174:175], v[184:185], v[172:173] neg_lo:[0,1] neg_hi:[0,1]
	v_min_f32_e32 v180, 0, v170
	v_pk_add_f32 v[186:187], v[182:183], v[174:175] neg_lo:[0,1] neg_hi:[0,1]
	v_add_f32_e32 v172, 1.0, v236
	v_add_f32_e32 v152, -1.0, v172
	v_sub_f32_e32 v170, v152, v172
	v_add_f32_e32 v170, 1.0, v170
	v_sub_f32_e32 v152, v236, v152
	v_add_f32_e32 v173, v152, v170
	v_max_f32_e32 v152, v153, v153
	v_min_f32_e32 v181, 0, v152
	v_mul_f32_e64 v152, |v153|, s5
	v_exp_f32_e32 v238, v152
	v_cvt_f64_f32_e32 v[170:171], v172
	v_frexp_exp_i32_f64_e32 v170, v[170:171]
	v_frexp_mant_f32_e32 v174, v172
	v_add_f32_e32 v171, 1.0, v238
	v_add_f32_e32 v152, -1.0, v171
	v_sub_f32_e32 v153, v152, v171
	v_add_f32_e32 v153, 1.0, v153
	v_sub_f32_e32 v152, v238, v152
	v_add_f32_e32 v175, v152, v153
	v_frexp_mant_f32_e32 v178, v171
	v_cvt_f64_f32_e32 v[152:153], v171
	v_cmp_gt_f32_e32 vcc, s72, v174
	v_frexp_exp_i32_f64_e32 v152, v[152:153]
	v_cmp_gt_f32_e64 s[14:15], s72, v178
	v_subbrev_co_u32_e32 v207, vcc, 0, v170, vcc
	s_nop 0
	v_subbrev_co_u32_e64 v206, s[14:15], 0, v152, s[14:15]
	v_sub_u32_e32 v153, 0, v207
	v_ldexp_f32 v152, v172, v153
	v_sub_u32_e32 v172, 0, v206
	v_ldexp_f32 v170, v173, v153
	v_ldexp_f32 v153, v171, v172
	v_ldexp_f32 v171, v175, v172
	v_pk_add_f32 v[172:173], v[152:153], 1.0 op_sel_hi:[1,0]
	v_pk_add_f32 v[192:193], v[152:153], -1.0 op_sel_hi:[1,0]
	v_pk_add_f32 v[174:175], v[172:173], -1.0 op_sel_hi:[1,0]
	v_pk_add_f32 v[194:195], v[192:193], 1.0 op_sel_hi:[1,0]
	v_pk_add_f32 v[174:175], v[152:153], v[174:175] neg_lo:[0,1] neg_hi:[0,1]
	v_pk_add_f32 v[152:153], v[152:153], v[194:195] neg_lo:[0,1] neg_hi:[0,1]
	v_pk_add_f32 v[174:175], v[170:171], v[174:175]
	v_pk_add_f32 v[152:153], v[170:171], v[152:153]
	v_pk_add_f32 v[178:179], v[172:173], v[174:175]
	v_pk_add_f32 v[170:171], v[192:193], v[152:153]
	v_rcp_f32_e32 v182, v178
	v_rcp_f32_e32 v183, v179
	v_pk_add_f32 v[172:173], v[178:179], v[172:173] neg_lo:[0,1] neg_hi:[0,1]
	v_pk_add_f32 v[192:193], v[170:171], v[192:193] neg_lo:[0,1] neg_hi:[0,1]
	v_pk_add_f32 v[172:173], v[174:175], v[172:173] neg_lo:[0,1] neg_hi:[0,1]
	v_pk_mul_f32 v[194:195], v[170:171], v[182:183]
	v_pk_add_f32 v[152:153], v[152:153], v[192:193] neg_lo:[0,1] neg_hi:[0,1]
	v_pk_mul_f32 v[174:175], v[178:179], v[194:195]
	v_add_f32_e32 v138, v144, v48
	v_pk_fma_f32 v[192:193], v[194:195], v[178:179], v[174:175] neg_lo:[0,0,1] neg_hi:[0,0,1]
	v_mul_f32_e32 v138, 0xbfb8aa3b, v138
	v_pk_fma_f32 v[192:193], v[194:195], v[172:173], v[192:193]
	v_exp_f32_e32 v138, v138
	v_pk_add_f32 v[196:197], v[174:175], v[192:193]
	v_rcp_f32_e32 v142, v142
	v_pk_add_f32 v[198:199], v[170:171], v[196:197] neg_lo:[0,1] neg_hi:[0,1]
	v_pk_add_f32 v[174:175], v[196:197], v[174:175] neg_lo:[0,1] neg_hi:[0,1]
	v_pk_add_f32 v[170:171], v[170:171], v[198:199] neg_lo:[0,1] neg_hi:[0,1]
	v_add_f32_e32 v138, 1.0, v138
	v_pk_add_f32 v[170:171], v[170:171], v[196:197] neg_lo:[0,1] neg_hi:[0,1]
	v_min_f32_e32 v168, 0, v168
	v_pk_add_f32 v[152:153], v[152:153], v[170:171]
	v_pk_add_f32 v[170:171], v[174:175], v[192:193] neg_lo:[0,1] neg_hi:[0,1]
	v_add_f32_e32 v130, v130, v26
	v_pk_add_f32 v[152:153], v[170:171], v[152:153]
	v_mul_f32_e32 v130, 0xbfb8aa3b, v130
	v_pk_add_f32 v[170:171], v[198:199], v[152:153]
	v_exp_f32_e32 v130, v130
	v_pk_mul_f32 v[174:175], v[182:183], v[170:171]
	v_pk_add_f32 v[198:199], v[198:199], v[170:171] neg_lo:[0,1] neg_hi:[0,1]
	v_pk_mul_f32 v[192:193], v[178:179], v[174:175]
	v_pk_add_f32 v[152:153], v[152:153], v[198:199]
	v_pk_fma_f32 v[178:179], v[174:175], v[178:179], v[192:193] neg_lo:[0,0,1] neg_hi:[0,0,1]
	v_pk_add_f32 v[204:205], v[194:195], v[174:175]
	v_pk_fma_f32 v[172:173], v[174:175], v[172:173], v[178:179]
	v_add_f32_e32 v130, 1.0, v130
	v_pk_add_f32 v[178:179], v[192:193], v[172:173]
	v_mul_f32_e32 v134, 0xbfb8aa3b, v134
	v_pk_add_f32 v[200:201], v[170:171], v[178:179] neg_lo:[0,1] neg_hi:[0,1]
	v_pk_add_f32 v[196:197], v[178:179], v[192:193] neg_lo:[0,1] neg_hi:[0,1]
	v_pk_add_f32 v[202:203], v[170:171], v[200:201] neg_lo:[0,1] neg_hi:[0,1]
	v_mov_b32_e32 v170, v179
	v_mov_b32_e32 v192, v193
	v_mov_b32_e32 v193, v201
	v_pk_add_f32 v[202:203], v[202:203], v[178:179] neg_lo:[0,1] neg_hi:[0,1]
	v_pk_add_f32 v[170:171], v[170:171], v[192:193] neg_lo:[0,1] neg_hi:[0,1]
	v_mov_b32_e32 v178, v173
	v_pk_add_f32 v[170:171], v[170:171], v[178:179] neg_lo:[0,1] neg_hi:[0,1]
	v_pk_add_f32 v[196:197], v[196:197], v[172:173] neg_lo:[0,1] neg_hi:[0,1]
	v_mov_b32_e32 v203, v171
	v_pk_add_f32 v[152:153], v[152:153], v[202:203]
	v_mov_b32_e32 v197, v170
	v_pk_add_f32 v[152:153], v[196:197], v[152:153]
	v_pk_add_f32 v[170:171], v[204:205], v[194:195] neg_lo:[0,1] neg_hi:[0,1]
	v_pk_add_f32 v[152:153], v[200:201], v[152:153]
	v_pk_add_f32 v[170:171], v[174:175], v[170:171] neg_lo:[0,1] neg_hi:[0,1]
	v_pk_mul_f32 v[152:153], v[182:183], v[152:153]
	v_cvt_f32_i32_e32 v183, v206
	v_pk_add_f32 v[152:153], v[170:171], v[152:153]
	v_cvt_f32_i32_e32 v182, v207
	v_pk_add_f32 v[170:171], v[204:205], v[152:153]
	v_exp_f32_e32 v134, v134
	v_pk_mul_f32 v[174:175], v[170:171], v[170:171]
	v_pk_add_f32 v[172:173], v[170:171], v[204:205] neg_lo:[0,1] neg_hi:[0,1]
	v_pk_fma_f32 v[178:179], v[174:175], s[28:29], v[150:151] op_sel_hi:[1,0,0]
	v_pk_add_f32 v[152:153], v[152:153], v[172:173] neg_lo:[0,1] neg_hi:[0,1]
	v_ldexp_f32 v172, v170, 1
	v_pk_fma_f32 v[178:179], v[174:175], v[178:179], s[30:31] op_sel_hi:[1,1,0]
	v_ldexp_f32 v173, v171, 1
	v_pk_mul_f32 v[170:171], v[170:171], v[174:175]
	v_pk_mul_f32 v[192:193], v[182:183], s[34:35] op_sel_hi:[1,0]
	v_pk_mul_f32 v[170:171], v[170:171], v[178:179]
	v_ldexp_f32 v152, v152, 1
	v_pk_add_f32 v[174:175], v[172:173], v[170:171]
	v_pk_fma_f32 v[194:195], v[182:183], s[34:35], v[192:193] op_sel_hi:[1,0,1] neg_lo:[0,0,1] neg_hi:[0,0,1]
	v_pk_add_f32 v[172:173], v[174:175], v[172:173] neg_lo:[0,1] neg_hi:[0,1]
	v_ldexp_f32 v153, v153, 1
	v_pk_add_f32 v[170:171], v[170:171], v[172:173] neg_lo:[0,1] neg_hi:[0,1]
	v_pk_fma_f32 v[182:183], v[182:183], s[36:37], v[194:195] op_sel_hi:[1,0,1]
	v_pk_add_f32 v[152:153], v[152:153], v[170:171]
	v_pk_add_f32 v[202:203], v[192:193], v[182:183]
	v_pk_add_f32 v[210:211], v[174:175], v[152:153]
	v_pk_add_f32 v[192:193], v[202:203], v[192:193] neg_lo:[0,1] neg_hi:[0,1]
	v_pk_add_f32 v[170:171], v[210:211], v[174:175] neg_lo:[0,1] neg_hi:[0,1]
	v_pk_add_f32 v[182:183], v[182:183], v[192:193] neg_lo:[0,1] neg_hi:[0,1]
	v_pk_add_f32 v[152:153], v[152:153], v[170:171] neg_lo:[0,1] neg_hi:[0,1]
	v_add_f32_e32 v134, 1.0, v134
	v_pk_add_f32 v[204:205], v[182:183], v[152:153]
	v_rcp_f32_e32 v134, v134
	v_pk_add_f32 v[170:171], v[204:205], v[182:183] neg_lo:[0,1] neg_hi:[0,1]
	v_add_f32_e32 v126, v126, v46
	v_pk_add_f32 v[208:209], v[152:153], v[170:171] neg_lo:[0,1] neg_hi:[0,1]
	v_max_f32_e32 v152, v146, v146
	v_mul_f32_e64 v146, |v146|, s5
	v_exp_f32_e32 v235, v146
	v_pk_add_f32 v[172:173], v[204:205], v[170:171] neg_lo:[0,1] neg_hi:[0,1]
	v_min_f32_e32 v178, 0, v152
	v_pk_add_f32 v[206:207], v[182:183], v[172:173] neg_lo:[0,1] neg_hi:[0,1]
	v_add_f32_e32 v170, 1.0, v235
	v_add_f32_e32 v146, -1.0, v170
	v_sub_f32_e32 v152, v146, v170
	v_add_f32_e32 v152, 1.0, v152
	v_sub_f32_e32 v146, v235, v146
	v_add_f32_e32 v171, v146, v152
	v_max_f32_e32 v146, v147, v147
	v_min_f32_e32 v179, 0, v146
	v_mul_f32_e64 v146, |v147|, s5
	v_exp_f32_e32 v237, v146
	v_cvt_f64_f32_e32 v[152:153], v170
	v_frexp_exp_i32_f64_e32 v152, v[152:153]
	v_frexp_mant_f32_e32 v172, v170
	v_add_f32_e32 v153, 1.0, v237
	v_add_f32_e32 v146, -1.0, v153
	v_sub_f32_e32 v147, v146, v153
	v_add_f32_e32 v147, 1.0, v147
	v_sub_f32_e32 v146, v237, v146
	v_add_f32_e32 v173, v146, v147
	v_frexp_mant_f32_e32 v174, v153
	v_cvt_f64_f32_e32 v[146:147], v153
	v_cmp_gt_f32_e32 vcc, s72, v172
	v_frexp_exp_i32_f64_e32 v146, v[146:147]
	v_cmp_gt_f32_e64 s[14:15], s72, v174
	v_subbrev_co_u32_e32 v217, vcc, 0, v152, vcc
	s_nop 0
	v_subbrev_co_u32_e64 v216, s[14:15], 0, v146, s[14:15]
	v_sub_u32_e32 v147, 0, v217
	v_ldexp_f32 v146, v170, v147
	v_sub_u32_e32 v170, 0, v216
	v_ldexp_f32 v152, v171, v147
	v_ldexp_f32 v147, v153, v170
	v_ldexp_f32 v153, v173, v170
	v_pk_add_f32 v[170:171], v[146:147], 1.0 op_sel_hi:[1,0]
	v_pk_add_f32 v[192:193], v[146:147], -1.0 op_sel_hi:[1,0]
	v_pk_add_f32 v[172:173], v[170:171], -1.0 op_sel_hi:[1,0]
	v_pk_add_f32 v[194:195], v[192:193], 1.0 op_sel_hi:[1,0]
	v_pk_add_f32 v[172:173], v[146:147], v[172:173] neg_lo:[0,1] neg_hi:[0,1]
	v_pk_add_f32 v[146:147], v[146:147], v[194:195] neg_lo:[0,1] neg_hi:[0,1]
	v_pk_add_f32 v[172:173], v[152:153], v[172:173]
	v_pk_add_f32 v[146:147], v[152:153], v[146:147]
	v_pk_add_f32 v[174:175], v[170:171], v[172:173]
	v_pk_add_f32 v[152:153], v[192:193], v[146:147]
	v_rcp_f32_e32 v182, v174
	v_rcp_f32_e32 v183, v175
	v_pk_add_f32 v[170:171], v[174:175], v[170:171] neg_lo:[0,1] neg_hi:[0,1]
	v_pk_add_f32 v[192:193], v[152:153], v[192:193] neg_lo:[0,1] neg_hi:[0,1]
	v_pk_add_f32 v[170:171], v[172:173], v[170:171] neg_lo:[0,1] neg_hi:[0,1]
	v_pk_mul_f32 v[194:195], v[152:153], v[182:183]
	v_pk_add_f32 v[146:147], v[146:147], v[192:193] neg_lo:[0,1] neg_hi:[0,1]
	v_pk_mul_f32 v[172:173], v[174:175], v[194:195]
	v_mul_f32_e32 v126, 0xbfb8aa3b, v126
	v_pk_fma_f32 v[192:193], v[194:195], v[174:175], v[172:173] neg_lo:[0,0,1] neg_hi:[0,0,1]
	v_exp_f32_e32 v126, v126
	v_pk_fma_f32 v[192:193], v[194:195], v[170:171], v[192:193]
	v_add_f32_e32 v122, v122, v42
	v_pk_add_f32 v[196:197], v[172:173], v[192:193]
	v_add_f32_e32 v126, 1.0, v126
	v_pk_add_f32 v[198:199], v[152:153], v[196:197] neg_lo:[0,1] neg_hi:[0,1]
	v_pk_add_f32 v[172:173], v[196:197], v[172:173] neg_lo:[0,1] neg_hi:[0,1]
	v_pk_add_f32 v[152:153], v[152:153], v[198:199] neg_lo:[0,1] neg_hi:[0,1]
	v_rcp_f32_e32 v126, v126
	v_pk_add_f32 v[152:153], v[152:153], v[196:197] neg_lo:[0,1] neg_hi:[0,1]
	v_mul_f32_e32 v122, 0xbfb8aa3b, v122
	v_pk_add_f32 v[146:147], v[146:147], v[152:153]
	v_pk_add_f32 v[152:153], v[172:173], v[192:193] neg_lo:[0,1] neg_hi:[0,1]
	v_exp_f32_e32 v122, v122
	v_pk_add_f32 v[146:147], v[152:153], v[146:147]
	v_add_f32_e32 v123, v123, v43
	v_pk_add_f32 v[152:153], v[198:199], v[146:147]
	v_add_f32_e32 v122, 1.0, v122
	v_pk_mul_f32 v[172:173], v[182:183], v[152:153]
	v_pk_add_f32 v[198:199], v[198:199], v[152:153] neg_lo:[0,1] neg_hi:[0,1]
	v_pk_mul_f32 v[192:193], v[174:175], v[172:173]
	v_pk_add_f32 v[146:147], v[146:147], v[198:199]
	v_pk_fma_f32 v[174:175], v[172:173], v[174:175], v[192:193] neg_lo:[0,0,1] neg_hi:[0,0,1]
	v_pk_add_f32 v[214:215], v[194:195], v[172:173]
	v_pk_fma_f32 v[170:171], v[172:173], v[170:171], v[174:175]
	v_rcp_f32_e32 v122, v122
	v_pk_add_f32 v[174:175], v[192:193], v[170:171]
	v_mul_f32_e32 v123, 0xbfb8aa3b, v123
	v_pk_add_f32 v[200:201], v[152:153], v[174:175] neg_lo:[0,1] neg_hi:[0,1]
	v_pk_add_f32 v[196:197], v[174:175], v[192:193] neg_lo:[0,1] neg_hi:[0,1]
	v_pk_add_f32 v[212:213], v[152:153], v[200:201] neg_lo:[0,1] neg_hi:[0,1]
	v_mov_b32_e32 v152, v175
	v_mov_b32_e32 v192, v193
	v_mov_b32_e32 v193, v201
	v_pk_add_f32 v[212:213], v[212:213], v[174:175] neg_lo:[0,1] neg_hi:[0,1]
	v_pk_add_f32 v[152:153], v[152:153], v[192:193] neg_lo:[0,1] neg_hi:[0,1]
	v_mov_b32_e32 v174, v171
	v_pk_add_f32 v[152:153], v[152:153], v[174:175] neg_lo:[0,1] neg_hi:[0,1]
	v_pk_add_f32 v[196:197], v[196:197], v[170:171] neg_lo:[0,1] neg_hi:[0,1]
	v_mov_b32_e32 v213, v153
	v_pk_add_f32 v[146:147], v[146:147], v[212:213]
	v_mov_b32_e32 v197, v152
	v_pk_add_f32 v[146:147], v[196:197], v[146:147]
	v_pk_add_f32 v[152:153], v[214:215], v[194:195] neg_lo:[0,1] neg_hi:[0,1]
	v_pk_add_f32 v[146:147], v[200:201], v[146:147]
	v_pk_add_f32 v[152:153], v[172:173], v[152:153] neg_lo:[0,1] neg_hi:[0,1]
	v_pk_mul_f32 v[146:147], v[182:183], v[146:147]
	v_cvt_f32_i32_e32 v183, v216
	v_pk_add_f32 v[146:147], v[152:153], v[146:147]
	v_cvt_f32_i32_e32 v182, v217
	v_pk_add_f32 v[152:153], v[214:215], v[146:147]
	v_exp_f32_e32 v123, v123
	v_pk_mul_f32 v[172:173], v[152:153], v[152:153]
	v_pk_add_f32 v[170:171], v[152:153], v[214:215] neg_lo:[0,1] neg_hi:[0,1]
	v_pk_fma_f32 v[174:175], v[172:173], s[28:29], v[150:151] op_sel_hi:[1,0,0]
	v_pk_add_f32 v[146:147], v[146:147], v[170:171] neg_lo:[0,1] neg_hi:[0,1]
	v_ldexp_f32 v170, v152, 1
	v_pk_fma_f32 v[174:175], v[172:173], v[174:175], s[30:31] op_sel_hi:[1,1,0]
	v_ldexp_f32 v171, v153, 1
	v_pk_mul_f32 v[152:153], v[152:153], v[172:173]
	v_pk_mul_f32 v[194:195], v[182:183], s[34:35] op_sel_hi:[1,0]
	v_pk_mul_f32 v[152:153], v[152:153], v[174:175]
	v_ldexp_f32 v146, v146, 1
	v_pk_add_f32 v[172:173], v[170:171], v[152:153]
	v_pk_fma_f32 v[192:193], v[182:183], s[34:35], v[194:195] op_sel_hi:[1,0,1] neg_lo:[0,0,1] neg_hi:[0,0,1]
	v_pk_add_f32 v[170:171], v[172:173], v[170:171] neg_lo:[0,1] neg_hi:[0,1]
	v_ldexp_f32 v147, v147, 1
	v_pk_add_f32 v[152:153], v[152:153], v[170:171] neg_lo:[0,1] neg_hi:[0,1]
	v_pk_fma_f32 v[182:183], v[182:183], s[36:37], v[192:193] op_sel_hi:[1,0,1]
	v_pk_add_f32 v[146:147], v[146:147], v[152:153]
	v_pk_add_f32 v[192:193], v[194:195], v[182:183]
	v_pk_add_f32 v[200:201], v[172:173], v[146:147]
	v_pk_add_f32 v[194:195], v[192:193], v[194:195] neg_lo:[0,1] neg_hi:[0,1]
	v_pk_add_f32 v[152:153], v[200:201], v[172:173] neg_lo:[0,1] neg_hi:[0,1]
	v_pk_add_f32 v[182:183], v[182:183], v[194:195] neg_lo:[0,1] neg_hi:[0,1]
	v_pk_add_f32 v[146:147], v[146:147], v[152:153] neg_lo:[0,1] neg_hi:[0,1]
	v_add_f32_e32 v123, 1.0, v123
	v_pk_add_f32 v[194:195], v[182:183], v[146:147]
	v_rcp_f32_e32 v123, v123
	v_pk_add_f32 v[152:153], v[194:195], v[182:183] neg_lo:[0,1] neg_hi:[0,1]
	v_add_f32_e32 v124, v124, v44
	v_pk_add_f32 v[170:171], v[194:195], v[152:153] neg_lo:[0,1] neg_hi:[0,1]
	v_pk_add_f32 v[198:199], v[146:147], v[152:153] neg_lo:[0,1] neg_hi:[0,1]
	v_max_f32_e32 v146, v148, v148
	v_pk_add_f32 v[196:197], v[182:183], v[170:171] neg_lo:[0,1] neg_hi:[0,1]
	v_min_f32_e32 v182, 0, v146
	v_mul_f32_e64 v146, |v148|, s5
	v_exp_f32_e32 v239, v146
	v_mul_f32_e32 v124, 0xbfb8aa3b, v124
	v_exp_f32_e32 v124, v124
	v_add_f32_e32 v118, v118, v30
	v_add_f32_e32 v148, 1.0, v239
	v_add_f32_e32 v146, -1.0, v148
	v_sub_f32_e32 v147, v146, v148
	v_add_f32_e32 v147, 1.0, v147
	v_sub_f32_e32 v146, v239, v146
	v_add_f32_e32 v152, v146, v147
	v_cvt_f64_f32_e32 v[146:147], v148
	v_frexp_exp_i32_f64_e32 v170, v[146:147]
	v_max_f32_e32 v146, v149, v149
	v_min_f32_e32 v183, 0, v146
	v_mul_f32_e64 v146, |v149|, s5
	v_exp_f32_e32 v240, v146
	v_frexp_mant_f32_e32 v153, v148
	v_cmp_gt_f32_e32 vcc, s72, v153
	v_add_f32_e32 v124, 1.0, v124
	v_add_f32_e32 v149, 1.0, v240
	v_add_f32_e32 v146, -1.0, v149
	v_sub_f32_e32 v147, v146, v149
	v_add_f32_e32 v147, 1.0, v147
	v_sub_f32_e32 v146, v240, v146
	v_add_f32_e32 v171, v146, v147
	v_frexp_mant_f32_e32 v172, v149
	v_cvt_f64_f32_e32 v[146:147], v149
	v_frexp_exp_i32_f64_e32 v146, v[146:147]
	v_cmp_gt_f32_e64 s[14:15], s72, v172
	v_subbrev_co_u32_e32 v241, vcc, 0, v170, vcc
	s_nop 0
	v_subbrev_co_u32_e64 v234, s[14:15], 0, v146, s[14:15]
	v_sub_u32_e32 v147, 0, v241
	v_ldexp_f32 v146, v148, v147
	v_ldexp_f32 v148, v152, v147
	v_sub_u32_e32 v152, 0, v234
	v_ldexp_f32 v147, v149, v152
	v_ldexp_f32 v149, v171, v152
	v_pk_add_f32 v[152:153], v[146:147], 1.0 op_sel_hi:[1,0]
	v_pk_add_f32 v[212:213], v[146:147], -1.0 op_sel_hi:[1,0]
	v_pk_add_f32 v[170:171], v[152:153], -1.0 op_sel_hi:[1,0]
	v_pk_add_f32 v[214:215], v[212:213], 1.0 op_sel_hi:[1,0]
	v_pk_add_f32 v[170:171], v[146:147], v[170:171] neg_lo:[0,1] neg_hi:[0,1]
	v_pk_add_f32 v[146:147], v[146:147], v[214:215] neg_lo:[0,1] neg_hi:[0,1]
	v_pk_add_f32 v[170:171], v[148:149], v[170:171]
	v_pk_add_f32 v[146:147], v[148:149], v[146:147]
	v_pk_add_f32 v[172:173], v[152:153], v[170:171]
	v_pk_add_f32 v[148:149], v[212:213], v[146:147]
	v_rcp_f32_e32 v174, v172
	v_rcp_f32_e32 v175, v173
	v_pk_add_f32 v[152:153], v[172:173], v[152:153] neg_lo:[0,1] neg_hi:[0,1]
	v_pk_add_f32 v[212:213], v[148:149], v[212:213] neg_lo:[0,1] neg_hi:[0,1]
	v_pk_add_f32 v[152:153], v[170:171], v[152:153] neg_lo:[0,1] neg_hi:[0,1]
	v_pk_mul_f32 v[214:215], v[148:149], v[174:175]
	v_pk_add_f32 v[146:147], v[146:147], v[212:213] neg_lo:[0,1] neg_hi:[0,1]
	v_pk_mul_f32 v[170:171], v[172:173], v[214:215]
	v_cmp_lt_f32_e64 s[14:15], |v233|, s77
	v_pk_fma_f32 v[212:213], v[214:215], v[172:173], v[170:171] neg_lo:[0,0,1] neg_hi:[0,0,1]
	v_rcp_f32_e32 v124, v124
	v_pk_fma_f32 v[212:213], v[214:215], v[152:153], v[212:213]
	v_add_f32_e32 v125, v125, v45
	v_pk_add_f32 v[216:217], v[170:171], v[212:213]
	v_mul_f32_e32 v118, 0xbfb8aa3b, v118
	v_pk_add_f32 v[218:219], v[148:149], v[216:217] neg_lo:[0,1] neg_hi:[0,1]
	v_pk_add_f32 v[170:171], v[216:217], v[170:171] neg_lo:[0,1] neg_hi:[0,1]
	v_pk_add_f32 v[148:149], v[148:149], v[218:219] neg_lo:[0,1] neg_hi:[0,1]
	v_mul_f32_e32 v125, 0xbfb8aa3b, v125
	v_pk_add_f32 v[148:149], v[148:149], v[216:217] neg_lo:[0,1] neg_hi:[0,1]
	v_exp_f32_e32 v118, v118
	v_pk_add_f32 v[146:147], v[146:147], v[148:149]
	v_pk_add_f32 v[148:149], v[170:171], v[212:213] neg_lo:[0,1] neg_hi:[0,1]
	v_exp_f32_e32 v125, v125
	v_pk_add_f32 v[146:147], v[148:149], v[146:147]
	v_add_f32_e32 v118, 1.0, v118
	v_pk_add_f32 v[148:149], v[218:219], v[146:147]
	v_add_f32_e32 v125, 1.0, v125
	v_pk_mul_f32 v[170:171], v[174:175], v[148:149]
	v_pk_add_f32 v[218:219], v[218:219], v[148:149] neg_lo:[0,1] neg_hi:[0,1]
	v_pk_mul_f32 v[212:213], v[172:173], v[170:171]
	v_pk_add_f32 v[146:147], v[146:147], v[218:219]
	v_pk_fma_f32 v[172:173], v[170:171], v[172:173], v[212:213] neg_lo:[0,0,1] neg_hi:[0,0,1]
	v_pk_add_f32 v[244:245], v[214:215], v[170:171]
	v_pk_fma_f32 v[152:153], v[170:171], v[152:153], v[172:173]
	v_rcp_f32_e32 v118, v118
	v_pk_add_f32 v[172:173], v[212:213], v[152:153]
	v_rcp_f32_e32 v125, v125
	v_pk_add_f32 v[220:221], v[148:149], v[172:173] neg_lo:[0,1] neg_hi:[0,1]
	v_pk_add_f32 v[216:217], v[172:173], v[212:213] neg_lo:[0,1] neg_hi:[0,1]
	v_pk_add_f32 v[242:243], v[148:149], v[220:221] neg_lo:[0,1] neg_hi:[0,1]
	v_mov_b32_e32 v148, v173
	v_mov_b32_e32 v212, v213
	v_mov_b32_e32 v213, v221
	v_pk_add_f32 v[242:243], v[242:243], v[172:173] neg_lo:[0,1] neg_hi:[0,1]
	v_pk_add_f32 v[148:149], v[148:149], v[212:213] neg_lo:[0,1] neg_hi:[0,1]
	v_mov_b32_e32 v172, v153
	v_pk_add_f32 v[148:149], v[148:149], v[172:173] neg_lo:[0,1] neg_hi:[0,1]
	v_pk_add_f32 v[216:217], v[216:217], v[152:153] neg_lo:[0,1] neg_hi:[0,1]
	v_mov_b32_e32 v243, v149
	v_pk_add_f32 v[146:147], v[146:147], v[242:243]
	v_mov_b32_e32 v217, v148
	v_pk_add_f32 v[146:147], v[216:217], v[146:147]
	v_pk_add_f32 v[148:149], v[244:245], v[214:215] neg_lo:[0,1] neg_hi:[0,1]
	v_pk_add_f32 v[146:147], v[220:221], v[146:147]
	v_pk_add_f32 v[148:149], v[170:171], v[148:149] neg_lo:[0,1] neg_hi:[0,1]
	v_pk_mul_f32 v[146:147], v[174:175], v[146:147]
	v_cvt_f32_i32_e32 v173, v234
	v_pk_add_f32 v[146:147], v[148:149], v[146:147]
	v_cvt_f32_i32_e32 v172, v241
	v_pk_add_f32 v[148:149], v[244:245], v[146:147]
	v_add_u32_e32 v234, s0, v167
	v_pk_mul_f32 v[170:171], v[148:149], v[148:149]
	v_pk_add_f32 v[152:153], v[148:149], v[244:245] neg_lo:[0,1] neg_hi:[0,1]
	v_pk_fma_f32 v[150:151], v[170:171], s[28:29], v[150:151] op_sel_hi:[1,0,0]
	v_pk_add_f32 v[146:147], v[146:147], v[152:153] neg_lo:[0,1] neg_hi:[0,1]
	v_ldexp_f32 v152, v148, 1
	v_pk_fma_f32 v[150:151], v[170:171], v[150:151], s[30:31] op_sel_hi:[1,1,0]
	v_ldexp_f32 v153, v149, 1
	v_pk_mul_f32 v[148:149], v[148:149], v[170:171]
	v_pk_mul_f32 v[174:175], v[172:173], s[34:35] op_sel_hi:[1,0]
	v_pk_mul_f32 v[148:149], v[148:149], v[150:151]
	v_ldexp_f32 v146, v146, 1
	v_pk_add_f32 v[150:151], v[152:153], v[148:149]
	v_pk_fma_f32 v[212:213], v[172:173], s[34:35], v[174:175] op_sel_hi:[1,0,1] neg_lo:[0,0,1] neg_hi:[0,0,1]
	v_pk_add_f32 v[152:153], v[150:151], v[152:153] neg_lo:[0,1] neg_hi:[0,1]
	v_ldexp_f32 v147, v147, 1
	v_pk_add_f32 v[148:149], v[148:149], v[152:153] neg_lo:[0,1] neg_hi:[0,1]
	v_pk_fma_f32 v[172:173], v[172:173], s[36:37], v[212:213] op_sel_hi:[1,0,1]
	v_pk_add_f32 v[146:147], v[146:147], v[148:149]
	v_pk_add_f32 v[212:213], v[174:175], v[172:173]
	v_pk_add_f32 v[220:221], v[150:151], v[146:147]
	v_pk_add_f32 v[174:175], v[212:213], v[174:175] neg_lo:[0,1] neg_hi:[0,1]
	v_pk_add_f32 v[148:149], v[220:221], v[150:151] neg_lo:[0,1] neg_hi:[0,1]
	v_pk_add_f32 v[172:173], v[172:173], v[174:175] neg_lo:[0,1] neg_hi:[0,1]
	v_pk_add_f32 v[146:147], v[146:147], v[148:149] neg_lo:[0,1] neg_hi:[0,1]
	v_ashrrev_i32_e32 v167, 31, v166
	v_pk_add_f32 v[214:215], v[172:173], v[146:147]
	v_mov_b32_e32 v242, v190
	v_pk_add_f32 v[148:149], v[214:215], v[172:173] neg_lo:[0,1] neg_hi:[0,1]
	v_mov_b32_e32 v243, v176
	v_pk_add_f32 v[218:219], v[146:147], v[148:149] neg_lo:[0,1] neg_hi:[0,1]
	v_mov_b32_e32 v146, v234
	v_pk_add_f32 v[150:151], v[214:215], v[148:149] neg_lo:[0,1] neg_hi:[0,1]
	v_ashrrev_i32_e32 v147, 31, v146
	v_lshlrev_b64 v[146:147], 10, v[146:147]
	v_lshl_add_u64 v[146:147], v[146:147], 0, v[166:167]
	v_lshlrev_b64 v[148:149], 1, v[146:147]
	v_lshl_add_u64 v[174:175], s[24:25], 0, v[148:149]
	v_pk_add_f32 v[216:217], v[172:173], v[150:151] neg_lo:[0,1] neg_hi:[0,1]
	global_load_dwordx4 v[150:153], v[174:175], off
	v_lshl_add_u64 v[170:171], s[50:51], 0, v[146:147]
	v_add_co_u32_e32 v146, vcc, s84, v174
	v_lshl_add_u64 v[172:173], s[48:49], 0, v[148:149]
	s_nop 0
	v_addc_co_u32_e32 v147, vcc, 0, v175, vcc
	global_load_dwordx4 v[146:149], v[146:147], off
	v_cmp_neq_f32_e32 vcc, s73, v232
	v_add_f32_e32 v114, v114, v26
	v_add_f32_e32 v119, v119, v31
	v_mul_f32_e32 v114, 0xbfb8aa3b, v114
	v_mul_f32_e32 v119, 0xbfb8aa3b, v119
	v_exp_f32_e32 v114, v114
	v_exp_f32_e32 v119, v119
	v_add_f32_e32 v120, v120, v32
	v_add_f32_e32 v115, v115, v27
	v_add_f32_e32 v114, 1.0, v114
	v_add_f32_e32 v119, 1.0, v119
	v_rcp_f32_e32 v114, v114
	v_rcp_f32_e32 v119, v119
	v_mul_f32_e32 v120, 0xbfb8aa3b, v120
	v_mul_f32_e32 v115, 0xbfb8aa3b, v115
	v_exp_f32_e32 v120, v120
	v_exp_f32_e32 v115, v115
	v_add_f32_e32 v121, v121, v33
	v_add_f32_e32 v116, v116, v28
	v_add_f32_e32 v120, 1.0, v120
	v_add_f32_e32 v115, 1.0, v115
	v_rcp_f32_e32 v120, v120
	v_rcp_f32_e32 v115, v115
	v_mul_f32_e32 v121, 0xbfb8aa3b, v121
	v_mul_f32_e32 v116, 0xbfb8aa3b, v116
	v_exp_f32_e32 v121, v121
	v_exp_f32_e32 v116, v116
	v_add_f32_e32 v117, v117, v29
	v_mul_f32_e32 v117, 0xbfb8aa3b, v117
	v_add_f32_e32 v121, 1.0, v121
	v_add_f32_e32 v116, 1.0, v116
	v_rcp_f32_e32 v121, v121
	v_rcp_f32_e32 v116, v116
	v_exp_f32_e32 v117, v117
	s_waitcnt vmcnt(0) lgkmcnt(0)
	v_lshlrev_b32_e32 v241, 16, v150
	v_and_b32_e32 v246, 0xffff0000, v150
	v_rcp_f32_e32 v150, v138
	v_add_f32_e32 v138, v140, v44
	v_mul_f32_e32 v138, 0xbfb8aa3b, v138
	v_exp_f32_e32 v138, v138
	v_lshlrev_b32_e32 v247, 16, v151
	v_and_b32_e32 v248, 0xffff0000, v151
	v_add_f32_e32 v117, 1.0, v117
	v_add_f32_e32 v138, 1.0, v138
	v_rcp_f32_e32 v251, v138
	v_add_f32_e32 v138, v145, v49
	v_mul_f32_e32 v138, 0xbfb8aa3b, v138
	v_exp_f32_e32 v138, v138
	v_rcp_f32_e32 v117, v117
	v_add_f32_e32 v138, 1.0, v138
	v_rcp_f32_e32 v151, v138
	v_add_f32_e32 v138, v141, v45
	v_mul_f32_e32 v138, 0xbfb8aa3b, v138
	v_exp_f32_e32 v138, v138
	s_nop 0
	v_add_f32_e32 v138, 1.0, v138
	v_rcp_f32_e32 v252, v138
	v_pk_add_f32 v[138:139], v[176:177], v[190:191]
	s_nop 0
	v_pk_add_f32 v[140:141], v[138:139], v[176:177] neg_lo:[0,1] neg_hi:[0,1]
	v_mov_b32_e32 v176, v191
	v_pk_add_f32 v[144:145], v[138:139], v[140:141] neg_lo:[0,1] neg_hi:[0,1]
	v_mov_b32_e32 v244, v140
	v_mov_b32_e32 v245, v144
	v_mov_b32_e32 v144, v141
	v_pk_add_f32 v[242:243], v[242:243], v[244:245] neg_lo:[0,1] neg_hi:[0,1]
	v_pk_add_f32 v[140:141], v[176:177], v[144:145] neg_lo:[0,1] neg_hi:[0,1]
	v_pk_add_f32 v[242:243], v[242:243], v[242:243] op_sel:[0,1] op_sel_hi:[1,0]
	v_pk_add_f32 v[140:141], v[140:141], v[140:141] op_sel_hi:[0,1]
	v_mov_b32_e32 v243, v185
	v_mov_b32_e32 v185, v141
	v_pk_add_f32 v[140:141], v[242:243], v[184:185]
	v_pk_add_f32 v[176:177], v[188:189], v[186:187]
	v_pk_add_f32 v[144:145], v[138:139], v[140:141]
	s_nop 0
	v_pk_add_f32 v[138:139], v[144:145], v[138:139] neg_lo:[0,1] neg_hi:[0,1]
	s_nop 0
	v_pk_add_f32 v[138:139], v[140:141], v[138:139] neg_lo:[0,1] neg_hi:[0,1]
	s_nop 0
	v_pk_add_f32 v[138:139], v[176:177], v[138:139]
	v_mov_b32_e32 v176, v210
	v_pk_add_f32 v[138:139], v[144:145], v[138:139]
	v_mov_b32_e32 v177, v202
	v_cndmask_b32_e32 v138, v228, v138, vcc
	v_cmp_neq_f32_e32 vcc, s73, v233
	s_nop 1
	v_cndmask_b32_e32 v139, v228, v139, vcc
	v_cmp_ngt_f32_e32 vcc, -1.0, v233
	s_nop 1
	v_cndmask_b32_e32 v139, v229, v139, vcc
	v_cmp_ngt_f32_e32 vcc, -1.0, v232
	s_nop 1
	v_cndmask_b32_e32 v138, v229, v138, vcc
	v_cmp_neq_f32_e32 vcc, -1.0, v232
	s_nop 1
	v_cndmask_b32_e32 v138, v230, v138, vcc
	v_cmp_neq_f32_e32 vcc, -1.0, v233
	s_nop 1
	v_cndmask_b32_e32 v139, v230, v139, vcc
	v_cmp_lt_f32_e64 vcc, |v232|, s77
	v_cndmask_b32_e64 v139, v139, v233, s[14:15]
	v_cmp_lt_f32_e64 s[14:15], |v238|, s77
	v_cndmask_b32_e32 v138, v138, v232, vcc
	v_pk_add_f32 v[138:139], v[168:169], v[138:139] neg_lo:[0,1] neg_hi:[0,1]
	v_cmp_neq_f32_e32 vcc, s73, v236
	v_pk_mul_f32 v[144:145], v[138:139], s[38:39] op_sel_hi:[1,0]
	s_nop 0
	v_pk_mul_f32 v[138:139], v[142:143], v[144:145]
	v_mul_f32_e32 v126, v126, v144
	v_add_f32_e32 v140, v138, v138
	v_mul_f32_e32 v140, 0x3fb8aa3b, v140
	v_exp_f32_e32 v140, v140
	v_cvt_pk_bf16_f32 v138, v138, v139
	v_sub_f32_e32 v140, 1.0, v140
	v_max_f32_e32 v140, 0, v140
	v_sqrt_f32_e32 v140, v140
	s_nop 0
	v_mul_f32_e32 v140, v249, v140
	v_mul_f32_e32 v186, v140, v241
	v_add_f32_e32 v140, v139, v139
	v_mul_f32_e32 v140, 0x3fb8aa3b, v140
	v_exp_f32_e32 v140, v140
	s_nop 0
	v_sub_f32_e32 v140, 1.0, v140
	v_max_f32_e32 v140, 0, v140
	v_sqrt_f32_e32 v140, v140
	s_nop 0
	v_mul_f32_e32 v140, v250, v140
	v_mul_f32_e32 v187, v140, v246
	v_pk_add_f32 v[140:141], v[202:203], v[210:211]
	s_nop 0
	v_pk_add_f32 v[142:143], v[140:141], v[202:203] neg_lo:[0,1] neg_hi:[0,1]
	v_mov_b32_e32 v202, v211
	v_pk_add_f32 v[168:169], v[140:141], v[142:143] neg_lo:[0,1] neg_hi:[0,1]
	v_mov_b32_e32 v184, v142
	v_mov_b32_e32 v185, v168
	v_mov_b32_e32 v168, v143
	v_pk_add_f32 v[176:177], v[176:177], v[184:185] neg_lo:[0,1] neg_hi:[0,1]
	v_pk_add_f32 v[142:143], v[202:203], v[168:169] neg_lo:[0,1] neg_hi:[0,1]
	v_pk_add_f32 v[176:177], v[176:177], v[176:177] op_sel:[0,1] op_sel_hi:[1,0]
	v_pk_add_f32 v[142:143], v[142:143], v[142:143] op_sel_hi:[0,1]
	v_mov_b32_e32 v177, v205
	v_mov_b32_e32 v205, v143
	v_pk_add_f32 v[142:143], v[176:177], v[204:205]
	v_pk_add_f32 v[176:177], v[208:209], v[206:207]
	v_pk_add_f32 v[168:169], v[140:141], v[142:143]
	s_nop 0
	v_pk_add_f32 v[140:141], v[168:169], v[140:141] neg_lo:[0,1] neg_hi:[0,1]
	s_nop 0
	v_pk_add_f32 v[140:141], v[142:143], v[140:141] neg_lo:[0,1] neg_hi:[0,1]
	s_nop 0
	v_pk_add_f32 v[140:141], v[176:177], v[140:141]
	v_rcp_f32_e32 v177, v130
	v_add_f32_e32 v130, v135, v31
	v_pk_add_f32 v[140:141], v[168:169], v[140:141]
	v_mul_f32_e32 v130, 0xbfb8aa3b, v130
	v_cndmask_b32_e32 v139, v228, v140, vcc
	v_cmp_neq_f32_e32 vcc, s73, v238
	v_exp_f32_e32 v130, v130
	v_and_b32_e32 v176, 0xffff0000, v152
	v_cndmask_b32_e32 v140, v228, v141, vcc
	v_cmp_ngt_f32_e32 vcc, -1.0, v238
	v_add_f32_e32 v130, 1.0, v130
	v_rcp_f32_e32 v135, v130
	v_cndmask_b32_e32 v140, v229, v140, vcc
	v_cmp_ngt_f32_e32 vcc, -1.0, v236
	v_add_f32_e32 v130, v131, v27
	v_mul_f32_e32 v130, 0xbfb8aa3b, v130
	v_cndmask_b32_e32 v139, v229, v139, vcc
	v_cmp_neq_f32_e32 vcc, -1.0, v236
	v_exp_f32_e32 v130, v130
	s_nop 0
	v_cndmask_b32_e32 v139, v230, v139, vcc
	v_cmp_neq_f32_e32 vcc, -1.0, v238
	v_add_f32_e32 v130, 1.0, v130
	v_rcp_f32_e32 v184, v130
	v_cndmask_b32_e32 v140, v230, v140, vcc
	v_cmp_lt_f32_e64 vcc, |v236|, s77
	v_cndmask_b32_e64 v141, v140, v238, s[14:15]
	v_add_f32_e32 v130, v136, v32
	v_cndmask_b32_e32 v140, v139, v236, vcc
	v_pk_add_f32 v[140:141], v[180:181], v[140:141] neg_lo:[0,1] neg_hi:[0,1]
	v_mul_f32_e32 v130, 0xbfb8aa3b, v130
	v_pk_mul_f32 v[142:143], v[140:141], s[38:39] op_sel_hi:[1,0]
	v_exp_f32_e32 v130, v130
	v_pk_mul_f32 v[140:141], v[150:151], v[142:143]
	v_lshlrev_b32_e32 v180, 16, v153
	v_add_f32_e32 v139, v140, v140
	v_mul_f32_e32 v139, 0x3fb8aa3b, v139
	v_exp_f32_e32 v139, v139
	v_add_f32_e32 v130, 1.0, v130
	v_rcp_f32_e32 v136, v130
	v_add_f32_e32 v130, v132, v28
	v_sub_f32_e32 v139, 1.0, v139
	v_max_f32_e32 v139, 0, v139
	v_sqrt_f32_e32 v139, v139
	v_mul_f32_e32 v130, 0xbfb8aa3b, v130
	v_exp_f32_e32 v130, v130
	v_and_b32_e32 v181, 0xffff0000, v153
	v_mul_f32_e32 v139, v251, v139
	v_mul_f32_e32 v150, v139, v247
	v_add_f32_e32 v139, v141, v141
	v_mul_f32_e32 v139, 0x3fb8aa3b, v139
	v_exp_f32_e32 v139, v139
	v_add_f32_e32 v130, 1.0, v130
	v_rcp_f32_e32 v185, v130
	v_add_f32_e32 v130, v137, v33
	v_mul_f32_e32 v130, 0xbfb8aa3b, v130
	v_exp_f32_e32 v130, v130
	v_sub_f32_e32 v139, 1.0, v139
	v_max_f32_e32 v139, 0, v139
	v_sqrt_f32_e32 v139, v139
	v_add_f32_e32 v130, 1.0, v130
	v_rcp_f32_e32 v137, v130
	v_add_f32_e32 v130, v133, v29
	v_mul_f32_e32 v130, 0xbfb8aa3b, v130
	v_mul_f32_e32 v139, v252, v139
	v_exp_f32_e32 v130, v130
	v_mul_f32_e32 v151, v139, v248
	v_cvt_pk_bf16_f32 v139, v140, v141
	v_mul_f32_e32 v140, 0x42000000, v186
	v_mul_f32_e32 v141, 0x42000000, v187
	v_mul_f32_e32 v168, 0x42000000, v150
	v_med3_f32 v140, v140, s29, v231
	v_med3_f32 v141, v141, s29, v231
	v_cvt_pk_fp8_f32 v150, v140, v141
	v_add_f32_e32 v130, 1.0, v130
	v_mul_f32_e32 v151, 0x42000000, v151
	v_rcp_f32_e32 v186, v130
	v_pk_add_f32 v[130:131], v[192:193], v[200:201]
	v_med3_f32 v140, v168, s29, v231
	v_med3_f32 v141, v151, s29, v231
	v_pk_add_f32 v[132:133], v[130:131], v[192:193] neg_lo:[0,1] neg_hi:[0,1]
	v_cvt_pk_fp8_f32 v150, v140, v141 op_sel:[0,0,1]
	v_pk_add_f32 v[140:141], v[130:131], v[132:133] neg_lo:[0,1] neg_hi:[0,1]
	v_lshlrev_b32_e32 v151, 16, v152
	v_mov_b32_e32 v152, v200
	v_mov_b32_e32 v153, v192
	v_mov_b32_e32 v168, v132
	v_mov_b32_e32 v169, v140
	v_mov_b32_e32 v192, v201
	v_mov_b32_e32 v140, v133
	v_pk_add_f32 v[152:153], v[152:153], v[168:169] neg_lo:[0,1] neg_hi:[0,1]
	v_pk_add_f32 v[132:133], v[192:193], v[140:141] neg_lo:[0,1] neg_hi:[0,1]
	v_pk_add_f32 v[152:153], v[152:153], v[152:153] op_sel:[0,1] op_sel_hi:[1,0]
	v_pk_add_f32 v[132:133], v[132:133], v[132:133] op_sel_hi:[0,1]
	v_mov_b32_e32 v153, v195
	v_mov_b32_e32 v195, v133
	v_pk_add_f32 v[132:133], v[152:153], v[194:195]
	v_pk_add_f32 v[152:153], v[198:199], v[196:197]
	v_pk_add_f32 v[140:141], v[130:131], v[132:133]
	v_cmp_neq_f32_e32 vcc, s73, v235
	v_pk_add_f32 v[130:131], v[140:141], v[130:131] neg_lo:[0,1] neg_hi:[0,1]
	v_cmp_lt_f32_e64 s[14:15], |v237|, s77
	v_pk_add_f32 v[130:131], v[132:133], v[130:131] neg_lo:[0,1] neg_hi:[0,1]
	v_mov_b32_e32 v168, v220
	v_pk_add_f32 v[130:131], v[152:153], v[130:131]
	v_mov_b32_e32 v169, v212
	v_pk_add_f32 v[130:131], v[140:141], v[130:131]
	s_nop 0
	v_cndmask_b32_e32 v130, v228, v130, vcc
	v_cmp_neq_f32_e32 vcc, s73, v237
	s_nop 1
	v_cndmask_b32_e32 v131, v228, v131, vcc
	v_cmp_ngt_f32_e32 vcc, -1.0, v237
	s_nop 1
	v_cndmask_b32_e32 v131, v229, v131, vcc
	v_cmp_ngt_f32_e32 vcc, -1.0, v235
	s_nop 1
	v_cndmask_b32_e32 v130, v229, v130, vcc
	v_cmp_neq_f32_e32 vcc, -1.0, v235
	s_nop 1
	v_cndmask_b32_e32 v130, v230, v130, vcc
	v_cmp_neq_f32_e32 vcc, -1.0, v237
	s_nop 1
	v_cndmask_b32_e32 v131, v230, v131, vcc
	v_cmp_lt_f32_e64 vcc, |v235|, s77
	v_cndmask_b32_e64 v131, v131, v237, s[14:15]
	v_cmp_lt_f32_e64 s[14:15], |v240|, s77
	v_cndmask_b32_e32 v130, v130, v235, vcc
	v_pk_add_f32 v[130:131], v[178:179], v[130:131] neg_lo:[0,1] neg_hi:[0,1]
	v_cmp_neq_f32_e32 vcc, s73, v239
	v_pk_mul_f32 v[130:131], v[130:131], s[38:39] op_sel_hi:[1,0]
	s_nop 0
	v_pk_mul_f32 v[132:133], v[134:135], v[130:131]
	v_mul_f32_e32 v118, v118, v130
	v_add_f32_e32 v134, v132, v132
	v_mul_f32_e32 v134, 0x3fb8aa3b, v134
	v_exp_f32_e32 v134, v134
	v_cvt_pk_bf16_f32 v140, v132, v133
	v_mul_f32_e32 v119, v119, v131
	v_sub_f32_e32 v134, 1.0, v134
	v_max_f32_e32 v134, 0, v134
	v_sqrt_f32_e32 v134, v134
	s_nop 0
	v_mul_f32_e32 v134, v177, v134
	v_mul_f32_e32 v151, v134, v151
	v_add_f32_e32 v134, v133, v133
	v_mul_f32_e32 v134, 0x3fb8aa3b, v134
	v_exp_f32_e32 v134, v134
	v_pk_add_f32 v[132:133], v[212:213], v[220:221]
	v_sub_f32_e32 v134, 1.0, v134
	v_max_f32_e32 v134, 0, v134
	v_sqrt_f32_e32 v134, v134
	s_nop 0
	v_mul_f32_e32 v134, v184, v134
	v_mul_f32_e32 v178, v134, v176
	v_pk_add_f32 v[134:135], v[132:133], v[212:213] neg_lo:[0,1] neg_hi:[0,1]
	v_mov_b32_e32 v212, v221
	v_pk_add_f32 v[152:153], v[132:133], v[134:135] neg_lo:[0,1] neg_hi:[0,1]
	v_mov_b32_e32 v176, v134
	v_mov_b32_e32 v177, v152
	v_mov_b32_e32 v152, v135
	v_pk_add_f32 v[168:169], v[168:169], v[176:177] neg_lo:[0,1] neg_hi:[0,1]
	v_pk_add_f32 v[134:135], v[212:213], v[152:153] neg_lo:[0,1] neg_hi:[0,1]
	v_pk_add_f32 v[168:169], v[168:169], v[168:169] op_sel:[0,1] op_sel_hi:[1,0]
	v_pk_add_f32 v[134:135], v[134:135], v[134:135] op_sel_hi:[0,1]
	v_mov_b32_e32 v169, v215
	v_mov_b32_e32 v215, v135
	v_pk_add_f32 v[134:135], v[168:169], v[214:215]
	v_pk_add_f32 v[168:169], v[218:219], v[216:217]
	v_pk_add_f32 v[152:153], v[132:133], v[134:135]
	s_nop 0
	v_pk_add_f32 v[132:133], v[152:153], v[132:133] neg_lo:[0,1] neg_hi:[0,1]
	s_nop 0
	v_pk_add_f32 v[132:133], v[134:135], v[132:133] neg_lo:[0,1] neg_hi:[0,1]
	s_nop 0
	v_pk_add_f32 v[132:133], v[168:169], v[132:133]
	s_nop 0
	v_pk_add_f32 v[132:133], v[152:153], v[132:133]
	s_nop 0
	v_cndmask_b32_e32 v132, v228, v132, vcc
	v_cmp_neq_f32_e32 vcc, s73, v240
	s_nop 1
	v_cndmask_b32_e32 v133, v228, v133, vcc
	v_cmp_ngt_f32_e32 vcc, -1.0, v240
	s_nop 1
	v_cndmask_b32_e32 v133, v229, v133, vcc
	v_cmp_ngt_f32_e32 vcc, -1.0, v239
	s_nop 1
	v_cndmask_b32_e32 v132, v229, v132, vcc
	v_cmp_neq_f32_e32 vcc, -1.0, v239
	s_nop 1
	v_cndmask_b32_e32 v132, v230, v132, vcc
	v_cmp_neq_f32_e32 vcc, -1.0, v240
	s_nop 1
	v_cndmask_b32_e32 v133, v230, v133, vcc
	v_cmp_lt_f32_e64 vcc, |v239|, s77
	v_cndmask_b32_e64 v133, v133, v240, s[14:15]
	s_nop 0
	v_cndmask_b32_e32 v132, v132, v239, vcc
	v_pk_add_f32 v[132:133], v[182:183], v[132:133] neg_lo:[0,1] neg_hi:[0,1]
	s_nop 0
	v_pk_mul_f32 v[132:133], v[132:133], s[38:39] op_sel_hi:[1,0]
	s_nop 0
	v_pk_mul_f32 v[134:135], v[136:137], v[132:133]
	v_mul_f32_e32 v120, v120, v132
	v_add_f32_e32 v136, v134, v134
	v_add_f32_e32 v137, v135, v135
	v_mul_f32_e32 v136, 0x3fb8aa3b, v136
	v_mul_f32_e32 v137, 0x3fb8aa3b, v137
	v_exp_f32_e32 v136, v136
	v_exp_f32_e32 v137, v137
	v_cvt_pk_bf16_f32 v141, v134, v135
	v_mul_f32_e32 v134, 0x42000000, v151
	v_sub_f32_e32 v136, 1.0, v136
	v_sub_f32_e32 v137, 1.0, v137
	v_max_f32_e32 v136, 0, v136
	v_max_f32_e32 v137, 0, v137
	v_sqrt_f32_e32 v136, v136
	v_sqrt_f32_e32 v137, v137
	v_mul_f32_e32 v135, 0x42000000, v178
	v_med3_f32 v134, v134, s29, v231
	v_med3_f32 v135, v135, s29, v231
	v_mul_f32_e32 v136, v185, v136
	v_mul_f32_e32 v137, v186, v137
	v_cvt_pk_fp8_f32 v151, v134, v135
	v_mul_f32_e32 v136, v136, v180
	v_mul_f32_e32 v137, v137, v181
	v_mul_f32_e32 v136, 0x42000000, v136
	v_mul_f32_e32 v137, 0x42000000, v137
	v_med3_f32 v134, v136, s29, v231
	v_med3_f32 v135, v137, s29, v231
	v_cvt_pk_fp8_f32 v151, v134, v135 op_sel:[0,0,1]
	global_store_dwordx4 v[172:173], v[138:141], off
	global_store_dwordx2 v[170:171], v[150:151], off
	s_nop 0
	v_add_f32_e32 v138, v126, v126
	v_mul_f32_e32 v138, 0x3fb8aa3b, v138
	v_exp_f32_e32 v138, v138
	v_lshlrev_b32_e32 v134, 16, v146
	v_and_b32_e32 v135, 0xffff0000, v146
	v_lshlrev_b32_e32 v136, 16, v147
	v_sub_f32_e32 v138, 1.0, v138
	v_max_f32_e32 v138, 0, v138
	v_sqrt_f32_e32 v138, v138
	v_and_b32_e32 v137, 0xffff0000, v147
	v_mul_f32_e32 v121, v121, v133
	v_mul_f32_e32 v122, v122, v138
	v_mul_f32_e32 v134, v122, v134
	v_add_f32_e32 v122, v127, v47
	v_mul_f32_e32 v122, 0xbfb8aa3b, v122
	v_exp_f32_e32 v122, v122
	s_nop 0
	v_add_f32_e32 v122, 1.0, v122
	v_rcp_f32_e32 v122, v122
	s_nop 0
	v_mul_f32_e32 v122, v122, v145
	v_add_f32_e32 v127, v122, v122
	v_mul_f32_e32 v127, 0x3fb8aa3b, v127
	v_exp_f32_e32 v127, v127
	v_cvt_pk_bf16_f32 v122, v126, v122
	v_mul_f32_e32 v126, 0x42000000, v134
	v_sub_f32_e32 v127, 1.0, v127
	v_max_f32_e32 v127, 0, v127
	v_sqrt_f32_e32 v127, v127
	s_nop 0
	v_mul_f32_e32 v123, v123, v127
	v_mul_f32_e32 v127, v123, v135
	v_add_f32_e32 v123, v128, v48
	v_mul_f32_e32 v123, 0xbfb8aa3b, v123
	v_exp_f32_e32 v123, v123
	v_mul_f32_e32 v127, 0x42000000, v127
	v_med3_f32 v127, v127, s29, v231
	v_add_f32_e32 v123, 1.0, v123
	v_rcp_f32_e32 v123, v123
	s_nop 0
	v_mul_f32_e32 v123, v123, v142
	v_add_f32_e32 v128, v123, v123
	v_mul_f32_e32 v128, 0x3fb8aa3b, v128
	v_exp_f32_e32 v128, v128
	s_nop 0
	v_sub_f32_e32 v128, 1.0, v128
	v_max_f32_e32 v128, 0, v128
	v_sqrt_f32_e32 v128, v128
	s_nop 0
	v_mul_f32_e32 v124, v124, v128
	v_add_f32_e32 v128, v129, v49
	v_mul_f32_e32 v128, 0xbfb8aa3b, v128
	v_exp_f32_e32 v128, v128
	v_mul_f32_e32 v124, v124, v136
	v_mul_f32_e32 v124, 0x42000000, v124
	v_med3_f32 v124, v124, s29, v231
	v_add_f32_e32 v128, 1.0, v128
	v_rcp_f32_e32 v128, v128
	s_nop 0
	v_mul_f32_e32 v128, v128, v143
	v_add_f32_e32 v129, v128, v128
	v_mul_f32_e32 v129, 0x3fb8aa3b, v129
	v_exp_f32_e32 v129, v129
	v_cvt_pk_bf16_f32 v123, v123, v128
	v_med3_f32 v128, v126, s29, v231
	v_sub_f32_e32 v129, 1.0, v129
	v_max_f32_e32 v129, 0, v129
	v_sqrt_f32_e32 v129, v129
	v_cvt_pk_fp8_f32 v126, v128, v127
	v_lshlrev_b32_e32 v127, 16, v149
	v_and_b32_e32 v128, 0xffff0000, v149
	v_mul_f32_e32 v125, v125, v129
	v_add_f32_e32 v129, v118, v118
	v_mul_f32_e32 v129, 0x3fb8aa3b, v129
	v_exp_f32_e32 v129, v129
	v_mul_f32_e32 v125, v125, v137
	v_mul_f32_e32 v125, 0x42000000, v125
	v_med3_f32 v125, v125, s29, v231
	v_sub_f32_e32 v129, 1.0, v129
	v_max_f32_e32 v129, 0, v129
	v_sqrt_f32_e32 v129, v129
	v_cvt_pk_fp8_f32 v126, v124, v125 op_sel:[0,0,1]
	v_lshlrev_b32_e32 v124, 16, v148
	v_and_b32_e32 v125, 0xffff0000, v148
	v_mul_f32_e32 v114, v114, v129
	v_mul_f32_e32 v114, v114, v124
	v_add_f32_e32 v124, v119, v119
	v_mul_f32_e32 v124, 0x3fb8aa3b, v124
	v_exp_f32_e32 v124, v124
	v_mul_f32_e32 v114, 0x42000000, v114
	v_med3_f32 v114, v114, s29, v231
	v_sub_f32_e32 v124, 1.0, v124
	v_max_f32_e32 v124, 0, v124
	v_sqrt_f32_e32 v124, v124
	s_nop 0
	v_mul_f32_e32 v115, v115, v124
	v_add_f32_e32 v124, v120, v120
	v_mul_f32_e32 v124, 0x3fb8aa3b, v124
	v_exp_f32_e32 v124, v124
	v_mul_f32_e32 v115, v115, v125
	v_mul_f32_e32 v115, 0x42000000, v115
	v_med3_f32 v115, v115, s29, v231
	v_sub_f32_e32 v124, 1.0, v124
	v_max_f32_e32 v124, 0, v124
	v_sqrt_f32_e32 v124, v124
	v_cvt_pk_bf16_f32 v125, v120, v121
	v_mul_f32_e32 v116, v116, v124
	v_add_f32_e32 v124, v121, v121
	v_mul_f32_e32 v124, 0x3fb8aa3b, v124
	v_exp_f32_e32 v124, v124
	v_mul_f32_e32 v116, v116, v127
	v_cvt_pk_fp8_f32 v127, v114, v115
	v_sub_f32_e32 v124, 1.0, v124
	v_max_f32_e32 v124, 0, v124
	v_sqrt_f32_e32 v124, v124
	v_mul_f32_e32 v116, 0x42000000, v116
	v_med3_f32 v114, v116, s29, v231
	v_mul_f32_e32 v117, v117, v124
	v_mul_f32_e32 v117, v117, v128
	v_mul_f32_e32 v117, 0x42000000, v117
	v_med3_f32 v115, v117, s29, v231
	v_cvt_pk_fp8_f32 v127, v114, v115 op_sel:[0,0,1]
	v_add_co_u32_e32 v114, vcc, s84, v172
	v_cvt_pk_bf16_f32 v124, v118, v119
	s_nop 0
	v_addc_co_u32_e32 v115, vcc, 0, v173, vcc
	global_store_dwordx4 v[114:115], v[122:125], off
	v_add_co_u32_e32 v114, vcc, s93, v170
	s_nop 1
	v_addc_co_u32_e32 v115, vcc, 0, v171, vcc
	global_store_dwordx2 v[114:115], v[126:127], off
	v_add_co_u32_e32 v114, vcc, s92, v174
	v_add_f32_e32 v110, v110, v46
	s_nop 0
	v_addc_co_u32_e32 v115, vcc, 0, v175, vcc
	global_load_dwordx4 v[114:117], v[114:115], off
	v_mul_f32_e32 v110, 0xbfb8aa3b, v110
	v_add_f32_e32 v111, v111, v47
	v_exp_f32_e32 v110, v110
	v_mul_f32_e32 v111, 0xbfb8aa3b, v111
	v_exp_f32_e32 v111, v111
	v_add_f32_e32 v112, v112, v48
	v_add_f32_e32 v113, v113, v49
	v_add_f32_e32 v110, 1.0, v110
	v_mul_f32_e32 v112, 0xbfb8aa3b, v112
	v_mul_f32_e32 v113, 0xbfb8aa3b, v113
	v_rcp_f32_e32 v110, v110
	v_exp_f32_e32 v112, v112
	v_exp_f32_e32 v113, v113
	v_add_f32_e32 v111, 1.0, v111
	v_rcp_f32_e32 v111, v111
	v_add_co_u32_e32 v118, vcc, s89, v174
	v_add_f32_e32 v120, v106, v42
	s_nop 0
	v_addc_co_u32_e32 v119, vcc, 0, v175, vcc
	v_add_f32_e32 v122, v108, v44
	v_mul_f32_e32 v110, v110, v144
	v_add_f32_e32 v121, v107, v43
	v_add_f32_e32 v123, v109, v45
	global_load_dwordx4 v[106:109], v[118:119], off
	v_mul_f32_e32 v118, 0xbfb8aa3b, v120
	v_mul_f32_e32 v120, 0xbfb8aa3b, v122
	v_add_f32_e32 v112, 1.0, v112
	v_add_f32_e32 v113, 1.0, v113
	v_add_f32_e32 v122, v110, v110
	v_rcp_f32_e32 v112, v112
	v_rcp_f32_e32 v113, v113
	v_mul_f32_e32 v111, v111, v145
	v_mul_f32_e32 v122, 0x3fb8aa3b, v122
	v_mul_f32_e32 v119, 0xbfb8aa3b, v121
	v_mul_f32_e32 v121, 0xbfb8aa3b, v123
	v_add_f32_e32 v123, v111, v111
	v_exp_f32_e32 v122, v122
	v_exp_f32_e32 v118, v118
	v_mul_f32_e32 v123, 0x3fb8aa3b, v123
	v_exp_f32_e32 v123, v123
	v_exp_f32_e32 v119, v119
	v_mul_f32_e32 v112, v112, v142
	v_mul_f32_e32 v113, v113, v143
	v_add_f32_e32 v124, v112, v112
	v_add_f32_e32 v125, v113, v113
	v_sub_f32_e32 v122, 1.0, v122
	v_add_f32_e32 v118, 1.0, v118
	v_mul_f32_e32 v124, 0x3fb8aa3b, v124
	v_mul_f32_e32 v125, 0x3fb8aa3b, v125
	v_max_f32_e32 v122, 0, v122
	v_rcp_f32_e32 v118, v118
	v_exp_f32_e32 v124, v124
	v_exp_f32_e32 v125, v125
	v_sub_f32_e32 v123, 1.0, v123
	v_sqrt_f32_e32 v122, v122
	v_exp_f32_e32 v120, v120
	v_exp_f32_e32 v121, v121
	v_add_f32_e32 v119, 1.0, v119
	v_max_f32_e32 v123, 0, v123
	v_rcp_f32_e32 v119, v119
	v_sqrt_f32_e32 v123, v123
	v_add_f32_e32 v102, v102, v30
	v_mul_f32_e32 v102, 0xbfb8aa3b, v102
	v_sub_f32_e32 v124, 1.0, v124
	v_sub_f32_e32 v125, 1.0, v125
	v_mul_f32_e32 v118, v118, v122
	v_exp_f32_e32 v102, v102
	v_add_f32_e32 v120, 1.0, v120
	v_add_f32_e32 v121, 1.0, v121
	v_max_f32_e32 v124, 0, v124
	v_rcp_f32_e32 v120, v120
	v_rcp_f32_e32 v121, v121
	v_sqrt_f32_e32 v124, v124
	v_mul_f32_e32 v119, v119, v123
	v_cvt_pk_bf16_f32 v110, v110, v111
	v_cvt_pk_bf16_f32 v111, v112, v113
	v_add_f32_e32 v102, 1.0, v102
	v_rcp_f32_e32 v102, v102
	s_waitcnt vmcnt(0) lgkmcnt(0)
	v_lshlrev_b32_e32 v122, 16, v114
	v_mul_f32_e32 v118, v118, v122
	v_max_f32_e32 v122, 0, v125
	v_and_b32_e32 v114, 0xffff0000, v114
	v_sqrt_f32_e32 v122, v122
	v_mul_f32_e32 v114, v119, v114
	v_mul_f32_e32 v112, 0x42000000, v118
	v_mul_f32_e32 v113, 0x42000000, v114
	v_med3_f32 v112, v112, s29, v231
	v_med3_f32 v113, v113, s29, v231
	v_lshlrev_b32_e32 v123, 16, v115
	v_and_b32_e32 v115, 0xffff0000, v115
	v_mul_f32_e32 v119, v120, v124
	v_mul_f32_e32 v120, v121, v122
	v_cvt_pk_fp8_f32 v114, v112, v113
	v_mul_f32_e32 v119, v119, v123
	v_mul_f32_e32 v115, v120, v115
	v_mul_f32_e32 v118, 0x42000000, v119
	v_mul_f32_e32 v112, 0x42000000, v115
	v_med3_f32 v113, v118, s29, v231
	v_med3_f32 v112, v112, s29, v231
	v_mul_f32_e32 v102, v102, v130
	v_cvt_pk_fp8_f32 v114, v113, v112 op_sel:[0,0,1]
	v_lshlrev_b32_e32 v112, 16, v116
	v_and_b32_e32 v113, 0xffff0000, v116
	v_add_f32_e32 v116, v102, v102
	v_add_f32_e32 v103, v103, v31
	v_add_f32_e32 v98, v98, v26
	v_mul_f32_e32 v116, 0x3fb8aa3b, v116
	v_mul_f32_e32 v103, 0xbfb8aa3b, v103
	v_mul_f32_e32 v98, 0xbfb8aa3b, v98
	v_exp_f32_e32 v116, v116
	v_exp_f32_e32 v103, v103
	v_exp_f32_e32 v98, v98
	v_add_f32_e32 v104, v104, v32
	v_sub_f32_e32 v116, 1.0, v116
	v_add_f32_e32 v103, 1.0, v103
	v_add_f32_e32 v98, 1.0, v98
	v_max_f32_e32 v116, 0, v116
	v_rcp_f32_e32 v103, v103
	v_rcp_f32_e32 v98, v98
	v_sqrt_f32_e32 v116, v116
	v_add_f32_e32 v105, v105, v33
	v_mul_f32_e32 v103, v103, v131
	v_add_f32_e32 v99, v99, v27
	v_mul_f32_e32 v98, v98, v116
	v_add_f32_e32 v116, v103, v103
	v_mul_f32_e32 v116, 0x3fb8aa3b, v116
	v_mul_f32_e32 v104, 0xbfb8aa3b, v104
	v_mul_f32_e32 v105, 0xbfb8aa3b, v105
	v_mul_f32_e32 v99, 0xbfb8aa3b, v99
	v_exp_f32_e32 v116, v116
	v_exp_f32_e32 v104, v104
	v_exp_f32_e32 v105, v105
	v_exp_f32_e32 v99, v99
	v_sub_f32_e32 v116, 1.0, v116
	v_add_f32_e32 v104, 1.0, v104
	v_add_f32_e32 v105, 1.0, v105
	v_add_f32_e32 v99, 1.0, v99
	v_max_f32_e32 v116, 0, v116
	v_rcp_f32_e32 v104, v104
	v_rcp_f32_e32 v105, v105
	v_rcp_f32_e32 v99, v99
	v_sqrt_f32_e32 v116, v116
	v_mul_f32_e32 v104, v104, v132
	v_mul_f32_e32 v105, v105, v133
	v_mul_f32_e32 v98, v98, v112
	v_mul_f32_e32 v99, v99, v116
	v_add_f32_e32 v112, v104, v104
	v_add_f32_e32 v116, v105, v105
	v_add_f32_e32 v100, v100, v28
	v_mul_f32_e32 v112, 0x3fb8aa3b, v112
	v_add_f32_e32 v101, v101, v29
	v_mul_f32_e32 v116, 0x3fb8aa3b, v116
	v_mul_f32_e32 v100, 0xbfb8aa3b, v100
	v_exp_f32_e32 v112, v112
	v_mul_f32_e32 v101, 0xbfb8aa3b, v101
	v_exp_f32_e32 v116, v116
	v_add_f32_e32 v94, v94, v46
	v_exp_f32_e32 v100, v100
	v_exp_f32_e32 v101, v101
	v_mul_f32_e32 v94, 0xbfb8aa3b, v94
	v_exp_f32_e32 v94, v94
	v_sub_f32_e32 v112, 1.0, v112
	v_sub_f32_e32 v116, 1.0, v116
	v_add_f32_e32 v100, 1.0, v100
	v_max_f32_e32 v112, 0, v112
	v_add_f32_e32 v101, 1.0, v101
	v_max_f32_e32 v116, 0, v116
	v_rcp_f32_e32 v100, v100
	v_sqrt_f32_e32 v112, v112
	v_rcp_f32_e32 v101, v101
	v_sqrt_f32_e32 v116, v116
	v_add_f32_e32 v94, 1.0, v94
	v_rcp_f32_e32 v94, v94
	v_mul_f32_e32 v99, v99, v113
	v_lshlrev_b32_e32 v115, 16, v117
	v_and_b32_e32 v117, 0xffff0000, v117
	v_mul_f32_e32 v100, v100, v112
	v_mul_f32_e32 v101, v101, v116
	v_mul_f32_e32 v98, 0x42000000, v98
	v_mul_f32_e32 v99, 0x42000000, v99
	v_mul_f32_e32 v100, v100, v115
	v_mul_f32_e32 v101, v101, v117
	v_med3_f32 v98, v98, s29, v231
	v_med3_f32 v99, v99, s29, v231
	v_mul_f32_e32 v94, v94, v144
	v_cvt_pk_fp8_f32 v115, v98, v99
	v_mul_f32_e32 v98, 0x42000000, v101
	v_add_f32_e32 v101, v94, v94
	v_add_f32_e32 v95, v95, v47
	v_add_f32_e32 v90, v90, v42
	v_mul_f32_e32 v101, 0x3fb8aa3b, v101
	v_mul_f32_e32 v95, 0xbfb8aa3b, v95
	v_mul_f32_e32 v90, 0xbfb8aa3b, v90
	v_exp_f32_e32 v101, v101
	v_exp_f32_e32 v95, v95
	v_exp_f32_e32 v90, v90
	v_add_f32_e32 v91, v91, v43
	v_sub_f32_e32 v101, 1.0, v101
	v_add_f32_e32 v95, 1.0, v95
	v_add_f32_e32 v90, 1.0, v90
	v_max_f32_e32 v101, 0, v101
	v_rcp_f32_e32 v95, v95
	v_rcp_f32_e32 v90, v90
	v_sqrt_f32_e32 v101, v101
	v_add_f32_e32 v96, v96, v48
	v_mul_f32_e32 v95, v95, v145
	v_mul_f32_e32 v91, 0xbfb8aa3b, v91
	v_mul_f32_e32 v90, v90, v101
	v_add_f32_e32 v101, v95, v95
	v_mul_f32_e32 v101, 0x3fb8aa3b, v101
	v_exp_f32_e32 v101, v101
	v_mul_f32_e32 v96, 0xbfb8aa3b, v96
	v_add_f32_e32 v97, v97, v49
	v_exp_f32_e32 v91, v91
	v_exp_f32_e32 v96, v96
	v_mul_f32_e32 v97, 0xbfb8aa3b, v97
	v_exp_f32_e32 v97, v97
	v_mul_f32_e32 v100, 0x42000000, v100
	v_med3_f32 v99, v100, s29, v231
	v_med3_f32 v98, v98, s29, v231
	v_sub_f32_e32 v101, 1.0, v101
	v_add_f32_e32 v92, v92, v44
	v_cvt_pk_fp8_f32 v115, v99, v98 op_sel:[0,0,1]
	v_add_co_u32_e32 v98, vcc, s92, v172
	v_add_f32_e32 v91, 1.0, v91
	v_max_f32_e32 v101, 0, v101
	v_add_f32_e32 v96, 1.0, v96
	v_mul_f32_e32 v92, 0xbfb8aa3b, v92
	v_cvt_pk_bf16_f32 v112, v102, v103
	v_cvt_pk_bf16_f32 v113, v104, v105
	v_addc_co_u32_e32 v99, vcc, 0, v173, vcc
	v_rcp_f32_e32 v91, v91
	v_sqrt_f32_e32 v101, v101
	v_exp_f32_e32 v92, v92
	v_rcp_f32_e32 v96, v96
	v_add_f32_e32 v97, 1.0, v97
	global_store_dwordx4 v[98:99], v[110:113], off
	v_add_co_u32_e32 v98, vcc, s84, v170
	v_rcp_f32_e32 v97, v97
	s_nop 0
	v_addc_co_u32_e32 v99, vcc, 0, v171, vcc
	global_store_dwordx2 v[98:99], v[114:115], off
	v_lshlrev_b32_e32 v98, 16, v106
	v_mul_f32_e32 v98, v90, v98
	v_mul_f32_e32 v90, v91, v101
	v_add_f32_e32 v91, 1.0, v92
	v_mul_f32_e32 v92, v96, v142
	v_add_f32_e32 v96, v92, v92
	v_mul_f32_e32 v97, v97, v143
	v_mul_f32_e32 v96, 0x3fb8aa3b, v96
	v_add_f32_e32 v101, v97, v97
	v_exp_f32_e32 v96, v96
	v_add_f32_e32 v93, v93, v45
	v_mul_f32_e32 v101, 0x3fb8aa3b, v101
	v_mul_f32_e32 v93, 0xbfb8aa3b, v93
	v_exp_f32_e32 v101, v101
	v_exp_f32_e32 v93, v93
	v_add_f32_e32 v86, v86, v30
	v_mul_f32_e32 v86, 0xbfb8aa3b, v86
	v_sub_f32_e32 v96, 1.0, v96
	v_exp_f32_e32 v86, v86
	v_max_f32_e32 v96, 0, v96
	v_sub_f32_e32 v101, 1.0, v101
	v_rcp_f32_e32 v91, v91
	v_sqrt_f32_e32 v96, v96
	v_add_f32_e32 v93, 1.0, v93
	v_max_f32_e32 v101, 0, v101
	v_rcp_f32_e32 v93, v93
	v_sqrt_f32_e32 v101, v101
	v_add_f32_e32 v86, 1.0, v86
	v_and_b32_e32 v99, 0xffff0000, v106
	v_rcp_f32_e32 v86, v86
	v_lshlrev_b32_e32 v100, 16, v107
	v_mul_f32_e32 v99, v90, v99
	v_mul_f32_e32 v90, v91, v96
	v_and_b32_e32 v102, 0xffff0000, v107
	v_mul_f32_e32 v96, v90, v100
	v_mul_f32_e32 v90, v93, v101
	v_mul_f32_e32 v93, v90, v102
	v_cvt_pk_bf16_f32 v90, v94, v95
	v_cvt_pk_bf16_f32 v91, v92, v97
	v_mul_f32_e32 v92, 0x42000000, v98
	v_mul_f32_e32 v94, 0x42000000, v99
	v_mul_f32_e32 v95, 0x42000000, v96
	v_med3_f32 v92, v92, s29, v231
	v_med3_f32 v96, v94, s29, v231
	v_mul_f32_e32 v86, v86, v130
	v_cvt_pk_fp8_f32 v94, v92, v96
	v_add_f32_e32 v96, v86, v86
	v_add_f32_e32 v87, v87, v31
	v_add_f32_e32 v82, v82, v26
	v_mul_f32_e32 v96, 0x3fb8aa3b, v96
	v_mul_f32_e32 v87, 0xbfb8aa3b, v87
	v_mul_f32_e32 v82, 0xbfb8aa3b, v82
	v_exp_f32_e32 v96, v96
	v_exp_f32_e32 v87, v87
	v_exp_f32_e32 v82, v82
	v_add_f32_e32 v88, v88, v32
	v_sub_f32_e32 v96, 1.0, v96
	v_add_f32_e32 v87, 1.0, v87
	v_add_f32_e32 v82, 1.0, v82
	v_max_f32_e32 v96, 0, v96
	v_rcp_f32_e32 v87, v87
	v_rcp_f32_e32 v82, v82
	v_sqrt_f32_e32 v96, v96
	v_mul_f32_e32 v88, 0xbfb8aa3b, v88
	v_mul_f32_e32 v87, v87, v131
	v_exp_f32_e32 v88, v88
	v_mul_f32_e32 v82, v82, v96
	v_add_f32_e32 v96, v87, v87
	v_add_f32_e32 v89, v89, v33
	v_add_f32_e32 v83, v83, v27
	v_mul_f32_e32 v96, 0x3fb8aa3b, v96
	v_mul_f32_e32 v89, 0xbfb8aa3b, v89
	v_mul_f32_e32 v83, 0xbfb8aa3b, v83
	v_exp_f32_e32 v96, v96
	v_exp_f32_e32 v89, v89
	v_exp_f32_e32 v83, v83
	v_add_f32_e32 v88, 1.0, v88
	v_rcp_f32_e32 v88, v88
	v_sub_f32_e32 v96, 1.0, v96
	v_add_f32_e32 v89, 1.0, v89
	v_mul_f32_e32 v92, 0x42000000, v93
	v_add_f32_e32 v83, 1.0, v83
	v_max_f32_e32 v96, 0, v96
	v_rcp_f32_e32 v89, v89
	v_med3_f32 v93, v95, s29, v231
	v_med3_f32 v92, v92, s29, v231
	v_rcp_f32_e32 v83, v83
	v_sqrt_f32_e32 v96, v96
	v_cvt_pk_fp8_f32 v94, v93, v92 op_sel:[0,0,1]
	v_lshlrev_b32_e32 v92, 16, v108
	v_mul_f32_e32 v88, v88, v132
	v_mul_f32_e32 v82, v82, v92
	v_add_f32_e32 v92, v88, v88
	v_add_f32_e32 v84, v84, v28
	v_mul_f32_e32 v92, 0x3fb8aa3b, v92
	v_mul_f32_e32 v89, v89, v133
	v_mul_f32_e32 v84, 0xbfb8aa3b, v84
	v_mul_f32_e32 v83, v83, v96
	v_exp_f32_e32 v92, v92
	v_add_f32_e32 v96, v89, v89
	v_exp_f32_e32 v84, v84
	v_add_f32_e32 v85, v85, v29
	v_mul_f32_e32 v96, 0x3fb8aa3b, v96
	v_mul_f32_e32 v85, 0xbfb8aa3b, v85
	v_exp_f32_e32 v96, v96
	v_exp_f32_e32 v85, v85
	v_sub_f32_e32 v92, 1.0, v92
	v_add_f32_e32 v84, 1.0, v84
	v_max_f32_e32 v92, 0, v92
	v_rcp_f32_e32 v84, v84
	v_sqrt_f32_e32 v92, v92
	v_sub_f32_e32 v96, 1.0, v96
	v_add_f32_e32 v85, 1.0, v85
	v_max_f32_e32 v96, 0, v96
	v_and_b32_e32 v93, 0xffff0000, v108
	v_rcp_f32_e32 v85, v85
	v_sqrt_f32_e32 v96, v96
	v_mul_f32_e32 v83, v83, v93
	v_lshlrev_b32_e32 v95, 16, v109
	v_mul_f32_e32 v84, v84, v92
	v_mul_f32_e32 v82, 0x42000000, v82
	v_mul_f32_e32 v83, 0x42000000, v83
	v_mul_f32_e32 v84, v84, v95
	v_med3_f32 v82, v82, s29, v231
	v_med3_f32 v83, v83, s29, v231
	v_and_b32_e32 v97, 0xffff0000, v109
	v_mul_f32_e32 v85, v85, v96
	v_cvt_pk_fp8_f32 v95, v82, v83
	v_mul_f32_e32 v85, v85, v97
	v_mul_f32_e32 v84, 0x42000000, v84
	v_mul_f32_e32 v82, 0x42000000, v85
	v_med3_f32 v83, v84, s29, v231
	v_med3_f32 v82, v82, s29, v231
	v_cvt_pk_fp8_f32 v95, v83, v82 op_sel:[0,0,1]
	v_add_co_u32_e32 v82, vcc, s89, v172
	v_cvt_pk_bf16_f32 v92, v86, v87
	v_cvt_pk_bf16_f32 v93, v88, v89
	v_addc_co_u32_e32 v83, vcc, 0, v173, vcc
	s_mov_b32 s0, 0xc000
	global_store_dwordx4 v[82:83], v[90:93], off
	v_add_co_u32_e32 v82, vcc, s0, v170
	s_nop 1
	v_addc_co_u32_e32 v83, vcc, 0, v171, vcc
	global_store_dwordx2 v[82:83], v[94:95], off
	v_add_u32_e32 v82, 0x80, v234
	v_add_f32_e32 v78, v78, v46
	v_ashrrev_i32_e32 v83, 31, v82
	v_lshlrev_b64 v[82:83], 10, v[82:83]
	v_lshl_add_u64 v[88:89], v[82:83], 0, v[166:167]
	v_lshlrev_b64 v[90:91], 1, v[88:89]
	v_lshl_add_u64 v[82:83], s[24:25], 0, v[90:91]
	global_load_dwordx4 v[84:87], v[82:83], off
	v_mul_f32_e32 v78, 0xbfb8aa3b, v78
	v_exp_f32_e32 v92, v78
	v_add_f32_e32 v79, v79, v47
	v_add_f32_e32 v80, v80, v48
	v_mul_f32_e32 v79, 0xbfb8aa3b, v79
	v_add_f32_e32 v74, v74, v42
	v_add_f32_e32 v81, v81, v49
	v_mul_f32_e32 v80, 0xbfb8aa3b, v80
	v_exp_f32_e32 v93, v79
	v_add_f32_e32 v75, v75, v43
	v_add_f32_e32 v76, v76, v44
	v_add_f32_e32 v77, v77, v45
	v_mul_f32_e32 v74, 0xbfb8aa3b, v74
	v_mul_f32_e32 v81, 0xbfb8aa3b, v81
	v_exp_f32_e32 v94, v80
	v_lshl_add_u64 v[78:79], s[50:51], 0, v[88:89]
	v_add_f32_e32 v88, 1.0, v92
	v_mul_f32_e32 v75, 0xbfb8aa3b, v75
	v_mul_f32_e32 v76, 0xbfb8aa3b, v76
	v_mul_f32_e32 v77, 0xbfb8aa3b, v77
	v_exp_f32_e32 v74, v74
	v_exp_f32_e32 v95, v81
	v_rcp_f32_e32 v88, v88
	v_exp_f32_e32 v75, v75
	v_exp_f32_e32 v76, v76
	v_exp_f32_e32 v77, v77
	v_lshl_add_u64 v[80:81], s[48:49], 0, v[90:91]
	v_add_f32_e32 v90, 1.0, v93
	v_add_f32_e32 v92, 1.0, v94
	v_rcp_f32_e32 v90, v90
	v_add_f32_e32 v89, 1.0, v74
	v_add_f32_e32 v93, 1.0, v95
	v_add_co_u32_e32 v74, vcc, s84, v82
	v_rcp_f32_e32 v92, v92
	v_mul_f32_e32 v88, v88, v144
	v_add_f32_e32 v91, 1.0, v75
	v_add_f32_e32 v76, 1.0, v76
	v_add_f32_e32 v77, 1.0, v77
	v_addc_co_u32_e32 v75, vcc, 0, v83, vcc
	v_rcp_f32_e32 v93, v93
	v_add_f32_e32 v96, v88, v88
	v_rcp_f32_e32 v94, v76
	v_rcp_f32_e32 v95, v77
	global_load_dwordx4 v[74:77], v[74:75], off
	v_mul_f32_e32 v96, 0x3fb8aa3b, v96
	v_mul_f32_e32 v90, v90, v145
	v_exp_f32_e32 v96, v96
	v_mul_f32_e32 v92, v92, v142
	v_add_f32_e32 v97, v90, v90
	v_mul_f32_e32 v93, v93, v143
	v_add_f32_e32 v98, v92, v92
	v_mul_f32_e32 v97, 0x3fb8aa3b, v97
	v_add_f32_e32 v99, v93, v93
	v_mul_f32_e32 v98, 0x3fb8aa3b, v98
	v_exp_f32_e32 v97, v97
	v_mul_f32_e32 v99, 0x3fb8aa3b, v99
	v_exp_f32_e32 v98, v98
	v_sub_f32_e32 v96, 1.0, v96
	v_exp_f32_e32 v99, v99
	v_max_f32_e32 v96, 0, v96
	v_rcp_f32_e32 v89, v89
	v_sqrt_f32_e32 v96, v96
	v_add_f32_e32 v70, v70, v30
	v_sub_f32_e32 v97, 1.0, v97
	v_mul_f32_e32 v70, 0xbfb8aa3b, v70
	v_sub_f32_e32 v98, 1.0, v98
	v_max_f32_e32 v97, 0, v97
	v_exp_f32_e32 v70, v70
	v_rcp_f32_e32 v91, v91
	v_sub_f32_e32 v99, 1.0, v99
	v_max_f32_e32 v98, 0, v98
	v_sqrt_f32_e32 v97, v97
	v_max_f32_e32 v99, 0, v99
	v_sqrt_f32_e32 v98, v98
	v_mul_f32_e32 v89, v89, v96
	v_add_f32_e32 v70, 1.0, v70
	v_mul_f32_e32 v91, v91, v97
	s_waitcnt vmcnt(0) lgkmcnt(0)
	v_lshlrev_b32_e32 v96, 16, v84
	v_mul_f32_e32 v89, v89, v96
	v_sqrt_f32_e32 v96, v99
	v_and_b32_e32 v84, 0xffff0000, v84
	v_rcp_f32_e32 v70, v70
	v_lshlrev_b32_e32 v97, 16, v85
	v_mul_f32_e32 v91, v91, v84
	v_mul_f32_e32 v84, v94, v98
	v_and_b32_e32 v85, 0xffff0000, v85
	v_mul_f32_e32 v94, v84, v97
	v_mul_f32_e32 v84, v95, v96
	v_mul_f32_e32 v95, v84, v85
	v_cvt_pk_bf16_f32 v84, v88, v90
	v_mul_f32_e32 v88, 0x42000000, v89
	v_mul_f32_e32 v89, 0x42000000, v91
	v_med3_f32 v91, v88, s29, v231
	v_med3_f32 v89, v89, s29, v231
	v_mul_f32_e32 v70, v70, v130
	v_cvt_pk_fp8_f32 v88, v91, v89
	v_add_f32_e32 v91, v70, v70
	v_add_f32_e32 v71, v71, v31
	v_add_f32_e32 v66, v66, v26
	v_mul_f32_e32 v91, 0x3fb8aa3b, v91
	v_mul_f32_e32 v71, 0xbfb8aa3b, v71
	v_mul_f32_e32 v66, 0xbfb8aa3b, v66
	v_exp_f32_e32 v91, v91
	v_exp_f32_e32 v71, v71
	v_exp_f32_e32 v66, v66
	v_add_f32_e32 v73, v73, v33
	v_sub_f32_e32 v91, 1.0, v91
	v_add_f32_e32 v71, 1.0, v71
	v_add_f32_e32 v66, 1.0, v66
	v_max_f32_e32 v91, 0, v91
	v_rcp_f32_e32 v71, v71
	v_rcp_f32_e32 v66, v66
	v_sqrt_f32_e32 v91, v91
	v_add_f32_e32 v67, v67, v27
	v_mul_f32_e32 v71, v71, v131
	v_add_f32_e32 v72, v72, v32
	v_mul_f32_e32 v66, v66, v91
	v_add_f32_e32 v91, v71, v71
	v_mul_f32_e32 v91, 0x3fb8aa3b, v91
	v_mul_f32_e32 v73, 0xbfb8aa3b, v73
	v_mul_f32_e32 v67, 0xbfb8aa3b, v67
	v_exp_f32_e32 v91, v91
	v_mul_f32_e32 v72, 0xbfb8aa3b, v72
	v_exp_f32_e32 v73, v73
	v_exp_f32_e32 v67, v67
	v_exp_f32_e32 v72, v72
	v_sub_f32_e32 v91, 1.0, v91
	v_add_f32_e32 v73, 1.0, v73
	v_add_f32_e32 v67, 1.0, v67
	v_max_f32_e32 v91, 0, v91
	v_add_f32_e32 v72, 1.0, v72
	v_rcp_f32_e32 v73, v73
	v_rcp_f32_e32 v67, v67
	v_sqrt_f32_e32 v91, v91
	v_rcp_f32_e32 v72, v72
	v_mul_f32_e32 v90, 0x42000000, v94
	v_mul_f32_e32 v89, 0x42000000, v95
	v_med3_f32 v90, v90, s29, v231
	v_med3_f32 v89, v89, s29, v231
	v_mul_f32_e32 v73, v73, v133
	v_cvt_pk_fp8_f32 v88, v90, v89 op_sel:[0,0,1]
	v_lshlrev_b32_e32 v89, 16, v86
	v_mul_f32_e32 v67, v67, v91
	v_mul_f32_e32 v72, v72, v132
	v_add_f32_e32 v91, v73, v73
	v_mul_f32_e32 v66, v66, v89
	v_add_f32_e32 v89, v72, v72
	v_add_f32_e32 v69, v69, v29
	v_mul_f32_e32 v91, 0x3fb8aa3b, v91
	v_add_f32_e32 v68, v68, v28
	v_mul_f32_e32 v89, 0x3fb8aa3b, v89
	v_mul_f32_e32 v69, 0xbfb8aa3b, v69
	v_exp_f32_e32 v91, v91
	v_add_f32_e32 v62, v62, v46
	v_mul_f32_e32 v68, 0xbfb8aa3b, v68
	v_exp_f32_e32 v89, v89
	v_exp_f32_e32 v69, v69
	v_mul_f32_e32 v62, 0xbfb8aa3b, v62
	v_exp_f32_e32 v68, v68
	v_exp_f32_e32 v62, v62
	v_sub_f32_e32 v91, 1.0, v91
	v_sub_f32_e32 v89, 1.0, v89
	v_add_f32_e32 v69, 1.0, v69
	v_max_f32_e32 v91, 0, v91
	v_add_f32_e32 v68, 1.0, v68
	v_max_f32_e32 v89, 0, v89
	v_rcp_f32_e32 v69, v69
	v_sqrt_f32_e32 v91, v91
	v_add_f32_e32 v62, 1.0, v62
	v_rcp_f32_e32 v68, v68
	v_sqrt_f32_e32 v89, v89
	v_rcp_f32_e32 v62, v62
	v_and_b32_e32 v86, 0xffff0000, v86
	v_mul_f32_e32 v67, v67, v86
	v_lshlrev_b32_e32 v90, 16, v87
	v_and_b32_e32 v87, 0xffff0000, v87
	v_mul_f32_e32 v69, v69, v91
	v_mul_f32_e32 v66, 0x42000000, v66
	v_mul_f32_e32 v67, 0x42000000, v67
	v_mul_f32_e32 v68, v68, v89
	v_mul_f32_e32 v69, v69, v87
	v_med3_f32 v66, v66, s29, v231
	v_med3_f32 v67, v67, s29, v231
	v_mul_f32_e32 v62, v62, v144
	v_cvt_pk_fp8_f32 v89, v66, v67
	v_mul_f32_e32 v66, 0x42000000, v69
	v_add_f32_e32 v69, v62, v62
	v_add_f32_e32 v63, v63, v47
	v_add_f32_e32 v58, v58, v42
	v_mul_f32_e32 v69, 0x3fb8aa3b, v69
	v_mul_f32_e32 v63, 0xbfb8aa3b, v63
	v_mul_f32_e32 v58, 0xbfb8aa3b, v58
	v_exp_f32_e32 v69, v69
	v_exp_f32_e32 v63, v63
	v_exp_f32_e32 v58, v58
	v_add_f32_e32 v59, v59, v43
	v_sub_f32_e32 v69, 1.0, v69
	v_add_f32_e32 v63, 1.0, v63
	v_add_f32_e32 v58, 1.0, v58
	v_max_f32_e32 v69, 0, v69
	v_rcp_f32_e32 v63, v63
	v_rcp_f32_e32 v58, v58
	v_sqrt_f32_e32 v69, v69
	v_add_f32_e32 v64, v64, v48
	v_mul_f32_e32 v63, v63, v145
	v_mul_f32_e32 v59, 0xbfb8aa3b, v59
	v_mul_f32_e32 v58, v58, v69
	v_add_f32_e32 v69, v63, v63
	v_mul_f32_e32 v69, 0x3fb8aa3b, v69
	v_exp_f32_e32 v69, v69
	v_mul_f32_e32 v64, 0xbfb8aa3b, v64
	v_add_f32_e32 v65, v65, v49
	v_exp_f32_e32 v59, v59
	v_exp_f32_e32 v64, v64
	v_mul_f32_e32 v65, 0xbfb8aa3b, v65
	v_exp_f32_e32 v65, v65
	v_sub_f32_e32 v69, 1.0, v69
	v_add_f32_e32 v60, v60, v44
	v_add_f32_e32 v59, 1.0, v59
	v_max_f32_e32 v69, 0, v69
	v_add_f32_e32 v64, 1.0, v64
	v_mul_f32_e32 v60, 0xbfb8aa3b, v60
	v_mul_f32_e32 v68, v68, v90
	v_rcp_f32_e32 v59, v59
	v_sqrt_f32_e32 v69, v69
	v_exp_f32_e32 v60, v60
	v_rcp_f32_e32 v64, v64
	v_add_f32_e32 v65, 1.0, v65
	v_mul_f32_e32 v68, 0x42000000, v68
	v_rcp_f32_e32 v65, v65
	v_med3_f32 v67, v68, s29, v231
	v_med3_f32 v66, v66, s29, v231
	v_cvt_pk_fp8_f32 v89, v67, v66 op_sel:[0,0,1]
	v_lshlrev_b32_e32 v66, 16, v74
	v_mul_f32_e32 v66, v58, v66
	v_mul_f32_e32 v58, v59, v69
	v_add_f32_e32 v59, 1.0, v60
	v_mul_f32_e32 v60, v64, v142
	v_add_f32_e32 v64, v60, v60
	v_mul_f32_e32 v65, v65, v143
	v_mul_f32_e32 v64, 0x3fb8aa3b, v64
	v_add_f32_e32 v69, v65, v65
	v_exp_f32_e32 v64, v64
	v_add_f32_e32 v61, v61, v45
	v_mul_f32_e32 v69, 0x3fb8aa3b, v69
	v_mul_f32_e32 v61, 0xbfb8aa3b, v61
	v_exp_f32_e32 v69, v69
	v_exp_f32_e32 v61, v61
	v_add_f32_e32 v54, v54, v30
	v_mul_f32_e32 v54, 0xbfb8aa3b, v54
	v_sub_f32_e32 v64, 1.0, v64
	v_exp_f32_e32 v54, v54
	v_max_f32_e32 v64, 0, v64
	v_sub_f32_e32 v69, 1.0, v69
	v_rcp_f32_e32 v59, v59
	v_sqrt_f32_e32 v64, v64
	v_add_f32_e32 v61, 1.0, v61
	v_max_f32_e32 v69, 0, v69
	v_rcp_f32_e32 v61, v61
	v_sqrt_f32_e32 v69, v69
	v_add_f32_e32 v54, 1.0, v54
	v_and_b32_e32 v67, 0xffff0000, v74
	v_rcp_f32_e32 v54, v54
	v_lshlrev_b32_e32 v68, 16, v75
	v_mul_f32_e32 v67, v58, v67
	v_mul_f32_e32 v58, v59, v64
	v_cvt_pk_bf16_f32 v86, v70, v71
	v_and_b32_e32 v70, 0xffff0000, v75
	v_mul_f32_e32 v64, v58, v68
	v_mul_f32_e32 v58, v61, v69
	v_mul_f32_e32 v61, v58, v70
	v_cvt_pk_bf16_f32 v58, v62, v63
	v_cvt_pk_bf16_f32 v59, v60, v65
	v_mul_f32_e32 v60, 0x42000000, v66
	v_mul_f32_e32 v62, 0x42000000, v67
	v_mul_f32_e32 v63, 0x42000000, v64
	v_med3_f32 v60, v60, s29, v231
	v_med3_f32 v64, v62, s29, v231
	v_mul_f32_e32 v54, v54, v130
	v_cvt_pk_fp8_f32 v62, v60, v64
	v_add_f32_e32 v64, v54, v54
	v_add_f32_e32 v55, v55, v31
	v_add_f32_e32 v50, v50, v26
	v_mul_f32_e32 v64, 0x3fb8aa3b, v64
	v_mul_f32_e32 v55, 0xbfb8aa3b, v55
	v_mul_f32_e32 v50, 0xbfb8aa3b, v50
	v_exp_f32_e32 v64, v64
	v_exp_f32_e32 v55, v55
	v_exp_f32_e32 v50, v50
	v_add_f32_e32 v56, v56, v32
	v_sub_f32_e32 v64, 1.0, v64
	v_add_f32_e32 v55, 1.0, v55
	v_add_f32_e32 v50, 1.0, v50
	v_max_f32_e32 v64, 0, v64
	v_rcp_f32_e32 v55, v55
	v_rcp_f32_e32 v50, v50
	v_sqrt_f32_e32 v64, v64
	v_mul_f32_e32 v56, 0xbfb8aa3b, v56
	v_mul_f32_e32 v55, v55, v131
	v_exp_f32_e32 v56, v56
	v_mul_f32_e32 v50, v50, v64
	v_add_f32_e32 v64, v55, v55
	v_add_f32_e32 v57, v57, v33
	v_add_f32_e32 v51, v51, v27
	v_mul_f32_e32 v64, 0x3fb8aa3b, v64
	v_mul_f32_e32 v57, 0xbfb8aa3b, v57
	v_mul_f32_e32 v51, 0xbfb8aa3b, v51
	v_exp_f32_e32 v64, v64
	v_exp_f32_e32 v57, v57
	v_exp_f32_e32 v51, v51
	v_add_f32_e32 v56, 1.0, v56
	v_rcp_f32_e32 v56, v56
	v_sub_f32_e32 v64, 1.0, v64
	v_add_f32_e32 v57, 1.0, v57
	v_mul_f32_e32 v60, 0x42000000, v61
	v_add_f32_e32 v51, 1.0, v51
	v_max_f32_e32 v64, 0, v64
	v_rcp_f32_e32 v57, v57
	v_med3_f32 v61, v63, s29, v231
	v_med3_f32 v60, v60, s29, v231
	v_rcp_f32_e32 v51, v51
	v_sqrt_f32_e32 v64, v64
	v_cvt_pk_fp8_f32 v62, v61, v60 op_sel:[0,0,1]
	v_lshlrev_b32_e32 v60, 16, v76
	v_mul_f32_e32 v56, v56, v132
	v_mul_f32_e32 v50, v50, v60
	v_add_f32_e32 v60, v56, v56
	v_add_f32_e32 v52, v52, v28
	v_mul_f32_e32 v60, 0x3fb8aa3b, v60
	v_mul_f32_e32 v57, v57, v133
	v_mul_f32_e32 v52, 0xbfb8aa3b, v52
	v_mul_f32_e32 v51, v51, v64
	v_exp_f32_e32 v60, v60
	v_add_f32_e32 v64, v57, v57
	v_exp_f32_e32 v52, v52
	v_add_f32_e32 v53, v53, v29
	v_mul_f32_e32 v64, 0x3fb8aa3b, v64
	v_mul_f32_e32 v53, 0xbfb8aa3b, v53
	v_exp_f32_e32 v64, v64
	v_exp_f32_e32 v53, v53
	v_sub_f32_e32 v60, 1.0, v60
	v_add_f32_e32 v52, 1.0, v52
	v_max_f32_e32 v60, 0, v60
	v_rcp_f32_e32 v52, v52
	v_sqrt_f32_e32 v60, v60
	v_sub_f32_e32 v64, 1.0, v64
	v_add_f32_e32 v53, 1.0, v53
	v_max_f32_e32 v64, 0, v64
	v_and_b32_e32 v61, 0xffff0000, v76
	v_rcp_f32_e32 v53, v53
	v_sqrt_f32_e32 v64, v64
	v_mul_f32_e32 v51, v51, v61
	v_lshlrev_b32_e32 v63, 16, v77
	v_mul_f32_e32 v52, v52, v60
	v_mul_f32_e32 v50, 0x42000000, v50
	v_mul_f32_e32 v51, 0x42000000, v51
	v_mul_f32_e32 v52, v52, v63
	v_med3_f32 v50, v50, s29, v231
	v_med3_f32 v51, v51, s29, v231
	v_and_b32_e32 v65, 0xffff0000, v77
	v_mul_f32_e32 v53, v53, v64
	v_cvt_pk_fp8_f32 v63, v50, v51
	v_mul_f32_e32 v53, v53, v65
	v_mul_f32_e32 v52, 0x42000000, v52
	v_mul_f32_e32 v50, 0x42000000, v53
	v_med3_f32 v51, v52, s29, v231
	v_med3_f32 v50, v50, s29, v231
	v_cvt_pk_fp8_f32 v63, v51, v50 op_sel:[0,0,1]
	v_add_co_u32_e32 v50, vcc, s84, v80
	v_cvt_pk_bf16_f32 v85, v92, v93
	v_cvt_pk_bf16_f32 v87, v72, v73
	v_cvt_pk_bf16_f32 v60, v54, v55
	v_cvt_pk_bf16_f32 v61, v56, v57
	v_addc_co_u32_e32 v51, vcc, 0, v81, vcc
	global_store_dwordx4 v[80:81], v[84:87], off
	global_store_dwordx2 v[78:79], v[88:89], off
	global_store_dwordx4 v[50:51], v[58:61], off
	v_add_co_u32_e32 v50, vcc, s93, v78
	s_nop 1
	v_addc_co_u32_e32 v51, vcc, 0, v79, vcc
	global_store_dwordx2 v[50:51], v[62:63], off
	v_add_co_u32_e32 v50, vcc, s92, v82
	v_add_f32_e32 v38, v38, v46
	s_nop 0
	v_addc_co_u32_e32 v51, vcc, 0, v83, vcc
	global_load_dwordx4 v[54:57], v[50:51], off
	v_mul_f32_e32 v38, 0xbfb8aa3b, v38
	v_exp_f32_e32 v38, v38
	v_add_f32_e32 v34, v34, v42
	v_mul_f32_e32 v34, 0xbfb8aa3b, v34
	v_exp_f32_e32 v34, v34
	v_add_f32_e32 v38, 1.0, v38
	v_rcp_f32_e32 v38, v38
	v_add_f32_e32 v39, v39, v47
	v_add_f32_e32 v34, 1.0, v34
	v_mul_f32_e32 v39, 0xbfb8aa3b, v39
	v_exp_f32_e32 v39, v39
	v_add_f32_e32 v35, v35, v43
	v_mul_f32_e32 v35, 0xbfb8aa3b, v35
	v_exp_f32_e32 v35, v35
	v_add_f32_e32 v39, 1.0, v39
	v_rcp_f32_e32 v39, v39
	v_add_f32_e32 v36, v36, v44
	v_add_f32_e32 v35, 1.0, v35
	v_rcp_f32_e32 v35, v35
	v_mul_f32_e32 v39, v39, v145
	v_mul_f32_e32 v36, 0xbfb8aa3b, v36
	v_exp_f32_e32 v36, v36
	v_add_co_u32_e32 v50, vcc, s89, v82
	v_add_f32_e32 v22, v22, v30
	v_add_f32_e32 v36, 1.0, v36
	v_rcp_f32_e32 v36, v36
	v_addc_co_u32_e32 v51, vcc, 0, v83, vcc
	global_load_dwordx4 v[50:53], v[50:51], off
	v_add_f32_e32 v37, v37, v45
	v_mul_f32_e32 v22, 0xbfb8aa3b, v22
	v_mul_f32_e32 v37, 0xbfb8aa3b, v37
	v_exp_f32_e32 v22, v22
	v_exp_f32_e32 v37, v37
	v_add_f32_e32 v18, v18, v26
	v_add_f32_e32 v23, v23, v31
	v_add_f32_e32 v22, 1.0, v22
	v_add_f32_e32 v37, 1.0, v37
	v_rcp_f32_e32 v22, v22
	v_rcp_f32_e32 v37, v37
	v_mul_f32_e32 v18, 0xbfb8aa3b, v18
	v_mul_f32_e32 v23, 0xbfb8aa3b, v23
	v_mul_f32_e32 v22, v22, v130
	v_exp_f32_e32 v18, v18
	v_exp_f32_e32 v23, v23
	v_add_f32_e32 v24, v24, v32
	v_add_f32_e32 v19, v19, v27
	v_add_f32_e32 v18, 1.0, v18
	v_add_f32_e32 v23, 1.0, v23
	v_rcp_f32_e32 v18, v18
	v_rcp_f32_e32 v23, v23
	v_mul_f32_e32 v24, 0xbfb8aa3b, v24
	v_mul_f32_e32 v19, 0xbfb8aa3b, v19
	v_exp_f32_e32 v24, v24
	v_mul_f32_e32 v23, v23, v131
	v_exp_f32_e32 v19, v19
	v_add_f32_e32 v25, v25, v33
	v_add_f32_e32 v24, 1.0, v24
	v_rcp_f32_e32 v24, v24
	v_add_f32_e32 v19, 1.0, v19
	v_rcp_f32_e32 v19, v19
	v_add_f32_e32 v20, v20, v28
	v_mul_f32_e32 v24, v24, v132
	v_mul_f32_e32 v25, 0xbfb8aa3b, v25
	v_mul_f32_e32 v20, 0xbfb8aa3b, v20
	v_exp_f32_e32 v25, v25
	v_exp_f32_e32 v20, v20
	v_add_f32_e32 v14, v14, v46
	v_add_f32_e32 v21, v21, v29
	v_add_f32_e32 v25, 1.0, v25
	v_add_f32_e32 v20, 1.0, v20
	v_rcp_f32_e32 v25, v25
	v_rcp_f32_e32 v20, v20
	v_mul_f32_e32 v14, 0xbfb8aa3b, v14
	v_mul_f32_e32 v21, 0xbfb8aa3b, v21
	v_mul_f32_e32 v25, v25, v133
	v_exp_f32_e32 v14, v14
	v_exp_f32_e32 v21, v21
	s_waitcnt vmcnt(0) lgkmcnt(0)
	v_lshlrev_b32_e32 v58, 16, v54
	v_and_b32_e32 v59, 0xffff0000, v54
	v_lshlrev_b32_e32 v60, 16, v55
	v_and_b32_e32 v54, 0xffff0000, v55
	v_rcp_f32_e32 v55, v34
	v_mul_f32_e32 v34, v38, v144
	v_add_f32_e32 v38, v34, v34
	v_mul_f32_e32 v38, 0x3fb8aa3b, v38
	v_exp_f32_e32 v38, v38
	v_cvt_pk_bf16_f32 v34, v34, v39
	v_add_f32_e32 v14, 1.0, v14
	v_add_f32_e32 v21, 1.0, v21
	v_sub_f32_e32 v38, 1.0, v38
	v_max_f32_e32 v38, 0, v38
	v_sqrt_f32_e32 v38, v38
	v_rcp_f32_e32 v14, v14
	v_rcp_f32_e32 v21, v21
	v_add_f32_e32 v10, v10, v42
	v_mul_f32_e32 v38, v55, v38
	v_add_f32_e32 v55, v39, v39
	v_mul_f32_e32 v55, 0x3fb8aa3b, v55
	v_exp_f32_e32 v55, v55
	v_mul_f32_e32 v38, v38, v58
	v_mul_f32_e32 v38, 0x42000000, v38
	v_mul_f32_e32 v14, v14, v144
	v_sub_f32_e32 v55, 1.0, v55
	v_max_f32_e32 v55, 0, v55
	v_sqrt_f32_e32 v55, v55
	v_mul_f32_e32 v10, 0xbfb8aa3b, v10
	v_exp_f32_e32 v10, v10
	v_add_f32_e32 v11, v11, v43
	v_mul_f32_e32 v35, v35, v55
	v_mul_f32_e32 v55, v35, v59
	v_add_f32_e32 v35, v40, v48
	v_mul_f32_e32 v35, 0xbfb8aa3b, v35
	v_exp_f32_e32 v35, v35
	v_mul_f32_e32 v39, 0x42000000, v55
	v_med3_f32 v39, v39, s29, v231
	v_add_f32_e32 v10, 1.0, v10
	v_add_f32_e32 v35, 1.0, v35
	v_rcp_f32_e32 v35, v35
	v_rcp_f32_e32 v10, v10
	v_mul_f32_e32 v11, 0xbfb8aa3b, v11
	v_exp_f32_e32 v11, v11
	v_mul_f32_e32 v35, v35, v142
	v_add_f32_e32 v40, v35, v35
	v_mul_f32_e32 v40, 0x3fb8aa3b, v40
	v_exp_f32_e32 v40, v40
	v_add_f32_e32 v11, 1.0, v11
	v_rcp_f32_e32 v11, v11
	v_add_f32_e32 v12, v12, v44
	v_sub_f32_e32 v40, 1.0, v40
	v_max_f32_e32 v40, 0, v40
	v_sqrt_f32_e32 v40, v40
	v_mul_f32_e32 v12, 0xbfb8aa3b, v12
	v_exp_f32_e32 v12, v12
	v_add_f32_e32 v6, v6, v30
	v_mul_f32_e32 v36, v36, v40
	v_add_f32_e32 v40, v41, v49
	v_mul_f32_e32 v40, 0xbfb8aa3b, v40
	v_exp_f32_e32 v40, v40
	v_mul_f32_e32 v36, v36, v60
	v_mul_f32_e32 v36, 0x42000000, v36
	v_med3_f32 v36, v36, s29, v231
	v_add_f32_e32 v40, 1.0, v40
	v_rcp_f32_e32 v40, v40
	v_add_f32_e32 v12, 1.0, v12
	v_rcp_f32_e32 v12, v12
	v_add_f32_e32 v13, v13, v45
	v_mul_f32_e32 v40, v40, v143
	v_add_f32_e32 v41, v40, v40
	v_mul_f32_e32 v41, 0x3fb8aa3b, v41
	v_exp_f32_e32 v41, v41
	v_cvt_pk_bf16_f32 v35, v35, v40
	v_med3_f32 v40, v38, s29, v231
	v_sub_f32_e32 v41, 1.0, v41
	v_max_f32_e32 v41, 0, v41
	v_sqrt_f32_e32 v41, v41
	v_cvt_pk_fp8_f32 v38, v40, v39
	v_lshlrev_b32_e32 v39, 16, v57
	v_and_b32_e32 v40, 0xffff0000, v57
	v_mul_f32_e32 v37, v37, v41
	v_add_f32_e32 v41, v22, v22
	v_mul_f32_e32 v41, 0x3fb8aa3b, v41
	v_exp_f32_e32 v41, v41
	v_mul_f32_e32 v37, v37, v54
	v_mul_f32_e32 v37, 0x42000000, v37
	v_med3_f32 v37, v37, s29, v231
	v_sub_f32_e32 v41, 1.0, v41
	v_max_f32_e32 v41, 0, v41
	v_sqrt_f32_e32 v41, v41
	v_cvt_pk_fp8_f32 v38, v36, v37 op_sel:[0,0,1]
	v_lshlrev_b32_e32 v36, 16, v56
	v_and_b32_e32 v37, 0xffff0000, v56
	v_mul_f32_e32 v18, v18, v41
	v_mul_f32_e32 v18, v18, v36
	v_add_f32_e32 v36, v23, v23
	v_mul_f32_e32 v36, 0x3fb8aa3b, v36
	v_exp_f32_e32 v36, v36
	v_mul_f32_e32 v18, 0x42000000, v18
	v_med3_f32 v18, v18, s29, v231
	v_mul_f32_e32 v6, 0xbfb8aa3b, v6
	v_sub_f32_e32 v36, 1.0, v36
	v_max_f32_e32 v36, 0, v36
	v_sqrt_f32_e32 v36, v36
	v_mul_f32_e32 v13, 0xbfb8aa3b, v13
	v_exp_f32_e32 v6, v6
	v_exp_f32_e32 v13, v13
	v_mul_f32_e32 v19, v19, v36
	v_add_f32_e32 v36, v24, v24
	v_mul_f32_e32 v36, 0x3fb8aa3b, v36
	v_exp_f32_e32 v36, v36
	v_mul_f32_e32 v19, v19, v37
	v_mul_f32_e32 v19, 0x42000000, v19
	v_med3_f32 v19, v19, s29, v231
	v_sub_f32_e32 v36, 1.0, v36
	v_max_f32_e32 v36, 0, v36
	v_sqrt_f32_e32 v36, v36
	v_cvt_pk_bf16_f32 v37, v24, v25
	v_add_f32_e32 v6, 1.0, v6
	v_add_f32_e32 v13, 1.0, v13
	v_mul_f32_e32 v20, v20, v36
	v_add_f32_e32 v36, v25, v25
	v_mul_f32_e32 v36, 0x3fb8aa3b, v36
	v_exp_f32_e32 v36, v36
	v_mul_f32_e32 v20, v20, v39
	v_cvt_pk_fp8_f32 v39, v18, v19
	v_sub_f32_e32 v36, 1.0, v36
	v_max_f32_e32 v36, 0, v36
	v_sqrt_f32_e32 v36, v36
	v_mul_f32_e32 v20, 0x42000000, v20
	v_med3_f32 v18, v20, s29, v231
	v_rcp_f32_e32 v6, v6
	v_mul_f32_e32 v21, v21, v36
	v_cvt_pk_bf16_f32 v36, v22, v23
	v_add_f32_e32 v22, v14, v14
	v_mul_f32_e32 v22, 0x3fb8aa3b, v22
	v_exp_f32_e32 v22, v22
	v_mul_f32_e32 v21, v21, v40
	v_mul_f32_e32 v21, 0x42000000, v21
	v_med3_f32 v19, v21, s29, v231
	v_sub_f32_e32 v22, 1.0, v22
	v_max_f32_e32 v22, 0, v22
	v_cvt_pk_fp8_f32 v39, v18, v19 op_sel:[0,0,1]
	v_add_co_u32_e32 v18, vcc, s92, v80
	v_sqrt_f32_e32 v22, v22
	s_nop 0
	v_addc_co_u32_e32 v19, vcc, 0, v81, vcc
	global_store_dwordx4 v[18:19], v[34:37], off
	v_add_co_u32_e32 v18, vcc, s84, v78
	v_mul_f32_e32 v10, v10, v22
	s_nop 0
	v_addc_co_u32_e32 v19, vcc, 0, v79, vcc
	global_store_dwordx2 v[18:19], v[38:39], off
	v_lshlrev_b32_e32 v18, 16, v50
	v_mul_f32_e32 v18, v10, v18
	v_add_f32_e32 v10, v15, v47
	v_mul_f32_e32 v10, 0xbfb8aa3b, v10
	v_exp_f32_e32 v10, v10
	v_and_b32_e32 v19, 0xffff0000, v50
	v_rcp_f32_e32 v13, v13
	v_mul_f32_e32 v6, v6, v130
	v_add_f32_e32 v10, 1.0, v10
	v_rcp_f32_e32 v10, v10
	v_add_f32_e32 v2, v2, v26
	v_add_f32_e32 v7, v7, v31
	v_mul_f32_e32 v2, 0xbfb8aa3b, v2
	v_mul_f32_e32 v10, v10, v145
	v_add_f32_e32 v15, v10, v10
	v_mul_f32_e32 v15, 0x3fb8aa3b, v15
	v_exp_f32_e32 v15, v15
	v_mul_f32_e32 v7, 0xbfb8aa3b, v7
	v_exp_f32_e32 v2, v2
	v_exp_f32_e32 v7, v7
	v_sub_f32_e32 v15, 1.0, v15
	v_max_f32_e32 v15, 0, v15
	v_sqrt_f32_e32 v15, v15
	v_cvt_pk_bf16_f32 v10, v14, v10
	v_mul_f32_e32 v14, 0x42000000, v18
	v_add_f32_e32 v2, 1.0, v2
	v_mul_f32_e32 v11, v11, v15
	v_mul_f32_e32 v15, v11, v19
	v_add_f32_e32 v11, v16, v48
	v_mul_f32_e32 v11, 0xbfb8aa3b, v11
	v_exp_f32_e32 v11, v11
	v_mul_f32_e32 v15, 0x42000000, v15
	v_med3_f32 v15, v15, s29, v231
	v_add_f32_e32 v7, 1.0, v7
	v_add_f32_e32 v11, 1.0, v11
	v_rcp_f32_e32 v11, v11
	v_lshlrev_b32_e32 v20, 16, v51
	v_and_b32_e32 v21, 0xffff0000, v51
	v_rcp_f32_e32 v2, v2
	v_mul_f32_e32 v11, v11, v142
	v_add_f32_e32 v16, v11, v11
	v_mul_f32_e32 v16, 0x3fb8aa3b, v16
	v_exp_f32_e32 v16, v16
	v_rcp_f32_e32 v7, v7
	v_add_f32_e32 v8, v8, v32
	v_add_f32_e32 v3, v3, v27
	v_sub_f32_e32 v16, 1.0, v16
	v_max_f32_e32 v16, 0, v16
	v_sqrt_f32_e32 v16, v16
	v_mul_f32_e32 v7, v7, v131
	v_mul_f32_e32 v8, 0xbfb8aa3b, v8
	v_mul_f32_e32 v3, 0xbfb8aa3b, v3
	v_mul_f32_e32 v12, v12, v16
	v_add_f32_e32 v16, v17, v49
	v_mul_f32_e32 v16, 0xbfb8aa3b, v16
	v_exp_f32_e32 v16, v16
	v_mul_f32_e32 v12, v12, v20
	v_mul_f32_e32 v12, 0x42000000, v12
	v_med3_f32 v12, v12, s29, v231
	v_add_f32_e32 v16, 1.0, v16
	v_rcp_f32_e32 v16, v16
	v_exp_f32_e32 v8, v8
	v_exp_f32_e32 v3, v3
	v_add_f32_e32 v9, v9, v33
	v_mul_f32_e32 v16, v16, v143
	v_add_f32_e32 v17, v16, v16
	v_mul_f32_e32 v17, 0x3fb8aa3b, v17
	v_exp_f32_e32 v17, v17
	v_cvt_pk_bf16_f32 v11, v11, v16
	v_med3_f32 v16, v14, s29, v231
	v_sub_f32_e32 v17, 1.0, v17
	v_max_f32_e32 v17, 0, v17
	v_sqrt_f32_e32 v17, v17
	v_cvt_pk_fp8_f32 v14, v16, v15
	v_add_f32_e32 v8, 1.0, v8
	v_add_f32_e32 v3, 1.0, v3
	v_mul_f32_e32 v13, v13, v17
	v_add_f32_e32 v17, v6, v6
	v_mul_f32_e32 v17, 0x3fb8aa3b, v17
	v_exp_f32_e32 v17, v17
	v_mul_f32_e32 v13, v13, v21
	v_mul_f32_e32 v13, 0x42000000, v13
	v_med3_f32 v13, v13, s29, v231
	v_sub_f32_e32 v17, 1.0, v17
	v_max_f32_e32 v17, 0, v17
	v_sqrt_f32_e32 v17, v17
	v_cvt_pk_fp8_f32 v14, v12, v13 op_sel:[0,0,1]
	v_lshlrev_b32_e32 v12, 16, v52
	v_rcp_f32_e32 v8, v8
	v_mul_f32_e32 v2, v2, v17
	v_mul_f32_e32 v2, v2, v12
	v_add_f32_e32 v12, v7, v7
	v_mul_f32_e32 v12, 0x3fb8aa3b, v12
	v_exp_f32_e32 v12, v12
	v_rcp_f32_e32 v3, v3
	v_mul_f32_e32 v8, v8, v132
	v_add_f32_e32 v4, v4, v28
	v_sub_f32_e32 v12, 1.0, v12
	v_max_f32_e32 v12, 0, v12
	v_sqrt_f32_e32 v12, v12
	v_mul_f32_e32 v9, 0xbfb8aa3b, v9
	v_mul_f32_e32 v4, 0xbfb8aa3b, v4
	v_exp_f32_e32 v9, v9
	v_mul_f32_e32 v3, v3, v12
	v_add_f32_e32 v12, v8, v8
	v_mul_f32_e32 v12, 0x3fb8aa3b, v12
	v_exp_f32_e32 v12, v12
	v_exp_f32_e32 v4, v4
	v_add_f32_e32 v9, 1.0, v9
	v_rcp_f32_e32 v9, v9
	v_sub_f32_e32 v12, 1.0, v12
	v_add_f32_e32 v4, 1.0, v4
	v_max_f32_e32 v12, 0, v12
	v_rcp_f32_e32 v4, v4
	v_sqrt_f32_e32 v12, v12
	v_mul_f32_e32 v9, v9, v133
	v_add_f32_e32 v5, v5, v29
	v_mul_f32_e32 v5, 0xbfb8aa3b, v5
	v_mul_f32_e32 v4, v4, v12
	v_add_f32_e32 v12, v9, v9
	v_mul_f32_e32 v12, 0x3fb8aa3b, v12
	v_exp_f32_e32 v12, v12
	v_exp_f32_e32 v5, v5
	v_and_b32_e32 v13, 0xffff0000, v52
	v_mul_f32_e32 v3, v3, v13
	v_sub_f32_e32 v12, 1.0, v12
	v_add_f32_e32 v5, 1.0, v5
	v_max_f32_e32 v12, 0, v12
	v_rcp_f32_e32 v5, v5
	v_sqrt_f32_e32 v12, v12
	v_lshlrev_b32_e32 v15, 16, v53
	v_mul_f32_e32 v2, 0x42000000, v2
	v_mul_f32_e32 v3, 0x42000000, v3
	v_mul_f32_e32 v4, v4, v15
	v_med3_f32 v2, v2, s29, v231
	v_med3_f32 v3, v3, s29, v231
	v_and_b32_e32 v16, 0xffff0000, v53
	v_mul_f32_e32 v5, v5, v12
	v_cvt_pk_fp8_f32 v15, v2, v3
	v_mul_f32_e32 v5, v5, v16
	v_mul_f32_e32 v4, 0x42000000, v4
	v_mul_f32_e32 v5, 0x42000000, v5
	v_med3_f32 v2, v4, s29, v231
	v_med3_f32 v3, v5, s29, v231
	v_cvt_pk_fp8_f32 v15, v2, v3 op_sel:[0,0,1]
	v_add_co_u32_e32 v2, vcc, 0x18000, v80
	v_cvt_pk_bf16_f32 v12, v6, v7
	v_cvt_pk_bf16_f32 v13, v8, v9
	v_addc_co_u32_e32 v3, vcc, 0, v81, vcc
	global_store_dwordx4 v[2:3], v[10:13], off
	v_add_co_u32_e32 v2, vcc, 0xc000, v78
	s_nop 1
	v_addc_co_u32_e32 v3, vcc, 0, v79, vcc
	global_store_dwordx2 v[2:3], v[14:15], off
	s_and_b64 vcc, exec, s[12:13]
	s_mov_b32 s82, s40
	s_mov_b32 s52, s42
	s_mov_b64 s[14:15], s[46:47]
	s_mov_b64 s[48:49], s[44:45]
	s_mov_b32 s94, s23
	s_cbranch_vccz .LBB0_1638
	s_waitcnt vmcnt(0)
	s_cmpk_gt_u32 s22, 0xff
	v_readlane_b32 s81, v253, 46
	v_readlane_b32 s80, v253, 45
	v_readlane_b32 s89, v253, 44
	s_cbranch_scc1 .LBB0_1649
	s_barrier

.LBB0_1784:
	v_bfe_u32 v166, v12, 4, 2
	s_lshl_b32 s0, s0, 5
	v_and_b32_e32 v151, 15, v12
	v_lshlrev_b32_e32 v13, 4, v166
	v_lshlrev_b32_e32 v12, 2, v12
	s_and_b32 s45, s0, 0x60
	s_lshl_b32 s44, s1, 6
	v_lshl_or_b32 v13, v151, 6, v13
	s_lshl_b32 s1, s1, 13
	v_and_b32_e32 v12, 32, v12
	s_lshl_b32 s0, s45, 7
	v_bitop3_b32 v167, v13, s0, v12 bitop3:0xde
	s_add_u32 s0, s22, 0x1800080
	v_bitop3_b32 v14, v13, s1, v12 bitop3:0xde
	s_addc_u32 s1, s23, 0
	s_add_i32 m0, s8, 0x18000
	s_waitcnt vmcnt(4)
	s_barrier
	global_load_lds_dwordx4 v156, s[0:1]
	v_lshl_add_u64 v[12:13], s[0:1], 0, v[152:153]
	s_add_i32 m0, s8, 0x1a000
	s_mov_b64 s[28:29], 0x80
	s_add_i32 s48, s8, 0x8000
	s_add_i32 s49, s8, 0xa000
	global_load_lds_dwordx4 v[12:13], off
	v_lshl_add_u64 v[4:5], v[4:5], 0, s[28:29]
	s_mov_b32 m0, s48
	s_add_u32 s0, s22, 0x1840080
	global_load_lds_dwordx4 v[4:5], off
	v_lshl_add_u64 v[2:3], v[2:3], 0, s[28:29]
	s_mov_b32 m0, s49
	s_addc_u32 s1, s23, 0
	global_load_lds_dwordx4 v[2:3], off
	s_add_i32 m0, s8, 0x1c000
	s_nop 0
	global_load_lds_dwordx4 v156, s[0:1]
	s_add_i32 m0, s8, 0x1e000
	s_add_i32 s52, 0, 0x10000
	global_load_lds_dwordx4 v152, s[0:1]
	v_lshlrev_b32_e32 v2, 14, v6
	v_and_b32_e32 v2, 0xffff8000, v2
	v_lshl_add_u32 v2, v7, 11, v2
	v_and_b32_e32 v3, 1, v6
	v_lshl_or_b32 v2, v3, 6, v2
	v_lshl_add_u32 v160, v8, 1, v2
	v_lshlrev_b32_e32 v2, 14, v10
	v_and_b32_e32 v2, 0xffff8000, v2
	s_waitcnt vmcnt(6)
	v_lshl_add_u32 v2, v9, 11, v2
	v_and_b32_e32 v3, 1, v10
	v_lshl_or_b32 v2, v3, 6, v2
	v_add_u32_e32 v168, s52, v167
	s_add_i32 s54, 0, 0x14000
	s_add_i32 s52, s52, s7
	s_mov_b32 s46, 0x18000
	s_mov_b32 s47, 0x8000
	v_mov_b32_e32 v161, v157
	v_lshl_add_u32 v162, v11, 1, v2
	v_mov_b32_e32 v163, v157
	v_add_u32_e32 v169, 0, v14
	v_add_u32_e32 v170, s54, v167
	s_mov_b32 s30, 0x3fd744fd
	s_add_i32 s50, s8, 0xc000
	s_add_i32 s51, s8, 0xe000
	s_add_i32 s53, s52, 0x2000
	s_add_i32 s54, s54, s7
	s_mov_b32 s59, s2
	s_mov_b64 s[36:37], s[24:25]
	s_mov_b32 s55, 0
	s_barrier
.LBB0_1785:
	s_add_i32 s55, s55, 1
	s_mov_b64 s[0:1], s[26:27]
	s_lshr_b32 s26, s55, 2
	s_mul_i32 s26, s26, s74
	s_mov_b64 s[38:39], s[36:37]
	s_mov_b32 s37, s56
	s_add_i32 s56, s26, s2
	s_cmpk_lt_i32 s56, 0x100
	s_cselect_b64 s[40:41], -1, 0
	s_cmpk_gt_i32 s56, 0xff
	s_mov_b32 s36, s57
	s_cselect_b64 s[34:35], -1, 0
	s_and_b32 s57, s55, 3
	s_and_b64 s[26:27], s[40:41], exec
	s_cselect_b32 s26, s56, s37
	s_cselect_b32 s36, s57, s36
	s_ashr_i32 s27, s26, 31
	s_lshl_b64 s[26:27], s[26:27], 19
	s_add_u32 s26, s5, s26
	s_addc_u32 s27, s6, s27
	s_and_b64 s[42:43], s[40:41], exec
	s_cselect_b32 s60, s27, s1
	s_cselect_b32 s61, s26, s0
	s_ashr_i32 s37, s36, 31
	s_lshl_b64 s[36:37], s[36:37], 19
	s_add_u32 s36, s24, s36
	s_addc_u32 s37, s25, s37
	s_and_b64 s[40:41], s[40:41], exec
	s_cselect_b32 s62, s37, s39
	s_cselect_b32 s63, s36, s38
	s_add_u32 s64, s38, 0x100
	s_addc_u32 s65, s39, 0
	s_add_u32 s38, s0, 0x40080
	s_addc_u32 s39, s1, 0
	s_mov_b32 s66, -2
	ds_read_b128 v[130:133], v168
	ds_read_b128 v[134:137], v168 offset:1024
	ds_read_b128 v[138:141], v168 offset:2048
	ds_read_b128 v[142:145], v168 offset:3072
	s_add_u32 s0, s38, 0xfffc0080
	s_addc_u32 s1, s39, -1
	s_cmp_eq_u32 s66, 12
	s_cselect_b32 s43, s60, s1
	s_cselect_b32 s42, s61, s0
	s_cselect_b32 s41, s62, s65
	s_cselect_b32 s40, s63, s64
	s_mov_b32 m0, s50
	ds_read_b128 v[146:149], v169
	ds_read_b128 v[172:175], v169 offset:1024
	ds_read_b128 v[176:179], v169 offset:2048
	ds_read_b128 v[180:183], v169 offset:3072
	ds_read_b128 v[184:187], v169 offset:4096
	ds_read_b128 v[188:191], v169 offset:5120
	ds_read_b128 v[192:195], v169 offset:6144
	ds_read_b128 v[196:199], v169 offset:7168
	global_load_lds_dwordx4 v162, s[38:39]
	s_mov_b32 m0, s51
	s_nop 0
	global_load_lds_dwordx4 v160, s[38:39]
	s_waitcnt lgkmcnt(8)
	s_waitcnt vmcnt(10)
	s_barrier
	s_waitcnt lgkmcnt(0)
	s_waitcnt lgkmcnt(0)
	v_mfma_f32_16x16x32_bf16 v[126:129], v[130:133], v[146:149], 0
	v_mfma_f32_16x16x32_bf16 v[122:125], v[138:141], v[146:149], 0
	v_mfma_f32_16x16x32_bf16 v[118:121], v[130:133], v[176:179], 0
	v_mfma_f32_16x16x32_bf16 v[110:113], v[138:141], v[176:179], 0
	v_mfma_f32_16x16x32_bf16 v[98:101], v[130:133], v[184:187], 0
	v_mfma_f32_16x16x32_bf16 v[90:93], v[138:141], v[184:187], 0
	v_mfma_f32_16x16x32_bf16 v[82:85], v[130:133], v[192:195], 0
	v_mfma_f32_16x16x32_bf16 v[74:77], v[138:141], v[192:195], 0
	v_mfma_f32_16x16x32_bf16 v[126:129], v[134:137], v[172:175], v[126:129]
	v_mfma_f32_16x16x32_bf16 v[122:125], v[142:145], v[172:175], v[122:125]
	v_mfma_f32_16x16x32_bf16 v[118:121], v[134:137], v[180:183], v[118:121]
	v_mfma_f32_16x16x32_bf16 v[110:113], v[142:145], v[180:183], v[110:113]
	v_mfma_f32_16x16x32_bf16 v[98:101], v[134:137], v[188:191], v[98:101]
	v_mfma_f32_16x16x32_bf16 v[90:93], v[142:145], v[188:191], v[90:93]
	v_mfma_f32_16x16x32_bf16 v[82:85], v[134:137], v[196:199], v[82:85]
	v_mfma_f32_16x16x32_bf16 v[74:77], v[142:145], v[196:199], v[74:77]
	s_barrier
	s_mov_b32 m0, s52
	v_lshl_add_u64 v[164:165], s[40:41], 0, v[156:157]
	ds_read_b128 v[200:203], v170
	ds_read_b128 v[204:207], v170 offset:1024
	ds_read_b128 v[208:211], v170 offset:2048
	ds_read_b128 v[212:215], v170 offset:3072
	global_load_lds_dwordx4 v[164:165], off
	v_lshl_add_u64 v[216:217], s[40:41], 0, v[152:153]
	s_mov_b32 m0, s53
	s_nop 0
	global_load_lds_dwordx4 v[216:217], off
	s_waitcnt vmcnt(10)
	s_barrier
	s_waitcnt lgkmcnt(0)
	s_waitcnt lgkmcnt(0)
	v_mfma_f32_16x16x32_bf16 v[114:117], v[200:203], v[146:149], 0
	v_mfma_f32_16x16x32_bf16 v[106:109], v[208:211], v[146:149], 0
	v_mfma_f32_16x16x32_bf16 v[102:105], v[200:203], v[176:179], 0
	v_mfma_f32_16x16x32_bf16 v[94:97], v[208:211], v[176:179], 0
	v_mfma_f32_16x16x32_bf16 v[86:89], v[200:203], v[184:187], 0
	v_mfma_f32_16x16x32_bf16 v[78:81], v[208:211], v[184:187], 0
	v_mfma_f32_16x16x32_bf16 v[70:73], v[200:203], v[192:195], 0
	v_mfma_f32_16x16x32_bf16 v[66:69], v[208:211], v[192:195], 0
	v_mfma_f32_16x16x32_bf16 v[114:117], v[204:207], v[172:175], v[114:117]
	v_mfma_f32_16x16x32_bf16 v[106:109], v[212:215], v[172:175], v[106:109]
	v_mfma_f32_16x16x32_bf16 v[102:105], v[204:207], v[180:183], v[102:105]
	v_mfma_f32_16x16x32_bf16 v[94:97], v[212:215], v[180:183], v[94:97]
	v_mfma_f32_16x16x32_bf16 v[86:89], v[204:207], v[188:191], v[86:89]
	v_mfma_f32_16x16x32_bf16 v[78:81], v[212:215], v[188:191], v[78:81]
	v_mfma_f32_16x16x32_bf16 v[70:73], v[204:207], v[196:199], v[70:73]
	v_mfma_f32_16x16x32_bf16 v[66:69], v[212:215], v[196:199], v[66:69]
	s_mov_b32 m0, s8
	v_lshl_add_u64 v[218:219], s[42:43], 0, v[158:159]
	s_barrier
	ds_read_b128 v[146:149], v169 offset:16384
	ds_read_b128 v[172:175], v169 offset:17408
	ds_read_b128 v[176:179], v169 offset:18432
	ds_read_b128 v[180:183], v169 offset:19456
	ds_read_b128 v[184:187], v169 offset:20480
	ds_read_b128 v[188:191], v169 offset:21504
	ds_read_b128 v[192:195], v169 offset:22528
	ds_read_b128 v[196:199], v169 offset:23552
	global_load_lds_dwordx4 v[218:219], off
	v_lshl_add_u64 v[220:221], s[42:43], 0, v[154:155]
	s_mov_b32 m0, s9
	s_nop 0
	global_load_lds_dwordx4 v[220:221], off
	s_waitcnt vmcnt(10)
	s_barrier
	s_waitcnt lgkmcnt(0)
	s_waitcnt lgkmcnt(0)
	v_mfma_f32_16x16x32_bf16 v[62:65], v[130:133], v[146:149], 0
	v_mfma_f32_16x16x32_bf16 v[58:61], v[138:141], v[146:149], 0
	v_mfma_f32_16x16x32_bf16 v[50:53], v[130:133], v[176:179], 0
	v_mfma_f32_16x16x32_bf16 v[42:45], v[138:141], v[176:179], 0
	v_mfma_f32_16x16x32_bf16 v[34:37], v[130:133], v[184:187], 0
	v_mfma_f32_16x16x32_bf16 v[26:29], v[138:141], v[184:187], 0
	v_mfma_f32_16x16x32_bf16 v[18:21], v[130:133], v[192:195], 0
	v_mfma_f32_16x16x32_bf16 v[10:13], v[138:141], v[192:195], 0
	v_mfma_f32_16x16x32_bf16 v[62:65], v[134:137], v[172:175], v[62:65]
	v_mfma_f32_16x16x32_bf16 v[58:61], v[142:145], v[172:175], v[58:61]
	v_mfma_f32_16x16x32_bf16 v[50:53], v[134:137], v[180:183], v[50:53]
	v_mfma_f32_16x16x32_bf16 v[42:45], v[142:145], v[180:183], v[42:45]
	v_mfma_f32_16x16x32_bf16 v[34:37], v[134:137], v[188:191], v[34:37]
	v_mfma_f32_16x16x32_bf16 v[26:29], v[142:145], v[188:191], v[26:29]
	v_mfma_f32_16x16x32_bf16 v[18:21], v[134:137], v[196:199], v[18:21]
	v_mfma_f32_16x16x32_bf16 v[10:13], v[142:145], v[196:199], v[10:13]
	s_barrier
	s_add_u32 s0, s40, 0x40000
	s_addc_u32 s1, s41, 0
	s_mov_b32 m0, s54
	s_nop 0
	global_load_lds_dwordx4 v156, s[0:1]
	s_add_i32 m0, s54, 0x2000
	s_nop 0
	global_load_lds_dwordx4 v152, s[0:1]
	s_waitcnt vmcnt(10)
	s_barrier
	v_mfma_f32_16x16x32_bf16 v[54:57], v[200:203], v[146:149], 0
	v_mfma_f32_16x16x32_bf16 v[46:49], v[208:211], v[146:149], 0
	v_mfma_f32_16x16x32_bf16 v[38:41], v[200:203], v[176:179], 0
	v_mfma_f32_16x16x32_bf16 v[30:33], v[208:211], v[176:179], 0
	v_mfma_f32_16x16x32_bf16 v[22:25], v[200:203], v[184:187], 0
	v_mfma_f32_16x16x32_bf16 v[14:17], v[208:211], v[184:187], 0
	v_mfma_f32_16x16x32_bf16 v[6:9], v[200:203], v[192:195], 0
	v_mfma_f32_16x16x32_bf16 v[2:5], v[208:211], v[192:195], 0
	v_mfma_f32_16x16x32_bf16 v[54:57], v[204:207], v[172:175], v[54:57]
	v_mfma_f32_16x16x32_bf16 v[46:49], v[212:215], v[172:175], v[46:49]
	v_mfma_f32_16x16x32_bf16 v[38:41], v[204:207], v[180:183], v[38:41]
	v_mfma_f32_16x16x32_bf16 v[30:33], v[212:215], v[180:183], v[30:33]
	v_mfma_f32_16x16x32_bf16 v[22:25], v[204:207], v[188:191], v[22:25]
	v_mfma_f32_16x16x32_bf16 v[14:17], v[212:215], v[188:191], v[14:17]
	v_mfma_f32_16x16x32_bf16 v[6:9], v[204:207], v[196:199], v[6:9]
	v_mfma_f32_16x16x32_bf16 v[2:5], v[212:215], v[196:199], v[2:5]
	s_add_i32 s67, 0, 0x18000
	v_add_u32_e32 v142, s67, v167
	s_barrier
	ds_read_b128 v[130:133], v142
	ds_read_b128 v[134:137], v142 offset:1024
	ds_read_b128 v[138:141], v142 offset:2048
	ds_read_b128 v[142:145], v142 offset:3072
	s_add_u32 s0, s42, 0x40000
	s_addc_u32 s1, s43, 0
	s_mov_b32 m0, s10
	ds_read_b128 v[146:149], v169 offset:32768
	ds_read_b128 v[172:175], v169 offset:33792
	ds_read_b128 v[176:179], v169 offset:34816
	ds_read_b128 v[180:183], v169 offset:35840
	ds_read_b128 v[184:187], v169 offset:36864
	ds_read_b128 v[188:191], v169 offset:37888
	ds_read_b128 v[192:195], v169 offset:38912
	ds_read_b128 v[196:199], v169 offset:39936
	global_load_lds_dwordx4 v158, s[0:1]
	s_mov_b32 m0, s11
	s_nop 0
	global_load_lds_dwordx4 v154, s[0:1]
	s_waitcnt lgkmcnt(8)
	s_waitcnt vmcnt(10)
	s_barrier
	s_waitcnt lgkmcnt(0)
	s_waitcnt lgkmcnt(0)
	v_mfma_f32_16x16x32_bf16 v[126:129], v[130:133], v[146:149], v[126:129]
	v_mfma_f32_16x16x32_bf16 v[122:125], v[138:141], v[146:149], v[122:125]
	v_mfma_f32_16x16x32_bf16 v[118:121], v[130:133], v[176:179], v[118:121]
	v_mfma_f32_16x16x32_bf16 v[110:113], v[138:141], v[176:179], v[110:113]
	v_mfma_f32_16x16x32_bf16 v[98:101], v[130:133], v[184:187], v[98:101]
	v_mfma_f32_16x16x32_bf16 v[90:93], v[138:141], v[184:187], v[90:93]
	v_mfma_f32_16x16x32_bf16 v[82:85], v[130:133], v[192:195], v[82:85]
	v_mfma_f32_16x16x32_bf16 v[74:77], v[138:141], v[192:195], v[74:77]
	v_mfma_f32_16x16x32_bf16 v[126:129], v[134:137], v[172:175], v[126:129]
	v_mfma_f32_16x16x32_bf16 v[122:125], v[142:145], v[172:175], v[122:125]
	v_mfma_f32_16x16x32_bf16 v[118:121], v[134:137], v[180:183], v[118:121]
	v_mfma_f32_16x16x32_bf16 v[110:113], v[142:145], v[180:183], v[110:113]
	v_mfma_f32_16x16x32_bf16 v[98:101], v[134:137], v[188:191], v[98:101]
	v_mfma_f32_16x16x32_bf16 v[90:93], v[142:145], v[188:191], v[90:93]
	v_mfma_f32_16x16x32_bf16 v[82:85], v[134:137], v[196:199], v[82:85]
	v_mfma_f32_16x16x32_bf16 v[74:77], v[142:145], v[196:199], v[74:77]
	s_barrier
	s_add_i32 s42, 0, 0x1c000
	s_add_i32 s0, s67, s7
	v_add_u32_e32 v171, s42, v167
	v_lshl_add_u64 v[164:165], v[164:165], 0, s[28:29]
	s_mov_b32 m0, s0
	ds_read_b128 v[200:203], v171
	ds_read_b128 v[204:207], v171 offset:1024
	ds_read_b128 v[208:211], v171 offset:2048
	ds_read_b128 v[212:215], v171 offset:3072
	global_load_lds_dwordx4 v[164:165], off
	v_lshl_add_u64 v[164:165], v[216:217], 0, s[28:29]
	s_add_i32 m0, s0, 0x2000
	s_nop 0
	global_load_lds_dwordx4 v[164:165], off
	s_waitcnt vmcnt(10)
	s_barrier
	s_waitcnt lgkmcnt(0)
	s_waitcnt lgkmcnt(0)
	v_mfma_f32_16x16x32_bf16 v[114:117], v[200:203], v[146:149], v[114:117]
	v_mfma_f32_16x16x32_bf16 v[106:109], v[208:211], v[146:149], v[106:109]
	v_mfma_f32_16x16x32_bf16 v[102:105], v[200:203], v[176:179], v[102:105]
	v_mfma_f32_16x16x32_bf16 v[94:97], v[208:211], v[176:179], v[94:97]
	v_mfma_f32_16x16x32_bf16 v[86:89], v[200:203], v[184:187], v[86:89]
	v_mfma_f32_16x16x32_bf16 v[78:81], v[208:211], v[184:187], v[78:81]
	v_mfma_f32_16x16x32_bf16 v[70:73], v[200:203], v[192:195], v[70:73]
	v_mfma_f32_16x16x32_bf16 v[66:69], v[208:211], v[192:195], v[66:69]
	v_mfma_f32_16x16x32_bf16 v[114:117], v[204:207], v[172:175], v[114:117]
	v_mfma_f32_16x16x32_bf16 v[106:109], v[212:215], v[172:175], v[106:109]
	v_mfma_f32_16x16x32_bf16 v[102:105], v[204:207], v[180:183], v[102:105]
	v_mfma_f32_16x16x32_bf16 v[94:97], v[212:215], v[180:183], v[94:97]
	v_mfma_f32_16x16x32_bf16 v[86:89], v[204:207], v[188:191], v[86:89]
	v_mfma_f32_16x16x32_bf16 v[78:81], v[212:215], v[188:191], v[78:81]
	v_mfma_f32_16x16x32_bf16 v[70:73], v[204:207], v[196:199], v[70:73]
	v_mfma_f32_16x16x32_bf16 v[66:69], v[212:215], v[196:199], v[66:69]
	s_mov_b32 m0, s48
	v_lshl_add_u64 v[164:165], v[218:219], 0, s[28:29]
	s_barrier
	ds_read_b128 v[146:149], v169 offset:49152
	ds_read_b128 v[172:175], v169 offset:50176
	ds_read_b128 v[176:179], v169 offset:51200
	ds_read_b128 v[180:183], v169 offset:52224
	ds_read_b128 v[184:187], v169 offset:53248
	ds_read_b128 v[188:191], v169 offset:54272
	ds_read_b128 v[192:195], v169 offset:55296
	ds_read_b128 v[196:199], v169 offset:56320
	global_load_lds_dwordx4 v[164:165], off
	v_lshl_add_u64 v[164:165], v[220:221], 0, s[28:29]
	s_mov_b32 m0, s49
	s_nop 0
	global_load_lds_dwordx4 v[164:165], off
	s_waitcnt vmcnt(10)
	s_barrier
	s_waitcnt lgkmcnt(0)
	s_waitcnt lgkmcnt(0)
	v_mfma_f32_16x16x32_bf16 v[62:65], v[130:133], v[146:149], v[62:65]
	v_mfma_f32_16x16x32_bf16 v[58:61], v[138:141], v[146:149], v[58:61]
	v_mfma_f32_16x16x32_bf16 v[50:53], v[130:133], v[176:179], v[50:53]
	v_mfma_f32_16x16x32_bf16 v[42:45], v[138:141], v[176:179], v[42:45]
	v_mfma_f32_16x16x32_bf16 v[34:37], v[130:133], v[184:187], v[34:37]
	v_mfma_f32_16x16x32_bf16 v[26:29], v[138:141], v[184:187], v[26:29]
	v_mfma_f32_16x16x32_bf16 v[18:21], v[130:133], v[192:195], v[18:21]
	v_mfma_f32_16x16x32_bf16 v[10:13], v[138:141], v[192:195], v[10:13]
	v_mfma_f32_16x16x32_bf16 v[62:65], v[134:137], v[172:175], v[62:65]
	v_mfma_f32_16x16x32_bf16 v[58:61], v[142:145], v[172:175], v[58:61]
	v_mfma_f32_16x16x32_bf16 v[50:53], v[134:137], v[180:183], v[50:53]
	v_mfma_f32_16x16x32_bf16 v[42:45], v[142:145], v[180:183], v[42:45]
	v_mfma_f32_16x16x32_bf16 v[34:37], v[134:137], v[188:191], v[34:37]
	v_mfma_f32_16x16x32_bf16 v[26:29], v[142:145], v[188:191], v[26:29]
	v_mfma_f32_16x16x32_bf16 v[18:21], v[134:137], v[196:199], v[18:21]
	v_mfma_f32_16x16x32_bf16 v[10:13], v[142:145], v[196:199], v[10:13]
	s_barrier
	s_add_u32 s0, s40, 0x40080
	s_addc_u32 s1, s41, 0
	s_add_i32 s40, s42, s7
	s_mov_b32 m0, s40
	s_nop 0
	global_load_lds_dwordx4 v156, s[0:1]
	s_add_i32 m0, s40, 0x2000
	s_nop 0
	global_load_lds_dwordx4 v152, s[0:1]
	s_waitcnt vmcnt(10)
	s_barrier
	v_mfma_f32_16x16x32_bf16 v[54:57], v[200:203], v[146:149], v[54:57]
	v_mfma_f32_16x16x32_bf16 v[46:49], v[208:211], v[146:149], v[46:49]
	v_mfma_f32_16x16x32_bf16 v[38:41], v[200:203], v[176:179], v[38:41]
	v_mfma_f32_16x16x32_bf16 v[30:33], v[208:211], v[176:179], v[30:33]
	v_mfma_f32_16x16x32_bf16 v[22:25], v[200:203], v[184:187], v[22:25]
	v_mfma_f32_16x16x32_bf16 v[14:17], v[208:211], v[184:187], v[14:17]
	v_mfma_f32_16x16x32_bf16 v[6:9], v[200:203], v[192:195], v[6:9]
	v_mfma_f32_16x16x32_bf16 v[2:5], v[208:211], v[192:195], v[2:5]
	v_mfma_f32_16x16x32_bf16 v[54:57], v[204:207], v[172:175], v[54:57]
	v_mfma_f32_16x16x32_bf16 v[46:49], v[212:215], v[172:175], v[46:49]
	v_mfma_f32_16x16x32_bf16 v[38:41], v[204:207], v[180:183], v[38:41]
	v_mfma_f32_16x16x32_bf16 v[30:33], v[212:215], v[180:183], v[30:33]
	v_mfma_f32_16x16x32_bf16 v[22:25], v[204:207], v[188:191], v[22:25]
	v_mfma_f32_16x16x32_bf16 v[14:17], v[212:215], v[188:191], v[14:17]
	v_mfma_f32_16x16x32_bf16 v[6:9], v[204:207], v[196:199], v[6:9]
	v_mfma_f32_16x16x32_bf16 v[2:5], v[212:215], v[196:199], v[2:5]
	s_add_i32 s66, s66, 2
	s_add_u32 s64, s64, 0x100
	s_addc_u32 s65, s65, 0
	s_add_u32 s38, s38, 0x100
	s_addc_u32 s39, s39, 0
	s_cmp_gt_u32 s66, 13
	s_barrier
	s_cbranch_scc1 .Lpeel_exit_10
.LBB0_1786:
	ds_read_b128 v[130:133], v168
	ds_read_b128 v[134:137], v168 offset:1024
	ds_read_b128 v[138:141], v168 offset:2048
	ds_read_b128 v[142:145], v168 offset:3072
	s_add_u32 s0, s38, 0xfffc0080
	s_addc_u32 s1, s39, -1
	s_cmp_eq_u32 s66, 12
	s_cselect_b32 s43, s60, s1
	s_cselect_b32 s42, s61, s0
	s_cselect_b32 s41, s62, s65
	s_cselect_b32 s40, s63, s64
	s_mov_b32 m0, s50
	ds_read_b128 v[146:149], v169
	ds_read_b128 v[172:175], v169 offset:1024
	ds_read_b128 v[176:179], v169 offset:2048
	ds_read_b128 v[180:183], v169 offset:3072
	ds_read_b128 v[184:187], v169 offset:4096
	ds_read_b128 v[188:191], v169 offset:5120
	ds_read_b128 v[192:195], v169 offset:6144
	ds_read_b128 v[196:199], v169 offset:7168
	global_load_lds_dwordx4 v162, s[38:39]
	s_mov_b32 m0, s51
	s_nop 0
	global_load_lds_dwordx4 v160, s[38:39]
	s_waitcnt lgkmcnt(8)
	s_waitcnt vmcnt(10)
	s_barrier
	s_waitcnt lgkmcnt(0)
	s_waitcnt lgkmcnt(0)
	v_mfma_f32_16x16x32_bf16 v[126:129], v[130:133], v[146:149], v[126:129]
	v_mfma_f32_16x16x32_bf16 v[122:125], v[138:141], v[146:149], v[122:125]
	v_mfma_f32_16x16x32_bf16 v[118:121], v[130:133], v[176:179], v[118:121]
	v_mfma_f32_16x16x32_bf16 v[110:113], v[138:141], v[176:179], v[110:113]
	v_mfma_f32_16x16x32_bf16 v[98:101], v[130:133], v[184:187], v[98:101]
	v_mfma_f32_16x16x32_bf16 v[90:93], v[138:141], v[184:187], v[90:93]
	v_mfma_f32_16x16x32_bf16 v[82:85], v[130:133], v[192:195], v[82:85]
	v_mfma_f32_16x16x32_bf16 v[74:77], v[138:141], v[192:195], v[74:77]
	v_mfma_f32_16x16x32_bf16 v[126:129], v[134:137], v[172:175], v[126:129]
	v_mfma_f32_16x16x32_bf16 v[122:125], v[142:145], v[172:175], v[122:125]
	v_mfma_f32_16x16x32_bf16 v[118:121], v[134:137], v[180:183], v[118:121]
	v_mfma_f32_16x16x32_bf16 v[110:113], v[142:145], v[180:183], v[110:113]
	v_mfma_f32_16x16x32_bf16 v[98:101], v[134:137], v[188:191], v[98:101]
	v_mfma_f32_16x16x32_bf16 v[90:93], v[142:145], v[188:191], v[90:93]
	v_mfma_f32_16x16x32_bf16 v[82:85], v[134:137], v[196:199], v[82:85]
	v_mfma_f32_16x16x32_bf16 v[74:77], v[142:145], v[196:199], v[74:77]
	s_barrier
	s_mov_b32 m0, s52
	v_lshl_add_u64 v[164:165], s[40:41], 0, v[156:157]
	ds_read_b128 v[200:203], v170
	ds_read_b128 v[204:207], v170 offset:1024
	ds_read_b128 v[208:211], v170 offset:2048
	ds_read_b128 v[212:215], v170 offset:3072
	global_load_lds_dwordx4 v[164:165], off
	v_lshl_add_u64 v[216:217], s[40:41], 0, v[152:153]
	s_mov_b32 m0, s53
	s_nop 0
	global_load_lds_dwordx4 v[216:217], off
	s_waitcnt vmcnt(10)
	s_barrier
	s_waitcnt lgkmcnt(0)
	s_waitcnt lgkmcnt(0)
	v_mfma_f32_16x16x32_bf16 v[114:117], v[200:203], v[146:149], v[114:117]
	v_mfma_f32_16x16x32_bf16 v[106:109], v[208:211], v[146:149], v[106:109]
	v_mfma_f32_16x16x32_bf16 v[102:105], v[200:203], v[176:179], v[102:105]
	v_mfma_f32_16x16x32_bf16 v[94:97], v[208:211], v[176:179], v[94:97]
	v_mfma_f32_16x16x32_bf16 v[86:89], v[200:203], v[184:187], v[86:89]
	v_mfma_f32_16x16x32_bf16 v[78:81], v[208:211], v[184:187], v[78:81]
	v_mfma_f32_16x16x32_bf16 v[70:73], v[200:203], v[192:195], v[70:73]
	v_mfma_f32_16x16x32_bf16 v[66:69], v[208:211], v[192:195], v[66:69]
	v_mfma_f32_16x16x32_bf16 v[114:117], v[204:207], v[172:175], v[114:117]
	v_mfma_f32_16x16x32_bf16 v[106:109], v[212:215], v[172:175], v[106:109]
	v_mfma_f32_16x16x32_bf16 v[102:105], v[204:207], v[180:183], v[102:105]
	v_mfma_f32_16x16x32_bf16 v[94:97], v[212:215], v[180:183], v[94:97]
	v_mfma_f32_16x16x32_bf16 v[86:89], v[204:207], v[188:191], v[86:89]
	v_mfma_f32_16x16x32_bf16 v[78:81], v[212:215], v[188:191], v[78:81]
	v_mfma_f32_16x16x32_bf16 v[70:73], v[204:207], v[196:199], v[70:73]
	v_mfma_f32_16x16x32_bf16 v[66:69], v[212:215], v[196:199], v[66:69]
	s_mov_b32 m0, s8
	v_lshl_add_u64 v[218:219], s[42:43], 0, v[158:159]
	s_barrier
	ds_read_b128 v[146:149], v169 offset:16384
	ds_read_b128 v[172:175], v169 offset:17408
	ds_read_b128 v[176:179], v169 offset:18432
	ds_read_b128 v[180:183], v169 offset:19456
	ds_read_b128 v[184:187], v169 offset:20480
	ds_read_b128 v[188:191], v169 offset:21504
	ds_read_b128 v[192:195], v169 offset:22528
	ds_read_b128 v[196:199], v169 offset:23552
	global_load_lds_dwordx4 v[218:219], off
	v_lshl_add_u64 v[220:221], s[42:43], 0, v[154:155]
	s_mov_b32 m0, s9
	s_nop 0
	global_load_lds_dwordx4 v[220:221], off
	s_waitcnt vmcnt(10)
	s_barrier
	s_waitcnt lgkmcnt(0)
	s_waitcnt lgkmcnt(0)
	v_mfma_f32_16x16x32_bf16 v[62:65], v[130:133], v[146:149], v[62:65]
	v_mfma_f32_16x16x32_bf16 v[58:61], v[138:141], v[146:149], v[58:61]
	v_mfma_f32_16x16x32_bf16 v[50:53], v[130:133], v[176:179], v[50:53]
	v_mfma_f32_16x16x32_bf16 v[42:45], v[138:141], v[176:179], v[42:45]
	v_mfma_f32_16x16x32_bf16 v[34:37], v[130:133], v[184:187], v[34:37]
	v_mfma_f32_16x16x32_bf16 v[26:29], v[138:141], v[184:187], v[26:29]
	v_mfma_f32_16x16x32_bf16 v[18:21], v[130:133], v[192:195], v[18:21]
	v_mfma_f32_16x16x32_bf16 v[10:13], v[138:141], v[192:195], v[10:13]
	v_mfma_f32_16x16x32_bf16 v[62:65], v[134:137], v[172:175], v[62:65]
	v_mfma_f32_16x16x32_bf16 v[58:61], v[142:145], v[172:175], v[58:61]
	v_mfma_f32_16x16x32_bf16 v[50:53], v[134:137], v[180:183], v[50:53]
	v_mfma_f32_16x16x32_bf16 v[42:45], v[142:145], v[180:183], v[42:45]
	v_mfma_f32_16x16x32_bf16 v[34:37], v[134:137], v[188:191], v[34:37]
	v_mfma_f32_16x16x32_bf16 v[26:29], v[142:145], v[188:191], v[26:29]
	v_mfma_f32_16x16x32_bf16 v[18:21], v[134:137], v[196:199], v[18:21]
	v_mfma_f32_16x16x32_bf16 v[10:13], v[142:145], v[196:199], v[10:13]
	s_barrier
	s_add_u32 s0, s40, 0x40000
	s_addc_u32 s1, s41, 0
	s_mov_b32 m0, s54
	s_nop 0
	global_load_lds_dwordx4 v156, s[0:1]
	s_add_i32 m0, s54, 0x2000
	s_nop 0
	global_load_lds_dwordx4 v152, s[0:1]
	s_waitcnt vmcnt(10)
	s_barrier
	v_mfma_f32_16x16x32_bf16 v[54:57], v[200:203], v[146:149], v[54:57]
	v_mfma_f32_16x16x32_bf16 v[46:49], v[208:211], v[146:149], v[46:49]
	v_mfma_f32_16x16x32_bf16 v[38:41], v[200:203], v[176:179], v[38:41]
	v_mfma_f32_16x16x32_bf16 v[30:33], v[208:211], v[176:179], v[30:33]
	v_mfma_f32_16x16x32_bf16 v[22:25], v[200:203], v[184:187], v[22:25]
	v_mfma_f32_16x16x32_bf16 v[14:17], v[208:211], v[184:187], v[14:17]
	v_mfma_f32_16x16x32_bf16 v[6:9], v[200:203], v[192:195], v[6:9]
	v_mfma_f32_16x16x32_bf16 v[2:5], v[208:211], v[192:195], v[2:5]
	v_mfma_f32_16x16x32_bf16 v[54:57], v[204:207], v[172:175], v[54:57]
	v_mfma_f32_16x16x32_bf16 v[46:49], v[212:215], v[172:175], v[46:49]
	v_mfma_f32_16x16x32_bf16 v[38:41], v[204:207], v[180:183], v[38:41]
	v_mfma_f32_16x16x32_bf16 v[30:33], v[212:215], v[180:183], v[30:33]
	v_mfma_f32_16x16x32_bf16 v[22:25], v[204:207], v[188:191], v[22:25]
	v_mfma_f32_16x16x32_bf16 v[14:17], v[212:215], v[188:191], v[14:17]
	v_mfma_f32_16x16x32_bf16 v[6:9], v[204:207], v[196:199], v[6:9]
	v_mfma_f32_16x16x32_bf16 v[2:5], v[212:215], v[196:199], v[2:5]
	s_add_i32 s67, 0, 0x18000
	v_add_u32_e32 v142, s67, v167
	s_barrier
	ds_read_b128 v[130:133], v142
	ds_read_b128 v[134:137], v142 offset:1024
	ds_read_b128 v[138:141], v142 offset:2048
	ds_read_b128 v[142:145], v142 offset:3072
	s_add_u32 s0, s42, 0x40000
	s_addc_u32 s1, s43, 0
	s_mov_b32 m0, s10
	ds_read_b128 v[146:149], v169 offset:32768
	ds_read_b128 v[172:175], v169 offset:33792
	ds_read_b128 v[176:179], v169 offset:34816
	ds_read_b128 v[180:183], v169 offset:35840
	ds_read_b128 v[184:187], v169 offset:36864
	ds_read_b128 v[188:191], v169 offset:37888
	ds_read_b128 v[192:195], v169 offset:38912
	ds_read_b128 v[196:199], v169 offset:39936
	global_load_lds_dwordx4 v158, s[0:1]
	s_mov_b32 m0, s11
	s_nop 0
	global_load_lds_dwordx4 v154, s[0:1]
	s_waitcnt lgkmcnt(8)
	s_waitcnt vmcnt(10)
	s_barrier
	s_waitcnt lgkmcnt(0)
	s_waitcnt lgkmcnt(0)
	v_mfma_f32_16x16x32_bf16 v[126:129], v[130:133], v[146:149], v[126:129]
	v_mfma_f32_16x16x32_bf16 v[122:125], v[138:141], v[146:149], v[122:125]
	v_mfma_f32_16x16x32_bf16 v[118:121], v[130:133], v[176:179], v[118:121]
	v_mfma_f32_16x16x32_bf16 v[110:113], v[138:141], v[176:179], v[110:113]
	v_mfma_f32_16x16x32_bf16 v[98:101], v[130:133], v[184:187], v[98:101]
	v_mfma_f32_16x16x32_bf16 v[90:93], v[138:141], v[184:187], v[90:93]
	v_mfma_f32_16x16x32_bf16 v[82:85], v[130:133], v[192:195], v[82:85]
	v_mfma_f32_16x16x32_bf16 v[74:77], v[138:141], v[192:195], v[74:77]
	v_mfma_f32_16x16x32_bf16 v[126:129], v[134:137], v[172:175], v[126:129]
	v_mfma_f32_16x16x32_bf16 v[122:125], v[142:145], v[172:175], v[122:125]
	v_mfma_f32_16x16x32_bf16 v[118:121], v[134:137], v[180:183], v[118:121]
	v_mfma_f32_16x16x32_bf16 v[110:113], v[142:145], v[180:183], v[110:113]
	v_mfma_f32_16x16x32_bf16 v[98:101], v[134:137], v[188:191], v[98:101]
	v_mfma_f32_16x16x32_bf16 v[90:93], v[142:145], v[188:191], v[90:93]
	v_mfma_f32_16x16x32_bf16 v[82:85], v[134:137], v[196:199], v[82:85]
	v_mfma_f32_16x16x32_bf16 v[74:77], v[142:145], v[196:199], v[74:77]
	s_barrier
	s_add_i32 s42, 0, 0x1c000
	s_add_i32 s0, s67, s7
	v_add_u32_e32 v171, s42, v167
	v_lshl_add_u64 v[164:165], v[164:165], 0, s[28:29]
	s_mov_b32 m0, s0
	ds_read_b128 v[200:203], v171
	ds_read_b128 v[204:207], v171 offset:1024
	ds_read_b128 v[208:211], v171 offset:2048
	ds_read_b128 v[212:215], v171 offset:3072
	global_load_lds_dwordx4 v[164:165], off
	v_lshl_add_u64 v[164:165], v[216:217], 0, s[28:29]
	s_add_i32 m0, s0, 0x2000
	s_nop 0
	global_load_lds_dwordx4 v[164:165], off
	s_waitcnt vmcnt(10)
	s_barrier
	s_waitcnt lgkmcnt(0)
	s_waitcnt lgkmcnt(0)
	v_mfma_f32_16x16x32_bf16 v[114:117], v[200:203], v[146:149], v[114:117]
	v_mfma_f32_16x16x32_bf16 v[106:109], v[208:211], v[146:149], v[106:109]
	v_mfma_f32_16x16x32_bf16 v[102:105], v[200:203], v[176:179], v[102:105]
	v_mfma_f32_16x16x32_bf16 v[94:97], v[208:211], v[176:179], v[94:97]
	v_mfma_f32_16x16x32_bf16 v[86:89], v[200:203], v[184:187], v[86:89]
	v_mfma_f32_16x16x32_bf16 v[78:81], v[208:211], v[184:187], v[78:81]
	v_mfma_f32_16x16x32_bf16 v[70:73], v[200:203], v[192:195], v[70:73]
	v_mfma_f32_16x16x32_bf16 v[66:69], v[208:211], v[192:195], v[66:69]
	v_mfma_f32_16x16x32_bf16 v[114:117], v[204:207], v[172:175], v[114:117]
	v_mfma_f32_16x16x32_bf16 v[106:109], v[212:215], v[172:175], v[106:109]
	v_mfma_f32_16x16x32_bf16 v[102:105], v[204:207], v[180:183], v[102:105]
	v_mfma_f32_16x16x32_bf16 v[94:97], v[212:215], v[180:183], v[94:97]
	v_mfma_f32_16x16x32_bf16 v[86:89], v[204:207], v[188:191], v[86:89]
	v_mfma_f32_16x16x32_bf16 v[78:81], v[212:215], v[188:191], v[78:81]
	v_mfma_f32_16x16x32_bf16 v[70:73], v[204:207], v[196:199], v[70:73]
	v_mfma_f32_16x16x32_bf16 v[66:69], v[212:215], v[196:199], v[66:69]
	s_mov_b32 m0, s48
	v_lshl_add_u64 v[164:165], v[218:219], 0, s[28:29]
	s_barrier
	ds_read_b128 v[146:149], v169 offset:49152
	ds_read_b128 v[172:175], v169 offset:50176
	ds_read_b128 v[176:179], v169 offset:51200
	ds_read_b128 v[180:183], v169 offset:52224
	ds_read_b128 v[184:187], v169 offset:53248
	ds_read_b128 v[188:191], v169 offset:54272
	ds_read_b128 v[192:195], v169 offset:55296
	ds_read_b128 v[196:199], v169 offset:56320
	global_load_lds_dwordx4 v[164:165], off
	v_lshl_add_u64 v[164:165], v[220:221], 0, s[28:29]
	s_mov_b32 m0, s49
	s_nop 0
	global_load_lds_dwordx4 v[164:165], off
	s_waitcnt vmcnt(10)
	s_barrier
	s_waitcnt lgkmcnt(0)
	s_waitcnt lgkmcnt(0)
	v_mfma_f32_16x16x32_bf16 v[62:65], v[130:133], v[146:149], v[62:65]
	v_mfma_f32_16x16x32_bf16 v[58:61], v[138:141], v[146:149], v[58:61]
	v_mfma_f32_16x16x32_bf16 v[50:53], v[130:133], v[176:179], v[50:53]
	v_mfma_f32_16x16x32_bf16 v[42:45], v[138:141], v[176:179], v[42:45]
	v_mfma_f32_16x16x32_bf16 v[34:37], v[130:133], v[184:187], v[34:37]
	v_mfma_f32_16x16x32_bf16 v[26:29], v[138:141], v[184:187], v[26:29]
	v_mfma_f32_16x16x32_bf16 v[18:21], v[130:133], v[192:195], v[18:21]
	v_mfma_f32_16x16x32_bf16 v[10:13], v[138:141], v[192:195], v[10:13]
	v_mfma_f32_16x16x32_bf16 v[62:65], v[134:137], v[172:175], v[62:65]
	v_mfma_f32_16x16x32_bf16 v[58:61], v[142:145], v[172:175], v[58:61]
	v_mfma_f32_16x16x32_bf16 v[50:53], v[134:137], v[180:183], v[50:53]
	v_mfma_f32_16x16x32_bf16 v[42:45], v[142:145], v[180:183], v[42:45]
	v_mfma_f32_16x16x32_bf16 v[34:37], v[134:137], v[188:191], v[34:37]
	v_mfma_f32_16x16x32_bf16 v[26:29], v[142:145], v[188:191], v[26:29]
	v_mfma_f32_16x16x32_bf16 v[18:21], v[134:137], v[196:199], v[18:21]
	v_mfma_f32_16x16x32_bf16 v[10:13], v[142:145], v[196:199], v[10:13]
	s_barrier
	s_add_u32 s0, s40, 0x40080
	s_addc_u32 s1, s41, 0
	s_add_i32 s40, s42, s7
	s_mov_b32 m0, s40
	s_nop 0
	global_load_lds_dwordx4 v156, s[0:1]
	s_add_i32 m0, s40, 0x2000
	s_nop 0
	global_load_lds_dwordx4 v152, s[0:1]
	s_waitcnt vmcnt(10)
	s_barrier
	v_mfma_f32_16x16x32_bf16 v[54:57], v[200:203], v[146:149], v[54:57]
	v_mfma_f32_16x16x32_bf16 v[46:49], v[208:211], v[146:149], v[46:49]
	v_mfma_f32_16x16x32_bf16 v[38:41], v[200:203], v[176:179], v[38:41]
	v_mfma_f32_16x16x32_bf16 v[30:33], v[208:211], v[176:179], v[30:33]
	v_mfma_f32_16x16x32_bf16 v[22:25], v[200:203], v[184:187], v[22:25]
	v_mfma_f32_16x16x32_bf16 v[14:17], v[208:211], v[184:187], v[14:17]
	v_mfma_f32_16x16x32_bf16 v[6:9], v[200:203], v[192:195], v[6:9]
	v_mfma_f32_16x16x32_bf16 v[2:5], v[208:211], v[192:195], v[2:5]
	v_mfma_f32_16x16x32_bf16 v[54:57], v[204:207], v[172:175], v[54:57]
	v_mfma_f32_16x16x32_bf16 v[46:49], v[212:215], v[172:175], v[46:49]
	v_mfma_f32_16x16x32_bf16 v[38:41], v[204:207], v[180:183], v[38:41]
	v_mfma_f32_16x16x32_bf16 v[30:33], v[212:215], v[180:183], v[30:33]
	v_mfma_f32_16x16x32_bf16 v[22:25], v[204:207], v[188:191], v[22:25]
	v_mfma_f32_16x16x32_bf16 v[14:17], v[212:215], v[188:191], v[14:17]
	v_mfma_f32_16x16x32_bf16 v[6:9], v[204:207], v[196:199], v[6:9]
	v_mfma_f32_16x16x32_bf16 v[2:5], v[212:215], v[196:199], v[2:5]
	s_add_i32 s66, s66, 2
	s_add_u32 s64, s64, 0x100
	s_addc_u32 s65, s65, 0
	s_add_u32 s38, s38, 0x100
	s_addc_u32 s39, s39, 0
	s_cmp_gt_u32 s66, 13
	s_barrier
	s_cbranch_scc0 .LBB0_1786

.LBB0_2029:
	v_bfe_u32 v196, v2, 4, 2
	v_and_b32_e32 v195, 15, v2
	v_lshlrev_b32_e32 v3, 4, v196
	v_lshlrev_b32_e32 v2, 2, v2
	v_lshl_or_b32 v3, v195, 6, v3
	s_lshl_b32 s0, s12, 13
	v_and_b32_e32 v2, 32, v2
	v_bitop3_b32 v8, v3, s0, v2 bitop3:0xde
	s_lshl_b32 s0, s1, 5
	v_mov_b32_e32 v165, v163
	s_and_b32 s50, s0, 0x60
	v_lshl_add_u64 v[4:5], s[36:37], 0, v[164:165]
	v_mov_b32_e32 v167, v163
	s_lshl_b32 s0, s50, 7
	v_lshl_add_u64 v[6:7], s[36:37], 0, v[166:167]
	v_bitop3_b32 v197, v3, s0, v2 bitop3:0xde
	s_add_i32 m0, s45, 0x18000
	v_lshl_add_u64 v[2:3], v[4:5], 0, s[24:25]
	v_mov_b32_e32 v169, v163
	s_lshl_b32 s49, s12, 6
	s_waitcnt vmcnt(4)
	s_barrier
	global_load_lds_dwordx4 v[2:3], off
	v_lshl_add_u64 v[2:3], v[6:7], 0, s[24:25]
	s_add_i32 m0, s45, 0x1a000
	s_add_i32 s51, s45, 0x8000
	s_add_i32 s52, s45, 0xa000
	v_mov_b32_e32 v171, v163
	global_load_lds_dwordx4 v[2:3], off
	v_lshl_add_u64 v[2:3], s[22:23], 0, v[168:169]
	s_mov_b32 m0, s51
	s_add_u32 s0, s36, 0x20080
	global_load_lds_dwordx4 v[2:3], off
	v_lshl_add_u64 v[2:3], s[22:23], 0, v[170:171]
	s_mov_b32 m0, s52
	s_addc_u32 s1, s37, 0
	global_load_lds_dwordx4 v[2:3], off
	s_add_i32 m0, s45, 0x1c000
	s_nop 0
	global_load_lds_dwordx4 v164, s[0:1]
	s_add_i32 m0, s45, 0x1e000
	s_mov_b32 s53, 0
	global_load_lds_dwordx4 v166, s[0:1]
	s_waitcnt vmcnt(6)
	v_add_u32_e32 v169, 0, v8
	s_barrier

.LBB0_2040:
	s_ashr_i32 s0, s54, 5
	s_ashr_i32 s1, s0, 31
	s_lshl_b64 s[0:1], s[0:1], 21
	s_add_u32 s16, s4, s0
	s_addc_u32 s17, s5, s1
	s_ashr_i32 s29, s28, 31
	s_lshl_b64 s[0:1], s[28:29], 18
	s_add_u32 s16, s16, s0
	s_addc_u32 s17, s17, s1
	s_and_b64 s[0:1], s[14:15], exec
	s_cselect_b32 s29, s17, s37
	s_cselect_b32 s31, s16, s36
	v_mov_b32_e32 v173, v163
	v_mov_b32_e32 v175, v163
	s_add_u32 s35, s36, 0x100
	s_addc_u32 s55, s37, 0
	v_lshl_add_u64 v[176:177], s[22:23], 0, v[174:175]
	v_lshl_add_u64 v[178:179], s[22:23], 0, v[172:173]
	s_mov_b32 s56, -2
	s_mov_b64 s[38:39], 0
	s_add_u32 s14, s38, 0x100
	s_addc_u32 s15, s39, 0
	s_add_u32 s36, s35, s38
	s_addc_u32 s37, s55, s39
	s_cmpk_eq_i32 s38, 0x300
	s_cselect_b64 vcc, -1, 0
	s_and_b64 s[0:1], vcc, exec
	s_cselect_b32 s1, 0, s14
	s_cselect_b32 s0, 0, s15
	s_cselect_b32 s36, s31, s36
	s_cselect_b32 s37, s29, s37
	s_add_u32 s40, s18, s1
	s_addc_u32 s41, s19, s0
	s_add_i32 s1, 0, 0x10000
	v_add_u32_e32 v14, s1, v197
	ds_read_b128 v[2:5], v14
	ds_read_b128 v[6:9], v14 offset:1024
	ds_read_b128 v[10:13], v14 offset:2048
	ds_read_b128 v[14:17], v14 offset:3072
	v_cndmask_b32_e32 v162, v168, v171, vcc
	v_cndmask_b32_e32 v184, v170, v198, vcc
	v_cndmask_b32_e32 v175, v172, v199, vcc
	v_cndmask_b32_e32 v173, v174, v200, vcc
	v_lshl_add_u64 v[18:19], v[178:179], 0, s[38:39]
	s_add_i32 m0, s45, 0xc000
	ds_read_b128 v[202:205], v169
	ds_read_b128 v[206:209], v169 offset:1024
	ds_read_b128 v[210:213], v169 offset:2048
	ds_read_b128 v[214:217], v169 offset:3072
	ds_read_b128 v[218:221], v169 offset:4096
	ds_read_b128 v[222:225], v169 offset:5120
	ds_read_b128 v[226:229], v169 offset:6144
	ds_read_b128 v[230:233], v169 offset:7168
	global_load_lds_dwordx4 v[18:19], off
	v_lshl_add_u64 v[18:19], v[176:177], 0, s[38:39]
	s_add_i32 m0, s45, 0xe000
	s_nop 0
	global_load_lds_dwordx4 v[18:19], off
	s_waitcnt lgkmcnt(8)
	s_waitcnt vmcnt(10)
	s_barrier
	s_waitcnt lgkmcnt(0)
	s_waitcnt lgkmcnt(0)
	v_mfma_scale_f32_16x16x128_f8f6f4 v[158:161], v[2:9], v[202:209], 0, v188, v188 op_sel_hi:[0,0,0]
	v_mfma_scale_f32_16x16x128_f8f6f4 v[150:153], v[10:17], v[202:209], 0, v188, v188 op_sel_hi:[0,0,0]
	v_mfma_scale_f32_16x16x128_f8f6f4 v[142:145], v[2:9], v[210:217], 0, v188, v188 op_sel_hi:[0,0,0]
	v_mfma_scale_f32_16x16x128_f8f6f4 v[134:137], v[10:17], v[210:217], 0, v188, v188 op_sel_hi:[0,0,0]
	v_mfma_scale_f32_16x16x128_f8f6f4 v[126:129], v[2:9], v[218:225], 0, v188, v188 op_sel_hi:[0,0,0]
	v_mfma_scale_f32_16x16x128_f8f6f4 v[118:121], v[10:17], v[218:225], 0, v188, v188 op_sel_hi:[0,0,0]
	v_mfma_scale_f32_16x16x128_f8f6f4 v[110:113], v[2:9], v[226:233], 0, v188, v188 op_sel_hi:[0,0,0]
	v_mfma_scale_f32_16x16x128_f8f6f4 v[102:105], v[10:17], v[226:233], 0, v188, v188 op_sel_hi:[0,0,0]
	s_barrier
	s_add_i32 s0, 0, 0x14000
	s_add_i32 s1, s1, s43
	v_add_u32_e32 v30, s0, v197
	v_lshl_add_u64 v[180:181], s[36:37], 0, v[164:165]
	s_mov_b32 m0, s1
	ds_read_b128 v[18:21], v30
	ds_read_b128 v[22:25], v30 offset:1024
	ds_read_b128 v[26:29], v30 offset:2048
	ds_read_b128 v[30:33], v30 offset:3072
	global_load_lds_dwordx4 v[180:181], off
	v_lshl_add_u64 v[182:183], s[36:37], 0, v[166:167]
	s_add_i32 m0, s1, 0x2000
	s_nop 0
	global_load_lds_dwordx4 v[182:183], off
	s_waitcnt vmcnt(10)
	s_barrier
	s_waitcnt lgkmcnt(0)
	s_waitcnt lgkmcnt(0)
	v_mfma_scale_f32_16x16x128_f8f6f4 v[154:157], v[18:25], v[202:209], 0, v188, v188 op_sel_hi:[0,0,0]
	v_mfma_scale_f32_16x16x128_f8f6f4 v[146:149], v[26:33], v[202:209], 0, v188, v188 op_sel_hi:[0,0,0]
	v_mfma_scale_f32_16x16x128_f8f6f4 v[138:141], v[18:25], v[210:217], 0, v188, v188 op_sel_hi:[0,0,0]
	v_mfma_scale_f32_16x16x128_f8f6f4 v[130:133], v[26:33], v[210:217], 0, v188, v188 op_sel_hi:[0,0,0]
	v_mfma_scale_f32_16x16x128_f8f6f4 v[122:125], v[18:25], v[218:225], 0, v188, v188 op_sel_hi:[0,0,0]
	v_mfma_scale_f32_16x16x128_f8f6f4 v[114:117], v[26:33], v[218:225], 0, v188, v188 op_sel_hi:[0,0,0]
	v_mfma_scale_f32_16x16x128_f8f6f4 v[106:109], v[18:25], v[226:233], 0, v188, v188 op_sel_hi:[0,0,0]
	v_mfma_scale_f32_16x16x128_f8f6f4 v[98:101], v[26:33], v[226:233], 0, v188, v188 op_sel_hi:[0,0,0]
	s_mov_b32 m0, s45
	s_barrier
	ds_read_b128 v[202:205], v169 offset:16384
	ds_read_b128 v[206:209], v169 offset:17408
	ds_read_b128 v[210:213], v169 offset:18432
	ds_read_b128 v[214:217], v169 offset:19456
	ds_read_b128 v[218:221], v169 offset:20480
	ds_read_b128 v[222:225], v169 offset:21504
	ds_read_b128 v[226:229], v169 offset:22528
	ds_read_b128 v[230:233], v169 offset:23552
	global_load_lds_dwordx4 v162, s[40:41]
	s_mov_b32 m0, s46
	v_mov_b32_e32 v185, v163
	global_load_lds_dwordx4 v184, s[40:41]
	s_waitcnt vmcnt(10)
	s_barrier
	s_waitcnt lgkmcnt(0)
	v_lshl_add_u64 v[186:187], s[40:41], 0, v[162:163]
	v_lshl_add_u64 v[184:185], s[40:41], 0, v[184:185]
	s_waitcnt lgkmcnt(0)
	v_mfma_scale_f32_16x16x128_f8f6f4 v[94:97], v[2:9], v[202:209], 0, v188, v188 op_sel_hi:[0,0,0]
	v_mfma_scale_f32_16x16x128_f8f6f4 v[86:89], v[10:17], v[202:209], 0, v188, v188 op_sel_hi:[0,0,0]
	v_mfma_scale_f32_16x16x128_f8f6f4 v[78:81], v[2:9], v[210:217], 0, v188, v188 op_sel_hi:[0,0,0]
	v_mfma_scale_f32_16x16x128_f8f6f4 v[70:73], v[10:17], v[210:217], 0, v188, v188 op_sel_hi:[0,0,0]
	v_mfma_scale_f32_16x16x128_f8f6f4 v[62:65], v[2:9], v[218:225], 0, v188, v188 op_sel_hi:[0,0,0]
	v_mfma_scale_f32_16x16x128_f8f6f4 v[54:57], v[10:17], v[218:225], 0, v188, v188 op_sel_hi:[0,0,0]
	v_mfma_scale_f32_16x16x128_f8f6f4 v[46:49], v[2:9], v[226:233], 0, v188, v188 op_sel_hi:[0,0,0]
	v_mfma_scale_f32_16x16x128_f8f6f4 v[38:41], v[10:17], v[226:233], 0, v188, v188 op_sel_hi:[0,0,0]
	s_barrier
	s_add_u32 s38, s36, 0x20000
	s_addc_u32 s39, s37, 0
	s_add_i32 s0, s0, s43
	s_mov_b32 m0, s0
	s_nop 0
	global_load_lds_dwordx4 v164, s[38:39]
	s_add_i32 m0, s0, 0x2000
	s_nop 0
	global_load_lds_dwordx4 v166, s[38:39]
	s_waitcnt vmcnt(10)
	s_barrier
	v_mfma_scale_f32_16x16x128_f8f6f4 v[90:93], v[18:25], v[202:209], 0, v188, v188 op_sel_hi:[0,0,0]
	v_mfma_scale_f32_16x16x128_f8f6f4 v[82:85], v[26:33], v[202:209], 0, v188, v188 op_sel_hi:[0,0,0]
	v_mfma_scale_f32_16x16x128_f8f6f4 v[74:77], v[18:25], v[210:217], 0, v188, v188 op_sel_hi:[0,0,0]
	v_mfma_scale_f32_16x16x128_f8f6f4 v[66:69], v[26:33], v[210:217], 0, v188, v188 op_sel_hi:[0,0,0]
	v_mfma_scale_f32_16x16x128_f8f6f4 v[58:61], v[18:25], v[218:225], 0, v188, v188 op_sel_hi:[0,0,0]
	v_mfma_scale_f32_16x16x128_f8f6f4 v[50:53], v[26:33], v[218:225], 0, v188, v188 op_sel_hi:[0,0,0]
	v_mfma_scale_f32_16x16x128_f8f6f4 v[42:45], v[18:25], v[226:233], 0, v188, v188 op_sel_hi:[0,0,0]
	v_mfma_scale_f32_16x16x128_f8f6f4 v[34:37], v[26:33], v[226:233], 0, v188, v188 op_sel_hi:[0,0,0]
	s_add_i32 s0, 0, 0x18000
	v_add_u32_e32 v14, s0, v197
	s_barrier
	ds_read_b128 v[2:5], v14
	ds_read_b128 v[6:9], v14 offset:1024
	ds_read_b128 v[10:13], v14 offset:2048
	ds_read_b128 v[14:17], v14 offset:3072
	s_mov_b32 m0, s47
	ds_read_b128 v[18:21], v169 offset:32768
	ds_read_b128 v[22:25], v169 offset:33792
	ds_read_b128 v[26:29], v169 offset:34816
	ds_read_b128 v[30:33], v169 offset:35840
	ds_read_b128 v[202:205], v169 offset:36864
	ds_read_b128 v[206:209], v169 offset:37888
	ds_read_b128 v[210:213], v169 offset:38912
	ds_read_b128 v[214:217], v169 offset:39936
	global_load_lds_dwordx4 v175, s[40:41]
	s_mov_b32 m0, s48
	s_nop 0
	global_load_lds_dwordx4 v173, s[40:41]
	s_waitcnt lgkmcnt(8)
	s_waitcnt vmcnt(10)
	s_barrier
	s_waitcnt lgkmcnt(0)
	s_waitcnt lgkmcnt(0)
	v_mfma_scale_f32_16x16x128_f8f6f4 v[158:161], v[2:9], v[18:25], v[158:161], v188, v188 op_sel_hi:[0,0,0]
	v_mfma_scale_f32_16x16x128_f8f6f4 v[150:153], v[10:17], v[18:25], v[150:153], v188, v188 op_sel_hi:[0,0,0]
	v_mfma_scale_f32_16x16x128_f8f6f4 v[142:145], v[2:9], v[26:33], v[142:145], v188, v188 op_sel_hi:[0,0,0]
	v_mfma_scale_f32_16x16x128_f8f6f4 v[134:137], v[10:17], v[26:33], v[134:137], v188, v188 op_sel_hi:[0,0,0]
	v_mfma_scale_f32_16x16x128_f8f6f4 v[126:129], v[2:9], v[202:209], v[126:129], v188, v188 op_sel_hi:[0,0,0]
	v_mfma_scale_f32_16x16x128_f8f6f4 v[118:121], v[10:17], v[202:209], v[118:121], v188, v188 op_sel_hi:[0,0,0]
	v_mfma_scale_f32_16x16x128_f8f6f4 v[110:113], v[2:9], v[210:217], v[110:113], v188, v188 op_sel_hi:[0,0,0]
	v_mfma_scale_f32_16x16x128_f8f6f4 v[102:105], v[10:17], v[210:217], v[102:105], v188, v188 op_sel_hi:[0,0,0]
	s_barrier
	s_add_i32 s38, 0, 0x1c000
	s_add_i32 s0, s0, s43
	v_add_u32_e32 v162, s38, v197
	v_lshl_add_u64 v[180:181], v[180:181], 0, s[24:25]
	s_mov_b32 m0, s0
	ds_read_b128 v[218:221], v162
	ds_read_b128 v[222:225], v162 offset:1024
	ds_read_b128 v[226:229], v162 offset:2048
	ds_read_b128 v[230:233], v162 offset:3072
	global_load_lds_dwordx4 v[180:181], off
	v_lshl_add_u64 v[180:181], v[182:183], 0, s[24:25]
	s_add_i32 m0, s0, 0x2000
	s_nop 0
	global_load_lds_dwordx4 v[180:181], off
	s_waitcnt vmcnt(10)
	s_barrier
	s_waitcnt lgkmcnt(0)
	s_waitcnt lgkmcnt(0)
	v_mfma_scale_f32_16x16x128_f8f6f4 v[154:157], v[218:225], v[18:25], v[154:157], v188, v188 op_sel_hi:[0,0,0]
	v_mfma_scale_f32_16x16x128_f8f6f4 v[146:149], v[226:233], v[18:25], v[146:149], v188, v188 op_sel_hi:[0,0,0]
	v_mfma_scale_f32_16x16x128_f8f6f4 v[138:141], v[218:225], v[26:33], v[138:141], v188, v188 op_sel_hi:[0,0,0]
	v_mfma_scale_f32_16x16x128_f8f6f4 v[130:133], v[226:233], v[26:33], v[130:133], v188, v188 op_sel_hi:[0,0,0]
	v_mfma_scale_f32_16x16x128_f8f6f4 v[122:125], v[218:225], v[202:209], v[122:125], v188, v188 op_sel_hi:[0,0,0]
	v_mfma_scale_f32_16x16x128_f8f6f4 v[114:117], v[226:233], v[202:209], v[114:117], v188, v188 op_sel_hi:[0,0,0]
	v_mfma_scale_f32_16x16x128_f8f6f4 v[106:109], v[218:225], v[210:217], v[106:109], v188, v188 op_sel_hi:[0,0,0]
	v_mfma_scale_f32_16x16x128_f8f6f4 v[98:101], v[226:233], v[210:217], v[98:101], v188, v188 op_sel_hi:[0,0,0]
	s_mov_b32 m0, s51
	v_lshl_add_u64 v[180:181], v[186:187], 0, s[24:25]
	s_barrier
	ds_read_b128 v[18:21], v169 offset:49152
	ds_read_b128 v[22:25], v169 offset:50176
	ds_read_b128 v[26:29], v169 offset:51200
	ds_read_b128 v[30:33], v169 offset:52224
	ds_read_b128 v[202:205], v169 offset:53248
	ds_read_b128 v[206:209], v169 offset:54272
	ds_read_b128 v[210:213], v169 offset:55296
	ds_read_b128 v[214:217], v169 offset:56320
	global_load_lds_dwordx4 v[180:181], off
	v_lshl_add_u64 v[180:181], v[184:185], 0, s[24:25]
	s_mov_b32 m0, s52
	s_nop 0
	global_load_lds_dwordx4 v[180:181], off
	s_waitcnt vmcnt(10)
	s_barrier
	s_waitcnt lgkmcnt(0)
	s_waitcnt lgkmcnt(0)
	v_mfma_scale_f32_16x16x128_f8f6f4 v[94:97], v[2:9], v[18:25], v[94:97], v188, v188 op_sel_hi:[0,0,0]
	v_mfma_scale_f32_16x16x128_f8f6f4 v[86:89], v[10:17], v[18:25], v[86:89], v188, v188 op_sel_hi:[0,0,0]
	v_mfma_scale_f32_16x16x128_f8f6f4 v[78:81], v[2:9], v[26:33], v[78:81], v188, v188 op_sel_hi:[0,0,0]
	v_mfma_scale_f32_16x16x128_f8f6f4 v[70:73], v[10:17], v[26:33], v[70:73], v188, v188 op_sel_hi:[0,0,0]
	v_mfma_scale_f32_16x16x128_f8f6f4 v[62:65], v[2:9], v[202:209], v[62:65], v188, v188 op_sel_hi:[0,0,0]
	v_mfma_scale_f32_16x16x128_f8f6f4 v[54:57], v[10:17], v[202:209], v[54:57], v188, v188 op_sel_hi:[0,0,0]
	v_mfma_scale_f32_16x16x128_f8f6f4 v[46:49], v[2:9], v[210:217], v[46:49], v188, v188 op_sel_hi:[0,0,0]
	v_mfma_scale_f32_16x16x128_f8f6f4 v[38:41], v[10:17], v[210:217], v[38:41], v188, v188 op_sel_hi:[0,0,0]
	s_barrier
	s_add_u32 s0, s36, 0x20080
	s_addc_u32 s1, s37, 0
	s_add_i32 s36, s38, s43
	s_mov_b32 m0, s36
	s_nop 0
	global_load_lds_dwordx4 v164, s[0:1]
	s_add_i32 m0, s36, 0x2000
	s_nop 0
	global_load_lds_dwordx4 v166, s[0:1]
	s_waitcnt vmcnt(10)
	s_barrier
	v_mfma_scale_f32_16x16x128_f8f6f4 v[90:93], v[218:225], v[18:25], v[90:93], v188, v188 op_sel_hi:[0,0,0]
	v_mfma_scale_f32_16x16x128_f8f6f4 v[82:85], v[226:233], v[18:25], v[82:85], v188, v188 op_sel_hi:[0,0,0]
	v_mfma_scale_f32_16x16x128_f8f6f4 v[74:77], v[218:225], v[26:33], v[74:77], v188, v188 op_sel_hi:[0,0,0]
	v_mfma_scale_f32_16x16x128_f8f6f4 v[66:69], v[226:233], v[26:33], v[66:69], v188, v188 op_sel_hi:[0,0,0]
	v_mfma_scale_f32_16x16x128_f8f6f4 v[58:61], v[218:225], v[202:209], v[58:61], v188, v188 op_sel_hi:[0,0,0]
	v_mfma_scale_f32_16x16x128_f8f6f4 v[50:53], v[226:233], v[202:209], v[50:53], v188, v188 op_sel_hi:[0,0,0]
	v_mfma_scale_f32_16x16x128_f8f6f4 v[42:45], v[218:225], v[210:217], v[42:45], v188, v188 op_sel_hi:[0,0,0]
	v_mfma_scale_f32_16x16x128_f8f6f4 v[34:37], v[226:233], v[210:217], v[34:37], v188, v188 op_sel_hi:[0,0,0]
	s_add_i32 s56, s56, 2
	s_cmp_gt_u32 s56, 5
	s_mov_b64 s[38:39], s[14:15]
	s_barrier
	s_cbranch_scc1 .Lpeel_exit_11
.LBB0_2041:
	s_add_u32 s14, s38, 0x100
	s_addc_u32 s15, s39, 0
	s_add_u32 s36, s35, s38
	s_addc_u32 s37, s55, s39
	s_cmpk_eq_i32 s38, 0x300
	s_cselect_b64 vcc, -1, 0
	s_and_b64 s[0:1], vcc, exec
	s_cselect_b32 s1, 0, s14
	s_cselect_b32 s0, 0, s15
	s_cselect_b32 s36, s31, s36
	s_cselect_b32 s37, s29, s37
	s_add_u32 s40, s18, s1
	s_addc_u32 s41, s19, s0
	s_add_i32 s1, 0, 0x10000
	v_add_u32_e32 v14, s1, v197
	ds_read_b128 v[2:5], v14
	ds_read_b128 v[6:9], v14 offset:1024
	ds_read_b128 v[10:13], v14 offset:2048
	ds_read_b128 v[14:17], v14 offset:3072
	v_cndmask_b32_e32 v162, v168, v171, vcc
	v_cndmask_b32_e32 v184, v170, v198, vcc
	v_cndmask_b32_e32 v175, v172, v199, vcc
	v_cndmask_b32_e32 v173, v174, v200, vcc
	v_lshl_add_u64 v[18:19], v[178:179], 0, s[38:39]
	s_add_i32 m0, s45, 0xc000
	ds_read_b128 v[202:205], v169
	ds_read_b128 v[206:209], v169 offset:1024
	ds_read_b128 v[210:213], v169 offset:2048
	ds_read_b128 v[214:217], v169 offset:3072
	ds_read_b128 v[218:221], v169 offset:4096
	ds_read_b128 v[222:225], v169 offset:5120
	ds_read_b128 v[226:229], v169 offset:6144
	ds_read_b128 v[230:233], v169 offset:7168
	global_load_lds_dwordx4 v[18:19], off
	v_lshl_add_u64 v[18:19], v[176:177], 0, s[38:39]
	s_add_i32 m0, s45, 0xe000
	s_nop 0
	global_load_lds_dwordx4 v[18:19], off
	s_waitcnt lgkmcnt(8)
	s_waitcnt vmcnt(10)
	s_barrier
	s_waitcnt lgkmcnt(0)
	s_waitcnt lgkmcnt(0)
	v_mfma_scale_f32_16x16x128_f8f6f4 v[158:161], v[2:9], v[202:209], v[158:161], v188, v188 op_sel_hi:[0,0,0]
	v_mfma_scale_f32_16x16x128_f8f6f4 v[150:153], v[10:17], v[202:209], v[150:153], v188, v188 op_sel_hi:[0,0,0]
	v_mfma_scale_f32_16x16x128_f8f6f4 v[142:145], v[2:9], v[210:217], v[142:145], v188, v188 op_sel_hi:[0,0,0]
	v_mfma_scale_f32_16x16x128_f8f6f4 v[134:137], v[10:17], v[210:217], v[134:137], v188, v188 op_sel_hi:[0,0,0]
	v_mfma_scale_f32_16x16x128_f8f6f4 v[126:129], v[2:9], v[218:225], v[126:129], v188, v188 op_sel_hi:[0,0,0]
	v_mfma_scale_f32_16x16x128_f8f6f4 v[118:121], v[10:17], v[218:225], v[118:121], v188, v188 op_sel_hi:[0,0,0]
	v_mfma_scale_f32_16x16x128_f8f6f4 v[110:113], v[2:9], v[226:233], v[110:113], v188, v188 op_sel_hi:[0,0,0]
	v_mfma_scale_f32_16x16x128_f8f6f4 v[102:105], v[10:17], v[226:233], v[102:105], v188, v188 op_sel_hi:[0,0,0]
	s_barrier
	s_add_i32 s0, 0, 0x14000
	s_add_i32 s1, s1, s43
	v_add_u32_e32 v30, s0, v197
	v_lshl_add_u64 v[180:181], s[36:37], 0, v[164:165]
	s_mov_b32 m0, s1
	ds_read_b128 v[18:21], v30
	ds_read_b128 v[22:25], v30 offset:1024
	ds_read_b128 v[26:29], v30 offset:2048
	ds_read_b128 v[30:33], v30 offset:3072
	global_load_lds_dwordx4 v[180:181], off
	v_lshl_add_u64 v[182:183], s[36:37], 0, v[166:167]
	s_add_i32 m0, s1, 0x2000
	s_nop 0
	global_load_lds_dwordx4 v[182:183], off
	s_waitcnt vmcnt(10)
	s_barrier
	s_waitcnt lgkmcnt(0)
	s_waitcnt lgkmcnt(0)
	v_mfma_scale_f32_16x16x128_f8f6f4 v[154:157], v[18:25], v[202:209], v[154:157], v188, v188 op_sel_hi:[0,0,0]
	v_mfma_scale_f32_16x16x128_f8f6f4 v[146:149], v[26:33], v[202:209], v[146:149], v188, v188 op_sel_hi:[0,0,0]
	v_mfma_scale_f32_16x16x128_f8f6f4 v[138:141], v[18:25], v[210:217], v[138:141], v188, v188 op_sel_hi:[0,0,0]
	v_mfma_scale_f32_16x16x128_f8f6f4 v[130:133], v[26:33], v[210:217], v[130:133], v188, v188 op_sel_hi:[0,0,0]
	v_mfma_scale_f32_16x16x128_f8f6f4 v[122:125], v[18:25], v[218:225], v[122:125], v188, v188 op_sel_hi:[0,0,0]
	v_mfma_scale_f32_16x16x128_f8f6f4 v[114:117], v[26:33], v[218:225], v[114:117], v188, v188 op_sel_hi:[0,0,0]
	v_mfma_scale_f32_16x16x128_f8f6f4 v[106:109], v[18:25], v[226:233], v[106:109], v188, v188 op_sel_hi:[0,0,0]
	v_mfma_scale_f32_16x16x128_f8f6f4 v[98:101], v[26:33], v[226:233], v[98:101], v188, v188 op_sel_hi:[0,0,0]
	s_mov_b32 m0, s45
	s_barrier
	ds_read_b128 v[202:205], v169 offset:16384
	ds_read_b128 v[206:209], v169 offset:17408
	ds_read_b128 v[210:213], v169 offset:18432
	ds_read_b128 v[214:217], v169 offset:19456
	ds_read_b128 v[218:221], v169 offset:20480
	ds_read_b128 v[222:225], v169 offset:21504
	ds_read_b128 v[226:229], v169 offset:22528
	ds_read_b128 v[230:233], v169 offset:23552
	global_load_lds_dwordx4 v162, s[40:41]
	s_mov_b32 m0, s46
	v_mov_b32_e32 v185, v163
	global_load_lds_dwordx4 v184, s[40:41]
	s_waitcnt vmcnt(10)
	s_barrier
	s_waitcnt lgkmcnt(0)
	v_lshl_add_u64 v[186:187], s[40:41], 0, v[162:163]
	v_lshl_add_u64 v[184:185], s[40:41], 0, v[184:185]
	s_waitcnt lgkmcnt(0)
	v_mfma_scale_f32_16x16x128_f8f6f4 v[94:97], v[2:9], v[202:209], v[94:97], v188, v188 op_sel_hi:[0,0,0]
	v_mfma_scale_f32_16x16x128_f8f6f4 v[86:89], v[10:17], v[202:209], v[86:89], v188, v188 op_sel_hi:[0,0,0]
	v_mfma_scale_f32_16x16x128_f8f6f4 v[78:81], v[2:9], v[210:217], v[78:81], v188, v188 op_sel_hi:[0,0,0]
	v_mfma_scale_f32_16x16x128_f8f6f4 v[70:73], v[10:17], v[210:217], v[70:73], v188, v188 op_sel_hi:[0,0,0]
	v_mfma_scale_f32_16x16x128_f8f6f4 v[62:65], v[2:9], v[218:225], v[62:65], v188, v188 op_sel_hi:[0,0,0]
	v_mfma_scale_f32_16x16x128_f8f6f4 v[54:57], v[10:17], v[218:225], v[54:57], v188, v188 op_sel_hi:[0,0,0]
	v_mfma_scale_f32_16x16x128_f8f6f4 v[46:49], v[2:9], v[226:233], v[46:49], v188, v188 op_sel_hi:[0,0,0]
	v_mfma_scale_f32_16x16x128_f8f6f4 v[38:41], v[10:17], v[226:233], v[38:41], v188, v188 op_sel_hi:[0,0,0]
	s_barrier
	s_add_u32 s38, s36, 0x20000
	s_addc_u32 s39, s37, 0
	s_add_i32 s0, s0, s43
	s_mov_b32 m0, s0
	s_nop 0
	global_load_lds_dwordx4 v164, s[38:39]
	s_add_i32 m0, s0, 0x2000
	s_nop 0
	global_load_lds_dwordx4 v166, s[38:39]
	s_waitcnt vmcnt(10)
	s_barrier
	v_mfma_scale_f32_16x16x128_f8f6f4 v[90:93], v[18:25], v[202:209], v[90:93], v188, v188 op_sel_hi:[0,0,0]
	v_mfma_scale_f32_16x16x128_f8f6f4 v[82:85], v[26:33], v[202:209], v[82:85], v188, v188 op_sel_hi:[0,0,0]
	v_mfma_scale_f32_16x16x128_f8f6f4 v[74:77], v[18:25], v[210:217], v[74:77], v188, v188 op_sel_hi:[0,0,0]
	v_mfma_scale_f32_16x16x128_f8f6f4 v[66:69], v[26:33], v[210:217], v[66:69], v188, v188 op_sel_hi:[0,0,0]
	v_mfma_scale_f32_16x16x128_f8f6f4 v[58:61], v[18:25], v[218:225], v[58:61], v188, v188 op_sel_hi:[0,0,0]
	v_mfma_scale_f32_16x16x128_f8f6f4 v[50:53], v[26:33], v[218:225], v[50:53], v188, v188 op_sel_hi:[0,0,0]
	v_mfma_scale_f32_16x16x128_f8f6f4 v[42:45], v[18:25], v[226:233], v[42:45], v188, v188 op_sel_hi:[0,0,0]
	v_mfma_scale_f32_16x16x128_f8f6f4 v[34:37], v[26:33], v[226:233], v[34:37], v188, v188 op_sel_hi:[0,0,0]
	s_add_i32 s0, 0, 0x18000
	v_add_u32_e32 v14, s0, v197
	s_barrier
	ds_read_b128 v[2:5], v14
	ds_read_b128 v[6:9], v14 offset:1024
	ds_read_b128 v[10:13], v14 offset:2048
	ds_read_b128 v[14:17], v14 offset:3072
	s_mov_b32 m0, s47
	ds_read_b128 v[18:21], v169 offset:32768
	ds_read_b128 v[22:25], v169 offset:33792
	ds_read_b128 v[26:29], v169 offset:34816
	ds_read_b128 v[30:33], v169 offset:35840
	ds_read_b128 v[202:205], v169 offset:36864
	ds_read_b128 v[206:209], v169 offset:37888
	ds_read_b128 v[210:213], v169 offset:38912
	ds_read_b128 v[214:217], v169 offset:39936
	global_load_lds_dwordx4 v175, s[40:41]
	s_mov_b32 m0, s48
	s_nop 0
	global_load_lds_dwordx4 v173, s[40:41]
	s_waitcnt lgkmcnt(8)
	s_waitcnt vmcnt(10)
	s_barrier
	s_waitcnt lgkmcnt(0)
	s_waitcnt lgkmcnt(0)
	v_mfma_scale_f32_16x16x128_f8f6f4 v[158:161], v[2:9], v[18:25], v[158:161], v188, v188 op_sel_hi:[0,0,0]
	v_mfma_scale_f32_16x16x128_f8f6f4 v[150:153], v[10:17], v[18:25], v[150:153], v188, v188 op_sel_hi:[0,0,0]
	v_mfma_scale_f32_16x16x128_f8f6f4 v[142:145], v[2:9], v[26:33], v[142:145], v188, v188 op_sel_hi:[0,0,0]
	v_mfma_scale_f32_16x16x128_f8f6f4 v[134:137], v[10:17], v[26:33], v[134:137], v188, v188 op_sel_hi:[0,0,0]
	v_mfma_scale_f32_16x16x128_f8f6f4 v[126:129], v[2:9], v[202:209], v[126:129], v188, v188 op_sel_hi:[0,0,0]
	v_mfma_scale_f32_16x16x128_f8f6f4 v[118:121], v[10:17], v[202:209], v[118:121], v188, v188 op_sel_hi:[0,0,0]
	v_mfma_scale_f32_16x16x128_f8f6f4 v[110:113], v[2:9], v[210:217], v[110:113], v188, v188 op_sel_hi:[0,0,0]
	v_mfma_scale_f32_16x16x128_f8f6f4 v[102:105], v[10:17], v[210:217], v[102:105], v188, v188 op_sel_hi:[0,0,0]
	s_barrier
	s_add_i32 s38, 0, 0x1c000
	s_add_i32 s0, s0, s43
	v_add_u32_e32 v162, s38, v197
	v_lshl_add_u64 v[180:181], v[180:181], 0, s[24:25]
	s_mov_b32 m0, s0
	ds_read_b128 v[218:221], v162
	ds_read_b128 v[222:225], v162 offset:1024
	ds_read_b128 v[226:229], v162 offset:2048
	ds_read_b128 v[230:233], v162 offset:3072
	global_load_lds_dwordx4 v[180:181], off
	v_lshl_add_u64 v[180:181], v[182:183], 0, s[24:25]
	s_add_i32 m0, s0, 0x2000
	s_nop 0
	global_load_lds_dwordx4 v[180:181], off
	s_waitcnt vmcnt(10)
	s_barrier
	s_waitcnt lgkmcnt(0)
	s_waitcnt lgkmcnt(0)
	v_mfma_scale_f32_16x16x128_f8f6f4 v[154:157], v[218:225], v[18:25], v[154:157], v188, v188 op_sel_hi:[0,0,0]
	v_mfma_scale_f32_16x16x128_f8f6f4 v[146:149], v[226:233], v[18:25], v[146:149], v188, v188 op_sel_hi:[0,0,0]
	v_mfma_scale_f32_16x16x128_f8f6f4 v[138:141], v[218:225], v[26:33], v[138:141], v188, v188 op_sel_hi:[0,0,0]
	v_mfma_scale_f32_16x16x128_f8f6f4 v[130:133], v[226:233], v[26:33], v[130:133], v188, v188 op_sel_hi:[0,0,0]
	v_mfma_scale_f32_16x16x128_f8f6f4 v[122:125], v[218:225], v[202:209], v[122:125], v188, v188 op_sel_hi:[0,0,0]
	v_mfma_scale_f32_16x16x128_f8f6f4 v[114:117], v[226:233], v[202:209], v[114:117], v188, v188 op_sel_hi:[0,0,0]
	v_mfma_scale_f32_16x16x128_f8f6f4 v[106:109], v[218:225], v[210:217], v[106:109], v188, v188 op_sel_hi:[0,0,0]
	v_mfma_scale_f32_16x16x128_f8f6f4 v[98:101], v[226:233], v[210:217], v[98:101], v188, v188 op_sel_hi:[0,0,0]
	s_mov_b32 m0, s51
	v_lshl_add_u64 v[180:181], v[186:187], 0, s[24:25]
	s_barrier
	ds_read_b128 v[18:21], v169 offset:49152
	ds_read_b128 v[22:25], v169 offset:50176
	ds_read_b128 v[26:29], v169 offset:51200
	ds_read_b128 v[30:33], v169 offset:52224
	ds_read_b128 v[202:205], v169 offset:53248
	ds_read_b128 v[206:209], v169 offset:54272
	ds_read_b128 v[210:213], v169 offset:55296
	ds_read_b128 v[214:217], v169 offset:56320
	global_load_lds_dwordx4 v[180:181], off
	v_lshl_add_u64 v[180:181], v[184:185], 0, s[24:25]
	s_mov_b32 m0, s52
	s_nop 0
	global_load_lds_dwordx4 v[180:181], off
	s_waitcnt vmcnt(10)
	s_barrier
	s_waitcnt lgkmcnt(0)
	s_waitcnt lgkmcnt(0)
	v_mfma_scale_f32_16x16x128_f8f6f4 v[94:97], v[2:9], v[18:25], v[94:97], v188, v188 op_sel_hi:[0,0,0]
	v_mfma_scale_f32_16x16x128_f8f6f4 v[86:89], v[10:17], v[18:25], v[86:89], v188, v188 op_sel_hi:[0,0,0]
	v_mfma_scale_f32_16x16x128_f8f6f4 v[78:81], v[2:9], v[26:33], v[78:81], v188, v188 op_sel_hi:[0,0,0]
	v_mfma_scale_f32_16x16x128_f8f6f4 v[70:73], v[10:17], v[26:33], v[70:73], v188, v188 op_sel_hi:[0,0,0]
	v_mfma_scale_f32_16x16x128_f8f6f4 v[62:65], v[2:9], v[202:209], v[62:65], v188, v188 op_sel_hi:[0,0,0]
	v_mfma_scale_f32_16x16x128_f8f6f4 v[54:57], v[10:17], v[202:209], v[54:57], v188, v188 op_sel_hi:[0,0,0]
	v_mfma_scale_f32_16x16x128_f8f6f4 v[46:49], v[2:9], v[210:217], v[46:49], v188, v188 op_sel_hi:[0,0,0]
	v_mfma_scale_f32_16x16x128_f8f6f4 v[38:41], v[10:17], v[210:217], v[38:41], v188, v188 op_sel_hi:[0,0,0]
	s_barrier
	s_add_u32 s0, s36, 0x20080
	s_addc_u32 s1, s37, 0
	s_add_i32 s36, s38, s43
	s_mov_b32 m0, s36
	s_nop 0
	global_load_lds_dwordx4 v164, s[0:1]
	s_add_i32 m0, s36, 0x2000
	s_nop 0
	global_load_lds_dwordx4 v166, s[0:1]
	s_waitcnt vmcnt(10)
	s_barrier
	v_mfma_scale_f32_16x16x128_f8f6f4 v[90:93], v[218:225], v[18:25], v[90:93], v188, v188 op_sel_hi:[0,0,0]
	v_mfma_scale_f32_16x16x128_f8f6f4 v[82:85], v[226:233], v[18:25], v[82:85], v188, v188 op_sel_hi:[0,0,0]
	v_mfma_scale_f32_16x16x128_f8f6f4 v[74:77], v[218:225], v[26:33], v[74:77], v188, v188 op_sel_hi:[0,0,0]
	v_mfma_scale_f32_16x16x128_f8f6f4 v[66:69], v[226:233], v[26:33], v[66:69], v188, v188 op_sel_hi:[0,0,0]
	v_mfma_scale_f32_16x16x128_f8f6f4 v[58:61], v[218:225], v[202:209], v[58:61], v188, v188 op_sel_hi:[0,0,0]
	v_mfma_scale_f32_16x16x128_f8f6f4 v[50:53], v[226:233], v[202:209], v[50:53], v188, v188 op_sel_hi:[0,0,0]
	v_mfma_scale_f32_16x16x128_f8f6f4 v[42:45], v[218:225], v[210:217], v[42:45], v188, v188 op_sel_hi:[0,0,0]
	v_mfma_scale_f32_16x16x128_f8f6f4 v[34:37], v[226:233], v[210:217], v[34:37], v188, v188 op_sel_hi:[0,0,0]
	s_add_i32 s56, s56, 2
	s_cmp_gt_u32 s56, 5
	s_mov_b64 s[38:39], s[14:15]
	s_barrier
	s_cbranch_scc0 .LBB0_2041

.LBB0_2100:
	s_add_u32 s14, s14, 0x12100000
	s_addc_u32 s15, s15, 0
	s_lshl_b32 s0, s0, 5
	s_mov_b64 s[16:17], 0x80
	s_and_b32 s42, s0, 0x60
	s_add_i32 m0, s10, 0x18000
	v_lshl_add_u64 v[4:5], v[4:5], 0, s[16:17]
	s_lshl_b32 s41, s1, 6
	s_lshl_b32 s13, s1, 13
	s_lshl_b32 s18, s42, 7
	s_waitcnt vmcnt(4)
	s_barrier
	global_load_lds_dwordx4 v[4:5], off
	s_add_i32 m0, s10, 0x1a000
	s_add_u32 s0, s34, 0x8000
	v_lshl_add_u64 v[2:3], v[2:3], 0, s[16:17]
	s_addc_u32 s1, s35, 0
	s_add_i32 s43, s10, 0x8000
	global_load_lds_dwordx4 v[2:3], off
	s_mov_b32 m0, s43
	s_add_i32 s44, s10, 0xa000
	global_load_lds_dwordx4 v152, s[0:1]
	v_lshl_add_u64 v[2:3], s[0:1], 0, v[148:149]
	s_add_u32 s0, s30, 0x20080
	s_mov_b32 m0, s44
	s_addc_u32 s1, s31, 0
	global_load_lds_dwordx4 v[2:3], off
	s_add_i32 m0, s10, 0x1c000
	s_nop 0
	global_load_lds_dwordx4 v150, s[0:1]
	s_add_i32 m0, s10, 0x1e000
	v_bfe_u32 v167, v6, 4, 2
	global_load_lds_dwordx4 v146, s[0:1]
	v_and_b32_e32 v166, 15, v6
	v_lshlrev_b32_e32 v2, 4, v167
	v_lshlrev_b32_e32 v3, 2, v6
	v_lshl_or_b32 v2, v166, 6, v2
	v_and_b32_e32 v3, 32, v3
	v_bitop3_b32 v4, v2, s13, v3 bitop3:0xde
	v_bitop3_b32 v168, v2, s18, v3 bitop3:0xde
	v_lshlrev_b32_e32 v2, 10, v7
	v_and_b32_e32 v2, 0xfffff800, v2
	v_lshl_add_u32 v2, v8, 7, v2
	v_and_b32_e32 v3, 1, v7
	v_lshl_or_b32 v2, v3, 6, v2
	v_lshl_add_u32 v154, v9, 1, v2
	v_lshlrev_b32_e32 v2, 10, v11
	v_and_b32_e32 v2, 0xfffff800, v2
	s_waitcnt vmcnt(6)
	v_lshl_add_u32 v2, v10, 7, v2
	v_and_b32_e32 v3, 1, v11
	v_lshl_or_b32 v2, v3, 6, v2
	s_add_i32 s45, 0, 0x10000
	s_add_i32 s46, 0, 0x14000
	s_sext_i32_i8 s48, s12
	v_mov_b32_e32 v155, v151
	v_lshl_add_u32 v156, v12, 1, v2
	v_mov_b32_e32 v157, v151
	v_mov_b64_e32 v[158:159], 0x800
	v_mov_b64_e32 v[160:161], 0x7ff
	v_add_u32_e32 v169, s45, v168
	v_add_u32_e32 v170, 0, v4
	v_mov_b32_e32 v171, 0x7f7f7f7f
	v_add_u32_e32 v172, s46, v168
	s_mov_b32 s18, 0x3d000000
	s_mov_b32 s47, 0xc3d00000
	v_mov_b32_e32 v173, 0x43d00000
	s_barrier

.LBB0_2107:
	s_ashr_i32 s23, s22, 31
	s_lshl_b64 s[0:1], s[22:23], 18
	v_cmp_lt_i64_e32 vcc, s[24:25], v[158:159]
	s_add_u32 s24, s5, s0
	s_addc_u32 s25, s6, s1
	s_and_b64 s[0:1], vcc, exec
	s_cselect_b32 s23, s25, s35
	s_cselect_b32 s49, s24, s34
	s_ashr_i32 s0, s22, 5
	s_ashr_i32 s1, s0, 31
	s_lshl_b64 s[0:1], s[0:1], 20
	s_add_u32 s26, s7, s0
	s_addc_u32 s27, s8, s1
	s_ashr_i32 s21, s20, 31
	s_lshl_b64 s[0:1], s[20:21], 18
	s_add_u32 s26, s26, s0
	s_addc_u32 s27, s27, s1
	s_and_b64 s[0:1], vcc, exec
	s_cselect_b32 s21, s27, s31
	s_cselect_b32 s50, s26, s30
	s_add_u32 s51, s30, 0x100
	s_addc_u32 s52, s31, 0
	s_add_u32 s30, s34, 0xc000
	s_addc_u32 s31, s35, 0
	s_mov_b32 s53, -2
	ds_read_b128 v[2:5], v169
	ds_read_b128 v[6:9], v169 offset:1024
	ds_read_b128 v[10:13], v169 offset:2048
	ds_read_b128 v[14:17], v169 offset:3072
	s_add_u32 s0, s30, 0x4000
	s_addc_u32 s1, s31, 0
	s_cmp_eq_u32 s53, 4
	s_cselect_b32 s38, s49, s0
	s_cselect_b32 s39, s23, s1
	s_cselect_b32 s34, s50, s51
	s_cselect_b32 s35, s21, s52
	s_add_u32 s36, s38, 0x8000
	s_addc_u32 s37, s39, 0
	s_add_i32 m0, s10, 0xc000
	ds_read_b128 v[174:177], v170
	ds_read_b128 v[178:181], v170 offset:1024
	ds_read_b128 v[182:185], v170 offset:2048
	ds_read_b128 v[186:189], v170 offset:3072
	ds_read_b128 v[190:193], v170 offset:4096
	ds_read_b128 v[194:197], v170 offset:5120
	ds_read_b128 v[198:201], v170 offset:6144
	ds_read_b128 v[202:205], v170 offset:7168
	global_load_lds_dwordx4 v156, s[30:31]
	s_add_i32 m0, s10, 0xe000
	s_nop 0
	global_load_lds_dwordx4 v154, s[30:31]
	s_waitcnt lgkmcnt(8)
	s_waitcnt vmcnt(10)
	s_barrier
	s_waitcnt lgkmcnt(0)
	s_waitcnt lgkmcnt(0)
	v_mfma_scale_f32_16x16x128_f8f6f4 v[142:145], v[2:9], v[174:181], 0, v171, v171 op_sel_hi:[0,0,0]
	v_mfma_scale_f32_16x16x128_f8f6f4 v[138:141], v[10:17], v[174:181], 0, v171, v171 op_sel_hi:[0,0,0]
	v_mfma_scale_f32_16x16x128_f8f6f4 v[126:129], v[2:9], v[182:189], 0, v171, v171 op_sel_hi:[0,0,0]
	v_mfma_scale_f32_16x16x128_f8f6f4 v[122:125], v[10:17], v[182:189], 0, v171, v171 op_sel_hi:[0,0,0]
	v_mfma_scale_f32_16x16x128_f8f6f4 v[110:113], v[2:9], v[190:197], 0, v171, v171 op_sel_hi:[0,0,0]
	v_mfma_scale_f32_16x16x128_f8f6f4 v[106:109], v[10:17], v[190:197], 0, v171, v171 op_sel_hi:[0,0,0]
	v_mfma_scale_f32_16x16x128_f8f6f4 v[94:97], v[2:9], v[198:205], 0, v171, v171 op_sel_hi:[0,0,0]
	v_mfma_scale_f32_16x16x128_f8f6f4 v[90:93], v[10:17], v[198:205], 0, v171, v171 op_sel_hi:[0,0,0]
	s_barrier
	s_add_i32 s0, s45, s9
	v_lshl_add_u64 v[162:163], s[34:35], 0, v[150:151]
	s_mov_b32 m0, s0
	ds_read_b128 v[206:209], v172
	ds_read_b128 v[210:213], v172 offset:1024
	ds_read_b128 v[214:217], v172 offset:2048
	ds_read_b128 v[218:221], v172 offset:3072
	global_load_lds_dwordx4 v[162:163], off
	v_lshl_add_u64 v[164:165], s[34:35], 0, v[146:147]
	s_add_i32 m0, s0, 0x2000
	s_nop 0
	global_load_lds_dwordx4 v[164:165], off
	s_waitcnt vmcnt(10)
	s_barrier
	s_waitcnt lgkmcnt(0)
	s_waitcnt lgkmcnt(0)
	v_mfma_scale_f32_16x16x128_f8f6f4 v[134:137], v[206:213], v[174:181], 0, v171, v171 op_sel_hi:[0,0,0]
	v_mfma_scale_f32_16x16x128_f8f6f4 v[130:133], v[214:221], v[174:181], 0, v171, v171 op_sel_hi:[0,0,0]
	v_mfma_scale_f32_16x16x128_f8f6f4 v[118:121], v[206:213], v[182:189], 0, v171, v171 op_sel_hi:[0,0,0]
	v_mfma_scale_f32_16x16x128_f8f6f4 v[114:117], v[214:221], v[182:189], 0, v171, v171 op_sel_hi:[0,0,0]
	v_mfma_scale_f32_16x16x128_f8f6f4 v[102:105], v[206:213], v[190:197], 0, v171, v171 op_sel_hi:[0,0,0]
	v_mfma_scale_f32_16x16x128_f8f6f4 v[98:101], v[214:221], v[190:197], 0, v171, v171 op_sel_hi:[0,0,0]
	v_mfma_scale_f32_16x16x128_f8f6f4 v[86:89], v[206:213], v[198:205], 0, v171, v171 op_sel_hi:[0,0,0]
	v_mfma_scale_f32_16x16x128_f8f6f4 v[82:85], v[214:221], v[198:205], 0, v171, v171 op_sel_hi:[0,0,0]
	s_mov_b32 m0, s10
	s_barrier
	ds_read_b128 v[174:177], v170 offset:16384
	ds_read_b128 v[178:181], v170 offset:17408
	ds_read_b128 v[182:185], v170 offset:18432
	ds_read_b128 v[186:189], v170 offset:19456
	ds_read_b128 v[190:193], v170 offset:20480
	ds_read_b128 v[194:197], v170 offset:21504
	ds_read_b128 v[198:201], v170 offset:22528
	ds_read_b128 v[202:205], v170 offset:23552
	global_load_lds_dwordx4 v152, s[38:39]
	s_mov_b32 m0, s11
	s_nop 0
	global_load_lds_dwordx4 v148, s[38:39]
	s_waitcnt vmcnt(10)
	s_barrier
	s_waitcnt lgkmcnt(0)
	s_waitcnt lgkmcnt(0)
	v_mfma_scale_f32_16x16x128_f8f6f4 v[78:81], v[2:9], v[174:181], 0, v171, v171 op_sel_hi:[0,0,0]
	v_mfma_scale_f32_16x16x128_f8f6f4 v[74:77], v[10:17], v[174:181], 0, v171, v171 op_sel_hi:[0,0,0]
	v_mfma_scale_f32_16x16x128_f8f6f4 v[62:65], v[2:9], v[182:189], 0, v171, v171 op_sel_hi:[0,0,0]
	v_mfma_scale_f32_16x16x128_f8f6f4 v[58:61], v[10:17], v[182:189], 0, v171, v171 op_sel_hi:[0,0,0]
	v_mfma_scale_f32_16x16x128_f8f6f4 v[46:49], v[2:9], v[190:197], 0, v171, v171 op_sel_hi:[0,0,0]
	v_mfma_scale_f32_16x16x128_f8f6f4 v[42:45], v[10:17], v[190:197], 0, v171, v171 op_sel_hi:[0,0,0]
	v_mfma_scale_f32_16x16x128_f8f6f4 v[30:33], v[2:9], v[198:205], 0, v171, v171 op_sel_hi:[0,0,0]
	v_mfma_scale_f32_16x16x128_f8f6f4 v[26:29], v[10:17], v[198:205], 0, v171, v171 op_sel_hi:[0,0,0]
	s_barrier
	s_add_u32 s0, s34, 0x20000
	s_addc_u32 s1, s35, 0
	s_add_i32 s54, s46, s9
	s_mov_b32 m0, s54
	s_nop 0
	global_load_lds_dwordx4 v150, s[0:1]
	s_add_i32 m0, s54, 0x2000
	s_nop 0
	global_load_lds_dwordx4 v146, s[0:1]
	s_waitcnt vmcnt(10)
	s_barrier
	v_mfma_scale_f32_16x16x128_f8f6f4 v[70:73], v[206:213], v[174:181], 0, v171, v171 op_sel_hi:[0,0,0]
	v_mfma_scale_f32_16x16x128_f8f6f4 v[66:69], v[214:221], v[174:181], 0, v171, v171 op_sel_hi:[0,0,0]
	v_mfma_scale_f32_16x16x128_f8f6f4 v[54:57], v[206:213], v[182:189], 0, v171, v171 op_sel_hi:[0,0,0]
	v_mfma_scale_f32_16x16x128_f8f6f4 v[50:53], v[214:221], v[182:189], 0, v171, v171 op_sel_hi:[0,0,0]
	v_mfma_scale_f32_16x16x128_f8f6f4 v[38:41], v[206:213], v[190:197], 0, v171, v171 op_sel_hi:[0,0,0]
	v_mfma_scale_f32_16x16x128_f8f6f4 v[34:37], v[214:221], v[190:197], 0, v171, v171 op_sel_hi:[0,0,0]
	v_mfma_scale_f32_16x16x128_f8f6f4 v[22:25], v[206:213], v[198:205], 0, v171, v171 op_sel_hi:[0,0,0]
	v_mfma_scale_f32_16x16x128_f8f6f4 v[18:21], v[214:221], v[198:205], 0, v171, v171 op_sel_hi:[0,0,0]
	s_add_i32 s54, 0, 0x18000
	v_add_u32_e32 v14, s54, v168
	s_barrier
	ds_read_b128 v[2:5], v14
	ds_read_b128 v[6:9], v14 offset:1024
	ds_read_b128 v[10:13], v14 offset:2048
	ds_read_b128 v[14:17], v14 offset:3072
	s_add_u32 s0, s38, 0x4000
	s_addc_u32 s1, s39, 0
	s_mov_b32 m0, s19
	ds_read_b128 v[174:177], v170 offset:32768
	ds_read_b128 v[178:181], v170 offset:33792
	ds_read_b128 v[182:185], v170 offset:34816
	ds_read_b128 v[186:189], v170 offset:35840
	ds_read_b128 v[190:193], v170 offset:36864
	ds_read_b128 v[194:197], v170 offset:37888
	ds_read_b128 v[198:201], v170 offset:38912
	ds_read_b128 v[202:205], v170 offset:39936
	global_load_lds_dwordx4 v152, s[0:1]
	s_mov_b32 m0, s29
	s_nop 0
	global_load_lds_dwordx4 v148, s[0:1]
	s_waitcnt lgkmcnt(8)
	s_waitcnt vmcnt(10)
	s_barrier
	s_waitcnt lgkmcnt(0)
	s_waitcnt lgkmcnt(0)
	v_mfma_scale_f32_16x16x128_f8f6f4 v[142:145], v[2:9], v[174:181], v[142:145], v171, v171 op_sel_hi:[0,0,0]
	v_mfma_scale_f32_16x16x128_f8f6f4 v[138:141], v[10:17], v[174:181], v[138:141], v171, v171 op_sel_hi:[0,0,0]
	v_mfma_scale_f32_16x16x128_f8f6f4 v[126:129], v[2:9], v[182:189], v[126:129], v171, v171 op_sel_hi:[0,0,0]
	v_mfma_scale_f32_16x16x128_f8f6f4 v[122:125], v[10:17], v[182:189], v[122:125], v171, v171 op_sel_hi:[0,0,0]
	v_mfma_scale_f32_16x16x128_f8f6f4 v[110:113], v[2:9], v[190:197], v[110:113], v171, v171 op_sel_hi:[0,0,0]
	v_mfma_scale_f32_16x16x128_f8f6f4 v[106:109], v[10:17], v[190:197], v[106:109], v171, v171 op_sel_hi:[0,0,0]
	v_mfma_scale_f32_16x16x128_f8f6f4 v[94:97], v[2:9], v[198:205], v[94:97], v171, v171 op_sel_hi:[0,0,0]
	v_mfma_scale_f32_16x16x128_f8f6f4 v[90:93], v[10:17], v[198:205], v[90:93], v171, v171 op_sel_hi:[0,0,0]
	s_barrier
	s_add_i32 s38, 0, 0x1c000
	s_add_i32 s0, s54, s9
	v_add_u32_e32 v218, s38, v168
	v_lshl_add_u64 v[162:163], v[162:163], 0, s[16:17]
	s_mov_b32 m0, s0
	ds_read_b128 v[206:209], v218
	ds_read_b128 v[210:213], v218 offset:1024
	ds_read_b128 v[214:217], v218 offset:2048
	ds_read_b128 v[218:221], v218 offset:3072
	global_load_lds_dwordx4 v[162:163], off
	v_lshl_add_u64 v[162:163], v[164:165], 0, s[16:17]
	s_add_i32 m0, s0, 0x2000
	s_nop 0
	global_load_lds_dwordx4 v[162:163], off
	s_waitcnt vmcnt(10)
	s_barrier
	s_waitcnt lgkmcnt(0)
	s_waitcnt lgkmcnt(0)
	v_mfma_scale_f32_16x16x128_f8f6f4 v[134:137], v[206:213], v[174:181], v[134:137], v171, v171 op_sel_hi:[0,0,0]
	v_mfma_scale_f32_16x16x128_f8f6f4 v[130:133], v[214:221], v[174:181], v[130:133], v171, v171 op_sel_hi:[0,0,0]
	v_mfma_scale_f32_16x16x128_f8f6f4 v[118:121], v[206:213], v[182:189], v[118:121], v171, v171 op_sel_hi:[0,0,0]
	v_mfma_scale_f32_16x16x128_f8f6f4 v[114:117], v[214:221], v[182:189], v[114:117], v171, v171 op_sel_hi:[0,0,0]
	v_mfma_scale_f32_16x16x128_f8f6f4 v[102:105], v[206:213], v[190:197], v[102:105], v171, v171 op_sel_hi:[0,0,0]
	v_mfma_scale_f32_16x16x128_f8f6f4 v[98:101], v[214:221], v[190:197], v[98:101], v171, v171 op_sel_hi:[0,0,0]
	v_mfma_scale_f32_16x16x128_f8f6f4 v[86:89], v[206:213], v[198:205], v[86:89], v171, v171 op_sel_hi:[0,0,0]
	v_mfma_scale_f32_16x16x128_f8f6f4 v[82:85], v[214:221], v[198:205], v[82:85], v171, v171 op_sel_hi:[0,0,0]
	s_mov_b32 m0, s43
	s_barrier
	ds_read_b128 v[174:177], v170 offset:49152
	ds_read_b128 v[178:181], v170 offset:50176
	ds_read_b128 v[182:185], v170 offset:51200
	ds_read_b128 v[186:189], v170 offset:52224
	ds_read_b128 v[190:193], v170 offset:53248
	ds_read_b128 v[194:197], v170 offset:54272
	ds_read_b128 v[198:201], v170 offset:55296
	ds_read_b128 v[202:205], v170 offset:56320
	global_load_lds_dwordx4 v152, s[36:37]
	s_mov_b32 m0, s44
	s_nop 0
	global_load_lds_dwordx4 v148, s[36:37]
	s_waitcnt vmcnt(10)
	s_barrier
	s_waitcnt lgkmcnt(0)
	s_waitcnt lgkmcnt(0)
	v_mfma_scale_f32_16x16x128_f8f6f4 v[78:81], v[2:9], v[174:181], v[78:81], v171, v171 op_sel_hi:[0,0,0]
	v_mfma_scale_f32_16x16x128_f8f6f4 v[74:77], v[10:17], v[174:181], v[74:77], v171, v171 op_sel_hi:[0,0,0]
	v_mfma_scale_f32_16x16x128_f8f6f4 v[62:65], v[2:9], v[182:189], v[62:65], v171, v171 op_sel_hi:[0,0,0]
	v_mfma_scale_f32_16x16x128_f8f6f4 v[58:61], v[10:17], v[182:189], v[58:61], v171, v171 op_sel_hi:[0,0,0]
	v_mfma_scale_f32_16x16x128_f8f6f4 v[46:49], v[2:9], v[190:197], v[46:49], v171, v171 op_sel_hi:[0,0,0]
	v_mfma_scale_f32_16x16x128_f8f6f4 v[42:45], v[10:17], v[190:197], v[42:45], v171, v171 op_sel_hi:[0,0,0]
	v_mfma_scale_f32_16x16x128_f8f6f4 v[30:33], v[2:9], v[198:205], v[30:33], v171, v171 op_sel_hi:[0,0,0]
	v_mfma_scale_f32_16x16x128_f8f6f4 v[26:29], v[10:17], v[198:205], v[26:29], v171, v171 op_sel_hi:[0,0,0]
	s_barrier
	s_add_u32 s0, s34, 0x20080
	s_addc_u32 s1, s35, 0
	s_add_i32 s34, s38, s9
	s_mov_b32 m0, s34
	s_nop 0
	global_load_lds_dwordx4 v150, s[0:1]
	s_add_i32 m0, s34, 0x2000
	s_nop 0
	global_load_lds_dwordx4 v146, s[0:1]
	s_waitcnt vmcnt(10)
	s_barrier
	v_mfma_scale_f32_16x16x128_f8f6f4 v[70:73], v[206:213], v[174:181], v[70:73], v171, v171 op_sel_hi:[0,0,0]
	v_mfma_scale_f32_16x16x128_f8f6f4 v[66:69], v[214:221], v[174:181], v[66:69], v171, v171 op_sel_hi:[0,0,0]
	v_mfma_scale_f32_16x16x128_f8f6f4 v[54:57], v[206:213], v[182:189], v[54:57], v171, v171 op_sel_hi:[0,0,0]
	v_mfma_scale_f32_16x16x128_f8f6f4 v[50:53], v[214:221], v[182:189], v[50:53], v171, v171 op_sel_hi:[0,0,0]
	v_mfma_scale_f32_16x16x128_f8f6f4 v[38:41], v[206:213], v[190:197], v[38:41], v171, v171 op_sel_hi:[0,0,0]
	v_mfma_scale_f32_16x16x128_f8f6f4 v[34:37], v[214:221], v[190:197], v[34:37], v171, v171 op_sel_hi:[0,0,0]
	v_mfma_scale_f32_16x16x128_f8f6f4 v[22:25], v[206:213], v[198:205], v[22:25], v171, v171 op_sel_hi:[0,0,0]
	v_mfma_scale_f32_16x16x128_f8f6f4 v[18:21], v[214:221], v[198:205], v[18:21], v171, v171 op_sel_hi:[0,0,0]
	s_add_i32 s53, s53, 2
	s_add_u32 s51, s51, 0x100
	s_addc_u32 s52, s52, 0
	s_add_u32 s30, s30, 0x10000
	s_addc_u32 s31, s31, 0
	s_cmp_gt_u32 s53, 5
	s_barrier
	s_cbranch_scc1 .Lpeel_exit_12
.LBB0_2108:
	ds_read_b128 v[2:5], v169
	ds_read_b128 v[6:9], v169 offset:1024
	ds_read_b128 v[10:13], v169 offset:2048
	ds_read_b128 v[14:17], v169 offset:3072
	s_add_u32 s0, s30, 0x4000
	s_addc_u32 s1, s31, 0
	s_cmp_eq_u32 s53, 4
	s_cselect_b32 s38, s49, s0
	s_cselect_b32 s39, s23, s1
	s_cselect_b32 s34, s50, s51
	s_cselect_b32 s35, s21, s52
	s_add_u32 s36, s38, 0x8000
	s_addc_u32 s37, s39, 0
	s_add_i32 m0, s10, 0xc000
	ds_read_b128 v[174:177], v170
	ds_read_b128 v[178:181], v170 offset:1024
	ds_read_b128 v[182:185], v170 offset:2048
	ds_read_b128 v[186:189], v170 offset:3072
	ds_read_b128 v[190:193], v170 offset:4096
	ds_read_b128 v[194:197], v170 offset:5120
	ds_read_b128 v[198:201], v170 offset:6144
	ds_read_b128 v[202:205], v170 offset:7168
	global_load_lds_dwordx4 v156, s[30:31]
	s_add_i32 m0, s10, 0xe000
	s_nop 0
	global_load_lds_dwordx4 v154, s[30:31]
	s_waitcnt lgkmcnt(8)
	s_waitcnt vmcnt(10)
	s_barrier
	s_waitcnt lgkmcnt(0)
	s_waitcnt lgkmcnt(0)
	v_mfma_scale_f32_16x16x128_f8f6f4 v[142:145], v[2:9], v[174:181], v[142:145], v171, v171 op_sel_hi:[0,0,0]
	v_mfma_scale_f32_16x16x128_f8f6f4 v[138:141], v[10:17], v[174:181], v[138:141], v171, v171 op_sel_hi:[0,0,0]
	v_mfma_scale_f32_16x16x128_f8f6f4 v[126:129], v[2:9], v[182:189], v[126:129], v171, v171 op_sel_hi:[0,0,0]
	v_mfma_scale_f32_16x16x128_f8f6f4 v[122:125], v[10:17], v[182:189], v[122:125], v171, v171 op_sel_hi:[0,0,0]
	v_mfma_scale_f32_16x16x128_f8f6f4 v[110:113], v[2:9], v[190:197], v[110:113], v171, v171 op_sel_hi:[0,0,0]
	v_mfma_scale_f32_16x16x128_f8f6f4 v[106:109], v[10:17], v[190:197], v[106:109], v171, v171 op_sel_hi:[0,0,0]
	v_mfma_scale_f32_16x16x128_f8f6f4 v[94:97], v[2:9], v[198:205], v[94:97], v171, v171 op_sel_hi:[0,0,0]
	v_mfma_scale_f32_16x16x128_f8f6f4 v[90:93], v[10:17], v[198:205], v[90:93], v171, v171 op_sel_hi:[0,0,0]
	s_barrier
	s_add_i32 s0, s45, s9
	v_lshl_add_u64 v[162:163], s[34:35], 0, v[150:151]
	s_mov_b32 m0, s0
	ds_read_b128 v[206:209], v172
	ds_read_b128 v[210:213], v172 offset:1024
	ds_read_b128 v[214:217], v172 offset:2048
	ds_read_b128 v[218:221], v172 offset:3072
	global_load_lds_dwordx4 v[162:163], off
	v_lshl_add_u64 v[164:165], s[34:35], 0, v[146:147]
	s_add_i32 m0, s0, 0x2000
	s_nop 0
	global_load_lds_dwordx4 v[164:165], off
	s_waitcnt vmcnt(10)
	s_barrier
	s_waitcnt lgkmcnt(0)
	s_waitcnt lgkmcnt(0)
	v_mfma_scale_f32_16x16x128_f8f6f4 v[134:137], v[206:213], v[174:181], v[134:137], v171, v171 op_sel_hi:[0,0,0]
	v_mfma_scale_f32_16x16x128_f8f6f4 v[130:133], v[214:221], v[174:181], v[130:133], v171, v171 op_sel_hi:[0,0,0]
	v_mfma_scale_f32_16x16x128_f8f6f4 v[118:121], v[206:213], v[182:189], v[118:121], v171, v171 op_sel_hi:[0,0,0]
	v_mfma_scale_f32_16x16x128_f8f6f4 v[114:117], v[214:221], v[182:189], v[114:117], v171, v171 op_sel_hi:[0,0,0]
	v_mfma_scale_f32_16x16x128_f8f6f4 v[102:105], v[206:213], v[190:197], v[102:105], v171, v171 op_sel_hi:[0,0,0]
	v_mfma_scale_f32_16x16x128_f8f6f4 v[98:101], v[214:221], v[190:197], v[98:101], v171, v171 op_sel_hi:[0,0,0]
	v_mfma_scale_f32_16x16x128_f8f6f4 v[86:89], v[206:213], v[198:205], v[86:89], v171, v171 op_sel_hi:[0,0,0]
	v_mfma_scale_f32_16x16x128_f8f6f4 v[82:85], v[214:221], v[198:205], v[82:85], v171, v171 op_sel_hi:[0,0,0]
	s_mov_b32 m0, s10
	s_barrier
	ds_read_b128 v[174:177], v170 offset:16384
	ds_read_b128 v[178:181], v170 offset:17408
	ds_read_b128 v[182:185], v170 offset:18432
	ds_read_b128 v[186:189], v170 offset:19456
	ds_read_b128 v[190:193], v170 offset:20480
	ds_read_b128 v[194:197], v170 offset:21504
	ds_read_b128 v[198:201], v170 offset:22528
	ds_read_b128 v[202:205], v170 offset:23552
	global_load_lds_dwordx4 v152, s[38:39]
	s_mov_b32 m0, s11
	s_nop 0
	global_load_lds_dwordx4 v148, s[38:39]
	s_waitcnt vmcnt(10)
	s_barrier
	s_waitcnt lgkmcnt(0)
	s_waitcnt lgkmcnt(0)
	v_mfma_scale_f32_16x16x128_f8f6f4 v[78:81], v[2:9], v[174:181], v[78:81], v171, v171 op_sel_hi:[0,0,0]
	v_mfma_scale_f32_16x16x128_f8f6f4 v[74:77], v[10:17], v[174:181], v[74:77], v171, v171 op_sel_hi:[0,0,0]
	v_mfma_scale_f32_16x16x128_f8f6f4 v[62:65], v[2:9], v[182:189], v[62:65], v171, v171 op_sel_hi:[0,0,0]
	v_mfma_scale_f32_16x16x128_f8f6f4 v[58:61], v[10:17], v[182:189], v[58:61], v171, v171 op_sel_hi:[0,0,0]
	v_mfma_scale_f32_16x16x128_f8f6f4 v[46:49], v[2:9], v[190:197], v[46:49], v171, v171 op_sel_hi:[0,0,0]
	v_mfma_scale_f32_16x16x128_f8f6f4 v[42:45], v[10:17], v[190:197], v[42:45], v171, v171 op_sel_hi:[0,0,0]
	v_mfma_scale_f32_16x16x128_f8f6f4 v[30:33], v[2:9], v[198:205], v[30:33], v171, v171 op_sel_hi:[0,0,0]
	v_mfma_scale_f32_16x16x128_f8f6f4 v[26:29], v[10:17], v[198:205], v[26:29], v171, v171 op_sel_hi:[0,0,0]
	s_barrier
	s_add_u32 s0, s34, 0x20000
	s_addc_u32 s1, s35, 0
	s_add_i32 s54, s46, s9
	s_mov_b32 m0, s54
	s_nop 0
	global_load_lds_dwordx4 v150, s[0:1]
	s_add_i32 m0, s54, 0x2000
	s_nop 0
	global_load_lds_dwordx4 v146, s[0:1]
	s_waitcnt vmcnt(10)
	s_barrier
	v_mfma_scale_f32_16x16x128_f8f6f4 v[70:73], v[206:213], v[174:181], v[70:73], v171, v171 op_sel_hi:[0,0,0]
	v_mfma_scale_f32_16x16x128_f8f6f4 v[66:69], v[214:221], v[174:181], v[66:69], v171, v171 op_sel_hi:[0,0,0]
	v_mfma_scale_f32_16x16x128_f8f6f4 v[54:57], v[206:213], v[182:189], v[54:57], v171, v171 op_sel_hi:[0,0,0]
	v_mfma_scale_f32_16x16x128_f8f6f4 v[50:53], v[214:221], v[182:189], v[50:53], v171, v171 op_sel_hi:[0,0,0]
	v_mfma_scale_f32_16x16x128_f8f6f4 v[38:41], v[206:213], v[190:197], v[38:41], v171, v171 op_sel_hi:[0,0,0]
	v_mfma_scale_f32_16x16x128_f8f6f4 v[34:37], v[214:221], v[190:197], v[34:37], v171, v171 op_sel_hi:[0,0,0]
	v_mfma_scale_f32_16x16x128_f8f6f4 v[22:25], v[206:213], v[198:205], v[22:25], v171, v171 op_sel_hi:[0,0,0]
	v_mfma_scale_f32_16x16x128_f8f6f4 v[18:21], v[214:221], v[198:205], v[18:21], v171, v171 op_sel_hi:[0,0,0]
	s_add_i32 s54, 0, 0x18000
	v_add_u32_e32 v14, s54, v168
	s_barrier
	ds_read_b128 v[2:5], v14
	ds_read_b128 v[6:9], v14 offset:1024
	ds_read_b128 v[10:13], v14 offset:2048
	ds_read_b128 v[14:17], v14 offset:3072
	s_add_u32 s0, s38, 0x4000
	s_addc_u32 s1, s39, 0
	s_mov_b32 m0, s19
	ds_read_b128 v[174:177], v170 offset:32768
	ds_read_b128 v[178:181], v170 offset:33792
	ds_read_b128 v[182:185], v170 offset:34816
	ds_read_b128 v[186:189], v170 offset:35840
	ds_read_b128 v[190:193], v170 offset:36864
	ds_read_b128 v[194:197], v170 offset:37888
	ds_read_b128 v[198:201], v170 offset:38912
	ds_read_b128 v[202:205], v170 offset:39936
	global_load_lds_dwordx4 v152, s[0:1]
	s_mov_b32 m0, s29
	s_nop 0
	global_load_lds_dwordx4 v148, s[0:1]
	s_waitcnt lgkmcnt(8)
	s_waitcnt vmcnt(10)
	s_barrier
	s_waitcnt lgkmcnt(0)
	s_waitcnt lgkmcnt(0)
	v_mfma_scale_f32_16x16x128_f8f6f4 v[142:145], v[2:9], v[174:181], v[142:145], v171, v171 op_sel_hi:[0,0,0]
	v_mfma_scale_f32_16x16x128_f8f6f4 v[138:141], v[10:17], v[174:181], v[138:141], v171, v171 op_sel_hi:[0,0,0]
	v_mfma_scale_f32_16x16x128_f8f6f4 v[126:129], v[2:9], v[182:189], v[126:129], v171, v171 op_sel_hi:[0,0,0]
	v_mfma_scale_f32_16x16x128_f8f6f4 v[122:125], v[10:17], v[182:189], v[122:125], v171, v171 op_sel_hi:[0,0,0]
	v_mfma_scale_f32_16x16x128_f8f6f4 v[110:113], v[2:9], v[190:197], v[110:113], v171, v171 op_sel_hi:[0,0,0]
	v_mfma_scale_f32_16x16x128_f8f6f4 v[106:109], v[10:17], v[190:197], v[106:109], v171, v171 op_sel_hi:[0,0,0]
	v_mfma_scale_f32_16x16x128_f8f6f4 v[94:97], v[2:9], v[198:205], v[94:97], v171, v171 op_sel_hi:[0,0,0]
	v_mfma_scale_f32_16x16x128_f8f6f4 v[90:93], v[10:17], v[198:205], v[90:93], v171, v171 op_sel_hi:[0,0,0]
	s_barrier
	s_add_i32 s38, 0, 0x1c000
	s_add_i32 s0, s54, s9
	v_add_u32_e32 v218, s38, v168
	v_lshl_add_u64 v[162:163], v[162:163], 0, s[16:17]
	s_mov_b32 m0, s0
	ds_read_b128 v[206:209], v218
	ds_read_b128 v[210:213], v218 offset:1024
	ds_read_b128 v[214:217], v218 offset:2048
	ds_read_b128 v[218:221], v218 offset:3072
	global_load_lds_dwordx4 v[162:163], off
	v_lshl_add_u64 v[162:163], v[164:165], 0, s[16:17]
	s_add_i32 m0, s0, 0x2000
	s_nop 0
	global_load_lds_dwordx4 v[162:163], off
	s_waitcnt vmcnt(10)
	s_barrier
	s_waitcnt lgkmcnt(0)
	s_waitcnt lgkmcnt(0)
	v_mfma_scale_f32_16x16x128_f8f6f4 v[134:137], v[206:213], v[174:181], v[134:137], v171, v171 op_sel_hi:[0,0,0]
	v_mfma_scale_f32_16x16x128_f8f6f4 v[130:133], v[214:221], v[174:181], v[130:133], v171, v171 op_sel_hi:[0,0,0]
	v_mfma_scale_f32_16x16x128_f8f6f4 v[118:121], v[206:213], v[182:189], v[118:121], v171, v171 op_sel_hi:[0,0,0]
	v_mfma_scale_f32_16x16x128_f8f6f4 v[114:117], v[214:221], v[182:189], v[114:117], v171, v171 op_sel_hi:[0,0,0]
	v_mfma_scale_f32_16x16x128_f8f6f4 v[102:105], v[206:213], v[190:197], v[102:105], v171, v171 op_sel_hi:[0,0,0]
	v_mfma_scale_f32_16x16x128_f8f6f4 v[98:101], v[214:221], v[190:197], v[98:101], v171, v171 op_sel_hi:[0,0,0]
	v_mfma_scale_f32_16x16x128_f8f6f4 v[86:89], v[206:213], v[198:205], v[86:89], v171, v171 op_sel_hi:[0,0,0]
	v_mfma_scale_f32_16x16x128_f8f6f4 v[82:85], v[214:221], v[198:205], v[82:85], v171, v171 op_sel_hi:[0,0,0]
	s_mov_b32 m0, s43
	s_barrier
	ds_read_b128 v[174:177], v170 offset:49152
	ds_read_b128 v[178:181], v170 offset:50176
	ds_read_b128 v[182:185], v170 offset:51200
	ds_read_b128 v[186:189], v170 offset:52224
	ds_read_b128 v[190:193], v170 offset:53248
	ds_read_b128 v[194:197], v170 offset:54272
	ds_read_b128 v[198:201], v170 offset:55296
	ds_read_b128 v[202:205], v170 offset:56320
	global_load_lds_dwordx4 v152, s[36:37]
	s_mov_b32 m0, s44
	s_nop 0
	global_load_lds_dwordx4 v148, s[36:37]
	s_waitcnt vmcnt(10)
	s_barrier
	s_waitcnt lgkmcnt(0)
	s_waitcnt lgkmcnt(0)
	v_mfma_scale_f32_16x16x128_f8f6f4 v[78:81], v[2:9], v[174:181], v[78:81], v171, v171 op_sel_hi:[0,0,0]
	v_mfma_scale_f32_16x16x128_f8f6f4 v[74:77], v[10:17], v[174:181], v[74:77], v171, v171 op_sel_hi:[0,0,0]
	v_mfma_scale_f32_16x16x128_f8f6f4 v[62:65], v[2:9], v[182:189], v[62:65], v171, v171 op_sel_hi:[0,0,0]
	v_mfma_scale_f32_16x16x128_f8f6f4 v[58:61], v[10:17], v[182:189], v[58:61], v171, v171 op_sel_hi:[0,0,0]
	v_mfma_scale_f32_16x16x128_f8f6f4 v[46:49], v[2:9], v[190:197], v[46:49], v171, v171 op_sel_hi:[0,0,0]
	v_mfma_scale_f32_16x16x128_f8f6f4 v[42:45], v[10:17], v[190:197], v[42:45], v171, v171 op_sel_hi:[0,0,0]
	v_mfma_scale_f32_16x16x128_f8f6f4 v[30:33], v[2:9], v[198:205], v[30:33], v171, v171 op_sel_hi:[0,0,0]
	v_mfma_scale_f32_16x16x128_f8f6f4 v[26:29], v[10:17], v[198:205], v[26:29], v171, v171 op_sel_hi:[0,0,0]
	s_barrier
	s_add_u32 s0, s34, 0x20080
	s_addc_u32 s1, s35, 0
	s_add_i32 s34, s38, s9
	s_mov_b32 m0, s34
	s_nop 0
	global_load_lds_dwordx4 v150, s[0:1]
	s_add_i32 m0, s34, 0x2000
	s_nop 0
	global_load_lds_dwordx4 v146, s[0:1]
	s_waitcnt vmcnt(10)
	s_barrier
	v_mfma_scale_f32_16x16x128_f8f6f4 v[70:73], v[206:213], v[174:181], v[70:73], v171, v171 op_sel_hi:[0,0,0]
	v_mfma_scale_f32_16x16x128_f8f6f4 v[66:69], v[214:221], v[174:181], v[66:69], v171, v171 op_sel_hi:[0,0,0]
	v_mfma_scale_f32_16x16x128_f8f6f4 v[54:57], v[206:213], v[182:189], v[54:57], v171, v171 op_sel_hi:[0,0,0]
	v_mfma_scale_f32_16x16x128_f8f6f4 v[50:53], v[214:221], v[182:189], v[50:53], v171, v171 op_sel_hi:[0,0,0]
	v_mfma_scale_f32_16x16x128_f8f6f4 v[38:41], v[206:213], v[190:197], v[38:41], v171, v171 op_sel_hi:[0,0,0]
	v_mfma_scale_f32_16x16x128_f8f6f4 v[34:37], v[214:221], v[190:197], v[34:37], v171, v171 op_sel_hi:[0,0,0]
	v_mfma_scale_f32_16x16x128_f8f6f4 v[22:25], v[206:213], v[198:205], v[22:25], v171, v171 op_sel_hi:[0,0,0]
	v_mfma_scale_f32_16x16x128_f8f6f4 v[18:21], v[214:221], v[198:205], v[18:21], v171, v171 op_sel_hi:[0,0,0]
	s_add_i32 s53, s53, 2
	s_add_u32 s51, s51, 0x100
	s_addc_u32 s52, s52, 0
	s_add_u32 s30, s30, 0x10000
	s_addc_u32 s31, s31, 0
	s_cmp_gt_u32 s53, 5
	s_barrier
	s_cbranch_scc0 .LBB0_2108

.LBB0_2243:
	v_bfe_u32 v144, v12, 4, 2
	v_and_b32_e32 v143, 15, v12
	v_lshlrev_b32_e32 v13, 4, v144
	v_lshlrev_b32_e32 v12, 2, v12
	s_and_b32 s1, s1, 3
	s_lshl_b32 s40, s0, 6
	v_lshl_or_b32 v13, v143, 6, v13
	s_lshl_b32 s0, s0, 13
	v_and_b32_e32 v12, 32, v12
	v_bitop3_b32 v14, v13, s0, v12 bitop3:0xde
	s_lshl_b32 s41, s1, 5
	s_lshl_b32 s0, s1, 12
	v_bitop3_b32 v145, v13, s0, v12 bitop3:0xde
	s_add_u32 s0, s22, 0x1a00080
	s_addc_u32 s1, s23, 0
	s_add_i32 m0, s9, 0x18000
	s_waitcnt vmcnt(4)
	s_barrier
	global_load_lds_dwordx4 v134, s[0:1]
	v_lshl_add_u64 v[12:13], s[0:1], 0, v[130:131]
	s_add_i32 m0, s9, 0x1a000
	s_mov_b64 s[24:25], 0x80
	s_add_i32 s42, s9, 0x8000
	s_add_i32 s43, s9, 0xa000
	global_load_lds_dwordx4 v[12:13], off
	v_lshl_add_u64 v[4:5], v[4:5], 0, s[24:25]
	s_mov_b32 m0, s42
	s_add_u32 s0, s22, 0x1a40080
	global_load_lds_dwordx4 v[4:5], off
	v_lshl_add_u64 v[2:3], v[2:3], 0, s[24:25]
	s_mov_b32 m0, s43
	s_addc_u32 s1, s23, 0
	global_load_lds_dwordx4 v[2:3], off
	s_add_i32 m0, s9, 0x1c000
	s_nop 0
	global_load_lds_dwordx4 v134, s[0:1]
	s_add_i32 m0, s9, 0x1e000
	s_add_i32 s48, 0, 0x10000
	global_load_lds_dwordx4 v130, s[0:1]
	v_lshlrev_b32_e32 v2, 14, v6
	v_and_b32_e32 v2, 0xffff8000, v2
	v_lshl_add_u32 v2, v7, 11, v2
	v_and_b32_e32 v3, 1, v6
	v_lshl_or_b32 v2, v3, 6, v2
	v_lshl_add_u32 v138, v8, 1, v2
	v_lshlrev_b32_e32 v2, 14, v10
	v_and_b32_e32 v2, 0xffff8000, v2
	s_waitcnt vmcnt(6)
	v_lshl_add_u32 v2, v9, 11, v2
	v_and_b32_e32 v3, 1, v10
	v_lshl_or_b32 v2, v3, 6, v2
	v_add_u32_e32 v146, s48, v145
	s_add_i32 s44, 0, 0x14000
	s_add_i32 s48, s48, s8
	v_mov_b32_e32 v139, v135
	v_lshl_add_u32 v140, v11, 1, v2
	v_mov_b32_e32 v141, v135
	v_add_u32_e32 v147, 0, v14
	v_add_u32_e32 v148, s44, v145
	s_movk_i32 s45, 0x600
	s_add_i32 s46, s9, 0xc000
	s_add_i32 s47, s9, 0xe000
	s_add_i32 s49, s48, 0x2000
	s_mov_b32 s54, s2
	s_mov_b64 s[28:29], s[10:11]
	s_mov_b32 s50, 0
	s_barrier
.LBB0_2244:
	s_add_i32 s50, s50, 1
	s_mov_b64 s[0:1], s[16:17]
	s_mul_hi_u32 s16, s50, 0xaaaaaaab
	s_lshr_b32 s16, s16, 1
	s_mul_i32 s17, s16, s74
	s_mov_b64 s[30:31], s[28:29]
	s_mov_b32 s29, s51
	s_add_i32 s51, s17, s2
	s_cmpk_lt_i32 s51, 0x100
	s_cselect_b64 s[34:35], -1, 0
	s_cmpk_gt_i32 s51, 0xff
	s_mul_i32 s16, s16, 3
	s_mov_b32 s28, s52
	s_cselect_b64 s[26:27], -1, 0
	s_sub_i32 s52, s50, s16
	s_and_b64 s[16:17], s[34:35], exec
	s_cselect_b32 s16, s51, s29
	s_cselect_b32 s28, s52, s28
	s_ashr_i32 s17, s16, 31
	s_lshl_b64 s[16:17], s[16:17], 19
	s_add_u32 s16, s6, s16
	s_addc_u32 s17, s7, s17
	s_and_b64 s[36:37], s[34:35], exec
	s_cselect_b32 s55, s17, s1
	s_cselect_b32 s56, s16, s0
	s_ashr_i32 s29, s28, 31
	s_lshl_b64 s[28:29], s[28:29], 19
	s_add_u32 s28, s10, s28
	s_addc_u32 s29, s11, s29
	s_and_b64 s[34:35], s[34:35], exec
	s_cselect_b32 s57, s29, s31
	s_cselect_b32 s58, s28, s30
	s_add_u32 s59, s30, 0x100
	s_addc_u32 s60, s31, 0
	s_add_u32 s30, s0, 0x40080
	s_addc_u32 s31, s1, 0
	s_mov_b32 s61, -2
	ds_read_b128 v[150:153], v146
	ds_read_b128 v[154:157], v146 offset:1024
	ds_read_b128 v[158:161], v146 offset:2048
	ds_read_b128 v[162:165], v146 offset:3072
	s_add_u32 s0, s30, 0xfffc0080
	s_addc_u32 s1, s31, -1
	s_cmp_eq_u32 s61, 12
	s_cselect_b32 s37, s55, s1
	s_cselect_b32 s36, s56, s0
	s_cselect_b32 s35, s57, s60
	s_cselect_b32 s34, s58, s59
	s_mov_b32 m0, s46
	ds_read_b128 v[166:169], v147
	ds_read_b128 v[170:173], v147 offset:1024
	ds_read_b128 v[174:177], v147 offset:2048
	ds_read_b128 v[178:181], v147 offset:3072
	ds_read_b128 v[182:185], v147 offset:4096
	ds_read_b128 v[186:189], v147 offset:5120
	ds_read_b128 v[190:193], v147 offset:6144
	ds_read_b128 v[194:197], v147 offset:7168
	global_load_lds_dwordx4 v140, s[30:31]
	s_mov_b32 m0, s47
	s_nop 0
	global_load_lds_dwordx4 v138, s[30:31]
	s_waitcnt lgkmcnt(8)
	s_waitcnt vmcnt(10)
	s_barrier
	s_waitcnt lgkmcnt(0)
	s_waitcnt lgkmcnt(0)
	v_mfma_f32_16x16x32_bf16 v[126:129], v[150:153], v[166:169], 0
	v_mfma_f32_16x16x32_bf16 v[122:125], v[158:161], v[166:169], 0
	v_mfma_f32_16x16x32_bf16 v[118:121], v[150:153], v[174:177], 0
	v_mfma_f32_16x16x32_bf16 v[114:117], v[158:161], v[174:177], 0
	v_mfma_f32_16x16x32_bf16 v[102:105], v[150:153], v[182:185], 0
	v_mfma_f32_16x16x32_bf16 v[98:101], v[158:161], v[182:185], 0
	v_mfma_f32_16x16x32_bf16 v[86:89], v[150:153], v[190:193], 0
	v_mfma_f32_16x16x32_bf16 v[82:85], v[158:161], v[190:193], 0
	v_mfma_f32_16x16x32_bf16 v[126:129], v[154:157], v[170:173], v[126:129]
	v_mfma_f32_16x16x32_bf16 v[122:125], v[162:165], v[170:173], v[122:125]
	v_mfma_f32_16x16x32_bf16 v[118:121], v[154:157], v[178:181], v[118:121]
	v_mfma_f32_16x16x32_bf16 v[114:117], v[162:165], v[178:181], v[114:117]
	v_mfma_f32_16x16x32_bf16 v[102:105], v[154:157], v[186:189], v[102:105]
	v_mfma_f32_16x16x32_bf16 v[98:101], v[162:165], v[186:189], v[98:101]
	v_mfma_f32_16x16x32_bf16 v[86:89], v[154:157], v[194:197], v[86:89]
	v_mfma_f32_16x16x32_bf16 v[82:85], v[162:165], v[194:197], v[82:85]
	s_barrier
	s_mov_b32 m0, s48
	v_lshl_add_u64 v[214:215], s[34:35], 0, v[134:135]
	ds_read_b128 v[198:201], v148
	ds_read_b128 v[202:205], v148 offset:1024
	ds_read_b128 v[206:209], v148 offset:2048
	ds_read_b128 v[210:213], v148 offset:3072
	global_load_lds_dwordx4 v[214:215], off
	v_lshl_add_u64 v[216:217], s[34:35], 0, v[130:131]
	s_mov_b32 m0, s49
	s_nop 0
	global_load_lds_dwordx4 v[216:217], off
	s_waitcnt vmcnt(10)
	s_barrier
	s_waitcnt lgkmcnt(0)
	s_waitcnt lgkmcnt(0)
	v_mfma_f32_16x16x32_bf16 v[110:113], v[198:201], v[166:169], 0
	v_mfma_f32_16x16x32_bf16 v[106:109], v[206:209], v[166:169], 0
	v_mfma_f32_16x16x32_bf16 v[94:97], v[198:201], v[174:177], 0
	v_mfma_f32_16x16x32_bf16 v[90:93], v[206:209], v[174:177], 0
	v_mfma_f32_16x16x32_bf16 v[78:81], v[198:201], v[182:185], 0
	v_mfma_f32_16x16x32_bf16 v[74:77], v[206:209], v[182:185], 0
	v_mfma_f32_16x16x32_bf16 v[70:73], v[198:201], v[190:193], 0
	v_mfma_f32_16x16x32_bf16 v[66:69], v[206:209], v[190:193], 0
	v_mfma_f32_16x16x32_bf16 v[110:113], v[202:205], v[170:173], v[110:113]
	v_mfma_f32_16x16x32_bf16 v[106:109], v[210:213], v[170:173], v[106:109]
	v_mfma_f32_16x16x32_bf16 v[94:97], v[202:205], v[178:181], v[94:97]
	v_mfma_f32_16x16x32_bf16 v[90:93], v[210:213], v[178:181], v[90:93]
	v_mfma_f32_16x16x32_bf16 v[78:81], v[202:205], v[186:189], v[78:81]
	v_mfma_f32_16x16x32_bf16 v[74:77], v[210:213], v[186:189], v[74:77]
	v_mfma_f32_16x16x32_bf16 v[70:73], v[202:205], v[194:197], v[70:73]
	v_mfma_f32_16x16x32_bf16 v[66:69], v[210:213], v[194:197], v[66:69]
	s_mov_b32 m0, s9
	v_lshl_add_u64 v[218:219], s[36:37], 0, v[136:137]
	s_barrier
	ds_read_b128 v[166:169], v147 offset:16384
	ds_read_b128 v[170:173], v147 offset:17408
	ds_read_b128 v[174:177], v147 offset:18432
	ds_read_b128 v[178:181], v147 offset:19456
	ds_read_b128 v[182:185], v147 offset:20480
	ds_read_b128 v[186:189], v147 offset:21504
	ds_read_b128 v[190:193], v147 offset:22528
	ds_read_b128 v[194:197], v147 offset:23552
	global_load_lds_dwordx4 v[218:219], off
	v_lshl_add_u64 v[220:221], s[36:37], 0, v[132:133]
	s_mov_b32 m0, s21
	s_nop 0
	global_load_lds_dwordx4 v[220:221], off
	s_waitcnt vmcnt(10)
	s_barrier
	s_waitcnt lgkmcnt(0)
	s_waitcnt lgkmcnt(0)
	v_mfma_f32_16x16x32_bf16 v[62:65], v[150:153], v[166:169], 0
	v_mfma_f32_16x16x32_bf16 v[58:61], v[158:161], v[166:169], 0
	v_mfma_f32_16x16x32_bf16 v[54:57], v[150:153], v[174:177], 0
	v_mfma_f32_16x16x32_bf16 v[50:53], v[158:161], v[174:177], 0
	v_mfma_f32_16x16x32_bf16 v[38:41], v[150:153], v[182:185], 0
	v_mfma_f32_16x16x32_bf16 v[34:37], v[158:161], v[182:185], 0
	v_mfma_f32_16x16x32_bf16 v[22:25], v[150:153], v[190:193], 0
	v_mfma_f32_16x16x32_bf16 v[18:21], v[158:161], v[190:193], 0
	v_mfma_f32_16x16x32_bf16 v[62:65], v[154:157], v[170:173], v[62:65]
	v_mfma_f32_16x16x32_bf16 v[58:61], v[162:165], v[170:173], v[58:61]
	v_mfma_f32_16x16x32_bf16 v[54:57], v[154:157], v[178:181], v[54:57]
	v_mfma_f32_16x16x32_bf16 v[50:53], v[162:165], v[178:181], v[50:53]
	v_mfma_f32_16x16x32_bf16 v[38:41], v[154:157], v[186:189], v[38:41]
	v_mfma_f32_16x16x32_bf16 v[34:37], v[162:165], v[186:189], v[34:37]
	v_mfma_f32_16x16x32_bf16 v[22:25], v[154:157], v[194:197], v[22:25]
	v_mfma_f32_16x16x32_bf16 v[18:21], v[162:165], v[194:197], v[18:21]
	s_barrier
	s_add_u32 s0, s34, 0x40000
	s_addc_u32 s1, s35, 0
	s_add_i32 s62, s44, s8
	s_mov_b32 m0, s62
	s_nop 0
	global_load_lds_dwordx4 v134, s[0:1]
	s_add_i32 m0, s62, 0x2000
	s_nop 0
	global_load_lds_dwordx4 v130, s[0:1]
	s_waitcnt vmcnt(10)
	s_barrier
	v_mfma_f32_16x16x32_bf16 v[46:49], v[198:201], v[166:169], 0
	v_mfma_f32_16x16x32_bf16 v[42:45], v[206:209], v[166:169], 0
	v_mfma_f32_16x16x32_bf16 v[30:33], v[198:201], v[174:177], 0
	v_mfma_f32_16x16x32_bf16 v[26:29], v[206:209], v[174:177], 0
	v_mfma_f32_16x16x32_bf16 v[14:17], v[198:201], v[182:185], 0
	v_mfma_f32_16x16x32_bf16 v[10:13], v[206:209], v[182:185], 0
	v_mfma_f32_16x16x32_bf16 v[6:9], v[198:201], v[190:193], 0
	v_mfma_f32_16x16x32_bf16 v[2:5], v[206:209], v[190:193], 0
	v_mfma_f32_16x16x32_bf16 v[46:49], v[202:205], v[170:173], v[46:49]
	v_mfma_f32_16x16x32_bf16 v[42:45], v[210:213], v[170:173], v[42:45]
	v_mfma_f32_16x16x32_bf16 v[30:33], v[202:205], v[178:181], v[30:33]
	v_mfma_f32_16x16x32_bf16 v[26:29], v[210:213], v[178:181], v[26:29]
	v_mfma_f32_16x16x32_bf16 v[14:17], v[202:205], v[186:189], v[14:17]
	v_mfma_f32_16x16x32_bf16 v[10:13], v[210:213], v[186:189], v[10:13]
	v_mfma_f32_16x16x32_bf16 v[6:9], v[202:205], v[194:197], v[6:9]
	v_mfma_f32_16x16x32_bf16 v[2:5], v[210:213], v[194:197], v[2:5]
	s_add_i32 s62, 0, 0x18000
	v_add_u32_e32 v149, s62, v145
	s_barrier
	ds_read_b128 v[150:153], v149
	ds_read_b128 v[154:157], v149 offset:1024
	ds_read_b128 v[158:161], v149 offset:2048
	ds_read_b128 v[162:165], v149 offset:3072
	s_add_u32 s0, s36, 0x40000
	s_addc_u32 s1, s37, 0
	s_mov_b32 m0, s38
	ds_read_b128 v[166:169], v147 offset:32768
	ds_read_b128 v[170:173], v147 offset:33792
	ds_read_b128 v[174:177], v147 offset:34816
	ds_read_b128 v[178:181], v147 offset:35840
	ds_read_b128 v[182:185], v147 offset:36864
	ds_read_b128 v[186:189], v147 offset:37888
	ds_read_b128 v[190:193], v147 offset:38912
	ds_read_b128 v[194:197], v147 offset:39936
	global_load_lds_dwordx4 v136, s[0:1]
	s_mov_b32 m0, s39
	s_nop 0
	global_load_lds_dwordx4 v132, s[0:1]
	s_waitcnt lgkmcnt(8)
	s_waitcnt vmcnt(10)
	s_barrier
	s_waitcnt lgkmcnt(0)
	s_waitcnt lgkmcnt(0)
	v_mfma_f32_16x16x32_bf16 v[126:129], v[150:153], v[166:169], v[126:129]
	v_mfma_f32_16x16x32_bf16 v[122:125], v[158:161], v[166:169], v[122:125]
	v_mfma_f32_16x16x32_bf16 v[118:121], v[150:153], v[174:177], v[118:121]
	v_mfma_f32_16x16x32_bf16 v[114:117], v[158:161], v[174:177], v[114:117]
	v_mfma_f32_16x16x32_bf16 v[102:105], v[150:153], v[182:185], v[102:105]
	v_mfma_f32_16x16x32_bf16 v[98:101], v[158:161], v[182:185], v[98:101]
	v_mfma_f32_16x16x32_bf16 v[86:89], v[150:153], v[190:193], v[86:89]
	v_mfma_f32_16x16x32_bf16 v[82:85], v[158:161], v[190:193], v[82:85]
	v_mfma_f32_16x16x32_bf16 v[126:129], v[154:157], v[170:173], v[126:129]
	v_mfma_f32_16x16x32_bf16 v[122:125], v[162:165], v[170:173], v[122:125]
	v_mfma_f32_16x16x32_bf16 v[118:121], v[154:157], v[178:181], v[118:121]
	v_mfma_f32_16x16x32_bf16 v[114:117], v[162:165], v[178:181], v[114:117]
	v_mfma_f32_16x16x32_bf16 v[102:105], v[154:157], v[186:189], v[102:105]
	v_mfma_f32_16x16x32_bf16 v[98:101], v[162:165], v[186:189], v[98:101]
	v_mfma_f32_16x16x32_bf16 v[86:89], v[154:157], v[194:197], v[86:89]
	v_mfma_f32_16x16x32_bf16 v[82:85], v[162:165], v[194:197], v[82:85]
	s_barrier
	s_add_i32 s36, 0, 0x1c000
	s_add_i32 s0, s62, s8
	v_add_u32_e32 v149, s36, v145
	v_lshl_add_u64 v[214:215], v[214:215], 0, s[24:25]
	s_mov_b32 m0, s0
	ds_read_b128 v[198:201], v149
	ds_read_b128 v[202:205], v149 offset:1024
	ds_read_b128 v[206:209], v149 offset:2048
	ds_read_b128 v[210:213], v149 offset:3072
	global_load_lds_dwordx4 v[214:215], off
	v_lshl_add_u64 v[214:215], v[216:217], 0, s[24:25]
	s_add_i32 m0, s0, 0x2000
	s_nop 0
	global_load_lds_dwordx4 v[214:215], off
	s_waitcnt vmcnt(10)
	s_barrier
	s_waitcnt lgkmcnt(0)
	s_waitcnt lgkmcnt(0)
	v_mfma_f32_16x16x32_bf16 v[110:113], v[198:201], v[166:169], v[110:113]
	v_mfma_f32_16x16x32_bf16 v[106:109], v[206:209], v[166:169], v[106:109]
	v_mfma_f32_16x16x32_bf16 v[94:97], v[198:201], v[174:177], v[94:97]
	v_mfma_f32_16x16x32_bf16 v[90:93], v[206:209], v[174:177], v[90:93]
	v_mfma_f32_16x16x32_bf16 v[78:81], v[198:201], v[182:185], v[78:81]
	v_mfma_f32_16x16x32_bf16 v[74:77], v[206:209], v[182:185], v[74:77]
	v_mfma_f32_16x16x32_bf16 v[70:73], v[198:201], v[190:193], v[70:73]
	v_mfma_f32_16x16x32_bf16 v[66:69], v[206:209], v[190:193], v[66:69]
	v_mfma_f32_16x16x32_bf16 v[110:113], v[202:205], v[170:173], v[110:113]
	v_mfma_f32_16x16x32_bf16 v[106:109], v[210:213], v[170:173], v[106:109]
	v_mfma_f32_16x16x32_bf16 v[94:97], v[202:205], v[178:181], v[94:97]
	v_mfma_f32_16x16x32_bf16 v[90:93], v[210:213], v[178:181], v[90:93]
	v_mfma_f32_16x16x32_bf16 v[78:81], v[202:205], v[186:189], v[78:81]
	v_mfma_f32_16x16x32_bf16 v[74:77], v[210:213], v[186:189], v[74:77]
	v_mfma_f32_16x16x32_bf16 v[70:73], v[202:205], v[194:197], v[70:73]
	v_mfma_f32_16x16x32_bf16 v[66:69], v[210:213], v[194:197], v[66:69]
	s_mov_b32 m0, s42
	v_lshl_add_u64 v[214:215], v[218:219], 0, s[24:25]
	s_barrier
	ds_read_b128 v[166:169], v147 offset:49152
	ds_read_b128 v[170:173], v147 offset:50176
	ds_read_b128 v[174:177], v147 offset:51200
	ds_read_b128 v[178:181], v147 offset:52224
	ds_read_b128 v[182:185], v147 offset:53248
	ds_read_b128 v[186:189], v147 offset:54272
	ds_read_b128 v[190:193], v147 offset:55296
	ds_read_b128 v[194:197], v147 offset:56320
	global_load_lds_dwordx4 v[214:215], off
	v_lshl_add_u64 v[214:215], v[220:221], 0, s[24:25]
	s_mov_b32 m0, s43
	s_nop 0
	global_load_lds_dwordx4 v[214:215], off
	s_waitcnt vmcnt(10)
	s_barrier
	s_waitcnt lgkmcnt(0)
	s_waitcnt lgkmcnt(0)
	v_mfma_f32_16x16x32_bf16 v[62:65], v[150:153], v[166:169], v[62:65]
	v_mfma_f32_16x16x32_bf16 v[58:61], v[158:161], v[166:169], v[58:61]
	v_mfma_f32_16x16x32_bf16 v[54:57], v[150:153], v[174:177], v[54:57]
	v_mfma_f32_16x16x32_bf16 v[50:53], v[158:161], v[174:177], v[50:53]
	v_mfma_f32_16x16x32_bf16 v[38:41], v[150:153], v[182:185], v[38:41]
	v_mfma_f32_16x16x32_bf16 v[34:37], v[158:161], v[182:185], v[34:37]
	v_mfma_f32_16x16x32_bf16 v[22:25], v[150:153], v[190:193], v[22:25]
	v_mfma_f32_16x16x32_bf16 v[18:21], v[158:161], v[190:193], v[18:21]
	v_mfma_f32_16x16x32_bf16 v[62:65], v[154:157], v[170:173], v[62:65]
	v_mfma_f32_16x16x32_bf16 v[58:61], v[162:165], v[170:173], v[58:61]
	v_mfma_f32_16x16x32_bf16 v[54:57], v[154:157], v[178:181], v[54:57]
	v_mfma_f32_16x16x32_bf16 v[50:53], v[162:165], v[178:181], v[50:53]
	v_mfma_f32_16x16x32_bf16 v[38:41], v[154:157], v[186:189], v[38:41]
	v_mfma_f32_16x16x32_bf16 v[34:37], v[162:165], v[186:189], v[34:37]
	v_mfma_f32_16x16x32_bf16 v[22:25], v[154:157], v[194:197], v[22:25]
	v_mfma_f32_16x16x32_bf16 v[18:21], v[162:165], v[194:197], v[18:21]
	s_barrier
	s_add_u32 s0, s34, 0x40080
	s_addc_u32 s1, s35, 0
	s_add_i32 s34, s36, s8
	s_mov_b32 m0, s34
	s_nop 0
	global_load_lds_dwordx4 v134, s[0:1]
	s_add_i32 m0, s34, 0x2000
	s_nop 0
	global_load_lds_dwordx4 v130, s[0:1]
	s_waitcnt vmcnt(10)
	s_barrier
	v_mfma_f32_16x16x32_bf16 v[46:49], v[198:201], v[166:169], v[46:49]
	v_mfma_f32_16x16x32_bf16 v[42:45], v[206:209], v[166:169], v[42:45]
	v_mfma_f32_16x16x32_bf16 v[30:33], v[198:201], v[174:177], v[30:33]
	v_mfma_f32_16x16x32_bf16 v[26:29], v[206:209], v[174:177], v[26:29]
	v_mfma_f32_16x16x32_bf16 v[14:17], v[198:201], v[182:185], v[14:17]
	v_mfma_f32_16x16x32_bf16 v[10:13], v[206:209], v[182:185], v[10:13]
	v_mfma_f32_16x16x32_bf16 v[6:9], v[198:201], v[190:193], v[6:9]
	v_mfma_f32_16x16x32_bf16 v[2:5], v[206:209], v[190:193], v[2:5]
	v_mfma_f32_16x16x32_bf16 v[46:49], v[202:205], v[170:173], v[46:49]
	v_mfma_f32_16x16x32_bf16 v[42:45], v[210:213], v[170:173], v[42:45]
	v_mfma_f32_16x16x32_bf16 v[30:33], v[202:205], v[178:181], v[30:33]
	v_mfma_f32_16x16x32_bf16 v[26:29], v[210:213], v[178:181], v[26:29]
	v_mfma_f32_16x16x32_bf16 v[14:17], v[202:205], v[186:189], v[14:17]
	v_mfma_f32_16x16x32_bf16 v[10:13], v[210:213], v[186:189], v[10:13]
	v_mfma_f32_16x16x32_bf16 v[6:9], v[202:205], v[194:197], v[6:9]
	v_mfma_f32_16x16x32_bf16 v[2:5], v[210:213], v[194:197], v[2:5]
	s_add_i32 s61, s61, 2
	s_add_u32 s59, s59, 0x100
	s_addc_u32 s60, s60, 0
	s_add_u32 s30, s30, 0x100
	s_addc_u32 s31, s31, 0
	s_cmp_gt_u32 s61, 13
	s_barrier
	s_cbranch_scc1 .Lpeel_exit_13
.LBB0_2245:
	ds_read_b128 v[150:153], v146
	ds_read_b128 v[154:157], v146 offset:1024
	ds_read_b128 v[158:161], v146 offset:2048
	ds_read_b128 v[162:165], v146 offset:3072
	s_add_u32 s0, s30, 0xfffc0080
	s_addc_u32 s1, s31, -1
	s_cmp_eq_u32 s61, 12
	s_cselect_b32 s37, s55, s1
	s_cselect_b32 s36, s56, s0
	s_cselect_b32 s35, s57, s60
	s_cselect_b32 s34, s58, s59
	s_mov_b32 m0, s46
	ds_read_b128 v[166:169], v147
	ds_read_b128 v[170:173], v147 offset:1024
	ds_read_b128 v[174:177], v147 offset:2048
	ds_read_b128 v[178:181], v147 offset:3072
	ds_read_b128 v[182:185], v147 offset:4096
	ds_read_b128 v[186:189], v147 offset:5120
	ds_read_b128 v[190:193], v147 offset:6144
	ds_read_b128 v[194:197], v147 offset:7168
	global_load_lds_dwordx4 v140, s[30:31]
	s_mov_b32 m0, s47
	s_nop 0
	global_load_lds_dwordx4 v138, s[30:31]
	s_waitcnt lgkmcnt(8)
	s_waitcnt vmcnt(10)
	s_barrier
	s_waitcnt lgkmcnt(0)
	s_waitcnt lgkmcnt(0)
	v_mfma_f32_16x16x32_bf16 v[126:129], v[150:153], v[166:169], v[126:129]
	v_mfma_f32_16x16x32_bf16 v[122:125], v[158:161], v[166:169], v[122:125]
	v_mfma_f32_16x16x32_bf16 v[118:121], v[150:153], v[174:177], v[118:121]
	v_mfma_f32_16x16x32_bf16 v[114:117], v[158:161], v[174:177], v[114:117]
	v_mfma_f32_16x16x32_bf16 v[102:105], v[150:153], v[182:185], v[102:105]
	v_mfma_f32_16x16x32_bf16 v[98:101], v[158:161], v[182:185], v[98:101]
	v_mfma_f32_16x16x32_bf16 v[86:89], v[150:153], v[190:193], v[86:89]
	v_mfma_f32_16x16x32_bf16 v[82:85], v[158:161], v[190:193], v[82:85]
	v_mfma_f32_16x16x32_bf16 v[126:129], v[154:157], v[170:173], v[126:129]
	v_mfma_f32_16x16x32_bf16 v[122:125], v[162:165], v[170:173], v[122:125]
	v_mfma_f32_16x16x32_bf16 v[118:121], v[154:157], v[178:181], v[118:121]
	v_mfma_f32_16x16x32_bf16 v[114:117], v[162:165], v[178:181], v[114:117]
	v_mfma_f32_16x16x32_bf16 v[102:105], v[154:157], v[186:189], v[102:105]
	v_mfma_f32_16x16x32_bf16 v[98:101], v[162:165], v[186:189], v[98:101]
	v_mfma_f32_16x16x32_bf16 v[86:89], v[154:157], v[194:197], v[86:89]
	v_mfma_f32_16x16x32_bf16 v[82:85], v[162:165], v[194:197], v[82:85]
	s_barrier
	s_mov_b32 m0, s48
	v_lshl_add_u64 v[214:215], s[34:35], 0, v[134:135]
	ds_read_b128 v[198:201], v148
	ds_read_b128 v[202:205], v148 offset:1024
	ds_read_b128 v[206:209], v148 offset:2048
	ds_read_b128 v[210:213], v148 offset:3072
	global_load_lds_dwordx4 v[214:215], off
	v_lshl_add_u64 v[216:217], s[34:35], 0, v[130:131]
	s_mov_b32 m0, s49
	s_nop 0
	global_load_lds_dwordx4 v[216:217], off
	s_waitcnt vmcnt(10)
	s_barrier
	s_waitcnt lgkmcnt(0)
	s_waitcnt lgkmcnt(0)
	v_mfma_f32_16x16x32_bf16 v[110:113], v[198:201], v[166:169], v[110:113]
	v_mfma_f32_16x16x32_bf16 v[106:109], v[206:209], v[166:169], v[106:109]
	v_mfma_f32_16x16x32_bf16 v[94:97], v[198:201], v[174:177], v[94:97]
	v_mfma_f32_16x16x32_bf16 v[90:93], v[206:209], v[174:177], v[90:93]
	v_mfma_f32_16x16x32_bf16 v[78:81], v[198:201], v[182:185], v[78:81]
	v_mfma_f32_16x16x32_bf16 v[74:77], v[206:209], v[182:185], v[74:77]
	v_mfma_f32_16x16x32_bf16 v[70:73], v[198:201], v[190:193], v[70:73]
	v_mfma_f32_16x16x32_bf16 v[66:69], v[206:209], v[190:193], v[66:69]
	v_mfma_f32_16x16x32_bf16 v[110:113], v[202:205], v[170:173], v[110:113]
	v_mfma_f32_16x16x32_bf16 v[106:109], v[210:213], v[170:173], v[106:109]
	v_mfma_f32_16x16x32_bf16 v[94:97], v[202:205], v[178:181], v[94:97]
	v_mfma_f32_16x16x32_bf16 v[90:93], v[210:213], v[178:181], v[90:93]
	v_mfma_f32_16x16x32_bf16 v[78:81], v[202:205], v[186:189], v[78:81]
	v_mfma_f32_16x16x32_bf16 v[74:77], v[210:213], v[186:189], v[74:77]
	v_mfma_f32_16x16x32_bf16 v[70:73], v[202:205], v[194:197], v[70:73]
	v_mfma_f32_16x16x32_bf16 v[66:69], v[210:213], v[194:197], v[66:69]
	s_mov_b32 m0, s9
	v_lshl_add_u64 v[218:219], s[36:37], 0, v[136:137]
	s_barrier
	ds_read_b128 v[166:169], v147 offset:16384
	ds_read_b128 v[170:173], v147 offset:17408
	ds_read_b128 v[174:177], v147 offset:18432
	ds_read_b128 v[178:181], v147 offset:19456
	ds_read_b128 v[182:185], v147 offset:20480
	ds_read_b128 v[186:189], v147 offset:21504
	ds_read_b128 v[190:193], v147 offset:22528
	ds_read_b128 v[194:197], v147 offset:23552
	global_load_lds_dwordx4 v[218:219], off
	v_lshl_add_u64 v[220:221], s[36:37], 0, v[132:133]
	s_mov_b32 m0, s21
	s_nop 0
	global_load_lds_dwordx4 v[220:221], off
	s_waitcnt vmcnt(10)
	s_barrier
	s_waitcnt lgkmcnt(0)
	s_waitcnt lgkmcnt(0)
	v_mfma_f32_16x16x32_bf16 v[62:65], v[150:153], v[166:169], v[62:65]
	v_mfma_f32_16x16x32_bf16 v[58:61], v[158:161], v[166:169], v[58:61]
	v_mfma_f32_16x16x32_bf16 v[54:57], v[150:153], v[174:177], v[54:57]
	v_mfma_f32_16x16x32_bf16 v[50:53], v[158:161], v[174:177], v[50:53]
	v_mfma_f32_16x16x32_bf16 v[38:41], v[150:153], v[182:185], v[38:41]
	v_mfma_f32_16x16x32_bf16 v[34:37], v[158:161], v[182:185], v[34:37]
	v_mfma_f32_16x16x32_bf16 v[22:25], v[150:153], v[190:193], v[22:25]
	v_mfma_f32_16x16x32_bf16 v[18:21], v[158:161], v[190:193], v[18:21]
	v_mfma_f32_16x16x32_bf16 v[62:65], v[154:157], v[170:173], v[62:65]
	v_mfma_f32_16x16x32_bf16 v[58:61], v[162:165], v[170:173], v[58:61]
	v_mfma_f32_16x16x32_bf16 v[54:57], v[154:157], v[178:181], v[54:57]
	v_mfma_f32_16x16x32_bf16 v[50:53], v[162:165], v[178:181], v[50:53]
	v_mfma_f32_16x16x32_bf16 v[38:41], v[154:157], v[186:189], v[38:41]
	v_mfma_f32_16x16x32_bf16 v[34:37], v[162:165], v[186:189], v[34:37]
	v_mfma_f32_16x16x32_bf16 v[22:25], v[154:157], v[194:197], v[22:25]
	v_mfma_f32_16x16x32_bf16 v[18:21], v[162:165], v[194:197], v[18:21]
	s_barrier
	s_add_u32 s0, s34, 0x40000
	s_addc_u32 s1, s35, 0
	s_add_i32 s62, s44, s8
	s_mov_b32 m0, s62
	s_nop 0
	global_load_lds_dwordx4 v134, s[0:1]
	s_add_i32 m0, s62, 0x2000
	s_nop 0
	global_load_lds_dwordx4 v130, s[0:1]
	s_waitcnt vmcnt(10)
	s_barrier
	v_mfma_f32_16x16x32_bf16 v[46:49], v[198:201], v[166:169], v[46:49]
	v_mfma_f32_16x16x32_bf16 v[42:45], v[206:209], v[166:169], v[42:45]
	v_mfma_f32_16x16x32_bf16 v[30:33], v[198:201], v[174:177], v[30:33]
	v_mfma_f32_16x16x32_bf16 v[26:29], v[206:209], v[174:177], v[26:29]
	v_mfma_f32_16x16x32_bf16 v[14:17], v[198:201], v[182:185], v[14:17]
	v_mfma_f32_16x16x32_bf16 v[10:13], v[206:209], v[182:185], v[10:13]
	v_mfma_f32_16x16x32_bf16 v[6:9], v[198:201], v[190:193], v[6:9]
	v_mfma_f32_16x16x32_bf16 v[2:5], v[206:209], v[190:193], v[2:5]
	v_mfma_f32_16x16x32_bf16 v[46:49], v[202:205], v[170:173], v[46:49]
	v_mfma_f32_16x16x32_bf16 v[42:45], v[210:213], v[170:173], v[42:45]
	v_mfma_f32_16x16x32_bf16 v[30:33], v[202:205], v[178:181], v[30:33]
	v_mfma_f32_16x16x32_bf16 v[26:29], v[210:213], v[178:181], v[26:29]
	v_mfma_f32_16x16x32_bf16 v[14:17], v[202:205], v[186:189], v[14:17]
	v_mfma_f32_16x16x32_bf16 v[10:13], v[210:213], v[186:189], v[10:13]
	v_mfma_f32_16x16x32_bf16 v[6:9], v[202:205], v[194:197], v[6:9]
	v_mfma_f32_16x16x32_bf16 v[2:5], v[210:213], v[194:197], v[2:5]
	s_add_i32 s62, 0, 0x18000
	v_add_u32_e32 v149, s62, v145
	s_barrier
	ds_read_b128 v[150:153], v149
	ds_read_b128 v[154:157], v149 offset:1024
	ds_read_b128 v[158:161], v149 offset:2048
	ds_read_b128 v[162:165], v149 offset:3072
	s_add_u32 s0, s36, 0x40000
	s_addc_u32 s1, s37, 0
	s_mov_b32 m0, s38
	ds_read_b128 v[166:169], v147 offset:32768
	ds_read_b128 v[170:173], v147 offset:33792
	ds_read_b128 v[174:177], v147 offset:34816
	ds_read_b128 v[178:181], v147 offset:35840
	ds_read_b128 v[182:185], v147 offset:36864
	ds_read_b128 v[186:189], v147 offset:37888
	ds_read_b128 v[190:193], v147 offset:38912
	ds_read_b128 v[194:197], v147 offset:39936
	global_load_lds_dwordx4 v136, s[0:1]
	s_mov_b32 m0, s39
	s_nop 0
	global_load_lds_dwordx4 v132, s[0:1]
	s_waitcnt lgkmcnt(8)
	s_waitcnt vmcnt(10)
	s_barrier
	s_waitcnt lgkmcnt(0)
	s_waitcnt lgkmcnt(0)
	v_mfma_f32_16x16x32_bf16 v[126:129], v[150:153], v[166:169], v[126:129]
	v_mfma_f32_16x16x32_bf16 v[122:125], v[158:161], v[166:169], v[122:125]
	v_mfma_f32_16x16x32_bf16 v[118:121], v[150:153], v[174:177], v[118:121]
	v_mfma_f32_16x16x32_bf16 v[114:117], v[158:161], v[174:177], v[114:117]
	v_mfma_f32_16x16x32_bf16 v[102:105], v[150:153], v[182:185], v[102:105]
	v_mfma_f32_16x16x32_bf16 v[98:101], v[158:161], v[182:185], v[98:101]
	v_mfma_f32_16x16x32_bf16 v[86:89], v[150:153], v[190:193], v[86:89]
	v_mfma_f32_16x16x32_bf16 v[82:85], v[158:161], v[190:193], v[82:85]
	v_mfma_f32_16x16x32_bf16 v[126:129], v[154:157], v[170:173], v[126:129]
	v_mfma_f32_16x16x32_bf16 v[122:125], v[162:165], v[170:173], v[122:125]
	v_mfma_f32_16x16x32_bf16 v[118:121], v[154:157], v[178:181], v[118:121]
	v_mfma_f32_16x16x32_bf16 v[114:117], v[162:165], v[178:181], v[114:117]
	v_mfma_f32_16x16x32_bf16 v[102:105], v[154:157], v[186:189], v[102:105]
	v_mfma_f32_16x16x32_bf16 v[98:101], v[162:165], v[186:189], v[98:101]
	v_mfma_f32_16x16x32_bf16 v[86:89], v[154:157], v[194:197], v[86:89]
	v_mfma_f32_16x16x32_bf16 v[82:85], v[162:165], v[194:197], v[82:85]
	s_barrier
	s_add_i32 s36, 0, 0x1c000
	s_add_i32 s0, s62, s8
	v_add_u32_e32 v149, s36, v145
	v_lshl_add_u64 v[214:215], v[214:215], 0, s[24:25]
	s_mov_b32 m0, s0
	ds_read_b128 v[198:201], v149
	ds_read_b128 v[202:205], v149 offset:1024
	ds_read_b128 v[206:209], v149 offset:2048
	ds_read_b128 v[210:213], v149 offset:3072
	global_load_lds_dwordx4 v[214:215], off
	v_lshl_add_u64 v[214:215], v[216:217], 0, s[24:25]
	s_add_i32 m0, s0, 0x2000
	s_nop 0
	global_load_lds_dwordx4 v[214:215], off
	s_waitcnt vmcnt(10)
	s_barrier
	s_waitcnt lgkmcnt(0)
	s_waitcnt lgkmcnt(0)
	v_mfma_f32_16x16x32_bf16 v[110:113], v[198:201], v[166:169], v[110:113]
	v_mfma_f32_16x16x32_bf16 v[106:109], v[206:209], v[166:169], v[106:109]
	v_mfma_f32_16x16x32_bf16 v[94:97], v[198:201], v[174:177], v[94:97]
	v_mfma_f32_16x16x32_bf16 v[90:93], v[206:209], v[174:177], v[90:93]
	v_mfma_f32_16x16x32_bf16 v[78:81], v[198:201], v[182:185], v[78:81]
	v_mfma_f32_16x16x32_bf16 v[74:77], v[206:209], v[182:185], v[74:77]
	v_mfma_f32_16x16x32_bf16 v[70:73], v[198:201], v[190:193], v[70:73]
	v_mfma_f32_16x16x32_bf16 v[66:69], v[206:209], v[190:193], v[66:69]
	v_mfma_f32_16x16x32_bf16 v[110:113], v[202:205], v[170:173], v[110:113]
	v_mfma_f32_16x16x32_bf16 v[106:109], v[210:213], v[170:173], v[106:109]
	v_mfma_f32_16x16x32_bf16 v[94:97], v[202:205], v[178:181], v[94:97]
	v_mfma_f32_16x16x32_bf16 v[90:93], v[210:213], v[178:181], v[90:93]
	v_mfma_f32_16x16x32_bf16 v[78:81], v[202:205], v[186:189], v[78:81]
	v_mfma_f32_16x16x32_bf16 v[74:77], v[210:213], v[186:189], v[74:77]
	v_mfma_f32_16x16x32_bf16 v[70:73], v[202:205], v[194:197], v[70:73]
	v_mfma_f32_16x16x32_bf16 v[66:69], v[210:213], v[194:197], v[66:69]
	s_mov_b32 m0, s42
	v_lshl_add_u64 v[214:215], v[218:219], 0, s[24:25]
	s_barrier
	ds_read_b128 v[166:169], v147 offset:49152
	ds_read_b128 v[170:173], v147 offset:50176
	ds_read_b128 v[174:177], v147 offset:51200
	ds_read_b128 v[178:181], v147 offset:52224
	ds_read_b128 v[182:185], v147 offset:53248
	ds_read_b128 v[186:189], v147 offset:54272
	ds_read_b128 v[190:193], v147 offset:55296
	ds_read_b128 v[194:197], v147 offset:56320
	global_load_lds_dwordx4 v[214:215], off
	v_lshl_add_u64 v[214:215], v[220:221], 0, s[24:25]
	s_mov_b32 m0, s43
	s_nop 0
	global_load_lds_dwordx4 v[214:215], off
	s_waitcnt vmcnt(10)
	s_barrier
	s_waitcnt lgkmcnt(0)
	s_waitcnt lgkmcnt(0)
	v_mfma_f32_16x16x32_bf16 v[62:65], v[150:153], v[166:169], v[62:65]
	v_mfma_f32_16x16x32_bf16 v[58:61], v[158:161], v[166:169], v[58:61]
	v_mfma_f32_16x16x32_bf16 v[54:57], v[150:153], v[174:177], v[54:57]
	v_mfma_f32_16x16x32_bf16 v[50:53], v[158:161], v[174:177], v[50:53]
	v_mfma_f32_16x16x32_bf16 v[38:41], v[150:153], v[182:185], v[38:41]
	v_mfma_f32_16x16x32_bf16 v[34:37], v[158:161], v[182:185], v[34:37]
	v_mfma_f32_16x16x32_bf16 v[22:25], v[150:153], v[190:193], v[22:25]
	v_mfma_f32_16x16x32_bf16 v[18:21], v[158:161], v[190:193], v[18:21]
	v_mfma_f32_16x16x32_bf16 v[62:65], v[154:157], v[170:173], v[62:65]
	v_mfma_f32_16x16x32_bf16 v[58:61], v[162:165], v[170:173], v[58:61]
	v_mfma_f32_16x16x32_bf16 v[54:57], v[154:157], v[178:181], v[54:57]
	v_mfma_f32_16x16x32_bf16 v[50:53], v[162:165], v[178:181], v[50:53]
	v_mfma_f32_16x16x32_bf16 v[38:41], v[154:157], v[186:189], v[38:41]
	v_mfma_f32_16x16x32_bf16 v[34:37], v[162:165], v[186:189], v[34:37]
	v_mfma_f32_16x16x32_bf16 v[22:25], v[154:157], v[194:197], v[22:25]
	v_mfma_f32_16x16x32_bf16 v[18:21], v[162:165], v[194:197], v[18:21]
	s_barrier
	s_add_u32 s0, s34, 0x40080
	s_addc_u32 s1, s35, 0
	s_add_i32 s34, s36, s8
	s_mov_b32 m0, s34
	s_nop 0
	global_load_lds_dwordx4 v134, s[0:1]
	s_add_i32 m0, s34, 0x2000
	s_nop 0
	global_load_lds_dwordx4 v130, s[0:1]
	s_waitcnt vmcnt(10)
	s_barrier
	v_mfma_f32_16x16x32_bf16 v[46:49], v[198:201], v[166:169], v[46:49]
	v_mfma_f32_16x16x32_bf16 v[42:45], v[206:209], v[166:169], v[42:45]
	v_mfma_f32_16x16x32_bf16 v[30:33], v[198:201], v[174:177], v[30:33]
	v_mfma_f32_16x16x32_bf16 v[26:29], v[206:209], v[174:177], v[26:29]
	v_mfma_f32_16x16x32_bf16 v[14:17], v[198:201], v[182:185], v[14:17]
	v_mfma_f32_16x16x32_bf16 v[10:13], v[206:209], v[182:185], v[10:13]
	v_mfma_f32_16x16x32_bf16 v[6:9], v[198:201], v[190:193], v[6:9]
	v_mfma_f32_16x16x32_bf16 v[2:5], v[206:209], v[190:193], v[2:5]
	v_mfma_f32_16x16x32_bf16 v[46:49], v[202:205], v[170:173], v[46:49]
	v_mfma_f32_16x16x32_bf16 v[42:45], v[210:213], v[170:173], v[42:45]
	v_mfma_f32_16x16x32_bf16 v[30:33], v[202:205], v[178:181], v[30:33]
	v_mfma_f32_16x16x32_bf16 v[26:29], v[210:213], v[178:181], v[26:29]
	v_mfma_f32_16x16x32_bf16 v[14:17], v[202:205], v[186:189], v[14:17]
	v_mfma_f32_16x16x32_bf16 v[10:13], v[210:213], v[186:189], v[10:13]
	v_mfma_f32_16x16x32_bf16 v[6:9], v[202:205], v[194:197], v[6:9]
	v_mfma_f32_16x16x32_bf16 v[2:5], v[210:213], v[194:197], v[2:5]
	s_add_i32 s61, s61, 2
	s_add_u32 s59, s59, 0x100
	s_addc_u32 s60, s60, 0
	s_add_u32 s30, s30, 0x100
	s_addc_u32 s31, s31, 0
	s_cmp_gt_u32 s61, 13
	s_barrier
	s_cbranch_scc0 .LBB0_2245

.LBB0_2493:
	v_bfe_u32 v166, v12, 4, 2
	s_lshl_b32 s0, s0, 5
	v_and_b32_e32 v151, 15, v12
	v_lshlrev_b32_e32 v13, 4, v166
	v_lshlrev_b32_e32 v12, 2, v12
	s_and_b32 s46, s0, 0x60
	s_lshl_b32 s45, s1, 6
	v_lshl_or_b32 v13, v151, 6, v13
	s_lshl_b32 s1, s1, 13
	v_and_b32_e32 v12, 32, v12
	s_lshl_b32 s0, s46, 7
	v_bitop3_b32 v167, v13, s0, v12 bitop3:0xde
	s_add_u32 s0, s18, 0x1da0080
	v_bitop3_b32 v14, v13, s1, v12 bitop3:0xde
	s_addc_u32 s1, s19, 0
	s_add_i32 m0, s9, 0x18000
	s_waitcnt vmcnt(4)
	s_barrier
	global_load_lds_dwordx4 v156, s[0:1]
	v_lshl_add_u64 v[12:13], s[0:1], 0, v[152:153]
	s_add_i32 m0, s9, 0x1a000
	s_mov_b64 s[26:27], 0x80
	s_add_i32 s49, s9, 0x8000
	s_add_i32 s50, s9, 0xa000
	global_load_lds_dwordx4 v[12:13], off
	v_lshl_add_u64 v[4:5], v[4:5], 0, s[26:27]
	s_mov_b32 m0, s49
	s_add_u32 s0, s18, 0x1de0080
	global_load_lds_dwordx4 v[4:5], off
	v_lshl_add_u64 v[2:3], v[2:3], 0, s[26:27]
	s_mov_b32 m0, s50
	s_addc_u32 s1, s19, 0
	global_load_lds_dwordx4 v[2:3], off
	s_add_i32 m0, s9, 0x1c000
	s_nop 0
	global_load_lds_dwordx4 v156, s[0:1]
	s_add_i32 m0, s9, 0x1e000
	s_add_i32 s53, 0, 0x10000
	global_load_lds_dwordx4 v152, s[0:1]
	v_lshlrev_b32_e32 v2, 14, v6
	v_and_b32_e32 v2, 0xffff8000, v2
	v_lshl_add_u32 v2, v7, 11, v2
	v_and_b32_e32 v3, 1, v6
	v_lshl_or_b32 v2, v3, 6, v2
	v_lshl_add_u32 v160, v8, 1, v2
	v_lshlrev_b32_e32 v2, 14, v10
	v_and_b32_e32 v2, 0xffff8000, v2
	s_waitcnt vmcnt(6)
	v_lshl_add_u32 v2, v9, 11, v2
	v_and_b32_e32 v3, 1, v10
	v_lshl_or_b32 v2, v3, 6, v2
	v_add_u32_e32 v168, s53, v167
	s_add_i32 s55, 0, 0x14000
	s_add_i32 s53, s53, s8
	s_mov_b32 s47, 0x18000
	s_mov_b32 s48, 0x8000
	v_mov_b32_e32 v161, v157
	v_lshl_add_u32 v162, v11, 1, v2
	v_mov_b32_e32 v163, v157
	v_add_u32_e32 v169, 0, v14
	v_add_u32_e32 v170, s55, v167
	s_mov_b32 s28, 0x3fd744fd
	s_add_i32 s51, s9, 0xc000
	s_add_i32 s52, s9, 0xe000
	s_add_i32 s54, s53, 0x2000
	s_add_i32 s55, s55, s8
	s_mov_b32 s60, s2
	s_mov_b64 s[34:35], s[22:23]
	s_mov_b32 s56, 0
	s_barrier
.LBB0_2494:
	s_add_i32 s56, s56, 1
	s_mov_b64 s[0:1], s[24:25]
	s_lshr_b32 s24, s56, 2
	s_mul_i32 s24, s24, s74
	s_mov_b64 s[36:37], s[34:35]
	s_mov_b32 s35, s57
	s_add_i32 s57, s24, s2
	s_cmpk_lt_i32 s57, 0x100
	s_cselect_b64 s[38:39], -1, 0
	s_cmpk_gt_i32 s57, 0xff
	s_mov_b32 s34, s58
	s_cselect_b64 s[30:31], -1, 0
	s_and_b32 s58, s56, 3
	s_and_b64 s[24:25], s[38:39], exec
	s_cselect_b32 s24, s57, s35
	s_cselect_b32 s34, s58, s34
	s_ashr_i32 s25, s24, 31
	s_lshl_b64 s[24:25], s[24:25], 19
	s_add_u32 s24, s6, s24
	s_addc_u32 s25, s7, s25
	s_and_b64 s[40:41], s[38:39], exec
	s_cselect_b32 s61, s25, s1
	s_cselect_b32 s62, s24, s0
	s_ashr_i32 s35, s34, 31
	s_lshl_b64 s[34:35], s[34:35], 19
	s_add_u32 s34, s22, s34
	s_addc_u32 s35, s23, s35
	s_and_b64 s[38:39], s[38:39], exec
	s_cselect_b32 s63, s35, s37
	s_cselect_b32 s64, s34, s36
	s_add_u32 s65, s36, 0x100
	s_addc_u32 s67, s37, 0
	s_add_u32 s36, s0, 0x40080
	s_addc_u32 s37, s1, 0
	s_mov_b32 s69, -2
	ds_read_b128 v[130:133], v168
	ds_read_b128 v[134:137], v168 offset:1024
	ds_read_b128 v[138:141], v168 offset:2048
	ds_read_b128 v[142:145], v168 offset:3072
	s_add_u32 s0, s36, 0xfffc0080
	s_addc_u32 s1, s37, -1
	s_cmp_eq_u32 s69, 12
	s_cselect_b32 s41, s61, s1
	s_cselect_b32 s40, s62, s0
	s_cselect_b32 s39, s63, s67
	s_cselect_b32 s38, s64, s65
	s_mov_b32 m0, s51
	ds_read_b128 v[146:149], v169
	ds_read_b128 v[172:175], v169 offset:1024
	ds_read_b128 v[176:179], v169 offset:2048
	ds_read_b128 v[180:183], v169 offset:3072
	ds_read_b128 v[184:187], v169 offset:4096
	ds_read_b128 v[188:191], v169 offset:5120
	ds_read_b128 v[192:195], v169 offset:6144
	ds_read_b128 v[196:199], v169 offset:7168
	global_load_lds_dwordx4 v162, s[36:37]
	s_mov_b32 m0, s52
	s_nop 0
	global_load_lds_dwordx4 v160, s[36:37]
	s_waitcnt lgkmcnt(8)
	s_waitcnt vmcnt(10)
	s_barrier
	s_waitcnt lgkmcnt(0)
	s_waitcnt lgkmcnt(0)
	v_mfma_f32_16x16x32_bf16 v[126:129], v[130:133], v[146:149], 0
	v_mfma_f32_16x16x32_bf16 v[122:125], v[138:141], v[146:149], 0
	v_mfma_f32_16x16x32_bf16 v[118:121], v[130:133], v[176:179], 0
	v_mfma_f32_16x16x32_bf16 v[110:113], v[138:141], v[176:179], 0
	v_mfma_f32_16x16x32_bf16 v[98:101], v[130:133], v[184:187], 0
	v_mfma_f32_16x16x32_bf16 v[90:93], v[138:141], v[184:187], 0
	v_mfma_f32_16x16x32_bf16 v[82:85], v[130:133], v[192:195], 0
	v_mfma_f32_16x16x32_bf16 v[74:77], v[138:141], v[192:195], 0
	v_mfma_f32_16x16x32_bf16 v[126:129], v[134:137], v[172:175], v[126:129]
	v_mfma_f32_16x16x32_bf16 v[122:125], v[142:145], v[172:175], v[122:125]
	v_mfma_f32_16x16x32_bf16 v[118:121], v[134:137], v[180:183], v[118:121]
	v_mfma_f32_16x16x32_bf16 v[110:113], v[142:145], v[180:183], v[110:113]
	v_mfma_f32_16x16x32_bf16 v[98:101], v[134:137], v[188:191], v[98:101]
	v_mfma_f32_16x16x32_bf16 v[90:93], v[142:145], v[188:191], v[90:93]
	v_mfma_f32_16x16x32_bf16 v[82:85], v[134:137], v[196:199], v[82:85]
	v_mfma_f32_16x16x32_bf16 v[74:77], v[142:145], v[196:199], v[74:77]
	s_barrier
	s_mov_b32 m0, s53
	v_lshl_add_u64 v[164:165], s[38:39], 0, v[156:157]
	ds_read_b128 v[200:203], v170
	ds_read_b128 v[204:207], v170 offset:1024
	ds_read_b128 v[208:211], v170 offset:2048
	ds_read_b128 v[212:215], v170 offset:3072
	global_load_lds_dwordx4 v[164:165], off
	v_lshl_add_u64 v[216:217], s[38:39], 0, v[152:153]
	s_mov_b32 m0, s54
	s_nop 0
	global_load_lds_dwordx4 v[216:217], off
	s_waitcnt vmcnt(10)
	s_barrier
	s_waitcnt lgkmcnt(0)
	s_waitcnt lgkmcnt(0)
	v_mfma_f32_16x16x32_bf16 v[114:117], v[200:203], v[146:149], 0
	v_mfma_f32_16x16x32_bf16 v[106:109], v[208:211], v[146:149], 0
	v_mfma_f32_16x16x32_bf16 v[102:105], v[200:203], v[176:179], 0
	v_mfma_f32_16x16x32_bf16 v[94:97], v[208:211], v[176:179], 0
	v_mfma_f32_16x16x32_bf16 v[86:89], v[200:203], v[184:187], 0
	v_mfma_f32_16x16x32_bf16 v[78:81], v[208:211], v[184:187], 0
	v_mfma_f32_16x16x32_bf16 v[70:73], v[200:203], v[192:195], 0
	v_mfma_f32_16x16x32_bf16 v[66:69], v[208:211], v[192:195], 0
	v_mfma_f32_16x16x32_bf16 v[114:117], v[204:207], v[172:175], v[114:117]
	v_mfma_f32_16x16x32_bf16 v[106:109], v[212:215], v[172:175], v[106:109]
	v_mfma_f32_16x16x32_bf16 v[102:105], v[204:207], v[180:183], v[102:105]
	v_mfma_f32_16x16x32_bf16 v[94:97], v[212:215], v[180:183], v[94:97]
	v_mfma_f32_16x16x32_bf16 v[86:89], v[204:207], v[188:191], v[86:89]
	v_mfma_f32_16x16x32_bf16 v[78:81], v[212:215], v[188:191], v[78:81]
	v_mfma_f32_16x16x32_bf16 v[70:73], v[204:207], v[196:199], v[70:73]
	v_mfma_f32_16x16x32_bf16 v[66:69], v[212:215], v[196:199], v[66:69]
	s_mov_b32 m0, s9
	v_lshl_add_u64 v[218:219], s[40:41], 0, v[158:159]
	s_barrier
	ds_read_b128 v[146:149], v169 offset:16384
	ds_read_b128 v[172:175], v169 offset:17408
	ds_read_b128 v[176:179], v169 offset:18432
	ds_read_b128 v[180:183], v169 offset:19456
	ds_read_b128 v[184:187], v169 offset:20480
	ds_read_b128 v[188:191], v169 offset:21504
	ds_read_b128 v[192:195], v169 offset:22528
	ds_read_b128 v[196:199], v169 offset:23552
	global_load_lds_dwordx4 v[218:219], off
	v_lshl_add_u64 v[220:221], s[40:41], 0, v[154:155]
	s_mov_b32 m0, s29
	s_nop 0
	global_load_lds_dwordx4 v[220:221], off
	s_waitcnt vmcnt(10)
	s_barrier
	s_waitcnt lgkmcnt(0)
	s_waitcnt lgkmcnt(0)
	v_mfma_f32_16x16x32_bf16 v[62:65], v[130:133], v[146:149], 0
	v_mfma_f32_16x16x32_bf16 v[58:61], v[138:141], v[146:149], 0
	v_mfma_f32_16x16x32_bf16 v[50:53], v[130:133], v[176:179], 0
	v_mfma_f32_16x16x32_bf16 v[42:45], v[138:141], v[176:179], 0
	v_mfma_f32_16x16x32_bf16 v[34:37], v[130:133], v[184:187], 0
	v_mfma_f32_16x16x32_bf16 v[26:29], v[138:141], v[184:187], 0
	v_mfma_f32_16x16x32_bf16 v[18:21], v[130:133], v[192:195], 0
	v_mfma_f32_16x16x32_bf16 v[10:13], v[138:141], v[192:195], 0
	v_mfma_f32_16x16x32_bf16 v[62:65], v[134:137], v[172:175], v[62:65]
	v_mfma_f32_16x16x32_bf16 v[58:61], v[142:145], v[172:175], v[58:61]
	v_mfma_f32_16x16x32_bf16 v[50:53], v[134:137], v[180:183], v[50:53]
	v_mfma_f32_16x16x32_bf16 v[42:45], v[142:145], v[180:183], v[42:45]
	v_mfma_f32_16x16x32_bf16 v[34:37], v[134:137], v[188:191], v[34:37]
	v_mfma_f32_16x16x32_bf16 v[26:29], v[142:145], v[188:191], v[26:29]
	v_mfma_f32_16x16x32_bf16 v[18:21], v[134:137], v[196:199], v[18:21]
	v_mfma_f32_16x16x32_bf16 v[10:13], v[142:145], v[196:199], v[10:13]
	s_barrier
	s_add_u32 s0, s38, 0x40000
	s_addc_u32 s1, s39, 0
	s_mov_b32 m0, s55
	s_nop 0
	global_load_lds_dwordx4 v156, s[0:1]
	s_add_i32 m0, s55, 0x2000
	s_nop 0
	global_load_lds_dwordx4 v152, s[0:1]
	s_waitcnt vmcnt(10)
	s_barrier
	v_mfma_f32_16x16x32_bf16 v[54:57], v[200:203], v[146:149], 0
	v_mfma_f32_16x16x32_bf16 v[46:49], v[208:211], v[146:149], 0
	v_mfma_f32_16x16x32_bf16 v[38:41], v[200:203], v[176:179], 0
	v_mfma_f32_16x16x32_bf16 v[30:33], v[208:211], v[176:179], 0
	v_mfma_f32_16x16x32_bf16 v[22:25], v[200:203], v[184:187], 0
	v_mfma_f32_16x16x32_bf16 v[14:17], v[208:211], v[184:187], 0
	v_mfma_f32_16x16x32_bf16 v[6:9], v[200:203], v[192:195], 0
	v_mfma_f32_16x16x32_bf16 v[2:5], v[208:211], v[192:195], 0
	v_mfma_f32_16x16x32_bf16 v[54:57], v[204:207], v[172:175], v[54:57]
	v_mfma_f32_16x16x32_bf16 v[46:49], v[212:215], v[172:175], v[46:49]
	v_mfma_f32_16x16x32_bf16 v[38:41], v[204:207], v[180:183], v[38:41]
	v_mfma_f32_16x16x32_bf16 v[30:33], v[212:215], v[180:183], v[30:33]
	v_mfma_f32_16x16x32_bf16 v[22:25], v[204:207], v[188:191], v[22:25]
	v_mfma_f32_16x16x32_bf16 v[14:17], v[212:215], v[188:191], v[14:17]
	v_mfma_f32_16x16x32_bf16 v[6:9], v[204:207], v[196:199], v[6:9]
	v_mfma_f32_16x16x32_bf16 v[2:5], v[212:215], v[196:199], v[2:5]
	s_add_i32 s70, 0, 0x18000
	v_add_u32_e32 v142, s70, v167
	s_barrier
	ds_read_b128 v[130:133], v142
	ds_read_b128 v[134:137], v142 offset:1024
	ds_read_b128 v[138:141], v142 offset:2048
	ds_read_b128 v[142:145], v142 offset:3072
	s_add_u32 s0, s40, 0x40000
	s_addc_u32 s1, s41, 0
	s_mov_b32 m0, s42
	ds_read_b128 v[146:149], v169 offset:32768
	ds_read_b128 v[172:175], v169 offset:33792
	ds_read_b128 v[176:179], v169 offset:34816
	ds_read_b128 v[180:183], v169 offset:35840
	ds_read_b128 v[184:187], v169 offset:36864
	ds_read_b128 v[188:191], v169 offset:37888
	ds_read_b128 v[192:195], v169 offset:38912
	ds_read_b128 v[196:199], v169 offset:39936
	global_load_lds_dwordx4 v158, s[0:1]
	s_mov_b32 m0, s43
	s_nop 0
	global_load_lds_dwordx4 v154, s[0:1]
	s_waitcnt lgkmcnt(8)
	s_waitcnt vmcnt(10)
	s_barrier
	s_waitcnt lgkmcnt(0)
	s_waitcnt lgkmcnt(0)
	v_mfma_f32_16x16x32_bf16 v[126:129], v[130:133], v[146:149], v[126:129]
	v_mfma_f32_16x16x32_bf16 v[122:125], v[138:141], v[146:149], v[122:125]
	v_mfma_f32_16x16x32_bf16 v[118:121], v[130:133], v[176:179], v[118:121]
	v_mfma_f32_16x16x32_bf16 v[110:113], v[138:141], v[176:179], v[110:113]
	v_mfma_f32_16x16x32_bf16 v[98:101], v[130:133], v[184:187], v[98:101]
	v_mfma_f32_16x16x32_bf16 v[90:93], v[138:141], v[184:187], v[90:93]
	v_mfma_f32_16x16x32_bf16 v[82:85], v[130:133], v[192:195], v[82:85]
	v_mfma_f32_16x16x32_bf16 v[74:77], v[138:141], v[192:195], v[74:77]
	v_mfma_f32_16x16x32_bf16 v[126:129], v[134:137], v[172:175], v[126:129]
	v_mfma_f32_16x16x32_bf16 v[122:125], v[142:145], v[172:175], v[122:125]
	v_mfma_f32_16x16x32_bf16 v[118:121], v[134:137], v[180:183], v[118:121]
	v_mfma_f32_16x16x32_bf16 v[110:113], v[142:145], v[180:183], v[110:113]
	v_mfma_f32_16x16x32_bf16 v[98:101], v[134:137], v[188:191], v[98:101]
	v_mfma_f32_16x16x32_bf16 v[90:93], v[142:145], v[188:191], v[90:93]
	v_mfma_f32_16x16x32_bf16 v[82:85], v[134:137], v[196:199], v[82:85]
	v_mfma_f32_16x16x32_bf16 v[74:77], v[142:145], v[196:199], v[74:77]
	s_barrier
	s_add_i32 s40, 0, 0x1c000
	s_add_i32 s0, s70, s8
	v_add_u32_e32 v171, s40, v167
	v_lshl_add_u64 v[164:165], v[164:165], 0, s[26:27]
	s_mov_b32 m0, s0
	ds_read_b128 v[200:203], v171
	ds_read_b128 v[204:207], v171 offset:1024
	ds_read_b128 v[208:211], v171 offset:2048
	ds_read_b128 v[212:215], v171 offset:3072
	global_load_lds_dwordx4 v[164:165], off
	v_lshl_add_u64 v[164:165], v[216:217], 0, s[26:27]
	s_add_i32 m0, s0, 0x2000
	s_nop 0
	global_load_lds_dwordx4 v[164:165], off
	s_waitcnt vmcnt(10)
	s_barrier
	s_waitcnt lgkmcnt(0)
	s_waitcnt lgkmcnt(0)
	v_mfma_f32_16x16x32_bf16 v[114:117], v[200:203], v[146:149], v[114:117]
	v_mfma_f32_16x16x32_bf16 v[106:109], v[208:211], v[146:149], v[106:109]
	v_mfma_f32_16x16x32_bf16 v[102:105], v[200:203], v[176:179], v[102:105]
	v_mfma_f32_16x16x32_bf16 v[94:97], v[208:211], v[176:179], v[94:97]
	v_mfma_f32_16x16x32_bf16 v[86:89], v[200:203], v[184:187], v[86:89]
	v_mfma_f32_16x16x32_bf16 v[78:81], v[208:211], v[184:187], v[78:81]
	v_mfma_f32_16x16x32_bf16 v[70:73], v[200:203], v[192:195], v[70:73]
	v_mfma_f32_16x16x32_bf16 v[66:69], v[208:211], v[192:195], v[66:69]
	v_mfma_f32_16x16x32_bf16 v[114:117], v[204:207], v[172:175], v[114:117]
	v_mfma_f32_16x16x32_bf16 v[106:109], v[212:215], v[172:175], v[106:109]
	v_mfma_f32_16x16x32_bf16 v[102:105], v[204:207], v[180:183], v[102:105]
	v_mfma_f32_16x16x32_bf16 v[94:97], v[212:215], v[180:183], v[94:97]
	v_mfma_f32_16x16x32_bf16 v[86:89], v[204:207], v[188:191], v[86:89]
	v_mfma_f32_16x16x32_bf16 v[78:81], v[212:215], v[188:191], v[78:81]
	v_mfma_f32_16x16x32_bf16 v[70:73], v[204:207], v[196:199], v[70:73]
	v_mfma_f32_16x16x32_bf16 v[66:69], v[212:215], v[196:199], v[66:69]
	s_mov_b32 m0, s49
	v_lshl_add_u64 v[164:165], v[218:219], 0, s[26:27]
	s_barrier
	ds_read_b128 v[146:149], v169 offset:49152
	ds_read_b128 v[172:175], v169 offset:50176
	ds_read_b128 v[176:179], v169 offset:51200
	ds_read_b128 v[180:183], v169 offset:52224
	ds_read_b128 v[184:187], v169 offset:53248
	ds_read_b128 v[188:191], v169 offset:54272
	ds_read_b128 v[192:195], v169 offset:55296
	ds_read_b128 v[196:199], v169 offset:56320
	global_load_lds_dwordx4 v[164:165], off
	v_lshl_add_u64 v[164:165], v[220:221], 0, s[26:27]
	s_mov_b32 m0, s50
	s_nop 0
	global_load_lds_dwordx4 v[164:165], off
	s_waitcnt vmcnt(10)
	s_barrier
	s_waitcnt lgkmcnt(0)
	s_waitcnt lgkmcnt(0)
	v_mfma_f32_16x16x32_bf16 v[62:65], v[130:133], v[146:149], v[62:65]
	v_mfma_f32_16x16x32_bf16 v[58:61], v[138:141], v[146:149], v[58:61]
	v_mfma_f32_16x16x32_bf16 v[50:53], v[130:133], v[176:179], v[50:53]
	v_mfma_f32_16x16x32_bf16 v[42:45], v[138:141], v[176:179], v[42:45]
	v_mfma_f32_16x16x32_bf16 v[34:37], v[130:133], v[184:187], v[34:37]
	v_mfma_f32_16x16x32_bf16 v[26:29], v[138:141], v[184:187], v[26:29]
	v_mfma_f32_16x16x32_bf16 v[18:21], v[130:133], v[192:195], v[18:21]
	v_mfma_f32_16x16x32_bf16 v[10:13], v[138:141], v[192:195], v[10:13]
	v_mfma_f32_16x16x32_bf16 v[62:65], v[134:137], v[172:175], v[62:65]
	v_mfma_f32_16x16x32_bf16 v[58:61], v[142:145], v[172:175], v[58:61]
	v_mfma_f32_16x16x32_bf16 v[50:53], v[134:137], v[180:183], v[50:53]
	v_mfma_f32_16x16x32_bf16 v[42:45], v[142:145], v[180:183], v[42:45]
	v_mfma_f32_16x16x32_bf16 v[34:37], v[134:137], v[188:191], v[34:37]
	v_mfma_f32_16x16x32_bf16 v[26:29], v[142:145], v[188:191], v[26:29]
	v_mfma_f32_16x16x32_bf16 v[18:21], v[134:137], v[196:199], v[18:21]
	v_mfma_f32_16x16x32_bf16 v[10:13], v[142:145], v[196:199], v[10:13]
	s_barrier
	s_add_u32 s0, s38, 0x40080
	s_addc_u32 s1, s39, 0
	s_add_i32 s38, s40, s8
	s_mov_b32 m0, s38
	s_nop 0
	global_load_lds_dwordx4 v156, s[0:1]
	s_add_i32 m0, s38, 0x2000
	s_nop 0
	global_load_lds_dwordx4 v152, s[0:1]
	s_waitcnt vmcnt(10)
	s_barrier
	v_mfma_f32_16x16x32_bf16 v[54:57], v[200:203], v[146:149], v[54:57]
	v_mfma_f32_16x16x32_bf16 v[46:49], v[208:211], v[146:149], v[46:49]
	v_mfma_f32_16x16x32_bf16 v[38:41], v[200:203], v[176:179], v[38:41]
	v_mfma_f32_16x16x32_bf16 v[30:33], v[208:211], v[176:179], v[30:33]
	v_mfma_f32_16x16x32_bf16 v[22:25], v[200:203], v[184:187], v[22:25]
	v_mfma_f32_16x16x32_bf16 v[14:17], v[208:211], v[184:187], v[14:17]
	v_mfma_f32_16x16x32_bf16 v[6:9], v[200:203], v[192:195], v[6:9]
	v_mfma_f32_16x16x32_bf16 v[2:5], v[208:211], v[192:195], v[2:5]
	v_mfma_f32_16x16x32_bf16 v[54:57], v[204:207], v[172:175], v[54:57]
	v_mfma_f32_16x16x32_bf16 v[46:49], v[212:215], v[172:175], v[46:49]
	v_mfma_f32_16x16x32_bf16 v[38:41], v[204:207], v[180:183], v[38:41]
	v_mfma_f32_16x16x32_bf16 v[30:33], v[212:215], v[180:183], v[30:33]
	v_mfma_f32_16x16x32_bf16 v[22:25], v[204:207], v[188:191], v[22:25]
	v_mfma_f32_16x16x32_bf16 v[14:17], v[212:215], v[188:191], v[14:17]
	v_mfma_f32_16x16x32_bf16 v[6:9], v[204:207], v[196:199], v[6:9]
	v_mfma_f32_16x16x32_bf16 v[2:5], v[212:215], v[196:199], v[2:5]
	s_add_i32 s69, s69, 2
	s_add_u32 s65, s65, 0x100
	s_addc_u32 s67, s67, 0
	s_add_u32 s36, s36, 0x100
	s_addc_u32 s37, s37, 0
	s_cmp_gt_u32 s69, 13
	s_barrier
	s_cbranch_scc1 .Lpeel_exit_16
.LBB0_2495:
	ds_read_b128 v[130:133], v168
	ds_read_b128 v[134:137], v168 offset:1024
	ds_read_b128 v[138:141], v168 offset:2048
	ds_read_b128 v[142:145], v168 offset:3072
	s_add_u32 s0, s36, 0xfffc0080
	s_addc_u32 s1, s37, -1
	s_cmp_eq_u32 s69, 12
	s_cselect_b32 s41, s61, s1
	s_cselect_b32 s40, s62, s0
	s_cselect_b32 s39, s63, s67
	s_cselect_b32 s38, s64, s65
	s_mov_b32 m0, s51
	ds_read_b128 v[146:149], v169
	ds_read_b128 v[172:175], v169 offset:1024
	ds_read_b128 v[176:179], v169 offset:2048
	ds_read_b128 v[180:183], v169 offset:3072
	ds_read_b128 v[184:187], v169 offset:4096
	ds_read_b128 v[188:191], v169 offset:5120
	ds_read_b128 v[192:195], v169 offset:6144
	ds_read_b128 v[196:199], v169 offset:7168
	global_load_lds_dwordx4 v162, s[36:37]
	s_mov_b32 m0, s52
	s_nop 0
	global_load_lds_dwordx4 v160, s[36:37]
	s_waitcnt lgkmcnt(8)
	s_waitcnt vmcnt(10)
	s_barrier
	s_waitcnt lgkmcnt(0)
	s_waitcnt lgkmcnt(0)
	v_mfma_f32_16x16x32_bf16 v[126:129], v[130:133], v[146:149], v[126:129]
	v_mfma_f32_16x16x32_bf16 v[122:125], v[138:141], v[146:149], v[122:125]
	v_mfma_f32_16x16x32_bf16 v[118:121], v[130:133], v[176:179], v[118:121]
	v_mfma_f32_16x16x32_bf16 v[110:113], v[138:141], v[176:179], v[110:113]
	v_mfma_f32_16x16x32_bf16 v[98:101], v[130:133], v[184:187], v[98:101]
	v_mfma_f32_16x16x32_bf16 v[90:93], v[138:141], v[184:187], v[90:93]
	v_mfma_f32_16x16x32_bf16 v[82:85], v[130:133], v[192:195], v[82:85]
	v_mfma_f32_16x16x32_bf16 v[74:77], v[138:141], v[192:195], v[74:77]
	v_mfma_f32_16x16x32_bf16 v[126:129], v[134:137], v[172:175], v[126:129]
	v_mfma_f32_16x16x32_bf16 v[122:125], v[142:145], v[172:175], v[122:125]
	v_mfma_f32_16x16x32_bf16 v[118:121], v[134:137], v[180:183], v[118:121]
	v_mfma_f32_16x16x32_bf16 v[110:113], v[142:145], v[180:183], v[110:113]
	v_mfma_f32_16x16x32_bf16 v[98:101], v[134:137], v[188:191], v[98:101]
	v_mfma_f32_16x16x32_bf16 v[90:93], v[142:145], v[188:191], v[90:93]
	v_mfma_f32_16x16x32_bf16 v[82:85], v[134:137], v[196:199], v[82:85]
	v_mfma_f32_16x16x32_bf16 v[74:77], v[142:145], v[196:199], v[74:77]
	s_barrier
	s_mov_b32 m0, s53
	v_lshl_add_u64 v[164:165], s[38:39], 0, v[156:157]
	ds_read_b128 v[200:203], v170
	ds_read_b128 v[204:207], v170 offset:1024
	ds_read_b128 v[208:211], v170 offset:2048
	ds_read_b128 v[212:215], v170 offset:3072
	global_load_lds_dwordx4 v[164:165], off
	v_lshl_add_u64 v[216:217], s[38:39], 0, v[152:153]
	s_mov_b32 m0, s54
	s_nop 0
	global_load_lds_dwordx4 v[216:217], off
	s_waitcnt vmcnt(10)
	s_barrier
	s_waitcnt lgkmcnt(0)
	s_waitcnt lgkmcnt(0)
	v_mfma_f32_16x16x32_bf16 v[114:117], v[200:203], v[146:149], v[114:117]
	v_mfma_f32_16x16x32_bf16 v[106:109], v[208:211], v[146:149], v[106:109]
	v_mfma_f32_16x16x32_bf16 v[102:105], v[200:203], v[176:179], v[102:105]
	v_mfma_f32_16x16x32_bf16 v[94:97], v[208:211], v[176:179], v[94:97]
	v_mfma_f32_16x16x32_bf16 v[86:89], v[200:203], v[184:187], v[86:89]
	v_mfma_f32_16x16x32_bf16 v[78:81], v[208:211], v[184:187], v[78:81]
	v_mfma_f32_16x16x32_bf16 v[70:73], v[200:203], v[192:195], v[70:73]
	v_mfma_f32_16x16x32_bf16 v[66:69], v[208:211], v[192:195], v[66:69]
	v_mfma_f32_16x16x32_bf16 v[114:117], v[204:207], v[172:175], v[114:117]
	v_mfma_f32_16x16x32_bf16 v[106:109], v[212:215], v[172:175], v[106:109]
	v_mfma_f32_16x16x32_bf16 v[102:105], v[204:207], v[180:183], v[102:105]
	v_mfma_f32_16x16x32_bf16 v[94:97], v[212:215], v[180:183], v[94:97]
	v_mfma_f32_16x16x32_bf16 v[86:89], v[204:207], v[188:191], v[86:89]
	v_mfma_f32_16x16x32_bf16 v[78:81], v[212:215], v[188:191], v[78:81]
	v_mfma_f32_16x16x32_bf16 v[70:73], v[204:207], v[196:199], v[70:73]
	v_mfma_f32_16x16x32_bf16 v[66:69], v[212:215], v[196:199], v[66:69]
	s_mov_b32 m0, s9
	v_lshl_add_u64 v[218:219], s[40:41], 0, v[158:159]
	s_barrier
	ds_read_b128 v[146:149], v169 offset:16384
	ds_read_b128 v[172:175], v169 offset:17408
	ds_read_b128 v[176:179], v169 offset:18432
	ds_read_b128 v[180:183], v169 offset:19456
	ds_read_b128 v[184:187], v169 offset:20480
	ds_read_b128 v[188:191], v169 offset:21504
	ds_read_b128 v[192:195], v169 offset:22528
	ds_read_b128 v[196:199], v169 offset:23552
	global_load_lds_dwordx4 v[218:219], off
	v_lshl_add_u64 v[220:221], s[40:41], 0, v[154:155]
	s_mov_b32 m0, s29
	s_nop 0
	global_load_lds_dwordx4 v[220:221], off
	s_waitcnt vmcnt(10)
	s_barrier
	s_waitcnt lgkmcnt(0)
	s_waitcnt lgkmcnt(0)
	v_mfma_f32_16x16x32_bf16 v[62:65], v[130:133], v[146:149], v[62:65]
	v_mfma_f32_16x16x32_bf16 v[58:61], v[138:141], v[146:149], v[58:61]
	v_mfma_f32_16x16x32_bf16 v[50:53], v[130:133], v[176:179], v[50:53]
	v_mfma_f32_16x16x32_bf16 v[42:45], v[138:141], v[176:179], v[42:45]
	v_mfma_f32_16x16x32_bf16 v[34:37], v[130:133], v[184:187], v[34:37]
	v_mfma_f32_16x16x32_bf16 v[26:29], v[138:141], v[184:187], v[26:29]
	v_mfma_f32_16x16x32_bf16 v[18:21], v[130:133], v[192:195], v[18:21]
	v_mfma_f32_16x16x32_bf16 v[10:13], v[138:141], v[192:195], v[10:13]
	v_mfma_f32_16x16x32_bf16 v[62:65], v[134:137], v[172:175], v[62:65]
	v_mfma_f32_16x16x32_bf16 v[58:61], v[142:145], v[172:175], v[58:61]
	v_mfma_f32_16x16x32_bf16 v[50:53], v[134:137], v[180:183], v[50:53]
	v_mfma_f32_16x16x32_bf16 v[42:45], v[142:145], v[180:183], v[42:45]
	v_mfma_f32_16x16x32_bf16 v[34:37], v[134:137], v[188:191], v[34:37]
	v_mfma_f32_16x16x32_bf16 v[26:29], v[142:145], v[188:191], v[26:29]
	v_mfma_f32_16x16x32_bf16 v[18:21], v[134:137], v[196:199], v[18:21]
	v_mfma_f32_16x16x32_bf16 v[10:13], v[142:145], v[196:199], v[10:13]
	s_barrier
	s_add_u32 s0, s38, 0x40000
	s_addc_u32 s1, s39, 0
	s_mov_b32 m0, s55
	s_nop 0
	global_load_lds_dwordx4 v156, s[0:1]
	s_add_i32 m0, s55, 0x2000
	s_nop 0
	global_load_lds_dwordx4 v152, s[0:1]
	s_waitcnt vmcnt(10)
	s_barrier
	v_mfma_f32_16x16x32_bf16 v[54:57], v[200:203], v[146:149], v[54:57]
	v_mfma_f32_16x16x32_bf16 v[46:49], v[208:211], v[146:149], v[46:49]
	v_mfma_f32_16x16x32_bf16 v[38:41], v[200:203], v[176:179], v[38:41]
	v_mfma_f32_16x16x32_bf16 v[30:33], v[208:211], v[176:179], v[30:33]
	v_mfma_f32_16x16x32_bf16 v[22:25], v[200:203], v[184:187], v[22:25]
	v_mfma_f32_16x16x32_bf16 v[14:17], v[208:211], v[184:187], v[14:17]
	v_mfma_f32_16x16x32_bf16 v[6:9], v[200:203], v[192:195], v[6:9]
	v_mfma_f32_16x16x32_bf16 v[2:5], v[208:211], v[192:195], v[2:5]
	v_mfma_f32_16x16x32_bf16 v[54:57], v[204:207], v[172:175], v[54:57]
	v_mfma_f32_16x16x32_bf16 v[46:49], v[212:215], v[172:175], v[46:49]
	v_mfma_f32_16x16x32_bf16 v[38:41], v[204:207], v[180:183], v[38:41]
	v_mfma_f32_16x16x32_bf16 v[30:33], v[212:215], v[180:183], v[30:33]
	v_mfma_f32_16x16x32_bf16 v[22:25], v[204:207], v[188:191], v[22:25]
	v_mfma_f32_16x16x32_bf16 v[14:17], v[212:215], v[188:191], v[14:17]
	v_mfma_f32_16x16x32_bf16 v[6:9], v[204:207], v[196:199], v[6:9]
	v_mfma_f32_16x16x32_bf16 v[2:5], v[212:215], v[196:199], v[2:5]
	s_add_i32 s70, 0, 0x18000
	v_add_u32_e32 v142, s70, v167
	s_barrier
	ds_read_b128 v[130:133], v142
	ds_read_b128 v[134:137], v142 offset:1024
	ds_read_b128 v[138:141], v142 offset:2048
	ds_read_b128 v[142:145], v142 offset:3072
	s_add_u32 s0, s40, 0x40000
	s_addc_u32 s1, s41, 0
	s_mov_b32 m0, s42
	ds_read_b128 v[146:149], v169 offset:32768
	ds_read_b128 v[172:175], v169 offset:33792
	ds_read_b128 v[176:179], v169 offset:34816
	ds_read_b128 v[180:183], v169 offset:35840
	ds_read_b128 v[184:187], v169 offset:36864
	ds_read_b128 v[188:191], v169 offset:37888
	ds_read_b128 v[192:195], v169 offset:38912
	ds_read_b128 v[196:199], v169 offset:39936
	global_load_lds_dwordx4 v158, s[0:1]
	s_mov_b32 m0, s43
	s_nop 0
	global_load_lds_dwordx4 v154, s[0:1]
	s_waitcnt lgkmcnt(8)
	s_waitcnt vmcnt(10)
	s_barrier
	s_waitcnt lgkmcnt(0)
	s_waitcnt lgkmcnt(0)
	v_mfma_f32_16x16x32_bf16 v[126:129], v[130:133], v[146:149], v[126:129]
	v_mfma_f32_16x16x32_bf16 v[122:125], v[138:141], v[146:149], v[122:125]
	v_mfma_f32_16x16x32_bf16 v[118:121], v[130:133], v[176:179], v[118:121]
	v_mfma_f32_16x16x32_bf16 v[110:113], v[138:141], v[176:179], v[110:113]
	v_mfma_f32_16x16x32_bf16 v[98:101], v[130:133], v[184:187], v[98:101]
	v_mfma_f32_16x16x32_bf16 v[90:93], v[138:141], v[184:187], v[90:93]
	v_mfma_f32_16x16x32_bf16 v[82:85], v[130:133], v[192:195], v[82:85]
	v_mfma_f32_16x16x32_bf16 v[74:77], v[138:141], v[192:195], v[74:77]
	v_mfma_f32_16x16x32_bf16 v[126:129], v[134:137], v[172:175], v[126:129]
	v_mfma_f32_16x16x32_bf16 v[122:125], v[142:145], v[172:175], v[122:125]
	v_mfma_f32_16x16x32_bf16 v[118:121], v[134:137], v[180:183], v[118:121]
	v_mfma_f32_16x16x32_bf16 v[110:113], v[142:145], v[180:183], v[110:113]
	v_mfma_f32_16x16x32_bf16 v[98:101], v[134:137], v[188:191], v[98:101]
	v_mfma_f32_16x16x32_bf16 v[90:93], v[142:145], v[188:191], v[90:93]
	v_mfma_f32_16x16x32_bf16 v[82:85], v[134:137], v[196:199], v[82:85]
	v_mfma_f32_16x16x32_bf16 v[74:77], v[142:145], v[196:199], v[74:77]
	s_barrier
	s_add_i32 s40, 0, 0x1c000
	s_add_i32 s0, s70, s8
	v_add_u32_e32 v171, s40, v167
	v_lshl_add_u64 v[164:165], v[164:165], 0, s[26:27]
	s_mov_b32 m0, s0
	ds_read_b128 v[200:203], v171
	ds_read_b128 v[204:207], v171 offset:1024
	ds_read_b128 v[208:211], v171 offset:2048
	ds_read_b128 v[212:215], v171 offset:3072
	global_load_lds_dwordx4 v[164:165], off
	v_lshl_add_u64 v[164:165], v[216:217], 0, s[26:27]
	s_add_i32 m0, s0, 0x2000
	s_nop 0
	global_load_lds_dwordx4 v[164:165], off
	s_waitcnt vmcnt(10)
	s_barrier
	s_waitcnt lgkmcnt(0)
	s_waitcnt lgkmcnt(0)
	v_mfma_f32_16x16x32_bf16 v[114:117], v[200:203], v[146:149], v[114:117]
	v_mfma_f32_16x16x32_bf16 v[106:109], v[208:211], v[146:149], v[106:109]
	v_mfma_f32_16x16x32_bf16 v[102:105], v[200:203], v[176:179], v[102:105]
	v_mfma_f32_16x16x32_bf16 v[94:97], v[208:211], v[176:179], v[94:97]
	v_mfma_f32_16x16x32_bf16 v[86:89], v[200:203], v[184:187], v[86:89]
	v_mfma_f32_16x16x32_bf16 v[78:81], v[208:211], v[184:187], v[78:81]
	v_mfma_f32_16x16x32_bf16 v[70:73], v[200:203], v[192:195], v[70:73]
	v_mfma_f32_16x16x32_bf16 v[66:69], v[208:211], v[192:195], v[66:69]
	v_mfma_f32_16x16x32_bf16 v[114:117], v[204:207], v[172:175], v[114:117]
	v_mfma_f32_16x16x32_bf16 v[106:109], v[212:215], v[172:175], v[106:109]
	v_mfma_f32_16x16x32_bf16 v[102:105], v[204:207], v[180:183], v[102:105]
	v_mfma_f32_16x16x32_bf16 v[94:97], v[212:215], v[180:183], v[94:97]
	v_mfma_f32_16x16x32_bf16 v[86:89], v[204:207], v[188:191], v[86:89]
	v_mfma_f32_16x16x32_bf16 v[78:81], v[212:215], v[188:191], v[78:81]
	v_mfma_f32_16x16x32_bf16 v[70:73], v[204:207], v[196:199], v[70:73]
	v_mfma_f32_16x16x32_bf16 v[66:69], v[212:215], v[196:199], v[66:69]
	s_mov_b32 m0, s49
	v_lshl_add_u64 v[164:165], v[218:219], 0, s[26:27]
	s_barrier
	ds_read_b128 v[146:149], v169 offset:49152
	ds_read_b128 v[172:175], v169 offset:50176
	ds_read_b128 v[176:179], v169 offset:51200
	ds_read_b128 v[180:183], v169 offset:52224
	ds_read_b128 v[184:187], v169 offset:53248
	ds_read_b128 v[188:191], v169 offset:54272
	ds_read_b128 v[192:195], v169 offset:55296
	ds_read_b128 v[196:199], v169 offset:56320
	global_load_lds_dwordx4 v[164:165], off
	v_lshl_add_u64 v[164:165], v[220:221], 0, s[26:27]
	s_mov_b32 m0, s50
	s_nop 0
	global_load_lds_dwordx4 v[164:165], off
	s_waitcnt vmcnt(10)
	s_barrier
	s_waitcnt lgkmcnt(0)
	s_waitcnt lgkmcnt(0)
	v_mfma_f32_16x16x32_bf16 v[62:65], v[130:133], v[146:149], v[62:65]
	v_mfma_f32_16x16x32_bf16 v[58:61], v[138:141], v[146:149], v[58:61]
	v_mfma_f32_16x16x32_bf16 v[50:53], v[130:133], v[176:179], v[50:53]
	v_mfma_f32_16x16x32_bf16 v[42:45], v[138:141], v[176:179], v[42:45]
	v_mfma_f32_16x16x32_bf16 v[34:37], v[130:133], v[184:187], v[34:37]
	v_mfma_f32_16x16x32_bf16 v[26:29], v[138:141], v[184:187], v[26:29]
	v_mfma_f32_16x16x32_bf16 v[18:21], v[130:133], v[192:195], v[18:21]
	v_mfma_f32_16x16x32_bf16 v[10:13], v[138:141], v[192:195], v[10:13]
	v_mfma_f32_16x16x32_bf16 v[62:65], v[134:137], v[172:175], v[62:65]
	v_mfma_f32_16x16x32_bf16 v[58:61], v[142:145], v[172:175], v[58:61]
	v_mfma_f32_16x16x32_bf16 v[50:53], v[134:137], v[180:183], v[50:53]
	v_mfma_f32_16x16x32_bf16 v[42:45], v[142:145], v[180:183], v[42:45]
	v_mfma_f32_16x16x32_bf16 v[34:37], v[134:137], v[188:191], v[34:37]
	v_mfma_f32_16x16x32_bf16 v[26:29], v[142:145], v[188:191], v[26:29]
	v_mfma_f32_16x16x32_bf16 v[18:21], v[134:137], v[196:199], v[18:21]
	v_mfma_f32_16x16x32_bf16 v[10:13], v[142:145], v[196:199], v[10:13]
	s_barrier
	s_add_u32 s0, s38, 0x40080
	s_addc_u32 s1, s39, 0
	s_add_i32 s38, s40, s8
	s_mov_b32 m0, s38
	s_nop 0
	global_load_lds_dwordx4 v156, s[0:1]
	s_add_i32 m0, s38, 0x2000
	s_nop 0
	global_load_lds_dwordx4 v152, s[0:1]
	s_waitcnt vmcnt(10)
	s_barrier
	v_mfma_f32_16x16x32_bf16 v[54:57], v[200:203], v[146:149], v[54:57]
	v_mfma_f32_16x16x32_bf16 v[46:49], v[208:211], v[146:149], v[46:49]
	v_mfma_f32_16x16x32_bf16 v[38:41], v[200:203], v[176:179], v[38:41]
	v_mfma_f32_16x16x32_bf16 v[30:33], v[208:211], v[176:179], v[30:33]
	v_mfma_f32_16x16x32_bf16 v[22:25], v[200:203], v[184:187], v[22:25]
	v_mfma_f32_16x16x32_bf16 v[14:17], v[208:211], v[184:187], v[14:17]
	v_mfma_f32_16x16x32_bf16 v[6:9], v[200:203], v[192:195], v[6:9]
	v_mfma_f32_16x16x32_bf16 v[2:5], v[208:211], v[192:195], v[2:5]
	v_mfma_f32_16x16x32_bf16 v[54:57], v[204:207], v[172:175], v[54:57]
	v_mfma_f32_16x16x32_bf16 v[46:49], v[212:215], v[172:175], v[46:49]
	v_mfma_f32_16x16x32_bf16 v[38:41], v[204:207], v[180:183], v[38:41]
	v_mfma_f32_16x16x32_bf16 v[30:33], v[212:215], v[180:183], v[30:33]
	v_mfma_f32_16x16x32_bf16 v[22:25], v[204:207], v[188:191], v[22:25]
	v_mfma_f32_16x16x32_bf16 v[14:17], v[212:215], v[188:191], v[14:17]
	v_mfma_f32_16x16x32_bf16 v[6:9], v[204:207], v[196:199], v[6:9]
	v_mfma_f32_16x16x32_bf16 v[2:5], v[212:215], v[196:199], v[2:5]
	s_add_i32 s69, s69, 2
	s_add_u32 s65, s65, 0x100
	s_addc_u32 s67, s67, 0
	s_add_u32 s36, s36, 0x100
	s_addc_u32 s37, s37, 0
	s_cmp_gt_u32 s69, 13
	s_barrier
	s_cbranch_scc0 .LBB0_2495

.LBB0_2737:
	v_bfe_u32 v195, v2, 4, 2
	v_and_b32_e32 v194, 15, v2
	v_lshlrev_b32_e32 v3, 4, v195
	v_lshlrev_b32_e32 v2, 2, v2
	v_lshl_or_b32 v3, v194, 6, v3
	s_lshl_b32 s0, s6, 13
	v_and_b32_e32 v2, 32, v2
	v_bitop3_b32 v8, v3, s0, v2 bitop3:0xde
	s_lshl_b32 s0, s1, 5
	v_mov_b32_e32 v165, v163
	s_and_b32 s50, s0, 0x60
	v_lshl_add_u64 v[4:5], s[30:31], 0, v[164:165]
	v_mov_b32_e32 v167, v163
	s_lshl_b32 s0, s50, 7
	v_lshl_add_u64 v[6:7], s[30:31], 0, v[166:167]
	v_bitop3_b32 v196, v3, s0, v2 bitop3:0xde
	s_add_i32 m0, s45, 0x18000
	v_lshl_add_u64 v[2:3], v[4:5], 0, s[20:21]
	v_mov_b32_e32 v169, v163
	s_lshl_b32 s49, s6, 6
	s_waitcnt vmcnt(4)
	s_barrier
	global_load_lds_dwordx4 v[2:3], off
	v_lshl_add_u64 v[2:3], v[6:7], 0, s[20:21]
	s_add_i32 m0, s45, 0x1a000
	s_add_i32 s51, s45, 0x8000
	s_add_i32 s52, s45, 0xa000
	v_mov_b32_e32 v171, v163
	global_load_lds_dwordx4 v[2:3], off
	v_lshl_add_u64 v[2:3], s[18:19], 0, v[168:169]
	s_mov_b32 m0, s51
	s_add_u32 s0, s30, 0x20080
	global_load_lds_dwordx4 v[2:3], off
	v_lshl_add_u64 v[2:3], s[18:19], 0, v[170:171]
	s_mov_b32 m0, s52
	s_addc_u32 s1, s31, 0
	global_load_lds_dwordx4 v[2:3], off
	s_add_i32 m0, s45, 0x1c000
	s_nop 0
	global_load_lds_dwordx4 v164, s[0:1]
	s_add_i32 m0, s45, 0x1e000
	s_mov_b32 s53, 0
	global_load_lds_dwordx4 v166, s[0:1]
	s_waitcnt vmcnt(6)
	v_add_u32_e32 v169, 0, v8
	s_barrier

.LBB0_2748:
	s_ashr_i32 s0, s54, 5
	s_ashr_i32 s1, s0, 31
	s_lshl_b64 s[0:1], s[0:1], 21
	s_add_u32 s12, s4, s0
	s_addc_u32 s13, s5, s1
	s_ashr_i32 s25, s24, 31
	s_lshl_b64 s[0:1], s[24:25], 18
	s_add_u32 s12, s12, s0
	s_addc_u32 s13, s13, s1
	s_and_b64 s[0:1], s[10:11], exec
	s_cselect_b32 s25, s13, s31
	s_cselect_b32 s27, s12, s30
	v_mov_b32_e32 v173, v163
	v_mov_b32_e32 v175, v163
	s_add_u32 s29, s30, 0x100
	s_addc_u32 s55, s31, 0
	v_lshl_add_u64 v[176:177], s[18:19], 0, v[174:175]
	v_lshl_add_u64 v[178:179], s[18:19], 0, v[172:173]
	s_mov_b32 s56, -2
	s_mov_b64 s[34:35], 0
	s_add_u32 s10, s34, 0x100
	s_addc_u32 s11, s35, 0
	s_add_u32 s30, s29, s34
	s_addc_u32 s31, s55, s35
	s_cmpk_eq_i32 s34, 0x300
	s_cselect_b64 vcc, -1, 0
	s_and_b64 s[0:1], vcc, exec
	s_cselect_b32 s1, 0, s10
	s_cselect_b32 s0, 0, s11
	s_cselect_b32 s30, s27, s30
	s_cselect_b32 s31, s25, s31
	s_add_u32 s36, s14, s1
	s_addc_u32 s37, s15, s0
	s_add_i32 s1, 0, 0x10000
	v_add_u32_e32 v14, s1, v196
	ds_read_b128 v[2:5], v14
	ds_read_b128 v[6:9], v14 offset:1024
	ds_read_b128 v[10:13], v14 offset:2048
	ds_read_b128 v[14:17], v14 offset:3072
	v_cndmask_b32_e32 v162, v168, v171, vcc
	v_cndmask_b32_e32 v184, v170, v197, vcc
	v_cndmask_b32_e32 v175, v172, v198, vcc
	v_cndmask_b32_e32 v173, v174, v199, vcc
	v_lshl_add_u64 v[18:19], v[178:179], 0, s[34:35]
	s_add_i32 m0, s45, 0xc000
	ds_read_b128 v[200:203], v169
	ds_read_b128 v[204:207], v169 offset:1024
	ds_read_b128 v[208:211], v169 offset:2048
	ds_read_b128 v[212:215], v169 offset:3072
	ds_read_b128 v[216:219], v169 offset:4096
	ds_read_b128 v[220:223], v169 offset:5120
	ds_read_b128 v[224:227], v169 offset:6144
	ds_read_b128 v[228:231], v169 offset:7168
	global_load_lds_dwordx4 v[18:19], off
	v_lshl_add_u64 v[18:19], v[176:177], 0, s[34:35]
	s_add_i32 m0, s45, 0xe000
	s_nop 0
	global_load_lds_dwordx4 v[18:19], off
	s_waitcnt lgkmcnt(8)
	s_waitcnt vmcnt(10)
	s_barrier
	s_waitcnt lgkmcnt(0)
	s_waitcnt lgkmcnt(0)
	v_mfma_scale_f32_16x16x128_f8f6f4 v[158:161], v[2:9], v[200:207], 0, v1, v1 op_sel_hi:[0,0,0]
	v_mfma_scale_f32_16x16x128_f8f6f4 v[150:153], v[10:17], v[200:207], 0, v1, v1 op_sel_hi:[0,0,0]
	v_mfma_scale_f32_16x16x128_f8f6f4 v[142:145], v[2:9], v[208:215], 0, v1, v1 op_sel_hi:[0,0,0]
	v_mfma_scale_f32_16x16x128_f8f6f4 v[134:137], v[10:17], v[208:215], 0, v1, v1 op_sel_hi:[0,0,0]
	v_mfma_scale_f32_16x16x128_f8f6f4 v[126:129], v[2:9], v[216:223], 0, v1, v1 op_sel_hi:[0,0,0]
	v_mfma_scale_f32_16x16x128_f8f6f4 v[118:121], v[10:17], v[216:223], 0, v1, v1 op_sel_hi:[0,0,0]
	v_mfma_scale_f32_16x16x128_f8f6f4 v[110:113], v[2:9], v[224:231], 0, v1, v1 op_sel_hi:[0,0,0]
	v_mfma_scale_f32_16x16x128_f8f6f4 v[102:105], v[10:17], v[224:231], 0, v1, v1 op_sel_hi:[0,0,0]
	s_barrier
	s_add_i32 s0, 0, 0x14000
	s_add_i32 s1, s1, s43
	v_add_u32_e32 v30, s0, v196
	v_lshl_add_u64 v[180:181], s[30:31], 0, v[164:165]
	s_mov_b32 m0, s1
	ds_read_b128 v[18:21], v30
	ds_read_b128 v[22:25], v30 offset:1024
	ds_read_b128 v[26:29], v30 offset:2048
	ds_read_b128 v[30:33], v30 offset:3072
	global_load_lds_dwordx4 v[180:181], off
	v_lshl_add_u64 v[182:183], s[30:31], 0, v[166:167]
	s_add_i32 m0, s1, 0x2000
	s_nop 0
	global_load_lds_dwordx4 v[182:183], off
	s_waitcnt vmcnt(10)
	s_barrier
	s_waitcnt lgkmcnt(0)
	s_waitcnt lgkmcnt(0)
	v_mfma_scale_f32_16x16x128_f8f6f4 v[154:157], v[18:25], v[200:207], 0, v1, v1 op_sel_hi:[0,0,0]
	v_mfma_scale_f32_16x16x128_f8f6f4 v[146:149], v[26:33], v[200:207], 0, v1, v1 op_sel_hi:[0,0,0]
	v_mfma_scale_f32_16x16x128_f8f6f4 v[138:141], v[18:25], v[208:215], 0, v1, v1 op_sel_hi:[0,0,0]
	v_mfma_scale_f32_16x16x128_f8f6f4 v[130:133], v[26:33], v[208:215], 0, v1, v1 op_sel_hi:[0,0,0]
	v_mfma_scale_f32_16x16x128_f8f6f4 v[122:125], v[18:25], v[216:223], 0, v1, v1 op_sel_hi:[0,0,0]
	v_mfma_scale_f32_16x16x128_f8f6f4 v[114:117], v[26:33], v[216:223], 0, v1, v1 op_sel_hi:[0,0,0]
	v_mfma_scale_f32_16x16x128_f8f6f4 v[106:109], v[18:25], v[224:231], 0, v1, v1 op_sel_hi:[0,0,0]
	v_mfma_scale_f32_16x16x128_f8f6f4 v[98:101], v[26:33], v[224:231], 0, v1, v1 op_sel_hi:[0,0,0]
	s_mov_b32 m0, s45
	s_barrier
	ds_read_b128 v[200:203], v169 offset:16384
	ds_read_b128 v[204:207], v169 offset:17408
	ds_read_b128 v[208:211], v169 offset:18432
	ds_read_b128 v[212:215], v169 offset:19456
	ds_read_b128 v[216:219], v169 offset:20480
	ds_read_b128 v[220:223], v169 offset:21504
	ds_read_b128 v[224:227], v169 offset:22528
	ds_read_b128 v[228:231], v169 offset:23552
	global_load_lds_dwordx4 v162, s[36:37]
	s_mov_b32 m0, s46
	v_mov_b32_e32 v185, v163
	global_load_lds_dwordx4 v184, s[36:37]
	s_waitcnt vmcnt(10)
	s_barrier
	s_waitcnt lgkmcnt(0)
	v_lshl_add_u64 v[186:187], s[36:37], 0, v[162:163]
	v_lshl_add_u64 v[184:185], s[36:37], 0, v[184:185]
	s_waitcnt lgkmcnt(0)
	v_mfma_scale_f32_16x16x128_f8f6f4 v[94:97], v[2:9], v[200:207], 0, v1, v1 op_sel_hi:[0,0,0]
	v_mfma_scale_f32_16x16x128_f8f6f4 v[86:89], v[10:17], v[200:207], 0, v1, v1 op_sel_hi:[0,0,0]
	v_mfma_scale_f32_16x16x128_f8f6f4 v[78:81], v[2:9], v[208:215], 0, v1, v1 op_sel_hi:[0,0,0]
	v_mfma_scale_f32_16x16x128_f8f6f4 v[70:73], v[10:17], v[208:215], 0, v1, v1 op_sel_hi:[0,0,0]
	v_mfma_scale_f32_16x16x128_f8f6f4 v[62:65], v[2:9], v[216:223], 0, v1, v1 op_sel_hi:[0,0,0]
	v_mfma_scale_f32_16x16x128_f8f6f4 v[54:57], v[10:17], v[216:223], 0, v1, v1 op_sel_hi:[0,0,0]
	v_mfma_scale_f32_16x16x128_f8f6f4 v[46:49], v[2:9], v[224:231], 0, v1, v1 op_sel_hi:[0,0,0]
	v_mfma_scale_f32_16x16x128_f8f6f4 v[38:41], v[10:17], v[224:231], 0, v1, v1 op_sel_hi:[0,0,0]
	s_barrier
	s_add_u32 s34, s30, 0x20000
	s_addc_u32 s35, s31, 0
	s_add_i32 s0, s0, s43
	s_mov_b32 m0, s0
	s_nop 0
	global_load_lds_dwordx4 v164, s[34:35]
	s_add_i32 m0, s0, 0x2000
	s_nop 0
	global_load_lds_dwordx4 v166, s[34:35]
	s_waitcnt vmcnt(10)
	s_barrier
	v_mfma_scale_f32_16x16x128_f8f6f4 v[90:93], v[18:25], v[200:207], 0, v1, v1 op_sel_hi:[0,0,0]
	v_mfma_scale_f32_16x16x128_f8f6f4 v[82:85], v[26:33], v[200:207], 0, v1, v1 op_sel_hi:[0,0,0]
	v_mfma_scale_f32_16x16x128_f8f6f4 v[74:77], v[18:25], v[208:215], 0, v1, v1 op_sel_hi:[0,0,0]
	v_mfma_scale_f32_16x16x128_f8f6f4 v[66:69], v[26:33], v[208:215], 0, v1, v1 op_sel_hi:[0,0,0]
	v_mfma_scale_f32_16x16x128_f8f6f4 v[58:61], v[18:25], v[216:223], 0, v1, v1 op_sel_hi:[0,0,0]
	v_mfma_scale_f32_16x16x128_f8f6f4 v[50:53], v[26:33], v[216:223], 0, v1, v1 op_sel_hi:[0,0,0]
	v_mfma_scale_f32_16x16x128_f8f6f4 v[42:45], v[18:25], v[224:231], 0, v1, v1 op_sel_hi:[0,0,0]
	v_mfma_scale_f32_16x16x128_f8f6f4 v[34:37], v[26:33], v[224:231], 0, v1, v1 op_sel_hi:[0,0,0]
	s_add_i32 s0, 0, 0x18000
	v_add_u32_e32 v14, s0, v196
	s_barrier
	ds_read_b128 v[2:5], v14
	ds_read_b128 v[6:9], v14 offset:1024
	ds_read_b128 v[10:13], v14 offset:2048
	ds_read_b128 v[14:17], v14 offset:3072
	s_mov_b32 m0, s47
	ds_read_b128 v[18:21], v169 offset:32768
	ds_read_b128 v[22:25], v169 offset:33792
	ds_read_b128 v[26:29], v169 offset:34816
	ds_read_b128 v[30:33], v169 offset:35840
	ds_read_b128 v[200:203], v169 offset:36864
	ds_read_b128 v[204:207], v169 offset:37888
	ds_read_b128 v[208:211], v169 offset:38912
	ds_read_b128 v[212:215], v169 offset:39936
	global_load_lds_dwordx4 v175, s[36:37]
	s_mov_b32 m0, s48
	s_nop 0
	global_load_lds_dwordx4 v173, s[36:37]
	s_waitcnt lgkmcnt(8)
	s_waitcnt vmcnt(10)
	s_barrier
	s_waitcnt lgkmcnt(0)
	s_waitcnt lgkmcnt(0)
	v_mfma_scale_f32_16x16x128_f8f6f4 v[158:161], v[2:9], v[18:25], v[158:161], v1, v1 op_sel_hi:[0,0,0]
	v_mfma_scale_f32_16x16x128_f8f6f4 v[150:153], v[10:17], v[18:25], v[150:153], v1, v1 op_sel_hi:[0,0,0]
	v_mfma_scale_f32_16x16x128_f8f6f4 v[142:145], v[2:9], v[26:33], v[142:145], v1, v1 op_sel_hi:[0,0,0]
	v_mfma_scale_f32_16x16x128_f8f6f4 v[134:137], v[10:17], v[26:33], v[134:137], v1, v1 op_sel_hi:[0,0,0]
	v_mfma_scale_f32_16x16x128_f8f6f4 v[126:129], v[2:9], v[200:207], v[126:129], v1, v1 op_sel_hi:[0,0,0]
	v_mfma_scale_f32_16x16x128_f8f6f4 v[118:121], v[10:17], v[200:207], v[118:121], v1, v1 op_sel_hi:[0,0,0]
	v_mfma_scale_f32_16x16x128_f8f6f4 v[110:113], v[2:9], v[208:215], v[110:113], v1, v1 op_sel_hi:[0,0,0]
	v_mfma_scale_f32_16x16x128_f8f6f4 v[102:105], v[10:17], v[208:215], v[102:105], v1, v1 op_sel_hi:[0,0,0]
	s_barrier
	s_add_i32 s34, 0, 0x1c000
	s_add_i32 s0, s0, s43
	v_add_u32_e32 v162, s34, v196
	v_lshl_add_u64 v[180:181], v[180:181], 0, s[20:21]
	s_mov_b32 m0, s0
	ds_read_b128 v[216:219], v162
	ds_read_b128 v[220:223], v162 offset:1024
	ds_read_b128 v[224:227], v162 offset:2048
	ds_read_b128 v[228:231], v162 offset:3072
	global_load_lds_dwordx4 v[180:181], off
	v_lshl_add_u64 v[180:181], v[182:183], 0, s[20:21]
	s_add_i32 m0, s0, 0x2000
	s_nop 0
	global_load_lds_dwordx4 v[180:181], off
	s_waitcnt vmcnt(10)
	s_barrier
	s_waitcnt lgkmcnt(0)
	s_waitcnt lgkmcnt(0)
	v_mfma_scale_f32_16x16x128_f8f6f4 v[154:157], v[216:223], v[18:25], v[154:157], v1, v1 op_sel_hi:[0,0,0]
	v_mfma_scale_f32_16x16x128_f8f6f4 v[146:149], v[224:231], v[18:25], v[146:149], v1, v1 op_sel_hi:[0,0,0]
	v_mfma_scale_f32_16x16x128_f8f6f4 v[138:141], v[216:223], v[26:33], v[138:141], v1, v1 op_sel_hi:[0,0,0]
	v_mfma_scale_f32_16x16x128_f8f6f4 v[130:133], v[224:231], v[26:33], v[130:133], v1, v1 op_sel_hi:[0,0,0]
	v_mfma_scale_f32_16x16x128_f8f6f4 v[122:125], v[216:223], v[200:207], v[122:125], v1, v1 op_sel_hi:[0,0,0]
	v_mfma_scale_f32_16x16x128_f8f6f4 v[114:117], v[224:231], v[200:207], v[114:117], v1, v1 op_sel_hi:[0,0,0]
	v_mfma_scale_f32_16x16x128_f8f6f4 v[106:109], v[216:223], v[208:215], v[106:109], v1, v1 op_sel_hi:[0,0,0]
	v_mfma_scale_f32_16x16x128_f8f6f4 v[98:101], v[224:231], v[208:215], v[98:101], v1, v1 op_sel_hi:[0,0,0]
	s_mov_b32 m0, s51
	v_lshl_add_u64 v[180:181], v[186:187], 0, s[20:21]
	s_barrier
	ds_read_b128 v[18:21], v169 offset:49152
	ds_read_b128 v[22:25], v169 offset:50176
	ds_read_b128 v[26:29], v169 offset:51200
	ds_read_b128 v[30:33], v169 offset:52224
	ds_read_b128 v[200:203], v169 offset:53248
	ds_read_b128 v[204:207], v169 offset:54272
	ds_read_b128 v[208:211], v169 offset:55296
	ds_read_b128 v[212:215], v169 offset:56320
	global_load_lds_dwordx4 v[180:181], off
	v_lshl_add_u64 v[180:181], v[184:185], 0, s[20:21]
	s_mov_b32 m0, s52
	s_nop 0
	global_load_lds_dwordx4 v[180:181], off
	s_waitcnt vmcnt(10)
	s_barrier
	s_waitcnt lgkmcnt(0)
	s_waitcnt lgkmcnt(0)
	v_mfma_scale_f32_16x16x128_f8f6f4 v[94:97], v[2:9], v[18:25], v[94:97], v1, v1 op_sel_hi:[0,0,0]
	v_mfma_scale_f32_16x16x128_f8f6f4 v[86:89], v[10:17], v[18:25], v[86:89], v1, v1 op_sel_hi:[0,0,0]
	v_mfma_scale_f32_16x16x128_f8f6f4 v[78:81], v[2:9], v[26:33], v[78:81], v1, v1 op_sel_hi:[0,0,0]
	v_mfma_scale_f32_16x16x128_f8f6f4 v[70:73], v[10:17], v[26:33], v[70:73], v1, v1 op_sel_hi:[0,0,0]
	v_mfma_scale_f32_16x16x128_f8f6f4 v[62:65], v[2:9], v[200:207], v[62:65], v1, v1 op_sel_hi:[0,0,0]
	v_mfma_scale_f32_16x16x128_f8f6f4 v[54:57], v[10:17], v[200:207], v[54:57], v1, v1 op_sel_hi:[0,0,0]
	v_mfma_scale_f32_16x16x128_f8f6f4 v[46:49], v[2:9], v[208:215], v[46:49], v1, v1 op_sel_hi:[0,0,0]
	v_mfma_scale_f32_16x16x128_f8f6f4 v[38:41], v[10:17], v[208:215], v[38:41], v1, v1 op_sel_hi:[0,0,0]
	s_barrier
	s_add_u32 s0, s30, 0x20080
	s_addc_u32 s1, s31, 0
	s_add_i32 s30, s34, s43
	s_mov_b32 m0, s30
	s_nop 0
	global_load_lds_dwordx4 v164, s[0:1]
	s_add_i32 m0, s30, 0x2000
	s_nop 0
	global_load_lds_dwordx4 v166, s[0:1]
	s_waitcnt vmcnt(10)
	s_barrier
	v_mfma_scale_f32_16x16x128_f8f6f4 v[90:93], v[216:223], v[18:25], v[90:93], v1, v1 op_sel_hi:[0,0,0]
	v_mfma_scale_f32_16x16x128_f8f6f4 v[82:85], v[224:231], v[18:25], v[82:85], v1, v1 op_sel_hi:[0,0,0]
	v_mfma_scale_f32_16x16x128_f8f6f4 v[74:77], v[216:223], v[26:33], v[74:77], v1, v1 op_sel_hi:[0,0,0]
	v_mfma_scale_f32_16x16x128_f8f6f4 v[66:69], v[224:231], v[26:33], v[66:69], v1, v1 op_sel_hi:[0,0,0]
	v_mfma_scale_f32_16x16x128_f8f6f4 v[58:61], v[216:223], v[200:207], v[58:61], v1, v1 op_sel_hi:[0,0,0]
	v_mfma_scale_f32_16x16x128_f8f6f4 v[50:53], v[224:231], v[200:207], v[50:53], v1, v1 op_sel_hi:[0,0,0]
	v_mfma_scale_f32_16x16x128_f8f6f4 v[42:45], v[216:223], v[208:215], v[42:45], v1, v1 op_sel_hi:[0,0,0]
	v_mfma_scale_f32_16x16x128_f8f6f4 v[34:37], v[224:231], v[208:215], v[34:37], v1, v1 op_sel_hi:[0,0,0]
	s_add_i32 s56, s56, 2
	s_cmp_gt_u32 s56, 5
	s_mov_b64 s[34:35], s[10:11]
	s_barrier
	s_cbranch_scc1 .Lpeel_exit_17
.LBB0_2749:
	s_add_u32 s10, s34, 0x100
	s_addc_u32 s11, s35, 0
	s_add_u32 s30, s29, s34
	s_addc_u32 s31, s55, s35
	s_cmpk_eq_i32 s34, 0x300
	s_cselect_b64 vcc, -1, 0
	s_and_b64 s[0:1], vcc, exec
	s_cselect_b32 s1, 0, s10
	s_cselect_b32 s0, 0, s11
	s_cselect_b32 s30, s27, s30
	s_cselect_b32 s31, s25, s31
	s_add_u32 s36, s14, s1
	s_addc_u32 s37, s15, s0
	s_add_i32 s1, 0, 0x10000
	v_add_u32_e32 v14, s1, v196
	ds_read_b128 v[2:5], v14
	ds_read_b128 v[6:9], v14 offset:1024
	ds_read_b128 v[10:13], v14 offset:2048
	ds_read_b128 v[14:17], v14 offset:3072
	v_cndmask_b32_e32 v162, v168, v171, vcc
	v_cndmask_b32_e32 v184, v170, v197, vcc
	v_cndmask_b32_e32 v175, v172, v198, vcc
	v_cndmask_b32_e32 v173, v174, v199, vcc
	v_lshl_add_u64 v[18:19], v[178:179], 0, s[34:35]
	s_add_i32 m0, s45, 0xc000
	ds_read_b128 v[200:203], v169
	ds_read_b128 v[204:207], v169 offset:1024
	ds_read_b128 v[208:211], v169 offset:2048
	ds_read_b128 v[212:215], v169 offset:3072
	ds_read_b128 v[216:219], v169 offset:4096
	ds_read_b128 v[220:223], v169 offset:5120
	ds_read_b128 v[224:227], v169 offset:6144
	ds_read_b128 v[228:231], v169 offset:7168
	global_load_lds_dwordx4 v[18:19], off
	v_lshl_add_u64 v[18:19], v[176:177], 0, s[34:35]
	s_add_i32 m0, s45, 0xe000
	s_nop 0
	global_load_lds_dwordx4 v[18:19], off
	s_waitcnt lgkmcnt(8)
	s_waitcnt vmcnt(10)
	s_barrier
	s_waitcnt lgkmcnt(0)
	s_waitcnt lgkmcnt(0)
	v_mfma_scale_f32_16x16x128_f8f6f4 v[158:161], v[2:9], v[200:207], v[158:161], v1, v1 op_sel_hi:[0,0,0]
	v_mfma_scale_f32_16x16x128_f8f6f4 v[150:153], v[10:17], v[200:207], v[150:153], v1, v1 op_sel_hi:[0,0,0]
	v_mfma_scale_f32_16x16x128_f8f6f4 v[142:145], v[2:9], v[208:215], v[142:145], v1, v1 op_sel_hi:[0,0,0]
	v_mfma_scale_f32_16x16x128_f8f6f4 v[134:137], v[10:17], v[208:215], v[134:137], v1, v1 op_sel_hi:[0,0,0]
	v_mfma_scale_f32_16x16x128_f8f6f4 v[126:129], v[2:9], v[216:223], v[126:129], v1, v1 op_sel_hi:[0,0,0]
	v_mfma_scale_f32_16x16x128_f8f6f4 v[118:121], v[10:17], v[216:223], v[118:121], v1, v1 op_sel_hi:[0,0,0]
	v_mfma_scale_f32_16x16x128_f8f6f4 v[110:113], v[2:9], v[224:231], v[110:113], v1, v1 op_sel_hi:[0,0,0]
	v_mfma_scale_f32_16x16x128_f8f6f4 v[102:105], v[10:17], v[224:231], v[102:105], v1, v1 op_sel_hi:[0,0,0]
	s_barrier
	s_add_i32 s0, 0, 0x14000
	s_add_i32 s1, s1, s43
	v_add_u32_e32 v30, s0, v196
	v_lshl_add_u64 v[180:181], s[30:31], 0, v[164:165]
	s_mov_b32 m0, s1
	ds_read_b128 v[18:21], v30
	ds_read_b128 v[22:25], v30 offset:1024
	ds_read_b128 v[26:29], v30 offset:2048
	ds_read_b128 v[30:33], v30 offset:3072
	global_load_lds_dwordx4 v[180:181], off
	v_lshl_add_u64 v[182:183], s[30:31], 0, v[166:167]
	s_add_i32 m0, s1, 0x2000
	s_nop 0
	global_load_lds_dwordx4 v[182:183], off
	s_waitcnt vmcnt(10)
	s_barrier
	s_waitcnt lgkmcnt(0)
	s_waitcnt lgkmcnt(0)
	v_mfma_scale_f32_16x16x128_f8f6f4 v[154:157], v[18:25], v[200:207], v[154:157], v1, v1 op_sel_hi:[0,0,0]
	v_mfma_scale_f32_16x16x128_f8f6f4 v[146:149], v[26:33], v[200:207], v[146:149], v1, v1 op_sel_hi:[0,0,0]
	v_mfma_scale_f32_16x16x128_f8f6f4 v[138:141], v[18:25], v[208:215], v[138:141], v1, v1 op_sel_hi:[0,0,0]
	v_mfma_scale_f32_16x16x128_f8f6f4 v[130:133], v[26:33], v[208:215], v[130:133], v1, v1 op_sel_hi:[0,0,0]
	v_mfma_scale_f32_16x16x128_f8f6f4 v[122:125], v[18:25], v[216:223], v[122:125], v1, v1 op_sel_hi:[0,0,0]
	v_mfma_scale_f32_16x16x128_f8f6f4 v[114:117], v[26:33], v[216:223], v[114:117], v1, v1 op_sel_hi:[0,0,0]
	v_mfma_scale_f32_16x16x128_f8f6f4 v[106:109], v[18:25], v[224:231], v[106:109], v1, v1 op_sel_hi:[0,0,0]
	v_mfma_scale_f32_16x16x128_f8f6f4 v[98:101], v[26:33], v[224:231], v[98:101], v1, v1 op_sel_hi:[0,0,0]
	s_mov_b32 m0, s45
	s_barrier
	ds_read_b128 v[200:203], v169 offset:16384
	ds_read_b128 v[204:207], v169 offset:17408
	ds_read_b128 v[208:211], v169 offset:18432
	ds_read_b128 v[212:215], v169 offset:19456
	ds_read_b128 v[216:219], v169 offset:20480
	ds_read_b128 v[220:223], v169 offset:21504
	ds_read_b128 v[224:227], v169 offset:22528
	ds_read_b128 v[228:231], v169 offset:23552
	global_load_lds_dwordx4 v162, s[36:37]
	s_mov_b32 m0, s46
	v_mov_b32_e32 v185, v163
	global_load_lds_dwordx4 v184, s[36:37]
	s_waitcnt vmcnt(10)
	s_barrier
	s_waitcnt lgkmcnt(0)
	v_lshl_add_u64 v[186:187], s[36:37], 0, v[162:163]
	v_lshl_add_u64 v[184:185], s[36:37], 0, v[184:185]
	s_waitcnt lgkmcnt(0)
	v_mfma_scale_f32_16x16x128_f8f6f4 v[94:97], v[2:9], v[200:207], v[94:97], v1, v1 op_sel_hi:[0,0,0]
	v_mfma_scale_f32_16x16x128_f8f6f4 v[86:89], v[10:17], v[200:207], v[86:89], v1, v1 op_sel_hi:[0,0,0]
	v_mfma_scale_f32_16x16x128_f8f6f4 v[78:81], v[2:9], v[208:215], v[78:81], v1, v1 op_sel_hi:[0,0,0]
	v_mfma_scale_f32_16x16x128_f8f6f4 v[70:73], v[10:17], v[208:215], v[70:73], v1, v1 op_sel_hi:[0,0,0]
	v_mfma_scale_f32_16x16x128_f8f6f4 v[62:65], v[2:9], v[216:223], v[62:65], v1, v1 op_sel_hi:[0,0,0]
	v_mfma_scale_f32_16x16x128_f8f6f4 v[54:57], v[10:17], v[216:223], v[54:57], v1, v1 op_sel_hi:[0,0,0]
	v_mfma_scale_f32_16x16x128_f8f6f4 v[46:49], v[2:9], v[224:231], v[46:49], v1, v1 op_sel_hi:[0,0,0]
	v_mfma_scale_f32_16x16x128_f8f6f4 v[38:41], v[10:17], v[224:231], v[38:41], v1, v1 op_sel_hi:[0,0,0]
	s_barrier
	s_add_u32 s34, s30, 0x20000
	s_addc_u32 s35, s31, 0
	s_add_i32 s0, s0, s43
	s_mov_b32 m0, s0
	s_nop 0
	global_load_lds_dwordx4 v164, s[34:35]
	s_add_i32 m0, s0, 0x2000
	s_nop 0
	global_load_lds_dwordx4 v166, s[34:35]
	s_waitcnt vmcnt(10)
	s_barrier
	v_mfma_scale_f32_16x16x128_f8f6f4 v[90:93], v[18:25], v[200:207], v[90:93], v1, v1 op_sel_hi:[0,0,0]
	v_mfma_scale_f32_16x16x128_f8f6f4 v[82:85], v[26:33], v[200:207], v[82:85], v1, v1 op_sel_hi:[0,0,0]
	v_mfma_scale_f32_16x16x128_f8f6f4 v[74:77], v[18:25], v[208:215], v[74:77], v1, v1 op_sel_hi:[0,0,0]
	v_mfma_scale_f32_16x16x128_f8f6f4 v[66:69], v[26:33], v[208:215], v[66:69], v1, v1 op_sel_hi:[0,0,0]
	v_mfma_scale_f32_16x16x128_f8f6f4 v[58:61], v[18:25], v[216:223], v[58:61], v1, v1 op_sel_hi:[0,0,0]
	v_mfma_scale_f32_16x16x128_f8f6f4 v[50:53], v[26:33], v[216:223], v[50:53], v1, v1 op_sel_hi:[0,0,0]
	v_mfma_scale_f32_16x16x128_f8f6f4 v[42:45], v[18:25], v[224:231], v[42:45], v1, v1 op_sel_hi:[0,0,0]
	v_mfma_scale_f32_16x16x128_f8f6f4 v[34:37], v[26:33], v[224:231], v[34:37], v1, v1 op_sel_hi:[0,0,0]
	s_add_i32 s0, 0, 0x18000
	v_add_u32_e32 v14, s0, v196
	s_barrier
	ds_read_b128 v[2:5], v14
	ds_read_b128 v[6:9], v14 offset:1024
	ds_read_b128 v[10:13], v14 offset:2048
	ds_read_b128 v[14:17], v14 offset:3072
	s_mov_b32 m0, s47
	ds_read_b128 v[18:21], v169 offset:32768
	ds_read_b128 v[22:25], v169 offset:33792
	ds_read_b128 v[26:29], v169 offset:34816
	ds_read_b128 v[30:33], v169 offset:35840
	ds_read_b128 v[200:203], v169 offset:36864
	ds_read_b128 v[204:207], v169 offset:37888
	ds_read_b128 v[208:211], v169 offset:38912
	ds_read_b128 v[212:215], v169 offset:39936
	global_load_lds_dwordx4 v175, s[36:37]
	s_mov_b32 m0, s48
	s_nop 0
	global_load_lds_dwordx4 v173, s[36:37]
	s_waitcnt lgkmcnt(8)
	s_waitcnt vmcnt(10)
	s_barrier
	s_waitcnt lgkmcnt(0)
	s_waitcnt lgkmcnt(0)
	v_mfma_scale_f32_16x16x128_f8f6f4 v[158:161], v[2:9], v[18:25], v[158:161], v1, v1 op_sel_hi:[0,0,0]
	v_mfma_scale_f32_16x16x128_f8f6f4 v[150:153], v[10:17], v[18:25], v[150:153], v1, v1 op_sel_hi:[0,0,0]
	v_mfma_scale_f32_16x16x128_f8f6f4 v[142:145], v[2:9], v[26:33], v[142:145], v1, v1 op_sel_hi:[0,0,0]
	v_mfma_scale_f32_16x16x128_f8f6f4 v[134:137], v[10:17], v[26:33], v[134:137], v1, v1 op_sel_hi:[0,0,0]
	v_mfma_scale_f32_16x16x128_f8f6f4 v[126:129], v[2:9], v[200:207], v[126:129], v1, v1 op_sel_hi:[0,0,0]
	v_mfma_scale_f32_16x16x128_f8f6f4 v[118:121], v[10:17], v[200:207], v[118:121], v1, v1 op_sel_hi:[0,0,0]
	v_mfma_scale_f32_16x16x128_f8f6f4 v[110:113], v[2:9], v[208:215], v[110:113], v1, v1 op_sel_hi:[0,0,0]
	v_mfma_scale_f32_16x16x128_f8f6f4 v[102:105], v[10:17], v[208:215], v[102:105], v1, v1 op_sel_hi:[0,0,0]
	s_barrier
	s_add_i32 s34, 0, 0x1c000
	s_add_i32 s0, s0, s43
	v_add_u32_e32 v162, s34, v196
	v_lshl_add_u64 v[180:181], v[180:181], 0, s[20:21]
	s_mov_b32 m0, s0
	ds_read_b128 v[216:219], v162
	ds_read_b128 v[220:223], v162 offset:1024
	ds_read_b128 v[224:227], v162 offset:2048
	ds_read_b128 v[228:231], v162 offset:3072
	global_load_lds_dwordx4 v[180:181], off
	v_lshl_add_u64 v[180:181], v[182:183], 0, s[20:21]
	s_add_i32 m0, s0, 0x2000
	s_nop 0
	global_load_lds_dwordx4 v[180:181], off
	s_waitcnt vmcnt(10)
	s_barrier
	s_waitcnt lgkmcnt(0)
	s_waitcnt lgkmcnt(0)
	v_mfma_scale_f32_16x16x128_f8f6f4 v[154:157], v[216:223], v[18:25], v[154:157], v1, v1 op_sel_hi:[0,0,0]
	v_mfma_scale_f32_16x16x128_f8f6f4 v[146:149], v[224:231], v[18:25], v[146:149], v1, v1 op_sel_hi:[0,0,0]
	v_mfma_scale_f32_16x16x128_f8f6f4 v[138:141], v[216:223], v[26:33], v[138:141], v1, v1 op_sel_hi:[0,0,0]
	v_mfma_scale_f32_16x16x128_f8f6f4 v[130:133], v[224:231], v[26:33], v[130:133], v1, v1 op_sel_hi:[0,0,0]
	v_mfma_scale_f32_16x16x128_f8f6f4 v[122:125], v[216:223], v[200:207], v[122:125], v1, v1 op_sel_hi:[0,0,0]
	v_mfma_scale_f32_16x16x128_f8f6f4 v[114:117], v[224:231], v[200:207], v[114:117], v1, v1 op_sel_hi:[0,0,0]
	v_mfma_scale_f32_16x16x128_f8f6f4 v[106:109], v[216:223], v[208:215], v[106:109], v1, v1 op_sel_hi:[0,0,0]
	v_mfma_scale_f32_16x16x128_f8f6f4 v[98:101], v[224:231], v[208:215], v[98:101], v1, v1 op_sel_hi:[0,0,0]
	s_mov_b32 m0, s51
	v_lshl_add_u64 v[180:181], v[186:187], 0, s[20:21]
	s_barrier
	ds_read_b128 v[18:21], v169 offset:49152
	ds_read_b128 v[22:25], v169 offset:50176
	ds_read_b128 v[26:29], v169 offset:51200
	ds_read_b128 v[30:33], v169 offset:52224
	ds_read_b128 v[200:203], v169 offset:53248
	ds_read_b128 v[204:207], v169 offset:54272
	ds_read_b128 v[208:211], v169 offset:55296
	ds_read_b128 v[212:215], v169 offset:56320
	global_load_lds_dwordx4 v[180:181], off
	v_lshl_add_u64 v[180:181], v[184:185], 0, s[20:21]
	s_mov_b32 m0, s52
	s_nop 0
	global_load_lds_dwordx4 v[180:181], off
	s_waitcnt vmcnt(10)
	s_barrier
	s_waitcnt lgkmcnt(0)
	s_waitcnt lgkmcnt(0)
	v_mfma_scale_f32_16x16x128_f8f6f4 v[94:97], v[2:9], v[18:25], v[94:97], v1, v1 op_sel_hi:[0,0,0]
	v_mfma_scale_f32_16x16x128_f8f6f4 v[86:89], v[10:17], v[18:25], v[86:89], v1, v1 op_sel_hi:[0,0,0]
	v_mfma_scale_f32_16x16x128_f8f6f4 v[78:81], v[2:9], v[26:33], v[78:81], v1, v1 op_sel_hi:[0,0,0]
	v_mfma_scale_f32_16x16x128_f8f6f4 v[70:73], v[10:17], v[26:33], v[70:73], v1, v1 op_sel_hi:[0,0,0]
	v_mfma_scale_f32_16x16x128_f8f6f4 v[62:65], v[2:9], v[200:207], v[62:65], v1, v1 op_sel_hi:[0,0,0]
	v_mfma_scale_f32_16x16x128_f8f6f4 v[54:57], v[10:17], v[200:207], v[54:57], v1, v1 op_sel_hi:[0,0,0]
	v_mfma_scale_f32_16x16x128_f8f6f4 v[46:49], v[2:9], v[208:215], v[46:49], v1, v1 op_sel_hi:[0,0,0]
	v_mfma_scale_f32_16x16x128_f8f6f4 v[38:41], v[10:17], v[208:215], v[38:41], v1, v1 op_sel_hi:[0,0,0]
	s_barrier
	s_add_u32 s0, s30, 0x20080
	s_addc_u32 s1, s31, 0
	s_add_i32 s30, s34, s43
	s_mov_b32 m0, s30
	s_nop 0
	global_load_lds_dwordx4 v164, s[0:1]
	s_add_i32 m0, s30, 0x2000
	s_nop 0
	global_load_lds_dwordx4 v166, s[0:1]
	s_waitcnt vmcnt(10)
	s_barrier
	v_mfma_scale_f32_16x16x128_f8f6f4 v[90:93], v[216:223], v[18:25], v[90:93], v1, v1 op_sel_hi:[0,0,0]
	v_mfma_scale_f32_16x16x128_f8f6f4 v[82:85], v[224:231], v[18:25], v[82:85], v1, v1 op_sel_hi:[0,0,0]
	v_mfma_scale_f32_16x16x128_f8f6f4 v[74:77], v[216:223], v[26:33], v[74:77], v1, v1 op_sel_hi:[0,0,0]
	v_mfma_scale_f32_16x16x128_f8f6f4 v[66:69], v[224:231], v[26:33], v[66:69], v1, v1 op_sel_hi:[0,0,0]
	v_mfma_scale_f32_16x16x128_f8f6f4 v[58:61], v[216:223], v[200:207], v[58:61], v1, v1 op_sel_hi:[0,0,0]
	v_mfma_scale_f32_16x16x128_f8f6f4 v[50:53], v[224:231], v[200:207], v[50:53], v1, v1 op_sel_hi:[0,0,0]
	v_mfma_scale_f32_16x16x128_f8f6f4 v[42:45], v[216:223], v[208:215], v[42:45], v1, v1 op_sel_hi:[0,0,0]
	v_mfma_scale_f32_16x16x128_f8f6f4 v[34:37], v[224:231], v[208:215], v[34:37], v1, v1 op_sel_hi:[0,0,0]
	s_add_i32 s56, s56, 2
	s_cmp_gt_u32 s56, 5
	s_mov_b64 s[34:35], s[10:11]
	s_barrier
	s_cbranch_scc0 .LBB0_2749

.LBB0_2808:
	s_add_u32 s10, s14, 0x12100000
	s_addc_u32 s11, s15, 0
	s_lshl_b32 s0, s0, 5
	s_mov_b64 s[12:13], 0x80
	s_and_b32 s42, s0, 0x60
	s_add_i32 m0, s25, 0x18000
	v_lshl_add_u64 v[4:5], v[4:5], 0, s[12:13]
	s_lshl_b32 s15, s1, 6
	s_lshl_b32 s7, s1, 13
	s_lshl_b32 s14, s42, 7
	s_waitcnt vmcnt(4)
	s_barrier
	global_load_lds_dwordx4 v[4:5], off
	s_add_i32 m0, s25, 0x1a000
	s_add_u32 s0, s28, 0x8000
	v_lshl_add_u64 v[2:3], v[2:3], 0, s[12:13]
	s_addc_u32 s1, s29, 0
	s_add_i32 s43, s25, 0x8000
	global_load_lds_dwordx4 v[2:3], off
	s_mov_b32 m0, s43
	s_add_i32 s44, s25, 0xa000
	global_load_lds_dwordx4 v152, s[0:1]
	v_lshl_add_u64 v[2:3], s[0:1], 0, v[148:149]
	s_add_u32 s0, s26, 0x20080
	s_mov_b32 m0, s44
	s_addc_u32 s1, s27, 0
	global_load_lds_dwordx4 v[2:3], off
	s_add_i32 m0, s25, 0x1c000
	s_nop 0
	global_load_lds_dwordx4 v150, s[0:1]
	s_add_i32 m0, s25, 0x1e000
	v_bfe_u32 v166, v6, 4, 2
	global_load_lds_dwordx4 v146, s[0:1]
	v_and_b32_e32 v1, 15, v6
	v_lshlrev_b32_e32 v2, 4, v166
	v_lshlrev_b32_e32 v3, 2, v6
	v_lshl_or_b32 v2, v1, 6, v2
	v_and_b32_e32 v3, 32, v3
	v_bitop3_b32 v4, v2, s7, v3 bitop3:0xde
	v_bitop3_b32 v167, v2, s14, v3 bitop3:0xde
	v_lshlrev_b32_e32 v2, 10, v7
	v_and_b32_e32 v2, 0xfffff800, v2
	v_lshl_add_u32 v2, v8, 7, v2
	v_and_b32_e32 v3, 1, v7
	v_lshl_or_b32 v2, v3, 6, v2
	v_lshl_add_u32 v154, v9, 1, v2
	v_lshlrev_b32_e32 v2, 10, v11
	v_and_b32_e32 v2, 0xfffff800, v2
	s_waitcnt vmcnt(6)
	v_lshl_add_u32 v2, v10, 7, v2
	v_and_b32_e32 v3, 1, v11
	v_lshl_or_b32 v2, v3, 6, v2
	s_add_i32 s45, 0, 0x10000
	s_add_i32 s46, 0, 0x14000
	s_sext_i32_i8 s48, s6
	v_mov_b32_e32 v155, v151
	v_lshl_add_u32 v156, v12, 1, v2
	v_mov_b32_e32 v157, v151
	v_mov_b64_e32 v[158:159], 0x800
	v_mov_b64_e32 v[160:161], 0x7ff
	v_add_u32_e32 v168, s45, v167
	v_add_u32_e32 v169, 0, v4
	v_mov_b32_e32 v170, 0x7f7f7f7f
	v_add_u32_e32 v171, s46, v167
	s_mov_b32 s14, 0x3d000000
	s_mov_b32 s47, 0xc3d00000
	v_mov_b32_e32 v172, 0x43d00000
	s_barrier

.LBB0_2815:
	s_ashr_i32 s19, s18, 31
	s_lshl_b64 s[0:1], s[18:19], 18
	v_cmp_lt_i64_e32 vcc, s[20:21], v[158:159]
	s_add_u32 s20, s5, s0
	s_addc_u32 s21, s8, s1
	s_and_b64 s[0:1], vcc, exec
	s_cselect_b32 s19, s21, s29
	s_cselect_b32 s49, s20, s28
	s_ashr_i32 s0, s18, 5
	s_ashr_i32 s1, s0, 31
	s_lshl_b64 s[0:1], s[0:1], 20
	s_add_u32 s22, s9, s0
	s_addc_u32 s23, s36, s1
	s_ashr_i32 s17, s16, 31
	s_lshl_b64 s[0:1], s[16:17], 18
	s_add_u32 s22, s22, s0
	s_addc_u32 s23, s23, s1
	s_and_b64 s[0:1], vcc, exec
	s_cselect_b32 s17, s23, s27
	s_cselect_b32 s50, s22, s26
	s_add_u32 s51, s26, 0x100
	s_addc_u32 s52, s27, 0
	s_add_u32 s26, s28, 0xc000
	s_addc_u32 s27, s29, 0
	s_mov_b32 s53, -2
	ds_read_b128 v[2:5], v168
	ds_read_b128 v[6:9], v168 offset:1024
	ds_read_b128 v[10:13], v168 offset:2048
	ds_read_b128 v[14:17], v168 offset:3072
	s_add_u32 s0, s26, 0x4000
	s_addc_u32 s1, s27, 0
	s_cmp_eq_u32 s53, 4
	s_cselect_b32 s34, s49, s0
	s_cselect_b32 s35, s19, s1
	s_cselect_b32 s28, s50, s51
	s_cselect_b32 s29, s17, s52
	s_add_u32 s30, s34, 0x8000
	s_addc_u32 s31, s35, 0
	s_add_i32 m0, s25, 0xc000
	ds_read_b128 v[174:177], v169
	ds_read_b128 v[178:181], v169 offset:1024
	ds_read_b128 v[182:185], v169 offset:2048
	ds_read_b128 v[186:189], v169 offset:3072
	ds_read_b128 v[190:193], v169 offset:4096
	ds_read_b128 v[194:197], v169 offset:5120
	ds_read_b128 v[198:201], v169 offset:6144
	ds_read_b128 v[202:205], v169 offset:7168
	global_load_lds_dwordx4 v156, s[26:27]
	s_add_i32 m0, s25, 0xe000
	s_nop 0
	global_load_lds_dwordx4 v154, s[26:27]
	s_waitcnt lgkmcnt(8)
	s_waitcnt vmcnt(10)
	s_barrier
	s_waitcnt lgkmcnt(0)
	s_waitcnt lgkmcnt(0)
	v_mfma_scale_f32_16x16x128_f8f6f4 v[142:145], v[2:9], v[174:181], 0, v170, v170 op_sel_hi:[0,0,0]
	v_mfma_scale_f32_16x16x128_f8f6f4 v[138:141], v[10:17], v[174:181], 0, v170, v170 op_sel_hi:[0,0,0]
	v_mfma_scale_f32_16x16x128_f8f6f4 v[126:129], v[2:9], v[182:189], 0, v170, v170 op_sel_hi:[0,0,0]
	v_mfma_scale_f32_16x16x128_f8f6f4 v[122:125], v[10:17], v[182:189], 0, v170, v170 op_sel_hi:[0,0,0]
	v_mfma_scale_f32_16x16x128_f8f6f4 v[110:113], v[2:9], v[190:197], 0, v170, v170 op_sel_hi:[0,0,0]
	v_mfma_scale_f32_16x16x128_f8f6f4 v[106:109], v[10:17], v[190:197], 0, v170, v170 op_sel_hi:[0,0,0]
	v_mfma_scale_f32_16x16x128_f8f6f4 v[94:97], v[2:9], v[198:205], 0, v170, v170 op_sel_hi:[0,0,0]
	v_mfma_scale_f32_16x16x128_f8f6f4 v[90:93], v[10:17], v[198:205], 0, v170, v170 op_sel_hi:[0,0,0]
	s_barrier
	s_add_i32 s0, s45, s37
	v_lshl_add_u64 v[162:163], s[28:29], 0, v[150:151]
	s_mov_b32 m0, s0
	ds_read_b128 v[206:209], v171
	ds_read_b128 v[210:213], v171 offset:1024
	ds_read_b128 v[214:217], v171 offset:2048
	ds_read_b128 v[218:221], v171 offset:3072
	global_load_lds_dwordx4 v[162:163], off
	v_lshl_add_u64 v[164:165], s[28:29], 0, v[146:147]
	s_add_i32 m0, s0, 0x2000
	s_nop 0
	global_load_lds_dwordx4 v[164:165], off
	s_waitcnt vmcnt(10)
	s_barrier
	s_waitcnt lgkmcnt(0)
	s_waitcnt lgkmcnt(0)
	v_mfma_scale_f32_16x16x128_f8f6f4 v[134:137], v[206:213], v[174:181], 0, v170, v170 op_sel_hi:[0,0,0]
	v_mfma_scale_f32_16x16x128_f8f6f4 v[130:133], v[214:221], v[174:181], 0, v170, v170 op_sel_hi:[0,0,0]
	v_mfma_scale_f32_16x16x128_f8f6f4 v[118:121], v[206:213], v[182:189], 0, v170, v170 op_sel_hi:[0,0,0]
	v_mfma_scale_f32_16x16x128_f8f6f4 v[114:117], v[214:221], v[182:189], 0, v170, v170 op_sel_hi:[0,0,0]
	v_mfma_scale_f32_16x16x128_f8f6f4 v[102:105], v[206:213], v[190:197], 0, v170, v170 op_sel_hi:[0,0,0]
	v_mfma_scale_f32_16x16x128_f8f6f4 v[98:101], v[214:221], v[190:197], 0, v170, v170 op_sel_hi:[0,0,0]
	v_mfma_scale_f32_16x16x128_f8f6f4 v[86:89], v[206:213], v[198:205], 0, v170, v170 op_sel_hi:[0,0,0]
	v_mfma_scale_f32_16x16x128_f8f6f4 v[82:85], v[214:221], v[198:205], 0, v170, v170 op_sel_hi:[0,0,0]
	s_mov_b32 m0, s25
	s_barrier
	ds_read_b128 v[174:177], v169 offset:16384
	ds_read_b128 v[178:181], v169 offset:17408
	ds_read_b128 v[182:185], v169 offset:18432
	ds_read_b128 v[186:189], v169 offset:19456
	ds_read_b128 v[190:193], v169 offset:20480
	ds_read_b128 v[194:197], v169 offset:21504
	ds_read_b128 v[198:201], v169 offset:22528
	ds_read_b128 v[202:205], v169 offset:23552
	global_load_lds_dwordx4 v152, s[34:35]
	s_mov_b32 m0, s38
	s_nop 0
	global_load_lds_dwordx4 v148, s[34:35]
	s_waitcnt vmcnt(10)
	s_barrier
	s_waitcnt lgkmcnt(0)
	s_waitcnt lgkmcnt(0)
	v_mfma_scale_f32_16x16x128_f8f6f4 v[78:81], v[2:9], v[174:181], 0, v170, v170 op_sel_hi:[0,0,0]
	v_mfma_scale_f32_16x16x128_f8f6f4 v[74:77], v[10:17], v[174:181], 0, v170, v170 op_sel_hi:[0,0,0]
	v_mfma_scale_f32_16x16x128_f8f6f4 v[62:65], v[2:9], v[182:189], 0, v170, v170 op_sel_hi:[0,0,0]
	v_mfma_scale_f32_16x16x128_f8f6f4 v[58:61], v[10:17], v[182:189], 0, v170, v170 op_sel_hi:[0,0,0]
	v_mfma_scale_f32_16x16x128_f8f6f4 v[46:49], v[2:9], v[190:197], 0, v170, v170 op_sel_hi:[0,0,0]
	v_mfma_scale_f32_16x16x128_f8f6f4 v[42:45], v[10:17], v[190:197], 0, v170, v170 op_sel_hi:[0,0,0]
	v_mfma_scale_f32_16x16x128_f8f6f4 v[30:33], v[2:9], v[198:205], 0, v170, v170 op_sel_hi:[0,0,0]
	v_mfma_scale_f32_16x16x128_f8f6f4 v[26:29], v[10:17], v[198:205], 0, v170, v170 op_sel_hi:[0,0,0]
	s_barrier
	s_add_u32 s0, s28, 0x20000
	s_addc_u32 s1, s29, 0
	s_add_i32 s54, s46, s37
	s_mov_b32 m0, s54
	s_nop 0
	global_load_lds_dwordx4 v150, s[0:1]
	s_add_i32 m0, s54, 0x2000
	s_nop 0
	global_load_lds_dwordx4 v146, s[0:1]
	s_waitcnt vmcnt(10)
	s_barrier
	v_mfma_scale_f32_16x16x128_f8f6f4 v[70:73], v[206:213], v[174:181], 0, v170, v170 op_sel_hi:[0,0,0]
	v_mfma_scale_f32_16x16x128_f8f6f4 v[66:69], v[214:221], v[174:181], 0, v170, v170 op_sel_hi:[0,0,0]
	v_mfma_scale_f32_16x16x128_f8f6f4 v[54:57], v[206:213], v[182:189], 0, v170, v170 op_sel_hi:[0,0,0]
	v_mfma_scale_f32_16x16x128_f8f6f4 v[50:53], v[214:221], v[182:189], 0, v170, v170 op_sel_hi:[0,0,0]
	v_mfma_scale_f32_16x16x128_f8f6f4 v[38:41], v[206:213], v[190:197], 0, v170, v170 op_sel_hi:[0,0,0]
	v_mfma_scale_f32_16x16x128_f8f6f4 v[34:37], v[214:221], v[190:197], 0, v170, v170 op_sel_hi:[0,0,0]
	v_mfma_scale_f32_16x16x128_f8f6f4 v[22:25], v[206:213], v[198:205], 0, v170, v170 op_sel_hi:[0,0,0]
	v_mfma_scale_f32_16x16x128_f8f6f4 v[18:21], v[214:221], v[198:205], 0, v170, v170 op_sel_hi:[0,0,0]
	s_add_i32 s54, 0, 0x18000
	v_add_u32_e32 v14, s54, v167
	s_barrier
	ds_read_b128 v[2:5], v14
	ds_read_b128 v[6:9], v14 offset:1024
	ds_read_b128 v[10:13], v14 offset:2048
	ds_read_b128 v[14:17], v14 offset:3072
	s_add_u32 s0, s34, 0x4000
	s_addc_u32 s1, s35, 0
	s_mov_b32 m0, s39
	ds_read_b128 v[174:177], v169 offset:32768
	ds_read_b128 v[178:181], v169 offset:33792
	ds_read_b128 v[182:185], v169 offset:34816
	ds_read_b128 v[186:189], v169 offset:35840
	ds_read_b128 v[190:193], v169 offset:36864
	ds_read_b128 v[194:197], v169 offset:37888
	ds_read_b128 v[198:201], v169 offset:38912
	ds_read_b128 v[202:205], v169 offset:39936
	global_load_lds_dwordx4 v152, s[0:1]
	s_mov_b32 m0, s40
	s_nop 0
	global_load_lds_dwordx4 v148, s[0:1]
	s_waitcnt lgkmcnt(8)
	s_waitcnt vmcnt(10)
	s_barrier
	s_waitcnt lgkmcnt(0)
	s_waitcnt lgkmcnt(0)
	v_mfma_scale_f32_16x16x128_f8f6f4 v[142:145], v[2:9], v[174:181], v[142:145], v170, v170 op_sel_hi:[0,0,0]
	v_mfma_scale_f32_16x16x128_f8f6f4 v[138:141], v[10:17], v[174:181], v[138:141], v170, v170 op_sel_hi:[0,0,0]
	v_mfma_scale_f32_16x16x128_f8f6f4 v[126:129], v[2:9], v[182:189], v[126:129], v170, v170 op_sel_hi:[0,0,0]
	v_mfma_scale_f32_16x16x128_f8f6f4 v[122:125], v[10:17], v[182:189], v[122:125], v170, v170 op_sel_hi:[0,0,0]
	v_mfma_scale_f32_16x16x128_f8f6f4 v[110:113], v[2:9], v[190:197], v[110:113], v170, v170 op_sel_hi:[0,0,0]
	v_mfma_scale_f32_16x16x128_f8f6f4 v[106:109], v[10:17], v[190:197], v[106:109], v170, v170 op_sel_hi:[0,0,0]
	v_mfma_scale_f32_16x16x128_f8f6f4 v[94:97], v[2:9], v[198:205], v[94:97], v170, v170 op_sel_hi:[0,0,0]
	v_mfma_scale_f32_16x16x128_f8f6f4 v[90:93], v[10:17], v[198:205], v[90:93], v170, v170 op_sel_hi:[0,0,0]
	s_barrier
	s_add_i32 s34, 0, 0x1c000
	s_add_i32 s0, s54, s37
	v_add_u32_e32 v173, s34, v167
	v_lshl_add_u64 v[162:163], v[162:163], 0, s[12:13]
	s_mov_b32 m0, s0
	ds_read_b128 v[206:209], v173
	ds_read_b128 v[210:213], v173 offset:1024
	ds_read_b128 v[214:217], v173 offset:2048
	ds_read_b128 v[218:221], v173 offset:3072
	global_load_lds_dwordx4 v[162:163], off
	v_lshl_add_u64 v[162:163], v[164:165], 0, s[12:13]
	s_add_i32 m0, s0, 0x2000
	s_nop 0
	global_load_lds_dwordx4 v[162:163], off
	s_waitcnt vmcnt(10)
	s_barrier
	s_waitcnt lgkmcnt(0)
	s_waitcnt lgkmcnt(0)
	v_mfma_scale_f32_16x16x128_f8f6f4 v[134:137], v[206:213], v[174:181], v[134:137], v170, v170 op_sel_hi:[0,0,0]
	v_mfma_scale_f32_16x16x128_f8f6f4 v[130:133], v[214:221], v[174:181], v[130:133], v170, v170 op_sel_hi:[0,0,0]
	v_mfma_scale_f32_16x16x128_f8f6f4 v[118:121], v[206:213], v[182:189], v[118:121], v170, v170 op_sel_hi:[0,0,0]
	v_mfma_scale_f32_16x16x128_f8f6f4 v[114:117], v[214:221], v[182:189], v[114:117], v170, v170 op_sel_hi:[0,0,0]
	v_mfma_scale_f32_16x16x128_f8f6f4 v[102:105], v[206:213], v[190:197], v[102:105], v170, v170 op_sel_hi:[0,0,0]
	v_mfma_scale_f32_16x16x128_f8f6f4 v[98:101], v[214:221], v[190:197], v[98:101], v170, v170 op_sel_hi:[0,0,0]
	v_mfma_scale_f32_16x16x128_f8f6f4 v[86:89], v[206:213], v[198:205], v[86:89], v170, v170 op_sel_hi:[0,0,0]
	v_mfma_scale_f32_16x16x128_f8f6f4 v[82:85], v[214:221], v[198:205], v[82:85], v170, v170 op_sel_hi:[0,0,0]
	s_mov_b32 m0, s43
	s_barrier
	ds_read_b128 v[174:177], v169 offset:49152
	ds_read_b128 v[178:181], v169 offset:50176
	ds_read_b128 v[182:185], v169 offset:51200
	ds_read_b128 v[186:189], v169 offset:52224
	ds_read_b128 v[190:193], v169 offset:53248
	ds_read_b128 v[194:197], v169 offset:54272
	ds_read_b128 v[198:201], v169 offset:55296
	ds_read_b128 v[202:205], v169 offset:56320
	global_load_lds_dwordx4 v152, s[30:31]
	s_mov_b32 m0, s44
	s_nop 0
	global_load_lds_dwordx4 v148, s[30:31]
	s_waitcnt vmcnt(10)
	s_barrier
	s_waitcnt lgkmcnt(0)
	s_waitcnt lgkmcnt(0)
	v_mfma_scale_f32_16x16x128_f8f6f4 v[78:81], v[2:9], v[174:181], v[78:81], v170, v170 op_sel_hi:[0,0,0]
	v_mfma_scale_f32_16x16x128_f8f6f4 v[74:77], v[10:17], v[174:181], v[74:77], v170, v170 op_sel_hi:[0,0,0]
	v_mfma_scale_f32_16x16x128_f8f6f4 v[62:65], v[2:9], v[182:189], v[62:65], v170, v170 op_sel_hi:[0,0,0]
	v_mfma_scale_f32_16x16x128_f8f6f4 v[58:61], v[10:17], v[182:189], v[58:61], v170, v170 op_sel_hi:[0,0,0]
	v_mfma_scale_f32_16x16x128_f8f6f4 v[46:49], v[2:9], v[190:197], v[46:49], v170, v170 op_sel_hi:[0,0,0]
	v_mfma_scale_f32_16x16x128_f8f6f4 v[42:45], v[10:17], v[190:197], v[42:45], v170, v170 op_sel_hi:[0,0,0]
	v_mfma_scale_f32_16x16x128_f8f6f4 v[30:33], v[2:9], v[198:205], v[30:33], v170, v170 op_sel_hi:[0,0,0]
	v_mfma_scale_f32_16x16x128_f8f6f4 v[26:29], v[10:17], v[198:205], v[26:29], v170, v170 op_sel_hi:[0,0,0]
	s_barrier
	s_add_u32 s0, s28, 0x20080
	s_addc_u32 s1, s29, 0
	s_add_i32 s28, s34, s37
	s_mov_b32 m0, s28
	s_nop 0
	global_load_lds_dwordx4 v150, s[0:1]
	s_add_i32 m0, s28, 0x2000
	s_nop 0
	global_load_lds_dwordx4 v146, s[0:1]
	s_waitcnt vmcnt(10)
	s_barrier
	v_mfma_scale_f32_16x16x128_f8f6f4 v[70:73], v[206:213], v[174:181], v[70:73], v170, v170 op_sel_hi:[0,0,0]
	v_mfma_scale_f32_16x16x128_f8f6f4 v[66:69], v[214:221], v[174:181], v[66:69], v170, v170 op_sel_hi:[0,0,0]
	v_mfma_scale_f32_16x16x128_f8f6f4 v[54:57], v[206:213], v[182:189], v[54:57], v170, v170 op_sel_hi:[0,0,0]
	v_mfma_scale_f32_16x16x128_f8f6f4 v[50:53], v[214:221], v[182:189], v[50:53], v170, v170 op_sel_hi:[0,0,0]
	v_mfma_scale_f32_16x16x128_f8f6f4 v[38:41], v[206:213], v[190:197], v[38:41], v170, v170 op_sel_hi:[0,0,0]
	v_mfma_scale_f32_16x16x128_f8f6f4 v[34:37], v[214:221], v[190:197], v[34:37], v170, v170 op_sel_hi:[0,0,0]
	v_mfma_scale_f32_16x16x128_f8f6f4 v[22:25], v[206:213], v[198:205], v[22:25], v170, v170 op_sel_hi:[0,0,0]
	v_mfma_scale_f32_16x16x128_f8f6f4 v[18:21], v[214:221], v[198:205], v[18:21], v170, v170 op_sel_hi:[0,0,0]
	s_add_i32 s53, s53, 2
	s_add_u32 s51, s51, 0x100
	s_addc_u32 s52, s52, 0
	s_add_u32 s26, s26, 0x10000
	s_addc_u32 s27, s27, 0
	s_cmp_gt_u32 s53, 5
	s_barrier
	s_cbranch_scc1 .Lpeel_exit_18
.LBB0_2816:
	ds_read_b128 v[2:5], v168
	ds_read_b128 v[6:9], v168 offset:1024
	ds_read_b128 v[10:13], v168 offset:2048
	ds_read_b128 v[14:17], v168 offset:3072
	s_add_u32 s0, s26, 0x4000
	s_addc_u32 s1, s27, 0
	s_cmp_eq_u32 s53, 4
	s_cselect_b32 s34, s49, s0
	s_cselect_b32 s35, s19, s1
	s_cselect_b32 s28, s50, s51
	s_cselect_b32 s29, s17, s52
	s_add_u32 s30, s34, 0x8000
	s_addc_u32 s31, s35, 0
	s_add_i32 m0, s25, 0xc000
	ds_read_b128 v[174:177], v169
	ds_read_b128 v[178:181], v169 offset:1024
	ds_read_b128 v[182:185], v169 offset:2048
	ds_read_b128 v[186:189], v169 offset:3072
	ds_read_b128 v[190:193], v169 offset:4096
	ds_read_b128 v[194:197], v169 offset:5120
	ds_read_b128 v[198:201], v169 offset:6144
	ds_read_b128 v[202:205], v169 offset:7168
	global_load_lds_dwordx4 v156, s[26:27]
	s_add_i32 m0, s25, 0xe000
	s_nop 0
	global_load_lds_dwordx4 v154, s[26:27]
	s_waitcnt lgkmcnt(8)
	s_waitcnt vmcnt(10)
	s_barrier
	s_waitcnt lgkmcnt(0)
	s_waitcnt lgkmcnt(0)
	v_mfma_scale_f32_16x16x128_f8f6f4 v[142:145], v[2:9], v[174:181], v[142:145], v170, v170 op_sel_hi:[0,0,0]
	v_mfma_scale_f32_16x16x128_f8f6f4 v[138:141], v[10:17], v[174:181], v[138:141], v170, v170 op_sel_hi:[0,0,0]
	v_mfma_scale_f32_16x16x128_f8f6f4 v[126:129], v[2:9], v[182:189], v[126:129], v170, v170 op_sel_hi:[0,0,0]
	v_mfma_scale_f32_16x16x128_f8f6f4 v[122:125], v[10:17], v[182:189], v[122:125], v170, v170 op_sel_hi:[0,0,0]
	v_mfma_scale_f32_16x16x128_f8f6f4 v[110:113], v[2:9], v[190:197], v[110:113], v170, v170 op_sel_hi:[0,0,0]
	v_mfma_scale_f32_16x16x128_f8f6f4 v[106:109], v[10:17], v[190:197], v[106:109], v170, v170 op_sel_hi:[0,0,0]
	v_mfma_scale_f32_16x16x128_f8f6f4 v[94:97], v[2:9], v[198:205], v[94:97], v170, v170 op_sel_hi:[0,0,0]
	v_mfma_scale_f32_16x16x128_f8f6f4 v[90:93], v[10:17], v[198:205], v[90:93], v170, v170 op_sel_hi:[0,0,0]
	s_barrier
	s_add_i32 s0, s45, s37
	v_lshl_add_u64 v[162:163], s[28:29], 0, v[150:151]
	s_mov_b32 m0, s0
	ds_read_b128 v[206:209], v171
	ds_read_b128 v[210:213], v171 offset:1024
	ds_read_b128 v[214:217], v171 offset:2048
	ds_read_b128 v[218:221], v171 offset:3072
	global_load_lds_dwordx4 v[162:163], off
	v_lshl_add_u64 v[164:165], s[28:29], 0, v[146:147]
	s_add_i32 m0, s0, 0x2000
	s_nop 0
	global_load_lds_dwordx4 v[164:165], off
	s_waitcnt vmcnt(10)
	s_barrier
	s_waitcnt lgkmcnt(0)
	s_waitcnt lgkmcnt(0)
	v_mfma_scale_f32_16x16x128_f8f6f4 v[134:137], v[206:213], v[174:181], v[134:137], v170, v170 op_sel_hi:[0,0,0]
	v_mfma_scale_f32_16x16x128_f8f6f4 v[130:133], v[214:221], v[174:181], v[130:133], v170, v170 op_sel_hi:[0,0,0]
	v_mfma_scale_f32_16x16x128_f8f6f4 v[118:121], v[206:213], v[182:189], v[118:121], v170, v170 op_sel_hi:[0,0,0]
	v_mfma_scale_f32_16x16x128_f8f6f4 v[114:117], v[214:221], v[182:189], v[114:117], v170, v170 op_sel_hi:[0,0,0]
	v_mfma_scale_f32_16x16x128_f8f6f4 v[102:105], v[206:213], v[190:197], v[102:105], v170, v170 op_sel_hi:[0,0,0]
	v_mfma_scale_f32_16x16x128_f8f6f4 v[98:101], v[214:221], v[190:197], v[98:101], v170, v170 op_sel_hi:[0,0,0]
	v_mfma_scale_f32_16x16x128_f8f6f4 v[86:89], v[206:213], v[198:205], v[86:89], v170, v170 op_sel_hi:[0,0,0]
	v_mfma_scale_f32_16x16x128_f8f6f4 v[82:85], v[214:221], v[198:205], v[82:85], v170, v170 op_sel_hi:[0,0,0]
	s_mov_b32 m0, s25
	s_barrier
	ds_read_b128 v[174:177], v169 offset:16384
	ds_read_b128 v[178:181], v169 offset:17408
	ds_read_b128 v[182:185], v169 offset:18432
	ds_read_b128 v[186:189], v169 offset:19456
	ds_read_b128 v[190:193], v169 offset:20480
	ds_read_b128 v[194:197], v169 offset:21504
	ds_read_b128 v[198:201], v169 offset:22528
	ds_read_b128 v[202:205], v169 offset:23552
	global_load_lds_dwordx4 v152, s[34:35]
	s_mov_b32 m0, s38
	s_nop 0
	global_load_lds_dwordx4 v148, s[34:35]
	s_waitcnt vmcnt(10)
	s_barrier
	s_waitcnt lgkmcnt(0)
	s_waitcnt lgkmcnt(0)
	v_mfma_scale_f32_16x16x128_f8f6f4 v[78:81], v[2:9], v[174:181], v[78:81], v170, v170 op_sel_hi:[0,0,0]
	v_mfma_scale_f32_16x16x128_f8f6f4 v[74:77], v[10:17], v[174:181], v[74:77], v170, v170 op_sel_hi:[0,0,0]
	v_mfma_scale_f32_16x16x128_f8f6f4 v[62:65], v[2:9], v[182:189], v[62:65], v170, v170 op_sel_hi:[0,0,0]
	v_mfma_scale_f32_16x16x128_f8f6f4 v[58:61], v[10:17], v[182:189], v[58:61], v170, v170 op_sel_hi:[0,0,0]
	v_mfma_scale_f32_16x16x128_f8f6f4 v[46:49], v[2:9], v[190:197], v[46:49], v170, v170 op_sel_hi:[0,0,0]
	v_mfma_scale_f32_16x16x128_f8f6f4 v[42:45], v[10:17], v[190:197], v[42:45], v170, v170 op_sel_hi:[0,0,0]
	v_mfma_scale_f32_16x16x128_f8f6f4 v[30:33], v[2:9], v[198:205], v[30:33], v170, v170 op_sel_hi:[0,0,0]
	v_mfma_scale_f32_16x16x128_f8f6f4 v[26:29], v[10:17], v[198:205], v[26:29], v170, v170 op_sel_hi:[0,0,0]
	s_barrier
	s_add_u32 s0, s28, 0x20000
	s_addc_u32 s1, s29, 0
	s_add_i32 s54, s46, s37
	s_mov_b32 m0, s54
	s_nop 0
	global_load_lds_dwordx4 v150, s[0:1]
	s_add_i32 m0, s54, 0x2000
	s_nop 0
	global_load_lds_dwordx4 v146, s[0:1]
	s_waitcnt vmcnt(10)
	s_barrier
	v_mfma_scale_f32_16x16x128_f8f6f4 v[70:73], v[206:213], v[174:181], v[70:73], v170, v170 op_sel_hi:[0,0,0]
	v_mfma_scale_f32_16x16x128_f8f6f4 v[66:69], v[214:221], v[174:181], v[66:69], v170, v170 op_sel_hi:[0,0,0]
	v_mfma_scale_f32_16x16x128_f8f6f4 v[54:57], v[206:213], v[182:189], v[54:57], v170, v170 op_sel_hi:[0,0,0]
	v_mfma_scale_f32_16x16x128_f8f6f4 v[50:53], v[214:221], v[182:189], v[50:53], v170, v170 op_sel_hi:[0,0,0]
	v_mfma_scale_f32_16x16x128_f8f6f4 v[38:41], v[206:213], v[190:197], v[38:41], v170, v170 op_sel_hi:[0,0,0]
	v_mfma_scale_f32_16x16x128_f8f6f4 v[34:37], v[214:221], v[190:197], v[34:37], v170, v170 op_sel_hi:[0,0,0]
	v_mfma_scale_f32_16x16x128_f8f6f4 v[22:25], v[206:213], v[198:205], v[22:25], v170, v170 op_sel_hi:[0,0,0]
	v_mfma_scale_f32_16x16x128_f8f6f4 v[18:21], v[214:221], v[198:205], v[18:21], v170, v170 op_sel_hi:[0,0,0]
	s_add_i32 s54, 0, 0x18000
	v_add_u32_e32 v14, s54, v167
	s_barrier
	ds_read_b128 v[2:5], v14
	ds_read_b128 v[6:9], v14 offset:1024
	ds_read_b128 v[10:13], v14 offset:2048
	ds_read_b128 v[14:17], v14 offset:3072
	s_add_u32 s0, s34, 0x4000
	s_addc_u32 s1, s35, 0
	s_mov_b32 m0, s39
	ds_read_b128 v[174:177], v169 offset:32768
	ds_read_b128 v[178:181], v169 offset:33792
	ds_read_b128 v[182:185], v169 offset:34816
	ds_read_b128 v[186:189], v169 offset:35840
	ds_read_b128 v[190:193], v169 offset:36864
	ds_read_b128 v[194:197], v169 offset:37888
	ds_read_b128 v[198:201], v169 offset:38912
	ds_read_b128 v[202:205], v169 offset:39936
	global_load_lds_dwordx4 v152, s[0:1]
	s_mov_b32 m0, s40
	s_nop 0
	global_load_lds_dwordx4 v148, s[0:1]
	s_waitcnt lgkmcnt(8)
	s_waitcnt vmcnt(10)
	s_barrier
	s_waitcnt lgkmcnt(0)
	s_waitcnt lgkmcnt(0)
	v_mfma_scale_f32_16x16x128_f8f6f4 v[142:145], v[2:9], v[174:181], v[142:145], v170, v170 op_sel_hi:[0,0,0]
	v_mfma_scale_f32_16x16x128_f8f6f4 v[138:141], v[10:17], v[174:181], v[138:141], v170, v170 op_sel_hi:[0,0,0]
	v_mfma_scale_f32_16x16x128_f8f6f4 v[126:129], v[2:9], v[182:189], v[126:129], v170, v170 op_sel_hi:[0,0,0]
	v_mfma_scale_f32_16x16x128_f8f6f4 v[122:125], v[10:17], v[182:189], v[122:125], v170, v170 op_sel_hi:[0,0,0]
	v_mfma_scale_f32_16x16x128_f8f6f4 v[110:113], v[2:9], v[190:197], v[110:113], v170, v170 op_sel_hi:[0,0,0]
	v_mfma_scale_f32_16x16x128_f8f6f4 v[106:109], v[10:17], v[190:197], v[106:109], v170, v170 op_sel_hi:[0,0,0]
	v_mfma_scale_f32_16x16x128_f8f6f4 v[94:97], v[2:9], v[198:205], v[94:97], v170, v170 op_sel_hi:[0,0,0]
	v_mfma_scale_f32_16x16x128_f8f6f4 v[90:93], v[10:17], v[198:205], v[90:93], v170, v170 op_sel_hi:[0,0,0]
	s_barrier
	s_add_i32 s34, 0, 0x1c000
	s_add_i32 s0, s54, s37
	v_add_u32_e32 v173, s34, v167
	v_lshl_add_u64 v[162:163], v[162:163], 0, s[12:13]
	s_mov_b32 m0, s0
	ds_read_b128 v[206:209], v173
	ds_read_b128 v[210:213], v173 offset:1024
	ds_read_b128 v[214:217], v173 offset:2048
	ds_read_b128 v[218:221], v173 offset:3072
	global_load_lds_dwordx4 v[162:163], off
	v_lshl_add_u64 v[162:163], v[164:165], 0, s[12:13]
	s_add_i32 m0, s0, 0x2000
	s_nop 0
	global_load_lds_dwordx4 v[162:163], off
	s_waitcnt vmcnt(10)
	s_barrier
	s_waitcnt lgkmcnt(0)
	s_waitcnt lgkmcnt(0)
	v_mfma_scale_f32_16x16x128_f8f6f4 v[134:137], v[206:213], v[174:181], v[134:137], v170, v170 op_sel_hi:[0,0,0]
	v_mfma_scale_f32_16x16x128_f8f6f4 v[130:133], v[214:221], v[174:181], v[130:133], v170, v170 op_sel_hi:[0,0,0]
	v_mfma_scale_f32_16x16x128_f8f6f4 v[118:121], v[206:213], v[182:189], v[118:121], v170, v170 op_sel_hi:[0,0,0]
	v_mfma_scale_f32_16x16x128_f8f6f4 v[114:117], v[214:221], v[182:189], v[114:117], v170, v170 op_sel_hi:[0,0,0]
	v_mfma_scale_f32_16x16x128_f8f6f4 v[102:105], v[206:213], v[190:197], v[102:105], v170, v170 op_sel_hi:[0,0,0]
	v_mfma_scale_f32_16x16x128_f8f6f4 v[98:101], v[214:221], v[190:197], v[98:101], v170, v170 op_sel_hi:[0,0,0]
	v_mfma_scale_f32_16x16x128_f8f6f4 v[86:89], v[206:213], v[198:205], v[86:89], v170, v170 op_sel_hi:[0,0,0]
	v_mfma_scale_f32_16x16x128_f8f6f4 v[82:85], v[214:221], v[198:205], v[82:85], v170, v170 op_sel_hi:[0,0,0]
	s_mov_b32 m0, s43
	s_barrier
	ds_read_b128 v[174:177], v169 offset:49152
	ds_read_b128 v[178:181], v169 offset:50176
	ds_read_b128 v[182:185], v169 offset:51200
	ds_read_b128 v[186:189], v169 offset:52224
	ds_read_b128 v[190:193], v169 offset:53248
	ds_read_b128 v[194:197], v169 offset:54272
	ds_read_b128 v[198:201], v169 offset:55296
	ds_read_b128 v[202:205], v169 offset:56320
	global_load_lds_dwordx4 v152, s[30:31]
	s_mov_b32 m0, s44
	s_nop 0
	global_load_lds_dwordx4 v148, s[30:31]
	s_waitcnt vmcnt(10)
	s_barrier
	s_waitcnt lgkmcnt(0)
	s_waitcnt lgkmcnt(0)
	v_mfma_scale_f32_16x16x128_f8f6f4 v[78:81], v[2:9], v[174:181], v[78:81], v170, v170 op_sel_hi:[0,0,0]
	v_mfma_scale_f32_16x16x128_f8f6f4 v[74:77], v[10:17], v[174:181], v[74:77], v170, v170 op_sel_hi:[0,0,0]
	v_mfma_scale_f32_16x16x128_f8f6f4 v[62:65], v[2:9], v[182:189], v[62:65], v170, v170 op_sel_hi:[0,0,0]
	v_mfma_scale_f32_16x16x128_f8f6f4 v[58:61], v[10:17], v[182:189], v[58:61], v170, v170 op_sel_hi:[0,0,0]
	v_mfma_scale_f32_16x16x128_f8f6f4 v[46:49], v[2:9], v[190:197], v[46:49], v170, v170 op_sel_hi:[0,0,0]
	v_mfma_scale_f32_16x16x128_f8f6f4 v[42:45], v[10:17], v[190:197], v[42:45], v170, v170 op_sel_hi:[0,0,0]
	v_mfma_scale_f32_16x16x128_f8f6f4 v[30:33], v[2:9], v[198:205], v[30:33], v170, v170 op_sel_hi:[0,0,0]
	v_mfma_scale_f32_16x16x128_f8f6f4 v[26:29], v[10:17], v[198:205], v[26:29], v170, v170 op_sel_hi:[0,0,0]
	s_barrier
	s_add_u32 s0, s28, 0x20080
	s_addc_u32 s1, s29, 0
	s_add_i32 s28, s34, s37
	s_mov_b32 m0, s28
	s_nop 0
	global_load_lds_dwordx4 v150, s[0:1]
	s_add_i32 m0, s28, 0x2000
	s_nop 0
	global_load_lds_dwordx4 v146, s[0:1]
	s_waitcnt vmcnt(10)
	s_barrier
	v_mfma_scale_f32_16x16x128_f8f6f4 v[70:73], v[206:213], v[174:181], v[70:73], v170, v170 op_sel_hi:[0,0,0]
	v_mfma_scale_f32_16x16x128_f8f6f4 v[66:69], v[214:221], v[174:181], v[66:69], v170, v170 op_sel_hi:[0,0,0]
	v_mfma_scale_f32_16x16x128_f8f6f4 v[54:57], v[206:213], v[182:189], v[54:57], v170, v170 op_sel_hi:[0,0,0]
	v_mfma_scale_f32_16x16x128_f8f6f4 v[50:53], v[214:221], v[182:189], v[50:53], v170, v170 op_sel_hi:[0,0,0]
	v_mfma_scale_f32_16x16x128_f8f6f4 v[38:41], v[206:213], v[190:197], v[38:41], v170, v170 op_sel_hi:[0,0,0]
	v_mfma_scale_f32_16x16x128_f8f6f4 v[34:37], v[214:221], v[190:197], v[34:37], v170, v170 op_sel_hi:[0,0,0]
	v_mfma_scale_f32_16x16x128_f8f6f4 v[22:25], v[206:213], v[198:205], v[22:25], v170, v170 op_sel_hi:[0,0,0]
	v_mfma_scale_f32_16x16x128_f8f6f4 v[18:21], v[214:221], v[198:205], v[18:21], v170, v170 op_sel_hi:[0,0,0]
	s_add_i32 s53, s53, 2
	s_add_u32 s51, s51, 0x100
	s_addc_u32 s52, s52, 0
	s_add_u32 s26, s26, 0x10000
	s_addc_u32 s27, s27, 0
	s_cmp_gt_u32 s53, 5
	s_barrier
	s_cbranch_scc0 .LBB0_2816
